# replace packed f32 VALU ops (v_pk_add/mul/fma_f32) by scalar f32 pairs throughout the layer loop
# speedup vs baseline: 1.0096x; 1.0096x over previous
; __device__ __forceinline__ void norm_row(const f32x4 (&v)[4], const f32x4 (&gn)[4], const float* sh, bf16_t* hrow, int lane) {
;     const float* scl = sh + 1024;
;     f32x4 sv[4], cv[4];
; #pragma unroll
;     for (int j = 0; j < 4; ++j) { sv[j] = *(const f32x4*)(sh + 4 * lane + 256 * j); cv[j] = *(const f32x4*)(scl + 4 * lane + 256 * j); }
;     float ss = 0.f;
; #pragma unroll
;     for (int j = 0; j < 4; ++j) ss += (v[j][0] * v[j][0] + v[j][1] * v[j][1]) + (v[j][2] * v[j][2] + v[j][3] * v[j][3]);
;     const float rstd = __builtin_amdgcn_rsqf(wave_sum(ss) * (1.0f / DM) + EPS);
; #pragma unroll
;     for (int j = 0; j < 4; ++j) {
;         const f32x4 y = v[j] * rstd * gn[j] * (cv[j] + 1.0f) + sv[j];
;         u32x2 w; w.x = cvt_pk_bf16(y[0], y[1]); w.y = cvt_pk_bf16(y[2], y[3]);
;         *(u32x2*)(hrow + 4 * lane + 256 * j) = w;
;     }
; }
; __device__ __forceinline__ void norm_phase(const float* xL, const float* xC, const float* gain, const float* modl  , int ishift, bf16_t* H, int nrows,
;                                            const float* part, int nsplit, const float* pgate  , float pscale, float* xCw) {
;     const int tid_ = opaque_tid(); const int lane = tid_ & 63, wave = __builtin_amdgcn_readfirstlane(tid_ >> 6);
;     const int gw = blockIdx.x * NWAVES + wave, NGW = gridDim.x * NWAVES;
;     f32x4 gn[4];
; #pragma unroll
;     for (int j = 0; j < 4; ++j) gn[j] = *(const f32x4*)(gain + 4 * lane + 256 * j);
;     const int nplain = (nsplit > 0 && nrows > RL) ? RL : nrows;
;     {
;         int row = gw; f32x4 v[4], vn[4];
;         if (row < nplain) { const float* xr = row < RL ? xL + (size_t)row * DM : xC + (size_t)(row - RL) * DM;
; #pragma unroll
;             for (int j = 0; j < 4; ++j) v[j] = *(const f32x4*)(xr + 4 * lane + 256 * j); }
;         for (; row < nplain; row += NGW) {
;             const int rn = row + NGW;
;             if (rn < nplain) { const float* xr = rn < RL ? xL + (size_t)rn * DM : xC + (size_t)(rn - RL) * DM;
; #pragma unroll
;                 for (int j = 0; j < 4; ++j) vn[j] = *(const f32x4*)(xr + 4 * lane + 256 * j); }
;             const int s = row < RL ? (row >> 13) : 4;
;             norm_row(v, gn, modl + (size_t)s * 9216 + ishift * 1024, H + (size_t)row * DM, lane);
; #pragma unroll
;             for (int j = 0; j < 4; ++j) v[j] = vn[j];
;         }
.LBB0_108:
	s_min_i32 s16, s16, 0x8000
	s_ashr_i32 s16, s16, 13
	s_mul_hi_i32 s17, s16, 0x9000
	s_mul_i32 s16, s16, 0x9000
	s_add_u32 s16, s38, s16
	s_addc_u32 s17, s39, s17
	v_lshl_add_u64 v[56:57], s[16:17], 0, v[194:195]
	v_add_co_u32_e32 v80, vcc, s20, v56
	v_lshl_add_u64 v[84:85], v[56:57], 0, s[26:27]
	s_nop 0
	v_addc_co_u32_e32 v81, vcc, 0, v57, vcc
	global_load_dwordx4 v[56:59], v194, s[16:17]
	global_load_dwordx4 v[60:63], v194, s[16:17] offset:1024
	global_load_dwordx4 v[64:67], v[84:85], off offset:1024
	global_load_dwordx4 v[68:71], v[84:85], off offset:2048
	global_load_dwordx4 v[72:75], v194, s[16:17] offset:2048
	global_load_dwordx4 v[76:79], v194, s[16:17] offset:3072
	s_nop 0
	global_load_dwordx4 v[80:83], v[80:81], off
	s_nop 0
	global_load_dwordx4 v[84:87], v[84:85], off offset:3072
	s_waitcnt vmcnt(9)
	v_mul_f32_e32 v55, v45, v45
	v_mul_f32_e32 v88, v47, v47
	v_fmac_f32_e32 v55, v44, v44
	v_fmac_f32_e32 v88, v46, v46
	v_add_f32_e32 v55, v55, v88
	s_waitcnt vmcnt(8)
	v_mul_f32_e32 v88, v41, v41
	v_mul_f32_e32 v89, v43, v43
	v_fmac_f32_e32 v88, v40, v40
	v_fmac_f32_e32 v89, v42, v42
	v_add_f32_e32 v88, v88, v89
	v_add_f32_e32 v55, v55, v88
	v_mul_f32_e32 v88, v37, v37
	v_mul_f32_e32 v89, v39, v39
	v_mul_f32_e32 v53, v53, v53
	v_fmac_f32_e32 v88, v36, v36
	v_fmac_f32_e32 v89, v38, v38
	v_fmac_f32_e32 v53, v51, v51
	v_mul_f32_e32 v51, v54, v54
	v_add_f32_e32 v88, v88, v89
	v_fmac_f32_e32 v51, v52, v52
	v_add_f32_e32 v55, v88, v55
	v_add_f32_e32 v51, v53, v51
	v_add_f32_e32 v51, v51, v55
	ds_swizzle_b32 v52, v51 offset:swizzle(SWAP,1)
	s_add_u32 s9, s9, s88
	s_addc_u32 s14, s14, s89
	s_andn2_b64 vcc, exec, s[10:11]
	s_mov_b32 s16, s15
	s_waitcnt lgkmcnt(0)
	v_add_f32_e32 v51, v51, v52
	ds_swizzle_b32 v52, v51 offset:swizzle(SWAP,2)
	s_waitcnt lgkmcnt(0)
	v_add_f32_e32 v51, v51, v52
	ds_swizzle_b32 v52, v51 offset:swizzle(SWAP,4)
	s_waitcnt lgkmcnt(0)
	v_add_f32_e32 v51, v51, v52
	ds_swizzle_b32 v52, v51 offset:swizzle(SWAP,8)
	s_waitcnt lgkmcnt(0)
	v_add_f32_e32 v51, v51, v52
	ds_swizzle_b32 v52, v51 offset:swizzle(SWAP,16)
	s_waitcnt lgkmcnt(0)
	v_add_f32_e32 v51, v51, v52
	v_mov_b32_e32 v52, v51
	s_nop 1
	v_permlane32_swap_b32_e32 v51, v52
	v_add_f32_e32 v51, v51, v52
	v_fmamk_f32 v51, v51, 0x3a800000, v193
	v_rsq_f32_e32 v52, v51
	v_mov_b32_e32 v51, v20
	v_mul_f32_e32 v46, v46, v52
	v_mul_f32_e32 v47, v47, v52
	v_mul_f32_e32 v44, v44, v52
	v_mul_f32_e32 v45, v45, v52
	v_mul_f32_e32 v42, v42, v52
	v_mul_f32_e32 v43, v43, v52
	v_mul_f32_e32 v40, v40, v52
	v_mul_f32_e32 v41, v41, v52
	v_mul_f32_e32 v38, v38, v52
	v_mul_f32_e32 v39, v39, v52
	v_mul_f32_e32 v36, v36, v52
	v_mul_f32_e32 v37, v37, v52
	v_mul_f32_e32 v44, v0, v44
	v_mul_f32_e32 v45, v1, v45
	v_mul_f32_e32 v46, v2, v46
	v_mul_f32_e32 v47, v3, v47
	v_mul_f32_e32 v40, v4, v40
	v_mul_f32_e32 v41, v5, v41
	v_mul_f32_e32 v42, v6, v42
	v_mul_f32_e32 v43, v7, v43
	v_mul_f32_e32 v36, v8, v36
	v_mul_f32_e32 v37, v9, v37
	v_mul_f32_e32 v38, v10, v38
	v_mul_f32_e32 v39, v11, v39
	s_waitcnt vmcnt(5)
	v_add_f32_e32 v54, 1.0, v66
	v_add_f32_e32 v55, 1.0, v67
	v_add_f32_e32 v64, 1.0, v64
	v_add_f32_e32 v65, 1.0, v65
	s_waitcnt vmcnt(4)
	v_add_f32_e32 v66, 1.0, v70
	v_add_f32_e32 v67, 1.0, v71
	v_add_f32_e32 v68, 1.0, v68
	v_add_f32_e32 v69, 1.0, v69
	s_waitcnt vmcnt(1)
	v_add_f32_e32 v70, 1.0, v82
	v_add_f32_e32 v71, 1.0, v83
	v_add_f32_e32 v80, 1.0, v80
	v_add_f32_e32 v81, 1.0, v81
	v_fma_f32 v42, v54, v42, v62
	v_fma_f32 v43, v55, v43, v63
	v_fma_f32 v40, v64, v40, v60
	v_fma_f32 v41, v65, v41, v61
	v_fma_f32 v38, v66, v38, v74
	v_fma_f32 v39, v67, v39, v75
	v_fma_f32 v36, v68, v36, v72
	v_fma_f32 v37, v69, v37, v73
	v_fma_f32 v46, v70, v46, v58
	v_fma_f32 v47, v71, v47, v59
	v_fma_f32 v44, v80, v44, v56
	v_fma_f32 v45, v81, v45, v57
	v_cvt_pk_bf16_f32 v40, v40, v41
	v_cvt_pk_bf16_f32 v41, v42, v43
	v_cvt_pk_bf16_f32 v36, v36, v37
	v_cvt_pk_bf16_f32 v37, v38, v39
	v_cvt_pk_bf16_f32 v38, v44, v45
	v_cvt_pk_bf16_f32 v39, v46, v47
	v_mul_f32_e32 v18, v18, v52
	v_mul_f32_e32 v19, v19, v52
	v_mul_f32_e32 v16, v16, v52
	v_mul_f32_e32 v17, v17, v52
	global_store_dwordx2 v[48:49], v[40:41], off offset:512
	global_store_dwordx2 v[48:49], v[38:39], off
	global_store_dwordx2 v[48:49], v[36:37], off offset:1024
	v_mul_f32_e32 v16, v12, v16
	v_mul_f32_e32 v17, v13, v17
	v_mul_f32_e32 v18, v14, v18
	v_mul_f32_e32 v19, v15, v19
	s_waitcnt vmcnt(3)
	v_add_f32_e32 v36, 1.0, v86
	v_add_f32_e32 v37, 1.0, v87
	v_add_f32_e32 v38, 1.0, v84
	v_add_f32_e32 v39, 1.0, v85
	v_fma_f32 v18, v36, v18, v78
	v_fma_f32 v19, v37, v19, v79
	v_fma_f32 v16, v38, v16, v76
	v_fma_f32 v17, v39, v17, v77
	v_mov_b32_e32 v44, v32
	v_cvt_pk_bf16_f32 v16, v16, v17
	v_cvt_pk_bf16_f32 v17, v18, v19
	global_store_dwordx2 v[48:49], v[16:17], off offset:1536
	v_mov_b64_e32 v[16:17], v[20:21]
	v_lshl_add_u64 v[48:49], v[48:49], 0, s[92:93]
	v_mov_b64_e32 v[18:19], v[22:23]
	v_mov_b32_e32 v45, v33
	v_mov_b32_e32 v46, v34
	v_mov_b32_e32 v47, v35
	v_mov_b32_e32 v40, v28
	v_mov_b32_e32 v41, v29
	v_mov_b32_e32 v42, v30
	v_mov_b32_e32 v43, v31
	v_mov_b32_e32 v36, v24
	v_mov_b32_e32 v37, v25
	v_mov_b32_e32 v38, v26
	v_mov_b32_e32 v39, v27
	v_mov_b32_e32 v53, v21
	v_mov_b32_e32 v52, v22
	v_mov_b32_e32 v54, v23
	s_cbranch_vccz .LBB0_111

; __device__ __forceinline__ void norm_phase(const float* xL, const float* xC, const float* gain, const float* modl  , int ishift, bf16_t* H, int nrows,
;                                            const float* part, int nsplit, const float* pgate  , float pscale, float* xCw) {
;     ...
;     if (nsplit > 0) for (int row = RL + gw; row < nrows; row += NGW) {
;         f32x4 v[4];
;         const float* xr = xC + (size_t)(row - RL) * DM;
; #pragma unroll
;         for (int j = 0; j < 4; ++j) v[j] = *(const f32x4*)(xr + 4 * lane + 256 * j);
; #pragma unroll
;         for (int j = 0; j < 4; ++j) {
;             f32x4 pv[11];
; #pragma unroll
;             for (int ks = 0; ks < 11; ++ks) if (ks < nsplit) pv[ks] = *(const f32x4*)(part + ((size_t)ks * RC + (row - RL)) * DM + 4 * lane + 256 * j);
;             f32x4 sum = {0.f, 0.f, 0.f, 0.f};
; #pragma unroll
;             for (int ks = 0; ks < 11; ++ks) if (ks < nsplit) sum += pv[ks];
;             v[j] += sum * (*(const f32x4*)(pgate + 4 * lane + 256 * j) * pscale);
;             *(f32x4*)(xCw + (size_t)(row - RL) * DM + 4 * lane + 256 * j) = v[j];
.LBB0_114:
	v_lshl_add_u64 v[20:21], s[96:97], 0, v[88:89]
	v_add_co_u32_e32 v90, vcc, 0x12000000, v20
	s_add_i32 s0, s0, s88
	s_nop 0
	v_addc_co_u32_e32 v91, vcc, 0, v21, vcc
	v_add_co_u32_e32 v36, vcc, 0x21b80000, v20
	v_lshl_add_u64 v[88:89], v[88:89], 0, s[64:65]
	s_nop 0
	v_addc_co_u32_e32 v37, vcc, 0, v21, vcc
	v_add_co_u32_e32 v38, vcc, 0x21f80000, v20
	global_load_dwordx4 v[16:19], v[90:91], off
	global_load_dwordx4 v[24:27], v[80:81], off offset:-4096
	global_load_dwordx4 v[28:31], v[36:37], off
	v_addc_co_u32_e32 v39, vcc, 0, v21, vcc
	v_add_co_u32_e32 v44, vcc, 0x22380000, v20
	global_load_dwordx4 v[32:35], v[38:39], off
	s_nop 0
	v_addc_co_u32_e32 v45, vcc, 0, v21, vcc
	v_add_co_u32_e32 v46, vcc, 0x22780000, v20
	global_load_dwordx4 v[40:43], v[44:45], off
	s_nop 0
	v_addc_co_u32_e32 v47, vcc, 0, v21, vcc
	v_add_co_u32_e32 v48, vcc, 0x22b80000, v20
	global_load_dwordx4 v[52:55], v[46:47], off
	s_nop 0
	v_addc_co_u32_e32 v49, vcc, 0, v21, vcc
	v_add_co_u32_e32 v50, vcc, 0x22f80000, v20
	global_load_dwordx4 v[60:63], v[48:49], off
	s_nop 0
	v_addc_co_u32_e32 v51, vcc, 0, v21, vcc
	v_add_co_u32_e32 v56, vcc, 0x23380000, v20
	global_load_dwordx4 v[68:71], v[50:51], off
	s_nop 0
	v_addc_co_u32_e32 v57, vcc, 0, v21, vcc
	v_add_co_u32_e32 v58, vcc, 0x23780000, v20
	global_load_dwordx4 v[74:77], v[56:57], off
	s_nop 0
	v_addc_co_u32_e32 v59, vcc, 0, v21, vcc
	v_add_co_u32_e32 v64, vcc, 0x23b80000, v20
	global_load_dwordx4 v[92:95], v[58:59], off
	s_nop 0
	v_addc_co_u32_e32 v65, vcc, 0, v21, vcc
	v_add_co_u32_e32 v66, vcc, 0x23f80000, v20
	global_load_dwordx4 v[96:99], v[64:65], off
	s_nop 0
	v_addc_co_u32_e32 v67, vcc, 0, v21, vcc
	global_load_dwordx4 v[100:103], v[66:67], off
	v_add_co_u32_e32 v72, vcc, 0x24380000, v20
	s_cmp_lt_i32 s0, 0x8400
	s_nop 0
	v_addc_co_u32_e32 v73, vcc, 0, v21, vcc
	global_load_dwordx4 v[104:107], v[72:73], off
	global_load_dwordx4 v[20:23], v[90:91], off offset:1024
	global_load_dwordx4 v[108:111], v[36:37], off offset:1024
	global_load_dwordx4 v[112:115], v[38:39], off offset:1024
	global_load_dwordx4 v[116:119], v[44:45], off offset:1024
	global_load_dwordx4 v[120:123], v[46:47], off offset:1024
	global_load_dwordx4 v[124:127], v[48:49], off offset:1024
	s_waitcnt vmcnt(17)
	v_mul_f32_e32 v78, 0.5, v26
	v_mul_f32_e32 v79, 0.5, v27
	v_mul_f32_e32 v128, 0.5, v24
	v_mul_f32_e32 v129, 0.5, v25
	s_waitcnt vmcnt(16)
	v_add_f32_e32 v24, 0, v30
	v_add_f32_e32 v25, 0, v31
	v_add_f32_e32 v26, 0, v28
	v_add_f32_e32 v27, 0, v29
	s_waitcnt vmcnt(15)
	v_add_f32_e32 v24, v24, v34
	v_add_f32_e32 v25, v25, v35
	v_add_f32_e32 v26, v26, v32
	v_add_f32_e32 v27, v27, v33
	global_load_dwordx4 v[32:35], v[72:73], off offset:1024
	s_waitcnt vmcnt(15)
	v_add_f32_e32 v24, v24, v42
	v_add_f32_e32 v25, v25, v43
	v_add_f32_e32 v26, v26, v40
	v_add_f32_e32 v27, v27, v41
	global_load_dwordx4 v[40:43], v[50:51], off offset:1024
	s_waitcnt vmcnt(15)
	v_add_f32_e32 v24, v24, v54
	v_add_f32_e32 v25, v25, v55
	v_add_f32_e32 v26, v26, v52
	v_add_f32_e32 v27, v27, v53
	global_load_dwordx4 v[52:55], v[56:57], off offset:1024
	s_waitcnt vmcnt(15)
	v_add_f32_e32 v24, v24, v62
	v_add_f32_e32 v25, v25, v63
	v_add_f32_e32 v26, v26, v60
	v_add_f32_e32 v27, v27, v61
	global_load_dwordx4 v[60:63], v[58:59], off offset:1024
	s_waitcnt vmcnt(15)
	v_add_f32_e32 v24, v24, v70
	v_add_f32_e32 v25, v25, v71
	v_add_f32_e32 v26, v26, v68
	v_add_f32_e32 v27, v27, v69
	global_load_dwordx4 v[68:71], v[64:65], off offset:1024
	s_waitcnt vmcnt(15)
	v_add_f32_e32 v28, v24, v76
	v_add_f32_e32 v29, v25, v77
	v_add_f32_e32 v30, v26, v74
	v_add_f32_e32 v31, v27, v75
	global_load_dwordx4 v[24:27], v[66:67], off offset:1024
	s_waitcnt vmcnt(15)
	v_add_f32_e32 v28, v28, v94
	v_add_f32_e32 v29, v29, v95
	v_add_f32_e32 v30, v30, v92
	v_add_f32_e32 v31, v31, v93
	s_waitcnt vmcnt(14)
	v_add_f32_e32 v28, v28, v98
	v_add_f32_e32 v29, v29, v99
	v_add_f32_e32 v30, v30, v96
	v_add_f32_e32 v31, v31, v97
	s_waitcnt vmcnt(13)
	v_add_f32_e32 v28, v28, v102
	v_add_f32_e32 v29, v29, v103
	v_add_f32_e32 v30, v30, v100
	v_add_f32_e32 v31, v31, v101
	s_waitcnt vmcnt(12)
	v_add_f32_e32 v28, v28, v106
	v_add_f32_e32 v29, v29, v107
	v_add_f32_e32 v30, v30, v104
	v_add_f32_e32 v31, v31, v105
	v_fma_f32 v18, v28, v78, v18
	v_fma_f32 v19, v29, v79, v19
	v_fma_f32 v16, v30, v128, v16
	v_fma_f32 v17, v31, v129, v17
	global_store_dwordx4 v[90:91], v[16:19], off
	global_load_dwordx4 v[92:95], v[80:81], off offset:-3072
	global_load_dwordx4 v[28:31], v[90:91], off offset:2048
	global_load_dwordx4 v[96:99], v[36:37], off offset:2048
	global_load_dwordx4 v[100:103], v[38:39], off offset:2048
	s_waitcnt vmcnt(15)
	v_add_f32_e32 v74, 0, v110
	v_add_f32_e32 v75, 0, v111
	v_add_f32_e32 v76, 0, v108
	v_add_f32_e32 v77, 0, v109
	global_load_dwordx4 v[104:107], v[44:45], off offset:2048
	global_load_dwordx4 v[108:111], v[46:47], off offset:2048
	s_waitcnt vmcnt(16)
	v_add_f32_e32 v74, v74, v114
	v_add_f32_e32 v75, v75, v115
	v_add_f32_e32 v76, v76, v112
	v_add_f32_e32 v77, v77, v113
	s_waitcnt vmcnt(15)
	v_add_f32_e32 v74, v74, v118
	v_add_f32_e32 v75, v75, v119
	v_add_f32_e32 v76, v76, v116
	v_add_f32_e32 v77, v77, v117
	global_load_dwordx4 v[112:115], v[48:49], off offset:2048
	s_waitcnt vmcnt(15)
	v_add_f32_e32 v74, v74, v122
	v_add_f32_e32 v75, v75, v123
	v_add_f32_e32 v116, v76, v120
	v_add_f32_e32 v117, v77, v121
	global_load_dwordx4 v[76:79], v[50:51], off offset:2048
	s_waitcnt vmcnt(15)
	v_add_f32_e32 v74, v74, v126
	v_add_f32_e32 v75, v75, v127
	v_add_f32_e32 v120, v116, v124
	v_add_f32_e32 v121, v117, v125
	global_load_dwordx4 v[116:119], v[56:57], off offset:2048
	global_load_dwordx4 v[124:127], v[64:65], off offset:2048
	global_load_dwordx4 v[128:131], v[66:67], off offset:2048
	global_load_dwordx4 v[132:135], v[72:73], off offset:2048
	s_waitcnt vmcnt(17)
; __device__ __forceinline__ void norm_phase(const float* xL, const float* xC, const float* gain, const float* modl  , int ishift, bf16_t* H, int nrows,
;                                            const float* part, int nsplit, const float* pgate  , float pscale, float* xCw) {
;     ...
;     if (nsplit > 0) for (int row = RL + gw; row < nrows; row += NGW) {
;         f32x4 v[4];
;         const float* xr = xC + (size_t)(row - RL) * DM;
; #pragma unroll
;         for (int j = 0; j < 4; ++j) v[j] = *(const f32x4*)(xr + 4 * lane + 256 * j);
; #pragma unroll
;         for (int j = 0; j < 4; ++j) {
;             f32x4 pv[11];
; #pragma unroll
;             for (int ks = 0; ks < 11; ++ks) if (ks < nsplit) pv[ks] = *(const f32x4*)(part + ((size_t)ks * RC + (row - RL)) * DM + 4 * lane + 256 * j);
;             f32x4 sum = {0.f, 0.f, 0.f, 0.f};
; #pragma unroll
;             for (int ks = 0; ks < 11; ++ks) if (ks < nsplit) sum += pv[ks];
;             v[j] += sum * (*(const f32x4*)(pgate + 4 * lane + 256 * j) * pscale);
;             *(f32x4*)(xCw + (size_t)(row - RL) * DM + 4 * lane + 256 * j) = v[j];
	v_add_f32_e32 v42, v74, v42
	v_add_f32_e32 v43, v75, v43
	v_add_f32_e32 v40, v120, v40
	v_add_f32_e32 v41, v121, v41
	global_load_dwordx4 v[120:123], v[58:59], off offset:2048
	s_waitcnt vmcnt(17)
	v_add_f32_e32 v42, v42, v54
	v_add_f32_e32 v43, v43, v55
	v_add_f32_e32 v40, v40, v52
	v_add_f32_e32 v41, v41, v53
	s_waitcnt vmcnt(16)
	v_add_f32_e32 v42, v42, v62
	v_add_f32_e32 v43, v43, v63
	v_add_f32_e32 v40, v40, v60
	v_add_f32_e32 v41, v41, v61
	s_waitcnt vmcnt(15)
	v_add_f32_e32 v42, v42, v70
	v_add_f32_e32 v43, v43, v71
	v_add_f32_e32 v40, v40, v68
	v_add_f32_e32 v41, v41, v69
	s_waitcnt vmcnt(14)
	v_add_f32_e32 v26, v42, v26
	v_add_f32_e32 v27, v43, v27
	v_add_f32_e32 v24, v40, v24
	v_add_f32_e32 v25, v41, v25
	v_add_f32_e32 v26, v26, v34
	v_add_f32_e32 v27, v27, v35
	v_add_f32_e32 v24, v24, v32
	v_add_f32_e32 v25, v25, v33
	s_waitcnt vmcnt(12)
	v_mul_f32_e32 v32, 0.5, v94
	v_mul_f32_e32 v33, 0.5, v95
	v_mul_f32_e32 v34, 0.5, v92
	v_mul_f32_e32 v35, 0.5, v93
	v_fma_f32 v22, v26, v32, v22
	v_fma_f32 v23, v27, v33, v23
	v_fma_f32 v20, v24, v34, v20
	v_fma_f32 v21, v25, v35, v21
	global_store_dwordx4 v[90:91], v[20:23], off offset:1024
	global_load_dwordx4 v[92:95], v[80:81], off offset:-2048
	global_load_dwordx4 v[24:27], v[90:91], off offset:3072
	global_load_dwordx4 v[40:43], v[36:37], off offset:3072
	s_nop 0
	global_load_dwordx4 v[36:39], v[38:39], off offset:3072
	s_nop 0
	global_load_dwordx4 v[32:35], v[44:45], off offset:3072
	s_waitcnt vmcnt(16)
	v_add_f32_e32 v52, 0, v98
	v_add_f32_e32 v53, 0, v99
	v_add_f32_e32 v54, 0, v96
	v_add_f32_e32 v55, 0, v97
	s_waitcnt vmcnt(15)
	v_add_f32_e32 v60, v52, v102
	v_add_f32_e32 v61, v53, v103
	v_add_f32_e32 v62, v54, v100
	v_add_f32_e32 v63, v55, v101
	s_waitcnt vmcnt(14)
	v_add_f32_e32 v68, v60, v106
	v_add_f32_e32 v69, v61, v107
	v_add_f32_e32 v70, v62, v104
	v_add_f32_e32 v71, v63, v105
	s_waitcnt vmcnt(13)
	v_add_f32_e32 v74, v68, v110
	v_add_f32_e32 v75, v69, v111
	v_add_f32_e32 v96, v70, v108
	v_add_f32_e32 v97, v71, v109
	s_waitcnt vmcnt(12)
	v_add_f32_e32 v98, v74, v114
	v_add_f32_e32 v99, v75, v115
	v_add_f32_e32 v96, v96, v112
	v_add_f32_e32 v97, v97, v113
	s_waitcnt vmcnt(11)
	v_add_f32_e32 v78, v98, v78
	v_add_f32_e32 v79, v99, v79
	v_add_f32_e32 v76, v96, v76
	v_add_f32_e32 v77, v97, v77
	global_load_dwordx4 v[44:47], v[46:47], off offset:3072
	s_waitcnt vmcnt(11)
	v_add_f32_e32 v78, v78, v118
	v_add_f32_e32 v79, v79, v119
	v_add_f32_e32 v76, v76, v116
	v_add_f32_e32 v77, v77, v117
	global_load_dwordx4 v[52:55], v[48:49], off offset:3072
	s_nop 0
	global_load_dwordx4 v[48:51], v[50:51], off offset:3072
	s_nop 0
	global_load_dwordx4 v[60:63], v[56:57], off offset:3072
	s_nop 0
	global_load_dwordx4 v[56:59], v[58:59], off offset:3072
	s_nop 0
	global_load_dwordx4 v[68:71], v[64:65], off offset:3072
	s_nop 0
	global_load_dwordx4 v[64:67], v[66:67], off offset:3072
	s_waitcnt vmcnt(13)
	v_add_f32_e32 v78, v78, v122
	v_add_f32_e32 v79, v79, v123
	v_add_f32_e32 v76, v76, v120
	v_add_f32_e32 v77, v77, v121
	v_add_f32_e32 v78, v78, v126
	v_add_f32_e32 v79, v79, v127
	v_add_f32_e32 v76, v76, v124
	v_add_f32_e32 v77, v77, v125
	v_add_f32_e32 v78, v78, v130
	v_add_f32_e32 v79, v79, v131
	v_add_f32_e32 v76, v76, v128
	v_add_f32_e32 v77, v77, v129
	v_add_f32_e32 v78, v78, v134
	v_add_f32_e32 v79, v79, v135
	v_add_f32_e32 v76, v76, v132
	v_add_f32_e32 v77, v77, v133
	global_load_dwordx4 v[72:75], v[72:73], off offset:3072
	s_waitcnt vmcnt(12)
	v_mul_f32_e32 v94, 0.5, v94
	v_mul_f32_e32 v95, 0.5, v95
	v_mul_f32_e32 v92, 0.5, v92
	v_mul_f32_e32 v93, 0.5, v93
	v_fma_f32 v30, v78, v94, v30
	v_fma_f32 v31, v79, v95, v31
	v_fma_f32 v28, v76, v92, v28
	v_fma_f32 v29, v77, v93, v29
	global_store_dwordx4 v[90:91], v[28:31], off offset:2048
	global_load_dwordx4 v[76:79], v[80:81], off offset:-1024
	s_waitcnt vmcnt(12)
	v_add_f32_e32 v42, 0, v42
	v_add_f32_e32 v43, 0, v43
	v_add_f32_e32 v40, 0, v40
	v_add_f32_e32 v41, 0, v41
	s_waitcnt vmcnt(11)
	v_add_f32_e32 v38, v42, v38
	v_add_f32_e32 v39, v43, v39
	v_add_f32_e32 v36, v40, v36
	v_add_f32_e32 v37, v41, v37
	s_waitcnt vmcnt(10)
	v_add_f32_e32 v34, v38, v34
	v_add_f32_e32 v35, v39, v35
	v_add_f32_e32 v32, v36, v32
	v_add_f32_e32 v33, v37, v33
	v_mul_f32_e32 v36, v17, v17
	v_mul_f32_e32 v37, v19, v19
	v_fmac_f32_e32 v36, v16, v16
	v_fmac_f32_e32 v37, v18, v18
	v_add_f32_e32 v36, v36, v37
	s_waitcnt vmcnt(9)
	v_add_f32_e32 v34, v34, v46
	v_add_f32_e32 v35, v35, v47
	v_add_f32_e32 v32, v32, v44
	v_add_f32_e32 v33, v33, v45
	s_waitcnt vmcnt(8)
	v_add_f32_e32 v34, v34, v54
	v_add_f32_e32 v35, v35, v55
	v_add_f32_e32 v32, v32, v52
	v_add_f32_e32 v33, v33, v53
	v_mul_f32_e32 v37, v21, v21
	v_mul_f32_e32 v38, v23, v23
	s_waitcnt vmcnt(7)
	v_add_f32_e32 v34, v34, v50
	v_add_f32_e32 v35, v35, v51
	v_add_f32_e32 v32, v32, v48
	v_add_f32_e32 v33, v33, v49
	v_fmac_f32_e32 v37, v20, v20
	v_fmac_f32_e32 v38, v22, v22
	s_waitcnt vmcnt(6)
	v_add_f32_e32 v34, v34, v62
	v_add_f32_e32 v35, v35, v63
	v_add_f32_e32 v32, v32, v60
	v_add_f32_e32 v33, v33, v61
	v_add_f32_e32 v37, v37, v38
	s_waitcnt vmcnt(5)
; __device__ __forceinline__ unsigned cvt_pk_bf16(float lo, float hi) { const f32x2 v = {lo, hi}; const bf16x2_t b = __builtin_convertvector(v, bf16x2_t); return __builtin_bit_cast(unsigned, b); }
; __device__ __forceinline__ float wave_sum(float v) { return xadd32(sum32(v)); }
; __device__ __forceinline__ void norm_row(const f32x4 (&v)[4], const f32x4 (&gn)[4], const float* sh, bf16_t* hrow, int lane) {
;     const float* scl = sh + 1024;
;     f32x4 sv[4], cv[4];
; #pragma unroll
;     for (int j = 0; j < 4; ++j) { sv[j] = *(const f32x4*)(sh + 4 * lane + 256 * j); cv[j] = *(const f32x4*)(scl + 4 * lane + 256 * j); }
;     float ss = 0.f;
; #pragma unroll
;     for (int j = 0; j < 4; ++j) ss += (v[j][0] * v[j][0] + v[j][1] * v[j][1]) + (v[j][2] * v[j][2] + v[j][3] * v[j][3]);
;     const float rstd = __builtin_amdgcn_rsqf(wave_sum(ss) * (1.0f / DM) + EPS);
; #pragma unroll
;     for (int j = 0; j < 4; ++j) {
;         const f32x4 y = v[j] * rstd * gn[j] * (cv[j] + 1.0f) + sv[j];
;         u32x2 w; w.x = cvt_pk_bf16(y[0], y[1]); w.y = cvt_pk_bf16(y[2], y[3]);
;         *(u32x2*)(hrow + 4 * lane + 256 * j) = w;
;     }
; }
; __device__ __forceinline__ void norm_phase(const float* xL, const float* xC, const float* gain, const float* modl  , int ishift, bf16_t* H, int nrows,
;                                            const float* part, int nsplit, const float* pgate  , float pscale, float* xCw) {
;     ...
;     if (nsplit > 0) for (int row = RL + gw; row < nrows; row += NGW) {
;         f32x4 v[4];
;         const float* xr = xC + (size_t)(row - RL) * DM;
; #pragma unroll
;         for (int j = 0; j < 4; ++j) v[j] = *(const f32x4*)(xr + 4 * lane + 256 * j);
; #pragma unroll
;         for (int j = 0; j < 4; ++j) {
;             f32x4 pv[11];
; #pragma unroll
;             for (int ks = 0; ks < 11; ++ks) if (ks < nsplit) pv[ks] = *(const f32x4*)(part + ((size_t)ks * RC + (row - RL)) * DM + 4 * lane + 256 * j);
;             f32x4 sum = {0.f, 0.f, 0.f, 0.f};
; #pragma unroll
;             for (int ks = 0; ks < 11; ++ks) if (ks < nsplit) sum += pv[ks];
;             v[j] += sum * (*(const f32x4*)(pgate + 4 * lane + 256 * j) * pscale);
;             *(f32x4*)(xCw + (size_t)(row - RL) * DM + 4 * lane + 256 * j) = v[j];
;         }
;         norm_row(v, gn, modl + (size_t)4 * 9216 + ishift * 1024, H + (size_t)row * DM, lane);
	v_add_f32_e32 v34, v34, v58
	v_add_f32_e32 v35, v35, v59
	v_add_f32_e32 v32, v32, v56
	v_add_f32_e32 v33, v33, v57
	v_add_f32_e32 v36, v36, v37
	v_mul_f32_e32 v37, v29, v29
	v_mul_f32_e32 v38, v31, v31
	s_waitcnt vmcnt(4)
	v_add_f32_e32 v34, v34, v70
	v_add_f32_e32 v35, v35, v71
	v_add_f32_e32 v32, v32, v68
	v_add_f32_e32 v33, v33, v69
	v_fmac_f32_e32 v37, v28, v28
	v_fmac_f32_e32 v38, v30, v30
	s_waitcnt vmcnt(3)
	v_add_f32_e32 v34, v34, v66
	v_add_f32_e32 v35, v35, v67
	v_add_f32_e32 v32, v32, v64
	v_add_f32_e32 v33, v33, v65
	v_add_f32_e32 v37, v37, v38
	v_add_f32_e32 v64, v36, v37
	v_lshl_add_u64 v[92:93], s[96:97], 0, v[86:87]
	v_add_co_u32_e32 v92, vcc, s47, v92
	v_lshl_add_u64 v[86:87], v[86:87], 0, s[92:93]
	s_nop 0
	v_addc_co_u32_e32 v93, vcc, 0, v93, vcc
	s_waitcnt vmcnt(2)
	v_add_f32_e32 v34, v34, v74
	v_add_f32_e32 v35, v35, v75
	v_add_f32_e32 v32, v32, v72
	v_add_f32_e32 v33, v33, v73
	s_waitcnt vmcnt(0)
	v_mul_f32_e32 v36, 0.5, v78
	v_mul_f32_e32 v37, 0.5, v79
	v_mul_f32_e32 v38, 0.5, v76
	v_mul_f32_e32 v39, 0.5, v77
	v_fma_f32 v26, v34, v36, v26
	v_fma_f32 v27, v35, v37, v27
	v_fma_f32 v24, v32, v38, v24
	v_fma_f32 v25, v33, v39, v25
	global_store_dwordx4 v[90:91], v[24:27], off offset:3072
	global_load_dwordx4 v[32:35], v[84:85], off
	global_load_dwordx4 v[36:39], v[84:85], off offset:1024
	global_load_dwordx4 v[40:43], v[84:85], off offset:2048
	global_load_dwordx4 v[44:47], v[84:85], off offset:3072
	global_load_dwordx4 v[48:51], v[82:83], off
	global_load_dwordx4 v[52:55], v[82:83], off offset:1024
	global_load_dwordx4 v[56:59], v[82:83], off offset:2048
	global_load_dwordx4 v[60:63], v[82:83], off offset:3072
	v_mul_f32_e32 v65, v25, v25
	v_mul_f32_e32 v66, v27, v27
	v_fmac_f32_e32 v65, v24, v24
	v_fmac_f32_e32 v66, v26, v26
	v_add_f32_e32 v65, v65, v66
	v_add_f32_e32 v64, v64, v65
	ds_swizzle_b32 v65, v64 offset:swizzle(SWAP,1)
	s_waitcnt lgkmcnt(0)
	v_add_f32_e32 v64, v64, v65
	ds_swizzle_b32 v65, v64 offset:swizzle(SWAP,2)
	s_waitcnt lgkmcnt(0)
	v_add_f32_e32 v64, v64, v65
	ds_swizzle_b32 v65, v64 offset:swizzle(SWAP,4)
	s_waitcnt lgkmcnt(0)
	v_add_f32_e32 v64, v64, v65
	ds_swizzle_b32 v65, v64 offset:swizzle(SWAP,8)
	s_waitcnt lgkmcnt(0)
	v_add_f32_e32 v64, v64, v65
	ds_swizzle_b32 v65, v64 offset:swizzle(SWAP,16)
	s_waitcnt lgkmcnt(0)
	v_add_f32_e32 v64, v64, v65
	v_mov_b32_e32 v65, v64
	s_nop 1
	v_permlane32_swap_b32_e32 v64, v65
	v_add_f32_e32 v64, v64, v65
	v_fmamk_f32 v64, v64, 0x3a800000, v193
	v_rsq_f32_e32 v64, v64
	s_waitcnt vmcnt(7)
	v_add_f32_e32 v34, 1.0, v34
	v_add_f32_e32 v35, 1.0, v35
	v_mul_f32_e32 v18, v18, v64
	v_mul_f32_e32 v19, v19, v64
	v_mul_f32_e32 v16, v16, v64
	v_mul_f32_e32 v17, v17, v64
	v_mul_f32_e32 v22, v22, v64
	v_mul_f32_e32 v23, v23, v64
	v_mul_f32_e32 v20, v20, v64
	v_mul_f32_e32 v21, v21, v64
	v_mul_f32_e32 v30, v30, v64
	v_mul_f32_e32 v31, v31, v64
	v_mul_f32_e32 v28, v28, v64
	v_mul_f32_e32 v29, v29, v64
	v_mul_f32_e32 v26, v26, v64
	v_mul_f32_e32 v27, v27, v64
	v_mul_f32_e32 v24, v24, v64
	v_mul_f32_e32 v25, v25, v64
	v_mul_f32_e32 v16, v0, v16
	v_mul_f32_e32 v17, v1, v17
	v_mul_f32_e32 v18, v2, v18
	v_mul_f32_e32 v19, v3, v19
	v_add_f32_e32 v32, 1.0, v32
	v_add_f32_e32 v33, 1.0, v33
	v_mul_f32_e32 v20, v4, v20
	v_mul_f32_e32 v21, v5, v21
	v_mul_f32_e32 v22, v6, v22
	v_mul_f32_e32 v23, v7, v23
	v_mul_f32_e32 v28, v8, v28
	v_mul_f32_e32 v29, v9, v29
	v_mul_f32_e32 v30, v10, v30
	v_mul_f32_e32 v31, v11, v31
	v_mul_f32_e32 v24, v12, v24
	v_mul_f32_e32 v25, v13, v25
	v_mul_f32_e32 v26, v14, v26
	v_mul_f32_e32 v27, v15, v27
	s_waitcnt vmcnt(6)
	v_add_f32_e32 v38, 1.0, v38
	v_add_f32_e32 v39, 1.0, v39
	v_add_f32_e32 v36, 1.0, v36
	v_add_f32_e32 v37, 1.0, v37
	s_waitcnt vmcnt(5)
	v_add_f32_e32 v42, 1.0, v42
	v_add_f32_e32 v43, 1.0, v43
	v_add_f32_e32 v40, 1.0, v40
	v_add_f32_e32 v41, 1.0, v41
	s_waitcnt vmcnt(4)
	v_add_f32_e32 v46, 1.0, v46
	v_add_f32_e32 v47, 1.0, v47
	v_add_f32_e32 v44, 1.0, v44
	v_add_f32_e32 v45, 1.0, v45
	s_waitcnt vmcnt(3)
	v_fma_f32 v18, v34, v18, v50
	v_fma_f32 v19, v35, v19, v51
	v_fma_f32 v16, v32, v16, v48
	v_fma_f32 v17, v33, v17, v49
	s_waitcnt vmcnt(2)
	v_fma_f32 v22, v38, v22, v54
	v_fma_f32 v23, v39, v23, v55
	v_fma_f32 v20, v36, v20, v52
	v_fma_f32 v21, v37, v21, v53
	s_waitcnt vmcnt(1)
	v_fma_f32 v30, v42, v30, v58
	v_fma_f32 v31, v43, v31, v59
	v_fma_f32 v28, v40, v28, v56
	v_fma_f32 v29, v41, v29, v57
	s_waitcnt vmcnt(0)
	v_fma_f32 v26, v46, v26, v62
	v_fma_f32 v27, v47, v27, v63
	v_fma_f32 v24, v44, v24, v60
	v_fma_f32 v25, v45, v25, v61
	v_cvt_pk_bf16_f32 v16, v16, v17
	v_cvt_pk_bf16_f32 v17, v18, v19
	v_cvt_pk_bf16_f32 v18, v20, v21
	v_cvt_pk_bf16_f32 v19, v22, v23
	v_cvt_pk_bf16_f32 v20, v28, v29
	v_cvt_pk_bf16_f32 v21, v30, v31
	v_cvt_pk_bf16_f32 v22, v24, v25
	v_cvt_pk_bf16_f32 v23, v26, v27
	global_store_dwordx2 v[92:93], v[16:17], off
	global_store_dwordx2 v[92:93], v[18:19], off offset:512
	global_store_dwordx2 v[92:93], v[20:21], off offset:1024
	global_store_dwordx2 v[92:93], v[22:23], off offset:1536
	s_cbranch_scc1 .LBB0_114

; __device__ __forceinline__ unsigned cvt_pk_bf16(float lo, float hi) { const f32x2 v = {lo, hi}; const bf16x2_t b = __builtin_convertvector(v, bf16x2_t); return __builtin_bit_cast(unsigned, b); }
; __device__ __forceinline__ float fast_exp2(float x) { return __builtin_amdgcn_exp2f(x); }
; __device__ __forceinline__ float fast_rcp(float x) { return __builtin_amdgcn_rcpf(x); }
; __device__ __forceinline__ float silu_f(float x) { return x * fast_rcp(1.0f + fast_exp2(-x * LOG2E)); }
;     __device__ __forceinline__ void operator()(const f32x4 (&acc)[2][2][4][2], const Unit& u, int wr, int wc, int fr, int fq) const {
;         asm volatile("" : "+v"(fr), "+v"(fq));
;         const int row0 = u.pm * BM + wr * 64 + fr; const int col0 = u.pn * 128 + wc * 32 + 8 * fq;
; #pragma unroll
;         for (int ai = 0; ai < 2; ++ai)
; #pragma unroll
;             for (int m = 0; m < 4; ++m) {
;                 bf16_t* rowp = act + (size_t)(row0 + ai * HALF + m * 16) * FF + col0;
;                 const f32x4 g0 = acc[ai][0][m][0], g1 = acc[ai][0][m][1], u0 = acc[ai][1][m][0], u1 = acc[ai][1][m][1];
;                 u32x4 w;
;                 w.x = cvt_pk_bf16(silu_f(g0[0]) * u0[0], silu_f(g0[1]) * u0[1]); w.y = cvt_pk_bf16(silu_f(g0[2]) * u0[2], silu_f(g0[3]) * u0[3]);
;                 w.z = cvt_pk_bf16(silu_f(g1[0]) * u1[0], silu_f(g1[1]) * u1[1]); w.w = cvt_pk_bf16(silu_f(g1[2]) * u1[2], silu_f(g1[3]) * u1[3]);
;                 *(u32x4*)rowp = w;
;             }
.LBB0_179:
	v_mul_f32_e32 v147, 0xbfb8aa3b, v124
	v_exp_f32_e32 v147, v147
	s_lshl_b32 s11, s67, 8
	v_mov_b32_e32 v138, v142
	v_mov_b32_e32 v139, v143
	v_add_f32_e32 v147, 1.0, v147
	v_rcp_f32_e32 v150, v147
	v_mul_f32_e32 v147, 0xbfb8aa3b, v125
	v_exp_f32_e32 v147, v147
	s_add_i32 s11, s11, s47
	s_andn2_b64 vcc, exec, s[34:35]
	v_add_f32_e32 v147, 1.0, v147
	v_rcp_f32_e32 v151, v147
	v_add_u32_e32 v146, s11, v138
	s_lshl_b32 s11, s66, 7
	s_or_b32 s11, s11, s56
	v_mul_f32_e32 v124, v124, v150
	v_mul_f32_e32 v125, v125, v151
	v_lshl_add_u32 v140, v139, 3, s11
	v_mul_f32_e32 v120, v120, v124
	v_mul_f32_e32 v121, v121, v125
	v_ashrrev_i32_e32 v141, 31, v140
	v_cvt_pk_bf16_f32 v120, v120, v121
	v_mul_f32_e32 v121, 0xbfb8aa3b, v126
	v_exp_f32_e32 v121, v121
	v_mov_b64_e32 v[138:139], s[90:91]
	v_mad_i64_i32 v[148:149], s[18:19], v146, s44, v[138:139]
	v_add_f32_e32 v121, 1.0, v121
	v_rcp_f32_e32 v124, v121
	v_mul_f32_e32 v121, 0xbfb8aa3b, v127
	v_exp_f32_e32 v121, v121
	v_lshlrev_b64 v[140:141], 1, v[140:141]
	v_lshl_add_u64 v[148:149], v[148:149], 0, v[140:141]
	v_add_f32_e32 v121, 1.0, v121
	v_rcp_f32_e32 v125, v121
	s_nop 0
	v_mul_f32_e32 v124, v126, v124
	v_mul_f32_e32 v125, v127, v125
	s_nop 0
	v_mul_f32_e32 v122, v122, v124
	v_mul_f32_e32 v123, v123, v125
	s_nop 0
	v_cvt_pk_bf16_f32 v121, v122, v123
	v_mul_f32_e32 v122, 0xbfb8aa3b, v116
	v_mul_f32_e32 v123, 0xbfb8aa3b, v117
	v_exp_f32_e32 v122, v122
	v_exp_f32_e32 v123, v123
	v_add_f32_e32 v122, 1.0, v122
	v_add_f32_e32 v123, 1.0, v123
	v_rcp_f32_e32 v122, v122
	v_rcp_f32_e32 v123, v123
	s_nop 0
	v_mul_f32_e32 v116, v116, v122
	v_mul_f32_e32 v117, v117, v123
	s_nop 0
	v_mul_f32_e32 v112, v112, v116
	v_mul_f32_e32 v113, v113, v117
	s_nop 0
	v_cvt_pk_bf16_f32 v122, v112, v113
	v_mul_f32_e32 v112, 0xbfb8aa3b, v118
	v_mul_f32_e32 v113, 0xbfb8aa3b, v119
	v_exp_f32_e32 v112, v112
	v_exp_f32_e32 v113, v113
	v_add_f32_e32 v112, 1.0, v112
	v_add_f32_e32 v113, 1.0, v113
	v_rcp_f32_e32 v112, v112
	v_rcp_f32_e32 v113, v113
	s_nop 0
	v_mul_f32_e32 v112, v118, v112
	v_mul_f32_e32 v113, v119, v113
	s_nop 0
	v_mul_f32_e32 v112, v114, v112
	v_mul_f32_e32 v113, v115, v113
	v_mul_f32_e32 v114, 0xbfb8aa3b, v108
	v_mul_f32_e32 v115, 0xbfb8aa3b, v109
	v_exp_f32_e32 v114, v114
	v_exp_f32_e32 v115, v115
	v_cvt_pk_bf16_f32 v123, v112, v113
	v_add_u32_e32 v112, 16, v146
	v_add_f32_e32 v114, 1.0, v114
	v_add_f32_e32 v115, 1.0, v115
	v_rcp_f32_e32 v114, v114
	v_rcp_f32_e32 v115, v115
	v_mad_i64_i32 v[112:113], s[18:19], v112, s44, v[138:139]
	v_lshl_add_u64 v[112:113], v[112:113], 0, v[140:141]
	v_mul_f32_e32 v108, v108, v114
	v_mul_f32_e32 v109, v109, v115
	global_store_dwordx4 v[148:149], v[120:123], off
	v_mul_f32_e32 v104, v104, v108
	v_mul_f32_e32 v105, v105, v109
	s_nop 0
	v_cvt_pk_bf16_f32 v104, v104, v105
	v_mul_f32_e32 v105, 0xbfb8aa3b, v110
	v_exp_f32_e32 v105, v105
	s_nop 0
	v_add_f32_e32 v105, 1.0, v105
	v_rcp_f32_e32 v108, v105
	v_mul_f32_e32 v105, 0xbfb8aa3b, v111
	v_exp_f32_e32 v105, v105
	s_nop 0
	v_add_f32_e32 v105, 1.0, v105
	v_rcp_f32_e32 v109, v105
	s_nop 0
	v_mul_f32_e32 v108, v110, v108
	v_mul_f32_e32 v109, v111, v109
	s_nop 0
	v_mul_f32_e32 v106, v106, v108
	v_mul_f32_e32 v107, v107, v109
	s_nop 0
	v_cvt_pk_bf16_f32 v105, v106, v107
	v_mul_f32_e32 v106, 0xbfb8aa3b, v100
	v_mul_f32_e32 v107, 0xbfb8aa3b, v101
	v_exp_f32_e32 v106, v106
	v_exp_f32_e32 v107, v107
	v_add_f32_e32 v106, 1.0, v106
	v_add_f32_e32 v107, 1.0, v107
	v_rcp_f32_e32 v106, v106
	v_rcp_f32_e32 v107, v107
	s_nop 0
	v_mul_f32_e32 v100, v100, v106
	v_mul_f32_e32 v101, v101, v107
	s_nop 0
	v_mul_f32_e32 v96, v96, v100
	v_mul_f32_e32 v97, v97, v101
	s_nop 0
	v_cvt_pk_bf16_f32 v106, v96, v97
	v_mul_f32_e32 v96, 0xbfb8aa3b, v102
	v_mul_f32_e32 v97, 0xbfb8aa3b, v103
	v_exp_f32_e32 v96, v96
	v_exp_f32_e32 v97, v97
	v_add_f32_e32 v96, 1.0, v96
	v_add_f32_e32 v97, 1.0, v97
	v_rcp_f32_e32 v96, v96
	v_rcp_f32_e32 v97, v97
	s_nop 0
	v_mul_f32_e32 v96, v102, v96
	v_mul_f32_e32 v97, v103, v97
	s_nop 0
	v_mul_f32_e32 v96, v98, v96
	v_mul_f32_e32 v97, v99, v97
	v_mul_f32_e32 v98, 0xbfb8aa3b, v92
	v_mul_f32_e32 v99, 0xbfb8aa3b, v93
	v_exp_f32_e32 v98, v98
	v_exp_f32_e32 v99, v99
	v_cvt_pk_bf16_f32 v107, v96, v97
	v_add_u32_e32 v96, 32, v146
	v_add_f32_e32 v98, 1.0, v98
	v_add_f32_e32 v99, 1.0, v99
	v_rcp_f32_e32 v98, v98
	v_rcp_f32_e32 v99, v99
	v_mad_i64_i32 v[96:97], s[18:19], v96, s44, v[138:139]
	v_lshl_add_u64 v[96:97], v[96:97], 0, v[140:141]
	v_mul_f32_e32 v92, v92, v98
	v_mul_f32_e32 v93, v93, v99
	global_store_dwordx4 v[112:113], v[104:107], off
	v_mul_f32_e32 v88, v88, v92
	v_mul_f32_e32 v89, v89, v93
	s_nop 0
	v_cvt_pk_bf16_f32 v88, v88, v89
	v_mul_f32_e32 v89, 0xbfb8aa3b, v94
	v_exp_f32_e32 v89, v89
	s_nop 0
	v_add_f32_e32 v89, 1.0, v89
	v_rcp_f32_e32 v92, v89
	v_mul_f32_e32 v89, 0xbfb8aa3b, v95
	v_exp_f32_e32 v89, v89
	s_nop 0
	v_add_f32_e32 v89, 1.0, v89
	v_rcp_f32_e32 v93, v89
	s_nop 0
	v_mul_f32_e32 v92, v94, v92
	v_mul_f32_e32 v93, v95, v93
	s_nop 0
	v_mul_f32_e32 v90, v90, v92
	v_mul_f32_e32 v91, v91, v93
	s_nop 0
	v_cvt_pk_bf16_f32 v89, v90, v91
	v_mul_f32_e32 v90, 0xbfb8aa3b, v84
	v_mul_f32_e32 v91, 0xbfb8aa3b, v85
	v_exp_f32_e32 v90, v90
	v_exp_f32_e32 v91, v91
	v_add_f32_e32 v90, 1.0, v90
	v_add_f32_e32 v91, 1.0, v91
	v_rcp_f32_e32 v90, v90
	v_rcp_f32_e32 v91, v91
	s_nop 0
	v_mul_f32_e32 v84, v84, v90
	v_mul_f32_e32 v85, v85, v91
	s_nop 0
	v_mul_f32_e32 v80, v80, v84
	v_mul_f32_e32 v81, v81, v85
	s_nop 0
	v_cvt_pk_bf16_f32 v90, v80, v81
	v_mul_f32_e32 v80, 0xbfb8aa3b, v86
	v_mul_f32_e32 v81, 0xbfb8aa3b, v87
	v_exp_f32_e32 v80, v80
	v_exp_f32_e32 v81, v81
	v_add_f32_e32 v80, 1.0, v80
	v_add_f32_e32 v81, 1.0, v81
; __device__ __forceinline__ unsigned cvt_pk_bf16(float lo, float hi) { const f32x2 v = {lo, hi}; const bf16x2_t b = __builtin_convertvector(v, bf16x2_t); return __builtin_bit_cast(unsigned, b); }
; __device__ __forceinline__ float silu_f(float x) { return x * fast_rcp(1.0f + fast_exp2(-x * LOG2E)); }
;     __device__ __forceinline__ void operator()(const f32x4 (&acc)[2][2][4][2], const Unit& u, int wr, int wc, int fr, int fq) const {
;         asm volatile("" : "+v"(fr), "+v"(fq));
;         const int row0 = u.pm * BM + wr * 64 + fr; const int col0 = u.pn * 128 + wc * 32 + 8 * fq;
; #pragma unroll
;         for (int ai = 0; ai < 2; ++ai)
; #pragma unroll
;             for (int m = 0; m < 4; ++m) {
;                 bf16_t* rowp = act + (size_t)(row0 + ai * HALF + m * 16) * FF + col0;
;                 const f32x4 g0 = acc[ai][0][m][0], g1 = acc[ai][0][m][1], u0 = acc[ai][1][m][0], u1 = acc[ai][1][m][1];
;                 u32x4 w;
;                 w.x = cvt_pk_bf16(silu_f(g0[0]) * u0[0], silu_f(g0[1]) * u0[1]); w.y = cvt_pk_bf16(silu_f(g0[2]) * u0[2], silu_f(g0[3]) * u0[3]);
;                 w.z = cvt_pk_bf16(silu_f(g1[0]) * u1[0], silu_f(g1[1]) * u1[1]); w.w = cvt_pk_bf16(silu_f(g1[2]) * u1[2], silu_f(g1[3]) * u1[3]);
;                 *(u32x4*)rowp = w;
;             }
	v_rcp_f32_e32 v80, v80
	v_rcp_f32_e32 v81, v81
	s_nop 0
	v_mul_f32_e32 v80, v86, v80
	v_mul_f32_e32 v81, v87, v81
	s_nop 0
	v_mul_f32_e32 v80, v82, v80
	v_mul_f32_e32 v81, v83, v81
	v_mul_f32_e32 v82, 0xbfb8aa3b, v76
	v_mul_f32_e32 v83, 0xbfb8aa3b, v77
	v_exp_f32_e32 v82, v82
	v_exp_f32_e32 v83, v83
	v_cvt_pk_bf16_f32 v91, v80, v81
	v_add_u32_e32 v80, 48, v146
	v_add_f32_e32 v82, 1.0, v82
	v_add_f32_e32 v83, 1.0, v83
	v_rcp_f32_e32 v82, v82
	v_rcp_f32_e32 v83, v83
	v_mad_i64_i32 v[80:81], s[18:19], v80, s44, v[138:139]
	v_lshl_add_u64 v[80:81], v[80:81], 0, v[140:141]
	v_mul_f32_e32 v76, v76, v82
	v_mul_f32_e32 v77, v77, v83
	global_store_dwordx4 v[96:97], v[88:91], off
	v_mul_f32_e32 v72, v72, v76
	v_mul_f32_e32 v73, v73, v77
	s_nop 0
	v_cvt_pk_bf16_f32 v72, v72, v73
	v_mul_f32_e32 v73, 0xbfb8aa3b, v78
	v_exp_f32_e32 v73, v73
	s_nop 0
	v_add_f32_e32 v73, 1.0, v73
	v_rcp_f32_e32 v76, v73
	v_mul_f32_e32 v73, 0xbfb8aa3b, v79
	v_exp_f32_e32 v73, v73
	s_nop 0
	v_add_f32_e32 v73, 1.0, v73
	v_rcp_f32_e32 v77, v73
	s_nop 0
	v_mul_f32_e32 v76, v78, v76
	v_mul_f32_e32 v77, v79, v77
	s_nop 0
	v_mul_f32_e32 v74, v74, v76
	v_mul_f32_e32 v75, v75, v77
	s_nop 0
	v_cvt_pk_bf16_f32 v73, v74, v75
	v_mul_f32_e32 v74, 0xbfb8aa3b, v68
	v_mul_f32_e32 v75, 0xbfb8aa3b, v69
	v_exp_f32_e32 v74, v74
	v_exp_f32_e32 v75, v75
	v_add_f32_e32 v74, 1.0, v74
	v_add_f32_e32 v75, 1.0, v75
	v_rcp_f32_e32 v74, v74
	v_rcp_f32_e32 v75, v75
	s_nop 0
	v_mul_f32_e32 v68, v68, v74
	v_mul_f32_e32 v69, v69, v75
	s_nop 0
	v_mul_f32_e32 v64, v64, v68
	v_mul_f32_e32 v65, v65, v69
	s_nop 0
	v_cvt_pk_bf16_f32 v74, v64, v65
	v_mul_f32_e32 v64, 0xbfb8aa3b, v70
	v_mul_f32_e32 v65, 0xbfb8aa3b, v71
	v_exp_f32_e32 v64, v64
	v_exp_f32_e32 v65, v65
	v_add_f32_e32 v64, 1.0, v64
	v_add_f32_e32 v65, 1.0, v65
	v_rcp_f32_e32 v64, v64
	v_rcp_f32_e32 v65, v65
	s_nop 0
	v_mul_f32_e32 v64, v70, v64
	v_mul_f32_e32 v65, v71, v65
	s_nop 0
	v_mul_f32_e32 v64, v66, v64
	v_mul_f32_e32 v65, v67, v65
	v_mul_f32_e32 v66, 0xbfb8aa3b, v60
	v_mul_f32_e32 v67, 0xbfb8aa3b, v61
	v_exp_f32_e32 v66, v66
	v_exp_f32_e32 v67, v67
	v_cvt_pk_bf16_f32 v75, v64, v65
	v_add_u32_e32 v64, 0x80, v146
	v_add_f32_e32 v66, 1.0, v66
	v_add_f32_e32 v67, 1.0, v67
	v_rcp_f32_e32 v66, v66
	v_rcp_f32_e32 v67, v67
	v_mad_i64_i32 v[64:65], s[18:19], v64, s44, v[138:139]
	v_lshl_add_u64 v[64:65], v[64:65], 0, v[140:141]
	v_mul_f32_e32 v60, v60, v66
	v_mul_f32_e32 v61, v61, v67
	global_store_dwordx4 v[80:81], v[72:75], off
	v_mul_f32_e32 v56, v56, v60
	v_mul_f32_e32 v57, v57, v61
	s_nop 0
	v_cvt_pk_bf16_f32 v56, v56, v57
	v_mul_f32_e32 v57, 0xbfb8aa3b, v62
	v_exp_f32_e32 v57, v57
	s_nop 0
	v_add_f32_e32 v57, 1.0, v57
	v_rcp_f32_e32 v60, v57
	v_mul_f32_e32 v57, 0xbfb8aa3b, v63
	v_exp_f32_e32 v57, v57
	s_nop 0
	v_add_f32_e32 v57, 1.0, v57
	v_rcp_f32_e32 v61, v57
	s_nop 0
	v_mul_f32_e32 v60, v62, v60
	v_mul_f32_e32 v61, v63, v61
	s_nop 0
	v_mul_f32_e32 v58, v58, v60
	v_mul_f32_e32 v59, v59, v61
	s_nop 0
	v_cvt_pk_bf16_f32 v57, v58, v59
	v_mul_f32_e32 v58, 0xbfb8aa3b, v52
	v_mul_f32_e32 v59, 0xbfb8aa3b, v53
	v_exp_f32_e32 v58, v58
	v_exp_f32_e32 v59, v59
	v_add_f32_e32 v58, 1.0, v58
	v_add_f32_e32 v59, 1.0, v59
	v_rcp_f32_e32 v58, v58
	v_rcp_f32_e32 v59, v59
	s_nop 0
	v_mul_f32_e32 v52, v52, v58
	v_mul_f32_e32 v53, v53, v59
	s_nop 0
	v_mul_f32_e32 v48, v48, v52
	v_mul_f32_e32 v49, v49, v53
	s_nop 0
	v_cvt_pk_bf16_f32 v58, v48, v49
	v_mul_f32_e32 v48, 0xbfb8aa3b, v54
	v_mul_f32_e32 v49, 0xbfb8aa3b, v55
	v_exp_f32_e32 v48, v48
	v_exp_f32_e32 v49, v49
	v_add_f32_e32 v48, 1.0, v48
	v_add_f32_e32 v49, 1.0, v49
	v_rcp_f32_e32 v48, v48
	v_rcp_f32_e32 v49, v49
	s_nop 0
	v_mul_f32_e32 v48, v54, v48
	v_mul_f32_e32 v49, v55, v49
	s_nop 0
	v_mul_f32_e32 v48, v50, v48
	v_mul_f32_e32 v49, v51, v49
	v_mul_f32_e32 v50, 0xbfb8aa3b, v44
	v_mul_f32_e32 v51, 0xbfb8aa3b, v45
	v_exp_f32_e32 v50, v50
	v_exp_f32_e32 v51, v51
	v_cvt_pk_bf16_f32 v59, v48, v49
	v_add_u32_e32 v48, 0x90, v146
	v_add_f32_e32 v50, 1.0, v50
	v_add_f32_e32 v51, 1.0, v51
	v_rcp_f32_e32 v50, v50
	v_rcp_f32_e32 v51, v51
	v_mad_i64_i32 v[48:49], s[18:19], v48, s44, v[138:139]
	v_lshl_add_u64 v[48:49], v[48:49], 0, v[140:141]
	v_mul_f32_e32 v44, v44, v50
	v_mul_f32_e32 v45, v45, v51
	global_store_dwordx4 v[64:65], v[56:59], off
	v_mul_f32_e32 v40, v40, v44
	v_mul_f32_e32 v41, v41, v45
	s_nop 0
	v_cvt_pk_bf16_f32 v40, v40, v41
	v_mul_f32_e32 v41, 0xbfb8aa3b, v46
	v_exp_f32_e32 v41, v41
	s_nop 0
	v_add_f32_e32 v41, 1.0, v41
	v_rcp_f32_e32 v44, v41
	v_mul_f32_e32 v41, 0xbfb8aa3b, v47
	v_exp_f32_e32 v41, v41
	s_nop 0
	v_add_f32_e32 v41, 1.0, v41
	v_rcp_f32_e32 v45, v41
	s_nop 0
	v_mul_f32_e32 v44, v46, v44
; __device__ __forceinline__ unsigned cvt_pk_bf16(float lo, float hi) { const f32x2 v = {lo, hi}; const bf16x2_t b = __builtin_convertvector(v, bf16x2_t); return __builtin_bit_cast(unsigned, b); }
; __device__ __forceinline__ float silu_f(float x) { return x * fast_rcp(1.0f + fast_exp2(-x * LOG2E)); }
;     __device__ __forceinline__ void operator()(const f32x4 (&acc)[2][2][4][2], const Unit& u, int wr, int wc, int fr, int fq) const {
;         asm volatile("" : "+v"(fr), "+v"(fq));
;         const int row0 = u.pm * BM + wr * 64 + fr; const int col0 = u.pn * 128 + wc * 32 + 8 * fq;
; #pragma unroll
;         for (int ai = 0; ai < 2; ++ai)
; #pragma unroll
;             for (int m = 0; m < 4; ++m) {
;                 bf16_t* rowp = act + (size_t)(row0 + ai * HALF + m * 16) * FF + col0;
;                 const f32x4 g0 = acc[ai][0][m][0], g1 = acc[ai][0][m][1], u0 = acc[ai][1][m][0], u1 = acc[ai][1][m][1];
;                 u32x4 w;
;                 w.x = cvt_pk_bf16(silu_f(g0[0]) * u0[0], silu_f(g0[1]) * u0[1]); w.y = cvt_pk_bf16(silu_f(g0[2]) * u0[2], silu_f(g0[3]) * u0[3]);
;                 w.z = cvt_pk_bf16(silu_f(g1[0]) * u1[0], silu_f(g1[1]) * u1[1]); w.w = cvt_pk_bf16(silu_f(g1[2]) * u1[2], silu_f(g1[3]) * u1[3]);
;                 *(u32x4*)rowp = w;
;             }
	v_mul_f32_e32 v45, v47, v45
	s_nop 0
	v_mul_f32_e32 v42, v42, v44
	v_mul_f32_e32 v43, v43, v45
	s_nop 0
	v_cvt_pk_bf16_f32 v41, v42, v43
	v_mul_f32_e32 v42, 0xbfb8aa3b, v36
	v_mul_f32_e32 v43, 0xbfb8aa3b, v37
	v_exp_f32_e32 v42, v42
	v_exp_f32_e32 v43, v43
	v_add_f32_e32 v42, 1.0, v42
	v_add_f32_e32 v43, 1.0, v43
	v_rcp_f32_e32 v42, v42
	v_rcp_f32_e32 v43, v43
	s_nop 0
	v_mul_f32_e32 v36, v36, v42
	v_mul_f32_e32 v37, v37, v43
	s_nop 0
	v_mul_f32_e32 v32, v32, v36
	v_mul_f32_e32 v33, v33, v37
	s_nop 0
	v_cvt_pk_bf16_f32 v42, v32, v33
	v_mul_f32_e32 v32, 0xbfb8aa3b, v38
	v_mul_f32_e32 v33, 0xbfb8aa3b, v39
	v_exp_f32_e32 v32, v32
	v_exp_f32_e32 v33, v33
	v_add_f32_e32 v32, 1.0, v32
	v_add_f32_e32 v33, 1.0, v33
	v_rcp_f32_e32 v32, v32
	v_rcp_f32_e32 v33, v33
	s_nop 0
	v_mul_f32_e32 v32, v38, v32
	v_mul_f32_e32 v33, v39, v33
	s_nop 0
	v_mul_f32_e32 v32, v34, v32
	v_mul_f32_e32 v33, v35, v33
	v_mul_f32_e32 v34, 0xbfb8aa3b, v28
	v_mul_f32_e32 v35, 0xbfb8aa3b, v29
	v_exp_f32_e32 v34, v34
	v_exp_f32_e32 v35, v35
	v_cvt_pk_bf16_f32 v43, v32, v33
	v_add_u32_e32 v32, 0xa0, v146
	v_add_f32_e32 v34, 1.0, v34
	v_add_f32_e32 v35, 1.0, v35
	v_rcp_f32_e32 v34, v34
	v_rcp_f32_e32 v35, v35
	v_mad_i64_i32 v[32:33], s[18:19], v32, s44, v[138:139]
	v_lshl_add_u64 v[32:33], v[32:33], 0, v[140:141]
	v_mul_f32_e32 v28, v28, v34
	v_mul_f32_e32 v29, v29, v35
	global_store_dwordx4 v[48:49], v[40:43], off
	v_mul_f32_e32 v24, v24, v28
	v_mul_f32_e32 v25, v25, v29
	s_nop 0
	v_cvt_pk_bf16_f32 v24, v24, v25
	v_mul_f32_e32 v25, 0xbfb8aa3b, v30
	v_exp_f32_e32 v25, v25
	s_nop 0
	v_add_f32_e32 v25, 1.0, v25
	v_rcp_f32_e32 v28, v25
	v_mul_f32_e32 v25, 0xbfb8aa3b, v31
	v_exp_f32_e32 v25, v25
	s_nop 0
	v_add_f32_e32 v25, 1.0, v25
	v_rcp_f32_e32 v29, v25
	s_nop 0
	v_mul_f32_e32 v28, v30, v28
	v_mul_f32_e32 v29, v31, v29
	s_nop 0
	v_mul_f32_e32 v26, v26, v28
	v_mul_f32_e32 v27, v27, v29
	s_nop 0
	v_cvt_pk_bf16_f32 v25, v26, v27
	v_mul_f32_e32 v26, 0xbfb8aa3b, v20
	v_mul_f32_e32 v27, 0xbfb8aa3b, v21
	v_exp_f32_e32 v26, v26
	v_exp_f32_e32 v27, v27
	v_add_f32_e32 v26, 1.0, v26
	v_add_f32_e32 v27, 1.0, v27
	v_rcp_f32_e32 v26, v26
	v_rcp_f32_e32 v27, v27
	s_nop 0
	v_mul_f32_e32 v20, v20, v26
	v_mul_f32_e32 v21, v21, v27
	s_nop 0
	v_mul_f32_e32 v16, v16, v20
	v_mul_f32_e32 v17, v17, v21
	s_nop 0
	v_cvt_pk_bf16_f32 v26, v16, v17
	v_mul_f32_e32 v16, 0xbfb8aa3b, v22
	v_mul_f32_e32 v17, 0xbfb8aa3b, v23
	v_exp_f32_e32 v16, v16
	v_exp_f32_e32 v17, v17
	v_add_f32_e32 v16, 1.0, v16
	v_add_f32_e32 v17, 1.0, v17
	v_rcp_f32_e32 v16, v16
	v_rcp_f32_e32 v17, v17
	s_nop 0
	v_mul_f32_e32 v16, v22, v16
	v_mul_f32_e32 v17, v23, v17
	s_nop 0
	v_mul_f32_e32 v16, v18, v16
	v_mul_f32_e32 v17, v19, v17
	v_mul_f32_e32 v18, 0xbfb8aa3b, v12
	v_mul_f32_e32 v19, 0xbfb8aa3b, v13
	v_exp_f32_e32 v18, v18
	v_exp_f32_e32 v19, v19
	v_cvt_pk_bf16_f32 v27, v16, v17
	v_add_u32_e32 v16, 0xb0, v146
	v_add_f32_e32 v18, 1.0, v18
	v_add_f32_e32 v19, 1.0, v19
	v_rcp_f32_e32 v18, v18
	v_rcp_f32_e32 v19, v19
	v_mad_i64_i32 v[16:17], s[18:19], v16, s44, v[138:139]
	v_lshl_add_u64 v[16:17], v[16:17], 0, v[140:141]
	v_mul_f32_e32 v12, v12, v18
	v_mul_f32_e32 v13, v13, v19
	s_mov_b64 s[18:19], -1
	v_mul_f32_e32 v8, v8, v12
	v_mul_f32_e32 v9, v9, v13
	global_store_dwordx4 v[32:33], v[24:27], off
	v_cvt_pk_bf16_f32 v8, v8, v9
	v_mul_f32_e32 v9, 0xbfb8aa3b, v14
	v_exp_f32_e32 v9, v9
	s_nop 0
	v_add_f32_e32 v9, 1.0, v9
	v_rcp_f32_e32 v12, v9
	v_mul_f32_e32 v9, 0xbfb8aa3b, v15
	v_exp_f32_e32 v9, v9
	s_nop 0
	v_add_f32_e32 v9, 1.0, v9
	v_rcp_f32_e32 v13, v9
	s_nop 0
	v_mul_f32_e32 v12, v14, v12
	v_mul_f32_e32 v13, v15, v13
	s_nop 0
	v_mul_f32_e32 v10, v10, v12
	v_mul_f32_e32 v11, v11, v13
	s_nop 0
	v_cvt_pk_bf16_f32 v9, v10, v11
	v_mul_f32_e32 v10, 0xbfb8aa3b, v4
	v_mul_f32_e32 v11, 0xbfb8aa3b, v5
	v_exp_f32_e32 v10, v10
	v_exp_f32_e32 v11, v11
	v_add_f32_e32 v10, 1.0, v10
	v_add_f32_e32 v11, 1.0, v11
	v_rcp_f32_e32 v10, v10
	v_rcp_f32_e32 v11, v11
	s_nop 0
	v_mul_f32_e32 v4, v4, v10
	v_mul_f32_e32 v5, v5, v11
	s_nop 0
	v_mul_f32_e32 v0, v0, v4
	v_mul_f32_e32 v1, v1, v5
	s_nop 0
	v_cvt_pk_bf16_f32 v10, v0, v1
	v_mul_f32_e32 v0, 0xbfb8aa3b, v6
	v_mul_f32_e32 v1, 0xbfb8aa3b, v7
	v_exp_f32_e32 v0, v0
	v_exp_f32_e32 v1, v1
	v_add_f32_e32 v0, 1.0, v0
	v_add_f32_e32 v1, 1.0, v1
	v_rcp_f32_e32 v0, v0
	v_rcp_f32_e32 v1, v1
	s_nop 0
	v_mul_f32_e32 v0, v6, v0
	v_mul_f32_e32 v1, v7, v1
	s_nop 0
	v_mul_f32_e32 v0, v2, v0
	v_mul_f32_e32 v1, v3, v1
	s_nop 0
	v_cvt_pk_bf16_f32 v11, v0, v1
	global_store_dwordx4 v[16:17], v[8:11], off
	s_cbranch_vccnz .LBB0_172
	s_andn2_b64 vcc, exec, s[0:1]
	s_cbranch_vccnz .LBB0_171
	s_barrier
	s_branch .LBB0_171

;     __device__ __forceinline__ void operator()(const f32x4 (&acc)[2][2][4][2], const Unit& u, int wr, int wc, int fr, int fq) const {
;     ...
;         f32x4 gv[2][2];
; #pragma unroll
;         for (int bj = 0; bj < 2; ++bj)
; #pragma unroll
;             for (int n = 0; n < 2; ++n) gv[bj][n] = *(const f32x4*)(gate + (size_t)s * 9216 + col0 + bj * HALF + 4 * n) * gscale;
;         if (partial) {
; #pragma unroll
;             for (int ai = 0; ai < 2; ++ai)
; #pragma unroll
;                 for (int m = 0; m < 4; ++m) {
;                     const size_t ro = (size_t)(ai * HALF + m * 16) * DM + col0;
; #pragma unroll
;                     for (int bj = 0; bj < 2; ++bj)
; #pragma unroll
;                         for (int n = 0; n < 2; ++n) *(f32x4*)(pp + ro + bj * HALF + 4 * n) = acc[ai][bj][m][n];
;                 }
;         } else {
; #pragma unroll
;             for (int ai = 0; ai < 2; ++ai) {
;                 f32x4 xv[4][2][2];
; #pragma unroll
;                 for (int m = 0; m < 4; ++m)
; #pragma unroll
;                     for (int bj = 0; bj < 2; ++bj)
; #pragma unroll
;                         for (int n = 0; n < 2; ++n) xv[m][bj][n] = *(const f32x4*)(xo + (size_t)(ai * HALF + m * 16) * DM + col0 + bj * HALF + 4 * n);
;                 __builtin_amdgcn_sched_barrier(0);
; #pragma unroll
;                 for (int m = 0; m < 4; ++m)
; #pragma unroll
;                     for (int bj = 0; bj < 2; ++bj)
; #pragma unroll
;                         for (int n = 0; n < 2; ++n) *(f32x4*)(xn + (size_t)(ai * HALF + m * 16) * DM + col0 + bj * HALF + 4 * n) = xv[m][bj][n] + gv[bj][n] * acc[ai][bj][m][n];
;                 __builtin_amdgcn_sched_barrier(0);
;             }
.LBB0_269:
	s_lshl_b64 s[14:15], s[14:15], 2
	s_add_u32 s14, s56, s14
	s_addc_u32 s15, s57, s15
	v_lshlrev_b64 v[172:173], 2, v[140:141]
	v_lshl_add_u64 v[152:153], s[14:15], 0, v[172:173]
	global_load_dwordx4 v[148:151], v[152:153], off offset:512
	global_load_dwordx4 v[144:147], v[152:153], off offset:528
	global_load_dwordx4 v[166:169], v[152:153], off
	s_nop 0
	global_load_dwordx4 v[152:155], v[152:153], off offset:16
	v_lshl_add_u64 v[160:161], v[158:159], 0, v[172:173]
	s_mov_b64 s[14:15], 0x10000
	v_add_co_u32_e32 v190, vcc, s49, v160
	v_lshl_add_u64 v[186:187], v[160:161], 0, s[14:15]
	s_nop 0
	v_addc_co_u32_e32 v191, vcc, 0, v161, vcc
	s_mov_b64 s[14:15], 0x10200
	v_lshl_add_u64 v[170:171], s[20:21], 0, v[142:143]
	v_lshl_add_u64 v[212:213], v[160:161], 0, s[14:15]
	s_mov_b64 s[14:15], 0x20000
	v_add_co_u32_e32 v226, vcc, s62, v160
	v_lshl_add_u64 v[158:159], v[170:171], 0, v[172:173]
	s_nop 0
	v_addc_co_u32_e32 v227, vcc, 0, v161, vcc
	s_waitcnt vmcnt(0)
	v_mul_f32_e32 v148, 0.5, v148
	v_mul_f32_e32 v149, 0.5, v149
	v_mul_f32_e32 v142, 0.5, v146
	v_mul_f32_e32 v143, 0.5, v147
	v_mul_f32_e32 v146, 0.5, v150
	v_mul_f32_e32 v147, 0.5, v151
	v_mul_f32_e32 v150, 0.5, v154
	v_mul_f32_e32 v151, 0.5, v155
	v_mul_f32_e32 v154, 0.5, v168
	v_mul_f32_e32 v155, 0.5, v169
	v_mul_f32_e32 v156, 0.5, v166
	v_mul_f32_e32 v157, 0.5, v167
	global_load_dwordx4 v[166:169], v[160:161], off offset:16
	global_load_dwordx4 v[170:173], v[160:161], off
	global_load_dwordx4 v[174:177], v[160:161], off offset:528
	global_load_dwordx4 v[178:181], v[160:161], off offset:512
	global_load_dwordx4 v[182:185], v[190:191], off
	s_nop 0
	global_load_dwordx4 v[186:189], v[186:187], off offset:16
	s_nop 0
	global_load_dwordx4 v[208:211], v[190:191], off offset:512
	s_nop 0
	global_load_dwordx4 v[212:215], v[212:213], off offset:16
	v_lshl_add_u64 v[190:191], v[160:161], 0, s[14:15]
	s_mov_b64 s[14:15], 0x20200
	global_load_dwordx4 v[216:219], v[226:227], off
	global_load_dwordx4 v[220:223], v[190:191], off offset:16
	v_lshl_add_u64 v[190:191], v[160:161], 0, s[14:15]
	global_load_dwordx4 v[230:233], v[226:227], off offset:512
	global_load_dwordx4 v[234:237], v[190:191], off offset:16
	s_mov_b64 s[14:15], 0x30000
	v_add_co_u32_e32 v226, vcc, s63, v160
	v_lshl_add_u64 v[190:191], v[160:161], 0, s[14:15]
	s_nop 0
	v_addc_co_u32_e32 v227, vcc, 0, v161, vcc
	s_mov_b64 s[14:15], 0x30200
	global_load_dwordx4 v[238:241], v[226:227], off
	global_load_dwordx4 v[242:245], v[190:191], off offset:16
	v_lshl_add_u64 v[190:191], v[160:161], 0, s[14:15]
	global_load_dwordx4 v[246:249], v[226:227], off offset:512
	s_nop 0
	global_load_dwordx4 v[226:229], v[190:191], off offset:16
	v_mul_f32_e32 v144, 0.5, v144
	v_mul_f32_e32 v145, 0.5, v145
	v_mul_f32_e32 v152, 0.5, v152
	v_mul_f32_e32 v153, 0.5, v153
	s_waitcnt vmcnt(15)
	v_fma_f32 v168, v122, v150, v168
	v_fma_f32 v169, v123, v151, v169
	v_fma_f32 v166, v120, v152, v166
	v_fma_f32 v167, v121, v153, v167
	s_waitcnt vmcnt(14)
	v_fma_f32 v172, v126, v154, v172
	v_fma_f32 v173, v127, v155, v173
	v_fma_f32 v170, v124, v156, v170
	v_fma_f32 v171, v125, v157, v171
	global_store_dwordx4 v[158:159], v[166:169], off offset:16
	global_store_dwordx4 v[158:159], v[170:173], off
	s_waitcnt vmcnt(14)
	v_fma_f32 v168, v110, v146, v180
	v_fma_f32 v169, v111, v147, v181
	v_fma_f32 v166, v108, v148, v178
	v_fma_f32 v167, v109, v149, v179
	global_store_dwordx4 v[158:159], v[166:169], off offset:512
	v_add_co_u32_e32 v170, vcc, s49, v158
	s_nop 0
	v_fma_f32 v168, v102, v142, v176
	v_fma_f32 v169, v103, v143, v177
	v_fma_f32 v166, v100, v144, v174
	v_fma_f32 v167, v101, v145, v175
	global_store_dwordx4 v[158:159], v[166:169], off offset:528
	v_addc_co_u32_e32 v171, vcc, 0, v159, vcc
	s_waitcnt vmcnt(15)
	v_fma_f32 v168, v118, v154, v184
	v_fma_f32 v169, v119, v155, v185
	v_fma_f32 v166, v116, v156, v182
	v_fma_f32 v167, v117, v157, v183
	global_store_dwordx4 v[170:171], v[166:169], off
	s_waitcnt vmcnt(15)
	s_nop 0
	v_fma_f32 v168, v114, v150, v188
	v_fma_f32 v169, v115, v151, v189
	v_fma_f32 v166, v112, v152, v186
	v_fma_f32 v167, v113, v153, v187
	global_store_dwordx4 v[170:171], v[166:169], off offset:16
	s_waitcnt vmcnt(15)
	s_nop 0
	v_fma_f32 v168, v94, v146, v210
	v_fma_f32 v169, v95, v147, v211
	v_fma_f32 v166, v92, v148, v208
	v_fma_f32 v167, v93, v149, v209
	global_store_dwordx4 v[170:171], v[166:169], off offset:512
	s_waitcnt vmcnt(15)
	s_nop 0
	v_fma_f32 v168, v86, v142, v214
	v_fma_f32 v169, v87, v143, v215
	v_fma_f32 v166, v84, v144, v212
	v_fma_f32 v167, v85, v145, v213
	global_store_dwordx4 v[170:171], v[166:169], off offset:528
	v_add_co_u32_e32 v170, vcc, s62, v158
	s_waitcnt vmcnt(15)
	v_fma_f32 v168, v106, v154, v218
	v_fma_f32 v169, v107, v155, v219
	v_fma_f32 v166, v104, v156, v216
	v_fma_f32 v167, v105, v157, v217
	v_addc_co_u32_e32 v171, vcc, 0, v159, vcc
	global_store_dwordx4 v[170:171], v[166:169], off
	s_waitcnt vmcnt(15)
	s_nop 0
	v_fma_f32 v168, v98, v150, v222
	v_fma_f32 v169, v99, v151, v223
	v_fma_f32 v166, v96, v152, v220
	v_fma_f32 v167, v97, v153, v221
	global_store_dwordx4 v[170:171], v[166:169], off offset:16
	s_waitcnt vmcnt(15)
	s_nop 0
	v_fma_f32 v168, v78, v146, v232
	v_fma_f32 v169, v79, v147, v233
	v_fma_f32 v166, v76, v148, v230
	v_fma_f32 v167, v77, v149, v231
	global_store_dwordx4 v[170:171], v[166:169], off offset:512
	s_waitcnt vmcnt(15)
	s_nop 0
	v_fma_f32 v168, v74, v142, v236
	v_fma_f32 v169, v75, v143, v237
	v_fma_f32 v166, v72, v144, v234
	v_fma_f32 v167, v73, v145, v235
	global_store_dwordx4 v[170:171], v[166:169], off offset:528
	v_add_co_u32_e32 v170, vcc, s63, v158
	s_waitcnt vmcnt(15)
;     __device__ __forceinline__ void operator()(const f32x4 (&acc)[2][2][4][2], const Unit& u, int wr, int wc, int fr, int fq) const {
;     ...
;             for (int ai = 0; ai < 2; ++ai) {
;                 f32x4 xv[4][2][2];
; #pragma unroll
;                 for (int m = 0; m < 4; ++m)
; #pragma unroll
;                     for (int bj = 0; bj < 2; ++bj)
; #pragma unroll
;                         for (int n = 0; n < 2; ++n) xv[m][bj][n] = *(const f32x4*)(xo + (size_t)(ai * HALF + m * 16) * DM + col0 + bj * HALF + 4 * n);
;                 __builtin_amdgcn_sched_barrier(0);
; #pragma unroll
;                 for (int m = 0; m < 4; ++m)
; #pragma unroll
;                     for (int bj = 0; bj < 2; ++bj)
; #pragma unroll
;                         for (int n = 0; n < 2; ++n) *(f32x4*)(xn + (size_t)(ai * HALF + m * 16) * DM + col0 + bj * HALF + 4 * n) = xv[m][bj][n] + gv[bj][n] * acc[ai][bj][m][n];
;                 __builtin_amdgcn_sched_barrier(0);
;             }
	v_fma_f32 v168, v90, v154, v240
	v_fma_f32 v169, v91, v155, v241
	v_fma_f32 v166, v88, v156, v238
	v_fma_f32 v167, v89, v157, v239
	v_addc_co_u32_e32 v171, vcc, 0, v159, vcc
	global_store_dwordx4 v[170:171], v[166:169], off
	s_waitcnt vmcnt(15)
	s_nop 0
	v_fma_f32 v168, v82, v150, v244
	v_fma_f32 v169, v83, v151, v245
	v_fma_f32 v166, v80, v152, v242
	v_fma_f32 v167, v81, v153, v243
	global_store_dwordx4 v[170:171], v[166:169], off offset:16
	s_waitcnt vmcnt(15)
	s_nop 0
	v_fma_f32 v168, v70, v146, v248
	v_fma_f32 v169, v71, v147, v249
	v_fma_f32 v166, v68, v148, v246
	v_fma_f32 v167, v69, v149, v247
	global_store_dwordx4 v[170:171], v[166:169], off offset:512
	s_waitcnt vmcnt(15)
	s_nop 0
	v_fma_f32 v168, v66, v142, v228
	v_fma_f32 v169, v67, v143, v229
	v_fma_f32 v166, v64, v144, v226
	v_fma_f32 v167, v65, v145, v227
	global_store_dwordx4 v[170:171], v[166:169], off offset:528
	s_mov_b64 s[14:15], 0x80000
	v_lshl_add_u64 v[170:171], v[160:161], 0, s[14:15]
	s_mov_b32 s14, 0x80000
	v_add_co_u32_e32 v174, vcc, s14, v160
	s_mov_b64 s[16:17], 0x80200
	s_nop 0
	v_addc_co_u32_e32 v175, vcc, 0, v161, vcc
	v_lshl_add_u64 v[178:179], v[160:161], 0, s[16:17]
	s_mov_b64 s[16:17], 0x90000
	s_mov_b32 s15, 0x90000
	v_lshl_add_u64 v[186:187], v[160:161], 0, s[16:17]
	v_add_co_u32_e32 v190, vcc, s15, v160
	s_mov_b64 s[16:17], 0x90200
	s_nop 0
	v_addc_co_u32_e32 v191, vcc, 0, v161, vcc
	v_lshl_add_u64 v[212:213], v[160:161], 0, s[16:17]
	s_mov_b64 s[16:17], 0xa0000
	global_load_dwordx4 v[166:169], v[174:175], off
	s_nop 0
	global_load_dwordx4 v[170:173], v[170:171], off offset:16
	s_nop 0
	global_load_dwordx4 v[174:177], v[174:175], off offset:512
	s_nop 0
	global_load_dwordx4 v[178:181], v[178:179], off offset:16
	s_nop 0
	global_load_dwordx4 v[182:185], v[190:191], off
	s_nop 0
	global_load_dwordx4 v[186:189], v[186:187], off offset:16
	s_nop 0
	global_load_dwordx4 v[208:211], v[190:191], off offset:512
	s_nop 0
	global_load_dwordx4 v[212:215], v[212:213], off offset:16
	v_lshl_add_u64 v[190:191], v[160:161], 0, s[16:17]
	s_mov_b32 s16, 0xa0000
	v_add_co_u32_e32 v226, vcc, s16, v160
	s_mov_b32 s17, 0xb0000
	s_nop 0
	v_addc_co_u32_e32 v227, vcc, 0, v161, vcc
	s_mov_b64 s[18:19], 0xa0200
	v_add_co_u32_e32 v242, vcc, s17, v160
	global_load_dwordx4 v[216:219], v[226:227], off
	global_load_dwordx4 v[220:223], v[190:191], off offset:16
	v_lshl_add_u64 v[190:191], v[160:161], 0, s[18:19]
	v_addc_co_u32_e32 v243, vcc, 0, v161, vcc
	s_mov_b64 s[18:19], 0xb0200
	global_load_dwordx4 v[226:229], v[226:227], off offset:512
	s_nop 0
	global_load_dwordx4 v[230:233], v[190:191], off offset:16
	v_lshl_add_u64 v[190:191], v[160:161], 0, s[30:31]
	global_load_dwordx4 v[234:237], v[242:243], off
	global_load_dwordx4 v[238:241], v[190:191], off offset:16
	v_lshl_add_u64 v[160:161], v[160:161], 0, s[18:19]
	global_load_dwordx4 v[242:245], v[242:243], off offset:512
	s_nop 0
	global_load_dwordx4 v[246:249], v[160:161], off offset:16
	v_add_co_u32_e32 v160, vcc, s14, v158
	s_waitcnt vmcnt(15)
	v_fma_f32 v168, v62, v154, v168
	v_fma_f32 v169, v63, v155, v169
	v_fma_f32 v166, v60, v156, v166
	v_fma_f32 v167, v61, v157, v167
	v_addc_co_u32_e32 v161, vcc, 0, v159, vcc
	global_store_dwordx4 v[160:161], v[166:169], off
	s_waitcnt vmcnt(15)
	s_nop 0
	v_fma_f32 v168, v58, v150, v172
	v_fma_f32 v169, v59, v151, v173
	v_fma_f32 v166, v56, v152, v170
	v_fma_f32 v167, v57, v153, v171
	global_store_dwordx4 v[160:161], v[166:169], off offset:16
	s_waitcnt vmcnt(15)
	s_nop 0
	v_fma_f32 v168, v46, v146, v176
	v_fma_f32 v169, v47, v147, v177
	v_fma_f32 v166, v44, v148, v174
	v_fma_f32 v167, v45, v149, v175
	global_store_dwordx4 v[160:161], v[166:169], off offset:512
	s_waitcnt vmcnt(15)
	s_nop 0
	v_fma_f32 v168, v38, v142, v180
	v_fma_f32 v169, v39, v143, v181
	v_fma_f32 v166, v36, v144, v178
	v_fma_f32 v167, v37, v145, v179
	global_store_dwordx4 v[160:161], v[166:169], off offset:528
	v_add_co_u32_e32 v160, vcc, s15, v158
	s_waitcnt vmcnt(15)
	v_fma_f32 v168, v54, v154, v184
	v_fma_f32 v169, v55, v155, v185
	v_fma_f32 v166, v52, v156, v182
	v_fma_f32 v167, v53, v157, v183
	v_addc_co_u32_e32 v161, vcc, 0, v159, vcc
	global_store_dwordx4 v[160:161], v[166:169], off
	s_waitcnt vmcnt(15)
	s_nop 0
	v_fma_f32 v168, v50, v150, v188
	v_fma_f32 v169, v51, v151, v189
	v_fma_f32 v166, v48, v152, v186
	v_fma_f32 v167, v49, v153, v187
	global_store_dwordx4 v[160:161], v[166:169], off offset:16
	s_waitcnt vmcnt(15)
	s_nop 0
	v_fma_f32 v168, v30, v146, v210
	v_fma_f32 v169, v31, v147, v211
	v_fma_f32 v166, v28, v148, v208
	v_fma_f32 v167, v29, v149, v209
	global_store_dwordx4 v[160:161], v[166:169], off offset:512
	s_waitcnt vmcnt(15)
	s_nop 0
	v_fma_f32 v168, v22, v142, v214
	v_fma_f32 v169, v23, v143, v215
	v_fma_f32 v166, v20, v144, v212
	v_fma_f32 v167, v21, v145, v213
	global_store_dwordx4 v[160:161], v[166:169], off offset:528
	v_add_co_u32_e32 v160, vcc, s16, v158
	s_waitcnt vmcnt(15)
	v_fma_f32 v168, v42, v154, v218
	v_fma_f32 v169, v43, v155, v219
	v_fma_f32 v166, v40, v156, v216
	v_fma_f32 v167, v41, v157, v217
	v_addc_co_u32_e32 v161, vcc, 0, v159, vcc
	global_store_dwordx4 v[160:161], v[166:169], off
	s_waitcnt vmcnt(15)
	s_nop 0
	v_fma_f32 v168, v34, v150, v222
	v_fma_f32 v169, v35, v151, v223
	v_fma_f32 v166, v32, v152, v220
	v_fma_f32 v167, v33, v153, v221
	global_store_dwordx4 v[160:161], v[166:169], off offset:16
	s_waitcnt vmcnt(12)
	v_fma_f32 v152, v16, v152, v238
	v_fma_f32 v153, v17, v153, v239
	v_fma_f32 v168, v14, v146, v228
	v_fma_f32 v169, v15, v147, v229
	v_fma_f32 v166, v12, v148, v226
	v_fma_f32 v167, v13, v149, v227
	global_store_dwordx4 v[160:161], v[166:169], off offset:512
	s_waitcnt vmcnt(12)
	v_fma_f32 v148, v4, v148, v242
	v_fma_f32 v149, v5, v149, v243
	v_fma_f32 v168, v10, v142, v232
	v_fma_f32 v169, v11, v143, v233
	v_fma_f32 v166, v8, v144, v230
	v_fma_f32 v167, v9, v145, v231
	global_store_dwordx4 v[160:161], v[166:169], off offset:528
	s_waitcnt vmcnt(12)
	v_fma_f32 v144, v0, v144, v246
	v_fma_f32 v145, v1, v145, v247
	v_fma_f32 v166, v24, v156, v234
	v_fma_f32 v167, v25, v157, v235
	v_add_co_u32_e32 v156, vcc, s17, v158
	v_fma_f32 v168, v26, v154, v236
	v_fma_f32 v169, v27, v155, v237
	s_nop 0
	v_addc_co_u32_e32 v157, vcc, 0, v159, vcc
	v_fma_f32 v154, v18, v150, v240
	v_fma_f32 v155, v19, v151, v241
	v_fma_f32 v150, v6, v146, v244
	v_fma_f32 v151, v7, v147, v245
	v_fma_f32 v146, v2, v142, v248
	v_fma_f32 v147, v3, v143, v249
	global_store_dwordx4 v[156:157], v[166:169], off
	global_store_dwordx4 v[156:157], v[152:155], off offset:16
	global_store_dwordx4 v[156:157], v[148:151], off offset:512
	global_store_dwordx4 v[156:157], v[144:147], off offset:528
	s_cbranch_execnz .LBB0_268

; __device__ __forceinline__ void norm_row(const f32x4 (&v)[4], const f32x4 (&gn)[4], const float* sh, bf16_t* hrow, int lane) {
;     const float* scl = sh + 1024;
;     f32x4 sv[4], cv[4];
; #pragma unroll
;     for (int j = 0; j < 4; ++j) { sv[j] = *(const f32x4*)(sh + 4 * lane + 256 * j); cv[j] = *(const f32x4*)(scl + 4 * lane + 256 * j); }
;     float ss = 0.f;
; #pragma unroll
;     for (int j = 0; j < 4; ++j) ss += (v[j][0] * v[j][0] + v[j][1] * v[j][1]) + (v[j][2] * v[j][2] + v[j][3] * v[j][3]);
;     const float rstd = __builtin_amdgcn_rsqf(wave_sum(ss) * (1.0f / DM) + EPS);
; #pragma unroll
;     for (int j = 0; j < 4; ++j) {
;         const f32x4 y = v[j] * rstd * gn[j] * (cv[j] + 1.0f) + sv[j];
;         u32x2 w; w.x = cvt_pk_bf16(y[0], y[1]); w.y = cvt_pk_bf16(y[2], y[3]);
;         *(u32x2*)(hrow + 4 * lane + 256 * j) = w;
;     }
; }
; __device__ __forceinline__ void norm_phase(const float* xL, const float* xC, const float* gain, const float* modl  , int ishift, bf16_t* H, int nrows,
;                                            const float* part, int nsplit, const float* pgate  , float pscale, float* xCw) {
;     const int tid_ = opaque_tid(); const int lane = tid_ & 63, wave = __builtin_amdgcn_readfirstlane(tid_ >> 6);
;     const int gw = blockIdx.x * NWAVES + wave, NGW = gridDim.x * NWAVES;
;     f32x4 gn[4];
; #pragma unroll
;     for (int j = 0; j < 4; ++j) gn[j] = *(const f32x4*)(gain + 4 * lane + 256 * j);
;     const int nplain = (nsplit > 0 && nrows > RL) ? RL : nrows;
;     {
;         int row = gw; f32x4 v[4], vn[4];
;         if (row < nplain) { const float* xr = row < RL ? xL + (size_t)row * DM : xC + (size_t)(row - RL) * DM;
; #pragma unroll
;             for (int j = 0; j < 4; ++j) v[j] = *(const f32x4*)(xr + 4 * lane + 256 * j); }
;         for (; row < nplain; row += NGW) {
;             const int rn = row + NGW;
;             if (rn < nplain) { const float* xr = rn < RL ? xL + (size_t)rn * DM : xC + (size_t)(rn - RL) * DM;
; #pragma unroll
;                 for (int j = 0; j < 4; ++j) vn[j] = *(const f32x4*)(xr + 4 * lane + 256 * j); }
;             const int s = row < RL ? (row >> 13) : 4;
;             norm_row(v, gn, modl + (size_t)s * 9216 + ishift * 1024, H + (size_t)row * DM, lane);
; #pragma unroll
;             for (int j = 0; j < 4; ++j) v[j] = vn[j];
;         }
.LBB0_329:
	s_ashr_i32 s9, s9, 13
	s_mul_hi_i32 s11, s9, 0x9000
	s_mul_i32 s9, s9, 0x9000
	s_add_u32 s10, s5, s9
	s_addc_u32 s11, s8, s11
	global_load_dwordx4 v[74:77], v194, s[10:11]
	v_lshl_add_u64 v[48:49], s[10:11], 0, v[194:195]
	v_lshl_add_u64 v[52:53], v[48:49], 0, s[12:13]
	v_add_co_u32_e32 v48, vcc, s76, v48
	v_mul_f32_e32 v73, v45, v45
	s_nop 0
	v_addc_co_u32_e32 v49, vcc, 0, v49, vcc
	global_load_dwordx4 v[78:81], v[48:49], off
	global_load_dwordx4 v[82:85], v194, s[10:11] offset:1024
	global_load_dwordx4 v[86:89], v[52:53], off offset:1024
	global_load_dwordx4 v[56:59], v194, s[10:11] offset:2048
	global_load_dwordx4 v[60:63], v[52:53], off offset:2048
	s_nop 0
	global_load_dwordx4 v[48:51], v194, s[10:11] offset:3072
	s_nop 0
	global_load_dwordx4 v[52:55], v[52:53], off offset:3072
	v_mul_f32_e32 v90, v47, v47
	v_fmac_f32_e32 v73, v44, v44
	v_fmac_f32_e32 v90, v46, v46
	v_add_f32_e32 v73, v73, v90
	v_mul_f32_e32 v90, v41, v41
	v_mul_f32_e32 v91, v43, v43
	v_fmac_f32_e32 v90, v40, v40
	v_fmac_f32_e32 v91, v42, v42
	v_add_f32_e32 v90, v90, v91
	v_add_f32_e32 v73, v73, v90
	v_mul_f32_e32 v90, v37, v37
	v_mul_f32_e32 v91, v39, v39
	v_mul_f32_e32 v70, v70, v70
	v_fmac_f32_e32 v90, v36, v36
	v_fmac_f32_e32 v91, v38, v38
	v_fmac_f32_e32 v70, v68, v68
	v_mul_f32_e32 v68, v71, v71
	v_add_f32_e32 v90, v90, v91
	v_fmac_f32_e32 v68, v69, v69
	v_add_f32_e32 v73, v90, v73
	v_add_f32_e32 v68, v70, v68
	v_add_f32_e32 v68, v68, v73
	ds_swizzle_b32 v69, v68 offset:swizzle(SWAP,1)
	v_lshl_add_u64 v[70:71], s[96:97], 0, v[64:65]
	v_lshl_add_u64 v[64:65], v[64:65], 0, s[92:93]
	v_lshl_add_u64 v[66:67], v[66:67], 0, s[64:65]
	s_mov_b32 s9, s7
	s_waitcnt lgkmcnt(0)
	v_add_f32_e32 v68, v68, v69
	ds_swizzle_b32 v69, v68 offset:swizzle(SWAP,2)
	s_waitcnt lgkmcnt(0)
	v_add_f32_e32 v68, v68, v69
	ds_swizzle_b32 v69, v68 offset:swizzle(SWAP,4)
	s_waitcnt lgkmcnt(0)
	v_add_f32_e32 v68, v68, v69
	ds_swizzle_b32 v69, v68 offset:swizzle(SWAP,8)
	s_waitcnt lgkmcnt(0)
	v_add_f32_e32 v68, v68, v69
	ds_swizzle_b32 v69, v68 offset:swizzle(SWAP,16)
	s_waitcnt lgkmcnt(0)
	v_add_f32_e32 v68, v68, v69
	v_mov_b32_e32 v69, v68
	s_nop 1
	v_permlane32_swap_b32_e32 v68, v69
	v_add_f32_e32 v68, v68, v69
	v_fmamk_f32 v68, v68, 0x3a800000, v193
	v_rsq_f32_e32 v68, v68
	s_waitcnt vmcnt(6)
	v_add_f32_e32 v80, 1.0, v80
	v_add_f32_e32 v81, 1.0, v81
	v_mul_f32_e32 v46, v46, v68
	v_mul_f32_e32 v47, v47, v68
	v_mul_f32_e32 v44, v44, v68
	v_mul_f32_e32 v45, v45, v68
	v_mul_f32_e32 v46, v2, v46
	v_mul_f32_e32 v47, v3, v47
	v_mul_f32_e32 v44, v0, v44
	v_mul_f32_e32 v45, v1, v45
	v_add_f32_e32 v78, 1.0, v78
	v_add_f32_e32 v79, 1.0, v79
	v_fma_f32 v46, v80, v46, v76
	v_fma_f32 v47, v81, v47, v77
	v_fma_f32 v44, v78, v44, v74
	v_fma_f32 v45, v79, v45, v75
	v_mul_f32_e32 v42, v42, v68
	v_mul_f32_e32 v43, v43, v68
	v_cvt_pk_bf16_f32 v44, v44, v45
	v_cvt_pk_bf16_f32 v45, v46, v47
	v_add_co_u32_e32 v46, vcc, s47, v70
	v_mul_f32_e32 v40, v40, v68
	v_mul_f32_e32 v41, v41, v68
	s_nop 0
	v_addc_co_u32_e32 v47, vcc, 0, v71, vcc
	global_store_dwordx2 v[46:47], v[44:45], off
	v_mul_f32_e32 v40, v4, v40
	v_mul_f32_e32 v41, v5, v41
	v_mul_f32_e32 v42, v6, v42
	v_mul_f32_e32 v43, v7, v43
	s_waitcnt vmcnt(5)
	v_add_f32_e32 v44, 1.0, v88
	v_add_f32_e32 v45, 1.0, v89
	v_add_f32_e32 v70, 1.0, v86
	v_add_f32_e32 v71, 1.0, v87
	v_fma_f32 v42, v44, v42, v84
	v_fma_f32 v43, v45, v43, v85
	v_fma_f32 v40, v70, v40, v82
	v_fma_f32 v41, v71, v41, v83
	v_mul_f32_e32 v38, v38, v68
	v_mul_f32_e32 v39, v39, v68
	v_cvt_pk_bf16_f32 v40, v40, v41
	v_cvt_pk_bf16_f32 v41, v42, v43
	v_mul_f32_e32 v36, v36, v68
	v_mul_f32_e32 v37, v37, v68
	global_store_dwordx2 v[46:47], v[40:41], off offset:512
	v_mul_f32_e32 v36, v8, v36
	v_mul_f32_e32 v37, v9, v37
	v_mul_f32_e32 v38, v10, v38
	v_mul_f32_e32 v39, v11, v39
	s_waitcnt vmcnt(4)
	v_add_f32_e32 v40, 1.0, v62
	v_add_f32_e32 v41, 1.0, v63
	v_add_f32_e32 v42, 1.0, v60
	v_add_f32_e32 v43, 1.0, v61
	v_fma_f32 v38, v40, v38, v58
	v_fma_f32 v39, v41, v39, v59
	v_fma_f32 v36, v42, v36, v56
	v_fma_f32 v37, v43, v37, v57
	v_mul_f32_e32 v18, v18, v68
	v_mul_f32_e32 v19, v19, v68
	v_cvt_pk_bf16_f32 v36, v36, v37
	v_cvt_pk_bf16_f32 v37, v38, v39
	v_mul_f32_e32 v16, v16, v68
	v_mul_f32_e32 v17, v17, v68
	global_store_dwordx2 v[46:47], v[36:37], off offset:1024
	v_mul_f32_e32 v16, v12, v16
	v_mul_f32_e32 v17, v13, v17
	v_mul_f32_e32 v18, v14, v18
	v_mul_f32_e32 v19, v15, v19
	s_waitcnt vmcnt(3)
	v_add_f32_e32 v36, 1.0, v54
	v_add_f32_e32 v37, 1.0, v55
	v_add_f32_e32 v38, 1.0, v52
	v_add_f32_e32 v39, 1.0, v53
	v_fma_f32 v18, v36, v18, v50
	v_fma_f32 v19, v37, v19, v51
	v_fma_f32 v16, v38, v16, v48
	v_fma_f32 v17, v39, v17, v49
	s_andn2_b64 vcc, exec, s[0:1]
	v_cvt_pk_bf16_f32 v16, v16, v17
	v_cvt_pk_bf16_f32 v17, v18, v19
	global_store_dwordx2 v[46:47], v[16:17], off offset:1536
	v_mov_b64_e32 v[16:17], v[20:21]
	v_mov_b64_e32 v[18:19], v[22:23]
	v_mov_b32_e32 v44, v32
	v_mov_b32_e32 v45, v33
	v_mov_b32_e32 v46, v34
	v_mov_b32_e32 v47, v35
	v_mov_b32_e32 v40, v28
	v_mov_b32_e32 v41, v29
	v_mov_b32_e32 v42, v30
	v_mov_b32_e32 v43, v31
	v_mov_b32_e32 v36, v24
	v_mov_b32_e32 v37, v25
	v_mov_b32_e32 v38, v26
	v_mov_b32_e32 v39, v27
	v_mov_b32_e32 v68, v20
	v_mov_b32_e32 v70, v21
	v_mov_b32_e32 v69, v22
	v_mov_b32_e32 v71, v23
	s_cbranch_vccz .LBB0_332

; __device__ __forceinline__ void norm_phase(const float* xL, const float* xC, const float* gain, const float* modl  , int ishift, bf16_t* H, int nrows,
;                                            const float* part, int nsplit, const float* pgate  , float pscale, float* xCw) {
;     ...
;     if (nsplit > 0) for (int row = RL + gw; row < nrows; row += NGW) {
;         f32x4 v[4];
;         const float* xr = xC + (size_t)(row - RL) * DM;
; #pragma unroll
;         for (int j = 0; j < 4; ++j) v[j] = *(const f32x4*)(xr + 4 * lane + 256 * j);
; #pragma unroll
;         for (int j = 0; j < 4; ++j) {
;             f32x4 pv[11];
; #pragma unroll
;             for (int ks = 0; ks < 11; ++ks) if (ks < nsplit) pv[ks] = *(const f32x4*)(part + ((size_t)ks * RC + (row - RL)) * DM + 4 * lane + 256 * j);
;             f32x4 sum = {0.f, 0.f, 0.f, 0.f};
; #pragma unroll
;             for (int ks = 0; ks < 11; ++ks) if (ks < nsplit) sum += pv[ks];
;             v[j] += sum * (*(const f32x4*)(pgate + 4 * lane + 256 * j) * pscale);
;             *(f32x4*)(xCw + (size_t)(row - RL) * DM + 4 * lane + 256 * j) = v[j];
.LBB0_334:
	v_lshl_add_u64 v[54:55], s[96:97], 0, v[72:73]
	v_add_co_u32_e32 v32, vcc, 0x12000000, v54
	s_add_i32 s0, s0, s88
	s_nop 0
	v_addc_co_u32_e32 v33, vcc, 0, v55, vcc
	v_add_co_u32_e32 v34, vcc, 0x21b80000, v54
	global_load_dwordx4 v[20:23], v[32:33], off
	global_load_dwordx4 v[28:31], v[32:33], off offset:1024
	global_load_dwordx4 v[24:27], v[32:33], off offset:2048
	global_load_dwordx4 v[16:19], v[32:33], off offset:3072
	v_addc_co_u32_e32 v35, vcc, 0, v55, vcc
	v_add_co_u32_e32 v36, vcc, 0x21f80000, v54
	global_load_dwordx4 v[56:59], v[34:35], off
	s_nop 0
	v_addc_co_u32_e32 v37, vcc, 0, v55, vcc
	v_add_co_u32_e32 v38, vcc, 0x22380000, v54
	global_load_dwordx4 v[60:63], v[36:37], off
	s_nop 0
	v_addc_co_u32_e32 v39, vcc, 0, v55, vcc
	v_add_co_u32_e32 v40, vcc, 0x22780000, v54
	global_load_dwordx4 v[74:77], v[38:39], off
	s_nop 0
	v_addc_co_u32_e32 v41, vcc, 0, v55, vcc
	v_add_co_u32_e32 v42, vcc, 0x22b80000, v54
	global_load_dwordx4 v[78:81], v[40:41], off
	s_nop 0
	v_addc_co_u32_e32 v43, vcc, 0, v55, vcc
	v_add_co_u32_e32 v44, vcc, 0x22f80000, v54
	global_load_dwordx4 v[82:85], v[42:43], off
	s_nop 0
	v_addc_co_u32_e32 v45, vcc, 0, v55, vcc
	v_add_co_u32_e32 v46, vcc, 0x23380000, v54
	global_load_dwordx4 v[86:89], v[44:45], off
	s_nop 0
	v_addc_co_u32_e32 v47, vcc, 0, v55, vcc
	v_add_co_u32_e32 v48, vcc, 0x23780000, v54
	global_load_dwordx4 v[90:93], v[46:47], off
	s_nop 0
	v_addc_co_u32_e32 v49, vcc, 0, v55, vcc
	v_add_co_u32_e32 v50, vcc, 0x23b80000, v54
	global_load_dwordx4 v[94:97], v[48:49], off
	s_nop 0
	v_addc_co_u32_e32 v51, vcc, 0, v55, vcc
	v_add_co_u32_e32 v52, vcc, 0x23f80000, v54
	global_load_dwordx4 v[98:101], v[50:51], off
	s_nop 0
	v_addc_co_u32_e32 v53, vcc, 0, v55, vcc
	v_add_co_u32_e32 v54, vcc, 0x24380000, v54
	global_load_dwordx4 v[102:105], v[52:53], off
	s_nop 0
	v_addc_co_u32_e32 v55, vcc, 0, v55, vcc
	global_load_dwordx4 v[106:109], v[54:55], off
	v_lshl_add_u64 v[72:73], v[72:73], 0, s[64:65]
	s_cmp_lt_i32 s0, 0x8400
	s_waitcnt vmcnt(10)
	v_add_f32_e32 v58, 0, v58
	v_add_f32_e32 v59, 0, v59
	v_add_f32_e32 v56, 0, v56
	v_add_f32_e32 v57, 0, v57
	s_waitcnt vmcnt(9)
	v_add_f32_e32 v58, v58, v62
	v_add_f32_e32 v59, v59, v63
	v_add_f32_e32 v56, v56, v60
	v_add_f32_e32 v57, v57, v61
	s_waitcnt vmcnt(8)
	v_add_f32_e32 v58, v58, v76
	v_add_f32_e32 v59, v59, v77
	v_add_f32_e32 v56, v56, v74
	v_add_f32_e32 v57, v57, v75
	s_waitcnt vmcnt(7)
	v_add_f32_e32 v58, v58, v80
	v_add_f32_e32 v59, v59, v81
	v_add_f32_e32 v56, v56, v78
	v_add_f32_e32 v57, v57, v79
	s_waitcnt vmcnt(6)
	v_add_f32_e32 v58, v58, v84
	v_add_f32_e32 v59, v59, v85
	v_add_f32_e32 v56, v56, v82
	v_add_f32_e32 v57, v57, v83
	s_waitcnt vmcnt(5)
	v_add_f32_e32 v58, v58, v88
	v_add_f32_e32 v59, v59, v89
	v_add_f32_e32 v56, v56, v86
	v_add_f32_e32 v57, v57, v87
	s_waitcnt vmcnt(4)
	v_add_f32_e32 v58, v58, v92
	v_add_f32_e32 v59, v59, v93
	v_add_f32_e32 v56, v56, v90
	v_add_f32_e32 v57, v57, v91
	s_waitcnt vmcnt(3)
	v_add_f32_e32 v58, v58, v96
	v_add_f32_e32 v59, v59, v97
	v_add_f32_e32 v56, v56, v94
	v_add_f32_e32 v57, v57, v95
	s_waitcnt vmcnt(2)
	v_add_f32_e32 v58, v58, v100
	v_add_f32_e32 v59, v59, v101
	v_add_f32_e32 v56, v56, v98
	v_add_f32_e32 v57, v57, v99
	s_waitcnt vmcnt(1)
	v_add_f32_e32 v58, v58, v104
	v_add_f32_e32 v59, v59, v105
	v_add_f32_e32 v60, v56, v102
	v_add_f32_e32 v61, v57, v103
	s_waitcnt vmcnt(0)
	v_add_f32_e32 v56, v58, v108
	v_add_f32_e32 v57, v59, v109
	v_add_f32_e32 v58, v60, v106
	v_add_f32_e32 v59, v61, v107
	global_load_dwordx4 v[60:63], v[64:65], off
	s_waitcnt vmcnt(0)
	v_mul_f32_e32 v62, 0.5, v62
	v_mul_f32_e32 v63, 0.5, v63
	v_mul_f32_e32 v60, 0.5, v60
	v_mul_f32_e32 v61, 0.5, v61
	v_fma_f32 v22, v56, v62, v22
	v_fma_f32 v23, v57, v63, v23
	v_fma_f32 v20, v58, v60, v20
	v_fma_f32 v21, v59, v61, v21
	global_store_dwordx4 v[32:33], v[20:23], off
	global_load_dwordx4 v[56:59], v[34:35], off offset:1024
	global_load_dwordx4 v[60:63], v[36:37], off offset:1024
	global_load_dwordx4 v[74:77], v[38:39], off offset:1024
	global_load_dwordx4 v[78:81], v[40:41], off offset:1024
	global_load_dwordx4 v[82:85], v[42:43], off offset:1024
	global_load_dwordx4 v[86:89], v[44:45], off offset:1024
	global_load_dwordx4 v[90:93], v[46:47], off offset:1024
	global_load_dwordx4 v[94:97], v[48:49], off offset:1024
	global_load_dwordx4 v[98:101], v[50:51], off offset:1024
	global_load_dwordx4 v[102:105], v[52:53], off offset:1024
	global_load_dwordx4 v[106:109], v[54:55], off offset:1024
	s_waitcnt vmcnt(10)
	v_add_f32_e32 v58, 0, v58
	v_add_f32_e32 v59, 0, v59
	v_add_f32_e32 v56, 0, v56
	v_add_f32_e32 v57, 0, v57
	s_waitcnt vmcnt(9)
	v_add_f32_e32 v58, v58, v62
	v_add_f32_e32 v59, v59, v63
	v_add_f32_e32 v56, v56, v60
	v_add_f32_e32 v57, v57, v61
	s_waitcnt vmcnt(8)
	v_add_f32_e32 v58, v58, v76
	v_add_f32_e32 v59, v59, v77
	v_add_f32_e32 v56, v56, v74
	v_add_f32_e32 v57, v57, v75
	s_waitcnt vmcnt(7)
	v_add_f32_e32 v58, v58, v80
	v_add_f32_e32 v59, v59, v81
	v_add_f32_e32 v56, v56, v78
	v_add_f32_e32 v57, v57, v79
	s_waitcnt vmcnt(6)
	v_add_f32_e32 v58, v58, v84
	v_add_f32_e32 v59, v59, v85
	v_add_f32_e32 v56, v56, v82
	v_add_f32_e32 v57, v57, v83
	s_waitcnt vmcnt(5)
	v_add_f32_e32 v58, v58, v88
	v_add_f32_e32 v59, v59, v89
	v_add_f32_e32 v56, v56, v86
	v_add_f32_e32 v57, v57, v87
	s_waitcnt vmcnt(4)
	v_add_f32_e32 v58, v58, v92
	v_add_f32_e32 v59, v59, v93
	v_add_f32_e32 v56, v56, v90
	v_add_f32_e32 v57, v57, v91
	s_waitcnt vmcnt(3)
	v_add_f32_e32 v58, v58, v96
	v_add_f32_e32 v59, v59, v97
	v_add_f32_e32 v56, v56, v94
	v_add_f32_e32 v57, v57, v95
	s_waitcnt vmcnt(2)
	v_add_f32_e32 v58, v58, v100
	v_add_f32_e32 v59, v59, v101
	v_add_f32_e32 v56, v56, v98
	v_add_f32_e32 v57, v57, v99
	s_waitcnt vmcnt(1)
; __device__ __forceinline__ void norm_phase(const float* xL, const float* xC, const float* gain, const float* modl  , int ishift, bf16_t* H, int nrows,
;                                            const float* part, int nsplit, const float* pgate  , float pscale, float* xCw) {
;     ...
;     if (nsplit > 0) for (int row = RL + gw; row < nrows; row += NGW) {
;         f32x4 v[4];
;         const float* xr = xC + (size_t)(row - RL) * DM;
; #pragma unroll
;         for (int j = 0; j < 4; ++j) v[j] = *(const f32x4*)(xr + 4 * lane + 256 * j);
; #pragma unroll
;         for (int j = 0; j < 4; ++j) {
;             f32x4 pv[11];
; #pragma unroll
;             for (int ks = 0; ks < 11; ++ks) if (ks < nsplit) pv[ks] = *(const f32x4*)(part + ((size_t)ks * RC + (row - RL)) * DM + 4 * lane + 256 * j);
;             f32x4 sum = {0.f, 0.f, 0.f, 0.f};
; #pragma unroll
;             for (int ks = 0; ks < 11; ++ks) if (ks < nsplit) sum += pv[ks];
;             v[j] += sum * (*(const f32x4*)(pgate + 4 * lane + 256 * j) * pscale);
;             *(f32x4*)(xCw + (size_t)(row - RL) * DM + 4 * lane + 256 * j) = v[j];
	v_add_f32_e32 v58, v58, v104
	v_add_f32_e32 v59, v59, v105
	v_add_f32_e32 v56, v56, v102
	v_add_f32_e32 v57, v57, v103
	s_waitcnt vmcnt(0)
	v_add_f32_e32 v60, v58, v108
	v_add_f32_e32 v61, v59, v109
	v_add_f32_e32 v62, v56, v106
	v_add_f32_e32 v63, v57, v107
	global_load_dwordx4 v[56:59], v[64:65], off offset:1024
	s_waitcnt vmcnt(0)
	v_mul_f32_e32 v58, 0.5, v58
	v_mul_f32_e32 v59, 0.5, v59
	v_mul_f32_e32 v56, 0.5, v56
	v_mul_f32_e32 v57, 0.5, v57
	v_fma_f32 v30, v60, v58, v30
	v_fma_f32 v31, v61, v59, v31
	v_fma_f32 v28, v62, v56, v28
	v_fma_f32 v29, v63, v57, v29
	global_store_dwordx4 v[32:33], v[28:31], off offset:1024
	global_load_dwordx4 v[56:59], v[34:35], off offset:2048
	global_load_dwordx4 v[60:63], v[36:37], off offset:2048
	global_load_dwordx4 v[74:77], v[38:39], off offset:2048
	global_load_dwordx4 v[78:81], v[40:41], off offset:2048
	global_load_dwordx4 v[82:85], v[42:43], off offset:2048
	global_load_dwordx4 v[86:89], v[44:45], off offset:2048
	global_load_dwordx4 v[90:93], v[46:47], off offset:2048
	global_load_dwordx4 v[94:97], v[48:49], off offset:2048
	global_load_dwordx4 v[98:101], v[50:51], off offset:2048
	global_load_dwordx4 v[102:105], v[52:53], off offset:2048
	global_load_dwordx4 v[106:109], v[54:55], off offset:2048
	s_waitcnt vmcnt(10)
	v_add_f32_e32 v58, 0, v58
	v_add_f32_e32 v59, 0, v59
	v_add_f32_e32 v56, 0, v56
	v_add_f32_e32 v57, 0, v57
	s_waitcnt vmcnt(9)
	v_add_f32_e32 v58, v58, v62
	v_add_f32_e32 v59, v59, v63
	v_add_f32_e32 v56, v56, v60
	v_add_f32_e32 v57, v57, v61
	s_waitcnt vmcnt(8)
	v_add_f32_e32 v58, v58, v76
	v_add_f32_e32 v59, v59, v77
	v_add_f32_e32 v56, v56, v74
	v_add_f32_e32 v57, v57, v75
	s_waitcnt vmcnt(7)
	v_add_f32_e32 v58, v58, v80
	v_add_f32_e32 v59, v59, v81
	v_add_f32_e32 v56, v56, v78
	v_add_f32_e32 v57, v57, v79
	s_waitcnt vmcnt(6)
	v_add_f32_e32 v58, v58, v84
	v_add_f32_e32 v59, v59, v85
	v_add_f32_e32 v56, v56, v82
	v_add_f32_e32 v57, v57, v83
	s_waitcnt vmcnt(5)
	v_add_f32_e32 v58, v58, v88
	v_add_f32_e32 v59, v59, v89
	v_add_f32_e32 v56, v56, v86
	v_add_f32_e32 v57, v57, v87
	s_waitcnt vmcnt(4)
	v_add_f32_e32 v58, v58, v92
	v_add_f32_e32 v59, v59, v93
	v_add_f32_e32 v56, v56, v90
	v_add_f32_e32 v57, v57, v91
	s_waitcnt vmcnt(3)
	v_add_f32_e32 v58, v58, v96
	v_add_f32_e32 v59, v59, v97
	v_add_f32_e32 v56, v56, v94
	v_add_f32_e32 v57, v57, v95
	s_waitcnt vmcnt(2)
	v_add_f32_e32 v58, v58, v100
	v_add_f32_e32 v59, v59, v101
	v_add_f32_e32 v56, v56, v98
	v_add_f32_e32 v57, v57, v99
	s_waitcnt vmcnt(1)
	v_add_f32_e32 v58, v58, v104
	v_add_f32_e32 v59, v59, v105
	v_add_f32_e32 v56, v56, v102
	v_add_f32_e32 v57, v57, v103
	s_waitcnt vmcnt(0)
	v_add_f32_e32 v60, v58, v108
	v_add_f32_e32 v61, v59, v109
	v_add_f32_e32 v62, v56, v106
	v_add_f32_e32 v63, v57, v107
	global_load_dwordx4 v[56:59], v[64:65], off offset:2048
	s_waitcnt vmcnt(0)
	v_mul_f32_e32 v58, 0.5, v58
	v_mul_f32_e32 v59, 0.5, v59
	v_mul_f32_e32 v56, 0.5, v56
	v_mul_f32_e32 v57, 0.5, v57
	v_fma_f32 v26, v60, v58, v26
	v_fma_f32 v27, v61, v59, v27
	v_fma_f32 v24, v62, v56, v24
	v_fma_f32 v25, v63, v57, v25
	global_store_dwordx4 v[32:33], v[24:27], off offset:2048
	global_load_dwordx4 v[56:59], v[34:35], off offset:3072
	s_nop 0
	global_load_dwordx4 v[34:37], v[36:37], off offset:3072
	s_nop 0
	global_load_dwordx4 v[60:63], v[38:39], off offset:3072
	s_nop 0
	global_load_dwordx4 v[38:41], v[40:41], off offset:3072
	s_nop 0
	global_load_dwordx4 v[74:77], v[42:43], off offset:3072
	s_nop 0
	global_load_dwordx4 v[42:45], v[44:45], off offset:3072
	s_nop 0
	global_load_dwordx4 v[78:81], v[46:47], off offset:3072
	s_nop 0
	global_load_dwordx4 v[46:49], v[48:49], off offset:3072
	s_nop 0
	global_load_dwordx4 v[82:85], v[50:51], off offset:3072
	s_nop 0
	global_load_dwordx4 v[50:53], v[52:53], off offset:3072
	s_nop 0
	global_load_dwordx4 v[86:89], v[54:55], off offset:3072
	s_waitcnt vmcnt(10)
	v_add_f32_e32 v54, 0, v58
	v_add_f32_e32 v55, 0, v59
	v_add_f32_e32 v56, 0, v56
	v_add_f32_e32 v57, 0, v57
	s_waitcnt vmcnt(9)
	v_add_f32_e32 v36, v54, v36
	v_add_f32_e32 v37, v55, v37
	v_add_f32_e32 v34, v56, v34
	v_add_f32_e32 v35, v57, v35
	s_waitcnt vmcnt(8)
	v_add_f32_e32 v36, v36, v62
	v_add_f32_e32 v37, v37, v63
	v_add_f32_e32 v34, v34, v60
	v_add_f32_e32 v35, v35, v61
	s_waitcnt vmcnt(7)
	v_add_f32_e32 v36, v36, v40
	v_add_f32_e32 v37, v37, v41
	v_add_f32_e32 v34, v34, v38
	v_add_f32_e32 v35, v35, v39
	s_waitcnt vmcnt(6)
	v_add_f32_e32 v36, v36, v76
	v_add_f32_e32 v37, v37, v77
	v_add_f32_e32 v34, v34, v74
	v_add_f32_e32 v35, v35, v75
	s_waitcnt vmcnt(5)
	v_add_f32_e32 v36, v36, v44
	v_add_f32_e32 v37, v37, v45
	v_add_f32_e32 v34, v34, v42
	v_add_f32_e32 v35, v35, v43
	s_waitcnt vmcnt(4)
	v_add_f32_e32 v36, v36, v80
	v_add_f32_e32 v37, v37, v81
	v_add_f32_e32 v34, v34, v78
	v_add_f32_e32 v35, v35, v79
	s_waitcnt vmcnt(3)
	v_add_f32_e32 v36, v36, v48
	v_add_f32_e32 v37, v37, v49
	v_add_f32_e32 v34, v34, v46
	v_add_f32_e32 v35, v35, v47
	s_waitcnt vmcnt(2)
	v_add_f32_e32 v36, v36, v84
	v_add_f32_e32 v37, v37, v85
	v_add_f32_e32 v34, v34, v82
	v_add_f32_e32 v35, v35, v83
	s_waitcnt vmcnt(1)
; __device__ __forceinline__ unsigned cvt_pk_bf16(float lo, float hi) { const f32x2 v = {lo, hi}; const bf16x2_t b = __builtin_convertvector(v, bf16x2_t); return __builtin_bit_cast(unsigned, b); }
; __device__ __forceinline__ float wave_sum(float v) { return xadd32(sum32(v)); }
; __device__ __forceinline__ void norm_row(const f32x4 (&v)[4], const f32x4 (&gn)[4], const float* sh, bf16_t* hrow, int lane) {
;     const float* scl = sh + 1024;
;     f32x4 sv[4], cv[4];
; #pragma unroll
;     for (int j = 0; j < 4; ++j) { sv[j] = *(const f32x4*)(sh + 4 * lane + 256 * j); cv[j] = *(const f32x4*)(scl + 4 * lane + 256 * j); }
;     float ss = 0.f;
; #pragma unroll
;     for (int j = 0; j < 4; ++j) ss += (v[j][0] * v[j][0] + v[j][1] * v[j][1]) + (v[j][2] * v[j][2] + v[j][3] * v[j][3]);
;     const float rstd = __builtin_amdgcn_rsqf(wave_sum(ss) * (1.0f / DM) + EPS);
; #pragma unroll
;     for (int j = 0; j < 4; ++j) {
;         const f32x4 y = v[j] * rstd * gn[j] * (cv[j] + 1.0f) + sv[j];
;         u32x2 w; w.x = cvt_pk_bf16(y[0], y[1]); w.y = cvt_pk_bf16(y[2], y[3]);
;         *(u32x2*)(hrow + 4 * lane + 256 * j) = w;
;     }
; }
; __device__ __forceinline__ void norm_phase(const float* xL, const float* xC, const float* gain, const float* modl  , int ishift, bf16_t* H, int nrows,
;                                            const float* part, int nsplit, const float* pgate  , float pscale, float* xCw) {
;     ...
;     if (nsplit > 0) for (int row = RL + gw; row < nrows; row += NGW) {
;         f32x4 v[4];
;         const float* xr = xC + (size_t)(row - RL) * DM;
; #pragma unroll
;         for (int j = 0; j < 4; ++j) v[j] = *(const f32x4*)(xr + 4 * lane + 256 * j);
; #pragma unroll
;         for (int j = 0; j < 4; ++j) {
;             f32x4 pv[11];
; #pragma unroll
;             for (int ks = 0; ks < 11; ++ks) if (ks < nsplit) pv[ks] = *(const f32x4*)(part + ((size_t)ks * RC + (row - RL)) * DM + 4 * lane + 256 * j);
;             f32x4 sum = {0.f, 0.f, 0.f, 0.f};
; #pragma unroll
;             for (int ks = 0; ks < 11; ++ks) if (ks < nsplit) sum += pv[ks];
;             v[j] += sum * (*(const f32x4*)(pgate + 4 * lane + 256 * j) * pscale);
;             *(f32x4*)(xCw + (size_t)(row - RL) * DM + 4 * lane + 256 * j) = v[j];
;         }
;         norm_row(v, gn, modl + (size_t)4 * 9216 + ishift * 1024, H + (size_t)row * DM, lane);
	v_add_f32_e32 v36, v36, v52
	v_add_f32_e32 v37, v37, v53
	v_add_f32_e32 v34, v34, v50
	v_add_f32_e32 v35, v35, v51
	s_waitcnt vmcnt(0)
	v_add_f32_e32 v38, v36, v88
	v_add_f32_e32 v39, v37, v89
	v_add_f32_e32 v40, v34, v86
	v_add_f32_e32 v41, v35, v87
	global_load_dwordx4 v[34:37], v[64:65], off offset:3072
	v_mul_f32_e32 v74, v21, v21
	v_mul_f32_e32 v75, v23, v23
	v_fmac_f32_e32 v74, v20, v20
	v_fmac_f32_e32 v75, v22, v22
	v_add_f32_e32 v74, v74, v75
	v_mul_f32_e32 v75, v29, v29
	v_mul_f32_e32 v76, v31, v31
	v_fmac_f32_e32 v75, v28, v28
	v_fmac_f32_e32 v76, v30, v30
	v_add_f32_e32 v75, v75, v76
	v_add_f32_e32 v74, v74, v75
	v_mul_f32_e32 v75, v25, v25
	v_mul_f32_e32 v76, v27, v27
	v_fmac_f32_e32 v75, v24, v24
	v_fmac_f32_e32 v76, v26, v26
	v_add_f32_e32 v75, v75, v76
	v_add_f32_e32 v74, v74, v75
	s_waitcnt vmcnt(0)
	v_mul_f32_e32 v36, 0.5, v36
	v_mul_f32_e32 v37, 0.5, v37
	v_mul_f32_e32 v34, 0.5, v34
	v_mul_f32_e32 v35, 0.5, v35
	v_fma_f32 v18, v38, v36, v18
	v_fma_f32 v19, v39, v37, v19
	v_fma_f32 v16, v40, v34, v16
	v_fma_f32 v17, v41, v35, v17
	global_store_dwordx4 v[32:33], v[16:19], off offset:3072
	global_load_dwordx4 v[56:59], v[66:67], off
	global_load_dwordx4 v[60:63], v[68:69], off
	global_load_dwordx4 v[48:51], v[66:67], off offset:1024
	global_load_dwordx4 v[52:55], v[68:69], off offset:1024
	global_load_dwordx4 v[40:43], v[66:67], off offset:2048
	global_load_dwordx4 v[44:47], v[68:69], off offset:2048
	global_load_dwordx4 v[32:35], v[66:67], off offset:3072
	global_load_dwordx4 v[36:39], v[68:69], off offset:3072
	v_mul_f32_e32 v75, v17, v17
	v_mul_f32_e32 v76, v19, v19
	v_fmac_f32_e32 v75, v16, v16
	v_fmac_f32_e32 v76, v18, v18
	v_add_f32_e32 v75, v75, v76
	v_add_f32_e32 v74, v74, v75
	ds_swizzle_b32 v75, v74 offset:swizzle(SWAP,1)
	v_lshl_add_u64 v[76:77], s[96:97], 0, v[70:71]
	v_lshl_add_u64 v[70:71], v[70:71], 0, s[92:93]
	s_waitcnt lgkmcnt(0)
	v_add_f32_e32 v74, v74, v75
	ds_swizzle_b32 v75, v74 offset:swizzle(SWAP,2)
	s_waitcnt lgkmcnt(0)
	v_add_f32_e32 v74, v74, v75
	ds_swizzle_b32 v75, v74 offset:swizzle(SWAP,4)
	s_waitcnt lgkmcnt(0)
	v_add_f32_e32 v74, v74, v75
	ds_swizzle_b32 v75, v74 offset:swizzle(SWAP,8)
	s_waitcnt lgkmcnt(0)
	v_add_f32_e32 v74, v74, v75
	ds_swizzle_b32 v75, v74 offset:swizzle(SWAP,16)
	s_waitcnt lgkmcnt(0)
	v_add_f32_e32 v74, v74, v75
	v_mov_b32_e32 v75, v74
	s_nop 1
	v_permlane32_swap_b32_e32 v74, v75
	v_add_f32_e32 v74, v74, v75
	v_fmamk_f32 v74, v74, 0x3a800000, v193
	v_rsq_f32_e32 v74, v74
	s_waitcnt vmcnt(6)
	v_add_f32_e32 v62, 1.0, v62
	v_add_f32_e32 v63, 1.0, v63
	v_mul_f32_e32 v22, v22, v74
	v_mul_f32_e32 v23, v23, v74
	v_mul_f32_e32 v20, v20, v74
	v_mul_f32_e32 v21, v21, v74
	v_mul_f32_e32 v22, v2, v22
	v_mul_f32_e32 v23, v3, v23
	v_mul_f32_e32 v20, v0, v20
	v_mul_f32_e32 v21, v1, v21
	v_add_f32_e32 v60, 1.0, v60
	v_add_f32_e32 v61, 1.0, v61
	v_fma_f32 v22, v62, v22, v58
	v_fma_f32 v23, v63, v23, v59
	v_fma_f32 v20, v60, v20, v56
	v_fma_f32 v21, v61, v21, v57
	v_mul_f32_e32 v28, v28, v74
	v_mul_f32_e32 v29, v29, v74
	v_cvt_pk_bf16_f32 v20, v20, v21
	v_cvt_pk_bf16_f32 v21, v22, v23
	v_add_co_u32_e32 v22, vcc, s47, v76
	v_mul_f32_e32 v28, v4, v28
	v_mul_f32_e32 v29, v5, v29
	s_nop 0
	v_addc_co_u32_e32 v23, vcc, 0, v77, vcc
	global_store_dwordx2 v[22:23], v[20:21], off
	v_mul_f32_e32 v20, v30, v74
	v_mul_f32_e32 v21, v31, v74
	s_waitcnt vmcnt(5)
	v_add_f32_e32 v30, 1.0, v54
	v_add_f32_e32 v31, 1.0, v55
	v_mul_f32_e32 v20, v6, v20
	v_mul_f32_e32 v21, v7, v21
	v_add_f32_e32 v52, 1.0, v52
	v_add_f32_e32 v53, 1.0, v53
	v_fma_f32 v20, v30, v20, v50
	v_fma_f32 v21, v31, v21, v51
	v_fma_f32 v28, v52, v28, v48
	v_fma_f32 v29, v53, v29, v49
	v_mul_f32_e32 v24, v24, v74
	v_mul_f32_e32 v25, v25, v74
	v_cvt_pk_bf16_f32 v28, v28, v29
	v_cvt_pk_bf16_f32 v29, v20, v21
	v_mul_f32_e32 v20, v26, v74
	v_mul_f32_e32 v21, v27, v74
	global_store_dwordx2 v[22:23], v[28:29], off offset:512
	v_mul_f32_e32 v24, v8, v24
	v_mul_f32_e32 v25, v9, v25
	v_mul_f32_e32 v20, v10, v20
	v_mul_f32_e32 v21, v11, v21
	s_waitcnt vmcnt(4)
	v_add_f32_e32 v26, 1.0, v46
	v_add_f32_e32 v27, 1.0, v47
	v_add_f32_e32 v28, 1.0, v44
	v_add_f32_e32 v29, 1.0, v45
	v_fma_f32 v20, v26, v20, v42
	v_fma_f32 v21, v27, v21, v43
	v_fma_f32 v24, v28, v24, v40
	v_fma_f32 v25, v29, v25, v41
	v_mul_f32_e32 v18, v18, v74
	v_mul_f32_e32 v19, v19, v74
	v_cvt_pk_bf16_f32 v24, v24, v25
	v_cvt_pk_bf16_f32 v25, v20, v21
	v_mul_f32_e32 v16, v16, v74
	v_mul_f32_e32 v17, v17, v74
	global_store_dwordx2 v[22:23], v[24:25], off offset:1024
	v_mul_f32_e32 v16, v12, v16
	v_mul_f32_e32 v17, v13, v17
	v_mul_f32_e32 v18, v14, v18
	v_mul_f32_e32 v19, v15, v19
	s_waitcnt vmcnt(3)
	v_add_f32_e32 v20, 1.0, v38
	v_add_f32_e32 v21, 1.0, v39
	v_add_f32_e32 v24, 1.0, v36
	v_add_f32_e32 v25, 1.0, v37
	v_fma_f32 v18, v20, v18, v34
	v_fma_f32 v19, v21, v19, v35
	v_fma_f32 v16, v24, v16, v32
	v_fma_f32 v17, v25, v17, v33
	s_nop 0
	v_cvt_pk_bf16_f32 v16, v16, v17
	v_cvt_pk_bf16_f32 v17, v18, v19
	global_store_dwordx2 v[22:23], v[16:17], off offset:1536
	s_cbranch_scc1 .LBB0_334

;     __device__ __forceinline__ void operator()(const f32x4 (&acc)[2][2][4][2], const Unit& u, int wr, int wc, int fr, int fq) const {
;     ...
; #pragma unroll
;             for (int bj = 0; bj < 2; ++bj) {
;                 const int j = (u.pn - 4) * 256 + 128 * bj + 32 * wc + 8 * fq;
;                 const int which = j >= 384 ? 1 : 0; const int rem = j - which * 384; const int ch = rem / 48; const int sidx = rem - ch * 48;
;                 const int blk = sidx >= 24 ? 1 : 0; const int ii = sidx - blk * 24;
;                 bf16_t* dst = (bf16_t*)(mx + (which ? MX_KC : MX_QC)) + (size_t)ch * R * 48 + sidx;
;                 const float qs = which ? 1.0f : 0.14433756729740643f * LOG2E;
;                 float fq4[4];
; #pragma unroll
;                 for (int e = 0; e < 4; ++e) fq4[e] = fast_exp2(-(float)(ii / 2 + e) * (13.287712379549449f / 12.0f)) * 0.15915494309189535f;
; #pragma unroll
;                 for (int ai = 0; ai < 2; ++ai)
; #pragma unroll
;                     for (int m = 0; m < 4; ++m) {
;                         const int row = row0 + ai * HALF + m * 16;
;                         f32x4 x0 = acc[ai][bj][m][0] * qs, x1 = acc[ai][bj][m][1] * qs;
;                         if (latent) {
;                             const int t = row & (SEQ - 1); const float pos = blk ? (float)(t & 63) : (float)(t >> 6);
;                             const float a0 = pos * fq4[0], a1 = pos * fq4[1], a2 = pos * fq4[2], a3 = pos * fq4[3];
;                             const float c0 = __builtin_amdgcn_cosf(a0), s0 = __builtin_amdgcn_sinf(a0), c1 = __builtin_amdgcn_cosf(a1), s1 = __builtin_amdgcn_sinf(a1);
;                             const float c2 = __builtin_amdgcn_cosf(a2), s2 = __builtin_amdgcn_sinf(a2), c3 = __builtin_amdgcn_cosf(a3), s3 = __builtin_amdgcn_sinf(a3);
;                             x0 = (f32x4){x0[0] * c0 - x0[1] * s0, x0[1] * c0 + x0[0] * s0, x0[2] * c1 - x0[3] * s1, x0[3] * c1 + x0[2] * s1};
;                             x1 = (f32x4){x1[0] * c2 - x1[1] * s2, x1[1] * c2 + x1[0] * s2, x1[2] * c3 - x1[3] * s3, x1[3] * c3 + x1[2] * s3};
;                         }
;                         u32x4 w; w.x = cvt_pk_bf16(x0[0], x0[1]); w.y = cvt_pk_bf16(x0[2], x0[3]); w.z = cvt_pk_bf16(x1[0], x1[1]); w.w = cvt_pk_bf16(x1[2], x1[3]);
;                         *(u32x4*)(dst + (size_t)row * 48) = w;
.LBB0_414:
	s_add_i32 s0, s11, s5
	s_cmpk_lt_i32 s41, 0x80
	v_add_u32_e32 v140, s0, v235
	s_cselect_b64 s[18:19], -1, 0
	s_cmp_gt_i32 s42, 1
	s_mov_b64 s[0:1], -1
	s_cbranch_scc0 .LBB0_452
	s_cmp_lt_u32 s42, 4
	s_cbranch_scc1 .LBB0_449
	s_lshl_b32 s0, s42, 8
	s_add_i32 s0, s77, s0
	v_lshl_add_u32 v173, v236, 3, s0
	v_cmp_lt_i32_e64 s[36:37], s20, v173
	s_and_b64 vcc, exec, s[18:19]
	s_nop 0
	v_cndmask_b32_e64 v141, 0, v207, s[36:37]
	v_add_u32_e32 v142, v141, v173
	v_mul_hi_i32 v141, v142, s21
	v_lshrrev_b32_e32 v143, 31, v141
	v_ashrrev_i32_e32 v141, 3, v141
	v_add_u32_e32 v154, v141, v143
	v_mad_u64_u32 v[144:145], s[0:1], v154, s26, v[142:143]
	v_cmp_lt_i32_e64 s[38:39], 23, v144
	v_not_b32_e32 v141, 23
	s_nop 0
	v_cndmask_b32_e64 v141, 0, v141, s[38:39]
	v_add_u32_e32 v141, v141, v144
	v_lshrrev_b32_e32 v142, 31, v141
	v_add_u32_e32 v141, v141, v142
	v_ashrrev_i32_e32 v142, 1, v141
	v_cvt_f32_i32_e32 v143, v142
	v_add_u32_e32 v141, 1, v142
	v_add_u32_e32 v146, 2, v142
	v_add_u32_e32 v142, 3, v142
	v_cvt_f32_i32_e32 v142, v142
	v_cvt_f32_i32_e32 v145, v141
	v_cvt_f32_i32_e32 v146, v146
	v_mul_f32_e32 v143, 0xbf8dbc50, v143
	v_mul_f32_e32 v142, 0xbf8dbc50, v142
	v_exp_f32_e32 v142, v142
	v_mul_f32_e32 v145, 0xbf8dbc50, v145
	v_mul_f32_e32 v146, 0xbf8dbc50, v146
	v_exp_f32_e32 v143, v143
	v_exp_f32_e32 v145, v145
	v_exp_f32_e32 v146, v146
	v_mul_f32_e32 v177, 0.15915494, v142
	v_mov_b32_e32 v142, 0x3e553b94
	v_cndmask_b32_e64 v142, v142, 1.0, s[36:37]
	v_and_b32_e32 v141, 63, v235
	v_mul_f32_e32 v174, 0.15915494, v143
	v_mul_f32_e32 v175, 0.15915494, v145
	v_mul_f32_e32 v176, 0.15915494, v146
	v_mul_f32_e32 v152, v126, v142
	v_mul_f32_e32 v153, v127, v142
	v_mul_f32_e32 v146, v124, v142
	v_mul_f32_e32 v147, v125, v142
	v_mul_f32_e32 v150, v122, v142
	v_mul_f32_e32 v151, v123, v142
	v_mul_f32_e32 v148, v120, v142
	v_mul_f32_e32 v149, v121, v142
	s_cbranch_vccz .LBB0_418
	v_bfe_u32 v143, v140, 6, 7
	v_cndmask_b32_e64 v143, v143, v141, s[38:39]
	v_cvt_f32_ubyte0_e32 v143, v143
	v_mul_f32_e32 v145, v174, v143
	v_sin_f32_e32 v158, v145
	v_mul_f32_e32 v155, v175, v143
	v_cos_f32_e32 v156, v145
	v_sin_f32_e32 v161, v155
	v_mul_f32_e32 v157, v176, v143
	v_mul_f32_e32 v143, v177, v143
	v_cos_f32_e32 v160, v155
	v_sin_f32_e32 v164, v157
	v_sin_f32_e32 v167, v143
	v_mul_f32_e32 v159, v146, v158
	v_mul_f32_e32 v158, v147, v158
	v_cos_f32_e32 v162, v157
	v_cos_f32_e32 v166, v143
	v_mul_f32_e32 v168, v146, v156
	v_mul_f32_e32 v169, v147, v156
	v_fma_f32 v146, v146, v156, v158
	v_fma_f32 v147, v147, v156, v159
	v_mov_b32_e32 v170, v161
	v_mul_f32_e32 v146, v153, v161
	v_fma_f32 v156, v152, v160, -v146
	v_fma_f32 v157, v153, v161, -v146
	v_mov_b32_e32 v171, v160
	v_mul_f32_e32 v146, v153, v160
	v_fma_f32 v160, v152, v170, v146
	v_fma_f32 v161, v153, v171, v146
	v_mul_f32_e32 v165, v148, v164
	v_mul_f32_e32 v164, v149, v164
	v_mul_f32_e32 v146, v151, v167
	v_mul_f32_e32 v152, v148, v162
	v_mul_f32_e32 v153, v149, v162
	v_fma_f32 v148, v148, v162, v164
	v_fma_f32 v149, v149, v162, v165
	v_fma_f32 v162, v150, v166, -v146
	v_fma_f32 v163, v151, v167, -v146
	v_mov_b32_e32 v170, v167
	v_mov_b32_e32 v171, v166
	v_mul_f32_e32 v146, v151, v166
	v_fma_f32 v166, v150, v170, v146
	v_fma_f32 v167, v151, v171, v146
	v_sub_f32_e32 v146, v168, v158
	v_sub_f32_e32 v148, v152, v164
	v_mov_b32_e32 v152, v156
	v_mov_b32_e32 v153, v160
	v_mov_b32_e32 v150, v162
	v_mov_b32_e32 v151, v166
.LBB0_418:
	v_add_u32_e32 v145, 16, v235
	v_and_b32_e32 v156, 63, v145
	v_mov_b32_e32 v145, 0x2100000
	v_mov_b32_e32 v155, 0x39c0000
	v_cndmask_b32_e64 v194, v145, v155, s[36:37]
	v_lshl_add_u64 v[158:159], s[90:91], 0, v[194:195]
	v_mad_i64_i32 v[154:155], s[0:1], v154, s27, v[158:159]
	v_ashrrev_i32_e32 v145, 31, v144
	v_lshl_add_u64 v[144:145], v[144:145], 1, v[154:155]
	v_mov_b32_e32 v143, v142
	v_cvt_pk_bf16_f32 v146, v146, v147
	v_cvt_pk_bf16_f32 v147, v152, v153
	v_cvt_pk_bf16_f32 v148, v148, v149
	v_cvt_pk_bf16_f32 v149, v150, v151
	v_mad_i64_i32 v[150:151], s[0:1], v140, s63, v[144:145]
	global_store_dwordx4 v[150:151], v[146:149], off
	v_add_u32_e32 v162, 16, v140
	s_nop 0
	v_mov_b32_e32 v146, v142
	v_mov_b32_e32 v147, v142
	v_cndmask_b32_e64 v157, 0, 1, s[18:19]
	v_mul_f32_e32 v154, v118, v146
	v_mul_f32_e32 v155, v119, v147
	v_mul_f32_e32 v148, v116, v142
	v_mul_f32_e32 v149, v117, v143
	v_mul_f32_e32 v152, v114, v146
	v_mul_f32_e32 v153, v115, v147
	v_mul_f32_e32 v150, v112, v142
	v_mul_f32_e32 v151, v113, v143
	v_cmp_ne_u32_e64 s[36:37], 1, v157
	s_andn2_b64 vcc, exec, s[18:19]
	v_bfe_u32 v172, v162, 6, 7
	s_cbranch_vccnz .LBB0_420
	v_cndmask_b32_e64 v157, v172, v156, s[38:39]
	v_cvt_f32_ubyte0_e32 v157, v157
	v_mul_f32_e32 v159, v174, v157
	v_sin_f32_e32 v160, v159
	v_mul_f32_e32 v161, v175, v157
	v_cos_f32_e32 v158, v159
	v_sin_f32_e32 v165, v161
	v_mul_f32_e32 v163, v176, v157
	v_mul_f32_e32 v157, v177, v157
	v_cos_f32_e32 v164, v161
	v_sin_f32_e32 v168, v163
	v_sin_f32_e32 v171, v157
	v_mul_f32_e32 v161, v148, v160
	v_mul_f32_e32 v160, v149, v160
	v_cos_f32_e32 v166, v163
	v_cos_f32_e32 v170, v157
	v_mul_f32_e32 v178, v148, v158
	v_mul_f32_e32 v179, v149, v158
	v_fma_f32 v148, v148, v158, v160
	v_fma_f32 v149, v149, v158, v161
	v_mov_b32_e32 v180, v165
	v_mul_f32_e32 v148, v155, v165
	v_fma_f32 v158, v154, v164, -v148
	v_fma_f32 v159, v155, v165, -v148
	v_mov_b32_e32 v181, v164
	v_mul_f32_e32 v148, v155, v164
	v_fma_f32 v164, v154, v180, v148
	v_fma_f32 v165, v155, v181, v148
	v_mul_f32_e32 v169, v150, v168
	v_mul_f32_e32 v168, v151, v168
	v_mul_f32_e32 v148, v153, v171
	v_mul_f32_e32 v154, v150, v166
	v_mul_f32_e32 v155, v151, v166
	v_fma_f32 v150, v150, v166, v168
	v_fma_f32 v151, v151, v166, v169
	v_fma_f32 v166, v152, v170, -v148
	v_fma_f32 v167, v153, v171, -v148
	v_mov_b32_e32 v180, v171
	v_mov_b32_e32 v181, v170
	v_mul_f32_e32 v148, v153, v170
	v_fma_f32 v170, v152, v180, v148
	v_fma_f32 v171, v153, v181, v148
	v_sub_f32_e32 v148, v178, v160
	v_sub_f32_e32 v150, v154, v168
	v_mov_b32_e32 v154, v158
	v_mov_b32_e32 v155, v164
	v_mov_b32_e32 v152, v166
	v_mov_b32_e32 v153, v170
; __device__ __forceinline__ unsigned cvt_pk_bf16(float lo, float hi) { const f32x2 v = {lo, hi}; const bf16x2_t b = __builtin_convertvector(v, bf16x2_t); return __builtin_bit_cast(unsigned, b); }
;     __device__ __forceinline__ void operator()(const f32x4 (&acc)[2][2][4][2], const Unit& u, int wr, int wc, int fr, int fq) const {
;     ...
; #pragma unroll
;                 for (int ai = 0; ai < 2; ++ai)
; #pragma unroll
;                     for (int m = 0; m < 4; ++m) {
;                         const int row = row0 + ai * HALF + m * 16;
;                         f32x4 x0 = acc[ai][bj][m][0] * qs, x1 = acc[ai][bj][m][1] * qs;
;                         if (latent) {
;                             const int t = row & (SEQ - 1); const float pos = blk ? (float)(t & 63) : (float)(t >> 6);
;                             const float a0 = pos * fq4[0], a1 = pos * fq4[1], a2 = pos * fq4[2], a3 = pos * fq4[3];
;                             const float c0 = __builtin_amdgcn_cosf(a0), s0 = __builtin_amdgcn_sinf(a0), c1 = __builtin_amdgcn_cosf(a1), s1 = __builtin_amdgcn_sinf(a1);
;                             const float c2 = __builtin_amdgcn_cosf(a2), s2 = __builtin_amdgcn_sinf(a2), c3 = __builtin_amdgcn_cosf(a3), s3 = __builtin_amdgcn_sinf(a3);
;                             x0 = (f32x4){x0[0] * c0 - x0[1] * s0, x0[1] * c0 + x0[0] * s0, x0[2] * c1 - x0[3] * s1, x0[3] * c1 + x0[2] * s1};
;                             x1 = (f32x4){x1[0] * c2 - x1[1] * s2, x1[1] * c2 + x1[0] * s2, x1[2] * c3 - x1[3] * s3, x1[3] * c3 + x1[2] * s3};
;                         }
;                         u32x4 w; w.x = cvt_pk_bf16(x0[0], x0[1]); w.y = cvt_pk_bf16(x0[2], x0[3]); w.z = cvt_pk_bf16(x1[0], x1[1]); w.w = cvt_pk_bf16(x1[2], x1[3]);
;                         *(u32x4*)(dst + (size_t)row * 48) = w;
.LBB0_420:
	v_xor_b32_e32 v158, 32, v141
	v_cvt_pk_bf16_f32 v148, v148, v149
	v_cvt_pk_bf16_f32 v149, v154, v155
	v_cvt_pk_bf16_f32 v150, v150, v151
	v_cvt_pk_bf16_f32 v151, v152, v153
	v_mad_i64_i32 v[152:153], s[0:1], v162, s63, v[144:145]
	global_store_dwordx4 v[152:153], v[148:151], off
	v_add_u32_e32 v165, 32, v140
	v_mul_f32_e32 v152, v102, v146
	v_mul_f32_e32 v153, v103, v147
	v_mul_f32_e32 v148, v100, v142
	v_mul_f32_e32 v149, v101, v143
	v_mul_f32_e32 v150, v98, v146
	v_mul_f32_e32 v151, v99, v147
	v_mul_f32_e32 v146, v96, v142
	v_mul_f32_e32 v147, v97, v143
	s_and_b64 vcc, exec, s[36:37]
	v_bfe_u32 v171, v165, 6, 7
	s_cbranch_vccnz .LBB0_422
	v_cndmask_b32_e64 v154, v171, v158, s[38:39]
	v_cvt_f32_ubyte0_e32 v154, v154
	v_mul_f32_e32 v155, v174, v154
	v_sin_f32_e32 v160, v155
	v_mul_f32_e32 v157, v175, v154
	v_mul_f32_e32 v159, v176, v154
	v_mul_f32_e32 v161, v177, v154
	v_cos_f32_e32 v154, v155
	v_sin_f32_e32 v167, v157
	v_cos_f32_e32 v166, v157
	v_sin_f32_e32 v168, v159
	v_cos_f32_e32 v164, v159
	v_cos_f32_e32 v178, v161
	v_sin_f32_e32 v179, v161
	v_mul_f32_e32 v161, v148, v160
	v_mul_f32_e32 v160, v149, v160
	v_mul_f32_e32 v180, v148, v154
	v_mul_f32_e32 v181, v149, v154
	v_fma_f32 v148, v148, v154, v160
	v_fma_f32 v149, v149, v154, v161
	v_mov_b32_e32 v182, v167
	v_mul_f32_e32 v148, v153, v167
	v_fma_f32 v154, v152, v166, -v148
	v_fma_f32 v155, v153, v167, -v148
	v_mov_b32_e32 v183, v166
	v_mul_f32_e32 v148, v153, v166
	v_mul_f32_e32 v169, v146, v168
	v_mul_f32_e32 v168, v147, v168
	v_fma_f32 v166, v152, v182, v148
	v_fma_f32 v167, v153, v183, v148
	v_mul_f32_e32 v152, v146, v164
	v_mul_f32_e32 v153, v147, v164
	v_fma_f32 v146, v146, v164, v168
	v_fma_f32 v147, v147, v164, v169
	v_mov_b32_e32 v184, v179
	v_mul_f32_e32 v146, v151, v179
	v_fma_f32 v182, v150, v178, -v146
	v_fma_f32 v183, v151, v179, -v146
	v_mov_b32_e32 v185, v178
	v_mul_f32_e32 v146, v151, v178
	v_fma_f32 v178, v150, v184, v146
	v_fma_f32 v179, v151, v185, v146
	v_sub_f32_e32 v148, v180, v160
	v_sub_f32_e32 v146, v152, v168
	v_mov_b32_e32 v152, v154
	v_mov_b32_e32 v153, v166
	v_mov_b32_e32 v150, v182
	v_mov_b32_e32 v151, v178
.LBB0_422:
	v_add_u32_e32 v154, 48, v235
	v_and_b32_e32 v157, 63, v154
	v_cvt_pk_bf16_f32 v166, v148, v149
	v_cvt_pk_bf16_f32 v167, v152, v153
	v_cvt_pk_bf16_f32 v168, v146, v147
	v_cvt_pk_bf16_f32 v169, v150, v151
	v_mad_i64_i32 v[146:147], s[0:1], v165, s63, v[144:145]
	global_store_dwordx4 v[146:147], v[166:169], off
	v_add_u32_e32 v163, 48, v140
	v_mov_b32_e32 v146, v142
	v_mov_b32_e32 v147, v142
	v_mul_f32_e32 v154, v86, v146
	v_mul_f32_e32 v155, v87, v147
	v_mul_f32_e32 v148, v84, v142
	v_mul_f32_e32 v149, v85, v143
	v_mul_f32_e32 v152, v82, v146
	v_mul_f32_e32 v153, v83, v147
	v_mul_f32_e32 v150, v80, v142
	v_mul_f32_e32 v151, v81, v143
	s_and_b64 vcc, exec, s[36:37]
	v_bfe_u32 v170, v163, 6, 7
	s_cbranch_vccnz .LBB0_424
	v_cndmask_b32_e64 v159, v170, v157, s[38:39]
	v_cvt_f32_ubyte0_e32 v159, v159
	v_mul_f32_e32 v161, v174, v159
	v_sin_f32_e32 v164, v161
	v_mul_f32_e32 v167, v175, v159
	v_cos_f32_e32 v160, v161
	v_cos_f32_e32 v166, v167
	v_sin_f32_e32 v167, v167
	v_mul_f32_e32 v169, v176, v159
	v_mul_f32_e32 v159, v177, v159
	v_sin_f32_e32 v178, v169
	v_sin_f32_e32 v181, v159
	v_mul_f32_e32 v184, v149, v164
	v_mul_f32_e32 v185, v148, v164
	v_cos_f32_e32 v168, v169
	v_cos_f32_e32 v180, v159
	v_mul_f32_e32 v182, v148, v160
	v_mul_f32_e32 v183, v149, v160
	v_fma_f32 v148, v148, v160, v184
	v_fma_f32 v149, v149, v160, v185
	v_mov_b32_e32 v186, v167
	v_mul_f32_e32 v148, v155, v167
	v_fma_f32 v160, v154, v166, -v148
	v_fma_f32 v161, v155, v167, -v148
	v_mov_b32_e32 v187, v166
	v_mul_f32_e32 v148, v155, v166
	v_fma_f32 v166, v154, v186, v148
	v_fma_f32 v167, v155, v187, v148
	v_mul_f32_e32 v179, v150, v178
	v_mul_f32_e32 v178, v151, v178
	v_mul_f32_e32 v148, v153, v181
	v_mul_f32_e32 v154, v150, v168
	v_mul_f32_e32 v155, v151, v168
	v_fma_f32 v150, v150, v168, v178
	v_fma_f32 v151, v151, v168, v179
	v_fma_f32 v168, v152, v180, -v148
	v_fma_f32 v169, v153, v181, -v148
	v_mov_b32_e32 v186, v181
	v_mov_b32_e32 v187, v180
	v_mul_f32_e32 v148, v153, v180
	v_fma_f32 v180, v152, v186, v148
	v_fma_f32 v181, v153, v187, v148
	v_sub_f32_e32 v148, v182, v184
	v_sub_f32_e32 v150, v154, v178
	v_mov_b32_e32 v154, v160
	v_mov_b32_e32 v155, v166
	v_mov_b32_e32 v152, v168
	v_mov_b32_e32 v153, v180
.LBB0_424:
	v_cvt_pk_bf16_f32 v148, v148, v149
	v_cvt_pk_bf16_f32 v149, v154, v155
	v_cvt_pk_bf16_f32 v150, v150, v151
	v_cvt_pk_bf16_f32 v151, v152, v153
	v_mad_i64_i32 v[152:153], s[0:1], v163, s63, v[144:145]
	global_store_dwordx4 v[152:153], v[148:151], off
	v_add_u32_e32 v164, 0x80, v140
	v_mul_f32_e32 v152, v62, v146
	v_mul_f32_e32 v153, v63, v147
	v_mul_f32_e32 v148, v60, v142
	v_mul_f32_e32 v149, v61, v143
	v_mul_f32_e32 v150, v58, v146
	v_mul_f32_e32 v151, v59, v147
	v_mul_f32_e32 v146, v56, v142
	v_mul_f32_e32 v147, v57, v143
	s_and_b64 vcc, exec, s[36:37]
	v_bfe_u32 v169, v164, 6, 7
	s_cbranch_vccnz .LBB0_426
	v_cndmask_b32_e64 v154, v169, v141, s[38:39]
	v_cvt_f32_ubyte0_e32 v154, v154
	v_mul_f32_e32 v155, v174, v154
	v_sin_f32_e32 v160, v155
	v_mul_f32_e32 v159, v175, v154
	v_mul_f32_e32 v161, v176, v154
	v_mul_f32_e32 v179, v177, v154
	v_cos_f32_e32 v154, v155
	v_sin_f32_e32 v167, v159
	v_cos_f32_e32 v166, v159
	v_sin_f32_e32 v178, v161
	v_cos_f32_e32 v168, v161
	v_mul_f32_e32 v161, v148, v160
	v_mul_f32_e32 v160, v149, v160
	v_sin_f32_e32 v181, v179
	v_mul_f32_e32 v182, v148, v154
	v_mul_f32_e32 v183, v149, v154
	v_fma_f32 v148, v148, v154, v160
	v_fma_f32 v149, v149, v154, v161
	v_cos_f32_e32 v180, v179
	v_mul_f32_e32 v148, v153, v167
	v_fma_f32 v154, v152, v166, -v148
	v_fma_f32 v155, v153, v167, -v148
	v_mov_b32_e32 v184, v167
	v_mov_b32_e32 v185, v166
	v_mul_f32_e32 v148, v153, v166
	v_mul_f32_e32 v179, v146, v178
	v_mul_f32_e32 v178, v147, v178
	v_fma_f32 v166, v152, v184, v148
	v_fma_f32 v167, v153, v185, v148
	v_mul_f32_e32 v152, v146, v168
	v_mul_f32_e32 v153, v147, v168
	v_fma_f32 v146, v146, v168, v178
	v_fma_f32 v147, v147, v168, v179
	v_mov_b32_e32 v186, v181
	v_mul_f32_e32 v146, v151, v181
	v_fma_f32 v184, v150, v180, -v146
	v_fma_f32 v185, v151, v181, -v146
	v_mov_b32_e32 v187, v180
	v_mul_f32_e32 v146, v151, v180
	v_fma_f32 v180, v150, v186, v146
	v_fma_f32 v181, v151, v187, v146
	v_sub_f32_e32 v148, v182, v160
	v_sub_f32_e32 v146, v152, v178
	v_mov_b32_e32 v152, v154
	v_mov_b32_e32 v153, v166
	v_mov_b32_e32 v150, v184
	v_mov_b32_e32 v151, v180
; __device__ __forceinline__ unsigned cvt_pk_bf16(float lo, float hi) { const f32x2 v = {lo, hi}; const bf16x2_t b = __builtin_convertvector(v, bf16x2_t); return __builtin_bit_cast(unsigned, b); }
;     __device__ __forceinline__ void operator()(const f32x4 (&acc)[2][2][4][2], const Unit& u, int wr, int wc, int fr, int fq) const {
;     ...
; #pragma unroll
;                 for (int ai = 0; ai < 2; ++ai)
; #pragma unroll
;                     for (int m = 0; m < 4; ++m) {
;                         const int row = row0 + ai * HALF + m * 16;
;                         f32x4 x0 = acc[ai][bj][m][0] * qs, x1 = acc[ai][bj][m][1] * qs;
;                         if (latent) {
;                             const int t = row & (SEQ - 1); const float pos = blk ? (float)(t & 63) : (float)(t >> 6);
;                             const float a0 = pos * fq4[0], a1 = pos * fq4[1], a2 = pos * fq4[2], a3 = pos * fq4[3];
;                             const float c0 = __builtin_amdgcn_cosf(a0), s0 = __builtin_amdgcn_sinf(a0), c1 = __builtin_amdgcn_cosf(a1), s1 = __builtin_amdgcn_sinf(a1);
;                             const float c2 = __builtin_amdgcn_cosf(a2), s2 = __builtin_amdgcn_sinf(a2), c3 = __builtin_amdgcn_cosf(a3), s3 = __builtin_amdgcn_sinf(a3);
;                             x0 = (f32x4){x0[0] * c0 - x0[1] * s0, x0[1] * c0 + x0[0] * s0, x0[2] * c1 - x0[3] * s1, x0[3] * c1 + x0[2] * s1};
;                             x1 = (f32x4){x1[0] * c2 - x1[1] * s2, x1[1] * c2 + x1[0] * s2, x1[2] * c3 - x1[3] * s3, x1[3] * c3 + x1[2] * s3};
;                         }
;                         u32x4 w; w.x = cvt_pk_bf16(x0[0], x0[1]); w.y = cvt_pk_bf16(x0[2], x0[3]); w.z = cvt_pk_bf16(x1[0], x1[1]); w.w = cvt_pk_bf16(x1[2], x1[3]);
;                         *(u32x4*)(dst + (size_t)row * 48) = w;
.LBB0_426:
	v_cvt_pk_bf16_f32 v178, v148, v149
	v_cvt_pk_bf16_f32 v179, v152, v153
	v_cvt_pk_bf16_f32 v180, v146, v147
	v_cvt_pk_bf16_f32 v181, v150, v151
	v_mad_i64_i32 v[146:147], s[0:1], v164, s63, v[144:145]
	global_store_dwordx4 v[146:147], v[178:181], off
	v_add_u32_e32 v160, 0x90, v140
	v_mov_b32_e32 v146, v142
	v_mov_b32_e32 v147, v142
	v_mul_f32_e32 v154, v54, v146
	v_mul_f32_e32 v155, v55, v147
	v_mul_f32_e32 v148, v52, v142
	v_mul_f32_e32 v149, v53, v143
	v_mul_f32_e32 v152, v50, v146
	v_mul_f32_e32 v153, v51, v147
	v_mul_f32_e32 v150, v48, v142
	v_mul_f32_e32 v151, v49, v143
	s_and_b64 vcc, exec, s[36:37]
	v_bfe_u32 v168, v160, 6, 7
	s_cbranch_vccnz .LBB0_428
	v_cndmask_b32_e64 v159, v168, v156, s[38:39]
	v_cvt_f32_ubyte0_e32 v159, v159
	v_mul_f32_e32 v161, v174, v159
	v_sin_f32_e32 v178, v161
	v_mul_f32_e32 v167, v175, v159
	v_cos_f32_e32 v166, v161
	v_sin_f32_e32 v181, v167
	v_mul_f32_e32 v179, v176, v159
	v_mul_f32_e32 v159, v177, v159
	v_cos_f32_e32 v180, v167
	v_cos_f32_e32 v182, v179
	v_sin_f32_e32 v184, v179
	v_sin_f32_e32 v187, v159
	v_mul_f32_e32 v179, v148, v178
	v_mul_f32_e32 v178, v149, v178
	v_cos_f32_e32 v186, v159
	v_mul_f32_e32 v188, v148, v166
	v_mul_f32_e32 v189, v149, v166
	v_fma_f32 v148, v148, v166, v178
	v_fma_f32 v149, v149, v166, v179
	v_mov_b32_e32 v190, v181
	v_mul_f32_e32 v148, v155, v181
	v_fma_f32 v166, v154, v180, -v148
	v_fma_f32 v167, v155, v181, -v148
	v_mov_b32_e32 v191, v180
	v_mul_f32_e32 v148, v155, v180
	v_fma_f32 v180, v154, v190, v148
	v_fma_f32 v181, v155, v191, v148
	v_mul_f32_e32 v185, v150, v184
	v_mul_f32_e32 v184, v151, v184
	v_mul_f32_e32 v148, v153, v187
	v_mul_f32_e32 v154, v150, v182
	v_mul_f32_e32 v155, v151, v182
	v_fma_f32 v150, v150, v182, v184
	v_fma_f32 v151, v151, v182, v185
	v_fma_f32 v182, v152, v186, -v148
	v_fma_f32 v183, v153, v187, -v148
	v_mov_b32_e32 v190, v187
	v_mov_b32_e32 v191, v186
	v_mul_f32_e32 v148, v153, v186
	v_fma_f32 v186, v152, v190, v148
	v_fma_f32 v187, v153, v191, v148
	v_sub_f32_e32 v148, v188, v178
	v_sub_f32_e32 v150, v154, v184
	v_mov_b32_e32 v154, v166
	v_mov_b32_e32 v155, v180
	v_mov_b32_e32 v152, v182
	v_mov_b32_e32 v153, v186
.LBB0_428:
	v_cvt_pk_bf16_f32 v148, v148, v149
	v_cvt_pk_bf16_f32 v149, v154, v155
	v_cvt_pk_bf16_f32 v150, v150, v151
	v_cvt_pk_bf16_f32 v151, v152, v153
	v_mad_i64_i32 v[152:153], s[0:1], v160, s63, v[144:145]
	global_store_dwordx4 v[152:153], v[148:151], off
	v_add_u32_e32 v161, 0xa0, v140
	v_mul_f32_e32 v152, v38, v146
	v_mul_f32_e32 v153, v39, v147
	v_mul_f32_e32 v148, v36, v142
	v_mul_f32_e32 v149, v37, v143
	v_mul_f32_e32 v150, v34, v146
	v_mul_f32_e32 v151, v35, v147
	v_mul_f32_e32 v146, v32, v142
	v_mul_f32_e32 v147, v33, v143
	s_and_b64 vcc, exec, s[36:37]
	v_bfe_u32 v167, v161, 6, 7
	s_cbranch_vccnz .LBB0_430
	v_cndmask_b32_e64 v154, v167, v158, s[38:39]
	v_cvt_f32_ubyte0_e32 v154, v154
	v_mul_f32_e32 v155, v174, v154
	v_sin_f32_e32 v166, v155
	v_mul_f32_e32 v159, v175, v154
	v_mul_f32_e32 v181, v176, v154
	v_mul_f32_e32 v183, v177, v154
	v_cos_f32_e32 v154, v155
	v_sin_f32_e32 v179, v159
	v_cos_f32_e32 v178, v159
	v_sin_f32_e32 v182, v181
	v_cos_f32_e32 v180, v181
	v_mul_f32_e32 v188, v149, v166
	v_mul_f32_e32 v189, v148, v166
	v_sin_f32_e32 v185, v183
	v_mul_f32_e32 v186, v148, v154
	v_mul_f32_e32 v187, v149, v154
	v_fma_f32 v148, v148, v154, v188
	v_fma_f32 v149, v149, v154, v189
	v_cos_f32_e32 v184, v183
	v_mul_f32_e32 v148, v153, v179
	v_fma_f32 v154, v152, v178, -v148
	v_fma_f32 v155, v153, v179, -v148
	v_mov_b32_e32 v190, v179
	v_mov_b32_e32 v191, v178
	v_mul_f32_e32 v148, v153, v178
	v_mul_f32_e32 v183, v146, v182
	v_mul_f32_e32 v182, v147, v182
	v_fma_f32 v178, v152, v190, v148
	v_fma_f32 v179, v153, v191, v148
	v_mul_f32_e32 v152, v146, v180
	v_mul_f32_e32 v153, v147, v180
	v_fma_f32 v146, v146, v180, v182
	v_fma_f32 v147, v147, v180, v183
	v_mov_b32_e32 v190, v185
	v_mul_f32_e32 v146, v151, v185
	v_fma_f32 v180, v150, v184, -v146
	v_fma_f32 v181, v151, v185, -v146
	v_mov_b32_e32 v191, v184
	v_mul_f32_e32 v146, v151, v184
	v_fma_f32 v184, v150, v190, v146
	v_fma_f32 v185, v151, v191, v146
	v_sub_f32_e32 v148, v186, v188
	v_sub_f32_e32 v146, v152, v182
	v_mov_b32_e32 v152, v154
	v_mov_b32_e32 v153, v178
	v_mov_b32_e32 v150, v180
	v_mov_b32_e32 v151, v184
.LBB0_430:
	v_cvt_pk_bf16_f32 v178, v148, v149
	v_cvt_pk_bf16_f32 v179, v152, v153
	v_cvt_pk_bf16_f32 v180, v146, v147
	v_cvt_pk_bf16_f32 v181, v150, v151
	v_mad_i64_i32 v[146:147], s[0:1], v161, s63, v[144:145]
	global_store_dwordx4 v[146:147], v[178:181], off
	v_add_u32_e32 v159, 0xb0, v140
	v_mov_b32_e32 v148, v142
	v_mov_b32_e32 v149, v142
	v_mul_f32_e32 v150, v22, v148
	v_mul_f32_e32 v151, v23, v149
	v_mul_f32_e32 v146, v20, v142
	v_mul_f32_e32 v147, v21, v143
	v_mul_f32_e32 v148, v18, v148
	v_mul_f32_e32 v149, v19, v149
	v_mul_f32_e32 v142, v16, v142
	v_mul_f32_e32 v143, v17, v143
	s_and_b64 vcc, exec, s[36:37]
	v_bfe_u32 v166, v159, 6, 7
	s_cbranch_vccnz .LBB0_432
	v_cndmask_b32_e64 v152, v166, v157, s[38:39]
	v_cvt_f32_ubyte0_e32 v152, v152
	v_mul_f32_e32 v153, v174, v152
	v_sin_f32_e32 v154, v153
	v_mul_f32_e32 v155, v175, v152
	v_mul_f32_e32 v178, v176, v152
	v_mul_f32_e32 v177, v177, v152
	v_cos_f32_e32 v152, v153
	v_sin_f32_e32 v175, v155
	v_cos_f32_e32 v174, v155
	v_cos_f32_e32 v176, v178
	v_sin_f32_e32 v178, v178
	v_mul_f32_e32 v155, v146, v154
	v_mul_f32_e32 v154, v147, v154
	v_sin_f32_e32 v181, v177
	v_mul_f32_e32 v182, v146, v152
	v_mul_f32_e32 v183, v147, v152
	v_fma_f32 v146, v146, v152, v154
	v_fma_f32 v147, v147, v152, v155
	v_cos_f32_e32 v180, v177
	v_mul_f32_e32 v146, v151, v175
	v_fma_f32 v152, v150, v174, -v146
	v_fma_f32 v153, v151, v175, -v146
	v_mov_b32_e32 v184, v175
	v_mov_b32_e32 v185, v174
	v_mul_f32_e32 v146, v151, v174
	v_mul_f32_e32 v179, v142, v178
	v_mul_f32_e32 v178, v143, v178
	v_fma_f32 v174, v150, v184, v146
	v_fma_f32 v175, v151, v185, v146
	v_mul_f32_e32 v150, v142, v176
	v_mul_f32_e32 v151, v143, v176
	v_fma_f32 v142, v142, v176, v178
	v_fma_f32 v143, v143, v176, v179
	v_mov_b32_e32 v184, v181
	v_mul_f32_e32 v142, v149, v181
	v_fma_f32 v176, v148, v180, -v142
	v_fma_f32 v177, v149, v181, -v142
	v_mov_b32_e32 v185, v180
	v_mul_f32_e32 v142, v149, v180
	v_fma_f32 v180, v148, v184, v142
	v_fma_f32 v181, v149, v185, v142
	v_sub_f32_e32 v146, v182, v154
	v_sub_f32_e32 v142, v150, v178
	v_mov_b32_e32 v150, v152
	v_mov_b32_e32 v151, v174
	v_mov_b32_e32 v148, v176
	v_mov_b32_e32 v149, v180
;     __device__ __forceinline__ void operator()(const f32x4 (&acc)[2][2][4][2], const Unit& u, int wr, int wc, int fr, int fq) const {
;     ...
;             for (int bj = 0; bj < 2; ++bj) {
;                 const int j = (u.pn - 4) * 256 + 128 * bj + 32 * wc + 8 * fq;
;                 const int which = j >= 384 ? 1 : 0; const int rem = j - which * 384; const int ch = rem / 48; const int sidx = rem - ch * 48;
;                 const int blk = sidx >= 24 ? 1 : 0; const int ii = sidx - blk * 24;
;                 bf16_t* dst = (bf16_t*)(mx + (which ? MX_KC : MX_QC)) + (size_t)ch * R * 48 + sidx;
;                 const float qs = which ? 1.0f : 0.14433756729740643f * LOG2E;
;                 float fq4[4];
; #pragma unroll
;                 for (int e = 0; e < 4; ++e) fq4[e] = fast_exp2(-(float)(ii / 2 + e) * (13.287712379549449f / 12.0f)) * 0.15915494309189535f;
; #pragma unroll
;                 for (int ai = 0; ai < 2; ++ai)
; #pragma unroll
;                     for (int m = 0; m < 4; ++m) {
;                         const int row = row0 + ai * HALF + m * 16;
;                         f32x4 x0 = acc[ai][bj][m][0] * qs, x1 = acc[ai][bj][m][1] * qs;
;                         if (latent) {
;                             const int t = row & (SEQ - 1); const float pos = blk ? (float)(t & 63) : (float)(t >> 6);
;                             const float a0 = pos * fq4[0], a1 = pos * fq4[1], a2 = pos * fq4[2], a3 = pos * fq4[3];
;                             const float c0 = __builtin_amdgcn_cosf(a0), s0 = __builtin_amdgcn_sinf(a0), c1 = __builtin_amdgcn_cosf(a1), s1 = __builtin_amdgcn_sinf(a1);
;                             const float c2 = __builtin_amdgcn_cosf(a2), s2 = __builtin_amdgcn_sinf(a2), c3 = __builtin_amdgcn_cosf(a3), s3 = __builtin_amdgcn_sinf(a3);
;                             x0 = (f32x4){x0[0] * c0 - x0[1] * s0, x0[1] * c0 + x0[0] * s0, x0[2] * c1 - x0[3] * s1, x0[3] * c1 + x0[2] * s1};
;                             x1 = (f32x4){x1[0] * c2 - x1[1] * s2, x1[1] * c2 + x1[0] * s2, x1[2] * c3 - x1[3] * s3, x1[3] * c3 + x1[2] * s3};
;                         }
;                         u32x4 w; w.x = cvt_pk_bf16(x0[0], x0[1]); w.y = cvt_pk_bf16(x0[2], x0[3]); w.z = cvt_pk_bf16(x1[0], x1[1]); w.w = cvt_pk_bf16(x1[2], x1[3]);
;                         *(u32x4*)(dst + (size_t)row * 48) = w;
.LBB0_432:
	v_cvt_pk_bf16_f32 v152, v146, v147
	v_cvt_pk_bf16_f32 v153, v150, v151
	v_cvt_pk_bf16_f32 v154, v142, v143
	v_cvt_pk_bf16_f32 v155, v148, v149
	v_mad_i64_i32 v[142:143], s[0:1], v159, s63, v[144:145]
	global_store_dwordx4 v[142:143], v[152:155], off
	v_add_u32_e32 v142, 0x80, v173
	v_cmp_lt_i32_e64 s[40:41], s20, v142
	s_and_b64 vcc, exec, s[36:37]
	s_nop 0
	v_cndmask_b32_e64 v143, 0, v207, s[40:41]
	v_add_u32_e32 v142, v143, v142
	v_mul_hi_i32 v143, v142, s21
	v_lshrrev_b32_e32 v144, 31, v143
	v_ashrrev_i32_e32 v143, 3, v143
	v_add_u32_e32 v154, v143, v144
	v_mad_u64_u32 v[144:145], s[0:1], v154, s26, v[142:143]
	v_cmp_lt_i32_e64 s[38:39], 23, v144
	v_not_b32_e32 v142, 23
	s_nop 0
	v_cndmask_b32_e64 v142, 0, v142, s[38:39]
	v_add_u32_e32 v142, v142, v144
	v_lshrrev_b32_e32 v143, 31, v142
	v_add_u32_e32 v142, v142, v143
	v_ashrrev_i32_e32 v142, 1, v142
	v_cvt_f32_i32_e32 v143, v142
	v_add_u32_e32 v145, 1, v142
	v_add_u32_e32 v146, 2, v142
	v_add_u32_e32 v142, 3, v142
	v_cvt_f32_i32_e32 v142, v142
	v_cvt_f32_i32_e32 v145, v145
	v_cvt_f32_i32_e32 v146, v146
	v_mul_f32_e32 v143, 0xbf8dbc50, v143
	v_mul_f32_e32 v142, 0xbf8dbc50, v142
	v_exp_f32_e32 v142, v142
	v_mul_f32_e32 v145, 0xbf8dbc50, v145
	v_mul_f32_e32 v146, 0xbf8dbc50, v146
	v_exp_f32_e32 v143, v143
	v_exp_f32_e32 v145, v145
	v_exp_f32_e32 v146, v146
	v_mul_f32_e32 v176, 0.15915494, v142
	v_mov_b32_e32 v142, 0x3e553b94
	v_cndmask_b32_e64 v142, v142, 1.0, s[40:41]
	v_mul_f32_e32 v173, 0.15915494, v143
	v_mul_f32_e32 v174, 0.15915494, v145
	v_mul_f32_e32 v175, 0.15915494, v146
	v_mul_f32_e32 v152, v110, v142
	v_mul_f32_e32 v153, v111, v142
	v_mul_f32_e32 v146, v108, v142
	v_mul_f32_e32 v147, v109, v142
	v_mul_f32_e32 v150, v106, v142
	v_mul_f32_e32 v151, v107, v142
	v_mul_f32_e32 v148, v104, v142
	v_mul_f32_e32 v149, v105, v142
	s_cbranch_vccnz .LBB0_434
	v_bfe_u32 v143, v140, 6, 7
	v_cndmask_b32_e64 v143, v143, v141, s[38:39]
	v_cvt_f32_ubyte0_e32 v143, v143
	v_mul_f32_e32 v145, v173, v143
	v_sin_f32_e32 v180, v145
	v_mul_f32_e32 v155, v174, v143
	v_cos_f32_e32 v178, v145
	v_sin_f32_e32 v183, v155
	v_mul_f32_e32 v177, v175, v143
	v_mul_f32_e32 v143, v176, v143
	v_cos_f32_e32 v182, v155
	v_sin_f32_e32 v186, v177
	v_sin_f32_e32 v189, v143
	v_mul_f32_e32 v181, v146, v180
	v_mul_f32_e32 v180, v147, v180
	v_cos_f32_e32 v184, v177
	v_cos_f32_e32 v188, v143
	v_mul_f32_e32 v190, v146, v178
	v_mul_f32_e32 v191, v147, v178
	v_fma_f32 v146, v146, v178, v180
	v_fma_f32 v147, v147, v178, v181
	v_mov_b32_e32 v208, v183
	v_mul_f32_e32 v146, v153, v183
	v_fma_f32 v178, v152, v182, -v146
	v_fma_f32 v179, v153, v183, -v146
	v_mov_b32_e32 v209, v182
	v_mul_f32_e32 v146, v153, v182
	v_fma_f32 v182, v152, v208, v146
	v_fma_f32 v183, v153, v209, v146
	v_mul_f32_e32 v187, v148, v186
	v_mul_f32_e32 v186, v149, v186
	v_mul_f32_e32 v146, v151, v189
	v_mul_f32_e32 v152, v148, v184
	v_mul_f32_e32 v153, v149, v184
	v_fma_f32 v148, v148, v184, v186
	v_fma_f32 v149, v149, v184, v187
	v_fma_f32 v184, v150, v188, -v146
	v_fma_f32 v185, v151, v189, -v146
	v_mov_b32_e32 v208, v189
	v_mov_b32_e32 v209, v188
	v_mul_f32_e32 v146, v151, v188
	v_fma_f32 v188, v150, v208, v146
	v_fma_f32 v189, v151, v209, v146
	v_sub_f32_e32 v146, v190, v180
	v_sub_f32_e32 v148, v152, v186
	v_mov_b32_e32 v152, v178
	v_mov_b32_e32 v153, v182
	v_mov_b32_e32 v150, v184
	v_mov_b32_e32 v151, v188
.LBB0_434:
	v_mov_b32_e32 v145, 0x2100000
	v_mov_b32_e32 v155, 0x39c0000
	v_cndmask_b32_e64 v194, v145, v155, s[40:41]
	v_lshl_add_u64 v[180:181], s[90:91], 0, v[194:195]
	v_mad_i64_i32 v[154:155], s[0:1], v154, s27, v[180:181]
	v_ashrrev_i32_e32 v145, 31, v144
	v_mad_i64_i32 v[178:179], s[0:1], v140, s63, 0
	v_lshl_add_u64 v[144:145], v[144:145], 1, v[154:155]
	v_mov_b32_e32 v143, v142
	v_cvt_pk_bf16_f32 v146, v146, v147
	v_cvt_pk_bf16_f32 v147, v152, v153
	v_cvt_pk_bf16_f32 v148, v148, v149
	v_cvt_pk_bf16_f32 v149, v150, v151
	v_lshl_add_u64 v[150:151], v[144:145], 0, v[178:179]
	global_store_dwordx4 v[150:151], v[146:149], off
	s_nop 1
	v_mov_b32_e32 v146, v142
	v_mov_b32_e32 v147, v142
	v_mul_f32_e32 v154, v94, v146
	v_mul_f32_e32 v155, v95, v147
	v_mul_f32_e32 v148, v92, v142
	v_mul_f32_e32 v149, v93, v143
	v_mul_f32_e32 v152, v90, v146
	v_mul_f32_e32 v153, v91, v147
	s_and_b64 vcc, exec, s[36:37]
	v_mul_f32_e32 v150, v88, v142
	v_mul_f32_e32 v151, v89, v143
	s_cbranch_vccnz .LBB0_436
	v_cndmask_b32_e64 v172, v172, v156, s[38:39]
	v_cvt_f32_ubyte0_e32 v172, v172
	v_mul_f32_e32 v177, v173, v172
	v_sin_f32_e32 v178, v177
	v_mul_f32_e32 v179, v174, v172
	v_mul_f32_e32 v183, v175, v172
	v_mul_f32_e32 v185, v176, v172
	v_cos_f32_e32 v172, v177
	v_sin_f32_e32 v181, v179
	v_cos_f32_e32 v180, v179
	v_sin_f32_e32 v184, v183
	v_sin_f32_e32 v187, v185
	v_mul_f32_e32 v179, v148, v178
	v_mul_f32_e32 v178, v149, v178
	v_cos_f32_e32 v182, v183
	v_cos_f32_e32 v186, v185
	v_mul_f32_e32 v188, v148, v172
	v_mul_f32_e32 v189, v149, v172
	v_fma_f32 v148, v148, v172, v178
	v_fma_f32 v149, v149, v172, v179
	v_mov_b32_e32 v208, v181
	v_mul_f32_e32 v148, v155, v181
	v_fma_f32 v190, v154, v180, -v148
	v_fma_f32 v191, v155, v181, -v148
	v_mov_b32_e32 v209, v180
	v_mul_f32_e32 v148, v155, v180
	v_fma_f32 v180, v154, v208, v148
	v_fma_f32 v181, v155, v209, v148
	v_mul_f32_e32 v185, v150, v184
	v_mul_f32_e32 v184, v151, v184
	v_mul_f32_e32 v148, v153, v187
	v_mul_f32_e32 v154, v150, v182
	v_mul_f32_e32 v155, v151, v182
	v_fma_f32 v150, v150, v182, v184
	v_fma_f32 v151, v151, v182, v185
	v_fma_f32 v182, v152, v186, -v148
	v_fma_f32 v183, v153, v187, -v148
	v_mov_b32_e32 v208, v187
	v_mov_b32_e32 v209, v186
	v_mul_f32_e32 v148, v153, v186
	v_fma_f32 v186, v152, v208, v148
	v_fma_f32 v187, v153, v209, v148
	v_sub_f32_e32 v148, v188, v178
	v_sub_f32_e32 v150, v154, v184
	v_mov_b32_e32 v154, v190
	v_mov_b32_e32 v155, v180
	v_mov_b32_e32 v152, v182
	v_mov_b32_e32 v153, v186
; __device__ __forceinline__ unsigned cvt_pk_bf16(float lo, float hi) { const f32x2 v = {lo, hi}; const bf16x2_t b = __builtin_convertvector(v, bf16x2_t); return __builtin_bit_cast(unsigned, b); }
;     __device__ __forceinline__ void operator()(const f32x4 (&acc)[2][2][4][2], const Unit& u, int wr, int wc, int fr, int fq) const {
;     ...
;                 for (int ai = 0; ai < 2; ++ai)
; #pragma unroll
;                     for (int m = 0; m < 4; ++m) {
;                         const int row = row0 + ai * HALF + m * 16;
;                         f32x4 x0 = acc[ai][bj][m][0] * qs, x1 = acc[ai][bj][m][1] * qs;
;                         if (latent) {
;                             const int t = row & (SEQ - 1); const float pos = blk ? (float)(t & 63) : (float)(t >> 6);
;                             const float a0 = pos * fq4[0], a1 = pos * fq4[1], a2 = pos * fq4[2], a3 = pos * fq4[3];
;                             const float c0 = __builtin_amdgcn_cosf(a0), s0 = __builtin_amdgcn_sinf(a0), c1 = __builtin_amdgcn_cosf(a1), s1 = __builtin_amdgcn_sinf(a1);
;                             const float c2 = __builtin_amdgcn_cosf(a2), s2 = __builtin_amdgcn_sinf(a2), c3 = __builtin_amdgcn_cosf(a3), s3 = __builtin_amdgcn_sinf(a3);
;                             x0 = (f32x4){x0[0] * c0 - x0[1] * s0, x0[1] * c0 + x0[0] * s0, x0[2] * c1 - x0[3] * s1, x0[3] * c1 + x0[2] * s1};
;                             x1 = (f32x4){x1[0] * c2 - x1[1] * s2, x1[1] * c2 + x1[0] * s2, x1[2] * c3 - x1[3] * s3, x1[3] * c3 + x1[2] * s3};
;                         }
;                         u32x4 w; w.x = cvt_pk_bf16(x0[0], x0[1]); w.y = cvt_pk_bf16(x0[2], x0[3]); w.z = cvt_pk_bf16(x1[0], x1[1]); w.w = cvt_pk_bf16(x1[2], x1[3]);
;                         *(u32x4*)(dst + (size_t)row * 48) = w;
.LBB0_436:
	v_mad_i64_i32 v[178:179], s[0:1], v162, s63, 0
	v_cvt_pk_bf16_f32 v148, v148, v149
	v_cvt_pk_bf16_f32 v149, v154, v155
	v_cvt_pk_bf16_f32 v150, v150, v151
	v_cvt_pk_bf16_f32 v151, v152, v153
	v_lshl_add_u64 v[152:153], v[144:145], 0, v[178:179]
	global_store_dwordx4 v[152:153], v[148:151], off
	v_mul_f32_e32 v152, v78, v146
	v_mul_f32_e32 v153, v79, v147
	s_nop 0
	v_mul_f32_e32 v148, v76, v142
	v_mul_f32_e32 v149, v77, v143
	v_mul_f32_e32 v150, v74, v146
	v_mul_f32_e32 v151, v75, v147
	s_and_b64 vcc, exec, s[36:37]
	v_mul_f32_e32 v146, v72, v142
	v_mul_f32_e32 v147, v73, v143
	s_cbranch_vccnz .LBB0_438
	v_cndmask_b32_e64 v154, v171, v158, s[38:39]
	v_cvt_f32_ubyte0_e32 v154, v154
	v_mul_f32_e32 v155, v173, v154
	v_sin_f32_e32 v162, v155
	v_mul_f32_e32 v171, v174, v154
	v_mul_f32_e32 v177, v175, v154
	v_mul_f32_e32 v181, v176, v154
	v_cos_f32_e32 v154, v155
	v_sin_f32_e32 v179, v171
	v_cos_f32_e32 v178, v171
	v_sin_f32_e32 v180, v177
	v_cos_f32_e32 v172, v177
	v_mul_f32_e32 v186, v149, v162
	v_mul_f32_e32 v187, v148, v162
	v_sin_f32_e32 v183, v181
	v_mul_f32_e32 v184, v148, v154
	v_mul_f32_e32 v185, v149, v154
	v_fma_f32 v148, v148, v154, v186
	v_fma_f32 v149, v149, v154, v187
	v_cos_f32_e32 v182, v181
	v_mul_f32_e32 v148, v153, v179
	v_fma_f32 v154, v152, v178, -v148
	v_fma_f32 v155, v153, v179, -v148
	v_mov_b32_e32 v188, v179
	v_mov_b32_e32 v189, v178
	v_mul_f32_e32 v148, v153, v178
	v_mul_f32_e32 v181, v146, v180
	v_mul_f32_e32 v180, v147, v180
	v_fma_f32 v178, v152, v188, v148
	v_fma_f32 v179, v153, v189, v148
	v_mul_f32_e32 v152, v146, v172
	v_mul_f32_e32 v153, v147, v172
	v_fma_f32 v146, v146, v172, v180
	v_fma_f32 v147, v147, v172, v181
	v_mov_b32_e32 v190, v183
	v_mul_f32_e32 v146, v151, v183
	v_fma_f32 v188, v150, v182, -v146
	v_fma_f32 v189, v151, v183, -v146
	v_mov_b32_e32 v191, v182
	v_mul_f32_e32 v146, v151, v182
	v_fma_f32 v182, v150, v190, v146
	v_fma_f32 v183, v151, v191, v146
	v_sub_f32_e32 v148, v184, v186
	v_sub_f32_e32 v146, v152, v180
	v_mov_b32_e32 v152, v154
	v_mov_b32_e32 v153, v178
	v_mov_b32_e32 v150, v188
	v_mov_b32_e32 v151, v182
.LBB0_438:
	v_mad_i64_i32 v[154:155], s[0:1], v165, s63, 0
	v_cvt_pk_bf16_f32 v178, v148, v149
	v_cvt_pk_bf16_f32 v179, v152, v153
	v_cvt_pk_bf16_f32 v180, v146, v147
	v_cvt_pk_bf16_f32 v181, v150, v151
	v_lshl_add_u64 v[146:147], v[144:145], 0, v[154:155]
	global_store_dwordx4 v[146:147], v[178:181], off
	v_mov_b32_e32 v146, v142
	v_mov_b32_e32 v147, v142
	v_mul_f32_e32 v154, v70, v146
	v_mul_f32_e32 v155, v71, v147
	v_mul_f32_e32 v148, v68, v142
	v_mul_f32_e32 v149, v69, v143
	v_mul_f32_e32 v152, v66, v146
	v_mul_f32_e32 v153, v67, v147
	s_and_b64 vcc, exec, s[36:37]
	v_mul_f32_e32 v150, v64, v142
	v_mul_f32_e32 v151, v65, v143
	s_cbranch_vccnz .LBB0_440
	v_cndmask_b32_e64 v162, v170, v157, s[38:39]
	v_cvt_f32_ubyte0_e32 v162, v162
	v_mul_f32_e32 v165, v173, v162
	v_sin_f32_e32 v170, v165
	v_mul_f32_e32 v171, v174, v162
	v_mul_f32_e32 v177, v175, v162
	v_mul_f32_e32 v181, v176, v162
	v_cos_f32_e32 v162, v165
	v_sin_f32_e32 v179, v171
	v_cos_f32_e32 v178, v171
	v_sin_f32_e32 v183, v181
	v_mul_f32_e32 v171, v148, v170
	v_mul_f32_e32 v170, v149, v170
	v_sin_f32_e32 v180, v177
	v_cos_f32_e32 v182, v181
	v_mul_f32_e32 v184, v148, v162
	v_mul_f32_e32 v185, v149, v162
	v_fma_f32 v148, v148, v162, v170
	v_fma_f32 v149, v149, v162, v171
	v_cos_f32_e32 v172, v177
	v_mul_f32_e32 v148, v155, v179
	v_fma_f32 v186, v154, v178, -v148
	v_fma_f32 v187, v155, v179, -v148
	v_mov_b32_e32 v188, v179
	v_mov_b32_e32 v189, v178
	v_mul_f32_e32 v148, v155, v178
	v_fma_f32 v178, v154, v188, v148
	v_fma_f32 v179, v155, v189, v148
	v_mul_f32_e32 v148, v153, v183
	v_mul_f32_e32 v181, v150, v180
	v_mul_f32_e32 v180, v151, v180
	v_fma_f32 v188, v152, v182, -v148
	v_fma_f32 v189, v153, v183, -v148
	v_mov_b32_e32 v190, v183
	v_mov_b32_e32 v191, v182
	v_mul_f32_e32 v148, v153, v182
	v_mul_f32_e32 v154, v150, v172
	v_mul_f32_e32 v155, v151, v172
	v_fma_f32 v150, v150, v172, v180
	v_fma_f32 v151, v151, v172, v181
	v_fma_f32 v182, v152, v190, v148
	v_fma_f32 v183, v153, v191, v148
	v_sub_f32_e32 v148, v184, v170
	v_sub_f32_e32 v150, v154, v180
	v_mov_b32_e32 v154, v186
	v_mov_b32_e32 v155, v178
	v_mov_b32_e32 v152, v188
	v_mov_b32_e32 v153, v182
.LBB0_440:
	v_mad_i64_i32 v[162:163], s[0:1], v163, s63, 0
	v_cvt_pk_bf16_f32 v148, v148, v149
	v_cvt_pk_bf16_f32 v149, v154, v155
	v_cvt_pk_bf16_f32 v150, v150, v151
	v_cvt_pk_bf16_f32 v151, v152, v153
	v_lshl_add_u64 v[152:153], v[144:145], 0, v[162:163]
	global_store_dwordx4 v[152:153], v[148:151], off
	v_mul_f32_e32 v152, v46, v146
	v_mul_f32_e32 v153, v47, v147
	s_nop 0
	v_mul_f32_e32 v148, v44, v142
	v_mul_f32_e32 v149, v45, v143
	v_mul_f32_e32 v150, v42, v146
	v_mul_f32_e32 v151, v43, v147
	s_and_b64 vcc, exec, s[36:37]
	v_mul_f32_e32 v146, v40, v142
	v_mul_f32_e32 v147, v41, v143
	s_cbranch_vccnz .LBB0_442
	v_cndmask_b32_e64 v141, v169, v141, s[38:39]
	v_cvt_f32_ubyte0_e32 v141, v141
	v_mul_f32_e32 v155, v173, v141
	v_sin_f32_e32 v162, v155
	v_mul_f32_e32 v163, v174, v141
	v_cos_f32_e32 v154, v155
	v_mul_f32_e32 v165, v175, v141
	v_sin_f32_e32 v171, v163
	v_cos_f32_e32 v170, v163
	v_sin_f32_e32 v178, v165
	v_mul_f32_e32 v141, v176, v141
	v_cos_f32_e32 v172, v165
	v_mul_f32_e32 v163, v148, v162
	v_mul_f32_e32 v162, v149, v162
	v_sin_f32_e32 v181, v141
	v_mul_f32_e32 v182, v148, v154
	v_mul_f32_e32 v183, v149, v154
	v_fma_f32 v148, v148, v154, v162
	v_fma_f32 v149, v149, v154, v163
	v_cos_f32_e32 v180, v141
	v_mul_f32_e32 v148, v153, v171
	v_fma_f32 v154, v152, v170, -v148
	v_fma_f32 v155, v153, v171, -v148
	v_mov_b32_e32 v184, v171
	v_mov_b32_e32 v185, v170
	v_mul_f32_e32 v148, v153, v170
	v_mul_f32_e32 v179, v146, v178
	v_mul_f32_e32 v178, v147, v178
	v_fma_f32 v170, v152, v184, v148
	v_fma_f32 v171, v153, v185, v148
	v_mul_f32_e32 v152, v146, v172
	v_mul_f32_e32 v153, v147, v172
	v_fma_f32 v146, v146, v172, v178
	v_fma_f32 v147, v147, v172, v179
	v_mov_b32_e32 v186, v181
	v_mul_f32_e32 v146, v151, v181
	v_fma_f32 v184, v150, v180, -v146
	v_fma_f32 v185, v151, v181, -v146
	v_mov_b32_e32 v187, v180
	v_mul_f32_e32 v146, v151, v180
	v_fma_f32 v180, v150, v186, v146
	v_fma_f32 v181, v151, v187, v146
	v_sub_f32_e32 v148, v182, v162
	v_sub_f32_e32 v146, v152, v178
	v_mov_b32_e32 v152, v154
	v_mov_b32_e32 v153, v170
	v_mov_b32_e32 v150, v184
	v_mov_b32_e32 v151, v180
; __device__ __forceinline__ unsigned cvt_pk_bf16(float lo, float hi) { const f32x2 v = {lo, hi}; const bf16x2_t b = __builtin_convertvector(v, bf16x2_t); return __builtin_bit_cast(unsigned, b); }
;     __device__ __forceinline__ void operator()(const f32x4 (&acc)[2][2][4][2], const Unit& u, int wr, int wc, int fr, int fq) const {
;     ...
;                 for (int ai = 0; ai < 2; ++ai)
; #pragma unroll
;                     for (int m = 0; m < 4; ++m) {
;                         const int row = row0 + ai * HALF + m * 16;
;                         f32x4 x0 = acc[ai][bj][m][0] * qs, x1 = acc[ai][bj][m][1] * qs;
;                         if (latent) {
;                             const int t = row & (SEQ - 1); const float pos = blk ? (float)(t & 63) : (float)(t >> 6);
;                             const float a0 = pos * fq4[0], a1 = pos * fq4[1], a2 = pos * fq4[2], a3 = pos * fq4[3];
;                             const float c0 = __builtin_amdgcn_cosf(a0), s0 = __builtin_amdgcn_sinf(a0), c1 = __builtin_amdgcn_cosf(a1), s1 = __builtin_amdgcn_sinf(a1);
;                             const float c2 = __builtin_amdgcn_cosf(a2), s2 = __builtin_amdgcn_sinf(a2), c3 = __builtin_amdgcn_cosf(a3), s3 = __builtin_amdgcn_sinf(a3);
;                             x0 = (f32x4){x0[0] * c0 - x0[1] * s0, x0[1] * c0 + x0[0] * s0, x0[2] * c1 - x0[3] * s1, x0[3] * c1 + x0[2] * s1};
;                             x1 = (f32x4){x1[0] * c2 - x1[1] * s2, x1[1] * c2 + x1[0] * s2, x1[2] * c3 - x1[3] * s3, x1[3] * c3 + x1[2] * s3};
;                         }
;                         u32x4 w; w.x = cvt_pk_bf16(x0[0], x0[1]); w.y = cvt_pk_bf16(x0[2], x0[3]); w.z = cvt_pk_bf16(x1[0], x1[1]); w.w = cvt_pk_bf16(x1[2], x1[3]);
;                         *(u32x4*)(dst + (size_t)row * 48) = w;
.LBB0_442:
	v_mad_i64_i32 v[154:155], s[0:1], v164, s63, 0
	v_cvt_pk_bf16_f32 v162, v148, v149
	v_cvt_pk_bf16_f32 v163, v152, v153
	v_cvt_pk_bf16_f32 v164, v146, v147
	v_cvt_pk_bf16_f32 v165, v150, v151
	v_lshl_add_u64 v[146:147], v[144:145], 0, v[154:155]
	global_store_dwordx4 v[146:147], v[162:165], off
	v_mov_b32_e32 v146, v142
	v_mov_b32_e32 v147, v142
	v_mul_f32_e32 v154, v30, v146
	v_mul_f32_e32 v155, v31, v147
	v_mul_f32_e32 v148, v28, v142
	v_mul_f32_e32 v149, v29, v143
	v_mul_f32_e32 v152, v26, v146
	v_mul_f32_e32 v153, v27, v147
	s_and_b64 vcc, exec, s[36:37]
	v_mul_f32_e32 v150, v24, v142
	v_mul_f32_e32 v151, v25, v143
	s_cbranch_vccnz .LBB0_444
	v_cndmask_b32_e64 v141, v168, v156, s[38:39]
	v_cvt_f32_ubyte0_e32 v141, v141
	v_mul_f32_e32 v162, v173, v141
	v_cos_f32_e32 v156, v162
	v_sin_f32_e32 v162, v162
	v_mul_f32_e32 v163, v174, v141
	v_sin_f32_e32 v165, v163
	v_mul_f32_e32 v169, v175, v141
	v_mul_f32_e32 v141, v176, v141
	v_cos_f32_e32 v164, v163
	v_sin_f32_e32 v170, v169
	v_sin_f32_e32 v179, v141
	v_mul_f32_e32 v163, v148, v162
	v_mul_f32_e32 v162, v149, v162
	v_cos_f32_e32 v168, v169
	v_cos_f32_e32 v178, v141
	v_mul_f32_e32 v180, v148, v156
	v_mul_f32_e32 v181, v149, v156
	v_fma_f32 v148, v148, v156, v162
	v_fma_f32 v149, v149, v156, v163
	v_mov_b32_e32 v184, v165
	v_mul_f32_e32 v148, v155, v165
	v_fma_f32 v182, v154, v164, -v148
	v_fma_f32 v183, v155, v165, -v148
	v_mov_b32_e32 v185, v164
	v_mul_f32_e32 v148, v155, v164
	v_fma_f32 v164, v154, v184, v148
	v_fma_f32 v165, v155, v185, v148
	v_mul_f32_e32 v171, v150, v170
	v_mul_f32_e32 v170, v151, v170
	v_mul_f32_e32 v148, v153, v179
	v_mul_f32_e32 v154, v150, v168
	v_mul_f32_e32 v155, v151, v168
	v_fma_f32 v150, v150, v168, v170
	v_fma_f32 v151, v151, v168, v171
	v_fma_f32 v168, v152, v178, -v148
	v_fma_f32 v169, v153, v179, -v148
	v_mov_b32_e32 v184, v179
	v_mov_b32_e32 v185, v178
	v_mul_f32_e32 v148, v153, v178
	v_fma_f32 v178, v152, v184, v148
	v_fma_f32 v179, v153, v185, v148
	v_sub_f32_e32 v148, v180, v162
	v_sub_f32_e32 v150, v154, v170
	v_mov_b32_e32 v154, v182
	v_mov_b32_e32 v155, v164
	v_mov_b32_e32 v152, v168
	v_mov_b32_e32 v153, v178
.LBB0_444:
	v_mad_i64_i32 v[162:163], s[0:1], v160, s63, 0
	v_cvt_pk_bf16_f32 v148, v148, v149
	v_cvt_pk_bf16_f32 v149, v154, v155
	v_cvt_pk_bf16_f32 v150, v150, v151
	v_cvt_pk_bf16_f32 v151, v152, v153
	v_lshl_add_u64 v[152:153], v[144:145], 0, v[162:163]
	global_store_dwordx4 v[152:153], v[148:151], off
	v_mul_f32_e32 v152, v14, v146
	v_mul_f32_e32 v153, v15, v147
	s_nop 0
	v_mul_f32_e32 v148, v12, v142
	v_mul_f32_e32 v149, v13, v143
	v_mul_f32_e32 v150, v10, v146
	v_mul_f32_e32 v151, v11, v147
	s_and_b64 vcc, exec, s[36:37]
	v_mul_f32_e32 v146, v8, v142
	v_mul_f32_e32 v147, v9, v143
	s_cbranch_vccnz .LBB0_446
	v_cndmask_b32_e64 v141, v167, v158, s[38:39]
	v_cvt_f32_ubyte0_e32 v141, v141
	v_mul_f32_e32 v155, v173, v141
	v_sin_f32_e32 v156, v155
	v_mul_f32_e32 v158, v174, v141
	v_cos_f32_e32 v154, v155
	v_sin_f32_e32 v163, v158
	v_mul_f32_e32 v160, v175, v141
	v_cos_f32_e32 v162, v158
	v_cos_f32_e32 v158, v160
	v_sin_f32_e32 v160, v160
	v_mul_f32_e32 v170, v149, v156
	v_mul_f32_e32 v171, v148, v156
	v_mul_f32_e32 v141, v176, v141
	v_mul_f32_e32 v168, v148, v154
	v_mul_f32_e32 v169, v149, v154
	v_fma_f32 v148, v148, v154, v170
	v_fma_f32 v149, v149, v154, v171
	v_sin_f32_e32 v165, v141
	v_mul_f32_e32 v148, v153, v163
	v_cos_f32_e32 v164, v141
	v_fma_f32 v154, v152, v162, -v148
	v_fma_f32 v155, v153, v163, -v148
	v_mov_b32_e32 v178, v163
	v_mov_b32_e32 v179, v162
	v_mul_f32_e32 v148, v153, v162
	v_fma_f32 v162, v152, v178, v148
	v_fma_f32 v163, v153, v179, v148
	v_mul_f32_e32 v178, v147, v160
	v_mul_f32_e32 v179, v146, v160
	v_mul_f32_e32 v152, v146, v158
	v_mul_f32_e32 v153, v147, v158
	v_fma_f32 v146, v146, v158, v178
	v_fma_f32 v147, v147, v158, v179
	v_mov_b32_e32 v182, v165
	v_mul_f32_e32 v146, v151, v165
	v_fma_f32 v180, v150, v164, -v146
	v_fma_f32 v181, v151, v165, -v146
	v_mov_b32_e32 v183, v164
	v_mul_f32_e32 v146, v151, v164
	v_fma_f32 v164, v150, v182, v146
	v_fma_f32 v165, v151, v183, v146
	v_sub_f32_e32 v148, v168, v170
	v_sub_f32_e32 v146, v152, v178
	v_mov_b32_e32 v152, v154
	v_mov_b32_e32 v153, v162
	v_mov_b32_e32 v150, v180
	v_mov_b32_e32 v151, v164
.LBB0_446:
	v_mad_i64_i32 v[154:155], s[0:1], v161, s63, 0
	v_cvt_pk_bf16_f32 v160, v148, v149
	v_cvt_pk_bf16_f32 v161, v152, v153
	v_cvt_pk_bf16_f32 v162, v146, v147
	v_cvt_pk_bf16_f32 v163, v150, v151
	v_lshl_add_u64 v[146:147], v[144:145], 0, v[154:155]
	global_store_dwordx4 v[146:147], v[160:163], off
	v_mov_b32_e32 v148, v142
	v_mov_b32_e32 v149, v142
	v_mul_f32_e32 v150, v6, v148
	v_mul_f32_e32 v151, v7, v149
	v_mul_f32_e32 v146, v4, v142
	v_mul_f32_e32 v147, v5, v143
	v_mul_f32_e32 v148, v2, v148
	v_mul_f32_e32 v149, v3, v149
	s_and_b64 vcc, exec, s[36:37]
	v_mul_f32_e32 v142, v0, v142
	v_mul_f32_e32 v143, v1, v143
	s_cbranch_vccnz .LBB0_448
	v_cndmask_b32_e64 v141, v166, v157, s[38:39]
	v_cvt_f32_ubyte0_e32 v141, v141
	v_mul_f32_e32 v153, v173, v141
	v_sin_f32_e32 v154, v153
	v_mul_f32_e32 v155, v174, v141
	v_cos_f32_e32 v152, v153
	v_mul_f32_e32 v160, v175, v141
	v_sin_f32_e32 v157, v155
	v_cos_f32_e32 v156, v155
	v_cos_f32_e32 v158, v160
	v_sin_f32_e32 v160, v160
	v_mul_f32_e32 v141, v176, v141
	v_mul_f32_e32 v155, v146, v154
	v_mul_f32_e32 v154, v147, v154
	v_sin_f32_e32 v163, v141
	v_mul_f32_e32 v164, v146, v152
	v_mul_f32_e32 v165, v147, v152
	v_fma_f32 v146, v146, v152, v154
	v_fma_f32 v147, v147, v152, v155
	v_cos_f32_e32 v162, v141
	v_mul_f32_e32 v146, v151, v157
	v_fma_f32 v152, v150, v156, -v146
	v_fma_f32 v153, v151, v157, -v146
	v_mov_b32_e32 v166, v157
	v_mov_b32_e32 v167, v156
	v_mul_f32_e32 v146, v151, v156
	v_mul_f32_e32 v161, v142, v160
	v_mul_f32_e32 v160, v143, v160
	v_fma_f32 v156, v150, v166, v146
	v_fma_f32 v157, v151, v167, v146
	v_mul_f32_e32 v150, v142, v158
	v_mul_f32_e32 v151, v143, v158
	v_fma_f32 v142, v142, v158, v160
	v_fma_f32 v143, v143, v158, v161
	v_mov_b32_e32 v168, v163
	v_mul_f32_e32 v142, v149, v163
	v_fma_f32 v166, v148, v162, -v142
	v_fma_f32 v167, v149, v163, -v142
	v_mov_b32_e32 v169, v162
	v_mul_f32_e32 v142, v149, v162
	v_fma_f32 v162, v148, v168, v142
	v_fma_f32 v163, v149, v169, v142
	v_sub_f32_e32 v146, v164, v154
	v_sub_f32_e32 v142, v150, v160
	v_mov_b32_e32 v150, v152
	v_mov_b32_e32 v151, v156
	v_mov_b32_e32 v148, v166
	v_mov_b32_e32 v149, v162

; __device__ __forceinline__ unsigned cvt_pk_bf16(float lo, float hi) { const f32x2 v = {lo, hi}; const bf16x2_t b = __builtin_convertvector(v, bf16x2_t); return __builtin_bit_cast(unsigned, b); }
; __device__ __forceinline__ float gelu_tanh_f(float x) { const float u = 0.7978845608028654f * (x + 0.044715f * x * x * x); return x * fast_rcp(1.0f + fast_exp2(-2.0f * LOG2E * u)); }
;     __device__ __forceinline__ void operator()(const f32x4 (&acc)[2][2][4][2], const Unit& u, int wr, int wc, int fr, int fq) const {
;     ...
;             bf16_t* dst = (bf16_t*)(mx + (u.pn == 2 ? MX_U : MX_VG));
;             const int col0 = wc * 32 + 8 * fq;
; #pragma unroll
;             for (int ai = 0; ai < 2; ++ai)
; #pragma unroll
;                 for (int m = 0; m < 4; ++m) { bf16_t* rowp = dst + (size_t)(row0 + ai * HALF + m * 16) * 256 + col0;
; #pragma unroll
;                     for (int bj = 0; bj < 2; ++bj) { const f32x4 v0 = acc[ai][bj][m][0], v1 = acc[ai][bj][m][1]; u32x4 w;
;                         w.x = cvt_pk_bf16(gelu_tanh_f(v0[0]), gelu_tanh_f(v0[1])); w.y = cvt_pk_bf16(gelu_tanh_f(v0[2]), gelu_tanh_f(v0[3]));
;                         w.z = cvt_pk_bf16(gelu_tanh_f(v1[0]), gelu_tanh_f(v1[1])); w.w = cvt_pk_bf16(gelu_tanh_f(v1[2]), gelu_tanh_f(v1[3]));
;                         *(u32x4*)(rowp + bj * HALF) = w; } }
.LBB0_449:
	s_and_b64 vcc, exec, s[0:1]
	s_cbranch_vccz .LBB0_451
	v_ashrrev_i32_e32 v141, 31, v140
	v_lshlrev_b64 v[144:145], 9, v[140:141]
	v_mul_f32_e32 v141, 0x3d372713, v124
	v_mul_f32_e32 v141, v124, v141
	v_fma_f32 v141, v124, v141, v124
	v_mul_f32_e32 v141, 0x3f4c422a, v141
	v_mul_f32_e32 v141, 0xc038aa3b, v141
	s_cmp_eq_u32 s42, 2
	s_mov_b32 s0, 0x5280000
	v_exp_f32_e32 v141, v141
	s_cselect_b32 s0, s0, 0x6300000
	s_add_u32 s0, s90, s0
	v_lshl_add_u32 v142, v236, 3, s43
	s_addc_u32 s1, s91, 0
	v_ashrrev_i32_e32 v143, 31, v142
	v_lshl_add_u64 v[142:143], v[142:143], 1, s[0:1]
	v_add_f32_e32 v141, 1.0, v141
	v_lshl_add_u64 v[142:143], v[142:143], 0, v[144:145]
	v_rcp_f32_e32 v144, v141
	v_mul_f32_e32 v141, 0x3d372713, v125
	v_mul_f32_e32 v141, v125, v141
	v_fma_f32 v141, v125, v141, v125
	v_mul_f32_e32 v141, 0x3f4c422a, v141
	v_mul_f32_e32 v141, 0xc038aa3b, v141
	v_exp_f32_e32 v141, v141
	s_mov_b64 s[0:1], 0x2000
	v_add_f32_e32 v141, 1.0, v141
	v_rcp_f32_e32 v145, v141
	v_mul_f32_e32 v141, 0x3d372713, v126
	v_mul_f32_e32 v141, v126, v141
	v_fma_f32 v141, v126, v141, v126
	v_mul_f32_e32 v141, 0x3f4c422a, v141
	v_mul_f32_e32 v141, 0xc038aa3b, v141
	v_exp_f32_e32 v141, v141
	v_mul_f32_e32 v144, v124, v144
	v_mul_f32_e32 v145, v125, v145
	v_add_f32_e32 v141, 1.0, v141
	v_rcp_f32_e32 v146, v141
	v_mul_f32_e32 v141, 0x3d372713, v127
	v_mul_f32_e32 v141, v127, v141
	v_fma_f32 v141, v127, v141, v127
	v_mul_f32_e32 v141, 0x3f4c422a, v141
	v_mul_f32_e32 v141, 0xc038aa3b, v141
	v_exp_f32_e32 v141, v141
	v_cvt_pk_bf16_f32 v144, v144, v145
	v_add_f32_e32 v141, 1.0, v141
	v_rcp_f32_e32 v147, v141
	v_mul_f32_e32 v141, 0x3d372713, v120
	v_mul_f32_e32 v141, v120, v141
	v_fma_f32 v141, v120, v141, v120
	v_mul_f32_e32 v141, 0x3f4c422a, v141
	v_mul_f32_e32 v141, 0xc038aa3b, v141
	v_exp_f32_e32 v141, v141
	v_mul_f32_e32 v146, v126, v146
	v_mul_f32_e32 v147, v127, v147
	v_add_f32_e32 v141, 1.0, v141
	v_cvt_pk_bf16_f32 v145, v146, v147
	v_rcp_f32_e32 v146, v141
	v_mul_f32_e32 v141, 0x3d372713, v121
	v_mul_f32_e32 v141, v121, v141
	v_fma_f32 v141, v121, v141, v121
	v_mul_f32_e32 v141, 0x3f4c422a, v141
	v_mul_f32_e32 v141, 0xc038aa3b, v141
	v_exp_f32_e32 v141, v141
	s_nop 0
	v_add_f32_e32 v141, 1.0, v141
	v_rcp_f32_e32 v147, v141
	v_mul_f32_e32 v141, 0x3d372713, v122
	v_mul_f32_e32 v141, v122, v141
	v_fma_f32 v141, v122, v141, v122
	v_mul_f32_e32 v141, 0x3f4c422a, v141
	v_mul_f32_e32 v141, 0xc038aa3b, v141
	v_exp_f32_e32 v141, v141
	v_mul_f32_e32 v146, v120, v146
	v_mul_f32_e32 v147, v121, v147
	v_add_f32_e32 v141, 1.0, v141
	v_rcp_f32_e32 v148, v141
	v_mul_f32_e32 v141, 0x3d372713, v123
	v_mul_f32_e32 v141, v123, v141
	v_fma_f32 v141, v123, v141, v123
	v_mul_f32_e32 v141, 0x3f4c422a, v141
	v_mul_f32_e32 v141, 0xc038aa3b, v141
	v_exp_f32_e32 v141, v141
	v_cvt_pk_bf16_f32 v146, v146, v147
	v_add_f32_e32 v141, 1.0, v141
	v_rcp_f32_e32 v149, v141
	v_mul_f32_e32 v141, 0x3d372713, v108
	v_mul_f32_e32 v141, v108, v141
	v_fma_f32 v141, v108, v141, v108
	v_mul_f32_e32 v141, 0x3f4c422a, v141
	v_mul_f32_e32 v141, 0xc038aa3b, v141
	v_exp_f32_e32 v141, v141
	v_mul_f32_e32 v148, v122, v148
	v_mul_f32_e32 v149, v123, v149
	v_add_f32_e32 v141, 1.0, v141
	v_cvt_pk_bf16_f32 v147, v148, v149
	global_store_dwordx4 v[142:143], v[144:147], off
	s_nop 1
	v_rcp_f32_e32 v144, v141
	v_mul_f32_e32 v141, 0x3d372713, v109
	v_mul_f32_e32 v141, v109, v141
	v_fma_f32 v141, v109, v141, v109
	v_mul_f32_e32 v141, 0x3f4c422a, v141
	v_mul_f32_e32 v141, 0xc038aa3b, v141
	v_exp_f32_e32 v141, v141
	s_nop 0
	v_add_f32_e32 v141, 1.0, v141
	v_rcp_f32_e32 v145, v141
	v_mul_f32_e32 v141, 0x3d372713, v110
	v_mul_f32_e32 v141, v110, v141
	v_fma_f32 v141, v110, v141, v110
	v_mul_f32_e32 v141, 0x3f4c422a, v141
	v_mul_f32_e32 v141, 0xc038aa3b, v141
	v_exp_f32_e32 v141, v141
	v_mul_f32_e32 v144, v108, v144
	v_mul_f32_e32 v145, v109, v145
	v_add_f32_e32 v141, 1.0, v141
	v_rcp_f32_e32 v146, v141
	v_mul_f32_e32 v141, 0x3d372713, v111
	v_mul_f32_e32 v141, v111, v141
	v_fma_f32 v141, v111, v141, v111
	v_mul_f32_e32 v141, 0x3f4c422a, v141
	v_mul_f32_e32 v141, 0xc038aa3b, v141
	v_exp_f32_e32 v141, v141
	v_cvt_pk_bf16_f32 v144, v144, v145
	v_add_f32_e32 v141, 1.0, v141
	v_rcp_f32_e32 v147, v141
	v_mul_f32_e32 v141, 0x3d372713, v104
	v_mul_f32_e32 v141, v104, v141
	v_fma_f32 v141, v104, v141, v104
	v_mul_f32_e32 v141, 0x3f4c422a, v141
	v_mul_f32_e32 v141, 0xc038aa3b, v141
	v_exp_f32_e32 v141, v141
	v_mul_f32_e32 v146, v110, v146
	v_mul_f32_e32 v147, v111, v147
	v_add_f32_e32 v141, 1.0, v141
	v_cvt_pk_bf16_f32 v145, v146, v147
	v_rcp_f32_e32 v146, v141
	v_mul_f32_e32 v141, 0x3d372713, v105
	v_mul_f32_e32 v141, v105, v141
	v_fma_f32 v141, v105, v141, v105
	v_mul_f32_e32 v141, 0x3f4c422a, v141
	v_mul_f32_e32 v141, 0xc038aa3b, v141
	v_exp_f32_e32 v141, v141
	s_nop 0
	v_add_f32_e32 v141, 1.0, v141
	v_rcp_f32_e32 v147, v141
	v_mul_f32_e32 v141, 0x3d372713, v106
	v_mul_f32_e32 v141, v106, v141
	v_fma_f32 v141, v106, v141, v106
	v_mul_f32_e32 v141, 0x3f4c422a, v141
	v_mul_f32_e32 v141, 0xc038aa3b, v141
	v_exp_f32_e32 v141, v141
	v_mul_f32_e32 v146, v104, v146
	v_mul_f32_e32 v147, v105, v147
	v_add_f32_e32 v141, 1.0, v141
	v_rcp_f32_e32 v148, v141
	v_mul_f32_e32 v141, 0x3d372713, v107
	v_mul_f32_e32 v141, v107, v141
	v_fma_f32 v141, v107, v141, v107
	v_mul_f32_e32 v141, 0x3f4c422a, v141
	v_mul_f32_e32 v141, 0xc038aa3b, v141
	v_exp_f32_e32 v141, v141
	v_cvt_pk_bf16_f32 v146, v146, v147
	v_add_f32_e32 v141, 1.0, v141
	v_rcp_f32_e32 v149, v141
	v_mul_f32_e32 v141, 0x3d372713, v116
	v_mul_f32_e32 v141, v116, v141
	v_fma_f32 v141, v116, v141, v116
	v_mul_f32_e32 v141, 0x3f4c422a, v141
	v_mul_f32_e32 v141, 0xc038aa3b, v141
; __device__ __forceinline__ unsigned cvt_pk_bf16(float lo, float hi) { const f32x2 v = {lo, hi}; const bf16x2_t b = __builtin_convertvector(v, bf16x2_t); return __builtin_bit_cast(unsigned, b); }
; __device__ __forceinline__ float gelu_tanh_f(float x) { const float u = 0.7978845608028654f * (x + 0.044715f * x * x * x); return x * fast_rcp(1.0f + fast_exp2(-2.0f * LOG2E * u)); }
;     __device__ __forceinline__ void operator()(const f32x4 (&acc)[2][2][4][2], const Unit& u, int wr, int wc, int fr, int fq) const {
;     ...
;                 for (int m = 0; m < 4; ++m) { bf16_t* rowp = dst + (size_t)(row0 + ai * HALF + m * 16) * 256 + col0;
; #pragma unroll
;                     for (int bj = 0; bj < 2; ++bj) { const f32x4 v0 = acc[ai][bj][m][0], v1 = acc[ai][bj][m][1]; u32x4 w;
;                         w.x = cvt_pk_bf16(gelu_tanh_f(v0[0]), gelu_tanh_f(v0[1])); w.y = cvt_pk_bf16(gelu_tanh_f(v0[2]), gelu_tanh_f(v0[3]));
;                         w.z = cvt_pk_bf16(gelu_tanh_f(v1[0]), gelu_tanh_f(v1[1])); w.w = cvt_pk_bf16(gelu_tanh_f(v1[2]), gelu_tanh_f(v1[3]));
;                         *(u32x4*)(rowp + bj * HALF) = w; } }
	v_exp_f32_e32 v141, v141
	v_mul_f32_e32 v148, v106, v148
	v_mul_f32_e32 v149, v107, v149
	v_add_f32_e32 v141, 1.0, v141
	v_cvt_pk_bf16_f32 v147, v148, v149
	global_store_dwordx4 v[142:143], v[144:147], off offset:256
	s_nop 1
	v_rcp_f32_e32 v146, v141
	v_mul_f32_e32 v141, 0x3d372713, v117
	v_mul_f32_e32 v141, v117, v141
	v_fma_f32 v141, v117, v141, v117
	v_mul_f32_e32 v141, 0x3f4c422a, v141
	v_mul_f32_e32 v141, 0xc038aa3b, v141
	v_exp_f32_e32 v141, v141
	v_lshl_add_u64 v[144:145], v[142:143], 0, s[0:1]
	s_movk_i32 s0, 0x2000
	v_add_f32_e32 v141, 1.0, v141
	v_rcp_f32_e32 v147, v141
	v_mul_f32_e32 v141, 0x3d372713, v118
	v_mul_f32_e32 v141, v118, v141
	v_fma_f32 v141, v118, v141, v118
	v_mul_f32_e32 v141, 0x3f4c422a, v141
	v_mul_f32_e32 v141, 0xc038aa3b, v141
	v_exp_f32_e32 v141, v141
	v_mul_f32_e32 v146, v116, v146
	v_mul_f32_e32 v147, v117, v147
	v_add_f32_e32 v141, 1.0, v141
	v_rcp_f32_e32 v148, v141
	v_mul_f32_e32 v141, 0x3d372713, v119
	v_mul_f32_e32 v141, v119, v141
	v_fma_f32 v141, v119, v141, v119
	v_mul_f32_e32 v141, 0x3f4c422a, v141
	v_mul_f32_e32 v141, 0xc038aa3b, v141
	v_exp_f32_e32 v141, v141
	v_cvt_pk_bf16_f32 v146, v146, v147
	v_add_f32_e32 v141, 1.0, v141
	v_rcp_f32_e32 v149, v141
	v_mul_f32_e32 v141, 0x3d372713, v112
	v_mul_f32_e32 v141, v112, v141
	v_fma_f32 v141, v112, v141, v112
	v_mul_f32_e32 v141, 0x3f4c422a, v141
	v_mul_f32_e32 v141, 0xc038aa3b, v141
	v_exp_f32_e32 v141, v141
	v_mul_f32_e32 v148, v118, v148
	v_mul_f32_e32 v149, v119, v149
	v_add_f32_e32 v141, 1.0, v141
	v_cvt_pk_bf16_f32 v147, v148, v149
	v_rcp_f32_e32 v148, v141
	v_mul_f32_e32 v141, 0x3d372713, v113
	v_mul_f32_e32 v141, v113, v141
	v_fma_f32 v141, v113, v141, v113
	v_mul_f32_e32 v141, 0x3f4c422a, v141
	v_mul_f32_e32 v141, 0xc038aa3b, v141
	v_exp_f32_e32 v141, v141
	s_nop 0
	v_add_f32_e32 v141, 1.0, v141
	v_rcp_f32_e32 v149, v141
	v_mul_f32_e32 v141, 0x3d372713, v114
	v_mul_f32_e32 v141, v114, v141
	v_fma_f32 v141, v114, v141, v114
	v_mul_f32_e32 v141, 0x3f4c422a, v141
	v_mul_f32_e32 v141, 0xc038aa3b, v141
	v_exp_f32_e32 v141, v141
	v_mul_f32_e32 v148, v112, v148
	v_mul_f32_e32 v149, v113, v149
	v_add_f32_e32 v141, 1.0, v141
	v_rcp_f32_e32 v150, v141
	v_mul_f32_e32 v141, 0x3d372713, v115
	v_mul_f32_e32 v141, v115, v141
	v_fma_f32 v141, v115, v141, v115
	v_mul_f32_e32 v141, 0x3f4c422a, v141
	v_mul_f32_e32 v141, 0xc038aa3b, v141
	v_exp_f32_e32 v141, v141
	v_cvt_pk_bf16_f32 v148, v148, v149
	v_add_f32_e32 v141, 1.0, v141
	v_rcp_f32_e32 v151, v141
	v_mul_f32_e32 v141, 0x3d372713, v92
	v_mul_f32_e32 v141, v92, v141
	v_fma_f32 v141, v92, v141, v92
	v_mul_f32_e32 v141, 0x3f4c422a, v141
	v_mul_f32_e32 v141, 0xc038aa3b, v141
	v_exp_f32_e32 v141, v141
	v_mul_f32_e32 v150, v114, v150
	v_mul_f32_e32 v151, v115, v151
	v_add_f32_e32 v141, 1.0, v141
	v_cvt_pk_bf16_f32 v149, v150, v151
	v_add_co_u32_e32 v150, vcc, s0, v142
	s_mov_b64 s[0:1], 0x4000
	s_nop 0
	v_addc_co_u32_e32 v151, vcc, 0, v143, vcc
	global_store_dwordx4 v[150:151], v[146:149], off
	s_nop 1
	v_rcp_f32_e32 v146, v141
	v_mul_f32_e32 v141, 0x3d372713, v93
	v_mul_f32_e32 v141, v93, v141
	v_fma_f32 v141, v93, v141, v93
	v_mul_f32_e32 v141, 0x3f4c422a, v141
	v_mul_f32_e32 v141, 0xc038aa3b, v141
	v_exp_f32_e32 v141, v141
	s_nop 0
	v_add_f32_e32 v141, 1.0, v141
	v_rcp_f32_e32 v147, v141
	v_mul_f32_e32 v141, 0x3d372713, v94
	v_mul_f32_e32 v141, v94, v141
	v_fma_f32 v141, v94, v141, v94
	v_mul_f32_e32 v141, 0x3f4c422a, v141
	v_mul_f32_e32 v141, 0xc038aa3b, v141
	v_exp_f32_e32 v141, v141
	v_mul_f32_e32 v146, v92, v146
	v_mul_f32_e32 v147, v93, v147
	v_add_f32_e32 v141, 1.0, v141
	v_rcp_f32_e32 v148, v141
	v_mul_f32_e32 v141, 0x3d372713, v95
	v_mul_f32_e32 v141, v95, v141
	v_fma_f32 v141, v95, v141, v95
	v_mul_f32_e32 v141, 0x3f4c422a, v141
	v_mul_f32_e32 v141, 0xc038aa3b, v141
	v_exp_f32_e32 v141, v141
	v_cvt_pk_bf16_f32 v146, v146, v147
	v_add_f32_e32 v141, 1.0, v141
	v_rcp_f32_e32 v149, v141
	v_mul_f32_e32 v141, 0x3d372713, v88
	v_mul_f32_e32 v141, v88, v141
	v_fma_f32 v141, v88, v141, v88
	v_mul_f32_e32 v141, 0x3f4c422a, v141
	v_mul_f32_e32 v141, 0xc038aa3b, v141
	v_exp_f32_e32 v141, v141
	v_mul_f32_e32 v148, v94, v148
	v_mul_f32_e32 v149, v95, v149
	v_add_f32_e32 v141, 1.0, v141
	v_cvt_pk_bf16_f32 v147, v148, v149
	v_rcp_f32_e32 v148, v141
	v_mul_f32_e32 v141, 0x3d372713, v89
	v_mul_f32_e32 v141, v89, v141
	v_fma_f32 v141, v89, v141, v89
	v_mul_f32_e32 v141, 0x3f4c422a, v141
	v_mul_f32_e32 v141, 0xc038aa3b, v141
	v_exp_f32_e32 v141, v141
	s_nop 0
	v_add_f32_e32 v141, 1.0, v141
	v_rcp_f32_e32 v149, v141
	v_mul_f32_e32 v141, 0x3d372713, v90
	v_mul_f32_e32 v141, v90, v141
	v_fma_f32 v141, v90, v141, v90
	v_mul_f32_e32 v141, 0x3f4c422a, v141
	v_mul_f32_e32 v141, 0xc038aa3b, v141
	v_exp_f32_e32 v141, v141
	v_mul_f32_e32 v148, v88, v148
	v_mul_f32_e32 v149, v89, v149
	v_add_f32_e32 v141, 1.0, v141
	v_rcp_f32_e32 v150, v141
	v_mul_f32_e32 v141, 0x3d372713, v91
	v_mul_f32_e32 v141, v91, v141
	v_fma_f32 v141, v91, v141, v91
	v_mul_f32_e32 v141, 0x3f4c422a, v141
	v_mul_f32_e32 v141, 0xc038aa3b, v141
	v_exp_f32_e32 v141, v141
	v_cvt_pk_bf16_f32 v148, v148, v149
	v_add_f32_e32 v141, 1.0, v141
	v_rcp_f32_e32 v151, v141
	v_mul_f32_e32 v141, 0x3d372713, v100
	v_mul_f32_e32 v141, v100, v141
	v_fma_f32 v141, v100, v141, v100
	v_mul_f32_e32 v141, 0x3f4c422a, v141
	v_mul_f32_e32 v141, 0xc038aa3b, v141
	v_exp_f32_e32 v141, v141
	v_mul_f32_e32 v150, v90, v150
	v_mul_f32_e32 v151, v91, v151
	v_add_f32_e32 v141, 1.0, v141
	v_cvt_pk_bf16_f32 v149, v150, v151
	global_store_dwordx4 v[144:145], v[146:149], off offset:256
	v_lshl_add_u64 v[144:145], v[142:143], 0, s[0:1]
	s_movk_i32 s0, 0x4000
	v_rcp_f32_e32 v146, v141
; __device__ __forceinline__ unsigned cvt_pk_bf16(float lo, float hi) { const f32x2 v = {lo, hi}; const bf16x2_t b = __builtin_convertvector(v, bf16x2_t); return __builtin_bit_cast(unsigned, b); }
; __device__ __forceinline__ float gelu_tanh_f(float x) { const float u = 0.7978845608028654f * (x + 0.044715f * x * x * x); return x * fast_rcp(1.0f + fast_exp2(-2.0f * LOG2E * u)); }
;     __device__ __forceinline__ void operator()(const f32x4 (&acc)[2][2][4][2], const Unit& u, int wr, int wc, int fr, int fq) const {
;     ...
;                 for (int m = 0; m < 4; ++m) { bf16_t* rowp = dst + (size_t)(row0 + ai * HALF + m * 16) * 256 + col0;
; #pragma unroll
;                     for (int bj = 0; bj < 2; ++bj) { const f32x4 v0 = acc[ai][bj][m][0], v1 = acc[ai][bj][m][1]; u32x4 w;
;                         w.x = cvt_pk_bf16(gelu_tanh_f(v0[0]), gelu_tanh_f(v0[1])); w.y = cvt_pk_bf16(gelu_tanh_f(v0[2]), gelu_tanh_f(v0[3]));
;                         w.z = cvt_pk_bf16(gelu_tanh_f(v1[0]), gelu_tanh_f(v1[1])); w.w = cvt_pk_bf16(gelu_tanh_f(v1[2]), gelu_tanh_f(v1[3]));
;                         *(u32x4*)(rowp + bj * HALF) = w; } }
	v_mul_f32_e32 v141, 0x3d372713, v101
	v_mul_f32_e32 v141, v101, v141
	v_fma_f32 v141, v101, v141, v101
	v_mul_f32_e32 v141, 0x3f4c422a, v141
	v_mul_f32_e32 v141, 0xc038aa3b, v141
	v_exp_f32_e32 v141, v141
	s_nop 0
	v_add_f32_e32 v141, 1.0, v141
	v_rcp_f32_e32 v147, v141
	v_mul_f32_e32 v141, 0x3d372713, v102
	v_mul_f32_e32 v141, v102, v141
	v_fma_f32 v141, v102, v141, v102
	v_mul_f32_e32 v141, 0x3f4c422a, v141
	v_mul_f32_e32 v141, 0xc038aa3b, v141
	v_exp_f32_e32 v141, v141
	v_mul_f32_e32 v146, v100, v146
	v_mul_f32_e32 v147, v101, v147
	v_add_f32_e32 v141, 1.0, v141
	v_rcp_f32_e32 v148, v141
	v_mul_f32_e32 v141, 0x3d372713, v103
	v_mul_f32_e32 v141, v103, v141
	v_fma_f32 v141, v103, v141, v103
	v_mul_f32_e32 v141, 0x3f4c422a, v141
	v_mul_f32_e32 v141, 0xc038aa3b, v141
	v_exp_f32_e32 v141, v141
	v_cvt_pk_bf16_f32 v146, v146, v147
	v_add_f32_e32 v141, 1.0, v141
	v_rcp_f32_e32 v149, v141
	v_mul_f32_e32 v141, 0x3d372713, v96
	v_mul_f32_e32 v141, v96, v141
	v_fma_f32 v141, v96, v141, v96
	v_mul_f32_e32 v141, 0x3f4c422a, v141
	v_mul_f32_e32 v141, 0xc038aa3b, v141
	v_exp_f32_e32 v141, v141
	v_mul_f32_e32 v148, v102, v148
	v_mul_f32_e32 v149, v103, v149
	v_add_f32_e32 v141, 1.0, v141
	v_cvt_pk_bf16_f32 v147, v148, v149
	v_rcp_f32_e32 v148, v141
	v_mul_f32_e32 v141, 0x3d372713, v97
	v_mul_f32_e32 v141, v97, v141
	v_fma_f32 v141, v97, v141, v97
	v_mul_f32_e32 v141, 0x3f4c422a, v141
	v_mul_f32_e32 v141, 0xc038aa3b, v141
	v_exp_f32_e32 v141, v141
	s_nop 0
	v_add_f32_e32 v141, 1.0, v141
	v_rcp_f32_e32 v149, v141
	v_mul_f32_e32 v141, 0x3d372713, v98
	v_mul_f32_e32 v141, v98, v141
	v_fma_f32 v141, v98, v141, v98
	v_mul_f32_e32 v141, 0x3f4c422a, v141
	v_mul_f32_e32 v141, 0xc038aa3b, v141
	v_exp_f32_e32 v141, v141
	v_mul_f32_e32 v148, v96, v148
	v_mul_f32_e32 v149, v97, v149
	v_add_f32_e32 v141, 1.0, v141
	v_rcp_f32_e32 v150, v141
	v_mul_f32_e32 v141, 0x3d372713, v99
	v_mul_f32_e32 v141, v99, v141
	v_fma_f32 v141, v99, v141, v99
	v_mul_f32_e32 v141, 0x3f4c422a, v141
	v_mul_f32_e32 v141, 0xc038aa3b, v141
	v_exp_f32_e32 v141, v141
	v_cvt_pk_bf16_f32 v148, v148, v149
	v_add_f32_e32 v141, 1.0, v141
	v_rcp_f32_e32 v151, v141
	v_mul_f32_e32 v141, 0x3d372713, v76
	v_mul_f32_e32 v141, v76, v141
	v_fma_f32 v141, v76, v141, v76
	v_mul_f32_e32 v141, 0x3f4c422a, v141
	v_mul_f32_e32 v141, 0xc038aa3b, v141
	v_exp_f32_e32 v141, v141
	v_mul_f32_e32 v150, v98, v150
	v_mul_f32_e32 v151, v99, v151
	v_add_f32_e32 v141, 1.0, v141
	v_cvt_pk_bf16_f32 v149, v150, v151
	v_add_co_u32_e32 v150, vcc, s0, v142
	s_mov_b64 s[0:1], 0x6000
	s_nop 0
	v_addc_co_u32_e32 v151, vcc, 0, v143, vcc
	global_store_dwordx4 v[150:151], v[146:149], off
	s_nop 1
	v_rcp_f32_e32 v146, v141
	v_mul_f32_e32 v141, 0x3d372713, v77
	v_mul_f32_e32 v141, v77, v141
	v_fma_f32 v141, v77, v141, v77
	v_mul_f32_e32 v141, 0x3f4c422a, v141
	v_mul_f32_e32 v141, 0xc038aa3b, v141
	v_exp_f32_e32 v141, v141
	s_nop 0
	v_add_f32_e32 v141, 1.0, v141
	v_rcp_f32_e32 v147, v141
	v_mul_f32_e32 v141, 0x3d372713, v78
	v_mul_f32_e32 v141, v78, v141
	v_fma_f32 v141, v78, v141, v78
	v_mul_f32_e32 v141, 0x3f4c422a, v141
	v_mul_f32_e32 v141, 0xc038aa3b, v141
	v_exp_f32_e32 v141, v141
	v_mul_f32_e32 v146, v76, v146
	v_mul_f32_e32 v147, v77, v147
	v_add_f32_e32 v141, 1.0, v141
	v_rcp_f32_e32 v148, v141
	v_mul_f32_e32 v141, 0x3d372713, v79
	v_mul_f32_e32 v141, v79, v141
	v_fma_f32 v141, v79, v141, v79
	v_mul_f32_e32 v141, 0x3f4c422a, v141
	v_mul_f32_e32 v141, 0xc038aa3b, v141
	v_exp_f32_e32 v141, v141
	v_cvt_pk_bf16_f32 v146, v146, v147
	v_add_f32_e32 v141, 1.0, v141
	v_rcp_f32_e32 v149, v141
	v_mul_f32_e32 v141, 0x3d372713, v72
	v_mul_f32_e32 v141, v72, v141
	v_fma_f32 v141, v72, v141, v72
	v_mul_f32_e32 v141, 0x3f4c422a, v141
	v_mul_f32_e32 v141, 0xc038aa3b, v141
	v_exp_f32_e32 v141, v141
	v_mul_f32_e32 v148, v78, v148
	v_mul_f32_e32 v149, v79, v149
	v_add_f32_e32 v141, 1.0, v141
	v_cvt_pk_bf16_f32 v147, v148, v149
	v_rcp_f32_e32 v148, v141
	v_mul_f32_e32 v141, 0x3d372713, v73
	v_mul_f32_e32 v141, v73, v141
	v_fma_f32 v141, v73, v141, v73
	v_mul_f32_e32 v141, 0x3f4c422a, v141
	v_mul_f32_e32 v141, 0xc038aa3b, v141
	v_exp_f32_e32 v141, v141
	s_nop 0
	v_add_f32_e32 v141, 1.0, v141
	v_rcp_f32_e32 v149, v141
	v_mul_f32_e32 v141, 0x3d372713, v74
	v_mul_f32_e32 v141, v74, v141
	v_fma_f32 v141, v74, v141, v74
	v_mul_f32_e32 v141, 0x3f4c422a, v141
	v_mul_f32_e32 v141, 0xc038aa3b, v141
	v_exp_f32_e32 v141, v141
	v_mul_f32_e32 v148, v72, v148
	v_mul_f32_e32 v149, v73, v149
	v_add_f32_e32 v141, 1.0, v141
	v_rcp_f32_e32 v150, v141
	v_mul_f32_e32 v141, 0x3d372713, v75
	v_mul_f32_e32 v141, v75, v141
	v_fma_f32 v141, v75, v141, v75
	v_mul_f32_e32 v141, 0x3f4c422a, v141
	v_mul_f32_e32 v141, 0xc038aa3b, v141
	v_exp_f32_e32 v141, v141
	v_cvt_pk_bf16_f32 v148, v148, v149
	v_add_f32_e32 v141, 1.0, v141
	v_rcp_f32_e32 v151, v141
	v_mul_f32_e32 v141, 0x3d372713, v84
	v_mul_f32_e32 v141, v84, v141
	v_fma_f32 v141, v84, v141, v84
	v_mul_f32_e32 v141, 0x3f4c422a, v141
	v_mul_f32_e32 v141, 0xc038aa3b, v141
	v_exp_f32_e32 v141, v141
	v_mul_f32_e32 v150, v74, v150
	v_mul_f32_e32 v151, v75, v151
	v_add_f32_e32 v141, 1.0, v141
	v_cvt_pk_bf16_f32 v149, v150, v151
	global_store_dwordx4 v[144:145], v[146:149], off offset:256
	v_lshl_add_u64 v[144:145], v[142:143], 0, s[0:1]
	s_movk_i32 s0, 0x6000
	v_rcp_f32_e32 v146, v141
	v_mul_f32_e32 v141, 0x3d372713, v85
	v_mul_f32_e32 v141, v85, v141
	v_fma_f32 v141, v85, v141, v85
	v_mul_f32_e32 v141, 0x3f4c422a, v141
	v_mul_f32_e32 v141, 0xc038aa3b, v141
	v_exp_f32_e32 v141, v141
	s_nop 0
	v_add_f32_e32 v141, 1.0, v141
	v_rcp_f32_e32 v147, v141
	v_mul_f32_e32 v141, 0x3d372713, v86
	v_mul_f32_e32 v141, v86, v141
; __device__ __forceinline__ unsigned cvt_pk_bf16(float lo, float hi) { const f32x2 v = {lo, hi}; const bf16x2_t b = __builtin_convertvector(v, bf16x2_t); return __builtin_bit_cast(unsigned, b); }
; __device__ __forceinline__ float gelu_tanh_f(float x) { const float u = 0.7978845608028654f * (x + 0.044715f * x * x * x); return x * fast_rcp(1.0f + fast_exp2(-2.0f * LOG2E * u)); }
;     __device__ __forceinline__ void operator()(const f32x4 (&acc)[2][2][4][2], const Unit& u, int wr, int wc, int fr, int fq) const {
;     ...
;                 for (int m = 0; m < 4; ++m) { bf16_t* rowp = dst + (size_t)(row0 + ai * HALF + m * 16) * 256 + col0;
; #pragma unroll
;                     for (int bj = 0; bj < 2; ++bj) { const f32x4 v0 = acc[ai][bj][m][0], v1 = acc[ai][bj][m][1]; u32x4 w;
;                         w.x = cvt_pk_bf16(gelu_tanh_f(v0[0]), gelu_tanh_f(v0[1])); w.y = cvt_pk_bf16(gelu_tanh_f(v0[2]), gelu_tanh_f(v0[3]));
;                         w.z = cvt_pk_bf16(gelu_tanh_f(v1[0]), gelu_tanh_f(v1[1])); w.w = cvt_pk_bf16(gelu_tanh_f(v1[2]), gelu_tanh_f(v1[3]));
;                         *(u32x4*)(rowp + bj * HALF) = w; } }
	v_fma_f32 v141, v86, v141, v86
	v_mul_f32_e32 v141, 0x3f4c422a, v141
	v_mul_f32_e32 v141, 0xc038aa3b, v141
	v_exp_f32_e32 v141, v141
	v_mul_f32_e32 v146, v84, v146
	v_mul_f32_e32 v147, v85, v147
	v_add_f32_e32 v141, 1.0, v141
	v_rcp_f32_e32 v148, v141
	v_mul_f32_e32 v141, 0x3d372713, v87
	v_mul_f32_e32 v141, v87, v141
	v_fma_f32 v141, v87, v141, v87
	v_mul_f32_e32 v141, 0x3f4c422a, v141
	v_mul_f32_e32 v141, 0xc038aa3b, v141
	v_exp_f32_e32 v141, v141
	v_cvt_pk_bf16_f32 v146, v146, v147
	v_add_f32_e32 v141, 1.0, v141
	v_rcp_f32_e32 v149, v141
	v_mul_f32_e32 v141, 0x3d372713, v80
	v_mul_f32_e32 v141, v80, v141
	v_fma_f32 v141, v80, v141, v80
	v_mul_f32_e32 v141, 0x3f4c422a, v141
	v_mul_f32_e32 v141, 0xc038aa3b, v141
	v_exp_f32_e32 v141, v141
	v_mul_f32_e32 v148, v86, v148
	v_mul_f32_e32 v149, v87, v149
	v_add_f32_e32 v141, 1.0, v141
	v_cvt_pk_bf16_f32 v147, v148, v149
	v_rcp_f32_e32 v148, v141
	v_mul_f32_e32 v141, 0x3d372713, v81
	v_mul_f32_e32 v141, v81, v141
	v_fma_f32 v141, v81, v141, v81
	v_mul_f32_e32 v141, 0x3f4c422a, v141
	v_mul_f32_e32 v141, 0xc038aa3b, v141
	v_exp_f32_e32 v141, v141
	s_nop 0
	v_add_f32_e32 v141, 1.0, v141
	v_rcp_f32_e32 v149, v141
	v_mul_f32_e32 v141, 0x3d372713, v82
	v_mul_f32_e32 v141, v82, v141
	v_fma_f32 v141, v82, v141, v82
	v_mul_f32_e32 v141, 0x3f4c422a, v141
	v_mul_f32_e32 v141, 0xc038aa3b, v141
	v_exp_f32_e32 v141, v141
	v_mul_f32_e32 v148, v80, v148
	v_mul_f32_e32 v149, v81, v149
	v_add_f32_e32 v141, 1.0, v141
	v_rcp_f32_e32 v150, v141
	v_mul_f32_e32 v141, 0x3d372713, v83
	v_mul_f32_e32 v141, v83, v141
	v_fma_f32 v141, v83, v141, v83
	v_mul_f32_e32 v141, 0x3f4c422a, v141
	v_mul_f32_e32 v141, 0xc038aa3b, v141
	v_exp_f32_e32 v141, v141
	v_cvt_pk_bf16_f32 v148, v148, v149
	v_add_f32_e32 v141, 1.0, v141
	v_rcp_f32_e32 v151, v141
	v_mul_f32_e32 v141, 0x3d372713, v68
	v_mul_f32_e32 v141, v68, v141
	v_fma_f32 v141, v68, v141, v68
	v_mul_f32_e32 v141, 0x3f4c422a, v141
	v_mul_f32_e32 v141, 0xc038aa3b, v141
	v_exp_f32_e32 v141, v141
	v_mul_f32_e32 v150, v82, v150
	v_mul_f32_e32 v151, v83, v151
	v_add_f32_e32 v141, 1.0, v141
	v_cvt_pk_bf16_f32 v149, v150, v151
	v_add_co_u32_e32 v150, vcc, s0, v142
	s_mov_b64 s[0:1], 0x10000
	s_nop 0
	v_addc_co_u32_e32 v151, vcc, 0, v143, vcc
	global_store_dwordx4 v[150:151], v[146:149], off
	s_nop 1
	v_rcp_f32_e32 v146, v141
	v_mul_f32_e32 v141, 0x3d372713, v69
	v_mul_f32_e32 v141, v69, v141
	v_fma_f32 v141, v69, v141, v69
	v_mul_f32_e32 v141, 0x3f4c422a, v141
	v_mul_f32_e32 v141, 0xc038aa3b, v141
	v_exp_f32_e32 v141, v141
	s_nop 0
	v_add_f32_e32 v141, 1.0, v141
	v_rcp_f32_e32 v147, v141
	v_mul_f32_e32 v141, 0x3d372713, v70
	v_mul_f32_e32 v141, v70, v141
	v_fma_f32 v141, v70, v141, v70
	v_mul_f32_e32 v141, 0x3f4c422a, v141
	v_mul_f32_e32 v141, 0xc038aa3b, v141
	v_exp_f32_e32 v141, v141
	v_mul_f32_e32 v146, v68, v146
	v_mul_f32_e32 v147, v69, v147
	v_add_f32_e32 v141, 1.0, v141
	v_rcp_f32_e32 v148, v141
	v_mul_f32_e32 v141, 0x3d372713, v71
	v_mul_f32_e32 v141, v71, v141
	v_fma_f32 v141, v71, v141, v71
	v_mul_f32_e32 v141, 0x3f4c422a, v141
	v_mul_f32_e32 v141, 0xc038aa3b, v141
	v_exp_f32_e32 v141, v141
	v_cvt_pk_bf16_f32 v146, v146, v147
	v_add_f32_e32 v141, 1.0, v141
	v_rcp_f32_e32 v149, v141
	v_mul_f32_e32 v141, 0x3d372713, v64
	v_mul_f32_e32 v141, v64, v141
	v_fma_f32 v141, v64, v141, v64
	v_mul_f32_e32 v141, 0x3f4c422a, v141
	v_mul_f32_e32 v141, 0xc038aa3b, v141
	v_exp_f32_e32 v141, v141
	v_mul_f32_e32 v148, v70, v148
	v_mul_f32_e32 v149, v71, v149
	v_add_f32_e32 v141, 1.0, v141
	v_cvt_pk_bf16_f32 v147, v148, v149
	v_rcp_f32_e32 v148, v141
	v_mul_f32_e32 v141, 0x3d372713, v65
	v_mul_f32_e32 v141, v65, v141
	v_fma_f32 v141, v65, v141, v65
	v_mul_f32_e32 v141, 0x3f4c422a, v141
	v_mul_f32_e32 v141, 0xc038aa3b, v141
	v_exp_f32_e32 v141, v141
	s_nop 0
	v_add_f32_e32 v141, 1.0, v141
	v_rcp_f32_e32 v149, v141
	v_mul_f32_e32 v141, 0x3d372713, v66
	v_mul_f32_e32 v141, v66, v141
	v_fma_f32 v141, v66, v141, v66
	v_mul_f32_e32 v141, 0x3f4c422a, v141
	v_mul_f32_e32 v141, 0xc038aa3b, v141
	v_exp_f32_e32 v141, v141
	v_mul_f32_e32 v148, v64, v148
	v_mul_f32_e32 v149, v65, v149
	v_add_f32_e32 v141, 1.0, v141
	v_rcp_f32_e32 v150, v141
	v_mul_f32_e32 v141, 0x3d372713, v67
	v_mul_f32_e32 v141, v67, v141
	v_fma_f32 v141, v67, v141, v67
	v_mul_f32_e32 v141, 0x3f4c422a, v141
	v_mul_f32_e32 v141, 0xc038aa3b, v141
	v_exp_f32_e32 v141, v141
	v_cvt_pk_bf16_f32 v148, v148, v149
	v_add_f32_e32 v141, 1.0, v141
	v_rcp_f32_e32 v151, v141
	v_mul_f32_e32 v141, 0x3d372713, v60
	v_mul_f32_e32 v141, v60, v141
	v_fma_f32 v141, v60, v141, v60
	v_mul_f32_e32 v141, 0x3f4c422a, v141
	v_mul_f32_e32 v141, 0xc038aa3b, v141
	v_exp_f32_e32 v141, v141
	v_mul_f32_e32 v150, v66, v150
	v_mul_f32_e32 v151, v67, v151
	v_add_f32_e32 v141, 1.0, v141
	v_cvt_pk_bf16_f32 v149, v150, v151
	global_store_dwordx4 v[144:145], v[146:149], off offset:256
	v_lshl_add_u64 v[144:145], v[142:143], 0, s[0:1]
	s_mov_b64 s[0:1], 0x12000
	v_rcp_f32_e32 v146, v141
	v_mul_f32_e32 v141, 0x3d372713, v61
	v_mul_f32_e32 v141, v61, v141
	v_fma_f32 v141, v61, v141, v61
	v_mul_f32_e32 v141, 0x3f4c422a, v141
	v_mul_f32_e32 v141, 0xc038aa3b, v141
	v_exp_f32_e32 v141, v141
	s_nop 0
	v_add_f32_e32 v141, 1.0, v141
	v_rcp_f32_e32 v147, v141
	v_mul_f32_e32 v141, 0x3d372713, v62
	v_mul_f32_e32 v141, v62, v141
	v_fma_f32 v141, v62, v141, v62
	v_mul_f32_e32 v141, 0x3f4c422a, v141
	v_mul_f32_e32 v141, 0xc038aa3b, v141
	v_exp_f32_e32 v141, v141
	v_mul_f32_e32 v146, v60, v146
	v_mul_f32_e32 v147, v61, v147
	v_add_f32_e32 v141, 1.0, v141
	v_rcp_f32_e32 v148, v141
	v_mul_f32_e32 v141, 0x3d372713, v63
	v_mul_f32_e32 v141, v63, v141
	v_fma_f32 v141, v63, v141, v63
; __device__ __forceinline__ unsigned cvt_pk_bf16(float lo, float hi) { const f32x2 v = {lo, hi}; const bf16x2_t b = __builtin_convertvector(v, bf16x2_t); return __builtin_bit_cast(unsigned, b); }
; __device__ __forceinline__ float gelu_tanh_f(float x) { const float u = 0.7978845608028654f * (x + 0.044715f * x * x * x); return x * fast_rcp(1.0f + fast_exp2(-2.0f * LOG2E * u)); }
;     __device__ __forceinline__ void operator()(const f32x4 (&acc)[2][2][4][2], const Unit& u, int wr, int wc, int fr, int fq) const {
;     ...
;                 for (int m = 0; m < 4; ++m) { bf16_t* rowp = dst + (size_t)(row0 + ai * HALF + m * 16) * 256 + col0;
; #pragma unroll
;                     for (int bj = 0; bj < 2; ++bj) { const f32x4 v0 = acc[ai][bj][m][0], v1 = acc[ai][bj][m][1]; u32x4 w;
;                         w.x = cvt_pk_bf16(gelu_tanh_f(v0[0]), gelu_tanh_f(v0[1])); w.y = cvt_pk_bf16(gelu_tanh_f(v0[2]), gelu_tanh_f(v0[3]));
;                         w.z = cvt_pk_bf16(gelu_tanh_f(v1[0]), gelu_tanh_f(v1[1])); w.w = cvt_pk_bf16(gelu_tanh_f(v1[2]), gelu_tanh_f(v1[3]));
;                         *(u32x4*)(rowp + bj * HALF) = w; } }
	v_mul_f32_e32 v141, 0x3f4c422a, v141
	v_mul_f32_e32 v141, 0xc038aa3b, v141
	v_exp_f32_e32 v141, v141
	v_cvt_pk_bf16_f32 v146, v146, v147
	v_add_f32_e32 v141, 1.0, v141
	v_rcp_f32_e32 v149, v141
	v_mul_f32_e32 v141, 0x3d372713, v56
	v_mul_f32_e32 v141, v56, v141
	v_fma_f32 v141, v56, v141, v56
	v_mul_f32_e32 v141, 0x3f4c422a, v141
	v_mul_f32_e32 v141, 0xc038aa3b, v141
	v_exp_f32_e32 v141, v141
	v_mul_f32_e32 v148, v62, v148
	v_mul_f32_e32 v149, v63, v149
	v_add_f32_e32 v141, 1.0, v141
	v_cvt_pk_bf16_f32 v147, v148, v149
	v_rcp_f32_e32 v148, v141
	v_mul_f32_e32 v141, 0x3d372713, v57
	v_mul_f32_e32 v141, v57, v141
	v_fma_f32 v141, v57, v141, v57
	v_mul_f32_e32 v141, 0x3f4c422a, v141
	v_mul_f32_e32 v141, 0xc038aa3b, v141
	v_exp_f32_e32 v141, v141
	s_nop 0
	v_add_f32_e32 v141, 1.0, v141
	v_rcp_f32_e32 v149, v141
	v_mul_f32_e32 v141, 0x3d372713, v58
	v_mul_f32_e32 v141, v58, v141
	v_fma_f32 v141, v58, v141, v58
	v_mul_f32_e32 v141, 0x3f4c422a, v141
	v_mul_f32_e32 v141, 0xc038aa3b, v141
	v_exp_f32_e32 v141, v141
	v_mul_f32_e32 v148, v56, v148
	v_mul_f32_e32 v149, v57, v149
	v_add_f32_e32 v141, 1.0, v141
	v_rcp_f32_e32 v150, v141
	v_mul_f32_e32 v141, 0x3d372713, v59
	v_mul_f32_e32 v141, v59, v141
	v_fma_f32 v141, v59, v141, v59
	v_mul_f32_e32 v141, 0x3f4c422a, v141
	v_mul_f32_e32 v141, 0xc038aa3b, v141
	v_exp_f32_e32 v141, v141
	v_cvt_pk_bf16_f32 v148, v148, v149
	v_add_f32_e32 v141, 1.0, v141
	v_rcp_f32_e32 v151, v141
	v_mul_f32_e32 v141, 0x3d372713, v44
	v_mul_f32_e32 v141, v44, v141
	v_fma_f32 v141, v44, v141, v44
	v_mul_f32_e32 v141, 0x3f4c422a, v141
	v_mul_f32_e32 v141, 0xc038aa3b, v141
	v_exp_f32_e32 v141, v141
	v_mul_f32_e32 v150, v58, v150
	v_mul_f32_e32 v151, v59, v151
	v_add_f32_e32 v141, 1.0, v141
	v_cvt_pk_bf16_f32 v149, v150, v151
	v_add_co_u32_e32 v150, vcc, s62, v142
	s_nop 1
	v_addc_co_u32_e32 v151, vcc, 0, v143, vcc
	global_store_dwordx4 v[150:151], v[146:149], off
	s_nop 1
	v_rcp_f32_e32 v146, v141
	v_mul_f32_e32 v141, 0x3d372713, v45
	v_mul_f32_e32 v141, v45, v141
	v_fma_f32 v141, v45, v141, v45
	v_mul_f32_e32 v141, 0x3f4c422a, v141
	v_mul_f32_e32 v141, 0xc038aa3b, v141
	v_exp_f32_e32 v141, v141
	s_nop 0
	v_add_f32_e32 v141, 1.0, v141
	v_rcp_f32_e32 v147, v141
	v_mul_f32_e32 v141, 0x3d372713, v46
	v_mul_f32_e32 v141, v46, v141
	v_fma_f32 v141, v46, v141, v46
	v_mul_f32_e32 v141, 0x3f4c422a, v141
	v_mul_f32_e32 v141, 0xc038aa3b, v141
	v_exp_f32_e32 v141, v141
	v_mul_f32_e32 v146, v44, v146
	v_mul_f32_e32 v147, v45, v147
	v_add_f32_e32 v141, 1.0, v141
	v_rcp_f32_e32 v148, v141
	v_mul_f32_e32 v141, 0x3d372713, v47
	v_mul_f32_e32 v141, v47, v141
	v_fma_f32 v141, v47, v141, v47
	v_mul_f32_e32 v141, 0x3f4c422a, v141
	v_mul_f32_e32 v141, 0xc038aa3b, v141
	v_exp_f32_e32 v141, v141
	v_cvt_pk_bf16_f32 v146, v146, v147
	v_add_f32_e32 v141, 1.0, v141
	v_rcp_f32_e32 v149, v141
	v_mul_f32_e32 v141, 0x3d372713, v40
	v_mul_f32_e32 v141, v40, v141
	v_fma_f32 v141, v40, v141, v40
	v_mul_f32_e32 v141, 0x3f4c422a, v141
	v_mul_f32_e32 v141, 0xc038aa3b, v141
	v_exp_f32_e32 v141, v141
	v_mul_f32_e32 v148, v46, v148
	v_mul_f32_e32 v149, v47, v149
	v_add_f32_e32 v141, 1.0, v141
	v_cvt_pk_bf16_f32 v147, v148, v149
	v_rcp_f32_e32 v148, v141
	v_mul_f32_e32 v141, 0x3d372713, v41
	v_mul_f32_e32 v141, v41, v141
	v_fma_f32 v141, v41, v141, v41
	v_mul_f32_e32 v141, 0x3f4c422a, v141
	v_mul_f32_e32 v141, 0xc038aa3b, v141
	v_exp_f32_e32 v141, v141
	s_nop 0
	v_add_f32_e32 v141, 1.0, v141
	v_rcp_f32_e32 v149, v141
	v_mul_f32_e32 v141, 0x3d372713, v42
	v_mul_f32_e32 v141, v42, v141
	v_fma_f32 v141, v42, v141, v42
	v_mul_f32_e32 v141, 0x3f4c422a, v141
	v_mul_f32_e32 v141, 0xc038aa3b, v141
	v_exp_f32_e32 v141, v141
	v_mul_f32_e32 v148, v40, v148
	v_mul_f32_e32 v149, v41, v149
	v_add_f32_e32 v141, 1.0, v141
	v_rcp_f32_e32 v150, v141
	v_mul_f32_e32 v141, 0x3d372713, v43
	v_mul_f32_e32 v141, v43, v141
	v_fma_f32 v141, v43, v141, v43
	v_mul_f32_e32 v141, 0x3f4c422a, v141
	v_mul_f32_e32 v141, 0xc038aa3b, v141
	v_exp_f32_e32 v141, v141
	v_cvt_pk_bf16_f32 v148, v148, v149
	v_add_f32_e32 v141, 1.0, v141
	v_rcp_f32_e32 v151, v141
	v_mul_f32_e32 v141, 0x3d372713, v52
	v_mul_f32_e32 v141, v52, v141
	v_fma_f32 v141, v52, v141, v52
	v_mul_f32_e32 v141, 0x3f4c422a, v141
	v_mul_f32_e32 v141, 0xc038aa3b, v141
	v_exp_f32_e32 v141, v141
	v_mul_f32_e32 v150, v42, v150
	v_mul_f32_e32 v151, v43, v151
	v_add_f32_e32 v141, 1.0, v141
	v_cvt_pk_bf16_f32 v149, v150, v151
	global_store_dwordx4 v[144:145], v[146:149], off offset:256
	v_lshl_add_u64 v[144:145], v[142:143], 0, s[0:1]
	s_mov_b32 s0, 0x12000
	v_rcp_f32_e32 v146, v141
	v_mul_f32_e32 v141, 0x3d372713, v53
	v_mul_f32_e32 v141, v53, v141
	v_fma_f32 v141, v53, v141, v53
	v_mul_f32_e32 v141, 0x3f4c422a, v141
	v_mul_f32_e32 v141, 0xc038aa3b, v141
	v_exp_f32_e32 v141, v141
	s_nop 0
	v_add_f32_e32 v141, 1.0, v141
	v_rcp_f32_e32 v147, v141
	v_mul_f32_e32 v141, 0x3d372713, v54
	v_mul_f32_e32 v141, v54, v141
	v_fma_f32 v141, v54, v141, v54
	v_mul_f32_e32 v141, 0x3f4c422a, v141
	v_mul_f32_e32 v141, 0xc038aa3b, v141
	v_exp_f32_e32 v141, v141
	v_mul_f32_e32 v146, v52, v146
	v_mul_f32_e32 v147, v53, v147
	v_add_f32_e32 v141, 1.0, v141
	v_rcp_f32_e32 v148, v141
	v_mul_f32_e32 v141, 0x3d372713, v55
	v_mul_f32_e32 v141, v55, v141
	v_fma_f32 v141, v55, v141, v55
	v_mul_f32_e32 v141, 0x3f4c422a, v141
	v_mul_f32_e32 v141, 0xc038aa3b, v141
	v_exp_f32_e32 v141, v141
	v_cvt_pk_bf16_f32 v146, v146, v147
	v_add_f32_e32 v141, 1.0, v141
	v_rcp_f32_e32 v149, v141
	v_mul_f32_e32 v141, 0x3d372713, v48
	v_mul_f32_e32 v141, v48, v141
	v_fma_f32 v141, v48, v141, v48
	v_mul_f32_e32 v141, 0x3f4c422a, v141
	v_mul_f32_e32 v141, 0xc038aa3b, v141
	v_exp_f32_e32 v141, v141
; __device__ __forceinline__ unsigned cvt_pk_bf16(float lo, float hi) { const f32x2 v = {lo, hi}; const bf16x2_t b = __builtin_convertvector(v, bf16x2_t); return __builtin_bit_cast(unsigned, b); }
; __device__ __forceinline__ float gelu_tanh_f(float x) { const float u = 0.7978845608028654f * (x + 0.044715f * x * x * x); return x * fast_rcp(1.0f + fast_exp2(-2.0f * LOG2E * u)); }
;     __device__ __forceinline__ void operator()(const f32x4 (&acc)[2][2][4][2], const Unit& u, int wr, int wc, int fr, int fq) const {
;     ...
;                 for (int m = 0; m < 4; ++m) { bf16_t* rowp = dst + (size_t)(row0 + ai * HALF + m * 16) * 256 + col0;
; #pragma unroll
;                     for (int bj = 0; bj < 2; ++bj) { const f32x4 v0 = acc[ai][bj][m][0], v1 = acc[ai][bj][m][1]; u32x4 w;
;                         w.x = cvt_pk_bf16(gelu_tanh_f(v0[0]), gelu_tanh_f(v0[1])); w.y = cvt_pk_bf16(gelu_tanh_f(v0[2]), gelu_tanh_f(v0[3]));
;                         w.z = cvt_pk_bf16(gelu_tanh_f(v1[0]), gelu_tanh_f(v1[1])); w.w = cvt_pk_bf16(gelu_tanh_f(v1[2]), gelu_tanh_f(v1[3]));
;                         *(u32x4*)(rowp + bj * HALF) = w; } }
	v_mul_f32_e32 v148, v54, v148
	v_mul_f32_e32 v149, v55, v149
	v_add_f32_e32 v141, 1.0, v141
	v_cvt_pk_bf16_f32 v147, v148, v149
	v_rcp_f32_e32 v148, v141
	v_mul_f32_e32 v141, 0x3d372713, v49
	v_mul_f32_e32 v141, v49, v141
	v_fma_f32 v141, v49, v141, v49
	v_mul_f32_e32 v141, 0x3f4c422a, v141
	v_mul_f32_e32 v141, 0xc038aa3b, v141
	v_exp_f32_e32 v141, v141
	s_nop 0
	v_add_f32_e32 v141, 1.0, v141
	v_rcp_f32_e32 v149, v141
	v_mul_f32_e32 v141, 0x3d372713, v50
	v_mul_f32_e32 v141, v50, v141
	v_fma_f32 v141, v50, v141, v50
	v_mul_f32_e32 v141, 0x3f4c422a, v141
	v_mul_f32_e32 v141, 0xc038aa3b, v141
	v_exp_f32_e32 v141, v141
	v_mul_f32_e32 v148, v48, v148
	v_mul_f32_e32 v149, v49, v149
	v_add_f32_e32 v141, 1.0, v141
	v_rcp_f32_e32 v150, v141
	v_mul_f32_e32 v141, 0x3d372713, v51
	v_mul_f32_e32 v141, v51, v141
	v_fma_f32 v141, v51, v141, v51
	v_mul_f32_e32 v141, 0x3f4c422a, v141
	v_mul_f32_e32 v141, 0xc038aa3b, v141
	v_exp_f32_e32 v141, v141
	v_cvt_pk_bf16_f32 v148, v148, v149
	v_add_f32_e32 v141, 1.0, v141
	v_rcp_f32_e32 v151, v141
	v_mul_f32_e32 v141, 0x3d372713, v28
	v_mul_f32_e32 v141, v28, v141
	v_fma_f32 v141, v28, v141, v28
	v_mul_f32_e32 v141, 0x3f4c422a, v141
	v_mul_f32_e32 v141, 0xc038aa3b, v141
	v_exp_f32_e32 v141, v141
	v_mul_f32_e32 v150, v50, v150
	v_mul_f32_e32 v151, v51, v151
	v_add_f32_e32 v141, 1.0, v141
	v_cvt_pk_bf16_f32 v149, v150, v151
	v_add_co_u32_e32 v150, vcc, s0, v142
	s_mov_b64 s[0:1], 0x14000
	s_nop 0
	v_addc_co_u32_e32 v151, vcc, 0, v143, vcc
	global_store_dwordx4 v[150:151], v[146:149], off
	s_nop 1
	v_rcp_f32_e32 v146, v141
	v_mul_f32_e32 v141, 0x3d372713, v29
	v_mul_f32_e32 v141, v29, v141
	v_fma_f32 v141, v29, v141, v29
	v_mul_f32_e32 v141, 0x3f4c422a, v141
	v_mul_f32_e32 v141, 0xc038aa3b, v141
	v_exp_f32_e32 v141, v141
	s_nop 0
	v_add_f32_e32 v141, 1.0, v141
	v_rcp_f32_e32 v147, v141
	v_mul_f32_e32 v141, 0x3d372713, v30
	v_mul_f32_e32 v141, v30, v141
	v_fma_f32 v141, v30, v141, v30
	v_mul_f32_e32 v141, 0x3f4c422a, v141
	v_mul_f32_e32 v141, 0xc038aa3b, v141
	v_exp_f32_e32 v141, v141
	v_mul_f32_e32 v146, v28, v146
	v_mul_f32_e32 v147, v29, v147
	v_add_f32_e32 v141, 1.0, v141
	v_rcp_f32_e32 v148, v141
	v_mul_f32_e32 v141, 0x3d372713, v31
	v_mul_f32_e32 v141, v31, v141
	v_fma_f32 v141, v31, v141, v31
	v_mul_f32_e32 v141, 0x3f4c422a, v141
	v_mul_f32_e32 v141, 0xc038aa3b, v141
	v_exp_f32_e32 v141, v141
	v_cvt_pk_bf16_f32 v146, v146, v147
	v_add_f32_e32 v141, 1.0, v141
	v_rcp_f32_e32 v149, v141
	v_mul_f32_e32 v141, 0x3d372713, v24
	v_mul_f32_e32 v141, v24, v141
	v_fma_f32 v141, v24, v141, v24
	v_mul_f32_e32 v141, 0x3f4c422a, v141
	v_mul_f32_e32 v141, 0xc038aa3b, v141
	v_exp_f32_e32 v141, v141
	v_mul_f32_e32 v148, v30, v148
	v_mul_f32_e32 v149, v31, v149
	v_add_f32_e32 v141, 1.0, v141
	v_cvt_pk_bf16_f32 v147, v148, v149
	v_rcp_f32_e32 v148, v141
	v_mul_f32_e32 v141, 0x3d372713, v25
	v_mul_f32_e32 v141, v25, v141
	v_fma_f32 v141, v25, v141, v25
	v_mul_f32_e32 v141, 0x3f4c422a, v141
	v_mul_f32_e32 v141, 0xc038aa3b, v141
	v_exp_f32_e32 v141, v141
	s_nop 0
	v_add_f32_e32 v141, 1.0, v141
	v_rcp_f32_e32 v149, v141
	v_mul_f32_e32 v141, 0x3d372713, v26
	v_mul_f32_e32 v141, v26, v141
	v_fma_f32 v141, v26, v141, v26
	v_mul_f32_e32 v141, 0x3f4c422a, v141
	v_mul_f32_e32 v141, 0xc038aa3b, v141
	v_exp_f32_e32 v141, v141
	v_mul_f32_e32 v148, v24, v148
	v_mul_f32_e32 v149, v25, v149
	v_add_f32_e32 v141, 1.0, v141
	v_rcp_f32_e32 v150, v141
	v_mul_f32_e32 v141, 0x3d372713, v27
	v_mul_f32_e32 v141, v27, v141
	v_fma_f32 v141, v27, v141, v27
	v_mul_f32_e32 v141, 0x3f4c422a, v141
	v_mul_f32_e32 v141, 0xc038aa3b, v141
	v_exp_f32_e32 v141, v141
	v_cvt_pk_bf16_f32 v148, v148, v149
	v_add_f32_e32 v141, 1.0, v141
	v_rcp_f32_e32 v151, v141
	v_mul_f32_e32 v141, 0x3d372713, v36
	v_mul_f32_e32 v141, v36, v141
	v_fma_f32 v141, v36, v141, v36
	v_mul_f32_e32 v141, 0x3f4c422a, v141
	v_mul_f32_e32 v141, 0xc038aa3b, v141
	v_exp_f32_e32 v141, v141
	v_mul_f32_e32 v150, v26, v150
	v_mul_f32_e32 v151, v27, v151
	v_add_f32_e32 v141, 1.0, v141
	v_cvt_pk_bf16_f32 v149, v150, v151
	global_store_dwordx4 v[144:145], v[146:149], off offset:256
	v_lshl_add_u64 v[144:145], v[142:143], 0, s[0:1]
	s_mov_b32 s0, 0x14000
	v_rcp_f32_e32 v146, v141
	v_mul_f32_e32 v141, 0x3d372713, v37
	v_mul_f32_e32 v141, v37, v141
	v_fma_f32 v141, v37, v141, v37
	v_mul_f32_e32 v141, 0x3f4c422a, v141
	v_mul_f32_e32 v141, 0xc038aa3b, v141
	v_exp_f32_e32 v141, v141
	s_nop 0
	v_add_f32_e32 v141, 1.0, v141
	v_rcp_f32_e32 v147, v141
	v_mul_f32_e32 v141, 0x3d372713, v38
	v_mul_f32_e32 v141, v38, v141
	v_fma_f32 v141, v38, v141, v38
	v_mul_f32_e32 v141, 0x3f4c422a, v141
	v_mul_f32_e32 v141, 0xc038aa3b, v141
	v_exp_f32_e32 v141, v141
	v_mul_f32_e32 v146, v36, v146
	v_mul_f32_e32 v147, v37, v147
	v_add_f32_e32 v141, 1.0, v141
	v_rcp_f32_e32 v148, v141
	v_mul_f32_e32 v141, 0x3d372713, v39
	v_mul_f32_e32 v141, v39, v141
	v_fma_f32 v141, v39, v141, v39
	v_mul_f32_e32 v141, 0x3f4c422a, v141
	v_mul_f32_e32 v141, 0xc038aa3b, v141
	v_exp_f32_e32 v141, v141
	v_cvt_pk_bf16_f32 v146, v146, v147
	v_add_f32_e32 v141, 1.0, v141
	v_rcp_f32_e32 v149, v141
	v_mul_f32_e32 v141, 0x3d372713, v32
	v_mul_f32_e32 v141, v32, v141
	v_fma_f32 v141, v32, v141, v32
	v_mul_f32_e32 v141, 0x3f4c422a, v141
	v_mul_f32_e32 v141, 0xc038aa3b, v141
	v_exp_f32_e32 v141, v141
	v_mul_f32_e32 v148, v38, v148
	v_mul_f32_e32 v149, v39, v149
	v_add_f32_e32 v141, 1.0, v141
	v_cvt_pk_bf16_f32 v147, v148, v149
	v_rcp_f32_e32 v148, v141
	v_mul_f32_e32 v141, 0x3d372713, v33
	v_mul_f32_e32 v141, v33, v141
	v_fma_f32 v141, v33, v141, v33
	v_mul_f32_e32 v141, 0x3f4c422a, v141
	v_mul_f32_e32 v141, 0xc038aa3b, v141
	v_exp_f32_e32 v141, v141
	s_nop 0
; __device__ __forceinline__ unsigned cvt_pk_bf16(float lo, float hi) { const f32x2 v = {lo, hi}; const bf16x2_t b = __builtin_convertvector(v, bf16x2_t); return __builtin_bit_cast(unsigned, b); }
; __device__ __forceinline__ float gelu_tanh_f(float x) { const float u = 0.7978845608028654f * (x + 0.044715f * x * x * x); return x * fast_rcp(1.0f + fast_exp2(-2.0f * LOG2E * u)); }
;     __device__ __forceinline__ void operator()(const f32x4 (&acc)[2][2][4][2], const Unit& u, int wr, int wc, int fr, int fq) const {
;     ...
;                 for (int m = 0; m < 4; ++m) { bf16_t* rowp = dst + (size_t)(row0 + ai * HALF + m * 16) * 256 + col0;
; #pragma unroll
;                     for (int bj = 0; bj < 2; ++bj) { const f32x4 v0 = acc[ai][bj][m][0], v1 = acc[ai][bj][m][1]; u32x4 w;
;                         w.x = cvt_pk_bf16(gelu_tanh_f(v0[0]), gelu_tanh_f(v0[1])); w.y = cvt_pk_bf16(gelu_tanh_f(v0[2]), gelu_tanh_f(v0[3]));
;                         w.z = cvt_pk_bf16(gelu_tanh_f(v1[0]), gelu_tanh_f(v1[1])); w.w = cvt_pk_bf16(gelu_tanh_f(v1[2]), gelu_tanh_f(v1[3]));
;                         *(u32x4*)(rowp + bj * HALF) = w; } }
	v_add_f32_e32 v141, 1.0, v141
	v_rcp_f32_e32 v149, v141
	v_mul_f32_e32 v141, 0x3d372713, v34
	v_mul_f32_e32 v141, v34, v141
	v_fma_f32 v141, v34, v141, v34
	v_mul_f32_e32 v141, 0x3f4c422a, v141
	v_mul_f32_e32 v141, 0xc038aa3b, v141
	v_exp_f32_e32 v141, v141
	v_mul_f32_e32 v148, v32, v148
	v_mul_f32_e32 v149, v33, v149
	v_add_f32_e32 v141, 1.0, v141
	v_rcp_f32_e32 v150, v141
	v_mul_f32_e32 v141, 0x3d372713, v35
	v_mul_f32_e32 v141, v35, v141
	v_fma_f32 v141, v35, v141, v35
	v_mul_f32_e32 v141, 0x3f4c422a, v141
	v_mul_f32_e32 v141, 0xc038aa3b, v141
	v_exp_f32_e32 v141, v141
	v_cvt_pk_bf16_f32 v148, v148, v149
	v_add_f32_e32 v141, 1.0, v141
	v_rcp_f32_e32 v151, v141
	v_mul_f32_e32 v141, 0x3d372713, v12
	v_mul_f32_e32 v141, v12, v141
	v_fma_f32 v141, v12, v141, v12
	v_mul_f32_e32 v141, 0x3f4c422a, v141
	v_mul_f32_e32 v141, 0xc038aa3b, v141
	v_exp_f32_e32 v141, v141
	v_mul_f32_e32 v150, v34, v150
	v_mul_f32_e32 v151, v35, v151
	v_add_f32_e32 v141, 1.0, v141
	v_cvt_pk_bf16_f32 v149, v150, v151
	v_add_co_u32_e32 v150, vcc, s0, v142
	s_mov_b64 s[0:1], 0x16000
	s_nop 0
	v_addc_co_u32_e32 v151, vcc, 0, v143, vcc
	global_store_dwordx4 v[150:151], v[146:149], off
	s_nop 1
	v_rcp_f32_e32 v146, v141
	v_mul_f32_e32 v141, 0x3d372713, v13
	v_mul_f32_e32 v141, v13, v141
	v_fma_f32 v141, v13, v141, v13
	v_mul_f32_e32 v141, 0x3f4c422a, v141
	v_mul_f32_e32 v141, 0xc038aa3b, v141
	v_exp_f32_e32 v141, v141
	s_nop 0
	v_add_f32_e32 v141, 1.0, v141
	v_rcp_f32_e32 v147, v141
	v_mul_f32_e32 v141, 0x3d372713, v14
	v_mul_f32_e32 v141, v14, v141
	v_fma_f32 v141, v14, v141, v14
	v_mul_f32_e32 v141, 0x3f4c422a, v141
	v_mul_f32_e32 v141, 0xc038aa3b, v141
	v_exp_f32_e32 v141, v141
	v_mul_f32_e32 v146, v12, v146
	v_mul_f32_e32 v147, v13, v147
	v_add_f32_e32 v141, 1.0, v141
	v_rcp_f32_e32 v148, v141
	v_mul_f32_e32 v141, 0x3d372713, v15
	v_mul_f32_e32 v141, v15, v141
	v_fma_f32 v141, v15, v141, v15
	v_mul_f32_e32 v141, 0x3f4c422a, v141
	v_mul_f32_e32 v141, 0xc038aa3b, v141
	v_exp_f32_e32 v141, v141
	v_cvt_pk_bf16_f32 v146, v146, v147
	v_add_f32_e32 v141, 1.0, v141
	v_rcp_f32_e32 v149, v141
	v_mul_f32_e32 v141, 0x3d372713, v8
	v_mul_f32_e32 v141, v8, v141
	v_fma_f32 v141, v8, v141, v8
	v_mul_f32_e32 v141, 0x3f4c422a, v141
	v_mul_f32_e32 v141, 0xc038aa3b, v141
	v_exp_f32_e32 v141, v141
	v_mul_f32_e32 v148, v14, v148
	v_mul_f32_e32 v149, v15, v149
	v_add_f32_e32 v141, 1.0, v141
	v_cvt_pk_bf16_f32 v147, v148, v149
	v_rcp_f32_e32 v148, v141
	v_mul_f32_e32 v141, 0x3d372713, v9
	v_mul_f32_e32 v141, v9, v141
	v_fma_f32 v141, v9, v141, v9
	v_mul_f32_e32 v141, 0x3f4c422a, v141
	v_mul_f32_e32 v141, 0xc038aa3b, v141
	v_exp_f32_e32 v141, v141
	s_nop 0
	v_add_f32_e32 v141, 1.0, v141
	v_rcp_f32_e32 v149, v141
	v_mul_f32_e32 v141, 0x3d372713, v10
	v_mul_f32_e32 v141, v10, v141
	v_fma_f32 v141, v10, v141, v10
	v_mul_f32_e32 v141, 0x3f4c422a, v141
	v_mul_f32_e32 v141, 0xc038aa3b, v141
	v_exp_f32_e32 v141, v141
	v_mul_f32_e32 v148, v8, v148
	v_mul_f32_e32 v149, v9, v149
	v_add_f32_e32 v141, 1.0, v141
	v_rcp_f32_e32 v150, v141
	v_mul_f32_e32 v141, 0x3d372713, v11
	v_mul_f32_e32 v141, v11, v141
	v_fma_f32 v141, v11, v141, v11
	v_mul_f32_e32 v141, 0x3f4c422a, v141
	v_mul_f32_e32 v141, 0xc038aa3b, v141
	v_exp_f32_e32 v141, v141
	v_cvt_pk_bf16_f32 v148, v148, v149
	v_add_f32_e32 v141, 1.0, v141
	v_rcp_f32_e32 v151, v141
	v_mul_f32_e32 v141, 0x3d372713, v20
	v_mul_f32_e32 v141, v20, v141
	v_fma_f32 v141, v20, v141, v20
	v_mul_f32_e32 v141, 0x3f4c422a, v141
	v_mul_f32_e32 v141, 0xc038aa3b, v141
	v_exp_f32_e32 v141, v141
	v_mul_f32_e32 v150, v10, v150
	v_mul_f32_e32 v151, v11, v151
	v_add_f32_e32 v141, 1.0, v141
	v_cvt_pk_bf16_f32 v149, v150, v151
	global_store_dwordx4 v[144:145], v[146:149], off offset:256
	v_lshl_add_u64 v[144:145], v[142:143], 0, s[0:1]
	s_mov_b32 s0, 0x16000
	v_rcp_f32_e32 v146, v141
	v_mul_f32_e32 v141, 0x3d372713, v21
	v_mul_f32_e32 v141, v21, v141
	v_fma_f32 v141, v21, v141, v21
	v_mul_f32_e32 v141, 0x3f4c422a, v141
	v_mul_f32_e32 v141, 0xc038aa3b, v141
	v_exp_f32_e32 v141, v141
	v_add_co_u32_e32 v142, vcc, s0, v142
	v_add_f32_e32 v141, 1.0, v141
	v_rcp_f32_e32 v147, v141
	v_mul_f32_e32 v141, 0x3d372713, v22
	v_mul_f32_e32 v141, v22, v141
	v_fma_f32 v141, v22, v141, v22
	v_mul_f32_e32 v141, 0x3f4c422a, v141
	v_mul_f32_e32 v141, 0xc038aa3b, v141
	v_exp_f32_e32 v141, v141
	v_mul_f32_e32 v146, v20, v146
; __device__ __forceinline__ unsigned cvt_pk_bf16(float lo, float hi) { const f32x2 v = {lo, hi}; const bf16x2_t b = __builtin_convertvector(v, bf16x2_t); return __builtin_bit_cast(unsigned, b); }
; __device__ __forceinline__ float gelu_tanh_f(float x) { const float u = 0.7978845608028654f * (x + 0.044715f * x * x * x); return x * fast_rcp(1.0f + fast_exp2(-2.0f * LOG2E * u)); }
;     __device__ __forceinline__ void operator()(const f32x4 (&acc)[2][2][4][2], const Unit& u, int wr, int wc, int fr, int fq) const {
;     ...
;                 for (int m = 0; m < 4; ++m) { bf16_t* rowp = dst + (size_t)(row0 + ai * HALF + m * 16) * 256 + col0;
; #pragma unroll
;                     for (int bj = 0; bj < 2; ++bj) { const f32x4 v0 = acc[ai][bj][m][0], v1 = acc[ai][bj][m][1]; u32x4 w;
;                         w.x = cvt_pk_bf16(gelu_tanh_f(v0[0]), gelu_tanh_f(v0[1])); w.y = cvt_pk_bf16(gelu_tanh_f(v0[2]), gelu_tanh_f(v0[3]));
;                         w.z = cvt_pk_bf16(gelu_tanh_f(v1[0]), gelu_tanh_f(v1[1])); w.w = cvt_pk_bf16(gelu_tanh_f(v1[2]), gelu_tanh_f(v1[3]));
;                         *(u32x4*)(rowp + bj * HALF) = w; } }
	v_mul_f32_e32 v147, v21, v147
	v_addc_co_u32_e32 v143, vcc, 0, v143, vcc
	v_add_f32_e32 v141, 1.0, v141
	v_rcp_f32_e32 v148, v141
	v_mul_f32_e32 v141, 0x3d372713, v23
	v_mul_f32_e32 v141, v23, v141
	v_fma_f32 v141, v23, v141, v23
	v_mul_f32_e32 v141, 0x3f4c422a, v141
	v_mul_f32_e32 v141, 0xc038aa3b, v141
	v_exp_f32_e32 v141, v141
	v_cvt_pk_bf16_f32 v146, v146, v147
	v_add_f32_e32 v141, 1.0, v141
	v_rcp_f32_e32 v149, v141
	v_mul_f32_e32 v141, 0x3d372713, v16
	v_mul_f32_e32 v141, v16, v141
	v_fma_f32 v141, v16, v141, v16
	v_mul_f32_e32 v141, 0x3f4c422a, v141
	v_mul_f32_e32 v141, 0xc038aa3b, v141
	v_exp_f32_e32 v141, v141
	v_mul_f32_e32 v148, v22, v148
	v_mul_f32_e32 v149, v23, v149
	v_add_f32_e32 v141, 1.0, v141
	v_cvt_pk_bf16_f32 v147, v148, v149
	v_rcp_f32_e32 v148, v141
	v_mul_f32_e32 v141, 0x3d372713, v17
	v_mul_f32_e32 v141, v17, v141
	v_fma_f32 v141, v17, v141, v17
	v_mul_f32_e32 v141, 0x3f4c422a, v141
	v_mul_f32_e32 v141, 0xc038aa3b, v141
	v_exp_f32_e32 v141, v141
	s_nop 0
	v_add_f32_e32 v141, 1.0, v141
	v_rcp_f32_e32 v149, v141
	v_mul_f32_e32 v141, 0x3d372713, v18
	v_mul_f32_e32 v141, v18, v141
	v_fma_f32 v141, v18, v141, v18
	v_mul_f32_e32 v141, 0x3f4c422a, v141
	v_mul_f32_e32 v141, 0xc038aa3b, v141
	v_exp_f32_e32 v141, v141
	v_mul_f32_e32 v148, v16, v148
	v_mul_f32_e32 v149, v17, v149
	v_add_f32_e32 v141, 1.0, v141
	v_rcp_f32_e32 v150, v141
	v_mul_f32_e32 v141, 0x3d372713, v19
	v_mul_f32_e32 v141, v19, v141
	v_fma_f32 v141, v19, v141, v19
	v_mul_f32_e32 v141, 0x3f4c422a, v141
	v_mul_f32_e32 v141, 0xc038aa3b, v141
	v_exp_f32_e32 v141, v141
	v_cvt_pk_bf16_f32 v148, v148, v149
	v_add_f32_e32 v141, 1.0, v141
	v_rcp_f32_e32 v151, v141
	v_mul_f32_e32 v141, 0x3d372713, v4
	v_mul_f32_e32 v141, v4, v141
	v_fma_f32 v141, v4, v141, v4
	v_mul_f32_e32 v141, 0x3f4c422a, v141
	v_mul_f32_e32 v141, 0xc038aa3b, v141
	v_exp_f32_e32 v141, v141
	v_mul_f32_e32 v150, v18, v150
	v_mul_f32_e32 v151, v19, v151
	v_add_f32_e32 v141, 1.0, v141
	v_cvt_pk_bf16_f32 v149, v150, v151
	global_store_dwordx4 v[142:143], v[146:149], off
	v_rcp_f32_e32 v142, v141
	v_mul_f32_e32 v141, 0x3d372713, v5
	v_mul_f32_e32 v141, v5, v141
	v_fma_f32 v141, v5, v141, v5
	v_mul_f32_e32 v141, 0x3f4c422a, v141
	v_mul_f32_e32 v141, 0xc038aa3b, v141
	v_exp_f32_e32 v141, v141
	s_nop 0
	v_add_f32_e32 v141, 1.0, v141
	v_rcp_f32_e32 v143, v141
	v_mul_f32_e32 v141, 0x3d372713, v6
	v_mul_f32_e32 v141, v6, v141
	v_fma_f32 v141, v6, v141, v6
	v_mul_f32_e32 v141, 0x3f4c422a, v141
	v_mul_f32_e32 v141, 0xc038aa3b, v141
	v_exp_f32_e32 v141, v141
	v_mul_f32_e32 v142, v4, v142
	v_mul_f32_e32 v143, v5, v143
	v_add_f32_e32 v141, 1.0, v141
	v_cvt_pk_bf16_f32 v146, v142, v143
	v_rcp_f32_e32 v142, v141
	v_mul_f32_e32 v141, 0x3d372713, v7
	v_mul_f32_e32 v141, v7, v141
	v_fma_f32 v141, v7, v141, v7
	v_mul_f32_e32 v141, 0x3f4c422a, v141
	v_mul_f32_e32 v141, 0xc038aa3b, v141
	v_exp_f32_e32 v141, v141
	s_nop 0
	v_add_f32_e32 v141, 1.0, v141
	v_rcp_f32_e32 v143, v141
	v_mul_f32_e32 v141, 0x3d372713, v0
	v_mul_f32_e32 v141, v0, v141
	v_fma_f32 v141, v0, v141, v0
	v_mul_f32_e32 v141, 0x3f4c422a, v141
	v_mul_f32_e32 v141, 0xc038aa3b, v141
	v_exp_f32_e32 v141, v141
	v_mul_f32_e32 v142, v6, v142
	v_mul_f32_e32 v143, v7, v143
	v_add_f32_e32 v141, 1.0, v141
	v_cvt_pk_bf16_f32 v147, v142, v143
	v_rcp_f32_e32 v142, v141
	v_mul_f32_e32 v141, 0x3d372713, v1
	v_mul_f32_e32 v141, v1, v141
	v_fma_f32 v141, v1, v141, v1
	v_mul_f32_e32 v141, 0x3f4c422a, v141
	v_mul_f32_e32 v141, 0xc038aa3b, v141
	v_exp_f32_e32 v141, v141
	s_nop 0
	v_add_f32_e32 v141, 1.0, v141
	v_rcp_f32_e32 v143, v141
	v_mul_f32_e32 v141, 0x3d372713, v2
	v_mul_f32_e32 v141, v2, v141
	v_fma_f32 v141, v2, v141, v2
	v_mul_f32_e32 v141, 0x3f4c422a, v141
	v_mul_f32_e32 v141, 0xc038aa3b, v141
	v_exp_f32_e32 v141, v141
	v_mul_f32_e32 v142, v0, v142
	v_mul_f32_e32 v143, v1, v143
	v_add_f32_e32 v141, 1.0, v141
	v_cvt_pk_bf16_f32 v148, v142, v143
	v_rcp_f32_e32 v142, v141
	v_mul_f32_e32 v141, 0x3d372713, v3
	v_mul_f32_e32 v141, v3, v141
	v_fma_f32 v141, v3, v141, v3
	v_mul_f32_e32 v141, 0x3f4c422a, v141
	v_mul_f32_e32 v141, 0xc038aa3b, v141
	v_exp_f32_e32 v141, v141
	s_nop 0
	v_add_f32_e32 v141, 1.0, v141
	v_rcp_f32_e32 v143, v141
	s_nop 0
	v_mul_f32_e32 v142, v2, v142
	v_mul_f32_e32 v143, v3, v143
	s_nop 0
	v_cvt_pk_bf16_f32 v149, v142, v143
	global_store_dwordx4 v[144:145], v[146:149], off offset:256

;     __device__ __forceinline__ void operator()(const f32x4 (&acc)[2][2][4][2], const Unit& u, int wr, int wc, int fr, int fq) const {
;     ...
;             const int slot = u.pn * 4 + wc; const bool isq = slot < 6;
;             const float* g = isq ? gq : gk;
;             bf16_t* dst = isq ? (bf16_t*)(mx + MX_QA) + (size_t)slot * R * 64 : (bf16_t*)(mx + MX_KA) + (size_t)(slot - 6) * R * 64;
;             float fr0[2], fr1[2];
; #pragma unroll
;             for (int n = 0; n < 2; ++n) { const float p = (float)(4 * fq + 2 * n);
;                 fr0[n] = fast_exp2(-p * (13.287712379549449f / 16.0f)) * 0.15915494309189535f; fr1[n] = fast_exp2(-(p + 1.0f) * (13.287712379549449f / 16.0f)) * 0.15915494309189535f; }
; #pragma unroll
;             for (int ai = 0; ai < 2; ++ai)
; #pragma unroll
;                 for (int m = 0; m < 4; ++m) {
;                     const int row = row0 + ai * HALF + m * 16;
;                     int fqo = fq; asm volatile("" : "+v"(fqo));
;                     f32x4 v[2][2]; float ss = 0.f;
; #pragma unroll
;                     for (int bj = 0; bj < 2; ++bj)
; #pragma unroll
;                         for (int n = 0; n < 2; ++n) { v[bj][n] = acc[ai][bj][m][n]; ss += (v[bj][n][0] * v[bj][n][0] + v[bj][n][1] * v[bj][n][1]) + (v[bj][n][2] * v[bj][n][2] + v[bj][n][3] * v[bj][n][3]); }
;                     ss += swz_xor<16>(ss); ss = xadd32(ss);
;                     const float rstd = __builtin_amdgcn_rsqf(ss * (1.0f / 64.0f) + EPS);
;                     const int t = row & (SEQ - 1); const float pos[2] = {(float)(t >> 6), (float)(t & 63)};
; #pragma unroll
;                     for (int bj = 0; bj < 2; ++bj) {
;                         u32x4 w;
; #pragma unroll
;                         for (int n = 0; n < 2; ++n) {
;                             f32x4 x = v[bj][n] * rstd * *(const f32x4*)(g + 32 * bj + 8 * fqo + 4 * n);
;                             if (latent) {
;                                 const float a0 = pos[bj] * fr0[n], a1 = pos[bj] * fr1[n];
;                                 const float c0 = __builtin_amdgcn_cosf(a0), s0 = __builtin_amdgcn_sinf(a0), c1 = __builtin_amdgcn_cosf(a1), s1 = __builtin_amdgcn_sinf(a1);
;                                 x = (f32x4){x[0] * c0 - x[1] * s0, x[1] * c0 + x[0] * s0, x[2] * c1 - x[3] * s1, x[3] * c1 + x[2] * s1};
;                             }
.LBB0_452:
	s_andn2_b64 vcc, exec, s[0:1]
	s_cbranch_vccnz .LBB0_518
	v_lshlrev_b32_e32 v141, 2, v236
	v_cvt_f32_i32_e32 v142, v141
	v_mul_f32_e32 v144, v124, v124
	v_mul_f32_e32 v145, v125, v125
	s_lshl_b32 s0, s42, 2
	s_or_b32 s15, s0, s76
	v_mul_f32_e32 v143, 0xbf549a78, v142
	v_add_f32_e32 v142, 1.0, v142
	v_mul_f32_e32 v142, 0xbf549a78, v142
	v_exp_f32_e32 v143, v143
	v_exp_f32_e32 v142, v142
	s_cmp_lt_i32 s15, 6
	s_cselect_b64 s[0:1], -1, 0
	v_mul_f32_e32 v194, 0.15915494, v143
	v_mul_f32_e32 v237, 0.15915494, v142
	v_mul_f32_e32 v142, v126, v126
	v_mul_f32_e32 v143, v127, v127
	v_mov_b32_e32 v151, v236
	v_pk_mov_b32 v[146:147], v[144:145], v[142:143] op_sel:[1,0]
	v_mov_b32_e32 v145, v143
	v_add_f32_e32 v142, v146, v144
	v_add_f32_e32 v143, v147, v145
	v_mul_f32_e32 v144, v122, v122
	v_mul_f32_e32 v145, v123, v123
	v_mul_f32_e32 v146, v120, v120
	v_mul_f32_e32 v147, v121, v121
	v_pk_add_f32 v[142:143], v[142:143], v[142:143] op_sel:[0,1] op_sel_hi:[1,0]
	v_pk_mov_b32 v[148:149], v[146:147], v[144:145] op_sel:[1,0]
	v_mov_b32_e32 v147, v145
	v_add_f32_e32 v144, v148, v146
	v_add_f32_e32 v145, v149, v147
	v_mul_f32_e32 v146, v104, v104
	v_mul_f32_e32 v147, v105, v105
	v_pk_add_f32 v[144:145], v[144:145], v[144:145] op_sel:[0,1] op_sel_hi:[1,0]
	v_mov_b32_e32 v143, v146
	v_mov_b32_e32 v145, v147
	v_add_f32_e32 v142, v142, v144
	v_add_f32_e32 v143, v143, v145
	v_mul_f32_e32 v144, v109, v109
	v_mul_f32_e32 v146, v111, v111
	v_mul_f32_e32 v148, v106, v106
	v_mul_f32_e32 v149, v107, v107
	v_fma_f32 v145, v109, v109, v144
	v_fma_f32 v144, v108, v108, v144
	v_fma_f32 v147, v111, v111, v146
	v_fma_f32 v146, v110, v110, v146
	v_mov_b32_e32 v145, v148
	v_mov_b32_e32 v147, v149
	v_add_f32_e32 v144, v144, v146
	v_add_f32_e32 v145, v145, v147
	s_and_b64 s[36:37], s[0:1], exec
	v_add_f32_e32 v142, v142, v144
	v_add_f32_e32 v143, v143, v145
	s_cselect_b32 s39, s73, s75
	v_add_f32_e32 v142, v142, v143
	ds_swizzle_b32 v143, v142 offset:swizzle(SWAP,16)
	s_cselect_b32 s38, s72, s74
	s_andn2_b64 vcc, exec, s[18:19]
	s_waitcnt lgkmcnt(0)
	v_add_f32_e32 v142, v142, v143
	v_mov_b32_e32 v143, v142
	s_nop 1
	v_permlane32_swap_b32_e32 v142, v143
	v_add_f32_e32 v142, v142, v143
	v_fmamk_f32 v142, v142, 0x3c800000, v193
	v_rsq_f32_e32 v150, v142
	v_bfe_u32 v142, v140, 6, 7
	v_cvt_f32_ubyte0_e32 v156, v142
	v_lshlrev_b32_e32 v142, 3, v151
	v_ashrrev_i32_e32 v143, 31, v142
	v_lshl_add_u64 v[152:153], v[142:143], 2, s[38:39]
	global_load_dwordx4 v[142:145], v[152:153], off
	v_mul_f32_e32 v146, v124, v150
	v_mul_f32_e32 v147, v125, v150
	v_mul_f32_e32 v148, v126, v150
	v_mul_f32_e32 v149, v127, v150
	s_waitcnt vmcnt(0)
	v_mul_f32_e32 v142, v142, v146
	v_mul_f32_e32 v143, v143, v147
	v_cndmask_b32_e64 v146, 0, 1, s[18:19]
	v_mul_f32_e32 v144, v144, v148
	v_mul_f32_e32 v145, v145, v149
	v_cmp_ne_u32_e64 s[36:37], 1, v146
	s_cbranch_vccnz .LBB0_455
	v_mul_f32_e32 v147, v194, v156
	v_sin_f32_e32 v148, v147
	v_mul_f32_e32 v149, v237, v156
	v_cos_f32_e32 v146, v147
	v_sin_f32_e32 v155, v149
	v_cos_f32_e32 v154, v149
	v_mul_f32_e32 v149, v148, v142
	v_mul_f32_e32 v148, v148, v143
	v_mul_f32_e32 v158, v146, v142
	v_mul_f32_e32 v159, v146, v143
	v_fma_f32 v142, v146, v142, v148
	v_fma_f32 v143, v146, v143, v149
	v_mul_f32_e32 v142, v155, v145
	v_fma_f32 v146, v154, v144, -v142
	v_fma_f32 v147, v155, v145, -v142
	v_mov_b32_e32 v160, v155
	v_mov_b32_e32 v161, v154
	v_mul_f32_e32 v142, v154, v145
	v_fma_f32 v154, v160, v144, v142
	v_fma_f32 v155, v161, v145, v142
	v_sub_f32_e32 v142, v158, v148
	v_mov_b32_e32 v144, v146
	v_mov_b32_e32 v145, v154
.LBB0_455:
	global_load_dwordx4 v[158:161], v[152:153], off offset:16
	v_or_b32_e32 v141, 2, v141
	v_cvt_f32_i32_e32 v141, v141
	v_mov_b32_e32 v151, v150
	v_mov_b32_e32 v146, v150
	v_mov_b32_e32 v147, v150
	v_mul_f32_e32 v148, 0xbf549a78, v141
	v_add_f32_e32 v141, 1.0, v141
	v_mul_f32_e32 v141, 0xbf549a78, v141
	v_exp_f32_e32 v154, v148
	v_exp_f32_e32 v141, v141
	v_mul_f32_e32 v148, v122, v146
	v_mul_f32_e32 v149, v123, v147
	v_mul_f32_e32 v162, v120, v150
	v_mul_f32_e32 v163, v121, v151
	s_and_b64 vcc, exec, s[36:37]
	v_mul_f32_e32 v238, 0.15915494, v154
	v_mul_f32_e32 v239, 0.15915494, v141
	s_waitcnt vmcnt(0)
	v_mul_f32_e32 v154, v148, v160
	v_mul_f32_e32 v155, v149, v161
	v_mul_f32_e32 v148, v162, v158
	v_mul_f32_e32 v149, v163, v159
	s_cbranch_vccnz .LBB0_457
	v_mul_f32_e32 v141, v238, v156
	v_sin_f32_e32 v158, v141
	v_mul_f32_e32 v157, v239, v156
	v_cos_f32_e32 v156, v141
	v_sin_f32_e32 v161, v157
	v_cos_f32_e32 v160, v157
	v_mul_f32_e32 v159, v158, v148
	v_mul_f32_e32 v158, v158, v149
	v_mul_f32_e32 v162, v156, v148
	v_mul_f32_e32 v163, v156, v149
	v_fma_f32 v148, v156, v148, v158
	v_fma_f32 v149, v156, v149, v159
	v_mul_f32_e32 v148, v161, v155
	v_fma_f32 v156, v160, v154, -v148
	v_fma_f32 v157, v161, v155, -v148
	v_mov_b32_e32 v164, v161
	v_mov_b32_e32 v165, v160
	v_mul_f32_e32 v148, v160, v155
	v_fma_f32 v160, v164, v154, v148
	v_fma_f32 v161, v165, v155, v148
	v_sub_f32_e32 v148, v162, v158
	v_mov_b32_e32 v154, v156
	v_mov_b32_e32 v155, v160
; __device__ __forceinline__ unsigned cvt_pk_bf16(float lo, float hi) { const f32x2 v = {lo, hi}; const bf16x2_t b = __builtin_convertvector(v, bf16x2_t); return __builtin_bit_cast(unsigned, b); }
;     __device__ __forceinline__ void operator()(const f32x4 (&acc)[2][2][4][2], const Unit& u, int wr, int wc, int fr, int fq) const {
;     ...
;             for (int ai = 0; ai < 2; ++ai)
; #pragma unroll
;                 for (int m = 0; m < 4; ++m) {
;                     const int row = row0 + ai * HALF + m * 16;
;                     int fqo = fq; asm volatile("" : "+v"(fqo));
;                     f32x4 v[2][2]; float ss = 0.f;
; #pragma unroll
;                     for (int bj = 0; bj < 2; ++bj)
; #pragma unroll
;                         for (int n = 0; n < 2; ++n) { v[bj][n] = acc[ai][bj][m][n]; ss += (v[bj][n][0] * v[bj][n][0] + v[bj][n][1] * v[bj][n][1]) + (v[bj][n][2] * v[bj][n][2] + v[bj][n][3] * v[bj][n][3]); }
;                     ss += swz_xor<16>(ss); ss = xadd32(ss);
;                     const float rstd = __builtin_amdgcn_rsqf(ss * (1.0f / 64.0f) + EPS);
;                     const int t = row & (SEQ - 1); const float pos[2] = {(float)(t >> 6), (float)(t & 63)};
; #pragma unroll
;                     for (int bj = 0; bj < 2; ++bj) {
;                         u32x4 w;
; #pragma unroll
;                         for (int n = 0; n < 2; ++n) {
;                             f32x4 x = v[bj][n] * rstd * *(const f32x4*)(g + 32 * bj + 8 * fqo + 4 * n);
;                             if (latent) {
;                                 const float a0 = pos[bj] * fr0[n], a1 = pos[bj] * fr1[n];
;                                 const float c0 = __builtin_amdgcn_cosf(a0), s0 = __builtin_amdgcn_sinf(a0), c1 = __builtin_amdgcn_cosf(a1), s1 = __builtin_amdgcn_sinf(a1);
;                                 x = (f32x4){x[0] * c0 - x[1] * s0, x[1] * c0 + x[0] * s0, x[2] * c1 - x[3] * s1, x[3] * c1 + x[2] * s1};
;                             }
;                             if (n == 0) { w.x = cvt_pk_bf16(x[0], x[1]); w.y = cvt_pk_bf16(x[2], x[3]); } else { w.z = cvt_pk_bf16(x[0], x[1]); w.w = cvt_pk_bf16(x[2], x[3]); }
;                         }
;                         *(u32x4*)(dst + (size_t)row * 64 + 32 * bj + 8 * fq) = w;
;                     }
.LBB0_457:
	s_add_i32 s18, s15, -6
	s_ashr_i32 s19, s15, 31
	s_and_b64 s[0:1], s[0:1], exec
	s_cselect_b32 s0, s15, s18
	s_cselect_b32 s1, s19, 0
	s_cselect_b32 s15, 0, 0x18c0000
	s_add_u32 s15, s90, s15
	s_mul_i32 s1, s1, 0x420000
	s_mul_hi_u32 s19, s0, 0x420000
	s_addc_u32 s18, s91, 0
	s_add_i32 s19, s19, s1
	s_mul_i32 s0, s0, 0x420000
	v_cvt_pk_bf16_f32 v158, v142, v143
	s_add_u32 s0, s15, s0
	v_lshlrev_b32_e32 v142, 3, v236
	s_addc_u32 s1, s18, s19
	v_ashrrev_i32_e32 v143, 31, v142
	v_ashrrev_i32_e32 v141, 31, v140
	v_cvt_pk_bf16_f32 v159, v144, v145
	v_lshl_add_u64 v[142:143], v[142:143], 1, s[0:1]
	v_lshlrev_b64 v[144:145], 7, v[140:141]
	v_lshl_add_u64 v[156:157], v[142:143], 0, v[144:145]
	v_cvt_pk_bf16_f32 v160, v148, v149
	v_cvt_pk_bf16_f32 v161, v154, v155
	global_store_dwordx4 v[156:157], v[158:161], off
	v_mul_f32_e32 v148, v110, v146
	v_mul_f32_e32 v149, v111, v147
	global_load_dwordx4 v[144:147], v[152:153], off offset:128
	v_and_b32_e32 v180, 63, v235
	v_cvt_f32_ubyte0_e32 v166, v180
	v_mul_f32_e32 v154, v108, v150
	v_mul_f32_e32 v155, v109, v151
	v_mul_f32_e32 v141, v194, v166
	s_and_b64 vcc, exec, s[36:37]
	s_waitcnt vmcnt(0)
	v_mul_f32_e32 v158, v154, v144
	v_mul_f32_e32 v159, v155, v145
	v_mul_f32_e32 v145, v237, v166
	v_mul_f32_e32 v160, v148, v146
	v_mul_f32_e32 v161, v149, v147
	v_cos_f32_e32 v146, v141
	v_sin_f32_e32 v148, v141
	v_cos_f32_e32 v144, v145
	v_sin_f32_e32 v145, v145
	s_cbranch_vccnz .LBB0_459
	v_mul_f32_e32 v162, v148, v159
	v_mul_f32_e32 v163, v148, v158
	v_mul_f32_e32 v154, v146, v158
	v_mul_f32_e32 v155, v146, v159
	v_fma_f32 v158, v146, v158, v162
	v_fma_f32 v159, v146, v159, v163
	v_mul_f32_e32 v158, v145, v161
	v_fma_f32 v164, v144, v160, -v158
	v_fma_f32 v165, v145, v161, -v158
	v_mov_b32_e32 v168, v145
	v_mov_b32_e32 v169, v144
	v_mul_f32_e32 v158, v144, v161
	v_fma_f32 v168, v168, v160, v158
	v_fma_f32 v169, v169, v161, v158
	v_sub_f32_e32 v158, v154, v162
	v_mov_b32_e32 v160, v164
	v_mov_b32_e32 v161, v168
.LBB0_459:
	v_mov_b32_e32 v154, v150
	v_mov_b32_e32 v155, v150
	v_mul_f32_e32 v162, v104, v150
	v_mul_f32_e32 v163, v105, v151
	global_load_dwordx4 v[150:153], v[152:153], off offset:144
	v_mul_f32_e32 v154, v106, v154
	v_mul_f32_e32 v155, v107, v155
	v_mul_f32_e32 v141, v238, v166
	v_mul_f32_e32 v147, v239, v166
	s_and_b64 vcc, exec, s[36:37]
	s_waitcnt vmcnt(0)
	v_mul_f32_e32 v164, v154, v152
	v_mul_f32_e32 v165, v155, v153
	v_mul_f32_e32 v162, v162, v150
	v_mul_f32_e32 v163, v163, v151
	v_cos_f32_e32 v152, v141
	v_sin_f32_e32 v154, v141
	v_cos_f32_e32 v150, v147
	v_sin_f32_e32 v151, v147
	s_cbranch_vccnz .LBB0_461
	v_mul_f32_e32 v168, v154, v163
	v_mul_f32_e32 v169, v154, v162
	v_mul_f32_e32 v166, v152, v162
	v_mul_f32_e32 v167, v152, v163
	v_fma_f32 v162, v152, v162, v168
	v_fma_f32 v163, v152, v163, v169
	v_mul_f32_e32 v162, v151, v165
	v_fma_f32 v170, v150, v164, -v162
	v_fma_f32 v171, v151, v165, -v162
	v_mov_b32_e32 v172, v151
	v_mov_b32_e32 v173, v150
	v_mul_f32_e32 v162, v150, v165
	v_fma_f32 v172, v172, v164, v162
	v_fma_f32 v173, v173, v165, v162
	v_sub_f32_e32 v162, v166, v168
	v_mov_b32_e32 v164, v170
	v_mov_b32_e32 v165, v172
.LBB0_461:
	v_cvt_pk_bf16_f32 v158, v158, v159
	v_cvt_pk_bf16_f32 v159, v160, v161
	v_cvt_pk_bf16_f32 v160, v162, v163
	v_cvt_pk_bf16_f32 v161, v164, v165
	global_store_dwordx4 v[156:157], v[158:161], off offset:64
	v_mul_f32_e32 v156, v118, v118
	v_mul_f32_e32 v157, v119, v119
	s_nop 0
	v_mul_f32_e32 v158, v116, v116
	v_mul_f32_e32 v159, v117, v117
	v_mul_f32_e32 v141, v88, v88
	v_pk_mov_b32 v[160:161], v[158:159], v[156:157] op_sel:[1,0]
	v_mov_b32_e32 v159, v157
	v_add_f32_e32 v156, v160, v158
	v_add_f32_e32 v157, v161, v159
	v_mul_f32_e32 v158, v114, v114
	v_mul_f32_e32 v159, v115, v115
	v_mul_f32_e32 v160, v112, v112
	v_mul_f32_e32 v161, v113, v113
	v_mul_f32_e32 v149, v89, v89
	v_pk_mov_b32 v[162:163], v[160:161], v[158:159] op_sel:[1,0]
	v_mov_b32_e32 v161, v159
	v_add_f32_e32 v158, v162, v160
	v_add_f32_e32 v159, v163, v161
	v_pk_add_f32 v[156:157], v[156:157], v[156:157] op_sel:[0,1] op_sel_hi:[1,0]
	v_pk_add_f32 v[158:159], v[158:159], v[158:159] op_sel:[0,1] op_sel_hi:[1,0]
	v_mov_b32_e32 v157, v141
	v_mov_b32_e32 v159, v149
	v_add_f32_e32 v156, v156, v158
	v_add_f32_e32 v157, v157, v159
	v_mul_f32_e32 v158, v93, v93
	v_mul_f32_e32 v160, v95, v95
	v_mul_f32_e32 v153, v90, v90
	v_mul_f32_e32 v155, v91, v91
	v_fma_f32 v159, v93, v93, v158
	v_fma_f32 v158, v92, v92, v158
	v_fma_f32 v161, v95, v95, v160
	v_fma_f32 v160, v94, v94, v160
	v_mov_b32_e32 v159, v153
	v_mov_b32_e32 v161, v155
	v_mov_b32_e32 v147, v236
	v_add_f32_e32 v158, v158, v160
	v_add_f32_e32 v159, v159, v161
	s_and_b64 vcc, exec, s[36:37]
	v_add_f32_e32 v156, v156, v158
	v_add_f32_e32 v157, v157, v159
	v_lshlrev_b32_e32 v158, 3, v147
	v_ashrrev_i32_e32 v159, 31, v158
	v_lshl_add_u64 v[164:165], v[158:159], 2, s[38:39]
	global_load_dwordx4 v[158:161], v[164:165], off
	v_add_f32_e32 v141, v156, v157
	ds_swizzle_b32 v149, v141 offset:swizzle(SWAP,16)
	v_add_u32_e32 v156, 16, v140
	s_waitcnt lgkmcnt(0)
	v_add_f32_e32 v141, v141, v149
	v_mov_b32_e32 v149, v141
	s_nop 1
	v_permlane32_swap_b32_e32 v141, v149
	v_add_f32_e32 v141, v141, v149
	v_fmamk_f32 v141, v141, 0x3c800000, v193
	v_rsq_f32_e32 v162, v141
	v_bfe_u32 v141, v156, 6, 7
	v_cvt_f32_ubyte0_e32 v141, v141
	v_mul_f32_e32 v166, v116, v162
	v_mul_f32_e32 v167, v117, v162
	v_mul_f32_e32 v168, v118, v162
	v_mul_f32_e32 v169, v119, v162
	s_waitcnt vmcnt(0)
	v_mul_f32_e32 v158, v158, v166
	v_mul_f32_e32 v159, v159, v167
	v_mul_f32_e32 v160, v160, v168
	v_mul_f32_e32 v161, v161, v169
	s_cbranch_vccnz .LBB0_463
	v_mul_f32_e32 v147, v194, v141
	v_sin_f32_e32 v168, v147
	v_mul_f32_e32 v149, v237, v141
	v_cos_f32_e32 v166, v147
	v_sin_f32_e32 v171, v149
	v_cos_f32_e32 v170, v149
	v_mul_f32_e32 v169, v168, v158
	v_mul_f32_e32 v168, v168, v159
	v_mul_f32_e32 v172, v166, v158
	v_mul_f32_e32 v173, v166, v159
	v_fma_f32 v158, v166, v158, v168
	v_fma_f32 v159, v166, v159, v169
	v_mul_f32_e32 v158, v171, v161
	v_fma_f32 v166, v170, v160, -v158
	v_fma_f32 v167, v171, v161, -v158
	v_mov_b32_e32 v174, v171
	v_mov_b32_e32 v175, v170
	v_mul_f32_e32 v158, v170, v161
	v_fma_f32 v170, v174, v160, v158
	v_fma_f32 v171, v175, v161, v158
	v_sub_f32_e32 v158, v172, v168
	v_mov_b32_e32 v160, v166
	v_mov_b32_e32 v161, v170
; __device__ __forceinline__ unsigned cvt_pk_bf16(float lo, float hi) { const f32x2 v = {lo, hi}; const bf16x2_t b = __builtin_convertvector(v, bf16x2_t); return __builtin_bit_cast(unsigned, b); }
; template <int M> __device__ __forceinline__ float swz_xor(float v) { return __builtin_bit_cast(float, __builtin_amdgcn_ds_swizzle(__builtin_bit_cast(int, v), (M << 10) | 0x1f)); }
;     __device__ __forceinline__ void operator()(const f32x4 (&acc)[2][2][4][2], const Unit& u, int wr, int wc, int fr, int fq) const {
;     ...
;                     const int row = row0 + ai * HALF + m * 16;
;                     int fqo = fq; asm volatile("" : "+v"(fqo));
;                     f32x4 v[2][2]; float ss = 0.f;
; #pragma unroll
;                     for (int bj = 0; bj < 2; ++bj)
; #pragma unroll
;                         for (int n = 0; n < 2; ++n) { v[bj][n] = acc[ai][bj][m][n]; ss += (v[bj][n][0] * v[bj][n][0] + v[bj][n][1] * v[bj][n][1]) + (v[bj][n][2] * v[bj][n][2] + v[bj][n][3] * v[bj][n][3]); }
;                     ss += swz_xor<16>(ss); ss = xadd32(ss);
;                     const float rstd = __builtin_amdgcn_rsqf(ss * (1.0f / 64.0f) + EPS);
;                     const int t = row & (SEQ - 1); const float pos[2] = {(float)(t >> 6), (float)(t & 63)};
; #pragma unroll
;                     for (int bj = 0; bj < 2; ++bj) {
;                         u32x4 w;
; #pragma unroll
;                         for (int n = 0; n < 2; ++n) {
;                             f32x4 x = v[bj][n] * rstd * *(const f32x4*)(g + 32 * bj + 8 * fqo + 4 * n);
;                             if (latent) {
;                                 const float a0 = pos[bj] * fr0[n], a1 = pos[bj] * fr1[n];
;                                 const float c0 = __builtin_amdgcn_cosf(a0), s0 = __builtin_amdgcn_sinf(a0), c1 = __builtin_amdgcn_cosf(a1), s1 = __builtin_amdgcn_sinf(a1);
;                                 x = (f32x4){x[0] * c0 - x[1] * s0, x[1] * c0 + x[0] * s0, x[2] * c1 - x[3] * s1, x[3] * c1 + x[2] * s1};
;                             }
;                             if (n == 0) { w.x = cvt_pk_bf16(x[0], x[1]); w.y = cvt_pk_bf16(x[2], x[3]); } else { w.z = cvt_pk_bf16(x[0], x[1]); w.w = cvt_pk_bf16(x[2], x[3]); }
;                         }
;                         *(u32x4*)(dst + (size_t)row * 64 + 32 * bj + 8 * fq) = w;
;                     }
.LBB0_463:
	global_load_dwordx4 v[168:171], v[164:165], off offset:16
	v_mov_b32_e32 v163, v162
	v_mov_b32_e32 v166, v162
	v_mov_b32_e32 v167, v162
	v_mul_f32_e32 v172, v114, v166
	v_mul_f32_e32 v173, v115, v167
	v_mul_f32_e32 v174, v112, v162
	v_mul_f32_e32 v175, v113, v163
	s_and_b64 vcc, exec, s[36:37]
	s_waitcnt vmcnt(0)
	v_mul_f32_e32 v172, v172, v170
	v_mul_f32_e32 v173, v173, v171
	v_mul_f32_e32 v170, v174, v168
	v_mul_f32_e32 v171, v175, v169
	s_cbranch_vccnz .LBB0_465
	v_mul_f32_e32 v147, v238, v141
	v_sin_f32_e32 v174, v147
	v_mul_f32_e32 v141, v239, v141
	v_cos_f32_e32 v168, v147
	v_cos_f32_e32 v176, v141
	v_sin_f32_e32 v177, v141
	v_mul_f32_e32 v175, v174, v170
	v_mul_f32_e32 v174, v174, v171
	v_mul_f32_e32 v178, v168, v170
	v_mul_f32_e32 v179, v168, v171
	v_fma_f32 v170, v168, v170, v174
	v_fma_f32 v171, v168, v171, v175
	v_mul_f32_e32 v168, v177, v173
	v_mov_b32_e32 v182, v177
	v_mov_b32_e32 v183, v176
	v_mul_f32_e32 v170, v176, v173
	v_fma_f32 v169, v177, v173, -v168
	v_fma_f32 v168, v176, v172, -v168
	v_fma_f32 v176, v182, v172, v170
	v_fma_f32 v177, v183, v173, v170
	v_sub_f32_e32 v170, v178, v174
	v_mov_b32_e32 v172, v168
	v_mov_b32_e32 v173, v176
.LBB0_465:
	v_ashrrev_i32_e32 v157, 31, v156
	v_lshlrev_b64 v[156:157], 7, v[156:157]
	v_cvt_pk_bf16_f32 v158, v158, v159
	v_cvt_pk_bf16_f32 v159, v160, v161
	v_lshl_add_u64 v[168:169], v[142:143], 0, v[156:157]
	v_cvt_pk_bf16_f32 v160, v170, v171
	v_cvt_pk_bf16_f32 v161, v172, v173
	global_store_dwordx4 v[168:169], v[158:161], off
	global_load_dwordx4 v[156:159], v[164:165], off offset:128
	v_add_u32_e32 v141, 16, v235
	v_and_b32_e32 v141, 63, v141
	v_cvt_f32_ubyte0_e32 v141, v141
	v_mul_f32_e32 v160, v94, v166
	v_mul_f32_e32 v161, v95, v167
	v_mul_f32_e32 v166, v92, v162
	v_mul_f32_e32 v167, v93, v163
	v_mul_f32_e32 v147, v194, v141
	v_mul_f32_e32 v149, v237, v141
	s_and_b64 vcc, exec, s[36:37]
	s_waitcnt vmcnt(0)
	v_mul_f32_e32 v172, v160, v158
	v_mul_f32_e32 v173, v161, v159
	v_mul_f32_e32 v170, v166, v156
	v_mul_f32_e32 v171, v167, v157
	v_cos_f32_e32 v158, v147
	v_sin_f32_e32 v160, v147
	v_cos_f32_e32 v156, v149
	v_sin_f32_e32 v157, v149
	s_cbranch_vccnz .LBB0_467
	v_mul_f32_e32 v174, v160, v171
	v_mul_f32_e32 v175, v160, v170
	v_mul_f32_e32 v166, v158, v170
	v_mul_f32_e32 v167, v158, v171
	v_fma_f32 v170, v158, v170, v174
	v_fma_f32 v171, v158, v171, v175
	v_mul_f32_e32 v170, v157, v173
	v_fma_f32 v176, v156, v172, -v170
	v_fma_f32 v177, v157, v173, -v170
	v_mov_b32_e32 v178, v157
	v_mov_b32_e32 v179, v156
	v_mul_f32_e32 v170, v156, v173
	v_fma_f32 v178, v178, v172, v170
	v_fma_f32 v179, v179, v173, v170
	v_sub_f32_e32 v170, v166, v174
	v_mov_b32_e32 v172, v176
	v_mov_b32_e32 v173, v178
.LBB0_467:
	v_mov_b32_e32 v166, v162
	v_mov_b32_e32 v167, v162
	v_mul_f32_e32 v174, v88, v162
	v_mul_f32_e32 v175, v89, v163
	global_load_dwordx4 v[162:165], v[164:165], off offset:144
	v_mul_f32_e32 v166, v90, v166
	v_mul_f32_e32 v167, v91, v167
	v_mul_f32_e32 v147, v238, v141
	v_mul_f32_e32 v141, v239, v141
	s_and_b64 vcc, exec, s[36:37]
	s_waitcnt vmcnt(0)
	v_mul_f32_e32 v176, v166, v164
	v_mul_f32_e32 v177, v167, v165
	v_mul_f32_e32 v174, v174, v162
	v_mul_f32_e32 v175, v175, v163
	v_cos_f32_e32 v164, v147
	v_sin_f32_e32 v166, v147
	v_cos_f32_e32 v162, v141
	v_sin_f32_e32 v163, v141
	s_cbranch_vccnz .LBB0_469
	v_mul_f32_e32 v182, v166, v175
	v_mul_f32_e32 v183, v166, v174
	v_mul_f32_e32 v178, v164, v174
	v_mul_f32_e32 v179, v164, v175
	v_fma_f32 v174, v164, v174, v182
	v_fma_f32 v175, v164, v175, v183
	v_mul_f32_e32 v174, v163, v177
	v_fma_f32 v184, v162, v176, -v174
	v_fma_f32 v185, v163, v177, -v174
	v_mov_b32_e32 v186, v163
	v_mov_b32_e32 v187, v162
	v_mul_f32_e32 v174, v162, v177
	v_fma_f32 v186, v186, v176, v174
	v_fma_f32 v187, v187, v177, v174
	v_sub_f32_e32 v174, v178, v182
	v_mov_b32_e32 v176, v184
	v_mov_b32_e32 v177, v186
.LBB0_469:
	v_cvt_pk_bf16_f32 v170, v170, v171
	v_cvt_pk_bf16_f32 v171, v172, v173
	v_cvt_pk_bf16_f32 v172, v174, v175
	v_cvt_pk_bf16_f32 v173, v176, v177
	global_store_dwordx4 v[168:169], v[170:173], off offset:64
	v_mul_f32_e32 v168, v102, v102
	v_mul_f32_e32 v169, v103, v103
	s_nop 0
	v_mul_f32_e32 v170, v100, v100
	v_mul_f32_e32 v171, v101, v101
	v_mul_f32_e32 v141, v72, v72
	v_pk_mov_b32 v[172:173], v[170:171], v[168:169] op_sel:[1,0]
	v_mov_b32_e32 v171, v169
	v_add_f32_e32 v168, v172, v170
	v_add_f32_e32 v169, v173, v171
	v_mul_f32_e32 v170, v98, v98
	v_mul_f32_e32 v171, v99, v99
	v_mul_f32_e32 v172, v96, v96
	v_mul_f32_e32 v173, v97, v97
	v_mul_f32_e32 v149, v73, v73
	v_pk_mov_b32 v[174:175], v[172:173], v[170:171] op_sel:[1,0]
	v_mov_b32_e32 v173, v171
	v_add_f32_e32 v170, v174, v172
	v_add_f32_e32 v171, v175, v173
	v_pk_add_f32 v[168:169], v[168:169], v[168:169] op_sel:[0,1] op_sel_hi:[1,0]
	v_pk_add_f32 v[170:171], v[170:171], v[170:171] op_sel:[0,1] op_sel_hi:[1,0]
	v_mov_b32_e32 v169, v141
	v_mov_b32_e32 v171, v149
	v_add_f32_e32 v168, v168, v170
	v_add_f32_e32 v169, v169, v171
	v_mul_f32_e32 v170, v77, v77
	v_mul_f32_e32 v172, v79, v79
	v_mul_f32_e32 v153, v74, v74
	v_mul_f32_e32 v155, v75, v75
	v_fma_f32 v171, v77, v77, v170
	v_fma_f32 v170, v76, v76, v170
	v_fma_f32 v173, v79, v79, v172
	v_fma_f32 v172, v78, v78, v172
	v_mov_b32_e32 v171, v153
	v_mov_b32_e32 v173, v155
	v_mov_b32_e32 v147, v236
	v_add_f32_e32 v170, v170, v172
	v_add_f32_e32 v171, v171, v173
	s_and_b64 vcc, exec, s[36:37]
	v_add_f32_e32 v168, v168, v170
	v_add_f32_e32 v169, v169, v171
	v_lshlrev_b32_e32 v170, 3, v147
	v_ashrrev_i32_e32 v171, 31, v170
	v_lshl_add_u64 v[176:177], v[170:171], 2, s[38:39]
	global_load_dwordx4 v[170:173], v[176:177], off
	v_add_f32_e32 v141, v168, v169
	ds_swizzle_b32 v149, v141 offset:swizzle(SWAP,16)
	v_add_u32_e32 v168, 32, v140
	s_waitcnt lgkmcnt(0)
	v_add_f32_e32 v141, v141, v149
	v_mov_b32_e32 v149, v141
	s_nop 1
	v_permlane32_swap_b32_e32 v141, v149
	v_add_f32_e32 v141, v141, v149
	v_fmamk_f32 v141, v141, 0x3c800000, v193
	v_rsq_f32_e32 v174, v141
	v_bfe_u32 v141, v168, 6, 7
	v_cvt_f32_ubyte0_e32 v141, v141
	v_mul_f32_e32 v178, v100, v174
	v_mul_f32_e32 v179, v101, v174
	v_mul_f32_e32 v182, v102, v174
	v_mul_f32_e32 v183, v103, v174
	s_waitcnt vmcnt(0)
	v_mul_f32_e32 v170, v170, v178
	v_mul_f32_e32 v171, v171, v179
	v_mul_f32_e32 v172, v172, v182
	v_mul_f32_e32 v173, v173, v183
	s_cbranch_vccnz .LBB0_471
	v_mul_f32_e32 v147, v194, v141
	v_sin_f32_e32 v182, v147
	v_mul_f32_e32 v149, v237, v141
	v_cos_f32_e32 v178, v147
	v_sin_f32_e32 v185, v149
	v_cos_f32_e32 v184, v149
	v_mul_f32_e32 v183, v182, v170
	v_mul_f32_e32 v182, v182, v171
	v_mul_f32_e32 v186, v178, v170
	v_mul_f32_e32 v187, v178, v171
	v_fma_f32 v170, v178, v170, v182
	v_fma_f32 v171, v178, v171, v183
	v_mul_f32_e32 v170, v185, v173
	v_fma_f32 v178, v184, v172, -v170
	v_fma_f32 v179, v185, v173, -v170
	v_mov_b32_e32 v188, v185
	v_mov_b32_e32 v189, v184
	v_mul_f32_e32 v170, v184, v173
	v_fma_f32 v184, v188, v172, v170
	v_fma_f32 v185, v189, v173, v170
	v_sub_f32_e32 v170, v186, v182
	v_mov_b32_e32 v172, v178
	v_mov_b32_e32 v173, v184
; __device__ __forceinline__ unsigned cvt_pk_bf16(float lo, float hi) { const f32x2 v = {lo, hi}; const bf16x2_t b = __builtin_convertvector(v, bf16x2_t); return __builtin_bit_cast(unsigned, b); }
; template <int M> __device__ __forceinline__ float swz_xor(float v) { return __builtin_bit_cast(float, __builtin_amdgcn_ds_swizzle(__builtin_bit_cast(int, v), (M << 10) | 0x1f)); }
;     __device__ __forceinline__ void operator()(const f32x4 (&acc)[2][2][4][2], const Unit& u, int wr, int wc, int fr, int fq) const {
;     ...
;                     const int row = row0 + ai * HALF + m * 16;
;                     int fqo = fq; asm volatile("" : "+v"(fqo));
;                     f32x4 v[2][2]; float ss = 0.f;
; #pragma unroll
;                     for (int bj = 0; bj < 2; ++bj)
; #pragma unroll
;                         for (int n = 0; n < 2; ++n) { v[bj][n] = acc[ai][bj][m][n]; ss += (v[bj][n][0] * v[bj][n][0] + v[bj][n][1] * v[bj][n][1]) + (v[bj][n][2] * v[bj][n][2] + v[bj][n][3] * v[bj][n][3]); }
;                     ss += swz_xor<16>(ss); ss = xadd32(ss);
;                     const float rstd = __builtin_amdgcn_rsqf(ss * (1.0f / 64.0f) + EPS);
;                     const int t = row & (SEQ - 1); const float pos[2] = {(float)(t >> 6), (float)(t & 63)};
; #pragma unroll
;                     for (int bj = 0; bj < 2; ++bj) {
;                         u32x4 w;
; #pragma unroll
;                         for (int n = 0; n < 2; ++n) {
;                             f32x4 x = v[bj][n] * rstd * *(const f32x4*)(g + 32 * bj + 8 * fqo + 4 * n);
;                             if (latent) {
;                                 const float a0 = pos[bj] * fr0[n], a1 = pos[bj] * fr1[n];
;                                 const float c0 = __builtin_amdgcn_cosf(a0), s0 = __builtin_amdgcn_sinf(a0), c1 = __builtin_amdgcn_cosf(a1), s1 = __builtin_amdgcn_sinf(a1);
;                                 x = (f32x4){x[0] * c0 - x[1] * s0, x[1] * c0 + x[0] * s0, x[2] * c1 - x[3] * s1, x[3] * c1 + x[2] * s1};
;                             }
;                             if (n == 0) { w.x = cvt_pk_bf16(x[0], x[1]); w.y = cvt_pk_bf16(x[2], x[3]); } else { w.z = cvt_pk_bf16(x[0], x[1]); w.w = cvt_pk_bf16(x[2], x[3]); }
;                         }
;                         *(u32x4*)(dst + (size_t)row * 64 + 32 * bj + 8 * fq) = w;
;                     }
.LBB0_471:
	global_load_dwordx4 v[182:185], v[176:177], off offset:16
	v_mov_b32_e32 v175, v174
	v_mov_b32_e32 v178, v174
	v_mov_b32_e32 v179, v174
	v_mul_f32_e32 v186, v98, v178
	v_mul_f32_e32 v187, v99, v179
	v_mul_f32_e32 v188, v96, v174
	v_mul_f32_e32 v189, v97, v175
	s_and_b64 vcc, exec, s[36:37]
	s_waitcnt vmcnt(0)
	v_mul_f32_e32 v184, v186, v184
	v_mul_f32_e32 v185, v187, v185
	v_mul_f32_e32 v182, v188, v182
	v_mul_f32_e32 v183, v189, v183
	s_cbranch_vccnz .LBB0_473
	v_mul_f32_e32 v147, v238, v141
	v_sin_f32_e32 v188, v147
	v_mul_f32_e32 v141, v239, v141
	v_cos_f32_e32 v186, v147
	v_sin_f32_e32 v191, v141
	v_cos_f32_e32 v190, v141
	v_mul_f32_e32 v189, v188, v182
	v_mul_f32_e32 v188, v188, v183
	v_mul_f32_e32 v208, v186, v182
	v_mul_f32_e32 v209, v186, v183
	v_fma_f32 v182, v186, v182, v188
	v_fma_f32 v183, v186, v183, v189
	v_mul_f32_e32 v182, v191, v185
	v_fma_f32 v186, v190, v184, -v182
	v_fma_f32 v187, v191, v185, -v182
	v_mov_b32_e32 v210, v191
	v_mov_b32_e32 v211, v190
	v_mul_f32_e32 v182, v190, v185
	v_fma_f32 v190, v210, v184, v182
	v_fma_f32 v191, v211, v185, v182
	v_sub_f32_e32 v182, v208, v188
	v_mov_b32_e32 v184, v186
	v_mov_b32_e32 v185, v190
.LBB0_473:
	v_ashrrev_i32_e32 v169, 31, v168
	v_lshlrev_b64 v[168:169], 7, v[168:169]
	v_cvt_pk_bf16_f32 v170, v170, v171
	v_cvt_pk_bf16_f32 v171, v172, v173
	v_xor_b32_e32 v141, 32, v180
	v_lshl_add_u64 v[180:181], v[142:143], 0, v[168:169]
	v_cvt_pk_bf16_f32 v172, v182, v183
	v_cvt_pk_bf16_f32 v173, v184, v185
	global_store_dwordx4 v[180:181], v[170:173], off
	global_load_dwordx4 v[168:171], v[176:177], off offset:128
	v_cvt_f32_ubyte0_e32 v141, v141
	v_mul_f32_e32 v172, v78, v178
	v_mul_f32_e32 v173, v79, v179
	v_mul_f32_e32 v178, v76, v174
	v_mul_f32_e32 v179, v77, v175
	v_mul_f32_e32 v147, v194, v141
	v_mul_f32_e32 v149, v237, v141
	s_and_b64 vcc, exec, s[36:37]
	s_waitcnt vmcnt(0)
	v_mul_f32_e32 v184, v172, v170
	v_mul_f32_e32 v185, v173, v171
	v_mul_f32_e32 v182, v178, v168
	v_mul_f32_e32 v183, v179, v169
	v_cos_f32_e32 v170, v147
	v_sin_f32_e32 v172, v147
	v_cos_f32_e32 v168, v149
	v_sin_f32_e32 v169, v149
	s_cbranch_vccnz .LBB0_475
	v_mul_f32_e32 v186, v172, v183
	v_mul_f32_e32 v187, v172, v182
	v_mul_f32_e32 v178, v170, v182
	v_mul_f32_e32 v179, v170, v183
	v_fma_f32 v182, v170, v182, v186
	v_fma_f32 v183, v170, v183, v187
	v_mul_f32_e32 v182, v169, v185
	v_fma_f32 v188, v168, v184, -v182
	v_fma_f32 v189, v169, v185, -v182
	v_mov_b32_e32 v190, v169
	v_mov_b32_e32 v191, v168
	v_mul_f32_e32 v182, v168, v185
	v_fma_f32 v190, v190, v184, v182
	v_fma_f32 v191, v191, v185, v182
	v_sub_f32_e32 v182, v178, v186
	v_mov_b32_e32 v184, v188
	v_mov_b32_e32 v185, v190
.LBB0_475:
	v_mov_b32_e32 v178, v174
	v_mov_b32_e32 v179, v174
	v_mul_f32_e32 v186, v72, v174
	v_mul_f32_e32 v187, v73, v175
	global_load_dwordx4 v[174:177], v[176:177], off offset:144
	v_mul_f32_e32 v178, v74, v178
	v_mul_f32_e32 v179, v75, v179
	v_mul_f32_e32 v147, v238, v141
	v_mul_f32_e32 v141, v239, v141
	s_and_b64 vcc, exec, s[36:37]
	s_waitcnt vmcnt(0)
	v_mul_f32_e32 v188, v178, v176
	v_mul_f32_e32 v189, v179, v177
	v_mul_f32_e32 v186, v186, v174
	v_mul_f32_e32 v187, v187, v175
	v_cos_f32_e32 v176, v147
	v_sin_f32_e32 v178, v147
	v_cos_f32_e32 v174, v141
	v_sin_f32_e32 v175, v141
	s_cbranch_vccnz .LBB0_477
	v_mul_f32_e32 v208, v178, v187
	v_mul_f32_e32 v209, v178, v186
	v_mul_f32_e32 v190, v176, v186
	v_mul_f32_e32 v191, v176, v187
	v_fma_f32 v186, v176, v186, v208
	v_fma_f32 v187, v176, v187, v209
	v_mul_f32_e32 v186, v175, v189
	v_fma_f32 v210, v174, v188, -v186
	v_fma_f32 v211, v175, v189, -v186
	v_mov_b32_e32 v212, v175
	v_mov_b32_e32 v213, v174
	v_mul_f32_e32 v186, v174, v189
	v_fma_f32 v212, v212, v188, v186
	v_fma_f32 v213, v213, v189, v186
	v_sub_f32_e32 v186, v190, v208
	v_mov_b32_e32 v188, v210
	v_mov_b32_e32 v189, v212
.LBB0_477:
	v_cvt_pk_bf16_f32 v182, v182, v183
	v_cvt_pk_bf16_f32 v183, v184, v185
	v_cvt_pk_bf16_f32 v184, v186, v187
	v_cvt_pk_bf16_f32 v185, v188, v189
	global_store_dwordx4 v[180:181], v[182:185], off offset:64
	v_mul_f32_e32 v180, v86, v86
	v_mul_f32_e32 v181, v87, v87
	s_nop 0
	v_mul_f32_e32 v182, v84, v84
	v_mul_f32_e32 v183, v85, v85
	v_mul_f32_e32 v141, v64, v64
	v_pk_mov_b32 v[184:185], v[182:183], v[180:181] op_sel:[1,0]
	v_mov_b32_e32 v183, v181
	v_add_f32_e32 v180, v184, v182
	v_add_f32_e32 v181, v185, v183
	v_mul_f32_e32 v182, v82, v82
	v_mul_f32_e32 v183, v83, v83
	v_mul_f32_e32 v184, v80, v80
	v_mul_f32_e32 v185, v81, v81
	v_mul_f32_e32 v149, v65, v65
	v_pk_mov_b32 v[186:187], v[184:185], v[182:183] op_sel:[1,0]
	v_mov_b32_e32 v185, v183
	v_add_f32_e32 v182, v186, v184
	v_add_f32_e32 v183, v187, v185
	v_pk_add_f32 v[180:181], v[180:181], v[180:181] op_sel:[0,1] op_sel_hi:[1,0]
	v_pk_add_f32 v[182:183], v[182:183], v[182:183] op_sel:[0,1] op_sel_hi:[1,0]
	v_mov_b32_e32 v181, v141
	v_mov_b32_e32 v183, v149
	v_add_f32_e32 v180, v180, v182
	v_add_f32_e32 v181, v181, v183
	v_mul_f32_e32 v182, v69, v69
	v_mul_f32_e32 v184, v71, v71
	v_mul_f32_e32 v153, v66, v66
	v_mul_f32_e32 v155, v67, v67
	v_fma_f32 v183, v69, v69, v182
	v_fma_f32 v182, v68, v68, v182
	v_fma_f32 v185, v71, v71, v184
	v_fma_f32 v184, v70, v70, v184
	v_mov_b32_e32 v183, v153
	v_mov_b32_e32 v185, v155
	v_mov_b32_e32 v147, v236
	v_add_f32_e32 v182, v182, v184
	v_add_f32_e32 v183, v183, v185
	s_and_b64 vcc, exec, s[36:37]
	v_add_f32_e32 v180, v180, v182
	v_add_f32_e32 v181, v181, v183
	v_lshlrev_b32_e32 v182, 3, v147
	v_ashrrev_i32_e32 v183, 31, v182
	v_lshl_add_u64 v[188:189], v[182:183], 2, s[38:39]
	global_load_dwordx4 v[182:185], v[188:189], off
	v_add_f32_e32 v141, v180, v181
	ds_swizzle_b32 v149, v141 offset:swizzle(SWAP,16)
	v_add_u32_e32 v180, 48, v140
	s_waitcnt lgkmcnt(0)
	v_add_f32_e32 v141, v141, v149
	v_mov_b32_e32 v149, v141
	s_nop 1
	v_permlane32_swap_b32_e32 v141, v149
	v_add_f32_e32 v141, v141, v149
	v_fmamk_f32 v141, v141, 0x3c800000, v193
	v_rsq_f32_e32 v186, v141
	v_bfe_u32 v141, v180, 6, 7
	v_cvt_f32_ubyte0_e32 v141, v141
	v_mul_f32_e32 v190, v84, v186
	v_mul_f32_e32 v191, v85, v186
	v_mul_f32_e32 v208, v86, v186
	v_mul_f32_e32 v209, v87, v186
	s_waitcnt vmcnt(0)
	v_mul_f32_e32 v182, v182, v190
	v_mul_f32_e32 v183, v183, v191
	v_mul_f32_e32 v184, v184, v208
	v_mul_f32_e32 v185, v185, v209
	s_cbranch_vccnz .LBB0_479
	v_mul_f32_e32 v147, v194, v141
	v_sin_f32_e32 v208, v147
	v_mul_f32_e32 v149, v237, v141
	v_cos_f32_e32 v190, v147
	v_sin_f32_e32 v211, v149
	v_cos_f32_e32 v210, v149
	v_mul_f32_e32 v209, v208, v182
	v_mul_f32_e32 v208, v208, v183
	v_mul_f32_e32 v212, v190, v182
	v_mul_f32_e32 v213, v190, v183
	v_fma_f32 v182, v190, v182, v208
	v_fma_f32 v183, v190, v183, v209
	v_mul_f32_e32 v182, v211, v185
	v_fma_f32 v190, v210, v184, -v182
	v_fma_f32 v191, v211, v185, -v182
	v_mov_b32_e32 v214, v211
	v_mov_b32_e32 v215, v210
	v_mul_f32_e32 v182, v210, v185
	v_fma_f32 v210, v214, v184, v182
	v_fma_f32 v211, v215, v185, v182
	v_sub_f32_e32 v182, v212, v208
	v_mov_b32_e32 v184, v190
	v_mov_b32_e32 v185, v210
; __device__ __forceinline__ unsigned cvt_pk_bf16(float lo, float hi) { const f32x2 v = {lo, hi}; const bf16x2_t b = __builtin_convertvector(v, bf16x2_t); return __builtin_bit_cast(unsigned, b); }
; template <int M> __device__ __forceinline__ float swz_xor(float v) { return __builtin_bit_cast(float, __builtin_amdgcn_ds_swizzle(__builtin_bit_cast(int, v), (M << 10) | 0x1f)); }
;     __device__ __forceinline__ void operator()(const f32x4 (&acc)[2][2][4][2], const Unit& u, int wr, int wc, int fr, int fq) const {
;     ...
;                     const int row = row0 + ai * HALF + m * 16;
;                     int fqo = fq; asm volatile("" : "+v"(fqo));
;                     f32x4 v[2][2]; float ss = 0.f;
; #pragma unroll
;                     for (int bj = 0; bj < 2; ++bj)
; #pragma unroll
;                         for (int n = 0; n < 2; ++n) { v[bj][n] = acc[ai][bj][m][n]; ss += (v[bj][n][0] * v[bj][n][0] + v[bj][n][1] * v[bj][n][1]) + (v[bj][n][2] * v[bj][n][2] + v[bj][n][3] * v[bj][n][3]); }
;                     ss += swz_xor<16>(ss); ss = xadd32(ss);
;                     const float rstd = __builtin_amdgcn_rsqf(ss * (1.0f / 64.0f) + EPS);
;                     const int t = row & (SEQ - 1); const float pos[2] = {(float)(t >> 6), (float)(t & 63)};
; #pragma unroll
;                     for (int bj = 0; bj < 2; ++bj) {
;                         u32x4 w;
; #pragma unroll
;                         for (int n = 0; n < 2; ++n) {
;                             f32x4 x = v[bj][n] * rstd * *(const f32x4*)(g + 32 * bj + 8 * fqo + 4 * n);
;                             if (latent) {
;                                 const float a0 = pos[bj] * fr0[n], a1 = pos[bj] * fr1[n];
;                                 const float c0 = __builtin_amdgcn_cosf(a0), s0 = __builtin_amdgcn_sinf(a0), c1 = __builtin_amdgcn_cosf(a1), s1 = __builtin_amdgcn_sinf(a1);
;                                 x = (f32x4){x[0] * c0 - x[1] * s0, x[1] * c0 + x[0] * s0, x[2] * c1 - x[3] * s1, x[3] * c1 + x[2] * s1};
;                             }
;                             if (n == 0) { w.x = cvt_pk_bf16(x[0], x[1]); w.y = cvt_pk_bf16(x[2], x[3]); } else { w.z = cvt_pk_bf16(x[0], x[1]); w.w = cvt_pk_bf16(x[2], x[3]); }
;                         }
;                         *(u32x4*)(dst + (size_t)row * 64 + 32 * bj + 8 * fq) = w;
;                     }
.LBB0_479:
	global_load_dwordx4 v[208:211], v[188:189], off offset:16
	v_mov_b32_e32 v187, v186
	v_mov_b32_e32 v190, v186
	v_mov_b32_e32 v191, v186
	v_mul_f32_e32 v212, v82, v190
	v_mul_f32_e32 v213, v83, v191
	v_mul_f32_e32 v214, v80, v186
	v_mul_f32_e32 v215, v81, v187
	s_and_b64 vcc, exec, s[36:37]
	s_waitcnt vmcnt(0)
	v_mul_f32_e32 v212, v212, v210
	v_mul_f32_e32 v213, v213, v211
	v_mul_f32_e32 v210, v214, v208
	v_mul_f32_e32 v211, v215, v209
	s_cbranch_vccnz .LBB0_481
	v_mul_f32_e32 v147, v238, v141
	v_sin_f32_e32 v214, v147
	v_mul_f32_e32 v141, v239, v141
	v_cos_f32_e32 v208, v147
	v_cos_f32_e32 v216, v141
	v_sin_f32_e32 v217, v141
	v_mul_f32_e32 v215, v214, v210
	v_mul_f32_e32 v214, v214, v211
	v_mul_f32_e32 v218, v208, v210
	v_mul_f32_e32 v219, v208, v211
	v_fma_f32 v210, v208, v210, v214
	v_fma_f32 v211, v208, v211, v215
	v_mul_f32_e32 v208, v217, v213
	v_mov_b32_e32 v220, v217
	v_mov_b32_e32 v221, v216
	v_mul_f32_e32 v210, v216, v213
	v_fma_f32 v209, v217, v213, -v208
	v_fma_f32 v208, v216, v212, -v208
	v_fma_f32 v216, v220, v212, v210
	v_fma_f32 v217, v221, v213, v210
	v_sub_f32_e32 v210, v218, v214
	v_mov_b32_e32 v212, v208
	v_mov_b32_e32 v213, v216
.LBB0_481:
	v_ashrrev_i32_e32 v181, 31, v180
	v_lshlrev_b64 v[180:181], 7, v[180:181]
	v_cvt_pk_bf16_f32 v182, v182, v183
	v_cvt_pk_bf16_f32 v183, v184, v185
	v_lshl_add_u64 v[208:209], v[142:143], 0, v[180:181]
	v_cvt_pk_bf16_f32 v184, v210, v211
	v_cvt_pk_bf16_f32 v185, v212, v213
	global_store_dwordx4 v[208:209], v[182:185], off
	global_load_dwordx4 v[180:183], v[188:189], off offset:128
	v_add_u32_e32 v141, 48, v235
	v_and_b32_e32 v141, 63, v141
	v_cvt_f32_ubyte0_e32 v141, v141
	v_mul_f32_e32 v184, v70, v190
	v_mul_f32_e32 v185, v71, v191
	v_mul_f32_e32 v190, v68, v186
	v_mul_f32_e32 v191, v69, v187
	v_mul_f32_e32 v147, v194, v141
	v_mul_f32_e32 v149, v237, v141
	s_and_b64 vcc, exec, s[36:37]
	s_waitcnt vmcnt(0)
	v_mul_f32_e32 v212, v184, v182
	v_mul_f32_e32 v213, v185, v183
	v_mul_f32_e32 v210, v190, v180
	v_mul_f32_e32 v211, v191, v181
	v_cos_f32_e32 v182, v147
	v_sin_f32_e32 v184, v147
	v_cos_f32_e32 v180, v149
	v_sin_f32_e32 v181, v149
	s_cbranch_vccnz .LBB0_483
	v_mul_f32_e32 v214, v184, v211
	v_mul_f32_e32 v215, v184, v210
	v_mul_f32_e32 v190, v182, v210
	v_mul_f32_e32 v191, v182, v211
	v_fma_f32 v210, v182, v210, v214
	v_fma_f32 v211, v182, v211, v215
	v_mul_f32_e32 v210, v181, v213
	v_fma_f32 v216, v180, v212, -v210
	v_fma_f32 v217, v181, v213, -v210
	v_mov_b32_e32 v218, v181
	v_mov_b32_e32 v219, v180
	v_mul_f32_e32 v210, v180, v213
	v_fma_f32 v218, v218, v212, v210
	v_fma_f32 v219, v219, v213, v210
	v_sub_f32_e32 v210, v190, v214
	v_mov_b32_e32 v212, v216
	v_mov_b32_e32 v213, v218
.LBB0_483:
	v_mov_b32_e32 v190, v186
	v_mov_b32_e32 v191, v186
	v_mul_f32_e32 v214, v64, v186
	v_mul_f32_e32 v215, v65, v187
	global_load_dwordx4 v[186:189], v[188:189], off offset:144
	v_mul_f32_e32 v190, v66, v190
	v_mul_f32_e32 v191, v67, v191
	v_mul_f32_e32 v147, v238, v141
	v_mul_f32_e32 v141, v239, v141
	s_and_b64 vcc, exec, s[36:37]
	s_waitcnt vmcnt(0)
	v_mul_f32_e32 v216, v190, v188
	v_mul_f32_e32 v217, v191, v189
	v_mul_f32_e32 v214, v214, v186
	v_mul_f32_e32 v215, v215, v187
	v_cos_f32_e32 v188, v147
	v_sin_f32_e32 v190, v147
	v_cos_f32_e32 v186, v141
	v_sin_f32_e32 v187, v141
	s_cbranch_vccnz .LBB0_485
	v_mul_f32_e32 v220, v190, v215
	v_mul_f32_e32 v221, v190, v214
	v_mul_f32_e32 v218, v188, v214
	v_mul_f32_e32 v219, v188, v215
	v_fma_f32 v214, v188, v214, v220
	v_fma_f32 v215, v188, v215, v221
	v_mul_f32_e32 v214, v187, v217
	v_fma_f32 v222, v186, v216, -v214
	v_fma_f32 v223, v187, v217, -v214
	v_mov_b32_e32 v226, v187
	v_mov_b32_e32 v227, v186
	v_mul_f32_e32 v214, v186, v217
	v_fma_f32 v226, v226, v216, v214
	v_fma_f32 v227, v227, v217, v214
	v_sub_f32_e32 v214, v218, v220
	v_mov_b32_e32 v216, v222
	v_mov_b32_e32 v217, v226
.LBB0_485:
	v_cvt_pk_bf16_f32 v210, v210, v211
	v_cvt_pk_bf16_f32 v211, v212, v213
	v_cvt_pk_bf16_f32 v212, v214, v215
	v_cvt_pk_bf16_f32 v213, v216, v217
	global_store_dwordx4 v[208:209], v[210:213], off offset:64
	v_mul_f32_e32 v208, v62, v62
	v_mul_f32_e32 v209, v63, v63
	s_nop 0
	v_mul_f32_e32 v212, v60, v60
	v_mul_f32_e32 v213, v61, v61
	v_mul_f32_e32 v141, v40, v40
	v_pk_mov_b32 v[214:215], v[212:213], v[208:209] op_sel:[1,0]
	v_mov_b32_e32 v213, v209
	v_add_f32_e32 v208, v214, v212
	v_add_f32_e32 v209, v215, v213
	v_mul_f32_e32 v212, v58, v58
	v_mul_f32_e32 v213, v59, v59
	v_mul_f32_e32 v214, v56, v56
	v_mul_f32_e32 v215, v57, v57
	v_mul_f32_e32 v149, v41, v41
	v_pk_mov_b32 v[216:217], v[214:215], v[212:213] op_sel:[1,0]
	v_mov_b32_e32 v215, v213
	v_add_f32_e32 v212, v216, v214
	v_add_f32_e32 v213, v217, v215
	v_pk_add_f32 v[208:209], v[208:209], v[208:209] op_sel:[0,1] op_sel_hi:[1,0]
	v_pk_add_f32 v[212:213], v[212:213], v[212:213] op_sel:[0,1] op_sel_hi:[1,0]
	v_mov_b32_e32 v209, v141
	v_mov_b32_e32 v213, v149
	v_add_f32_e32 v208, v208, v212
	v_add_f32_e32 v209, v209, v213
	v_mul_f32_e32 v212, v45, v45
	v_mul_f32_e32 v214, v47, v47
	v_mul_f32_e32 v153, v42, v42
	v_mul_f32_e32 v155, v43, v43
	v_fma_f32 v213, v45, v45, v212
	v_fma_f32 v212, v44, v44, v212
	v_fma_f32 v215, v47, v47, v214
	v_fma_f32 v214, v46, v46, v214
	v_mov_b32_e32 v213, v153
	v_mov_b32_e32 v215, v155
	v_mov_b32_e32 v147, v236
	v_add_f32_e32 v212, v212, v214
	v_add_f32_e32 v213, v213, v215
	v_add_u32_e32 v210, 0x80, v140
	v_add_f32_e32 v208, v208, v212
	v_add_f32_e32 v209, v209, v213
	v_lshlrev_b32_e32 v212, 3, v147
	v_ashrrev_i32_e32 v213, 31, v212
	v_lshl_add_u64 v[212:213], v[212:213], 2, s[38:39]
	global_load_dwordx4 v[214:217], v[212:213], off
	v_add_f32_e32 v141, v208, v209
	ds_swizzle_b32 v149, v141 offset:swizzle(SWAP,16)
	s_and_b64 vcc, exec, s[36:37]
	s_waitcnt lgkmcnt(0)
	v_add_f32_e32 v141, v141, v149
	v_mov_b32_e32 v149, v141
	s_nop 1
	v_permlane32_swap_b32_e32 v141, v149
	v_add_f32_e32 v141, v141, v149
	v_fmamk_f32 v141, v141, 0x3c800000, v193
	v_rsq_f32_e32 v208, v141
	v_bfe_u32 v141, v210, 6, 7
	v_cvt_f32_ubyte0_e32 v141, v141
	v_mul_f32_e32 v218, v60, v208
	v_mul_f32_e32 v219, v61, v208
	v_mul_f32_e32 v220, v62, v208
	v_mul_f32_e32 v221, v63, v208
	s_waitcnt vmcnt(0)
	v_mul_f32_e32 v214, v214, v218
	v_mul_f32_e32 v215, v215, v219
	v_mul_f32_e32 v216, v216, v220
	v_mul_f32_e32 v217, v217, v221
	s_cbranch_vccnz .LBB0_487
	v_mul_f32_e32 v147, v194, v141
	v_sin_f32_e32 v220, v147
	v_mul_f32_e32 v149, v237, v141
	v_cos_f32_e32 v218, v147
	v_sin_f32_e32 v223, v149
	v_cos_f32_e32 v222, v149
	v_mul_f32_e32 v221, v220, v214
	v_mul_f32_e32 v220, v220, v215
	v_mul_f32_e32 v226, v218, v214
	v_mul_f32_e32 v227, v218, v215
	v_fma_f32 v214, v218, v214, v220
	v_fma_f32 v215, v218, v215, v221
	v_mul_f32_e32 v214, v223, v217
	v_fma_f32 v218, v222, v216, -v214
	v_fma_f32 v219, v223, v217, -v214
	v_mov_b32_e32 v228, v223
	v_mov_b32_e32 v229, v222
	v_mul_f32_e32 v214, v222, v217
	v_fma_f32 v222, v228, v216, v214
	v_fma_f32 v223, v229, v217, v214
	v_sub_f32_e32 v214, v226, v220
	v_mov_b32_e32 v216, v218
	v_mov_b32_e32 v217, v222
; __device__ __forceinline__ unsigned cvt_pk_bf16(float lo, float hi) { const f32x2 v = {lo, hi}; const bf16x2_t b = __builtin_convertvector(v, bf16x2_t); return __builtin_bit_cast(unsigned, b); }
;     __device__ __forceinline__ void operator()(const f32x4 (&acc)[2][2][4][2], const Unit& u, int wr, int wc, int fr, int fq) const {
;     ...
;             for (int ai = 0; ai < 2; ++ai)
; #pragma unroll
;                 for (int m = 0; m < 4; ++m) {
;                     const int row = row0 + ai * HALF + m * 16;
;                     int fqo = fq; asm volatile("" : "+v"(fqo));
;                     f32x4 v[2][2]; float ss = 0.f;
; #pragma unroll
;                     for (int bj = 0; bj < 2; ++bj)
; #pragma unroll
;                         for (int n = 0; n < 2; ++n) { v[bj][n] = acc[ai][bj][m][n]; ss += (v[bj][n][0] * v[bj][n][0] + v[bj][n][1] * v[bj][n][1]) + (v[bj][n][2] * v[bj][n][2] + v[bj][n][3] * v[bj][n][3]); }
;                     ss += swz_xor<16>(ss); ss = xadd32(ss);
;                     const float rstd = __builtin_amdgcn_rsqf(ss * (1.0f / 64.0f) + EPS);
;                     const int t = row & (SEQ - 1); const float pos[2] = {(float)(t >> 6), (float)(t & 63)};
; #pragma unroll
;                     for (int bj = 0; bj < 2; ++bj) {
;                         u32x4 w;
; #pragma unroll
;                         for (int n = 0; n < 2; ++n) {
;                             f32x4 x = v[bj][n] * rstd * *(const f32x4*)(g + 32 * bj + 8 * fqo + 4 * n);
;                             if (latent) {
;                                 const float a0 = pos[bj] * fr0[n], a1 = pos[bj] * fr1[n];
;                                 const float c0 = __builtin_amdgcn_cosf(a0), s0 = __builtin_amdgcn_sinf(a0), c1 = __builtin_amdgcn_cosf(a1), s1 = __builtin_amdgcn_sinf(a1);
;                                 x = (f32x4){x[0] * c0 - x[1] * s0, x[1] * c0 + x[0] * s0, x[2] * c1 - x[3] * s1, x[3] * c1 + x[2] * s1};
;                             }
;                             if (n == 0) { w.x = cvt_pk_bf16(x[0], x[1]); w.y = cvt_pk_bf16(x[2], x[3]); } else { w.z = cvt_pk_bf16(x[0], x[1]); w.w = cvt_pk_bf16(x[2], x[3]); }
;                         }
;                         *(u32x4*)(dst + (size_t)row * 64 + 32 * bj + 8 * fq) = w;
;                     }
.LBB0_487:
	global_load_dwordx4 v[220:223], v[212:213], off offset:16
	v_mov_b32_e32 v209, v208
	v_mov_b32_e32 v218, v208
	v_mov_b32_e32 v219, v208
	v_mul_f32_e32 v226, v58, v218
	v_mul_f32_e32 v227, v59, v219
	v_mul_f32_e32 v228, v56, v208
	v_mul_f32_e32 v229, v57, v209
	s_and_b64 vcc, exec, s[36:37]
	s_waitcnt vmcnt(0)
	v_mul_f32_e32 v222, v226, v222
	v_mul_f32_e32 v223, v227, v223
	v_mul_f32_e32 v220, v228, v220
	v_mul_f32_e32 v221, v229, v221
	s_cbranch_vccnz .LBB0_489
	v_mul_f32_e32 v147, v238, v141
	v_sin_f32_e32 v228, v147
	v_mul_f32_e32 v141, v239, v141
	v_cos_f32_e32 v226, v147
	v_sin_f32_e32 v241, v141
	v_cos_f32_e32 v240, v141
	v_mul_f32_e32 v229, v228, v220
	v_mul_f32_e32 v228, v228, v221
	v_mul_f32_e32 v242, v226, v220
	v_mul_f32_e32 v243, v226, v221
	v_fma_f32 v220, v226, v220, v228
	v_fma_f32 v221, v226, v221, v229
	v_mul_f32_e32 v220, v241, v223
	v_fma_f32 v226, v240, v222, -v220
	v_fma_f32 v227, v241, v223, -v220
	v_mov_b32_e32 v244, v241
	v_mov_b32_e32 v245, v240
	v_mul_f32_e32 v220, v240, v223
	v_fma_f32 v240, v244, v222, v220
	v_fma_f32 v241, v245, v223, v220
	v_sub_f32_e32 v220, v242, v228
	v_mov_b32_e32 v222, v226
	v_mov_b32_e32 v223, v240
.LBB0_489:
	v_ashrrev_i32_e32 v211, 31, v210
	v_lshlrev_b64 v[210:211], 7, v[210:211]
	v_cvt_pk_bf16_f32 v214, v214, v215
	v_cvt_pk_bf16_f32 v215, v216, v217
	v_lshl_add_u64 v[210:211], v[142:143], 0, v[210:211]
	v_cvt_pk_bf16_f32 v216, v220, v221
	v_cvt_pk_bf16_f32 v217, v222, v223
	global_store_dwordx4 v[210:211], v[214:217], off
	global_load_dwordx4 v[214:217], v[212:213], off offset:128
	v_mul_f32_e32 v218, v46, v218
	v_mul_f32_e32 v219, v47, v219
	v_mul_f32_e32 v220, v44, v208
	v_mul_f32_e32 v221, v45, v209
	s_and_b64 vcc, exec, s[36:37]
	s_waitcnt vmcnt(0)
	v_mul_f32_e32 v216, v218, v216
	v_mul_f32_e32 v217, v219, v217
	v_mul_f32_e32 v214, v220, v214
	v_mul_f32_e32 v215, v221, v215
	s_cbranch_vccnz .LBB0_491
	v_mul_f32_e32 v149, v148, v214
	v_mul_f32_e32 v148, v148, v215
	v_mul_f32_e32 v218, v146, v214
	v_mul_f32_e32 v219, v146, v215
	v_fma_f32 v214, v146, v214, v148
	v_fma_f32 v215, v146, v215, v149
	v_mul_f32_e32 v146, v145, v217
	v_fma_f32 v147, v145, v217, -v146
	v_fma_f32 v146, v144, v216, -v146
	v_mov_b32_e32 v220, v145
	v_mov_b32_e32 v221, v144
	v_mul_f32_e32 v144, v144, v217
	v_fma_f32 v145, v221, v217, v144
	v_fma_f32 v144, v220, v216, v144
	v_sub_f32_e32 v214, v218, v148
	v_mov_b32_e32 v216, v146
	v_mov_b32_e32 v217, v144
.LBB0_491:
	global_load_dwordx4 v[144:147], v[212:213], off offset:144
	v_mov_b32_e32 v148, v208
	v_mov_b32_e32 v149, v208
	v_mul_f32_e32 v208, v40, v208
	v_mul_f32_e32 v209, v41, v209
	v_mul_f32_e32 v148, v42, v148
	v_mul_f32_e32 v149, v43, v149
	s_and_b64 vcc, exec, s[36:37]
	s_waitcnt vmcnt(0)
	v_mul_f32_e32 v146, v148, v146
	v_mul_f32_e32 v147, v149, v147
	v_mul_f32_e32 v144, v208, v144
	v_mul_f32_e32 v145, v209, v145
	s_cbranch_vccnz .LBB0_493
	v_mul_f32_e32 v155, v154, v144
	v_mul_f32_e32 v154, v154, v145
	v_mul_f32_e32 v148, v152, v144
	v_mul_f32_e32 v149, v152, v145
	v_fma_f32 v144, v152, v144, v154
	v_fma_f32 v145, v152, v145, v155
	v_mul_f32_e32 v144, v151, v147
	v_fma_f32 v152, v150, v146, -v144
	v_fma_f32 v153, v151, v147, -v144
	v_mov_b32_e32 v208, v151
	v_mov_b32_e32 v209, v150
	v_mul_f32_e32 v144, v150, v147
	v_fma_f32 v150, v208, v146, v144
	v_fma_f32 v151, v209, v147, v144
	v_sub_f32_e32 v144, v148, v154
	v_mov_b32_e32 v146, v152
	v_mov_b32_e32 v147, v150
.LBB0_493:
	v_cvt_pk_bf16_f32 v148, v214, v215
	v_cvt_pk_bf16_f32 v149, v216, v217
	v_cvt_pk_bf16_f32 v150, v144, v145
	v_cvt_pk_bf16_f32 v151, v146, v147
	global_store_dwordx4 v[210:211], v[148:151], off offset:64
	v_mul_f32_e32 v144, v54, v54
	v_mul_f32_e32 v145, v55, v55
	v_mul_f32_e32 v146, v52, v52
	v_mul_f32_e32 v147, v53, v53
	v_mul_f32_e32 v141, v24, v24
	v_pk_mov_b32 v[148:149], v[146:147], v[144:145] op_sel:[1,0]
	v_mov_b32_e32 v147, v145
	v_add_f32_e32 v144, v148, v146
	v_add_f32_e32 v145, v149, v147
	v_mul_f32_e32 v146, v50, v50
	v_mul_f32_e32 v147, v51, v51
	v_mul_f32_e32 v148, v48, v48
	v_mul_f32_e32 v149, v49, v49
	v_pk_add_f32 v[144:145], v[144:145], v[144:145] op_sel:[0,1] op_sel_hi:[1,0]
	v_pk_mov_b32 v[150:151], v[148:149], v[146:147] op_sel:[1,0]
	v_mov_b32_e32 v149, v147
	v_add_f32_e32 v146, v150, v148
	v_add_f32_e32 v147, v151, v149
	v_mul_f32_e32 v148, v25, v25
	v_pk_add_f32 v[146:147], v[146:147], v[146:147] op_sel:[0,1] op_sel_hi:[1,0]
	v_mov_b32_e32 v145, v141
	v_mov_b32_e32 v147, v148
	v_add_f32_e32 v144, v144, v146
	v_add_f32_e32 v145, v145, v147
	v_mul_f32_e32 v146, v29, v29
	v_mul_f32_e32 v149, v26, v26
	v_fma_f32 v147, v29, v29, v146
	v_fma_f32 v146, v28, v28, v146
	v_mul_f32_e32 v148, v31, v31
	v_mul_f32_e32 v150, v27, v27
	v_mov_b32_e32 v147, v149
	v_fma_f32 v149, v31, v31, v148
	v_fma_f32 v148, v30, v30, v148
	v_mov_b32_e32 v152, v236
	v_mov_b32_e32 v149, v150
	v_add_f32_e32 v146, v146, v148
	v_add_f32_e32 v147, v147, v149
	v_lshlrev_b32_e32 v148, 3, v152
	v_ashrrev_i32_e32 v149, 31, v148
	v_lshl_add_u64 v[148:149], v[148:149], 2, s[38:39]
	global_load_dwordx4 v[150:153], v[148:149], off
	v_add_f32_e32 v144, v144, v146
	v_add_f32_e32 v145, v145, v147
	v_add_u32_e32 v146, 0x90, v140
	v_add_f32_e32 v141, v144, v145
	ds_swizzle_b32 v144, v141 offset:swizzle(SWAP,16)
	s_and_b64 vcc, exec, s[36:37]
	s_waitcnt lgkmcnt(0)
	v_add_f32_e32 v141, v141, v144
	v_mov_b32_e32 v144, v141
	s_nop 1
	v_permlane32_swap_b32_e32 v141, v144
	v_add_f32_e32 v141, v141, v144
	v_fmamk_f32 v141, v141, 0x3c800000, v193
	v_rsq_f32_e32 v144, v141
	v_bfe_u32 v141, v146, 6, 7
	v_cvt_f32_ubyte0_e32 v141, v141
	v_mul_f32_e32 v154, v52, v144
	v_mul_f32_e32 v155, v53, v144
	v_mul_f32_e32 v208, v54, v144
	v_mul_f32_e32 v209, v55, v144
	s_waitcnt vmcnt(0)
	v_mul_f32_e32 v150, v150, v154
	v_mul_f32_e32 v151, v151, v155
	v_mul_f32_e32 v152, v152, v208
	v_mul_f32_e32 v153, v153, v209
	s_cbranch_vccnz .LBB0_495
	v_mul_f32_e32 v145, v194, v141
	v_sin_f32_e32 v208, v145
	v_mul_f32_e32 v147, v237, v141
	v_cos_f32_e32 v154, v145
	v_sin_f32_e32 v211, v147
	v_cos_f32_e32 v210, v147
	v_mul_f32_e32 v209, v208, v150
	v_mul_f32_e32 v208, v208, v151
	v_mul_f32_e32 v212, v154, v150
	v_mul_f32_e32 v213, v154, v151
	v_fma_f32 v150, v154, v150, v208
	v_fma_f32 v151, v154, v151, v209
	v_mul_f32_e32 v150, v211, v153
	v_fma_f32 v154, v210, v152, -v150
	v_fma_f32 v155, v211, v153, -v150
	v_mov_b32_e32 v214, v211
	v_mov_b32_e32 v215, v210
	v_mul_f32_e32 v150, v210, v153
	v_fma_f32 v210, v214, v152, v150
	v_fma_f32 v211, v215, v153, v150
	v_sub_f32_e32 v150, v212, v208
	v_mov_b32_e32 v152, v154
	v_mov_b32_e32 v153, v210
; __device__ __forceinline__ unsigned cvt_pk_bf16(float lo, float hi) { const f32x2 v = {lo, hi}; const bf16x2_t b = __builtin_convertvector(v, bf16x2_t); return __builtin_bit_cast(unsigned, b); }
;     __device__ __forceinline__ void operator()(const f32x4 (&acc)[2][2][4][2], const Unit& u, int wr, int wc, int fr, int fq) const {
;     ...
;             for (int ai = 0; ai < 2; ++ai)
; #pragma unroll
;                 for (int m = 0; m < 4; ++m) {
;                     const int row = row0 + ai * HALF + m * 16;
;                     int fqo = fq; asm volatile("" : "+v"(fqo));
;                     f32x4 v[2][2]; float ss = 0.f;
; #pragma unroll
;                     for (int bj = 0; bj < 2; ++bj)
; #pragma unroll
;                         for (int n = 0; n < 2; ++n) { v[bj][n] = acc[ai][bj][m][n]; ss += (v[bj][n][0] * v[bj][n][0] + v[bj][n][1] * v[bj][n][1]) + (v[bj][n][2] * v[bj][n][2] + v[bj][n][3] * v[bj][n][3]); }
;                     ss += swz_xor<16>(ss); ss = xadd32(ss);
;                     const float rstd = __builtin_amdgcn_rsqf(ss * (1.0f / 64.0f) + EPS);
;                     const int t = row & (SEQ - 1); const float pos[2] = {(float)(t >> 6), (float)(t & 63)};
; #pragma unroll
;                     for (int bj = 0; bj < 2; ++bj) {
;                         u32x4 w;
; #pragma unroll
;                         for (int n = 0; n < 2; ++n) {
;                             f32x4 x = v[bj][n] * rstd * *(const f32x4*)(g + 32 * bj + 8 * fqo + 4 * n);
;                             if (latent) {
;                                 const float a0 = pos[bj] * fr0[n], a1 = pos[bj] * fr1[n];
;                                 const float c0 = __builtin_amdgcn_cosf(a0), s0 = __builtin_amdgcn_sinf(a0), c1 = __builtin_amdgcn_cosf(a1), s1 = __builtin_amdgcn_sinf(a1);
;                                 x = (f32x4){x[0] * c0 - x[1] * s0, x[1] * c0 + x[0] * s0, x[2] * c1 - x[3] * s1, x[3] * c1 + x[2] * s1};
;                             }
;                             if (n == 0) { w.x = cvt_pk_bf16(x[0], x[1]); w.y = cvt_pk_bf16(x[2], x[3]); } else { w.z = cvt_pk_bf16(x[0], x[1]); w.w = cvt_pk_bf16(x[2], x[3]); }
;                         }
;                         *(u32x4*)(dst + (size_t)row * 64 + 32 * bj + 8 * fq) = w;
;                     }
.LBB0_495:
	global_load_dwordx4 v[208:211], v[148:149], off offset:16
	v_mov_b32_e32 v145, v144
	v_mov_b32_e32 v154, v144
	v_mov_b32_e32 v155, v144
	v_mul_f32_e32 v212, v50, v154
	v_mul_f32_e32 v213, v51, v155
	v_mul_f32_e32 v214, v48, v144
	v_mul_f32_e32 v215, v49, v145
	s_and_b64 vcc, exec, s[36:37]
	s_waitcnt vmcnt(0)
	v_mul_f32_e32 v210, v212, v210
	v_mul_f32_e32 v211, v213, v211
	v_mul_f32_e32 v208, v214, v208
	v_mul_f32_e32 v209, v215, v209
	s_cbranch_vccnz .LBB0_497
	v_mul_f32_e32 v147, v238, v141
	v_sin_f32_e32 v214, v147
	v_mul_f32_e32 v141, v239, v141
	v_cos_f32_e32 v212, v147
	v_sin_f32_e32 v217, v141
	v_cos_f32_e32 v216, v141
	v_mul_f32_e32 v215, v214, v208
	v_mul_f32_e32 v214, v214, v209
	v_mul_f32_e32 v218, v212, v208
	v_mul_f32_e32 v219, v212, v209
	v_fma_f32 v208, v212, v208, v214
	v_fma_f32 v209, v212, v209, v215
	v_mul_f32_e32 v208, v217, v211
	v_fma_f32 v212, v216, v210, -v208
	v_fma_f32 v213, v217, v211, -v208
	v_mov_b32_e32 v220, v217
	v_mov_b32_e32 v221, v216
	v_mul_f32_e32 v208, v216, v211
	v_fma_f32 v216, v220, v210, v208
	v_fma_f32 v217, v221, v211, v208
	v_sub_f32_e32 v208, v218, v214
	v_mov_b32_e32 v210, v212
	v_mov_b32_e32 v211, v216
.LBB0_497:
	v_ashrrev_i32_e32 v147, 31, v146
	v_lshlrev_b64 v[146:147], 7, v[146:147]
	v_cvt_pk_bf16_f32 v150, v150, v151
	v_cvt_pk_bf16_f32 v151, v152, v153
	v_lshl_add_u64 v[146:147], v[142:143], 0, v[146:147]
	v_cvt_pk_bf16_f32 v152, v208, v209
	v_cvt_pk_bf16_f32 v153, v210, v211
	global_store_dwordx4 v[146:147], v[150:153], off
	global_load_dwordx4 v[150:153], v[148:149], off offset:128
	v_mul_f32_e32 v154, v30, v154
	v_mul_f32_e32 v155, v31, v155
	v_mul_f32_e32 v208, v28, v144
	v_mul_f32_e32 v209, v29, v145
	s_and_b64 vcc, exec, s[36:37]
	s_waitcnt vmcnt(0)
	v_mul_f32_e32 v152, v154, v152
	v_mul_f32_e32 v153, v155, v153
	v_mul_f32_e32 v150, v208, v150
	v_mul_f32_e32 v151, v209, v151
	s_cbranch_vccnz .LBB0_499
	v_mul_f32_e32 v161, v160, v150
	v_mul_f32_e32 v160, v160, v151
	v_mul_f32_e32 v154, v158, v150
	v_mul_f32_e32 v155, v158, v151
	v_fma_f32 v150, v158, v150, v160
	v_fma_f32 v151, v158, v151, v161
	v_mul_f32_e32 v150, v157, v153
	v_fma_f32 v158, v156, v152, -v150
	v_fma_f32 v159, v157, v153, -v150
	v_mov_b32_e32 v208, v157
	v_mov_b32_e32 v209, v156
	v_mul_f32_e32 v150, v156, v153
	v_fma_f32 v156, v208, v152, v150
	v_fma_f32 v157, v209, v153, v150
	v_sub_f32_e32 v150, v154, v160
	v_mov_b32_e32 v152, v158
	v_mov_b32_e32 v153, v156
.LBB0_499:
	global_load_dwordx4 v[154:157], v[148:149], off offset:144
	v_mov_b32_e32 v148, v144
	v_mov_b32_e32 v149, v144
	v_mul_f32_e32 v144, v24, v144
	v_mul_f32_e32 v145, v25, v145
	v_mul_f32_e32 v148, v26, v148
	v_mul_f32_e32 v149, v27, v149
	s_and_b64 vcc, exec, s[36:37]
	s_waitcnt vmcnt(0)
	v_mul_f32_e32 v148, v148, v156
	v_mul_f32_e32 v149, v149, v157
	v_mul_f32_e32 v144, v144, v154
	v_mul_f32_e32 v145, v145, v155
	s_cbranch_vccnz .LBB0_501
	v_mul_f32_e32 v156, v166, v145
	v_mul_f32_e32 v157, v166, v144
	v_mul_f32_e32 v154, v164, v144
	v_mul_f32_e32 v155, v164, v145
	v_fma_f32 v144, v164, v144, v156
	v_fma_f32 v145, v164, v145, v157
	v_mul_f32_e32 v144, v163, v149
	v_fma_f32 v158, v162, v148, -v144
	v_fma_f32 v159, v163, v149, -v144
	v_mov_b32_e32 v160, v163
	v_mov_b32_e32 v161, v162
	v_mul_f32_e32 v144, v162, v149
	v_fma_f32 v160, v160, v148, v144
	v_fma_f32 v161, v161, v149, v144
	v_sub_f32_e32 v144, v154, v156
	v_mov_b32_e32 v148, v158
	v_mov_b32_e32 v149, v160
.LBB0_501:
	v_cvt_pk_bf16_f32 v150, v150, v151
	v_cvt_pk_bf16_f32 v151, v152, v153
	v_cvt_pk_bf16_f32 v152, v144, v145
	v_cvt_pk_bf16_f32 v153, v148, v149
	global_store_dwordx4 v[146:147], v[150:153], off offset:64
	v_mul_f32_e32 v144, v38, v38
	v_mul_f32_e32 v145, v39, v39
	v_mul_f32_e32 v146, v36, v36
	v_mul_f32_e32 v147, v37, v37
	v_mul_f32_e32 v141, v8, v8
	v_pk_mov_b32 v[148:149], v[146:147], v[144:145] op_sel:[1,0]
	v_mov_b32_e32 v147, v145
	v_add_f32_e32 v144, v148, v146
	v_add_f32_e32 v145, v149, v147
	v_mul_f32_e32 v146, v34, v34
	v_mul_f32_e32 v147, v35, v35
	v_mul_f32_e32 v148, v32, v32
	v_mul_f32_e32 v149, v33, v33
	v_pk_add_f32 v[144:145], v[144:145], v[144:145] op_sel:[0,1] op_sel_hi:[1,0]
	v_pk_mov_b32 v[150:151], v[148:149], v[146:147] op_sel:[1,0]
	v_mov_b32_e32 v149, v147
	v_add_f32_e32 v146, v150, v148
	v_add_f32_e32 v147, v151, v149
	v_mul_f32_e32 v148, v9, v9
	v_pk_add_f32 v[146:147], v[146:147], v[146:147] op_sel:[0,1] op_sel_hi:[1,0]
	v_mov_b32_e32 v145, v141
	v_mov_b32_e32 v147, v148
	v_add_f32_e32 v144, v144, v146
	v_add_f32_e32 v145, v145, v147
	v_mul_f32_e32 v146, v13, v13
	v_mul_f32_e32 v149, v10, v10
	v_fma_f32 v147, v13, v13, v146
	v_fma_f32 v146, v12, v12, v146
	v_mul_f32_e32 v148, v15, v15
	v_mul_f32_e32 v150, v11, v11
	v_mov_b32_e32 v147, v149
	v_fma_f32 v149, v15, v15, v148
	v_fma_f32 v148, v14, v14, v148
	v_mov_b32_e32 v152, v236
	v_mov_b32_e32 v149, v150
	v_add_f32_e32 v146, v146, v148
	v_add_f32_e32 v147, v147, v149
	v_lshlrev_b32_e32 v148, 3, v152
	v_ashrrev_i32_e32 v149, 31, v148
	v_lshl_add_u64 v[148:149], v[148:149], 2, s[38:39]
	global_load_dwordx4 v[150:153], v[148:149], off
	v_add_f32_e32 v144, v144, v146
	v_add_f32_e32 v145, v145, v147
	v_add_u32_e32 v146, 0xa0, v140
	v_add_f32_e32 v141, v144, v145
	ds_swizzle_b32 v144, v141 offset:swizzle(SWAP,16)
	s_and_b64 vcc, exec, s[36:37]
	s_waitcnt lgkmcnt(0)
	v_add_f32_e32 v141, v141, v144
	v_mov_b32_e32 v144, v141
	s_nop 1
	v_permlane32_swap_b32_e32 v141, v144
	v_add_f32_e32 v141, v141, v144
	v_fmamk_f32 v141, v141, 0x3c800000, v193
	v_rsq_f32_e32 v144, v141
	v_bfe_u32 v141, v146, 6, 7
	v_cvt_f32_ubyte0_e32 v141, v141
	v_mul_f32_e32 v154, v36, v144
	v_mul_f32_e32 v155, v37, v144
	v_mul_f32_e32 v156, v38, v144
	v_mul_f32_e32 v157, v39, v144
	s_waitcnt vmcnt(0)
	v_mul_f32_e32 v150, v150, v154
	v_mul_f32_e32 v151, v151, v155
	v_mul_f32_e32 v152, v152, v156
	v_mul_f32_e32 v153, v153, v157
	s_cbranch_vccnz .LBB0_503
	v_mul_f32_e32 v145, v194, v141
	v_sin_f32_e32 v156, v145
	v_mul_f32_e32 v147, v237, v141
	v_cos_f32_e32 v154, v145
	v_sin_f32_e32 v159, v147
	v_cos_f32_e32 v158, v147
	v_mul_f32_e32 v157, v156, v150
	v_mul_f32_e32 v156, v156, v151
	v_mul_f32_e32 v160, v154, v150
	v_mul_f32_e32 v161, v154, v151
	v_fma_f32 v150, v154, v150, v156
	v_fma_f32 v151, v154, v151, v157
	v_mul_f32_e32 v150, v159, v153
	v_fma_f32 v154, v158, v152, -v150
	v_fma_f32 v155, v159, v153, -v150
	v_mov_b32_e32 v162, v159
	v_mov_b32_e32 v163, v158
	v_mul_f32_e32 v150, v158, v153
	v_fma_f32 v158, v162, v152, v150
	v_fma_f32 v159, v163, v153, v150
	v_sub_f32_e32 v150, v160, v156
	v_mov_b32_e32 v152, v154
	v_mov_b32_e32 v153, v158
; __device__ __forceinline__ unsigned cvt_pk_bf16(float lo, float hi) { const f32x2 v = {lo, hi}; const bf16x2_t b = __builtin_convertvector(v, bf16x2_t); return __builtin_bit_cast(unsigned, b); }
;     __device__ __forceinline__ void operator()(const f32x4 (&acc)[2][2][4][2], const Unit& u, int wr, int wc, int fr, int fq) const {
;     ...
;                     for (int bj = 0; bj < 2; ++bj) {
;                         u32x4 w;
; #pragma unroll
;                         for (int n = 0; n < 2; ++n) {
;                             f32x4 x = v[bj][n] * rstd * *(const f32x4*)(g + 32 * bj + 8 * fqo + 4 * n);
;                             if (latent) {
;                                 const float a0 = pos[bj] * fr0[n], a1 = pos[bj] * fr1[n];
;                                 const float c0 = __builtin_amdgcn_cosf(a0), s0 = __builtin_amdgcn_sinf(a0), c1 = __builtin_amdgcn_cosf(a1), s1 = __builtin_amdgcn_sinf(a1);
;                                 x = (f32x4){x[0] * c0 - x[1] * s0, x[1] * c0 + x[0] * s0, x[2] * c1 - x[3] * s1, x[3] * c1 + x[2] * s1};
;                             }
;                             if (n == 0) { w.x = cvt_pk_bf16(x[0], x[1]); w.y = cvt_pk_bf16(x[2], x[3]); } else { w.z = cvt_pk_bf16(x[0], x[1]); w.w = cvt_pk_bf16(x[2], x[3]); }
;                         }
;                         *(u32x4*)(dst + (size_t)row * 64 + 32 * bj + 8 * fq) = w;
;                     }
.LBB0_503:
	global_load_dwordx4 v[156:159], v[148:149], off offset:16
	v_mov_b32_e32 v145, v144
	v_mov_b32_e32 v154, v144
	v_mov_b32_e32 v155, v144
	v_mul_f32_e32 v160, v34, v154
	v_mul_f32_e32 v161, v35, v155
	v_mul_f32_e32 v162, v32, v144
	v_mul_f32_e32 v163, v33, v145
	s_and_b64 vcc, exec, s[36:37]
	s_waitcnt vmcnt(0)
	v_mul_f32_e32 v158, v160, v158
	v_mul_f32_e32 v159, v161, v159
	v_mul_f32_e32 v156, v162, v156
	v_mul_f32_e32 v157, v163, v157
	s_cbranch_vccnz .LBB0_505
	v_mul_f32_e32 v147, v238, v141
	v_sin_f32_e32 v162, v147
	v_mul_f32_e32 v141, v239, v141
	v_cos_f32_e32 v160, v147
	v_sin_f32_e32 v165, v141
	v_cos_f32_e32 v164, v141
	v_mul_f32_e32 v163, v162, v156
	v_mul_f32_e32 v162, v162, v157
	v_mul_f32_e32 v166, v160, v156
	v_mul_f32_e32 v167, v160, v157
	v_fma_f32 v156, v160, v156, v162
	v_fma_f32 v157, v160, v157, v163
	v_mul_f32_e32 v156, v165, v159
	v_fma_f32 v160, v164, v158, -v156
	v_fma_f32 v161, v165, v159, -v156
	v_mov_b32_e32 v208, v165
	v_mov_b32_e32 v209, v164
	v_mul_f32_e32 v156, v164, v159
	v_fma_f32 v164, v208, v158, v156
	v_fma_f32 v165, v209, v159, v156
	v_sub_f32_e32 v156, v166, v162
	v_mov_b32_e32 v158, v160
	v_mov_b32_e32 v159, v164
.LBB0_505:
	v_ashrrev_i32_e32 v147, 31, v146
	v_lshlrev_b64 v[146:147], 7, v[146:147]
	v_cvt_pk_bf16_f32 v150, v150, v151
	v_cvt_pk_bf16_f32 v151, v152, v153
	v_lshl_add_u64 v[146:147], v[142:143], 0, v[146:147]
	v_cvt_pk_bf16_f32 v152, v156, v157
	v_cvt_pk_bf16_f32 v153, v158, v159
	global_store_dwordx4 v[146:147], v[150:153], off
	global_load_dwordx4 v[150:153], v[148:149], off offset:128
	v_mul_f32_e32 v154, v14, v154
	v_mul_f32_e32 v155, v15, v155
	v_mul_f32_e32 v156, v12, v144
	v_mul_f32_e32 v157, v13, v145
	s_and_b64 vcc, exec, s[36:37]
	s_waitcnt vmcnt(0)
	v_mul_f32_e32 v152, v154, v152
	v_mul_f32_e32 v153, v155, v153
	v_mul_f32_e32 v150, v156, v150
	v_mul_f32_e32 v151, v157, v151
	s_cbranch_vccnz .LBB0_507
	v_mul_f32_e32 v156, v172, v151
	v_mul_f32_e32 v157, v172, v150
	v_mul_f32_e32 v154, v170, v150
	v_mul_f32_e32 v155, v170, v151
	v_fma_f32 v150, v170, v150, v156
	v_fma_f32 v151, v170, v151, v157
	v_mul_f32_e32 v150, v169, v153
	v_fma_f32 v158, v168, v152, -v150
	v_fma_f32 v159, v169, v153, -v150
	v_mov_b32_e32 v160, v169
	v_mov_b32_e32 v161, v168
	v_mul_f32_e32 v150, v168, v153
	v_fma_f32 v160, v160, v152, v150
	v_fma_f32 v161, v161, v153, v150
	v_sub_f32_e32 v150, v154, v156
	v_mov_b32_e32 v152, v158
	v_mov_b32_e32 v153, v160
.LBB0_507:
	global_load_dwordx4 v[154:157], v[148:149], off offset:144
	v_mov_b32_e32 v148, v144
	v_mov_b32_e32 v149, v144
	v_mul_f32_e32 v144, v8, v144
	v_mul_f32_e32 v145, v9, v145
	v_mul_f32_e32 v148, v10, v148
	v_mul_f32_e32 v149, v11, v149
	s_and_b64 vcc, exec, s[36:37]
	s_waitcnt vmcnt(0)
	v_mul_f32_e32 v148, v148, v156
	v_mul_f32_e32 v149, v149, v157
	v_mul_f32_e32 v144, v144, v154
	v_mul_f32_e32 v145, v145, v155
	s_cbranch_vccnz .LBB0_509
	v_mul_f32_e32 v156, v178, v145
	v_mul_f32_e32 v157, v178, v144
	v_mul_f32_e32 v154, v176, v144
	v_mul_f32_e32 v155, v176, v145
	v_fma_f32 v144, v176, v144, v156
	v_fma_f32 v145, v176, v145, v157
	v_mul_f32_e32 v144, v175, v149
	v_fma_f32 v158, v174, v148, -v144
	v_fma_f32 v159, v175, v149, -v144
	v_mov_b32_e32 v160, v175
	v_mov_b32_e32 v161, v174
	v_mul_f32_e32 v144, v174, v149
	v_fma_f32 v160, v160, v148, v144
	v_fma_f32 v161, v161, v149, v144
	v_sub_f32_e32 v144, v154, v156
	v_mov_b32_e32 v148, v158
	v_mov_b32_e32 v149, v160
; __device__ __forceinline__ unsigned cvt_pk_bf16(float lo, float hi) { const f32x2 v = {lo, hi}; const bf16x2_t b = __builtin_convertvector(v, bf16x2_t); return __builtin_bit_cast(unsigned, b); }
;     __device__ __forceinline__ void operator()(const f32x4 (&acc)[2][2][4][2], const Unit& u, int wr, int wc, int fr, int fq) const {
;     ...
;             for (int ai = 0; ai < 2; ++ai)
; #pragma unroll
;                 for (int m = 0; m < 4; ++m) {
;                     const int row = row0 + ai * HALF + m * 16;
;                     int fqo = fq; asm volatile("" : "+v"(fqo));
;                     f32x4 v[2][2]; float ss = 0.f;
; #pragma unroll
;                     for (int bj = 0; bj < 2; ++bj)
; #pragma unroll
;                         for (int n = 0; n < 2; ++n) { v[bj][n] = acc[ai][bj][m][n]; ss += (v[bj][n][0] * v[bj][n][0] + v[bj][n][1] * v[bj][n][1]) + (v[bj][n][2] * v[bj][n][2] + v[bj][n][3] * v[bj][n][3]); }
;                     ss += swz_xor<16>(ss); ss = xadd32(ss);
;                     const float rstd = __builtin_amdgcn_rsqf(ss * (1.0f / 64.0f) + EPS);
;                     const int t = row & (SEQ - 1); const float pos[2] = {(float)(t >> 6), (float)(t & 63)};
; #pragma unroll
;                     for (int bj = 0; bj < 2; ++bj) {
;                         u32x4 w;
; #pragma unroll
;                         for (int n = 0; n < 2; ++n) {
;                             f32x4 x = v[bj][n] * rstd * *(const f32x4*)(g + 32 * bj + 8 * fqo + 4 * n);
;                             if (latent) {
;                                 const float a0 = pos[bj] * fr0[n], a1 = pos[bj] * fr1[n];
;                                 const float c0 = __builtin_amdgcn_cosf(a0), s0 = __builtin_amdgcn_sinf(a0), c1 = __builtin_amdgcn_cosf(a1), s1 = __builtin_amdgcn_sinf(a1);
;                                 x = (f32x4){x[0] * c0 - x[1] * s0, x[1] * c0 + x[0] * s0, x[2] * c1 - x[3] * s1, x[3] * c1 + x[2] * s1};
;                             }
;                             if (n == 0) { w.x = cvt_pk_bf16(x[0], x[1]); w.y = cvt_pk_bf16(x[2], x[3]); } else { w.z = cvt_pk_bf16(x[0], x[1]); w.w = cvt_pk_bf16(x[2], x[3]); }
;                         }
;                         *(u32x4*)(dst + (size_t)row * 64 + 32 * bj + 8 * fq) = w;
;                     }
.LBB0_509:
	v_cvt_pk_bf16_f32 v150, v150, v151
	v_cvt_pk_bf16_f32 v151, v152, v153
	v_cvt_pk_bf16_f32 v152, v144, v145
	v_cvt_pk_bf16_f32 v153, v148, v149
	global_store_dwordx4 v[146:147], v[150:153], off offset:64
	v_mul_f32_e32 v144, v22, v22
	v_mul_f32_e32 v145, v23, v23
	v_mul_f32_e32 v146, v20, v20
	v_mul_f32_e32 v147, v21, v21
	v_mov_b32_e32 v141, v236
	v_pk_mov_b32 v[148:149], v[146:147], v[144:145] op_sel:[1,0]
	v_mov_b32_e32 v147, v145
	v_add_f32_e32 v144, v148, v146
	v_add_f32_e32 v145, v149, v147
	v_mul_f32_e32 v146, v18, v18
	v_mul_f32_e32 v147, v19, v19
	v_mul_f32_e32 v148, v16, v16
	v_mul_f32_e32 v149, v17, v17
	v_pk_add_f32 v[144:145], v[144:145], v[144:145] op_sel:[0,1] op_sel_hi:[1,0]
	v_pk_mov_b32 v[150:151], v[148:149], v[146:147] op_sel:[1,0]
	v_mov_b32_e32 v149, v147
	v_add_f32_e32 v146, v150, v148
	v_add_f32_e32 v147, v151, v149
	v_mul_f32_e32 v148, v0, v0
	v_mul_f32_e32 v149, v1, v1
	v_pk_add_f32 v[146:147], v[146:147], v[146:147] op_sel:[0,1] op_sel_hi:[1,0]
	v_mov_b32_e32 v145, v148
	v_mov_b32_e32 v147, v149
	v_add_f32_e32 v144, v144, v146
	v_add_f32_e32 v145, v145, v147
	v_mul_f32_e32 v146, v5, v5
	v_mul_f32_e32 v148, v7, v7
	v_mul_f32_e32 v150, v2, v2
	v_mul_f32_e32 v151, v3, v3
	v_fma_f32 v147, v5, v5, v146
	v_fma_f32 v146, v4, v4, v146
	v_fma_f32 v149, v7, v7, v148
	v_fma_f32 v148, v6, v6, v148
	v_mov_b32_e32 v147, v150
	v_mov_b32_e32 v149, v151
	v_add_f32_e32 v146, v146, v148
	v_add_f32_e32 v147, v147, v149
	s_and_b64 vcc, exec, s[36:37]
	v_add_f32_e32 v144, v144, v146
	v_add_f32_e32 v145, v145, v147
	v_lshlrev_b32_e32 v146, 3, v141
	v_ashrrev_i32_e32 v147, 31, v146
	v_lshl_add_u64 v[146:147], v[146:147], 2, s[38:39]
	global_load_dwordx4 v[148:151], v[146:147], off
	v_add_f32_e32 v145, v144, v145
	v_add_u32_e32 v144, 0xb0, v140
	ds_swizzle_b32 v140, v145 offset:swizzle(SWAP,16)
	s_waitcnt lgkmcnt(0)
	v_add_f32_e32 v140, v145, v140
	v_mov_b32_e32 v145, v140
	s_nop 1
	v_permlane32_swap_b32_e32 v140, v145
	v_add_f32_e32 v140, v140, v145
	v_fmamk_f32 v140, v140, 0x3c800000, v193
	v_rsq_f32_e32 v140, v140
	v_bfe_u32 v145, v144, 6, 7
	v_cvt_f32_ubyte0_e32 v145, v145
	v_mul_f32_e32 v152, v20, v140
	v_mul_f32_e32 v153, v21, v140
	v_mul_f32_e32 v154, v22, v140
	v_mul_f32_e32 v155, v23, v140
	s_waitcnt vmcnt(0)
	v_mul_f32_e32 v148, v148, v152
	v_mul_f32_e32 v149, v149, v153
	v_mul_f32_e32 v150, v150, v154
	v_mul_f32_e32 v151, v151, v155
	s_cbranch_vccnz .LBB0_511
	v_mul_f32_e32 v141, v194, v145
	v_sin_f32_e32 v154, v141
	v_mul_f32_e32 v153, v237, v145
	v_cos_f32_e32 v152, v141
	v_sin_f32_e32 v157, v153
	v_cos_f32_e32 v156, v153
	v_mul_f32_e32 v155, v154, v148
	v_mul_f32_e32 v154, v154, v149
	v_mul_f32_e32 v158, v152, v148
	v_mul_f32_e32 v159, v152, v149
	v_fma_f32 v148, v152, v148, v154
	v_fma_f32 v149, v152, v149, v155
	v_mul_f32_e32 v148, v157, v151
	v_fma_f32 v152, v156, v150, -v148
	v_fma_f32 v153, v157, v151, -v148
	v_mov_b32_e32 v160, v157
	v_mov_b32_e32 v161, v156
	v_mul_f32_e32 v148, v156, v151
	v_fma_f32 v156, v160, v150, v148
	v_fma_f32 v157, v161, v151, v148
	v_sub_f32_e32 v148, v158, v154
	v_mov_b32_e32 v150, v152
	v_mov_b32_e32 v151, v156
.LBB0_511:
	global_load_dwordx4 v[154:157], v[146:147], off offset:16
	v_mov_b32_e32 v141, v140
	v_mov_b32_e32 v152, v140
	v_mov_b32_e32 v153, v140
	v_mul_f32_e32 v158, v18, v152
	v_mul_f32_e32 v159, v19, v153
	v_mul_f32_e32 v160, v16, v140
	v_mul_f32_e32 v161, v17, v141
	s_and_b64 vcc, exec, s[36:37]
	s_waitcnt vmcnt(0)
	v_mul_f32_e32 v156, v158, v156
	v_mul_f32_e32 v157, v159, v157
	v_mul_f32_e32 v154, v160, v154
	v_mul_f32_e32 v155, v161, v155
	s_cbranch_vccnz .LBB0_513
	v_mul_f32_e32 v159, v238, v145
	v_sin_f32_e32 v160, v159
	v_mul_f32_e32 v145, v239, v145
	v_cos_f32_e32 v158, v159
	v_sin_f32_e32 v163, v145
	v_cos_f32_e32 v162, v145
	v_mul_f32_e32 v161, v160, v154
	v_mul_f32_e32 v160, v160, v155
	v_mul_f32_e32 v164, v158, v154
	v_mul_f32_e32 v165, v158, v155
	v_fma_f32 v154, v158, v154, v160
	v_fma_f32 v155, v158, v155, v161
	v_mul_f32_e32 v154, v163, v157
	v_fma_f32 v158, v162, v156, -v154
	v_fma_f32 v159, v163, v157, -v154
	v_mov_b32_e32 v166, v163
	v_mov_b32_e32 v167, v162
	v_mul_f32_e32 v154, v162, v157
	v_fma_f32 v162, v166, v156, v154
	v_fma_f32 v163, v167, v157, v154
	v_sub_f32_e32 v154, v164, v160
	v_mov_b32_e32 v156, v158
	v_mov_b32_e32 v157, v162
.LBB0_513:
	v_ashrrev_i32_e32 v145, 31, v144
	v_lshlrev_b64 v[144:145], 7, v[144:145]
	v_cvt_pk_bf16_f32 v148, v148, v149
	v_cvt_pk_bf16_f32 v149, v150, v151
	v_lshl_add_u64 v[142:143], v[142:143], 0, v[144:145]
	v_cvt_pk_bf16_f32 v150, v154, v155
	v_cvt_pk_bf16_f32 v151, v156, v157
	global_store_dwordx4 v[142:143], v[148:151], off
	global_load_dwordx4 v[154:157], v[146:147], off offset:128
	v_mul_f32_e32 v144, v6, v152
	v_mul_f32_e32 v145, v7, v153
	v_mul_f32_e32 v150, v4, v140
	v_mul_f32_e32 v151, v5, v141
	s_and_b64 vcc, exec, s[36:37]
	s_waitcnt vmcnt(0)
	v_mul_f32_e32 v148, v144, v156
	v_mul_f32_e32 v149, v145, v157
	v_mul_f32_e32 v144, v150, v154
	v_mul_f32_e32 v145, v151, v155
	s_cbranch_vccnz .LBB0_515
	v_mul_f32_e32 v152, v184, v145
	v_mul_f32_e32 v153, v184, v144
	v_mul_f32_e32 v150, v182, v144
	v_mul_f32_e32 v151, v182, v145
	v_fma_f32 v144, v182, v144, v152
	v_fma_f32 v145, v182, v145, v153
	v_mul_f32_e32 v144, v181, v149
	v_fma_f32 v154, v180, v148, -v144
	v_fma_f32 v155, v181, v149, -v144
	v_mov_b32_e32 v156, v181
	v_mov_b32_e32 v157, v180
	v_mul_f32_e32 v144, v180, v149
	v_fma_f32 v156, v156, v148, v144
	v_fma_f32 v157, v157, v149, v144
	v_sub_f32_e32 v144, v150, v152
	v_mov_b32_e32 v148, v154
	v_mov_b32_e32 v149, v156
.LBB0_515:
	global_load_dwordx4 v[150:153], v[146:147], off offset:144
	v_mov_b32_e32 v146, v140
	v_mov_b32_e32 v147, v140
	v_mul_f32_e32 v140, v0, v140
	v_mul_f32_e32 v141, v1, v141
	v_mul_f32_e32 v146, v2, v146
	v_mul_f32_e32 v147, v3, v147
	s_and_b64 vcc, exec, s[36:37]
	s_waitcnt vmcnt(0)
	v_mul_f32_e32 v146, v146, v152
	v_mul_f32_e32 v147, v147, v153
	v_mul_f32_e32 v140, v140, v150
	v_mul_f32_e32 v141, v141, v151
	s_cbranch_vccnz .LBB0_517
	v_mul_f32_e32 v152, v190, v141
	v_mul_f32_e32 v153, v190, v140
	v_mul_f32_e32 v150, v188, v140
	v_mul_f32_e32 v151, v188, v141
	v_fma_f32 v140, v188, v140, v152
	v_fma_f32 v141, v188, v141, v153
	v_mul_f32_e32 v140, v187, v147
	v_fma_f32 v154, v186, v146, -v140
	v_fma_f32 v155, v187, v147, -v140
	v_mov_b32_e32 v156, v187
	v_mov_b32_e32 v157, v186
	v_mul_f32_e32 v140, v186, v147
	v_fma_f32 v156, v156, v146, v140
	v_fma_f32 v157, v157, v147, v140
	v_sub_f32_e32 v140, v150, v152
	v_mov_b32_e32 v146, v154
	v_mov_b32_e32 v147, v156

; #define LAS __attribute__((address_space(3)))
; __device__ __forceinline__ void mixer_phase(const Args& a, LAS unsigned char* lds, int l, unsigned* ctr) {
;     ...
;     const int nC = 512, nA = 512, nCc = last ? 0 : 16, nAc = last ? 0 : 16, nB = last ? 1024 : 1056;
;     const int total = nC + nA + nCc + nAc + nB;
;     const float* lv = a.in[I_LAM] + l * 4 * 48;
;     float d1 = 0.f, d2 = 0.f;
;     for (int i = 0; i < 48; ++i) { d1 += lv[i] * lv[48 + i]; d2 += lv[96 + i] * lv[144 + i]; }
;     const float lam_init = 0.8f - 0.6f * expf(-0.3f * (float)l);
;     const float lam = expf(d1) - expf(d2) + lam_init;
;     LAS unsigned* sidx = (LAS unsigned*)(lds + LDS_MISC + 64);
.LBB0_576:
	s_add_u32 s6, s70, s0
	s_addc_u32 s7, s71, s1
	global_load_dwordx4 v[2:5], v195, s[6:7] offset:48
	global_load_dwordx4 v[6:9], v195, s[6:7] offset:32
	global_load_dwordx4 v[10:13], v195, s[6:7] offset:16
	global_load_dwordx4 v[14:17], v195, s[6:7]
	global_load_dwordx4 v[18:21], v195, s[6:7] offset:240
	global_load_dwordx4 v[22:25], v195, s[6:7] offset:224
	global_load_dwordx4 v[26:29], v195, s[6:7] offset:208
	global_load_dwordx4 v[30:33], v195, s[6:7] offset:192
	global_load_dwordx4 v[34:37], v195, s[6:7] offset:432
	global_load_dwordx4 v[38:41], v195, s[6:7] offset:416
	global_load_dwordx4 v[42:45], v195, s[6:7] offset:400
	global_load_dwordx4 v[46:49], v195, s[6:7] offset:384
	global_load_dwordx4 v[50:53], v195, s[6:7] offset:624
	global_load_dwordx4 v[54:57], v195, s[6:7] offset:608
	global_load_dwordx4 v[58:61], v195, s[6:7] offset:592
	global_load_dwordx4 v[62:65], v195, s[6:7] offset:576
	s_add_u32 s0, s0, 64
	s_addc_u32 s1, s1, 0
	s_cmpk_eq_i32 s0, 0xc0
	s_waitcnt vmcnt(12)
	v_mov_b32_e32 v66, v14
	v_mov_b32_e32 v14, v16
	s_waitcnt vmcnt(9)
	v_mov_b32_e32 v16, v26
	s_waitcnt vmcnt(8)
	v_mov_b32_e32 v68, v30
	v_mov_b32_e32 v30, v32
	s_waitcnt vmcnt(4)
	v_mov_b32_e32 v67, v46
	v_mov_b32_e32 v46, v15
	v_mov_b32_e32 v15, v48
	v_mov_b32_e32 v48, v17
	s_waitcnt vmcnt(0)
	v_mov_b32_e32 v69, v62
	v_fma_f32 v0, v66, v68, v0
	v_fma_f32 v1, v67, v69, v1
	v_mov_b32_e32 v62, v31
	v_fma_f32 v0, v46, v62, v0
	v_fma_f32 v1, v47, v63, v1
	v_mov_b32_e32 v31, v64
	v_fma_f32 v0, v14, v30, v0
	v_fma_f32 v1, v15, v31, v1
	v_mov_b32_e32 v64, v33
	v_fma_f32 v0, v48, v64, v0
	v_fma_f32 v1, v49, v65, v1
	v_mov_b32_e32 v14, v10
	v_mov_b32_e32 v15, v42
	v_mov_b32_e32 v17, v58
	v_fma_f32 v0, v14, v16, v0
	v_fma_f32 v1, v15, v17, v1
	v_mov_b32_e32 v42, v11
	v_mov_b32_e32 v58, v27
	v_fma_f32 v0, v42, v58, v0
	v_fma_f32 v1, v43, v59, v1
	v_mov_b32_e32 v10, v12
	v_mov_b32_e32 v11, v44
	v_mov_b32_e32 v14, v28
	v_mov_b32_e32 v15, v60
	v_fma_f32 v0, v10, v14, v0
	v_fma_f32 v1, v11, v15, v1
	v_mov_b32_e32 v44, v13
	v_mov_b32_e32 v60, v29
	v_fma_f32 v0, v44, v60, v0
	v_fma_f32 v1, v45, v61, v1
	v_mov_b32_e32 v10, v6
	v_mov_b32_e32 v11, v38
	v_mov_b32_e32 v12, v22
	v_mov_b32_e32 v13, v54
	v_fma_f32 v0, v10, v12, v0
	v_fma_f32 v1, v11, v13, v1
	v_mov_b32_e32 v38, v7
	v_mov_b32_e32 v54, v23
	v_fma_f32 v0, v38, v54, v0
	v_fma_f32 v1, v39, v55, v1
	v_mov_b32_e32 v6, v8
	v_mov_b32_e32 v7, v40
	v_mov_b32_e32 v10, v24
	v_mov_b32_e32 v11, v56
	v_fma_f32 v0, v6, v10, v0
	v_fma_f32 v1, v7, v11, v1
	v_mov_b32_e32 v40, v9
	v_mov_b32_e32 v56, v25
	v_fma_f32 v0, v40, v56, v0
	v_fma_f32 v1, v41, v57, v1
	v_mov_b32_e32 v6, v2
	v_mov_b32_e32 v7, v34
	v_mov_b32_e32 v8, v18
	v_mov_b32_e32 v9, v50
	v_fma_f32 v0, v6, v8, v0
	v_fma_f32 v1, v7, v9, v1
	v_mov_b32_e32 v34, v3
	v_mov_b32_e32 v50, v19
	v_fma_f32 v0, v34, v50, v0
	v_fma_f32 v1, v35, v51, v1
	v_mov_b32_e32 v2, v4
	v_mov_b32_e32 v3, v36
	v_mov_b32_e32 v6, v20
	v_mov_b32_e32 v7, v52
	v_fma_f32 v0, v2, v6, v0
	v_fma_f32 v1, v3, v7, v1
	v_mov_b32_e32 v36, v5
	v_mov_b32_e32 v52, v21
	v_fma_f32 v0, v36, v52, v0
	v_fma_f32 v1, v37, v53, v1
	s_cbranch_scc0 .LBB0_576
	v_readlane_b32 s6, v255, 20
	s_lshl_b32 s22, s6, 6
	s_lshl_b64 s[0:1], s[22:23], 2
	v_readlane_b32 s5, v252, 51
	s_add_u32 s78, s5, s0
	v_readlane_b32 s0, v252, 52
	s_addc_u32 s79, s0, s1
	s_cmp_eq_u32 s6, 3
	s_cselect_b64 s[0:1], -1, 0
	v_cvt_f32_u32_e32 v2, s6
	v_writelane_b32 v255, s0, 25
	s_mov_b32 s5, 0x42b17218
	v_mov_b32_e32 v6, 0x7f800000
	v_writelane_b32 v255, s1, 26
	s_and_b64 s[0:1], s[0:1], exec
	s_cselect_b32 s1, 0, 16
	s_movk_i32 s0, 0x800
	s_cselect_b32 s0, s0, 0x820
	s_lshl_b32 s47, s1, 1
	v_mul_f32_e32 v2, 0xbe99999a, v2
	s_add_i32 s47, s47, s0
	v_mul_f32_e32 v3, 0x3fb8aa3b, v2
	s_mov_b32 s0, 0x3fb8aa3b
	v_fma_f32 v4, v2, s0, -v3
	v_rndne_f32_e32 v5, v3
	v_fmac_f32_e32 v4, 0x32a5705f, v2
	v_sub_f32_e32 v3, v3, v5
	v_add_f32_e32 v3, v3, v4
	v_exp_f32_e32 v3, v3
	v_cvt_i32_f32_e32 v4, v5
	s_mov_b32 s20, s1
	s_mov_b32 s1, 0xc2ce8ed0
	v_cmp_ngt_f32_e32 vcc, s1, v2
	v_ldexp_f32 v3, v3, v4
	v_readlane_b32 s48, v252, 0
	v_cndmask_b32_e32 v3, 0, v3, vcc
	v_cmp_nlt_f32_e32 vcc, s5, v2
	v_readlane_b32 s62, v252, 14
	v_readlane_b32 s63, v252, 15
	v_cndmask_b32_e32 v2, v6, v3, vcc
	v_mov_b32_e32 v3, 0x3f4ccccd
	v_fmamk_f32 v2, v2, 0xbf19999a, v3
	v_mul_f32_e32 v3, 0x3fb8aa3b, v0
	v_rndne_f32_e32 v4, v3
	v_sub_f32_e32 v5, v3, v4
	v_fma_f32 v3, v0, s0, -v3
	v_fmac_f32_e32 v3, 0x32a5705f, v0
	v_add_f32_e32 v3, v5, v3
	v_exp_f32_e32 v3, v3
	v_cvt_i32_f32_e32 v4, v4
	v_cmp_ngt_f32_e32 vcc, s1, v0
	s_mov_b64 s[12:13], s[68:69]
	s_lshl_b32 s22, s6, 8
	v_ldexp_f32 v3, v3, v4
	v_cndmask_b32_e32 v3, 0, v3, vcc
	v_cmp_nlt_f32_e32 vcc, s5, v0
	v_readlane_b32 s60, v252, 12
	v_readlane_b32 s61, v252, 13
	v_cndmask_b32_e32 v0, v6, v3, vcc
	v_mul_f32_e32 v3, 0x3fb8aa3b, v1
	v_rndne_f32_e32 v4, v3
	v_sub_f32_e32 v5, v3, v4
	v_fma_f32 v3, v1, s0, -v3
	v_fmac_f32_e32 v3, 0x32a5705f, v1
	v_add_f32_e32 v3, v5, v3
	v_exp_f32_e32 v3, v3
	v_cvt_i32_f32_e32 v4, v4
	v_cmp_ngt_f32_e32 vcc, s1, v1
	s_mov_b64 s[14:15], s[70:71]
	s_mov_b64 s[16:17], s[72:73]
	v_ldexp_f32 v3, v3, v4
	s_mov_b64 s[18:19], s[74:75]
	s_mov_b64 s[70:71], s[62:63]
	v_cndmask_b32_e32 v3, 0, v3, vcc
	v_cmp_nlt_f32_e32 vcc, s5, v1
	s_lshl_b32 s5, s6, 18
	s_lshl_b32 s0, s6, 9
	s_lshl_b64 s[8:9], s[22:23], 2
	s_mov_b64 s[68:69], s[60:61]
	s_add_u32 s26, s68, s8
	s_addc_u32 s27, s69, s9
	s_mov_b32 s1, s23
	s_add_u32 s8, s70, s5
	s_addc_u32 s9, s71, 0
	s_lshl_b64 s[0:1], s[0:1], 2
	v_writelane_b32 v255, s8, 27
	s_add_u32 s0, s12, s0
	s_addc_u32 s1, s13, s1
	v_writelane_b32 v255, s9, 28
	s_mulk_i32 s6, 0x60
	s_mov_b32 s7, s23
	v_writelane_b32 v255, s0, 29
	v_cndmask_b32_e32 v1, v6, v3, vcc
	v_readlane_b32 s49, v252, 1
	v_writelane_b32 v255, s1, 30
	s_lshl_b64 s[0:1], s[6:7], 2
	v_sub_f32_e32 v0, v0, v1
	v_readlane_b32 s50, v252, 2
	v_readlane_b32 s51, v252, 3
	v_readlane_b32 s52, v252, 4
	v_readlane_b32 s53, v252, 5
	v_readlane_b32 s54, v252, 6
	v_readlane_b32 s55, v252, 7
	s_add_u32 s80, s16, s0
	v_readlane_b32 s82, v252, 53
	v_readlane_b32 s48, v254, 21
	v_add_f32_e32 v216, v2, v0
	v_sub_f32_e32 v217, 1.0, v2
	s_addc_u32 s81, s17, s1
	v_readlane_b32 s83, v252, 54
	v_readlane_b32 s25, v255, 19
	v_readlane_b32 s49, v254, 22
	v_readlane_b32 s21, v254, 23
	v_readlane_b32 s24, v254, 24
	v_readlane_b32 s50, v254, 25
	v_readlane_b32 s51, v254, 26
	v_readlane_b32 s52, v254, 27
	v_readlane_b32 s53, v254, 28
	v_readlane_b32 s54, v254, 33
	v_readlane_b32 s55, v254, 34
	s_mov_b32 s60, 0x8400
	s_movk_i32 s61, 0x60
	s_movk_i32 s62, 0x100
	s_mov_b32 s63, 0x2aaaaaab
	v_readlane_b32 s75, v255, 17
	v_readlane_b32 s56, v252, 8
	v_readlane_b32 s57, v252, 9
	v_readlane_b32 s58, v252, 10
	v_readlane_b32 s59, v252, 11
	s_branch .LBB0_581

; #define LAS __attribute__((address_space(3)))
; __device__ __forceinline__ unsigned cvt_pk_bf16(float lo, float hi) { const f32x2 v = {lo, hi}; const bf16x2_t b = __builtin_convertvector(v, bf16x2_t); return __builtin_bit_cast(unsigned, b); }
; __device__ __forceinline__ void bmix_unit(LAS unsigned char* lds, const bf16_t* U, const bf16_t* VG, const float* gv  , const float* ws  , const float* bs  ,
;                                           int ci, int g, bf16_t* Y) {
;     ...
;     for (int i = 0; i < 2; ++i) {
;         const int idx = tid + i * NTHREADS; const int q = idx >> 3, c8 = idx & 7;
;         const u32x4 w = *(const u32x4*)(VG + (size_t)(r0 + q) * 256 + g * 64 + c8 * 8); const float rs = rstd[q];
; #pragma unroll
;         for (int e = 0; e < 4; ++e) {
;             const float lo = __uint_as_float(w[e] << 16) * rs * gv[g * 64 + c8 * 8 + 2 * e], hi2 = __uint_as_float(w[e] & 0xffff0000u) * rs * gv[g * 64 + c8 * 8 + 2 * e + 1];
;             const unsigned pk = cvt_pk_bf16(lo, hi2);
;             vnT[(c8 * 8 + 2 * e) * 136 + q] = (bf16_t)(pk & 0xffffu); vnT[(c8 * 8 + 2 * e + 1) * 136 + q] = (bf16_t)(pk >> 16);
;         }
;     }
;     __syncthreads();
;     const int pblk = wid & 3, cblk = wid >> 2;
;     f32x16 acc;
; #pragma unroll
;     for (int r = 0; r < 16; ++r) acc[r] = 0.f;
;     const float* wrow = ws + ((size_t)g * 128 + pblk * 32 + r32) * 128 + hi * 8;
; #pragma unroll
;     for (int ks = 0; ks < 8; ++ks) {
;         const f32x4 a0 = *(const f32x4*)(wrow + ks * 16), a1 = *(const f32x4*)(wrow + ks * 16 + 4);
;         u32x4 aw; aw.x = cvt_pk_bf16(a0[0], a0[1]); aw.y = cvt_pk_bf16(a0[2], a0[3]); aw.z = cvt_pk_bf16(a1[0], a1[1]); aw.w = cvt_pk_bf16(a1[2], a1[3]);
;         const bf16x8 bfr = *(const LAS bf16x8*)(vnT + (cblk * 32 + r32) * 136 + ks * 16 + hi * 8);
;         acc = __builtin_amdgcn_mfma_f32_32x32x16_bf16(__builtin_bit_cast(bf16x8, aw), bfr, acc, 0, 0, 0);
.LBB0_592:
	s_or_b64 exec, exec, s[0:1]
	s_and_b32 s0, s56, 3
	s_lshl_b32 s1, s0, 6
	s_lshl_b32 s0, s0, 7
	v_readlane_b32 s8, v254, 31
	v_lshlrev_b32_e32 v0, 3, v16
	v_ashrrev_i32_e32 v19, 3, v16
	v_readlane_b32 s9, v254, 32
	s_add_u32 s8, s8, s0
	v_and_b32_e32 v15, 56, v0
	v_add_u32_e32 v0, s6, v19
	s_addc_u32 s9, s9, 0
	v_lshlrev_b32_e32 v194, 1, v15
	s_waitcnt lgkmcnt(0)
	v_ashrrev_i32_e32 v1, 31, v0
	v_lshl_add_u64 v[12:13], s[8:9], 0, v[194:195]
	v_lshlrev_b64 v[0:1], 9, v[0:1]
	v_lshl_add_u64 v[0:1], v[12:13], 0, v[0:1]
	s_barrier
	global_load_dwordx4 v[8:11], v[0:1], off
	v_lshl_add_u32 v0, v19, 2, 0
	ds_read_b32 v14, v0
	v_or_b32_e32 v2, s1, v15
	v_lshlrev_b32_e32 v4, 2, v2
	s_movk_i32 s10, 0x110
	s_lshr_b32 s8, s7, 1
	s_and_b32 s8, s8, 0x60
	v_and_b32_e32 v17, 31, v16
	s_or_b32 s9, s0, s8
	v_readlane_b32 s12, v255, 27
	v_bfe_u32 v18, v16, 5, 1
	v_readlane_b32 s13, v255, 28
	s_waitcnt vmcnt(0)
	v_lshlrev_b32_e32 v0, 16, v8
	v_and_b32_e32 v1, 0xffff0000, v8
	s_waitcnt lgkmcnt(0)
	v_mul_f32_e32 v20, v14, v0
	v_mul_f32_e32 v21, v14, v1
	global_load_dwordx4 v[0:3], v4, s[26:27] offset:16
	s_nop 0
	global_load_dwordx4 v[4:7], v4, s[26:27]
	s_waitcnt vmcnt(0)
	v_mul_f32_e32 v20, v4, v20
	v_mul_f32_e32 v21, v5, v21
	s_nop 0
	v_cvt_pk_bf16_f32 v8, v20, v21
	v_mad_u32_u24 v20, v15, s10, 0
	v_lshl_add_u32 v15, v19, 1, v20
	ds_write_b16 v15, v8 offset:512
	ds_write_b16_d16_hi v15, v8 offset:784
	v_lshlrev_b32_e32 v8, 16, v9
	v_and_b32_e32 v9, 0xffff0000, v9
	v_mul_f32_e32 v8, v14, v8
	v_mul_f32_e32 v9, v14, v9
	v_mul_f32_e32 v8, v8, v6
	v_mul_f32_e32 v9, v9, v7
	s_nop 0
	v_cvt_pk_bf16_f32 v8, v8, v9
	ds_write_b16 v15, v8 offset:1056
	ds_write_b16_d16_hi v15, v8 offset:1328
	v_lshlrev_b32_e32 v8, 16, v10
	v_and_b32_e32 v9, 0xffff0000, v10
	v_mul_f32_e32 v8, v14, v8
	v_mul_f32_e32 v9, v14, v9
	v_mul_f32_e32 v8, v8, v0
	v_mul_f32_e32 v9, v9, v1
	s_nop 0
	v_cvt_pk_bf16_f32 v8, v8, v9
	ds_write_b16 v15, v8 offset:1600
	ds_write_b16_d16_hi v15, v8 offset:1872
	v_lshlrev_b32_e32 v8, 16, v11
	v_and_b32_e32 v9, 0xffff0000, v11
	v_mul_f32_e32 v8, v14, v8
	v_mul_f32_e32 v9, v14, v9
	v_mul_f32_e32 v8, v8, v2
	v_mul_f32_e32 v9, v9, v3
	s_nop 0
	v_cvt_pk_bf16_f32 v8, v8, v9
	ds_write_b16 v15, v8 offset:2144
	ds_write_b16_d16_hi v15, v8 offset:2416
	v_add_u32_e32 v8, 0x200, v16
	v_ashrrev_i32_e32 v19, 3, v8
	v_add_u32_e32 v8, s6, v19
	v_ashrrev_i32_e32 v9, 31, v8
	v_lshlrev_b64 v[8:9], 9, v[8:9]
	v_lshl_add_u64 v[8:9], v[12:13], 0, v[8:9]
	global_load_dwordx4 v[8:11], v[8:9], off
	v_lshl_add_u32 v12, v19, 2, 0
	ds_read_b32 v12, v12
	s_waitcnt vmcnt(0)
	v_lshlrev_b32_e32 v14, 16, v8
	v_and_b32_e32 v15, 0xffff0000, v8
	s_waitcnt lgkmcnt(0)
	v_mul_f32_e32 v14, v12, v14
	v_mul_f32_e32 v15, v12, v15
	v_mul_f32_e32 v4, v4, v14
	v_mul_f32_e32 v5, v5, v15
	v_lshl_add_u32 v8, v19, 1, v20
	v_cvt_pk_bf16_f32 v4, v4, v5
	ds_write_b16 v8, v4 offset:512
	ds_write_b16_d16_hi v8, v4 offset:784
	v_lshlrev_b32_e32 v4, 16, v9
	v_and_b32_e32 v5, 0xffff0000, v9
	v_mul_f32_e32 v4, v12, v4
	v_mul_f32_e32 v5, v12, v5
	v_mul_f32_e32 v4, v6, v4
	v_mul_f32_e32 v5, v7, v5
	s_nop 0
	v_cvt_pk_bf16_f32 v4, v4, v5
	ds_write_b16 v8, v4 offset:1056
	ds_write_b16_d16_hi v8, v4 offset:1328
	v_lshlrev_b32_e32 v4, 16, v10
	v_and_b32_e32 v5, 0xffff0000, v10
	v_mul_f32_e32 v4, v12, v4
	v_mul_f32_e32 v5, v12, v5
	v_mul_f32_e32 v0, v0, v4
	v_mul_f32_e32 v1, v1, v5
	s_nop 0
	v_cvt_pk_bf16_f32 v0, v0, v1
	ds_write_b16 v8, v0 offset:1600
	ds_write_b16_d16_hi v8, v0 offset:1872
	v_lshlrev_b32_e32 v0, 16, v11
	v_and_b32_e32 v1, 0xffff0000, v11
	v_mul_f32_e32 v0, v12, v0
	v_mul_f32_e32 v1, v12, v1
	v_mul_f32_e32 v0, v2, v0
	v_mul_f32_e32 v1, v3, v1
	s_nop 0
	v_cvt_pk_bf16_f32 v0, v0, v1
	ds_write_b16 v8, v0 offset:2144
	ds_write_b16_d16_hi v8, v0 offset:2416
	v_or_b32_e32 v0, s9, v17
	v_lshlrev_b32_e32 v194, 9, v0
	v_lshl_add_u64 v[0:1], s[12:13], 0, v[194:195]
	v_lshlrev_b32_e32 v194, 5, v18
	s_ashr_i32 s9, s7, 3
	v_lshl_add_u64 v[32:33], v[0:1], 0, v[194:195]
	s_and_b32 s7, s9, 0xffffffe0
	v_mov_b32_e32 v0, s9
	s_movk_i32 s9, 0xffe0
	v_bfi_b32 v0, s9, v0, v16
	v_mul_lo_u32 v0, v0, s10
	v_lshlrev_b32_e32 v1, 4, v18
	s_waitcnt lgkmcnt(0)
	s_barrier
	v_add3_u32 v16, 0, v0, v1
	global_load_dwordx4 v[0:3], v[32:33], off offset:16
	global_load_dwordx4 v[4:7], v[32:33], off
	s_add_i32 s7, s7, s1
	s_waitcnt vmcnt(0)
	v_cvt_pk_bf16_f32 v4, v4, v5
	v_cvt_pk_bf16_f32 v5, v6, v7
	v_cvt_pk_bf16_f32 v6, v0, v1
	v_cvt_pk_bf16_f32 v7, v2, v3
	ds_read_b128 v[0:3], v16 offset:512
	ds_read_b128 v[20:23], v16 offset:544
	global_load_dwordx4 v[24:27], v[32:33], off offset:80
	global_load_dwordx4 v[28:31], v[32:33], off offset:64
	s_waitcnt lgkmcnt(1)
	v_mfma_f32_32x32x16_bf16 v[0:15], v[4:7], v[0:3], 0
	s_waitcnt vmcnt(0)
	v_cvt_pk_bf16_f32 v28, v28, v29
	v_cvt_pk_bf16_f32 v29, v30, v31
	v_cvt_pk_bf16_f32 v30, v24, v25
	v_cvt_pk_bf16_f32 v31, v26, v27
	s_waitcnt lgkmcnt(0)
	s_nop 0
	v_mfma_f32_32x32x16_bf16 v[0:15], v[28:31], v[20:23], v[0:15]
	global_load_dwordx4 v[20:23], v[32:33], off offset:144
	global_load_dwordx4 v[24:27], v[32:33], off offset:128
	s_waitcnt vmcnt(0)
	v_cvt_pk_bf16_f32 v24, v24, v25
	v_cvt_pk_bf16_f32 v25, v26, v27
	v_cvt_pk_bf16_f32 v26, v20, v21
	v_cvt_pk_bf16_f32 v27, v22, v23
	ds_read_b128 v[20:23], v16 offset:576
	s_waitcnt lgkmcnt(0)
	v_mfma_f32_32x32x16_bf16 v[0:15], v[24:27], v[20:23], v[0:15]
	global_load_dwordx4 v[20:23], v[32:33], off offset:208
	global_load_dwordx4 v[24:27], v[32:33], off offset:192
	s_waitcnt vmcnt(0)
	v_cvt_pk_bf16_f32 v24, v24, v25
	v_cvt_pk_bf16_f32 v25, v26, v27
	v_cvt_pk_bf16_f32 v26, v20, v21
	v_cvt_pk_bf16_f32 v27, v22, v23
	ds_read_b128 v[20:23], v16 offset:608
	s_waitcnt lgkmcnt(0)
; #define LAS __attribute__((address_space(3)))
; __device__ __forceinline__ unsigned cvt_pk_bf16(float lo, float hi) { const f32x2 v = {lo, hi}; const bf16x2_t b = __builtin_convertvector(v, bf16x2_t); return __builtin_bit_cast(unsigned, b); }
; __device__ __forceinline__ float bf2f(bf16_t v) { return __uint_as_float(((unsigned)v) << 16); }
; __device__ __forceinline__ int crow(int r, int hi) { return (r & 3) + 8 * (r >> 2) + 4 * hi; }
; __device__ __forceinline__ void bmix_unit(LAS unsigned char* lds, const bf16_t* U, const bf16_t* VG, const float* gv  , const float* ws  , const float* bs  ,
;                                           int ci, int g, bf16_t* Y) {
;     ...
;     for (int ks = 0; ks < 8; ++ks) {
;         const f32x4 a0 = *(const f32x4*)(wrow + ks * 16), a1 = *(const f32x4*)(wrow + ks * 16 + 4);
;         u32x4 aw; aw.x = cvt_pk_bf16(a0[0], a0[1]); aw.y = cvt_pk_bf16(a0[2], a0[3]); aw.z = cvt_pk_bf16(a1[0], a1[1]); aw.w = cvt_pk_bf16(a1[2], a1[3]);
;         const bf16x8 bfr = *(const LAS bf16x8*)(vnT + (cblk * 32 + r32) * 136 + ks * 16 + hi * 8);
;         acc = __builtin_amdgcn_mfma_f32_32x32x16_bf16(__builtin_bit_cast(bf16x8, aw), bfr, acc, 0, 0, 0);
;     }
; #pragma unroll
;     for (int r = 0; r < 16; ++r) {
;         const int p = pblk * 32 + crow(r, hi); const int col = g * 64 + cblk * 32 + r32;
;         const float mixed = acc[r] + bs[g * 128 + p];
;         const float uu = bf2f(U[(size_t)(r0 + p) * 256 + col]);
;         Y[(size_t)(r0 + p) * DM + 384 + col] = (bf16_t)(cvt_pk_bf16(uu * mixed, 0.f) & 0xffffu);
;     }
	v_mfma_f32_32x32x16_bf16 v[0:15], v[24:27], v[20:23], v[0:15]
	global_load_dwordx4 v[20:23], v[32:33], off offset:272
	global_load_dwordx4 v[24:27], v[32:33], off offset:256
	s_waitcnt vmcnt(0)
	v_cvt_pk_bf16_f32 v24, v24, v25
	v_cvt_pk_bf16_f32 v25, v26, v27
	v_cvt_pk_bf16_f32 v26, v20, v21
	v_cvt_pk_bf16_f32 v27, v22, v23
	ds_read_b128 v[20:23], v16 offset:640
	s_waitcnt lgkmcnt(0)
	v_mfma_f32_32x32x16_bf16 v[0:15], v[24:27], v[20:23], v[0:15]
	global_load_dwordx4 v[20:23], v[32:33], off offset:336
	global_load_dwordx4 v[24:27], v[32:33], off offset:320
	s_waitcnt vmcnt(0)
	v_cvt_pk_bf16_f32 v24, v24, v25
	v_cvt_pk_bf16_f32 v25, v26, v27
	v_cvt_pk_bf16_f32 v26, v20, v21
	v_cvt_pk_bf16_f32 v27, v22, v23
	ds_read_b128 v[20:23], v16 offset:672
	s_waitcnt lgkmcnt(0)
	v_mfma_f32_32x32x16_bf16 v[0:15], v[24:27], v[20:23], v[0:15]
	global_load_dwordx4 v[20:23], v[32:33], off offset:400
	global_load_dwordx4 v[24:27], v[32:33], off offset:384
	s_waitcnt vmcnt(0)
	v_cvt_pk_bf16_f32 v24, v24, v25
	v_cvt_pk_bf16_f32 v25, v26, v27
	v_cvt_pk_bf16_f32 v26, v20, v21
	v_cvt_pk_bf16_f32 v27, v22, v23
	ds_read_b128 v[20:23], v16 offset:704
	s_waitcnt lgkmcnt(0)
	v_mfma_f32_32x32x16_bf16 v[0:15], v[24:27], v[20:23], v[0:15]
	global_load_dwordx4 v[20:23], v[32:33], off offset:464
	global_load_dwordx4 v[24:27], v[32:33], off offset:448
	s_waitcnt vmcnt(0)
	v_cvt_pk_bf16_f32 v24, v24, v25
	v_cvt_pk_bf16_f32 v25, v26, v27
	v_cvt_pk_bf16_f32 v26, v20, v21
	v_cvt_pk_bf16_f32 v27, v22, v23
	ds_read_b128 v[20:23], v16 offset:736
	v_or_b32_e32 v16, s7, v17
	s_waitcnt lgkmcnt(0)
	v_mfma_f32_32x32x16_bf16 v[0:15], v[24:27], v[20:23], v[0:15]
	v_lshl_or_b32 v25, v18, 2, s8
	v_ashrrev_i32_e32 v17, 31, v16
	v_lshlrev_b64 v[20:21], 1, v[16:17]
	v_or_b32_e32 v16, s0, v25
	v_readlane_b32 s0, v255, 29
	v_lshlrev_b32_e32 v24, 2, v16
	v_readlane_b32 s1, v255, 30
	v_readlane_b32 s8, v254, 29
	v_readlane_b32 s9, v254, 30
	v_or_b32_e32 v194, s6, v25
	v_lshlrev_b64 v[26:27], 9, v[194:195]
	v_lshl_add_u64 v[22:23], s[8:9], 0, v[20:21]
	global_load_dwordx4 v[16:19], v24, s[0:1]
	v_lshl_add_u64 v[26:27], v[22:23], 0, v[26:27]
	s_waitcnt vmcnt(0)
	v_add_f32_e32 v0, v0, v16
	global_load_ushort v16, v[26:27], off
	v_lshlrev_b64 v[26:27], 11, v[194:195]
	v_lshl_add_u64 v[26:27], s[86:87], 0, v[26:27]
	v_lshl_add_u64 v[26:27], v[26:27], 0, v[20:21]
	v_add_f32_e32 v25, v1, v17
	v_mov_b32_e32 v1, v195
	v_add_f32_e32 v2, v2, v18
	s_waitcnt vmcnt(0)
	v_lshlrev_b32_e32 v16, 16, v16
	v_mul_f32_e32 v0, v0, v16
	v_cvt_pk_bf16_f32 v0, v0, s0
	global_store_short v[26:27], v0, off offset:768
	v_or_b32_e32 v0, 1, v194
	v_lshlrev_b64 v[16:17], 9, v[0:1]
	v_lshl_add_u64 v[16:17], v[22:23], 0, v[16:17]
	global_load_ushort v16, v[16:17], off
	v_lshlrev_b64 v[0:1], 11, v[0:1]
	v_lshl_add_u64 v[0:1], s[86:87], 0, v[0:1]
	v_lshl_add_u64 v[0:1], v[0:1], 0, v[20:21]
	s_waitcnt vmcnt(0)
	v_lshlrev_b32_e32 v16, 16, v16
	v_mul_f32_e32 v16, v25, v16
	v_cvt_pk_bf16_f32 v16, v16, s0
	global_store_short v[0:1], v16, off offset:768
	v_or_b32_e32 v0, 2, v194
	v_mov_b32_e32 v1, v195
	v_lshlrev_b64 v[16:17], 9, v[0:1]
	v_lshl_add_u64 v[16:17], v[22:23], 0, v[16:17]
	global_load_ushort v16, v[16:17], off
	v_lshlrev_b64 v[0:1], 11, v[0:1]
	v_lshl_add_u64 v[0:1], s[86:87], 0, v[0:1]
	v_lshl_add_u64 v[0:1], v[0:1], 0, v[20:21]
	v_mov_b32_e32 v17, v195
	s_waitcnt vmcnt(0)
	v_lshlrev_b32_e32 v16, 16, v16
	v_mul_f32_e32 v2, v2, v16
	v_cvt_pk_bf16_f32 v2, v2, s0
	global_store_short v[0:1], v2, off offset:768
	v_or_b32_e32 v0, 3, v194
	v_mov_b32_e32 v1, v195
	v_add_f32_e32 v16, v3, v19
	v_lshlrev_b64 v[2:3], 9, v[0:1]
	v_lshl_add_u64 v[2:3], v[22:23], 0, v[2:3]
	global_load_ushort v2, v[2:3], off
	v_lshlrev_b64 v[0:1], 11, v[0:1]
	v_lshl_add_u64 v[0:1], s[86:87], 0, v[0:1]
	v_lshl_add_u64 v[0:1], v[0:1], 0, v[20:21]
	s_waitcnt vmcnt(0)
	v_lshlrev_b32_e32 v2, 16, v2
	v_mul_f32_e32 v2, v16, v2
	v_cvt_pk_bf16_f32 v2, v2, s0
	global_store_short v[0:1], v2, off offset:768
	global_load_dwordx4 v[0:3], v24, s[0:1] offset:32
	v_or_b32_e32 v16, 8, v194
	v_lshlrev_b64 v[18:19], 9, v[16:17]
	v_lshl_add_u64 v[18:19], v[22:23], 0, v[18:19]
	v_lshlrev_b64 v[16:17], 11, v[16:17]
	v_lshl_add_u64 v[16:17], s[86:87], 0, v[16:17]
	v_lshl_add_u64 v[16:17], v[16:17], 0, v[20:21]
	s_waitcnt vmcnt(0)
	v_add_f32_e32 v0, v4, v0
	global_load_ushort v4, v[18:19], off
	v_add_f32_e32 v2, v6, v2
	s_waitcnt vmcnt(0)
	v_lshlrev_b32_e32 v4, 16, v4
	v_mul_f32_e32 v0, v0, v4
	v_cvt_pk_bf16_f32 v0, v0, s0
	global_store_short v[16:17], v0, off offset:768
	v_add_f32_e32 v16, v5, v1
	v_or_b32_e32 v0, 9, v194
	v_mov_b32_e32 v1, v195
	v_lshlrev_b64 v[4:5], 9, v[0:1]
	v_lshl_add_u64 v[4:5], v[22:23], 0, v[4:5]
	global_load_ushort v4, v[4:5], off
	v_lshlrev_b64 v[0:1], 11, v[0:1]
	v_lshl_add_u64 v[0:1], s[86:87], 0, v[0:1]
	v_lshl_add_u64 v[0:1], v[0:1], 0, v[20:21]
	s_waitcnt vmcnt(0)
; __device__ __forceinline__ unsigned cvt_pk_bf16(float lo, float hi) { const f32x2 v = {lo, hi}; const bf16x2_t b = __builtin_convertvector(v, bf16x2_t); return __builtin_bit_cast(unsigned, b); }
; __device__ __forceinline__ float bf2f(bf16_t v) { return __uint_as_float(((unsigned)v) << 16); }
; __device__ __forceinline__ int crow(int r, int hi) { return (r & 3) + 8 * (r >> 2) + 4 * hi; }
; __device__ __forceinline__ void bmix_unit(LAS unsigned char* lds, const bf16_t* U, const bf16_t* VG, const float* gv  , const float* ws  , const float* bs  ,
;                                           int ci, int g, bf16_t* Y) {
;     ...
; #pragma unroll
;     for (int r = 0; r < 16; ++r) {
;         const int p = pblk * 32 + crow(r, hi); const int col = g * 64 + cblk * 32 + r32;
;         const float mixed = acc[r] + bs[g * 128 + p];
;         const float uu = bf2f(U[(size_t)(r0 + p) * 256 + col]);
;         Y[(size_t)(r0 + p) * DM + 384 + col] = (bf16_t)(cvt_pk_bf16(uu * mixed, 0.f) & 0xffffu);
;     }
	v_lshlrev_b32_e32 v4, 16, v4
	v_mul_f32_e32 v4, v16, v4
	v_cvt_pk_bf16_f32 v4, v4, s0
	global_store_short v[0:1], v4, off offset:768
	v_or_b32_e32 v0, 10, v194
	v_mov_b32_e32 v1, v195
	v_lshlrev_b64 v[4:5], 9, v[0:1]
	v_lshl_add_u64 v[4:5], v[22:23], 0, v[4:5]
	global_load_ushort v4, v[4:5], off
	v_lshlrev_b64 v[0:1], 11, v[0:1]
	v_lshl_add_u64 v[0:1], s[86:87], 0, v[0:1]
	v_lshl_add_u64 v[0:1], v[0:1], 0, v[20:21]
	v_mov_b32_e32 v5, v195
	s_waitcnt vmcnt(0)
	v_lshlrev_b32_e32 v4, 16, v4
	v_mul_f32_e32 v2, v2, v4
	v_cvt_pk_bf16_f32 v2, v2, s0
	global_store_short v[0:1], v2, off offset:768
	v_or_b32_e32 v0, 11, v194
	v_mov_b32_e32 v1, v195
	v_add_f32_e32 v4, v7, v3
	v_lshlrev_b64 v[2:3], 9, v[0:1]
	v_lshl_add_u64 v[2:3], v[22:23], 0, v[2:3]
	global_load_ushort v2, v[2:3], off
	v_lshlrev_b64 v[0:1], 11, v[0:1]
	v_lshl_add_u64 v[0:1], s[86:87], 0, v[0:1]
	v_lshl_add_u64 v[0:1], v[0:1], 0, v[20:21]
	s_waitcnt vmcnt(0)
	v_lshlrev_b32_e32 v2, 16, v2
	v_mul_f32_e32 v2, v4, v2
	v_or_b32_e32 v4, 16, v194
	v_lshlrev_b64 v[6:7], 9, v[4:5]
	v_cvt_pk_bf16_f32 v2, v2, s0
	v_lshl_add_u64 v[6:7], v[22:23], 0, v[6:7]
	global_store_short v[0:1], v2, off offset:768
	global_load_dwordx4 v[0:3], v24, s[0:1] offset:64
	v_lshlrev_b64 v[4:5], 11, v[4:5]
	global_load_ushort v6, v[6:7], off
	v_lshl_add_u64 v[4:5], s[86:87], 0, v[4:5]
	v_lshl_add_u64 v[4:5], v[4:5], 0, v[20:21]
	s_waitcnt vmcnt(1)
	v_add_f32_e32 v0, v8, v0
	v_add_f32_e32 v2, v10, v2
	s_waitcnt vmcnt(0)
	v_lshlrev_b32_e32 v6, 16, v6
	v_mul_f32_e32 v0, v0, v6
	v_cvt_pk_bf16_f32 v0, v0, s0
	global_store_short v[4:5], v0, off offset:768
	v_add_f32_e32 v6, v9, v1
	v_or_b32_e32 v0, 17, v194
	v_mov_b32_e32 v1, v195
	v_lshlrev_b64 v[4:5], 9, v[0:1]
	v_lshl_add_u64 v[4:5], v[22:23], 0, v[4:5]
	global_load_ushort v4, v[4:5], off
	v_lshlrev_b64 v[0:1], 11, v[0:1]
	v_lshl_add_u64 v[0:1], s[86:87], 0, v[0:1]
	v_lshl_add_u64 v[0:1], v[0:1], 0, v[20:21]
	s_waitcnt vmcnt(0)
	v_lshlrev_b32_e32 v4, 16, v4
	v_mul_f32_e32 v4, v6, v4
	v_cvt_pk_bf16_f32 v4, v4, s0
	global_store_short v[0:1], v4, off offset:768
	v_or_b32_e32 v0, 18, v194
	v_mov_b32_e32 v1, v195
	v_lshlrev_b64 v[4:5], 9, v[0:1]
	v_lshl_add_u64 v[4:5], v[22:23], 0, v[4:5]
	global_load_ushort v4, v[4:5], off
	v_lshlrev_b64 v[0:1], 11, v[0:1]
	v_lshl_add_u64 v[0:1], s[86:87], 0, v[0:1]
	v_lshl_add_u64 v[0:1], v[0:1], 0, v[20:21]
	v_mov_b32_e32 v5, v195
	s_waitcnt vmcnt(0)
	v_lshlrev_b32_e32 v4, 16, v4
	v_mul_f32_e32 v2, v2, v4
	v_cvt_pk_bf16_f32 v2, v2, s0
	global_store_short v[0:1], v2, off offset:768
	v_or_b32_e32 v0, 19, v194
	v_mov_b32_e32 v1, v195
	v_add_f32_e32 v4, v11, v3
	v_lshlrev_b64 v[2:3], 9, v[0:1]
	v_lshl_add_u64 v[2:3], v[22:23], 0, v[2:3]
	global_load_ushort v2, v[2:3], off
	v_lshlrev_b64 v[0:1], 11, v[0:1]
	v_lshl_add_u64 v[0:1], s[86:87], 0, v[0:1]
	v_lshl_add_u64 v[0:1], v[0:1], 0, v[20:21]
	s_waitcnt vmcnt(0)
	v_lshlrev_b32_e32 v2, 16, v2
	v_mul_f32_e32 v2, v4, v2
	v_or_b32_e32 v4, 24, v194
	v_lshlrev_b64 v[6:7], 9, v[4:5]
	v_cvt_pk_bf16_f32 v2, v2, s0
	v_lshl_add_u64 v[6:7], v[22:23], 0, v[6:7]
	global_store_short v[0:1], v2, off offset:768
	global_load_dwordx4 v[0:3], v24, s[0:1] offset:96
	v_lshlrev_b64 v[4:5], 11, v[4:5]
	global_load_ushort v6, v[6:7], off
	v_lshl_add_u64 v[4:5], s[86:87], 0, v[4:5]
	v_lshl_add_u64 v[4:5], v[4:5], 0, v[20:21]
	s_waitcnt vmcnt(1)
	v_add_f32_e32 v0, v12, v0
	v_add_f32_e32 v2, v14, v2
	s_waitcnt vmcnt(0)
	v_lshlrev_b32_e32 v6, 16, v6
	v_mul_f32_e32 v0, v0, v6
	v_cvt_pk_bf16_f32 v0, v0, s0
	global_store_short v[4:5], v0, off offset:768
	v_add_f32_e32 v6, v13, v1
	v_or_b32_e32 v0, 25, v194
	v_mov_b32_e32 v1, v195
	v_lshlrev_b64 v[4:5], 9, v[0:1]
	v_lshl_add_u64 v[4:5], v[22:23], 0, v[4:5]
	global_load_ushort v4, v[4:5], off
	v_lshlrev_b64 v[0:1], 11, v[0:1]
	v_lshl_add_u64 v[0:1], s[86:87], 0, v[0:1]
	v_lshl_add_u64 v[0:1], v[0:1], 0, v[20:21]
	s_waitcnt vmcnt(0)
	v_lshlrev_b32_e32 v4, 16, v4
	v_mul_f32_e32 v4, v6, v4
	v_cvt_pk_bf16_f32 v4, v4, s0
	global_store_short v[0:1], v4, off offset:768
	v_or_b32_e32 v0, 26, v194
	v_mov_b32_e32 v1, v195
	v_lshlrev_b64 v[4:5], 9, v[0:1]
	v_lshl_add_u64 v[4:5], v[22:23], 0, v[4:5]
	global_load_ushort v4, v[4:5], off
	v_lshlrev_b64 v[0:1], 11, v[0:1]
	v_lshl_add_u64 v[0:1], s[86:87], 0, v[0:1]
	v_lshl_add_u64 v[0:1], v[0:1], 0, v[20:21]
	v_or_b32_e32 v194, 27, v194
	s_waitcnt vmcnt(0)
	v_lshlrev_b32_e32 v4, 16, v4
	v_mul_f32_e32 v2, v2, v4
	v_cvt_pk_bf16_f32 v2, v2, s0
	global_store_short v[0:1], v2, off offset:768
	v_lshlrev_b64 v[0:1], 9, v[194:195]
	v_lshl_add_u64 v[0:1], v[22:23], 0, v[0:1]
	global_load_ushort v0, v[0:1], off
	v_add_f32_e32 v2, v15, v3
	s_waitcnt vmcnt(0)
	v_lshlrev_b32_e32 v0, 16, v0
	v_mul_f32_e32 v0, v2, v0
	v_cvt_pk_bf16_f32 v2, v0, s0
	v_lshlrev_b64 v[0:1], 11, v[194:195]
	v_lshl_add_u64 v[0:1], s[86:87], 0, v[0:1]
	v_lshl_add_u64 v[0:1], v[0:1], 0, v[20:21]
	global_store_short v[0:1], v2, off offset:768
	s_barrier
	s_mov_b64 s[0:1], 0

.LBB0_607:
	s_nop 6
	v_maximum3_f32 v32, v16, v0, v0
	v_maximum3_f32 v33, v1, v18, v2
	v_maximum3_f32 v32, v32, v17, v19
	v_maximum3_f32 v33, v33, v20, v4
	v_maximum3_f32 v32, v32, v3, v21
	v_maximum3_f32 v33, v33, v22, v6
	v_maximum3_f32 v32, v32, v5, v23
	v_maximum3_f32 v33, v33, v24, v8
	v_maximum3_f32 v32, v32, v7, v25
	v_maximum3_f32 v33, v33, v26, v10
	v_maximum3_f32 v32, v32, v9, v27
	v_maximum3_f32 v33, v33, v28, v12
	v_maximum3_f32 v32, v32, v11, v29
	v_maximum3_f32 v33, v33, v30, v14
	v_maximum3_f32 v32, v32, v13, v31
	v_maximum3_f32 v32, v32, v15, v33
	v_mov_b32_e32 v33, v32
	s_nop 1
	v_permlane32_swap_b32_e32 v32, v33
	v_maximum3_f32 v32, v32, v33, v33
	v_sub_f32_e32 v16, v16, v32
	v_sub_f32_e32 v33, v0, v32
	v_sub_f32_e32 v34, v17, v32
	v_sub_f32_e32 v35, v1, v32
	v_sub_f32_e32 v18, v18, v32
	v_sub_f32_e32 v36, v2, v32
	v_sub_f32_e32 v37, v19, v32
	v_sub_f32_e32 v38, v3, v32
	v_sub_f32_e32 v39, v20, v32
	v_sub_f32_e32 v40, v4, v32
	v_sub_f32_e32 v41, v21, v32
	v_sub_f32_e32 v42, v5, v32
	v_exp_f32_e32 v17, v16
	v_exp_f32_e32 v19, v34
	v_exp_f32_e32 v59, v33
	v_exp_f32_e32 v61, v35
	v_exp_f32_e32 v16, v18
	v_exp_f32_e32 v18, v37
	v_exp_f32_e32 v58, v36
	v_exp_f32_e32 v60, v38
	v_exp_f32_e32 v63, v39
	v_exp_f32_e32 v65, v41
	v_exp_f32_e32 v62, v40
	v_exp_f32_e32 v64, v42
	v_sub_f32_e32 v43, v22, v32
	v_sub_f32_e32 v45, v23, v32
	v_add_f32_e32 v20, v18, v16
	v_add_f32_e32 v21, v19, v17
	v_add_f32_e32 v22, v60, v58
	v_add_f32_e32 v23, v61, v59
	v_sub_f32_e32 v44, v6, v32
	v_sub_f32_e32 v46, v7, v32
	v_add_f32_e32 v20, v22, v20
	v_add_f32_e32 v21, v23, v21
	v_add_f32_e32 v22, v64, v62
	v_add_f32_e32 v23, v65, v63
	v_sub_f32_e32 v24, v24, v32
	v_sub_f32_e32 v47, v8, v32
	v_sub_f32_e32 v25, v25, v32
	v_sub_f32_e32 v49, v9, v32
	v_add_f32_e32 v21, 0, v21
	v_exp_f32_e32 v130, v43
	v_exp_f32_e32 v131, v45
	v_add_f32_e32 v23, v22, v23
	v_add_f32_e32 v22, v22, v22
	v_exp_f32_e32 v136, v44
	v_exp_f32_e32 v137, v46
	v_add_f32_e32 v21, v20, v21
	v_exp_f32_e32 v20, v24
	v_exp_f32_e32 v22, v25
	v_exp_f32_e32 v66, v47
	v_exp_f32_e32 v68, v49
	v_sub_f32_e32 v26, v26, v32
	v_sub_f32_e32 v51, v10, v32
	v_sub_f32_e32 v27, v27, v32
	v_sub_f32_e32 v52, v11, v32
	v_exp_f32_e32 v71, v26
	v_exp_f32_e32 v73, v27
	v_exp_f32_e32 v70, v51
	v_exp_f32_e32 v72, v52
	v_add_f32_e32 v67, v131, v130
	v_add_f32_e32 v69, v137, v136
	v_add_f32_e32 v24, v22, v20
	v_add_f32_e32 v25, v23, v21
	v_add_f32_e32 v26, v68, v66
	v_add_f32_e32 v27, v69, v67
	v_sub_f32_e32 v28, v28, v32
	v_add_f32_e32 v24, v26, v24
	v_add_f32_e32 v25, v27, v25
	v_sub_f32_e32 v53, v12, v32
	v_sub_f32_e32 v29, v29, v32
	v_sub_f32_e32 v54, v13, v32
	v_add_f32_e32 v56, v24, v24
	v_add_f32_e32 v57, v24, v25
	v_add_f32_e32 v24, v72, v70
	v_add_f32_e32 v25, v73, v71
	v_sub_f32_e32 v30, v30, v32
	v_sub_f32_e32 v55, v14, v32
	v_sub_f32_e32 v31, v31, v32
	v_sub_f32_e32 v77, v15, v32
	v_add_f32_e32 v74, v24, v24
	v_add_f32_e32 v75, v24, v25
	v_exp_f32_e32 v49, v28
	v_exp_f32_e32 v51, v29
	v_exp_f32_e32 v67, v53
	v_exp_f32_e32 v69, v54
	v_mov_b32_e32 v0, v195
	v_exp_f32_e32 v56, v30
	v_exp_f32_e32 v74, v31
	v_exp_f32_e32 v76, v55
	v_exp_f32_e32 v78, v77
	v_add_f32_e32 v77, v51, v49
	v_add_u32_e32 v4, v135, v0
	ds_read_b128 v[0:3], v4 offset:16384
	v_add_f32_e32 v79, v69, v67
	v_add_f32_e32 v24, v74, v56
	v_add_f32_e32 v25, v75, v57
	v_add_f32_e32 v26, v78, v76
	v_add_f32_e32 v27, v79, v77
	v_mov_b32_e32 v8, v195
	v_add_f32_e32 v24, v26, v24
	v_add_f32_e32 v25, v27, v25
	ds_read_b128 v[4:7], v4 offset:16896
	v_pk_add_f32 v[24:25], v[24:25], v[24:25] op_sel:[0,1] op_sel_hi:[1,0]
	v_cvt_pk_bf16_f32 v52, v20, v22
	v_mov_b32_e32 v25, v32
	v_add_f32_e32 v128, 0, v24
	v_add_f32_e32 v129, 0, v25
	v_add_u32_e32 v12, v135, v8
	v_xor_b32_e32 v32, 0x80000000, v129
	ds_read_b128 v[8:11], v12 offset:18432
	v_mov_b32_e32 v33, v32
	v_mov_b32_e32 v34, v32
	v_mov_b32_e32 v35, v32
	v_mov_b32_e32 v36, v32
	v_mov_b32_e32 v37, v32
	v_mov_b32_e32 v38, v32
	v_mov_b32_e32 v39, v32
	v_mov_b32_e32 v40, v32
	v_mov_b32_e32 v41, v32
	v_mov_b32_e32 v42, v32
	v_mov_b32_e32 v43, v32
	v_mov_b32_e32 v44, v32
	v_mov_b32_e32 v45, v32
	v_mov_b32_e32 v46, v32
	v_mov_b32_e32 v47, v32
	ds_read_b128 v[12:15], v12 offset:18944
	v_mov_b64_e32 v[110:111], v[46:47]
	s_waitcnt lgkmcnt(0)
	v_mfma_f32_32x32x16_bf16 v[80:95], v[0:3], v[124:127], v[32:47]
	v_mov_b32_e32 v0, v195
	v_mov_b64_e32 v[108:109], v[44:45]
	v_add_u32_e32 v21, v135, v0
	ds_read_b128 v[0:3], v21 offset:20480
	v_mov_b64_e32 v[106:107], v[42:43]
	v_mov_b64_e32 v[104:105], v[40:41]
	v_mov_b64_e32 v[102:103], v[38:39]
	v_mov_b64_e32 v[100:101], v[36:37]
	v_mov_b64_e32 v[98:99], v[34:35]
	v_mov_b64_e32 v[96:97], v[32:33]
	v_cvt_pk_bf16_f32 v53, v71, v73
	v_cvt_pk_bf16_f32 v54, v49, v51
	v_mfma_f32_32x32x16_bf16 v[96:111], v[4:7], v[124:127], v[96:111]
	ds_read_b128 v[34:37], v21 offset:20992
	v_mov_b32_e32 v4, v195
	v_cvt_pk_bf16_f32 v5, v16, v18
	v_add_u32_e32 v6, v135, v4
	v_cvt_pk_bf16_f32 v4, v17, v19
	v_cvt_pk_bf16_f32 v7, v130, v131
	v_mfma_f32_32x32x16_bf16 v[80:95], v[8:11], v[120:123], v[80:95]
	ds_read_b128 v[38:41], v6 offset:22528
	v_cvt_pk_bf16_f32 v55, v56, v74
	v_cvt_pk_bf16_f32 v56, v59, v61
	v_cvt_pk_bf16_f32 v57, v58, v60
	v_cvt_pk_bf16_f32 v58, v62, v64
	v_cvt_pk_bf16_f32 v59, v136, v137
	v_cvt_pk_bf16_f32 v60, v66, v68
	v_mfma_f32_32x32x16_bf16 v[96:111], v[12:15], v[120:123], v[96:111]
	ds_read_b128 v[42:45], v6 offset:23040
	v_cvt_pk_bf16_f32 v6, v63, v65
	v_cvt_pk_bf16_f32 v61, v70, v72
	v_cvt_pk_bf16_f32 v62, v67, v69
	v_cvt_pk_bf16_f32 v63, v76, v78
	s_and_b64 vcc, exec, s[34:35]
	s_or_b32 s6, s71, 0x80c0
	s_waitcnt lgkmcnt(0)
	v_mfma_f32_32x32x16_bf16 v[80:95], v[0:3], v[116:119], v[80:95]
	ds_read_b128 v[0:3], v135 offset:8192
	s_waitcnt lgkmcnt(0)
	v_mfma_f32_32x32x16_bf16 v[16:31], v[4:7], v[0:3], 0
	ds_read_b128 v[0:3], v135 offset:10240
	s_waitcnt lgkmcnt(0)
	v_mfma_f32_32x32x16_bf16 v[16:31], v[52:55], v[0:3], v[16:31]
	ds_read_b128 v[0:3], v135 offset:12288
	s_waitcnt lgkmcnt(0)
	v_mfma_f32_32x32x16_bf16 v[16:31], v[56:59], v[0:3], v[16:31]
	ds_read_b128 v[0:3], v135 offset:14336
	s_waitcnt lgkmcnt(0)
	v_mfma_f32_32x32x16_bf16 v[16:31], v[60:63], v[0:3], v[16:31]
	ds_read_b128 v[0:3], v135 offset:8704
	s_waitcnt lgkmcnt(0)
	v_mfma_f32_32x32x16_bf16 v[0:15], v[4:7], v[0:3], 0
	ds_read_b128 v[64:67], v135 offset:10752
	s_waitcnt lgkmcnt(0)
	v_mfma_f32_32x32x16_bf16 v[0:15], v[52:55], v[64:67], v[0:15]
	ds_read_b128 v[52:55], v135 offset:12800
	s_waitcnt lgkmcnt(0)
	v_mfma_f32_32x32x16_bf16 v[0:15], v[56:59], v[52:55], v[0:15]
	ds_read_b128 v[52:55], v135 offset:14848
	s_waitcnt vmcnt(0)
	s_waitcnt vmcnt(0) lgkmcnt(0)
	s_barrier
	v_mfma_f32_32x32x16_bf16 v[96:111], v[34:37], v[116:119], v[96:111]
	v_mfma_f32_32x32x16_bf16 v[0:15], v[60:63], v[52:55], v[0:15]
	v_mfma_f32_32x32x16_bf16 v[80:95], v[38:41], v[112:115], v[80:95]
	v_mfma_f32_32x32x16_bf16 v[96:111], v[42:45], v[112:115], v[96:111]
	s_cbranch_vccnz .LBB0_609
	v_or_b32_e32 v33, s6, v50
	v_lshl_add_u32 v34, v33, 6, s72
	v_mov_b32_e32 v35, v195
	v_lshl_add_u64 v[34:35], v[34:35], 1, s[38:39]
	s_add_i32 m0, s5, 0
	s_nop 0
	global_load_lds_dwordx4 v[34:35], off

.LBB0_611:
	s_nop 8
	v_maximum3_f32 v33, v80, v96, v96
	v_maximum3_f32 v34, v97, v82, v98
	v_maximum3_f32 v33, v33, v81, v83
	v_maximum3_f32 v34, v34, v84, v100
	v_maximum3_f32 v33, v33, v99, v85
	v_maximum3_f32 v34, v34, v86, v102
	v_maximum3_f32 v33, v33, v101, v87
	v_maximum3_f32 v34, v34, v88, v104
	v_maximum3_f32 v33, v33, v103, v89
	v_maximum3_f32 v34, v34, v90, v106
	v_maximum3_f32 v33, v33, v105, v91
	v_maximum3_f32 v34, v34, v92, v108
	v_maximum3_f32 v33, v33, v107, v93
	v_maximum3_f32 v34, v34, v94, v110
	v_maximum3_f32 v33, v33, v109, v95
	v_maximum3_f32 v33, v33, v111, v34
	v_mov_b32_e32 v34, v33
	s_nop 1
	v_permlane32_swap_b32_e32 v33, v34
	v_and_b32_e32 v136, 63, v132
	v_maximum3_f32 v33, v33, v34, v34
	v_cmp_gt_u32_e64 s[34:35], 32, v136
	v_lshl_add_u32 v137, v133, 2, s70
	v_cmp_lt_f32_e32 vcc, s46, v33
	s_cbranch_vccz .LBB0_615
	v_max_f32_e32 v32, v33, v33
	v_max_f32_e32 v35, 0, v32
	v_exp_f32_e64 v34, -v35
	s_and_saveexec_b64 s[6:7], s[34:35]
	ds_write_b32 v137, v34 offset:49152
	s_or_b64 exec, exec, s[6:7]
	v_add_f32_e32 v32, v128, v34
	v_add_f32_e32 v33, v129, v35
	v_mov_b32_e32 v36, v35
	s_waitcnt lgkmcnt(0)
	v_add_u32_e32 v35, s70, v194
	v_sub_f32_e32 v80, v80, v36
	v_sub_f32_e32 v81, v81, v36
	v_sub_f32_e32 v96, v96, v36
	v_sub_f32_e32 v97, v97, v36
	v_sub_f32_e32 v82, v82, v36
	v_sub_f32_e32 v83, v83, v36
	v_sub_f32_e32 v98, v98, v36
	v_sub_f32_e32 v99, v99, v36
	v_sub_f32_e32 v84, v84, v36
	v_sub_f32_e32 v85, v85, v36
	v_sub_f32_e32 v100, v100, v36
	v_sub_f32_e32 v101, v101, v36
	v_sub_f32_e32 v86, v86, v36
	v_sub_f32_e32 v87, v87, v36
	v_sub_f32_e32 v102, v102, v36
	v_sub_f32_e32 v103, v103, v36
	v_sub_f32_e32 v88, v88, v36
	v_sub_f32_e32 v89, v89, v36
	v_sub_f32_e32 v104, v104, v36
	v_sub_f32_e32 v105, v105, v36
	v_sub_f32_e32 v90, v90, v36
	v_sub_f32_e32 v91, v91, v36
	v_sub_f32_e32 v106, v106, v36
	v_sub_f32_e32 v107, v107, v36
	v_sub_f32_e32 v92, v92, v36
	v_sub_f32_e32 v93, v93, v36
	v_sub_f32_e32 v108, v108, v36
	v_sub_f32_e32 v109, v109, v36
	v_sub_f32_e32 v94, v94, v36
	v_sub_f32_e32 v95, v95, v36
	v_sub_f32_e32 v110, v110, v36
	v_sub_f32_e32 v111, v111, v36
	ds_read_b128 v[36:39], v35 offset:49152
	ds_read_b128 v[40:43], v35 offset:49184
	ds_read_b128 v[44:47], v35 offset:49216
	ds_read_b128 v[48:51], v35 offset:49248
	s_waitcnt lgkmcnt(0)
	v_xor_b32_e32 v32, 0x80000000, v33
	s_waitcnt lgkmcnt(0)
	v_mul_f32_e32 v20, v20, v40
	v_mul_f32_e32 v21, v21, v41
	v_mul_f32_e32 v24, v24, v44
	v_mul_f32_e32 v25, v25, v45
	v_mul_f32_e32 v28, v28, v48
	v_mul_f32_e32 v29, v29, v49
	v_mul_f32_e32 v30, v30, v50
	v_mul_f32_e32 v31, v31, v51
	v_mul_f32_e32 v26, v26, v46
	v_mul_f32_e32 v27, v27, v47
	v_mul_f32_e32 v22, v22, v42
	v_mul_f32_e32 v23, v23, v43
	v_mul_f32_e32 v18, v18, v38
	v_mul_f32_e32 v19, v19, v39
	v_mul_f32_e32 v16, v16, v36
	v_mul_f32_e32 v17, v17, v37
	v_mul_f32_e32 v12, v12, v48
	v_mul_f32_e32 v13, v13, v49
	v_mul_f32_e32 v8, v8, v44
	v_mul_f32_e32 v9, v9, v45
	v_mul_f32_e32 v4, v4, v40
	v_mul_f32_e32 v5, v5, v41
	v_mul_f32_e32 v14, v14, v50
	v_mul_f32_e32 v15, v15, v51
	v_mul_f32_e32 v10, v10, v46
	v_mul_f32_e32 v11, v11, v47
	v_mul_f32_e32 v6, v6, v42
	v_mul_f32_e32 v7, v7, v43
	v_mul_f32_e32 v2, v2, v38
	v_mul_f32_e32 v3, v3, v39
	v_mul_f32_e32 v0, v0, v36
	v_mul_f32_e32 v1, v1, v37
	v_mul_f32_e32 v128, v128, v34
	v_mov_b32_e32 v129, v33
.LBB0_615:
	v_mov_b32_e32 v48, v195
	v_mov_b32_e32 v33, v32
	v_add_u32_e32 v52, v135, v48
	ds_read_b128 v[48:51], v52 offset:32768
	ds_read_b128 v[138:141], v52 offset:33280
	v_mov_b32_e32 v52, v195
	v_mov_b32_e32 v34, v32
	v_mov_b32_e32 v35, v32
	v_mov_b32_e32 v36, v32
	v_mov_b32_e32 v37, v32
	v_mov_b32_e32 v38, v32
	v_mov_b32_e32 v39, v32
	v_mov_b32_e32 v40, v32
	v_mov_b32_e32 v41, v32
	v_mov_b32_e32 v42, v32
	v_mov_b32_e32 v43, v32
	v_mov_b32_e32 v44, v32
	v_mov_b32_e32 v45, v32
	v_mov_b32_e32 v46, v32
	v_mov_b32_e32 v47, v32
	v_add_u32_e32 v52, v135, v52
	ds_read_b128 v[142:145], v52 offset:34816
	ds_read_b128 v[146:149], v52 offset:35328
	s_waitcnt lgkmcnt(0)
	v_mfma_f32_32x32x16_bf16 v[64:79], v[48:51], v[124:127], v[32:47]
	v_exp_f32_e32 v131, v80
	v_exp_f32_e32 v151, v97
	v_exp_f32_e32 v130, v82
	v_exp_f32_e32 v150, v99
	v_exp_f32_e32 v85, v85
	v_exp_f32_e32 v91, v91
	v_mfma_f32_32x32x16_bf16 v[48:63], v[138:141], v[124:127], v[32:47]
	v_exp_f32_e32 v139, v81
	v_exp_f32_e32 v141, v96
	v_exp_f32_e32 v138, v83
	v_exp_f32_e32 v140, v98
	v_cvt_pk_bf16_f32 v96, v131, v139
	v_cvt_pk_bf16_f32 v80, v141, v151
	v_add_f32_e32 v82, v138, v130
	v_add_f32_e32 v83, v139, v131
	v_add_f32_e32 v98, v150, v140
	v_add_f32_e32 v99, v151, v141
	v_cvt_pk_bf16_f32 v97, v130, v138
	v_add_f32_e32 v82, v98, v82
	v_add_f32_e32 v83, v99, v83
	v_exp_f32_e32 v130, v88
	v_add_f32_e32 v81, 0, v83
	v_add_f32_e32 v131, v82, v81
	v_mov_b32_e32 v82, v195
	v_cvt_pk_bf16_f32 v81, v140, v150
	v_add_u32_e32 v82, v135, v82
	ds_read_b128 v[138:141], v82 offset:36864
	v_mfma_f32_32x32x16_bf16 v[64:79], v[142:145], v[120:123], v[64:79]
	ds_read_b128 v[150:153], v82 offset:37376
	v_exp_f32_e32 v83, v84
	v_exp_f32_e32 v82, v100
	v_exp_f32_e32 v84, v101
	v_exp_f32_e32 v100, v103
	v_add_f32_e32 v98, v84, v82
	v_add_f32_e32 v99, v85, v83
	s_nop 0
	v_add_f32_e32 v154, v98, v98
	v_add_f32_e32 v155, v98, v99
	v_cvt_pk_bf16_f32 v98, v83, v85
	v_cvt_pk_bf16_f32 v82, v82, v84
	v_exp_f32_e32 v83, v86
	v_exp_f32_e32 v84, v87
	v_exp_f32_e32 v86, v102
	v_mfma_f32_32x32x16_bf16 v[48:63], v[146:149], v[120:123], v[48:63]
	v_exp_f32_e32 v154, v89
	v_add_f32_e32 v85, v84, v83
	v_cvt_pk_bf16_f32 v99, v83, v84
	v_mov_b32_e32 v84, v195
	v_add_f32_e32 v87, v100, v86
	v_add_u32_e32 v84, v135, v84
	v_cvt_pk_bf16_f32 v83, v86, v100
	ds_read_b128 v[142:145], v84 offset:38912
	s_waitcnt lgkmcnt(0)
	v_mfma_f32_32x32x16_bf16 v[64:79], v[138:141], v[116:119], v[64:79]
	ds_read_b128 v[146:149], v84 offset:39424
	v_exp_f32_e32 v84, v104
	v_exp_f32_e32 v86, v105
	ds_read_b128 v[138:141], v135 offset:24576
	v_add_f32_e32 v88, v154, v130
	v_add_f32_e32 v89, v155, v131
	v_exp_f32_e32 v104, v111
	v_add_f32_e32 v100, v86, v84
	v_add_f32_e32 v101, v87, v85
	v_cvt_pk_bf16_f32 v84, v84, v86
	v_exp_f32_e32 v87, v90
	v_exp_f32_e32 v86, v106
	v_exp_f32_e32 v90, v107
	v_add_f32_e32 v88, v100, v88
	v_add_f32_e32 v89, v101, v89
	v_add_f32_e32 v102, v90, v86
	v_add_f32_e32 v103, v91, v87
	v_add_f32_e32 v100, v88, v88
	v_add_f32_e32 v101, v88, v89
	v_add_f32_e32 v103, v102, v103
	v_add_f32_e32 v102, v102, v102
	v_cvt_pk_bf16_f32 v89, v87, v91
	v_cvt_pk_bf16_f32 v85, v86, v90
	v_exp_f32_e32 v86, v92
	v_exp_f32_e32 v87, v93
	v_exp_f32_e32 v91, v108
	v_exp_f32_e32 v92, v109
	v_exp_f32_e32 v100, v94
	v_exp_f32_e32 v102, v95
	ds_read_b128 v[106:109], v135 offset:26624
	s_waitcnt lgkmcnt(0)
	v_mfma_f32_32x32x16_bf16 v[16:31], v[96:99], v[138:141], v[16:31]
	v_cvt_pk_bf16_f32 v88, v130, v154
	v_add_f32_e32 v93, v87, v86
	v_add_f32_e32 v105, v92, v91
	v_cvt_pk_bf16_f32 v90, v86, v87
	v_cvt_pk_bf16_f32 v86, v91, v92
	v_cvt_pk_bf16_f32 v91, v100, v102
	ds_read_b128 v[138:141], v135 offset:28672
	v_exp_f32_e32 v92, v110
	v_mfma_f32_32x32x16_bf16 v[16:31], v[88:91], v[106:109], v[16:31]
	ds_read_b128 v[106:109], v135 offset:30720
	v_cvt_pk_bf16_f32 v87, v92, v104
	s_waitcnt lgkmcnt(0)
	v_mfma_f32_32x32x16_bf16 v[16:31], v[80:83], v[138:141], v[16:31]
	ds_read_b128 v[138:141], v135 offset:25088
	v_mfma_f32_32x32x16_bf16 v[16:31], v[84:87], v[106:109], v[16:31]
	ds_read_b128 v[106:109], v135 offset:27136
	s_waitcnt lgkmcnt(0)
	v_mfma_f32_32x32x16_bf16 v[0:15], v[96:99], v[138:141], v[0:15]
	v_mfma_f32_32x32x16_bf16 v[0:15], v[88:91], v[106:109], v[0:15]
	ds_read_b128 v[88:91], v135 offset:31232
	v_mfma_f32_32x32x16_bf16 v[48:63], v[150:153], v[116:119], v[48:63]
	v_mfma_f32_32x32x16_bf16 v[64:79], v[142:145], v[112:115], v[64:79]
	v_mfma_f32_32x32x16_bf16 v[48:63], v[146:149], v[112:115], v[48:63]
	ds_read_b128 v[94:97], v135 offset:29184
	s_waitcnt vmcnt(0)
	s_waitcnt vmcnt(0) lgkmcnt(0)
	s_barrier
	v_mfma_f32_32x32x16_bf16 v[0:15], v[80:83], v[94:97], v[0:15]
	v_add_f32_e64 v80, v102, v100
	v_add_f32_e64 v81, v103, v101
	v_add_f32_e64 v82, v104, v92
	v_add_f32_e64 v83, v105, v93
	v_add_f32_e64 v80, v82, v80
	v_add_f32_e64 v81, v83, v81
	v_add_f32_e32 v80, v80, v81
	v_add_f32_e32 v98, v128, v80
	v_maximum3_f32 v80, v64, v48, v48
	v_maximum3_f32 v81, v49, v66, v50
	v_maximum3_f32 v80, v80, v65, v67
	v_maximum3_f32 v81, v81, v68, v52
	v_maximum3_f32 v80, v80, v51, v69
	v_maximum3_f32 v81, v81, v70, v54
	v_maximum3_f32 v80, v80, v53, v71
	v_maximum3_f32 v81, v81, v72, v56
	v_maximum3_f32 v80, v80, v55, v73
	v_mfma_f32_32x32x16_bf16 v[0:15], v[84:87], v[88:91], v[0:15]
	v_maximum3_f32 v81, v81, v74, v58
	v_maximum3_f32 v80, v80, v57, v75
	v_maximum3_f32 v81, v81, v76, v60
	v_maximum3_f32 v80, v80, v59, v77
	v_maximum3_f32 v81, v81, v78, v62
	v_maximum3_f32 v80, v80, v61, v79
	v_maximum3_f32 v80, v80, v63, v81
	v_mov_b32_e32 v81, v80
	s_nop 1
	v_permlane32_swap_b32_e32 v80, v81
	v_maximum3_f32 v80, v80, v81, v81
	v_cmp_lt_f32_e32 vcc, s46, v80
	s_cbranch_vccz .LBB0_619
	v_max_f32_e32 v32, v80, v80
	v_max_f32_e32 v34, 0, v32
	v_exp_f32_e64 v33, -v34
	s_and_saveexec_b64 s[6:7], s[34:35]
	ds_write_b32 v137, v33 offset:49152
	s_or_b64 exec, exec, s[6:7]
	v_mul_f32_e32 v98, v98, v33
	s_waitcnt lgkmcnt(0)
	v_add_u32_e32 v33, s70, v194
	v_add_f32_e32 v32, v129, v34
	v_sub_f32_e32 v64, v64, v34
	v_sub_f32_e32 v65, v65, v34
	v_sub_f32_e32 v48, v48, v34
	v_sub_f32_e32 v49, v49, v34
	v_sub_f32_e32 v66, v66, v34
	v_sub_f32_e32 v67, v67, v34
	v_sub_f32_e32 v50, v50, v34
	v_sub_f32_e32 v51, v51, v34
	v_sub_f32_e32 v68, v68, v34
	v_sub_f32_e32 v69, v69, v34
	v_sub_f32_e32 v52, v52, v34
	v_sub_f32_e32 v53, v53, v34
	v_sub_f32_e32 v70, v70, v34
	v_sub_f32_e32 v71, v71, v34
	v_sub_f32_e32 v54, v54, v34
	v_sub_f32_e32 v55, v55, v34
	v_sub_f32_e32 v72, v72, v34
	v_sub_f32_e32 v73, v73, v34
	v_sub_f32_e32 v56, v56, v34
	v_sub_f32_e32 v57, v57, v34
	v_sub_f32_e32 v74, v74, v34
	v_sub_f32_e32 v75, v75, v34
	v_sub_f32_e32 v58, v58, v34
	v_sub_f32_e32 v59, v59, v34
	v_sub_f32_e32 v76, v76, v34
	v_sub_f32_e32 v77, v77, v34
	v_sub_f32_e32 v60, v60, v34
	v_sub_f32_e32 v61, v61, v34
	v_sub_f32_e32 v78, v78, v34
	v_sub_f32_e32 v79, v79, v34
	v_sub_f32_e32 v62, v62, v34
	v_sub_f32_e32 v63, v63, v34
	ds_read_b128 v[34:37], v33 offset:49152
	ds_read_b128 v[38:41], v33 offset:49184
	ds_read_b128 v[42:45], v33 offset:49216
	ds_read_b128 v[80:83], v33 offset:49248
	s_waitcnt lgkmcnt(0)
	v_xor_b32_e32 v32, 0x80000000, v32
	s_waitcnt lgkmcnt(2)
	v_mul_f32_e32 v20, v20, v38
	v_mul_f32_e32 v21, v21, v39
	s_waitcnt lgkmcnt(1)
	v_mul_f32_e32 v24, v24, v42
	v_mul_f32_e32 v25, v25, v43
	s_waitcnt lgkmcnt(0)
	v_mul_f32_e32 v28, v28, v80
	v_mul_f32_e32 v29, v29, v81
	v_mul_f32_e32 v30, v30, v82
	v_mul_f32_e32 v31, v31, v83
	v_mul_f32_e32 v26, v26, v44
	v_mul_f32_e32 v27, v27, v45
	v_mul_f32_e32 v22, v22, v40
	v_mul_f32_e32 v23, v23, v41
	v_mul_f32_e32 v18, v18, v36
	v_mul_f32_e32 v19, v19, v37
	v_mul_f32_e32 v16, v16, v34
	v_mul_f32_e32 v17, v17, v35
	v_mul_f32_e32 v12, v12, v80
	v_mul_f32_e32 v13, v13, v81
	v_mul_f32_e32 v8, v8, v42
	v_mul_f32_e32 v9, v9, v43
	v_mul_f32_e32 v4, v4, v38
	v_mul_f32_e32 v5, v5, v39
	v_mul_f32_e32 v14, v14, v82
	v_mul_f32_e32 v15, v15, v83
	v_mul_f32_e32 v10, v10, v44
	v_mul_f32_e32 v11, v11, v45
	v_mul_f32_e32 v6, v6, v40
	v_mul_f32_e32 v7, v7, v41
	v_mul_f32_e32 v2, v2, v36
	v_mul_f32_e32 v3, v3, v37
	v_mul_f32_e32 v0, v0, v34
	v_mul_f32_e32 v1, v1, v35
	v_mov_b32_e32 v33, v32
	v_mov_b32_e32 v34, v32
	v_mov_b32_e32 v35, v32
	v_mov_b32_e32 v36, v32
	v_mov_b32_e32 v37, v32
	v_mov_b32_e32 v38, v32
	v_mov_b32_e32 v39, v32
	v_mov_b32_e32 v40, v32
	v_mov_b32_e32 v41, v32
	v_mov_b32_e32 v42, v32
	v_mov_b32_e32 v43, v32
	v_mov_b32_e32 v44, v32
	v_mov_b32_e32 v45, v32
	v_mov_b32_e32 v46, v32
	v_mov_b32_e32 v47, v32
.LBB0_619:
	v_mov_b32_e32 v80, v195
	v_exp_f32_e32 v97, v64
	v_add_u32_e32 v80, v135, v80
	ds_read_b128 v[100:103], v80
	ds_read_b128 v[104:107], v80 offset:512
	v_mov_b32_e32 v80, v195
	v_exp_f32_e32 v96, v66
	v_add_u32_e32 v80, v135, v80
	ds_read_b128 v[108:111], v80 offset:2048
	ds_read_b128 v[128:131], v80 offset:2560
	s_waitcnt lgkmcnt(3)
	v_mfma_f32_32x32x16_bf16 v[80:95], v[100:103], v[124:127], v[32:47]
	v_exp_f32_e32 v101, v65
	v_exp_f32_e32 v103, v48
	v_exp_f32_e32 v100, v67
	v_exp_f32_e32 v102, v50
	v_cvt_pk_bf16_f32 v64, v97, v101
	v_exp_f32_e32 v69, v69
	v_cvt_pk_bf16_f32 v65, v96, v100
	s_waitcnt lgkmcnt(2)
	v_mfma_f32_32x32x16_bf16 v[32:47], v[104:107], v[124:127], v[32:47]
	v_exp_f32_e32 v105, v49
	v_exp_f32_e32 v104, v51
	v_add_f32_e32 v50, v100, v96
	v_add_f32_e32 v51, v101, v97
	v_exp_f32_e32 v54, v54
	v_cvt_pk_bf16_f32 v48, v103, v105
	v_add_f32_e32 v66, v104, v102
	v_add_f32_e32 v67, v105, v103
	v_exp_f32_e32 v96, v72
	v_add_f32_e32 v50, v66, v50
	v_add_f32_e32 v51, v67, v51
	v_exp_f32_e32 v72, v59
	v_add_f32_e32 v49, 0, v51
	v_add_f32_e32 v97, v50, v49
	v_mov_b32_e32 v50, v195
	v_cvt_pk_bf16_f32 v49, v102, v104
	v_add_u32_e32 v50, v135, v50
	ds_read_b128 v[100:103], v50 offset:4096
	s_waitcnt lgkmcnt(2)
	v_mfma_f32_32x32x16_bf16 v[80:95], v[108:111], v[120:123], v[80:95]
	ds_read_b128 v[104:107], v50 offset:4608
	v_exp_f32_e32 v51, v68
	v_exp_f32_e32 v50, v52
	v_exp_f32_e32 v68, v53
	v_cvt_pk_bf16_f32 v66, v51, v69
	v_add_f32_e32 v52, v68, v50
	v_add_f32_e32 v53, v69, v51
	s_nop 0
	v_add_f32_e32 v53, v52, v53
	v_add_f32_e32 v52, v52, v52
	v_exp_f32_e32 v51, v70
	v_exp_f32_e32 v52, v71
	v_cvt_pk_bf16_f32 v50, v50, v68
	v_exp_f32_e32 v68, v55
	s_waitcnt lgkmcnt(2)
	v_mfma_f32_32x32x16_bf16 v[32:47], v[128:131], v[120:123], v[32:47]
	v_add_f32_e32 v55, v52, v51
	v_cvt_pk_bf16_f32 v67, v51, v52
	v_mov_b32_e32 v52, v195
	v_add_f32_e32 v71, v68, v54
	v_add_u32_e32 v52, v135, v52
	v_cvt_pk_bf16_f32 v51, v54, v68
	ds_read_b128 v[108:111], v52 offset:6144
	s_waitcnt lgkmcnt(2)
	v_mfma_f32_32x32x16_bf16 v[80:95], v[100:103], v[116:119], v[80:95]
	ds_read_b128 v[120:123], v52 offset:6656
	v_exp_f32_e32 v52, v73
	v_exp_f32_e32 v54, v56
	v_exp_f32_e32 v70, v57
	v_exp_f32_e32 v73, v75
	v_add_f32_e32 v56, v52, v96
	v_add_f32_e32 v57, v53, v97
	ds_read_b128 v[100:103], v135 offset:40960
	v_add_f32_e32 v68, v70, v54
	v_add_f32_e32 v69, v71, v55
	v_exp_f32_e32 v55, v74
	v_add_f32_e32 v56, v68, v56
	v_add_f32_e32 v57, v69, v57
	s_nop 0
	v_add_f32_e32 v68, v56, v56
	v_add_f32_e32 v69, v56, v57
	v_cvt_pk_bf16_f32 v56, v96, v52
	v_cvt_pk_bf16_f32 v52, v54, v70
	v_exp_f32_e32 v54, v58
	v_cvt_pk_bf16_f32 v57, v55, v73
	v_exp_f32_e32 v68, v78
	v_add_f32_e32 v58, v72, v54
	v_add_f32_e32 v59, v73, v55
	s_nop 0
	v_add_f32_e32 v70, v58, v58
	v_add_f32_e32 v71, v58, v59
	v_cvt_pk_bf16_f32 v53, v54, v72
	v_exp_f32_e32 v54, v76
	v_exp_f32_e32 v55, v77
	v_exp_f32_e32 v59, v60
	v_exp_f32_e32 v60, v61
	v_exp_f32_e32 v70, v79
	ds_read_b128 v[74:77], v135 offset:43008
	s_waitcnt lgkmcnt(1)
	v_mfma_f32_32x32x16_bf16 v[16:31], v[64:67], v[100:103], v[16:31]
	v_add_f32_e32 v61, v55, v54
	v_add_f32_e32 v73, v60, v59
	v_cvt_pk_bf16_f32 v58, v54, v55
	v_cvt_pk_bf16_f32 v54, v59, v60
	v_cvt_pk_bf16_f32 v59, v68, v70
	ds_read_b128 v[100:103], v135 offset:45056
	v_exp_f32_e32 v60, v62
	s_waitcnt lgkmcnt(1)
	v_mfma_f32_32x32x16_bf16 v[16:31], v[56:59], v[74:77], v[16:31]
	v_exp_f32_e32 v72, v63
	ds_read_b128 v[74:77], v135 offset:47104
	v_cvt_pk_bf16_f32 v55, v60, v72
	s_waitcnt lgkmcnt(1)
	v_mfma_f32_32x32x16_bf16 v[16:31], v[48:51], v[100:103], v[16:31]
	ds_read_b128 v[100:103], v135 offset:41472
	s_waitcnt lgkmcnt(1)
	v_mfma_f32_32x32x16_bf16 v[16:31], v[52:55], v[74:77], v[16:31]
	ds_read_b128 v[74:77], v135 offset:43520
	s_waitcnt lgkmcnt(1)
	v_mfma_f32_32x32x16_bf16 v[0:15], v[64:67], v[100:103], v[0:15]
	s_waitcnt lgkmcnt(0)
	v_mfma_f32_32x32x16_bf16 v[0:15], v[56:59], v[74:77], v[0:15]
	ds_read_b128 v[56:59], v135 offset:47616
	v_mfma_f32_32x32x16_bf16 v[32:47], v[104:107], v[116:119], v[32:47]
	v_mfma_f32_32x32x16_bf16 v[80:95], v[108:111], v[112:115], v[80:95]
	v_mfma_f32_32x32x16_bf16 v[32:47], v[120:123], v[112:115], v[32:47]
	ds_read_b128 v[62:65], v135 offset:45568
	s_waitcnt vmcnt(0)
	s_waitcnt lgkmcnt(0)
	s_barrier
	v_mfma_f32_32x32x16_bf16 v[0:15], v[48:51], v[62:65], v[0:15]
	v_add_f32_e64 v48, v70, v68
	v_add_f32_e64 v49, v71, v69
	v_add_f32_e64 v50, v72, v60
	v_add_f32_e64 v51, v73, v61
	v_add_f32_e64 v48, v50, v48
	v_add_f32_e64 v49, v51, v49
	v_add_f32_e32 v48, v48, v49
	s_nop 0
	v_maximum3_f32 v49, v33, v82, v34
	v_mfma_f32_32x32x16_bf16 v[0:15], v[52:55], v[56:59], v[0:15]
	v_add_f32_e32 v52, v98, v48
	v_maximum3_f32 v48, v80, v32, v32
	v_maximum3_f32 v48, v48, v81, v83
	v_maximum3_f32 v49, v49, v84, v36
	v_maximum3_f32 v48, v48, v35, v85
	v_maximum3_f32 v49, v49, v86, v38
	v_maximum3_f32 v48, v48, v37, v87
	v_maximum3_f32 v49, v49, v88, v40
	v_maximum3_f32 v48, v48, v39, v89
	v_maximum3_f32 v49, v49, v90, v42
	v_maximum3_f32 v48, v48, v41, v91
	v_maximum3_f32 v49, v49, v92, v44
	v_maximum3_f32 v48, v48, v43, v93
	v_maximum3_f32 v49, v49, v94, v46
	v_maximum3_f32 v48, v48, v45, v95
	v_maximum3_f32 v48, v48, v47, v49
	v_mov_b32_e32 v49, v48
	s_nop 1
	v_permlane32_swap_b32_e32 v48, v49
	v_maximum3_f32 v48, v48, v49, v49
	v_cmp_lt_f32_e32 vcc, s46, v48
	s_cbranch_vccz .LBB0_623
	v_max_f32_e32 v48, v48, v48
	v_max_f32_e32 v48, 0, v48
	v_exp_f32_e64 v49, -v48
	s_and_saveexec_b64 s[6:7], s[34:35]
	ds_write_b32 v137, v49 offset:49152
	s_or_b64 exec, exec, s[6:7]
	s_waitcnt lgkmcnt(0)
	v_add_u32_e32 v53, s70, v194
	v_sub_f32_e32 v80, v80, v48
	v_sub_f32_e32 v81, v81, v48
	v_sub_f32_e32 v32, v32, v48
	v_sub_f32_e32 v33, v33, v48
	v_sub_f32_e32 v82, v82, v48
	v_sub_f32_e32 v83, v83, v48
	v_sub_f32_e32 v34, v34, v48
	v_sub_f32_e32 v35, v35, v48
	v_sub_f32_e32 v84, v84, v48
	v_sub_f32_e32 v85, v85, v48
	v_sub_f32_e32 v36, v36, v48
	v_sub_f32_e32 v37, v37, v48
	v_sub_f32_e32 v86, v86, v48
	v_sub_f32_e32 v87, v87, v48
	v_sub_f32_e32 v38, v38, v48
	v_sub_f32_e32 v39, v39, v48
	v_sub_f32_e32 v88, v88, v48
	v_sub_f32_e32 v89, v89, v48
	v_sub_f32_e32 v40, v40, v48
	v_sub_f32_e32 v41, v41, v48
	v_sub_f32_e32 v90, v90, v48
	v_sub_f32_e32 v91, v91, v48
	v_sub_f32_e32 v42, v42, v48
	v_sub_f32_e32 v43, v43, v48
	v_sub_f32_e32 v92, v92, v48
	v_sub_f32_e32 v93, v93, v48
	v_sub_f32_e32 v44, v44, v48
	v_sub_f32_e32 v45, v45, v48
	v_sub_f32_e32 v94, v94, v48
	v_sub_f32_e32 v95, v95, v48
	v_sub_f32_e32 v46, v46, v48
	v_sub_f32_e32 v47, v47, v48
	v_mul_f32_e32 v52, v52, v49
	ds_read_b128 v[48:51], v53 offset:49152
	ds_read_b128 v[54:57], v53 offset:49184
	ds_read_b128 v[58:61], v53 offset:49216
	ds_read_b128 v[62:65], v53 offset:49248
	s_waitcnt lgkmcnt(0)
	s_waitcnt lgkmcnt(3)
	v_mul_f32_e32 v18, v18, v50
	v_mul_f32_e32 v19, v19, v51
	s_waitcnt lgkmcnt(2)
	v_mul_f32_e32 v20, v20, v54
	v_mul_f32_e32 v21, v21, v55
	s_waitcnt lgkmcnt(1)
	v_mul_f32_e32 v24, v24, v58
	v_mul_f32_e32 v25, v25, v59
	s_waitcnt lgkmcnt(0)
	v_mul_f32_e32 v28, v28, v62
	v_mul_f32_e32 v29, v29, v63
	v_mul_f32_e32 v30, v30, v64
	v_mul_f32_e32 v31, v31, v65
	v_mul_f32_e32 v26, v26, v60
	v_mul_f32_e32 v27, v27, v61
	v_mul_f32_e32 v22, v22, v56
	v_mul_f32_e32 v23, v23, v57
	v_mul_f32_e32 v16, v16, v48
	v_mul_f32_e32 v17, v17, v49
	v_mul_f32_e32 v12, v12, v62
	v_mul_f32_e32 v13, v13, v63
	v_mul_f32_e32 v8, v8, v58
	v_mul_f32_e32 v9, v9, v59
	v_mul_f32_e32 v4, v4, v54
	v_mul_f32_e32 v5, v5, v55
	v_mul_f32_e32 v14, v14, v64
	v_mul_f32_e32 v15, v15, v65
	v_mul_f32_e32 v10, v10, v60
	v_mul_f32_e32 v11, v11, v61
	v_mul_f32_e32 v6, v6, v56
	v_mul_f32_e32 v7, v7, v57
	v_mul_f32_e32 v2, v2, v50
	v_mul_f32_e32 v3, v3, v51
	v_mul_f32_e32 v0, v0, v48
	v_mul_f32_e32 v1, v1, v49

.LBB0_639:
	s_nop 6
	v_maximum3_f32 v32, v16, v0, v0
	v_maximum3_f32 v33, v1, v18, v2
	v_maximum3_f32 v32, v32, v17, v19
	v_maximum3_f32 v33, v33, v20, v4
	v_maximum3_f32 v32, v32, v3, v21
	v_maximum3_f32 v33, v33, v22, v6
	v_maximum3_f32 v32, v32, v5, v23
	v_maximum3_f32 v33, v33, v24, v8
	v_maximum3_f32 v32, v32, v7, v25
	v_maximum3_f32 v33, v33, v26, v10
	v_maximum3_f32 v32, v32, v9, v27
	v_maximum3_f32 v33, v33, v28, v12
	v_maximum3_f32 v32, v32, v11, v29
	v_maximum3_f32 v33, v33, v30, v14
	v_maximum3_f32 v32, v32, v13, v31
	v_maximum3_f32 v32, v32, v15, v33
	v_mov_b32_e32 v33, v32
	s_nop 1
	v_permlane32_swap_b32_e32 v32, v33
	v_maximum3_f32 v48, v32, v33, v33
	v_sub_f32_e32 v85, v8, v48
	v_mov_b32_e32 v8, v195
	v_sub_f32_e32 v59, v4, v48
	v_sub_f32_e32 v50, v0, v48
	v_add_u32_e32 v4, v223, v8
	v_sub_f32_e32 v52, v1, v48
	v_sub_f32_e32 v55, v2, v48
	v_sub_f32_e32 v57, v3, v48
	ds_read_b128 v[0:3], v4
	v_sub_f32_e32 v62, v5, v48
	v_sub_f32_e32 v63, v6, v48
	v_sub_f32_e32 v80, v7, v48
	ds_read_b128 v[4:7], v4 offset:512
	s_mov_b32 s5, 0x14800
	v_add3_u32 v8, v221, v8, s5
	v_sub_f32_e32 v86, v9, v48
	v_sub_f32_e32 v87, v10, v48
	v_sub_f32_e32 v88, v11, v48
	ds_read_b128 v[8:11], v8
	v_sub_f32_e32 v91, v12, v48
	v_mov_b32_e32 v12, v195
	v_sub_f32_e32 v58, v20, v48
	v_sub_f32_e32 v49, v16, v48
	v_add_u32_e32 v20, v223, v12
	v_sub_f32_e32 v51, v17, v48
	v_sub_f32_e32 v54, v18, v48
	v_sub_f32_e32 v56, v19, v48
	ds_read_b128 v[16:19], v20 offset:2048
	s_waitcnt lgkmcnt(0)
	v_mfma_f32_32x32x16_bf16 v[32:47], v[0:3], v[8:11], 0
	s_mov_b32 s5, 0x16800
	v_sub_f32_e32 v100, v13, v48
	v_sub_f32_e32 v101, v14, v48
	ds_read_b128 v[0:3], v20 offset:2560
	v_add3_u32 v14, v221, v12, s5
	v_exp_f32_e32 v13, v51
	v_exp_f32_e32 v51, v50
	v_mfma_f32_32x32x16_bf16 v[64:79], v[4:7], v[8:11], 0
	v_exp_f32_e32 v11, v49
	v_exp_f32_e32 v53, v52
	v_exp_f32_e32 v10, v54
	v_exp_f32_e32 v12, v56
	v_exp_f32_e32 v50, v55
	v_exp_f32_e32 v52, v57
	ds_read_b128 v[4:7], v14
	v_sub_f32_e32 v60, v21, v48
	v_sub_f32_e32 v102, v15, v48
	v_add_f32_e32 v14, v12, v10
	v_add_f32_e32 v15, v13, v11
	v_add_f32_e32 v20, v52, v50
	v_add_f32_e32 v21, v53, v51
	s_waitcnt lgkmcnt(0)
	v_mfma_f32_32x32x16_bf16 v[32:47], v[16:19], v[4:7], v[32:47]
	v_add_f32_e64 v14, v20, v14
	v_add_f32_e64 v15, v21, v15
	v_cvt_pk_bf16_f32 v8, v11, v13
	v_add_f32_e32 v9, 0, v15
	v_add_f32_e32 v17, v14, v9
	v_mov_b32_e32 v14, v195
	v_cvt_pk_bf16_f32 v9, v10, v12
	v_add_u32_e32 v15, v223, v14
	ds_read_b128 v[10:13], v15 offset:4096
	s_mov_b32 s5, 0x18800
	v_mfma_f32_32x32x16_bf16 v[64:79], v[0:3], v[4:7], v[64:79]
	v_add3_u32 v4, v221, v14, s5
	ds_read_b128 v[0:3], v15 offset:4608
	ds_read_b128 v[4:7], v4
	v_exp_f32_e32 v55, v58
	v_exp_f32_e32 v61, v60
	v_exp_f32_e32 v54, v59
	v_exp_f32_e32 v60, v62
	s_waitcnt lgkmcnt(0)
	v_mfma_f32_32x32x16_bf16 v[32:47], v[10:13], v[4:7], v[32:47]
	v_mov_b32_e32 v11, v195
	v_add_f32_e64 v14, v60, v54
	v_add_f32_e64 v15, v61, v55
	v_add_u32_e32 v16, v223, v11
	v_add_f32_e64 v18, v14, v14
	v_add_f32_e64 v19, v14, v15
	ds_read_b128 v[12:15], v16 offset:6144
	s_mov_b32 s5, 0x1a800
	v_mfma_f32_32x32x16_bf16 v[64:79], v[0:3], v[4:7], v[64:79]
	ds_read_b128 v[0:3], v16 offset:6656
	v_add3_u32 v4, v221, v11, s5
	v_sub_f32_e32 v22, v22, v48
	v_sub_f32_e32 v23, v23, v48
	ds_read_b128 v[4:7], v4
	v_sub_f32_e32 v24, v24, v48
	v_sub_f32_e32 v25, v25, v48
	v_exp_f32_e32 v20, v22
	v_exp_f32_e32 v21, v23
	v_exp_f32_e32 v49, v63
	v_exp_f32_e32 v89, v80
	v_sub_f32_e32 v26, v26, v48
	v_sub_f32_e32 v27, v27, v48
	v_exp_f32_e32 v16, v24
	v_exp_f32_e32 v18, v25
	v_exp_f32_e32 v62, v85
	v_exp_f32_e32 v80, v86
	v_exp_f32_e32 v93, v26
	v_exp_f32_e32 v97, v27
	v_exp_f32_e32 v92, v87
	v_exp_f32_e32 v96, v88
	v_cvt_pk_bf16_f32 v10, v55, v61
	v_add_f32_e32 v63, v21, v20
	v_add_f32_e32 v81, v89, v49
	v_cvt_pk_bf16_f32 v11, v20, v21
	s_waitcnt lgkmcnt(0)
	v_mfma_f32_32x32x16_bf16 v[32:47], v[12:15], v[4:7], v[32:47]
	ds_read_b128 v[12:15], v223 offset:8192
	v_add_f32_e64 v20, v18, v16
	v_add_f32_e64 v21, v19, v17
	v_add_f32_e64 v22, v80, v62
	v_add_f32_e64 v23, v81, v63
	v_sub_f32_e32 v28, v28, v48
	v_add_f32_e32 v20, v22, v20
	v_add_f32_e32 v21, v23, v21
	v_sub_f32_e32 v29, v29, v48
	v_sub_f32_e32 v30, v30, v48
	v_mfma_f32_32x32x16_bf16 v[64:79], v[0:3], v[4:7], v[64:79]
	v_add_f32_e64 v0, v96, v92
	v_add_f32_e64 v1, v97, v93
	v_sub_f32_e32 v31, v31, v48
	v_add_f32_e64 v94, v20, v20
	v_add_f32_e64 v95, v20, v21
	v_add_f32_e32 v98, v0, v0
	v_add_f32_e32 v99, v0, v1
	v_exp_f32_e32 v55, v28
	v_exp_f32_e32 v61, v29
	v_exp_f32_e32 v94, v30
	v_exp_f32_e32 v98, v31
	v_cvt_pk_bf16_f32 v56, v16, v18
	ds_read_b128 v[0:3], v223 offset:10240
	s_waitcnt lgkmcnt(0)
	v_mfma_f32_32x32x16_bf16 v[16:31], v[8:11], v[12:15], 0
	v_cvt_pk_bf16_f32 v57, v93, v97
	v_cvt_pk_bf16_f32 v58, v55, v61
	v_cvt_pk_bf16_f32 v59, v94, v98
	ds_read_b128 v[4:7], v223 offset:12288
	v_cvt_pk_bf16_f32 v86, v51, v53
	v_cvt_pk_bf16_f32 v87, v50, v52
	v_cvt_pk_bf16_f32 v88, v54, v60
	v_mfma_f32_32x32x16_bf16 v[16:31], v[56:59], v[0:3], v[16:31]
	v_cvt_pk_bf16_f32 v89, v49, v89
	v_exp_f32_e32 v15, v91
	v_exp_f32_e32 v49, v100
	v_exp_f32_e32 v12, v101
	v_exp_f32_e32 v14, v102
	ds_read_b128 v[0:3], v223 offset:14336
	v_cvt_pk_bf16_f32 v90, v62, v80
	s_waitcnt lgkmcnt(0)
	v_mfma_f32_32x32x16_bf16 v[16:31], v[86:89], v[4:7], v[16:31]
	v_cvt_pk_bf16_f32 v91, v92, v96
	v_cvt_pk_bf16_f32 v92, v15, v49
	v_cvt_pk_bf16_f32 v93, v12, v14
	ds_read_b128 v[4:7], v223 offset:8704
	v_add_f32_e32 v13, v61, v55
	v_add_f32_e32 v15, v49, v15
	v_add_f32_e32 v50, v98, v94
	v_add_f32_e32 v51, v99, v95
	v_mfma_f32_32x32x16_bf16 v[16:31], v[90:93], v[0:3], v[16:31]
	v_add_f32_e64 v0, v14, v12
	v_add_f32_e64 v1, v15, v13
	ds_read_b128 v[60:63], v223 offset:10752
	v_add_f32_e64 v0, v0, v50
	v_add_f32_e64 v1, v1, v51
	v_mov_b32_e32 v81, v195
	v_add_f32_e32 v1, v0, v1
	v_add_f32_e32 v0, v0, v0
	v_mov_b32_e32 v49, v1
	v_maximum3_f32 v80, v32, v64, v64
	s_waitcnt lgkmcnt(0)
	v_mfma_f32_32x32x16_bf16 v[0:15], v[8:11], v[4:7], 0
	ds_read_b128 v[94:97], v223 offset:12800
	v_maximum3_f32 v80, v80, v33, v35
	v_maximum3_f32 v80, v80, v67, v37
	v_maximum3_f32 v80, v80, v69, v39
	v_maximum3_f32 v80, v80, v71, v41
	v_maximum3_f32 v80, v80, v73, v43
	v_maximum3_f32 v80, v80, v75, v45
	v_mfma_f32_32x32x16_bf16 v[0:15], v[56:59], v[60:63], v[0:15]
	ds_read_b128 v[98:101], v223 offset:14848
	v_maximum3_f32 v80, v80, v77, v47
	v_add_u32_e32 v85, v223, v81
	v_add_f32_e64 v208, v48, 0
	v_add_f32_e64 v209, v49, 0
	s_mov_b32 s5, 0x12800
	v_pk_add_f32 v[48:49], v[208:209], 0 neg_lo:[1,1] neg_hi:[1,1]
	s_waitcnt lgkmcnt(0)
	v_mfma_f32_32x32x16_bf16 v[0:15], v[86:89], v[94:97], v[0:15]
	ds_read_b128 v[86:89], v85 offset:16384
	v_mov_b32_e32 v49, v48
	v_mov_b32_e32 v50, v48
	v_mov_b32_e32 v51, v48
	v_mov_b32_e32 v52, v48
	v_mov_b32_e32 v53, v48
	v_mov_b32_e32 v54, v48
	v_mfma_f32_32x32x16_bf16 v[0:15], v[90:93], v[98:101], v[0:15]
	v_maximum3_f32 v90, v65, v34, v66
	v_maximum3_f32 v90, v90, v36, v68
	v_maximum3_f32 v90, v90, v38, v70
	v_maximum3_f32 v90, v90, v40, v72
	v_maximum3_f32 v90, v90, v42, v74
	v_maximum3_f32 v90, v90, v44, v76
	v_maximum3_f32 v90, v90, v46, v78
	v_maximum3_f32 v80, v80, v79, v90
	v_mov_b32_e32 v90, v80
	s_nop 1
	v_permlane32_swap_b32_e32 v80, v90
	v_maximum3_f32 v80, v80, v90, v90
	v_sub_f32_e32 v90, v32, v80
	v_sub_f32_e32 v91, v33, v80
	v_sub_f32_e32 v92, v34, v80
	v_sub_f32_e32 v93, v35, v80
	ds_read_b128 v[32:35], v85 offset:16896
	v_sub_f32_e32 v94, v36, v80
	v_add_u32_e32 v36, v221, v81
	v_sub_f32_e32 v95, v37, v80
	v_sub_f32_e32 v112, v38, v80
	v_sub_f32_e32 v114, v39, v80
	ds_read_b128 v[36:39], v36 offset:51200
	v_sub_f32_e32 v124, v44, v80
	v_mov_b32_e32 v44, v195
	v_mov_b32_e32 v55, v48
	v_mov_b32_e32 v56, v48
	v_mov_b32_e32 v57, v48
	v_mov_b32_e32 v58, v48
	v_mov_b32_e32 v59, v48
	v_mov_b32_e32 v60, v48
	v_mov_b32_e32 v61, v48
	v_mov_b32_e32 v62, v48
	v_mov_b32_e32 v63, v48
	v_sub_f32_e32 v81, v45, v80
	v_sub_f32_e32 v116, v40, v80
	v_add_u32_e32 v45, v223, v44
	v_sub_f32_e32 v118, v41, v80
	v_sub_f32_e32 v120, v42, v80
	v_sub_f32_e32 v122, v43, v80
	s_waitcnt lgkmcnt(0)
	v_mfma_f32_32x32x16_bf16 v[96:111], v[86:89], v[36:39], v[48:63]
	ds_read_b128 v[40:43], v45 offset:18432
	v_mov_b64_e32 v[142:143], v[62:63]
	v_mov_b64_e32 v[140:141], v[60:61]
	v_mov_b64_e32 v[138:139], v[58:59]
	v_mov_b64_e32 v[136:137], v[56:57]
	v_mov_b64_e32 v[134:135], v[54:55]
	v_mov_b64_e32 v[132:133], v[52:53]
	v_mov_b64_e32 v[130:131], v[50:51]
	v_mov_b64_e32 v[128:129], v[48:49]
	v_sub_f32_e32 v64, v64, v80
	v_sub_f32_e32 v65, v65, v80
	v_sub_f32_e32 v66, v66, v80
	v_sub_f32_e32 v67, v67, v80
	v_mfma_f32_32x32x16_bf16 v[128:143], v[32:35], v[36:39], v[128:143]
	ds_read_b128 v[32:35], v45 offset:18944
	v_sub_f32_e32 v113, v70, v80
	v_sub_f32_e32 v115, v71, v80
	v_sub_f32_e32 v117, v72, v80
	v_sub_f32_e32 v119, v73, v80
	v_sub_f32_e32 v126, v46, v80
	v_sub_f32_e32 v87, v47, v80
	v_add_u32_e32 v36, v221, v44
	v_exp_f32_e32 v45, v90
	v_exp_f32_e32 v47, v91
	v_exp_f32_e32 v71, v64
	v_exp_f32_e32 v73, v65
	v_exp_f32_e32 v44, v92
	v_exp_f32_e32 v46, v93
	v_exp_f32_e32 v70, v66
	v_exp_f32_e32 v72, v67
	ds_read_b128 v[36:39], v36 offset:59392
	v_add_f32_e32 v52, v46, v44
	v_add_f32_e32 v53, v47, v45
	v_cvt_pk_bf16_f32 v51, v44, v46
	v_add_f32_e32 v54, v72, v70
	v_add_f32_e32 v55, v73, v71
	v_mov_b32_e32 v44, v195
	v_add_f32_e32 v52, v54, v52
	v_add_f32_e32 v53, v55, v53
	v_sub_f32_e32 v68, v68, v80
	v_sub_f32_e32 v69, v69, v80
	s_waitcnt lgkmcnt(0)
	v_mfma_f32_32x32x16_bf16 v[96:111], v[40:43], v[36:39], v[96:111]
	v_add_f32_e32 v40, 0, v53
	v_sub_f32_e32 v121, v74, v80
	v_add_u32_e32 v46, v223, v44
	v_sub_f32_e32 v123, v75, v80
	v_sub_f32_e32 v125, v76, v80
	v_sub_f32_e32 v85, v77, v80
	v_cvt_pk_bf16_f32 v50, v45, v47
	v_add_f32_e32 v45, v52, v40
	ds_read_b128 v[40:43], v46 offset:20480
	v_exp_f32_e32 v75, v94
	v_exp_f32_e32 v77, v95
	v_exp_f32_e32 v74, v68
	v_exp_f32_e32 v76, v69
	v_mfma_f32_32x32x16_bf16 v[128:143], v[32:35], v[36:39], v[128:143]
	ds_read_b128 v[32:35], v46 offset:20992
	v_add3_u32 v36, v221, v44, s45
	v_exp_f32_e32 v44, v112
	v_exp_f32_e32 v49, v114
	ds_read_b128 v[36:39], v36
	v_add_f32_e32 v46, v76, v74
	v_add_f32_e32 v47, v77, v75
	v_exp_f32_e32 v93, v113
	v_exp_f32_e32 v145, v115
	v_add_f32_e32 v47, v46, v47
	v_add_f32_e32 v46, v46, v46
	v_sub_f32_e32 v127, v78, v80
	v_sub_f32_e32 v144, v79, v80
	v_add_f32_e32 v79, v49, v44
	v_cvt_pk_bf16_f32 v53, v44, v49
	v_exp_f32_e32 v44, v116
	v_exp_f32_e32 v46, v118
	v_exp_f32_e32 v78, v117
	v_exp_f32_e32 v94, v119
	v_mov_b32_e32 v49, v195
	v_exp_f32_e32 v113, v120
	v_exp_f32_e32 v115, v122
	v_exp_f32_e32 v112, v121
	v_exp_f32_e32 v114, v123
	v_add_f32_e32 v95, v145, v93
	s_waitcnt lgkmcnt(0)
	v_mfma_f32_32x32x16_bf16 v[96:111], v[40:43], v[36:39], v[96:111]
	v_cvt_pk_bf16_f32 v52, v75, v77
	v_add_u32_e32 v40, v223, v49
	ds_read_b128 v[62:65], v40 offset:22528
	v_exp_f32_e32 v81, v81
	v_cvt_pk_bf16_f32 v86, v44, v46
	v_cvt_pk_bf16_f32 v90, v71, v73
	v_mfma_f32_32x32x16_bf16 v[128:143], v[32:35], v[36:39], v[128:143]
	v_add_f32_e64 v32, v46, v44
	v_add_f32_e64 v33, v47, v45
	v_add_f32_e64 v34, v94, v78
	v_add_f32_e64 v35, v95, v79
	ds_read_b128 v[66:69], v40 offset:23040
	v_add_f32_e32 v32, v34, v32
	v_add_f32_e32 v33, v35, v33
	v_exp_f32_e32 v95, v124
	v_add_f32_e32 v58, v32, v32
	v_add_f32_e32 v59, v32, v33
	v_add_f32_e32 v32, v114, v112
	v_add_f32_e32 v33, v115, v113
	v_exp_f32_e32 v58, v126
	v_add_f32_e32 v60, v32, v32
	v_add_f32_e32 v61, v32, v33
	ds_read_b128 v[32:35], v223 offset:8704
	v_exp_f32_e32 v60, v87
	s_waitcnt lgkmcnt(0)
	v_mfma_f32_32x32x16_bf16 v[32:47], v[50:53], v[32:35], 0
	ds_read_b128 v[54:57], v223 offset:10752
	v_cvt_pk_bf16_f32 v87, v113, v115
	v_cvt_pk_bf16_f32 v88, v95, v81
	v_cvt_pk_bf16_f32 v89, v58, v60
	v_cvt_pk_bf16_f32 v91, v70, v72
	v_cvt_pk_bf16_f32 v92, v74, v76
	v_cvt_pk_bf16_f32 v93, v93, v145
	s_waitcnt lgkmcnt(0)
	v_mfma_f32_32x32x16_bf16 v[32:47], v[86:89], v[54:57], v[32:47]
	ds_read_b128 v[70:73], v223 offset:12800
	v_cvt_pk_bf16_f32 v54, v78, v94
	v_exp_f32_e32 v117, v125
	v_exp_f32_e32 v85, v85
	v_exp_f32_e32 v94, v127
	v_exp_f32_e32 v116, v144
	v_cvt_pk_bf16_f32 v55, v112, v114
	s_waitcnt lgkmcnt(0)
	v_mfma_f32_32x32x16_bf16 v[32:47], v[90:93], v[70:73], v[32:47]
	ds_read_b128 v[74:77], v223 offset:14848
	v_cvt_pk_bf16_f32 v56, v117, v85
	v_cvt_pk_bf16_f32 v57, v94, v116
	v_add3_u32 v49, v221, v49, s5
	v_add_f32_e32 v95, v81, v95
	v_add_f32_e32 v117, v85, v117
	s_mul_i32 s6, s71, 0x20ffc0
	s_waitcnt lgkmcnt(0)
	v_mfma_f32_32x32x16_bf16 v[32:47], v[54:57], v[74:77], v[32:47]
	ds_read_b128 v[70:73], v49
	s_lshl_b32 s7, s58, 14
	s_add_i32 s6, s6, s7
	v_lshlrev_b32_e32 v49, 7, v219
	s_add_i32 s6, s6, 0x203000
	v_and_b32_e32 v49, 0x200, v49
	v_cmp_gt_u32_e64 s[38:39], 32, v219
	s_waitcnt lgkmcnt(0)
	v_mfma_f32_32x32x16_bf16 v[96:111], v[62:65], v[70:73], v[96:111]
	ds_read_b128 v[62:65], v223 offset:8192
	v_lshl_add_u32 v231, v220, 2, s67
	s_mov_b32 s5, 0
	s_add_i32 s8, s72, 0
	s_mov_b32 s18, 0x12800
	s_mov_b32 s17, 0x1a800
	s_mov_b32 s16, 0x18800
	v_mfma_f32_32x32x16_bf16 v[128:143], v[66:69], v[70:73], v[128:143]
	ds_read_b128 v[112:115], v223 offset:10240
	s_mov_b32 s15, 0x16800
	s_mov_b32 s14, 0x14800
	s_movk_i32 s9, 0x80
	s_mov_b32 s10, 0x8000
	s_waitcnt lgkmcnt(0)
	v_mfma_f32_32x32x16_bf16 v[64:79], v[50:53], v[62:65], 0
	ds_read_b128 v[50:53], v223 offset:12288
	v_mov_b32_e32 v62, v48
	v_mfma_f32_32x32x16_bf16 v[64:79], v[86:89], v[112:115], v[64:79]
	ds_read_b128 v[86:89], v223 offset:14336
	s_waitcnt vmcnt(0)
	v_mov_b32_e32 v112, v48
	s_waitcnt vmcnt(0) lgkmcnt(0)
	s_barrier
	v_mfma_f32_32x32x16_bf16 v[64:79], v[90:93], v[50:53], v[64:79]
	v_add_f32_e64 v50, v60, v58
	v_add_f32_e64 v51, v61, v59
	v_add_f32_e64 v52, v116, v94
	v_add_f32_e64 v53, v117, v95
	v_mov_b32_e32 v58, v48
	v_add_f32_e32 v50, v52, v50
	v_add_f32_e32 v51, v53, v51
	v_mov_b32_e32 v52, v48
	v_add_f32_e32 v51, v50, v51
	v_add_f32_e32 v50, v50, v50
	v_lshlrev_b32_e32 v50, 5, v218
	v_mfma_f32_32x32x16_bf16 v[64:79], v[54:57], v[86:89], v[64:79]
	v_and_b32_e32 v50, 0x100, v50
	v_add3_u32 v49, s6, v49, v50
	v_lshlrev_b32_e32 v50, 6, v83
	s_lshl_b32 s6, s70, 3
	v_mov_b32_e32 v81, v51
	v_add3_u32 v212, v49, v50, s6
	s_mov_b32 s6, 0x20fff8
	v_add_f32_e32 v210, 0, v80
	v_add_f32_e32 v211, 0, v81
	v_add_u32_e32 v49, s69, v82
	v_mul_lo_u32 v50, v84, s6
	v_pk_add_f32 v[80:81], v[210:211], 0 neg_lo:[1,1] neg_hi:[1,1]
	v_sub_u32_e32 v49, v49, v50
	v_add_u32_e32 v214, 0x80c0, v49
	s_movk_i32 s6, 0x4000
	v_mov_b32_e32 v49, v48
	v_mov_b32_e32 v50, v48
	v_mov_b32_e32 v51, v48
	v_mov_b32_e32 v53, v48
	v_mov_b32_e32 v54, v48
	v_mov_b32_e32 v55, v48
	v_mov_b32_e32 v56, v48
	v_mov_b32_e32 v57, v48
	v_mov_b32_e32 v59, v48
	v_mov_b32_e32 v60, v48
	v_mov_b32_e32 v61, v48
	v_mov_b32_e32 v81, v80
	v_mov_b32_e32 v82, v80
	v_mov_b32_e32 v83, v80
	v_mov_b32_e32 v84, v80
	v_mov_b32_e32 v85, v80
	v_mov_b32_e32 v86, v80
	v_mov_b32_e32 v87, v80
	v_mov_b32_e32 v88, v80
	v_mov_b32_e32 v89, v80
	v_mov_b32_e32 v90, v80
	v_mov_b32_e32 v91, v80
	v_mov_b32_e32 v92, v80
	v_mov_b32_e32 v93, v80
	v_mov_b32_e32 v94, v80
	v_mov_b32_e32 v95, v80
	s_cmpk_gt_u32 s9, 0x80
	s_mov_b32 s11, s6
	s_cbranch_scc1 .LBB0_644

.LBB0_644:
	v_maximum3_f32 v63, v96, v128, v128
	v_maximum3_f32 v113, v129, v98, v130
	v_maximum3_f32 v63, v63, v97, v99
	v_maximum3_f32 v113, v113, v100, v132
	v_maximum3_f32 v63, v63, v131, v101
	v_maximum3_f32 v113, v113, v102, v134
	v_maximum3_f32 v63, v63, v133, v103
	v_maximum3_f32 v113, v113, v104, v136
	v_maximum3_f32 v63, v63, v135, v105
	v_maximum3_f32 v113, v113, v106, v138
	v_maximum3_f32 v63, v63, v137, v107
	v_maximum3_f32 v113, v113, v108, v140
	v_maximum3_f32 v63, v63, v139, v109
	v_maximum3_f32 v113, v113, v110, v142
	v_maximum3_f32 v63, v63, v141, v111
	v_maximum3_f32 v63, v63, v143, v113
	v_mov_b32_e32 v113, v63
	s_nop 1
	v_permlane32_swap_b32_e32 v63, v113
	v_maximum3_f32 v63, v63, v113, v113
	v_cmp_lt_f32_e32 vcc, s46, v63
	s_cbranch_vccz .LBB0_648
	v_max_f32_e32 v48, v63, v63
	v_max_f32_e32 v48, 0, v48
	v_exp_f32_e64 v49, -v48
	s_and_saveexec_b64 s[6:7], s[38:39]
	ds_write_b32 v231, v49 offset:49152
	s_or_b64 exec, exec, s[6:7]
	v_sub_f32_e32 v96, v96, v48
	v_sub_f32_e32 v97, v97, v48
	v_sub_f32_e32 v128, v128, v48
	v_sub_f32_e32 v129, v129, v48
	v_sub_f32_e32 v98, v98, v48
	v_sub_f32_e32 v99, v99, v48
	v_sub_f32_e32 v130, v130, v48
	v_sub_f32_e32 v131, v131, v48
	v_sub_f32_e32 v100, v100, v48
	v_sub_f32_e32 v101, v101, v48
	v_sub_f32_e32 v132, v132, v48
	v_sub_f32_e32 v133, v133, v48
	v_sub_f32_e32 v102, v102, v48
	v_sub_f32_e32 v103, v103, v48
	v_sub_f32_e32 v134, v134, v48
	v_sub_f32_e32 v135, v135, v48
	v_sub_f32_e32 v104, v104, v48
	v_sub_f32_e32 v105, v105, v48
	v_sub_f32_e32 v136, v136, v48
	v_sub_f32_e32 v137, v137, v48
	v_sub_f32_e32 v106, v106, v48
	v_sub_f32_e32 v107, v107, v48
	v_sub_f32_e32 v138, v138, v48
	v_sub_f32_e32 v139, v139, v48
	v_sub_f32_e32 v108, v108, v48
	v_sub_f32_e32 v109, v109, v48
	v_sub_f32_e32 v140, v140, v48
	v_sub_f32_e32 v141, v141, v48
	v_sub_f32_e32 v110, v110, v48
	v_sub_f32_e32 v111, v111, v48
	v_sub_f32_e32 v142, v142, v48
	v_sub_f32_e32 v143, v143, v48
	v_add_f32_e32 v144, v208, v48
	v_add_f32_e32 v145, v209, v49
	v_mul_f32_e32 v48, v208, v48
	v_mul_f32_e32 v49, v209, v49
	s_waitcnt lgkmcnt(0)
	v_add_u32_e32 v60, s67, v194
	v_mov_b32_e32 v145, v49
	ds_read_b128 v[48:51], v60 offset:49216
	ds_read_b128 v[52:55], v60 offset:49248
	ds_read_b128 v[56:59], v60 offset:49152
	ds_read_b128 v[60:63], v60 offset:49184
	v_pk_add_f32 v[112:113], v[144:145], 0 neg_lo:[1,1] neg_hi:[1,1]
	s_waitcnt lgkmcnt(0)
	v_mov_b64_e32 v[208:209], v[144:145]
	v_mov_b32_e32 v126, v112
	v_mov_b32_e32 v127, v112
	v_mov_b32_e32 v113, v112
	v_mov_b32_e32 v114, v112
	v_mov_b32_e32 v115, v112
	v_mov_b32_e32 v116, v112
	v_mov_b32_e32 v117, v112
	v_mov_b32_e32 v118, v112
	v_mov_b32_e32 v119, v112
	v_mov_b32_e32 v120, v112
	v_mov_b32_e32 v121, v112
	v_mov_b32_e32 v122, v112
	v_mov_b32_e32 v123, v112
	v_mov_b32_e32 v124, v112
	v_mov_b32_e32 v125, v112
	v_mov_b64_e32 v[158:159], v[126:127]
	s_waitcnt lgkmcnt(0)
	v_mul_f32_e32 v28, v28, v52
	v_mul_f32_e32 v29, v29, v53
	v_mul_f32_e32 v24, v24, v48
	v_mul_f32_e32 v25, v25, v49
	v_mul_f32_e32 v20, v20, v60
	v_mul_f32_e32 v21, v21, v61
	v_mul_f32_e32 v30, v30, v54
	v_mul_f32_e32 v31, v31, v55
	v_mul_f32_e32 v26, v26, v50
	v_mul_f32_e32 v27, v27, v51
	v_mul_f32_e32 v22, v22, v62
	v_mul_f32_e32 v23, v23, v63
	v_mul_f32_e32 v18, v18, v58
	v_mul_f32_e32 v19, v19, v59
	v_mul_f32_e32 v16, v16, v56
	v_mul_f32_e32 v17, v17, v57
	v_mul_f32_e32 v12, v12, v52
	v_mul_f32_e32 v13, v13, v53
	v_mul_f32_e32 v8, v8, v48
	v_mul_f32_e32 v9, v9, v49
	v_mul_f32_e32 v4, v4, v60
	v_mul_f32_e32 v5, v5, v61
	v_mul_f32_e32 v14, v14, v54
	v_mul_f32_e32 v15, v15, v55
	v_mul_f32_e32 v10, v10, v50
	v_mul_f32_e32 v11, v11, v51
	v_mul_f32_e32 v6, v6, v62
	v_mul_f32_e32 v7, v7, v63
	v_mul_f32_e32 v2, v2, v58
	v_mul_f32_e32 v3, v3, v59
	v_mul_f32_e32 v0, v0, v56
	v_mul_f32_e32 v1, v1, v57
	v_mov_b32_e32 v62, v112
	v_mov_b32_e32 v61, v112
	v_mov_b32_e32 v60, v112
	v_mov_b32_e32 v59, v112
	v_mov_b32_e32 v58, v112
	v_mov_b32_e32 v57, v112
	v_mov_b32_e32 v56, v112
	v_mov_b32_e32 v55, v112
	v_mov_b32_e32 v54, v112
	v_mov_b32_e32 v53, v112
	v_mov_b32_e32 v52, v112
	v_mov_b32_e32 v51, v112
	v_mov_b32_e32 v50, v112
	v_mov_b32_e32 v49, v112
	v_mov_b32_e32 v48, v112
	v_mov_b64_e32 v[156:157], v[124:125]
	v_mov_b64_e32 v[154:155], v[122:123]
	v_mov_b64_e32 v[152:153], v[120:121]
	v_mov_b64_e32 v[150:151], v[118:119]
	v_mov_b64_e32 v[148:149], v[116:117]
	v_mov_b64_e32 v[146:147], v[114:115]
	v_mov_b64_e32 v[144:145], v[112:113]
	s_branch .LBB0_649

.LBB0_649:
	v_add_u32_e32 v63, s11, v223
	v_mov_b32_e32 v113, 0
	v_mov_b32_e32 v126, 0
	v_add_u32_e32 v122, v63, v113
	ds_read_b128 v[114:117], v122
	ds_read_b128 v[122:125], v122 offset:512
	v_add3_u32 v113, v221, v113, s14
	ds_read_b128 v[118:121], v113
	v_mov_b64_e32 v[174:175], v[94:95]
	v_add_u32_e32 v113, v63, v126
	ds_read_b128 v[226:229], v113 offset:2048
	s_waitcnt lgkmcnt(0)
	v_mfma_f32_32x32x16_bf16 v[176:191], v[114:117], v[118:121], v[80:95]
	ds_read_b128 v[238:241], v113 offset:2560
	v_mov_b64_e32 v[172:173], v[92:93]
	v_mov_b64_e32 v[170:171], v[90:91]
	v_mov_b64_e32 v[168:169], v[88:89]
	v_mov_b64_e32 v[166:167], v[86:87]
	v_mov_b64_e32 v[164:165], v[84:85]
	v_mov_b64_e32 v[162:163], v[82:83]
	v_mov_b64_e32 v[160:161], v[80:81]
	v_add3_u32 v113, v221, v126, s15
	v_exp_f32_e32 v215, v98
	v_mfma_f32_32x32x16_bf16 v[160:175], v[122:125], v[118:121], v[160:175]
	ds_read_b128 v[116:119], v113
	v_mov_b32_e32 v98, 0
	v_exp_f32_e32 v234, v99
	v_exp_f32_e32 v122, v128
	v_add_u32_e32 v99, v63, v98
	v_add3_u32 v98, v221, v98, s16
	s_waitcnt lgkmcnt(0)
	v_mfma_f32_32x32x16_bf16 v[176:191], v[226:229], v[116:119], v[176:191]
	ds_read_b128 v[124:127], v99 offset:4096
	v_exp_f32_e32 v123, v129
	v_exp_f32_e32 v235, v130
	v_exp_f32_e32 v237, v131
	v_exp_f32_e32 v113, v100
	v_exp_f32_e32 v213, v101
	v_exp_f32_e32 v233, v102
	v_mfma_f32_32x32x16_bf16 v[160:175], v[238:241], v[116:119], v[160:175]
	ds_read_b128 v[116:119], v99 offset:4608
	ds_read_b128 v[128:131], v98
	v_mov_b32_e32 v99, 0
	v_exp_f32_e32 v238, v103
	v_add_u32_e32 v115, v63, v99
	v_add3_u32 v99, v221, v99, s17
	s_waitcnt lgkmcnt(0)
	v_mfma_f32_32x32x16_bf16 v[176:191], v[124:127], v[128:131], v[176:191]
	ds_read_b128 v[100:103], v115 offset:6144
	v_exp_f32_e32 v120, v96
	v_exp_f32_e32 v121, v97
	v_cvt_pk_bf16_f32 v97, v215, v234
	v_cvt_pk_bf16_f32 v98, v113, v213
	v_exp_f32_e32 v241, v104
	v_cvt_pk_bf16_f32 v96, v120, v121
	v_mfma_f32_32x32x16_bf16 v[160:175], v[116:119], v[128:131], v[160:175]
	ds_read_b128 v[116:119], v115 offset:6656
	ds_read_b128 v[124:127], v99
	v_cvt_pk_bf16_f32 v99, v233, v238
	v_exp_f32_e32 v242, v105
	v_exp_f32_e32 v249, v106
	v_exp_f32_e32 v250, v107
	v_exp_f32_e32 v246, v108
	s_waitcnt lgkmcnt(0)
	v_mfma_f32_32x32x16_bf16 v[176:191], v[100:103], v[124:127], v[176:191]
	v_exp_f32_e32 v248, v109
	v_exp_f32_e32 v243, v110
	v_exp_f32_e32 v244, v111
	v_cvt_pk_bf16_f32 v104, v241, v242
	v_cvt_pk_bf16_f32 v105, v249, v250
	v_cvt_pk_bf16_f32 v106, v246, v248
	v_cvt_pk_bf16_f32 v107, v243, v244
	v_mfma_f32_32x32x16_bf16 v[160:175], v[116:119], v[124:127], v[160:175]
	ds_read_b128 v[116:119], v63 offset:8192
	v_exp_f32_e32 v232, v132
	v_exp_f32_e32 v236, v133
	v_exp_f32_e32 v239, v134
	v_exp_f32_e32 v240, v135
	v_cvt_pk_bf16_f32 v114, v122, v123
	v_cvt_pk_bf16_f32 v115, v235, v237
	s_waitcnt lgkmcnt(0)
	v_mfma_f32_32x32x16_bf16 v[16:31], v[96:99], v[116:119], v[16:31]
	ds_read_b128 v[108:111], v63 offset:10240
	v_cvt_pk_bf16_f32 v116, v232, v236
	v_cvt_pk_bf16_f32 v117, v239, v240
	v_exp_f32_e32 v245, v136
	v_exp_f32_e32 v247, v137
	v_exp_f32_e32 v227, v138
	v_exp_f32_e32 v228, v139
	s_waitcnt lgkmcnt(0)
	v_mfma_f32_32x32x16_bf16 v[16:31], v[104:107], v[108:111], v[16:31]
	ds_read_b128 v[108:111], v63 offset:12288
	v_exp_f32_e32 v225, v140
	v_exp_f32_e32 v226, v141
	v_exp_f32_e32 v251, v142
	v_exp_f32_e32 v230, v143
	v_cvt_pk_bf16_f32 v128, v245, v247
	v_cvt_pk_bf16_f32 v129, v227, v228
	s_waitcnt lgkmcnt(0)
	v_mfma_f32_32x32x16_bf16 v[16:31], v[114:117], v[108:111], v[16:31]
	ds_read_b128 v[108:111], v63 offset:14336
	v_cvt_pk_bf16_f32 v130, v225, v226
	v_cvt_pk_bf16_f32 v131, v251, v230
	s_waitcnt lgkmcnt(0)
	s_nop 0
	v_mfma_f32_32x32x16_bf16 v[16:31], v[128:131], v[108:111], v[16:31]
	ds_read_b128 v[108:111], v63 offset:8704
	s_waitcnt lgkmcnt(0)
	v_mfma_f32_32x32x16_bf16 v[0:15], v[96:99], v[108:111], v[0:15]
	ds_read_b128 v[96:99], v63 offset:10752
	s_waitcnt lgkmcnt(0)
	v_mfma_f32_32x32x16_bf16 v[0:15], v[104:107], v[96:99], v[0:15]
	ds_read_b128 v[96:99], v63 offset:12800
	s_waitcnt lgkmcnt(0)
	v_mfma_f32_32x32x16_bf16 v[0:15], v[114:117], v[96:99], v[0:15]
	ds_read_b128 v[96:99], v63 offset:14848
	s_waitcnt lgkmcnt(0)
	v_mfma_f32_32x32x16_bf16 v[0:15], v[128:131], v[96:99], v[0:15]
	v_maximum3_f32 v96, v176, v160, v160
	v_maximum3_f32 v97, v161, v178, v162
	v_maximum3_f32 v96, v96, v177, v179
	v_maximum3_f32 v97, v97, v180, v164
	v_maximum3_f32 v96, v96, v163, v181
	v_maximum3_f32 v97, v97, v182, v166
	v_maximum3_f32 v96, v96, v165, v183
	v_maximum3_f32 v97, v97, v184, v168
	v_maximum3_f32 v96, v96, v167, v185
	v_maximum3_f32 v97, v97, v186, v170
	v_maximum3_f32 v96, v96, v169, v187
	v_maximum3_f32 v97, v97, v188, v172
	v_maximum3_f32 v96, v96, v171, v189
	v_maximum3_f32 v97, v97, v190, v174
	v_maximum3_f32 v96, v96, v173, v191
	v_maximum3_f32 v96, v96, v175, v97
	v_mov_b32_e32 v97, v96
	s_nop 1
	v_permlane32_swap_b32_e32 v96, v97
	v_maximum3_f32 v96, v96, v97, v97
	v_cmp_lt_f32_e32 vcc, s46, v96
	s_cbranch_vccz .LBB0_653
	v_max_f32_e32 v80, v96, v96
	v_max_f32_e32 v80, 0, v80
	v_exp_f32_e64 v81, -v80
	s_and_saveexec_b64 s[6:7], s[38:39]
	ds_write_b32 v231, v81 offset:49152
	s_or_b64 exec, exec, s[6:7]
	v_mul_f32_e32 v92, v210, v80
	v_mul_f32_e32 v93, v211, v81
	s_waitcnt lgkmcnt(0)
	v_sub_f32_e32 v176, v176, v80
	v_sub_f32_e32 v177, v177, v80
	v_add_u32_e32 v92, s67, v194
	v_sub_f32_e32 v160, v160, v80
	v_sub_f32_e32 v161, v161, v80
	v_sub_f32_e32 v178, v178, v80
	v_sub_f32_e32 v179, v179, v80
	v_sub_f32_e32 v162, v162, v80
	v_sub_f32_e32 v163, v163, v80
	v_sub_f32_e32 v180, v180, v80
	v_sub_f32_e32 v181, v181, v80
	v_sub_f32_e32 v164, v164, v80
	v_sub_f32_e32 v165, v165, v80
	v_sub_f32_e32 v182, v182, v80
	v_sub_f32_e32 v183, v183, v80
	v_sub_f32_e32 v166, v166, v80
	v_sub_f32_e32 v167, v167, v80
	v_sub_f32_e32 v184, v184, v80
	v_sub_f32_e32 v185, v185, v80
	v_sub_f32_e32 v168, v168, v80
	v_sub_f32_e32 v169, v169, v80
	v_sub_f32_e32 v186, v186, v80
	v_sub_f32_e32 v187, v187, v80
	v_sub_f32_e32 v170, v170, v80
	v_sub_f32_e32 v171, v171, v80
	v_sub_f32_e32 v188, v188, v80
	v_sub_f32_e32 v189, v189, v80
	v_sub_f32_e32 v172, v172, v80
	v_sub_f32_e32 v173, v173, v80
	v_sub_f32_e32 v190, v190, v80
	v_sub_f32_e32 v191, v191, v80
	v_sub_f32_e32 v174, v174, v80
	v_sub_f32_e32 v175, v175, v80
	v_add_f32_e32 v126, v210, v80
	v_add_f32_e32 v127, v211, v81
	ds_read_b128 v[80:83], v92 offset:49216
	ds_read_b128 v[84:87], v92 offset:49248
	ds_read_b128 v[88:91], v92 offset:49152
	ds_read_b128 v[96:99], v92 offset:49184
	v_mov_b32_e32 v127, v93
	s_waitcnt lgkmcnt(0)
	v_pk_add_f32 v[94:95], v[126:127], 0 neg_lo:[1,1] neg_hi:[1,1]
	s_waitcnt lgkmcnt(0)
	v_mul_f32_e32 v76, v76, v84
	v_mul_f32_e32 v77, v77, v85
	v_mul_f32_e32 v72, v72, v80
	v_mul_f32_e32 v73, v73, v81
	v_mul_f32_e32 v68, v68, v96
	v_mul_f32_e32 v69, v69, v97
	v_mul_f32_e32 v78, v78, v86
	v_mul_f32_e32 v79, v79, v87
	v_mul_f32_e32 v74, v74, v82
	v_mul_f32_e32 v75, v75, v83
	v_mul_f32_e32 v70, v70, v98
	v_mul_f32_e32 v71, v71, v99
	v_mul_f32_e32 v66, v66, v90
	v_mul_f32_e32 v67, v67, v91
	v_mul_f32_e32 v64, v64, v88
	v_mul_f32_e32 v65, v65, v89
	v_mul_f32_e32 v44, v44, v84
	v_mul_f32_e32 v45, v45, v85
	v_mul_f32_e32 v40, v40, v80
	v_mul_f32_e32 v41, v41, v81
	v_mul_f32_e32 v36, v36, v96
	v_mul_f32_e32 v37, v37, v97
	v_mul_f32_e32 v46, v46, v86
	v_mul_f32_e32 v47, v47, v87
	v_mul_f32_e32 v42, v42, v82
	v_mul_f32_e32 v43, v43, v83
	v_mul_f32_e32 v38, v38, v98
	v_mul_f32_e32 v39, v39, v99
	v_mul_f32_e32 v34, v34, v90
	v_mul_f32_e32 v35, v35, v91
	v_mul_f32_e32 v32, v32, v88
	v_mul_f32_e32 v33, v33, v89
	v_mov_b32_e32 v210, v126
	v_mov_b32_e32 v95, v94
	v_mov_b32_e32 v93, v94
	v_mov_b32_e32 v92, v94
	v_mov_b32_e32 v91, v94
	v_mov_b32_e32 v90, v94
	v_mov_b32_e32 v89, v94
	v_mov_b32_e32 v88, v94
	v_mov_b32_e32 v87, v94
	v_mov_b32_e32 v86, v94
	v_mov_b32_e32 v85, v94
	v_mov_b32_e32 v84, v94
	v_mov_b32_e32 v83, v94
	v_mov_b32_e32 v82, v94
	v_mov_b32_e32 v81, v94
	v_mov_b32_e32 v80, v94
	s_branch .LBB0_654

; #define ATT_SYNC() do { asm volatile("s_waitcnt vmcnt(0)" ::: "memory"); __syncthreads(); } while (0)
; template <int NS, int DQK, int DV, bool KSH  > ...
;     ...
;         for (int t = tlo; t < thi; ++t) {
;             if (t + 2 < thi) ATT_DMA(t + 2, bnn);
;             ATT_MAX(pA0, pA1, 0, t == tlo);
;             ATT_QKEXP(pB0, pB1, NS - 1, bc, pA0, pA1, 0);
;             ATT_PV(0, bc);
;             ATT_MAX(pB0, pB1, NS - 1, t == tlo);
;             ATT_QKEXP(pA0, pA1, 0, bn, pB0, pB1, NS - 1);
;             ATT_PV(NS - 1, bc);
;             ATT_SYNC();
;             const int tmp = bc; bc = bn; bn = bnn; bnn = tmp;
;         }
.LBB0_654:
	v_add_u32_e32 v200, s10, v223
	v_mov_b32_e32 v96, 0
	v_mov_b32_e32 v124, 0
	v_add_u32_e32 v97, v200, v96
	ds_read_b128 v[114:117], v97
	ds_read_b128 v[132:135], v97 offset:512
	v_add_u32_e32 v96, v221, v96
	ds_read_b128 v[128:131], v96 offset:51200
	v_exp_f32_e32 v125, v176
	v_add_u32_e32 v118, v200, v124
	ds_read_b128 v[136:139], v118 offset:2048
	s_waitcnt lgkmcnt(0)
	v_mfma_f32_32x32x16_bf16 v[96:111], v[114:117], v[128:131], v[144:159]
	ds_read_b128 v[116:119], v118 offset:2560
	v_add_u32_e32 v114, v221, v124
	v_exp_f32_e32 v124, v178
	v_add_f32_e32 v140, v121, v120
	v_add_f32_e32 v141, v123, v122
	v_exp_f32_e32 v201, v166
	v_exp_f32_e32 v211, v167
	v_mfma_f32_32x32x16_bf16 v[144:159], v[132:135], v[128:131], v[144:159]
	v_exp_f32_e32 v133, v177
	v_exp_f32_e32 v129, v160
	v_exp_f32_e32 v131, v161
	v_exp_f32_e32 v132, v179
	v_exp_f32_e32 v128, v162
	v_exp_f32_e32 v130, v163
	ds_read_b128 v[120:123], v114 offset:59392
	v_add_f32_e32 v134, v132, v124
	v_add_f32_e32 v135, v133, v125
	s_waitcnt lgkmcnt(0)
	v_mfma_f32_32x32x16_bf16 v[96:111], v[136:139], v[120:123], v[96:111]
	v_add_f32_e64 v142, v130, v128
	v_add_f32_e64 v143, v131, v129
	v_mov_b32_e32 v136, 0
	v_add_f32_e64 v134, v142, v134
	v_add_f32_e64 v135, v143, v135
	v_cvt_pk_bf16_f32 v114, v125, v133
	v_add_f32_e32 v115, 0, v135
	v_add_f32_e32 v143, v134, v115
	v_cvt_pk_bf16_f32 v115, v124, v132
	v_exp_f32_e32 v133, v180
	v_add_u32_e32 v124, v200, v136
	v_exp_f32_e32 v135, v181
	v_exp_f32_e32 v132, v164
	v_exp_f32_e32 v134, v165
	ds_read_b128 v[160:163], v124 offset:4096
	v_mfma_f32_32x32x16_bf16 v[144:159], v[116:119], v[120:123], v[144:159]
	ds_read_b128 v[122:125], v124 offset:4608
	v_add3_u32 v116, v221, v136, s45
	ds_read_b128 v[176:179], v116
	v_add_f32_e64 v116, v134, v132
	v_add_f32_e64 v117, v135, v133
	v_exp_f32_e32 v118, v182
	v_exp_f32_e32 v119, v183
	v_add_f32_e32 v166, v116, v116
	v_add_f32_e32 v167, v116, v117
	v_exp_f32_e32 v142, v184
	v_exp_f32_e32 v166, v185
	v_exp_f32_e32 v136, v168
	v_exp_f32_e32 v138, v169
	v_mov_b32_e32 v224, 0
	v_exp_f32_e32 v181, v186
	v_exp_f32_e32 v183, v187
	v_exp_f32_e32 v180, v170
	v_exp_f32_e32 v182, v171
	v_cvt_pk_bf16_f32 v116, v133, v135
	v_add_f32_e32 v137, v119, v118
	v_add_f32_e32 v139, v211, v201
	v_cvt_pk_bf16_f32 v117, v118, v119
	v_add_u32_e32 v133, v200, v224
	s_waitcnt lgkmcnt(0)
	v_mfma_f32_32x32x16_bf16 v[96:111], v[160:163], v[176:179], v[96:111]
	ds_read_b128 v[118:121], v133 offset:6144
	v_add_f32_e64 v160, v166, v142
	v_add_f32_e64 v161, v167, v143
	v_add_f32_e64 v162, v138, v136
	v_add_f32_e64 v163, v139, v137
	v_exp_f32_e32 v185, v188
	v_add_f32_e32 v160, v162, v160
	v_add_f32_e32 v161, v163, v161
	v_exp_f32_e32 v187, v189
	v_add_f32_e32 v164, v160, v160
	v_add_f32_e32 v165, v160, v161
	v_mfma_f32_32x32x16_bf16 v[144:159], v[122:125], v[176:179], v[144:159]
	ds_read_b128 v[122:125], v133 offset:6656
	ds_read_b128 v[168:171], v63 offset:8704
	v_cvt_pk_bf16_f32 v160, v142, v166
	v_add_f32_e64 v142, v182, v180
	v_add_f32_e64 v143, v183, v181
	v_exp_f32_e32 v164, v190
	v_add_f32_e32 v166, v142, v142
	v_add_f32_e32 v167, v142, v143
	v_exp_f32_e32 v166, v191
	s_waitcnt lgkmcnt(0)
	v_mfma_f32_32x32x16_bf16 v[32:47], v[114:117], v[168:171], v[32:47]
	ds_read_b128 v[176:179], v63 offset:10752
	v_cvt_pk_bf16_f32 v161, v181, v183
	v_cvt_pk_bf16_f32 v162, v185, v187
	v_cvt_pk_bf16_f32 v163, v164, v166
	v_cvt_pk_bf16_f32 v168, v129, v131
	v_cvt_pk_bf16_f32 v169, v128, v130
	v_cvt_pk_bf16_f32 v170, v132, v134
	s_waitcnt lgkmcnt(0)
	v_mfma_f32_32x32x16_bf16 v[32:47], v[160:163], v[176:179], v[32:47]
	ds_read_b128 v[128:131], v63 offset:12800
	v_cvt_pk_bf16_f32 v171, v201, v211
	v_exp_f32_e32 v181, v172
	v_exp_f32_e32 v183, v173
	v_exp_f32_e32 v184, v174
	v_exp_f32_e32 v186, v175
	v_cvt_pk_bf16_f32 v176, v136, v138
	s_waitcnt lgkmcnt(0)
	v_mfma_f32_32x32x16_bf16 v[32:47], v[168:171], v[128:131], v[32:47]
	ds_read_b128 v[132:135], v63 offset:14848
	v_cvt_pk_bf16_f32 v177, v180, v182
	v_cvt_pk_bf16_f32 v178, v181, v183
	v_cvt_pk_bf16_f32 v179, v184, v186
	v_add_f32_e32 v129, v234, v215
	v_add_f32_e32 v130, v237, v235
	v_add_f32_e32 v129, v130, v129
	v_add3_u32 v130, v221, v224, s18
	s_waitcnt lgkmcnt(0)
	v_mfma_f32_32x32x16_bf16 v[32:47], v[176:179], v[132:135], v[32:47]
	ds_read_b128 v[172:175], v130
	v_add_f32_e32 v128, v141, v140
	v_add_f32_e32 v128, 0, v128
	v_add_f32_e32 v128, v129, v128
	v_add_f32_e32 v113, v213, v113
	v_add_f32_e32 v129, v236, v232
	v_add_f32_e32 v113, v129, v113
	s_waitcnt lgkmcnt(0)
	v_mfma_f32_32x32x16_bf16 v[96:111], v[118:121], v[172:175], v[96:111]
	v_add_f32_e32 v118, v238, v233
	v_add_f32_e32 v119, v240, v239
	v_add_f32_e32 v113, v113, v128
	v_add_f32_e32 v118, v119, v118
	v_add_f32_e32 v113, v118, v113
	ds_read_b128 v[118:121], v63 offset:8192
	v_mov_b64_e32 v[128:129], v[144:145]
	v_mov_b64_e32 v[130:131], v[146:147]
	v_mov_b64_e32 v[132:133], v[148:149]
	v_mov_b64_e32 v[134:135], v[150:151]
	v_mov_b64_e32 v[136:137], v[152:153]
	v_mov_b64_e32 v[138:139], v[154:155]
	v_mov_b64_e32 v[140:141], v[156:157]
	v_mov_b64_e32 v[142:143], v[158:159]
	v_add_f32_e32 v144, v250, v249
	v_add_f32_e32 v145, v228, v227
	v_mfma_f32_32x32x16_bf16 v[128:143], v[122:125], v[172:175], v[128:143]
	v_add_f32_e32 v122, v242, v241
	v_add_f32_e32 v123, v247, v245
	v_add_f32_e32 v122, v123, v122
	v_add_f32_e32 v113, v122, v113
	ds_read_b128 v[122:125], v63 offset:10240
	v_add_f32_e32 v185, v187, v185
	v_add_f32_e32 v187, v183, v181
	s_waitcnt lgkmcnt(0)
	v_mfma_f32_32x32x16_bf16 v[64:79], v[114:117], v[118:121], v[64:79]
	v_add_f32_e32 v114, v145, v144
	v_add_f32_e32 v113, v114, v113
	v_add_f32_e32 v114, v248, v246
	v_add_f32_e32 v115, v226, v225
	v_add_f32_e32 v114, v115, v114
	v_add_f32_e32 v113, v114, v113
	ds_read_b128 v[114:117], v63 offset:12288
	v_mfma_f32_32x32x16_bf16 v[64:79], v[160:163], v[122:125], v[64:79]
	v_add_f32_e32 v118, v244, v243
	v_add_f32_e32 v119, v230, v251
	v_add_f32_e32 v118, v119, v118
	v_add_f32_e32 v113, v118, v113
	ds_read_b128 v[118:121], v63 offset:14336
	s_waitcnt vmcnt(0)
	s_add_i32 s9, s9, 1
	s_waitcnt lgkmcnt(0)
	v_mfma_f32_32x32x16_bf16 v[64:79], v[168:171], v[114:117], v[64:79]
	v_add_f32_e64 v114, v166, v164
	v_add_f32_e64 v115, v167, v165
	v_add_f32_e64 v116, v186, v184
	v_add_f32_e64 v117, v187, v185
	v_add_f32_e32 v209, v209, v113
	v_add_f32_e32 v114, v116, v114
	v_add_f32_e32 v115, v117, v115
	v_add_u32_e32 v212, 0x1000, v212
	v_pk_add_f32 v[114:115], v[114:115], v[114:115] op_sel:[0,1] op_sel_hi:[1,0]
	s_cmpk_eq_i32 s9, 0x83
	v_mfma_f32_32x32x16_bf16 v[64:79], v[176:179], v[118:121], v[64:79]
	v_add_f32_e64 v114, v127, v114
	v_add_f32_e64 v115, v126, v115
	v_add_u32_e32 v214, 64, v214
	s_waitcnt vmcnt(0)
	s_barrier
	s_cbranch_scc1 .LBB0_844
	s_mov_b32 s6, s10
	s_mov_b32 s10, s5
	s_mov_b32 s5, s11
	v_mov_b32_e32 v211, v114
	s_cmpk_gt_u32 s9, 0x80
	s_mov_b32 s11, s6
	s_cbranch_scc0 .LBB0_640
	s_branch .LBB0_644

.LBB0_679:
	s_nop 2
	v_maximum3_f32 v33, v0, v16, v16
	v_maximum3_f32 v34, v17, v2, v18
	v_maximum3_f32 v33, v33, v1, v3
	v_maximum3_f32 v34, v34, v4, v20
	v_maximum3_f32 v33, v33, v19, v5
	v_maximum3_f32 v34, v34, v6, v22
	v_maximum3_f32 v33, v33, v21, v7
	v_maximum3_f32 v34, v34, v8, v24
	v_maximum3_f32 v33, v33, v23, v9
	v_maximum3_f32 v34, v34, v10, v26
	v_maximum3_f32 v33, v33, v25, v11
	v_maximum3_f32 v34, v34, v12, v28
	v_maximum3_f32 v33, v33, v27, v13
	v_maximum3_f32 v34, v34, v14, v30
	v_maximum3_f32 v33, v33, v29, v15
	v_maximum3_f32 v33, v33, v31, v34
	v_mov_b32_e32 v34, v33
	s_nop 1
	v_permlane32_swap_b32_e32 v33, v34
	v_maximum3_f32 v116, v33, v34, v34
	v_sub_f32_e32 v83, v8, v116
	v_mov_b32_e32 v8, v195
	v_sub_f32_e32 v45, v4, v116
	v_sub_f32_e32 v41, v24, v116
	v_add_u32_e32 v4, v218, v8
	v_sub_f32_e32 v42, v25, v116
	v_sub_f32_e32 v24, v0, v116
	v_sub_f32_e32 v25, v1, v116
	v_sub_f32_e32 v43, v2, v116
	v_sub_f32_e32 v44, v3, v116
	ds_read_b128 v[0:3], v4 offset:6144
	v_sub_f32_e32 v46, v5, v116
	v_sub_f32_e32 v47, v6, v116
	v_sub_f32_e32 v82, v7, v116
	ds_read_b128 v[4:7], v4 offset:6656
	v_add_u32_e32 v8, v213, v8
	v_sub_f32_e32 v33, v16, v116
	v_sub_f32_e32 v34, v17, v116
	v_sub_f32_e32 v35, v18, v116
	v_sub_f32_e32 v36, v19, v116
	ds_read_b128 v[16:19], v8 offset:24576
	v_mov_b32_e32 v8, v195
	s_mov_b32 s18, s4
	s_mov_b32 s19, s4
	v_sub_f32_e32 v92, v9, v116
	s_mov_b32 s5, s4
	v_add_u32_e32 v9, v218, v8
	s_mov_b32 s6, s4
	s_mov_b32 s7, s4
	s_mov_b32 s8, s4
	s_mov_b32 s9, s4
	s_mov_b32 s10, s4
	s_mov_b32 s11, s4
	s_mov_b32 s12, s4
	s_mov_b32 s13, s4
	s_mov_b32 s14, s4
	s_mov_b32 s15, s4
	s_mov_b32 s16, s4
	s_mov_b32 s17, s4
	v_mov_b64_e32 v[78:79], s[18:19]
	v_sub_f32_e32 v37, v20, v116
	v_sub_f32_e32 v38, v21, v116
	v_sub_f32_e32 v39, v22, v116
	v_sub_f32_e32 v40, v23, v116
	ds_read_b128 v[20:23], v9 offset:8192
	v_mov_b64_e32 v[76:77], s[16:17]
	v_mov_b64_e32 v[74:75], s[14:15]
	v_mov_b64_e32 v[72:73], s[12:13]
	v_mov_b64_e32 v[70:71], s[10:11]
	v_mov_b64_e32 v[68:69], s[8:9]
	v_mov_b64_e32 v[66:67], s[6:7]
	v_mov_b64_e32 v[64:65], s[4:5]
	v_sub_f32_e32 v93, v10, v116
	v_sub_f32_e32 v94, v11, v116
	s_waitcnt lgkmcnt(0)
	v_mfma_f32_32x32x16_bf16 v[48:63], v[0:3], v[16:19], v[64:79]
	v_sub_f32_e32 v95, v12, v116
	v_sub_f32_e32 v96, v13, v116
	v_sub_f32_e32 v97, v14, v116
	v_sub_f32_e32 v98, v15, v116
	ds_read_b128 v[0:3], v9 offset:8704
	v_exp_f32_e32 v11, v24
	v_exp_f32_e32 v13, v25
	v_mfma_f32_32x32x16_bf16 v[64:79], v[4:7], v[16:19], v[64:79]
	v_exp_f32_e32 v15, v33
	v_exp_f32_e32 v17, v34
	v_exp_f32_e32 v10, v43
	v_exp_f32_e32 v12, v44
	v_exp_f32_e32 v14, v35
	v_exp_f32_e32 v16, v36
	v_add_u32_e32 v8, v213, v8
	ds_read_b128 v[4:7], v8 offset:32768
	v_add_f32_e32 v18, v12, v10
	v_add_f32_e32 v19, v13, v11
	v_add_f32_e32 v24, v16, v14
	v_add_f32_e32 v25, v17, v15
	v_cvt_pk_bf16_f32 v80, v15, v17
	v_add_f32_e32 v18, v24, v18
	v_add_f32_e32 v19, v25, v19
	s_waitcnt lgkmcnt(0)
	v_mfma_f32_32x32x16_bf16 v[48:63], v[20:23], v[4:7], v[48:63]
	v_add_f32_e32 v9, 0, v19
	v_add_f32_e32 v17, v18, v9
	v_exp_f32_e32 v19, v45
	v_exp_f32_e32 v21, v46
	v_exp_f32_e32 v18, v37
	v_exp_f32_e32 v20, v38
	v_cvt_pk_bf16_f32 v9, v10, v12
	v_mov_b32_e32 v10, v195
	v_cvt_pk_bf16_f32 v8, v11, v13
	v_cvt_pk_bf16_f32 v81, v14, v16
	v_add_u32_e32 v11, v218, v10
	ds_read_b128 v[12:15], v11 offset:10240
	v_mfma_f32_32x32x16_bf16 v[64:79], v[0:3], v[4:7], v[64:79]
	v_add_u32_e32 v0, v213, v10
	ds_read_b128 v[84:87], v11 offset:10752
	ds_read_b128 v[88:91], v0 offset:40960
	v_add_f32_e64 v0, v20, v18
	v_add_f32_e64 v1, v21, v19
	v_exp_f32_e32 v2, v47
	v_add_f32_e32 v1, v0, v1
	v_add_f32_e32 v0, v0, v0
	v_exp_f32_e32 v3, v82
	v_cvt_pk_bf16_f32 v10, v19, v21
	v_exp_f32_e32 v19, v39
	v_exp_f32_e32 v21, v40
	v_exp_f32_e32 v16, v83
	v_exp_f32_e32 v0, v92
	v_exp_f32_e32 v4, v41
	v_exp_f32_e32 v6, v42
	v_add_f32_e32 v5, v3, v2
	v_add_f32_e32 v7, v21, v19
	v_cvt_pk_bf16_f32 v11, v2, v3
	v_add_f32_e32 v2, v0, v16
	v_add_f32_e32 v3, v1, v17
	v_add_f32_e32 v22, v6, v4
	v_add_f32_e32 v23, v7, v5
	v_cvt_pk_bf16_f32 v92, v16, v0
	v_lshlrev_b32_e32 v0, 9, v211
	v_add_f32_e32 v2, v22, v2
	v_add_f32_e32 v3, v23, v3
	v_add3_u32 v133, v32, v0, v215
	v_add_f32_e32 v104, v2, v2
	v_add_f32_e32 v105, v2, v3
	s_waitcnt lgkmcnt(0)
	v_mfma_f32_32x32x16_bf16 v[48:63], v[12:15], v[88:91], v[48:63]
	ds_read_b128 v[0:3], v133 offset:12288
	v_exp_f32_e32 v106, v98
	v_exp_f32_e32 v104, v97
	v_exp_f32_e32 v107, v96
	v_exp_f32_e32 v115, v95
	v_exp_f32_e32 v109, v94
	v_exp_f32_e32 v111, v93
	s_waitcnt lgkmcnt(0)
	v_mfma_f32_32x32x16_bf16 v[32:47], v[8:11], v[0:3], 0
	v_cvt_pk_bf16_f32 v95, v104, v106
	v_cvt_pk_bf16_f32 v94, v115, v107
	v_cvt_pk_bf16_f32 v93, v111, v109
	ds_read_b128 v[0:3], v133 offset:15360
	v_cvt_pk_bf16_f32 v82, v18, v20
	v_cvt_pk_bf16_f32 v83, v19, v21
	v_sub_f32_e32 v26, v26, v116
	s_waitcnt lgkmcnt(0)
	v_mfma_f32_32x32x16_bf16 v[32:47], v[92:95], v[0:3], v[32:47]
	ds_read_b128 v[0:3], v133 offset:18432
	v_sub_f32_e32 v27, v27, v116
	v_sub_f32_e32 v28, v28, v116
	v_sub_f32_e32 v29, v29, v116
	v_sub_f32_e32 v30, v30, v116
	v_sub_f32_e32 v31, v31, v116
	v_exp_f32_e32 v112, v31
	v_exp_f32_e32 v114, v30
	v_exp_f32_e32 v113, v29
	v_exp_f32_e32 v117, v28
	v_exp_f32_e32 v108, v27
	v_exp_f32_e32 v110, v26
	s_waitcnt lgkmcnt(0)
	v_mfma_f32_32x32x16_bf16 v[32:47], v[80:83], v[0:3], v[32:47]
	v_cvt_pk_bf16_f32 v96, v4, v6
	v_cvt_pk_bf16_f32 v99, v114, v112
	v_cvt_pk_bf16_f32 v98, v117, v113
	v_cvt_pk_bf16_f32 v97, v110, v108
	ds_read_b128 v[0:3], v133 offset:21504
	v_add_f32_e32 v113, v113, v117
	v_add_f32_e32 v115, v107, v115
	s_waitcnt lgkmcnt(0)
	v_mfma_f32_32x32x16_bf16 v[32:47], v[96:99], v[0:3], v[32:47]
	ds_read_b128 v[0:3], v133 offset:12800
	s_add_i32 s7, s73, 0x80c0
	s_mul_i32 s8, s7, 48
	s_lshl_b32 s5, s42, 2
	s_add_i32 s5, s5, 0
	s_add_i32 s5, s5, 0x12000
	v_cmp_gt_u32_e64 s[42:43], 32, v210
	s_waitcnt lgkmcnt(0)
	v_mfma_f32_32x32x16_bf16 v[16:31], v[8:11], v[0:3], 0
	ds_read_b128 v[0:3], v133 offset:15872
	v_lshl_add_u32 v219, v212, 2, s5
	v_mul_u32_u24_e32 v220, 0x600, v211
	s_mov_b32 s6, 0
	s_waitcnt lgkmcnt(0)
	v_mfma_f32_32x32x16_bf16 v[16:31], v[92:95], v[0:3], v[16:31]
	ds_read_b128 v[0:3], v133 offset:18944
	s_waitcnt lgkmcnt(0)
	v_mfma_f32_32x32x16_bf16 v[16:31], v[80:83], v[0:3], v[16:31]
	ds_read_b128 v[0:3], v133 offset:22016
	s_waitcnt lgkmcnt(0)
	v_mfma_f32_32x32x16_bf16 v[16:31], v[96:99], v[0:3], v[16:31]
	ds_read_b128 v[0:3], v133 offset:13312
	s_waitcnt lgkmcnt(0)
	v_mfma_f32_32x32x16_bf16 v[0:15], v[8:11], v[0:3], 0
	ds_read_b128 v[100:103], v133 offset:16384
	s_waitcnt lgkmcnt(0)
	v_mfma_f32_32x32x16_bf16 v[0:15], v[92:95], v[100:103], v[0:15]
	ds_read_b128 v[92:95], v133 offset:19456
	v_add_f32_e64 v100, v108, v110
	v_add_f32_e64 v101, v109, v111
	v_add_f32_e32 v101, v100, v101
	v_add_f32_e32 v100, v100, v100
	v_mov_b32_e32 v107, v101
	s_waitcnt lgkmcnt(0)
	v_mfma_f32_32x32x16_bf16 v[0:15], v[80:83], v[92:95], v[0:15]
	ds_read_b128 v[80:83], v133 offset:22528
	v_add_f32_e64 v92, v112, v114
	v_add_f32_e64 v93, v113, v115
	v_add_f32_e64 v94, v106, v104
	v_add_f32_e64 v95, v107, v105
	v_add_f32_e32 v92, v92, v94
	v_add_f32_e32 v93, v93, v95
	s_waitcnt lgkmcnt(0)
	v_mfma_f32_32x32x16_bf16 v[0:15], v[96:99], v[80:83], v[0:15]
	v_add_f32_e64 v80, v92, v93
	v_add_f32_e64 v81, v93, v92
	v_mov_b32_e32 v92, v195
	v_mov_b32_e32 v81, v116
	v_add_f32_e64 v180, v80, 0
	v_add_f32_e64 v181, v81, 0
	v_add_u32_e32 v93, v218, v92
	ds_read_b128 v[80:83], v93 offset:24576
	v_mfma_f32_32x32x16_bf16 v[64:79], v[84:87], v[88:91], v[64:79]
	v_xor_b32_e32 v96, 0x80000000, v181
	v_mov_b32_e32 v97, v96
	v_mov_b32_e32 v98, v96
	v_mov_b32_e32 v99, v96
	v_mov_b32_e32 v100, v96
	v_mov_b32_e32 v101, v96
	v_mov_b32_e32 v102, v96
	s_nop 4
	v_maximum3_f32 v84, v48, v64, v64
	v_maximum3_f32 v85, v65, v50, v66
	v_maximum3_f32 v84, v84, v49, v51
	v_maximum3_f32 v85, v85, v52, v68
	v_maximum3_f32 v84, v84, v67, v53
	v_maximum3_f32 v85, v85, v54, v70
	v_maximum3_f32 v84, v84, v69, v55
	v_maximum3_f32 v85, v85, v56, v72
	v_maximum3_f32 v84, v84, v71, v57
	v_maximum3_f32 v85, v85, v58, v74
	v_maximum3_f32 v84, v84, v73, v59
	v_maximum3_f32 v85, v85, v60, v76
	v_maximum3_f32 v84, v84, v75, v61
	v_maximum3_f32 v85, v85, v62, v78
	v_maximum3_f32 v84, v84, v77, v63
	v_maximum3_f32 v84, v84, v79, v85
	v_mov_b32_e32 v85, v84
	s_nop 1
	v_permlane32_swap_b32_e32 v84, v85
	v_maximum3_f32 v136, v84, v85, v85
	v_sub_f32_e32 v84, v48, v136
	v_sub_f32_e32 v85, v49, v136
	v_sub_f32_e32 v86, v50, v136
	v_sub_f32_e32 v87, v51, v136
	ds_read_b128 v[48:51], v93 offset:25088
	v_sub_f32_e32 v88, v52, v136
	v_add_u32_e32 v52, v213, v92
	v_sub_f32_e32 v89, v53, v136
	v_sub_f32_e32 v90, v54, v136
	v_sub_f32_e32 v91, v55, v136
	ds_read_b128 v[52:55], v52
	v_sub_f32_e32 v135, v60, v136
	v_mov_b32_e32 v103, v96
	v_mov_b32_e32 v104, v96
	v_mov_b32_e32 v105, v96
	v_mov_b32_e32 v106, v96
	v_mov_b32_e32 v107, v96
	v_mov_b32_e32 v108, v96
	v_mov_b32_e32 v109, v96
	v_mov_b32_e32 v110, v96
	v_mov_b32_e32 v111, v96
	v_mov_b32_e32 v60, v195
	v_sub_f32_e32 v94, v56, v136
	s_waitcnt lgkmcnt(0)
	v_mfma_f32_32x32x16_bf16 v[112:127], v[80:83], v[52:55], v[96:111]
	v_sub_f32_e32 v80, v61, v136
	v_add_u32_e32 v61, v218, v60
	v_sub_f32_e32 v95, v57, v136
	v_sub_f32_e32 v130, v58, v136
	v_sub_f32_e32 v131, v59, v136
	ds_read_b128 v[56:59], v61 offset:26624
	v_sub_f32_e32 v81, v62, v136
	v_mfma_f32_32x32x16_bf16 v[96:111], v[48:51], v[52:55], v[96:111]
	ds_read_b128 v[50:53], v61 offset:27136
	v_add_u32_e32 v48, v213, v60
	v_sub_f32_e32 v82, v63, v136
	ds_read_b128 v[60:63], v48 offset:8192
	v_sub_f32_e32 v64, v64, v136
	v_exp_f32_e32 v143, v64
	v_mov_b32_e32 v64, v195
	s_waitcnt lgkmcnt(0)
	v_mfma_f32_32x32x16_bf16 v[112:127], v[56:59], v[60:63], v[112:127]
	v_sub_f32_e32 v65, v65, v136
	v_add_u32_e32 v58, v218, v64
	ds_read_b128 v[54:57], v58 offset:28672
	v_exp_f32_e32 v145, v65
	v_exp_f32_e32 v139, v84
	v_exp_f32_e32 v141, v85
	v_mfma_f32_32x32x16_bf16 v[96:111], v[50:53], v[60:63], v[96:111]
	ds_read_b128 v[58:61], v58 offset:29184
	v_add_u32_e32 v50, v213, v64
	ds_read_b128 v[62:65], v50 offset:16384
	v_exp_f32_e32 v138, v86
	v_exp_f32_e32 v140, v87
	v_exp_f32_e32 v147, v88
	v_exp_f32_e32 v149, v89
	v_exp_f32_e32 v137, v90
	v_exp_f32_e32 v151, v91
	v_cvt_pk_bf16_f32 v48, v139, v141
	v_cvt_pk_bf16_f32 v49, v138, v140
	v_cvt_pk_bf16_f32 v50, v147, v149
	s_waitcnt lgkmcnt(0)
; #define ATT_SYNC() do { asm volatile("s_waitcnt vmcnt(0)" ::: "memory"); __syncthreads(); } while (0)
; template <int NS, int DQK, int DV, bool KSH  > ...
;     ...
;         for (int t = tlo; t < thi; ++t) {
;             if (t + 2 < thi) ATT_DMA(t + 2, bnn);
;             ATT_MAX(pA0, pA1, 0, t == tlo);
;             ATT_QKEXP(pB0, pB1, NS - 1, bc, pA0, pA1, 0);
;             ATT_PV(0, bc);
;             ATT_MAX(pB0, pB1, NS - 1, t == tlo);
;             ATT_QKEXP(pA0, pA1, 0, bn, pB0, pB1, NS - 1);
;             ATT_PV(NS - 1, bc);
;             ATT_SYNC();
;             const int tmp = bc; bc = bn; bn = bnn; bnn = tmp;
;         }
	v_mfma_f32_32x32x16_bf16 v[96:111], v[58:61], v[62:65], v[96:111]
	v_cvt_pk_bf16_f32 v51, v137, v151
	ds_read_b128 v[182:185], v133 offset:16384
	v_exp_f32_e32 v154, v94
	v_exp_f32_e32 v156, v95
	v_exp_f32_e32 v150, v81
	v_exp_f32_e32 v152, v82
	v_exp_f32_e32 v167, v131
	v_mfma_f32_32x32x16_bf16 v[112:127], v[54:57], v[62:65], v[112:127]
	ds_read_b128 v[52:55], v133 offset:12288
	v_exp_f32_e32 v157, v80
	v_exp_f32_e32 v135, v135
	v_exp_f32_e32 v169, v130
	v_cvt_pk_bf16_f32 v172, v154, v156
	v_cvt_pk_bf16_f32 v175, v150, v152
	v_cvt_pk_bf16_f32 v174, v135, v157
	s_waitcnt lgkmcnt(0)
	v_mfma_f32_32x32x16_bf16 v[80:95], v[48:51], v[52:55], 0
	v_cvt_pk_bf16_f32 v173, v169, v167
	ds_read_b128 v[52:55], v133 offset:15360
	v_sub_f32_e32 v66, v66, v136
	v_sub_f32_e32 v67, v67, v136
	v_sub_f32_e32 v68, v68, v136
	v_sub_f32_e32 v69, v69, v136
	v_sub_f32_e32 v70, v70, v136
	v_sub_f32_e32 v71, v71, v136
	v_exp_f32_e32 v142, v66
	v_exp_f32_e32 v144, v67
	v_exp_f32_e32 v146, v68
	v_exp_f32_e32 v148, v69
	v_exp_f32_e32 v153, v70
	v_exp_f32_e32 v155, v71
	s_waitcnt lgkmcnt(0)
	v_mfma_f32_32x32x16_bf16 v[80:95], v[172:175], v[52:55], v[80:95]
	v_cvt_pk_bf16_f32 v128, v143, v145
	v_cvt_pk_bf16_f32 v129, v142, v144
	v_cvt_pk_bf16_f32 v130, v146, v148
	v_cvt_pk_bf16_f32 v131, v153, v155
	ds_read_b128 v[52:55], v133 offset:18432
	v_sub_f32_e32 v72, v72, v136
	v_sub_f32_e32 v73, v73, v136
	v_sub_f32_e32 v74, v74, v136
	v_sub_f32_e32 v75, v75, v136
	v_sub_f32_e32 v76, v76, v136
	v_sub_f32_e32 v77, v77, v136
	v_sub_f32_e32 v78, v78, v136
	v_sub_f32_e32 v79, v79, v136
	v_exp_f32_e32 v158, v72
	v_exp_f32_e32 v160, v73
	v_exp_f32_e32 v162, v78
	v_exp_f32_e32 v164, v79
	v_exp_f32_e32 v166, v75
	v_exp_f32_e32 v159, v77
	v_exp_f32_e32 v161, v76
	v_exp_f32_e32 v168, v74
	s_waitcnt lgkmcnt(0)
	v_mfma_f32_32x32x16_bf16 v[80:95], v[128:131], v[52:55], v[80:95]
	v_cvt_pk_bf16_f32 v176, v158, v160
	v_cvt_pk_bf16_f32 v179, v162, v164
	v_cvt_pk_bf16_f32 v178, v161, v159
	v_cvt_pk_bf16_f32 v177, v168, v166
	ds_read_b128 v[52:55], v133 offset:21504
	v_add_f32_e32 v142, v144, v142
	v_add_f32_e32 v143, v145, v143
	v_add_f32_e32 v138, v140, v138
	v_add_f32_e32 v139, v141, v139
	s_waitcnt lgkmcnt(0)
	v_mfma_f32_32x32x16_bf16 v[80:95], v[176:179], v[52:55], v[80:95]
	ds_read_b128 v[52:55], v133 offset:12800
	v_add_f32_e64 v138, v142, v138
	v_add_f32_e64 v139, v143, v139
	v_add_f32_e32 v165, v159, v161
	v_add_f32_e32 v163, v157, v135
	v_add_f32_e32 v161, v155, v153
	v_add_f32_e32 v159, v151, v137
	s_waitcnt lgkmcnt(0)
	v_mfma_f32_32x32x16_bf16 v[64:79], v[48:51], v[52:55], 0
	ds_read_b128 v[52:55], v133 offset:15872
	s_waitcnt lgkmcnt(0)
	v_mfma_f32_32x32x16_bf16 v[64:79], v[172:175], v[52:55], v[64:79]
	ds_read_b128 v[52:55], v133 offset:18944
	s_waitcnt lgkmcnt(0)
	v_mfma_f32_32x32x16_bf16 v[64:79], v[128:131], v[52:55], v[64:79]
	ds_read_b128 v[52:55], v133 offset:22016
	s_waitcnt lgkmcnt(0)
	v_mfma_f32_32x32x16_bf16 v[64:79], v[176:179], v[52:55], v[64:79]
	ds_read_b128 v[52:55], v133 offset:13312
	s_waitcnt lgkmcnt(0)
	v_mfma_f32_32x32x16_bf16 v[48:63], v[48:51], v[52:55], 0
	v_mfma_f32_32x32x16_bf16 v[48:63], v[172:175], v[182:185], v[48:63]
	ds_read_b128 v[172:175], v133 offset:19456
	s_waitcnt lgkmcnt(0)
	v_mfma_f32_32x32x16_bf16 v[48:63], v[128:131], v[172:175], v[48:63]
	ds_read_b128 v[128:131], v133 offset:22528
	s_waitcnt vmcnt(0)
	s_waitcnt vmcnt(0) lgkmcnt(0)
	s_barrier
	v_mfma_f32_32x32x16_bf16 v[48:63], v[176:179], v[128:131], v[48:63]
	v_add_f32_e64 v128, v166, v168
	v_add_f32_e64 v129, v167, v169
	v_add_f32_e64 v130, v148, v146
	v_add_f32_e64 v131, v149, v147
	v_add_f32_e32 v129, v128, v129
	v_add_f32_e32 v128, v128, v128
	v_add_f32_e32 v131, v130, v131
	v_add_f32_e32 v130, v130, v130
	v_add_f32_e32 v128, 0, v139
	v_add_f32_e32 v155, v138, v128
	v_mov_b32_e32 v157, v131
	v_add_f32_e32 v138, v160, v158
	v_add_f32_e32 v139, v161, v159
	v_add_f32_e32 v130, v156, v154
	v_add_f32_e32 v131, v157, v155
	v_mov_b32_e32 v153, v129
	v_add_f32_e32 v130, v138, v130
	v_add_f32_e32 v131, v139, v131
	v_add_f32_e32 v138, v164, v162
	v_add_f32_e32 v139, v165, v163
	v_add_f32_e32 v131, v130, v131
	v_add_f32_e32 v130, v130, v130
	v_mov_b32_e32 v151, v131
	v_add_f32_e32 v128, v152, v150
	v_add_f32_e32 v129, v153, v151
	s_nop 0
	v_add_f32_e32 v128, v138, v128
	v_add_f32_e32 v129, v139, v129
	s_nop 0
	v_add_f32_e32 v129, v128, v129
	v_add_f32_e32 v128, v128, v128
	v_add_u32_e32 v128, s8, v170
	v_mov_b32_e32 v137, v129
	v_ashrrev_i32_e32 v129, 31, v128
	v_lshl_add_u64 v[182:183], v[128:129], 1, s[0:1]
	v_add_u32_e32 v128, s8, v171
	v_ashrrev_i32_e32 v129, 31, v128
	v_lshl_add_u64 v[184:185], v[128:129], 1, s[0:1]
	v_add_u32_e32 v128, s7, v132
	v_ashrrev_i32_e32 v129, 31, v128
	v_lshl_add_u64 v[186:187], v[128:129], 1, s[68:69]
	v_add_u32_e32 v128, s7, v134
	v_ashrrev_i32_e32 v129, 31, v128
	v_add_f32_e32 v190, 0, v136
	v_add_f32_e32 v191, 0, v137
	v_lshl_add_u64 v[188:189], v[128:129], 1, s[68:69]
	s_movk_i32 s7, 0x81
	s_mov_b32 s8, 0xc000
	s_movk_i32 s0, 0x6000
	s_cmpk_gt_u32 s7, 0x81
	s_mov_b32 s9, s0
	s_cbranch_scc1 .LBB0_685

.LBB0_685:
	v_maximum3_f32 v128, v112, v96, v96
	v_maximum3_f32 v129, v97, v114, v98
	v_maximum3_f32 v128, v128, v113, v115
	v_maximum3_f32 v129, v129, v116, v100
	v_maximum3_f32 v128, v128, v99, v117
	v_maximum3_f32 v129, v129, v118, v102
	v_maximum3_f32 v128, v128, v101, v119
	v_maximum3_f32 v129, v129, v120, v104
	v_maximum3_f32 v128, v128, v103, v121
	v_maximum3_f32 v129, v129, v122, v106
	v_maximum3_f32 v128, v128, v105, v123
	v_maximum3_f32 v129, v129, v124, v108
	v_maximum3_f32 v128, v128, v107, v125
	v_maximum3_f32 v129, v129, v126, v110
	v_maximum3_f32 v128, v128, v109, v127
	v_maximum3_f32 v128, v128, v111, v129
	v_mov_b32_e32 v129, v128
	s_nop 1
	v_permlane32_swap_b32_e32 v128, v129
	v_maximum3_f32 v128, v128, v129, v129
	v_cmp_lt_f32_e32 vcc, s46, v128
	s_cbranch_vccz .LBB0_689
	v_max_f32_e32 v128, v128, v128
	v_max_f32_e32 v130, 0, v128
	v_exp_f32_e64 v128, -v130
	s_and_saveexec_b64 s[0:1], s[42:43]
	ds_write_b32 v219, v128
	s_or_b64 exec, exec, s[0:1]
	v_mov_b32_e32 v129, v130
	v_sub_f32_e32 v112, v112, v130
	v_sub_f32_e32 v113, v113, v130
	v_sub_f32_e32 v96, v96, v130
	v_sub_f32_e32 v97, v97, v130
	v_sub_f32_e32 v114, v114, v130
	v_sub_f32_e32 v115, v115, v130
	v_sub_f32_e32 v98, v98, v130
	v_sub_f32_e32 v99, v99, v130
	v_sub_f32_e32 v116, v116, v130
	v_sub_f32_e32 v117, v117, v130
	v_sub_f32_e32 v100, v100, v130
	v_sub_f32_e32 v101, v101, v130
	v_sub_f32_e32 v118, v118, v130
	v_sub_f32_e32 v119, v119, v130
	v_sub_f32_e32 v102, v102, v130
	v_sub_f32_e32 v103, v103, v130
	v_sub_f32_e32 v120, v120, v130
	v_sub_f32_e32 v121, v121, v130
	v_sub_f32_e32 v104, v104, v130
	v_sub_f32_e32 v105, v105, v130
	v_sub_f32_e32 v122, v122, v130
	v_sub_f32_e32 v123, v123, v130
	v_sub_f32_e32 v106, v106, v130
	v_sub_f32_e32 v107, v107, v130
	v_sub_f32_e32 v124, v124, v130
	v_sub_f32_e32 v125, v125, v130
	v_sub_f32_e32 v108, v108, v130
	v_sub_f32_e32 v109, v109, v130
	v_sub_f32_e32 v126, v126, v130
	v_sub_f32_e32 v127, v127, v130
	v_sub_f32_e32 v110, v110, v130
	v_sub_f32_e32 v111, v111, v130
	v_add_f32_e32 v130, v180, v128
	v_add_f32_e32 v131, v181, v129
	v_mul_f32_e32 v180, v180, v128
	v_mul_f32_e32 v181, v181, v129
	s_waitcnt lgkmcnt(0)
	v_add_u32_e32 v140, s5, v194
	v_mov_b32_e32 v181, v131
	ds_read_b128 v[128:131], v140
	ds_read_b128 v[132:135], v140 offset:32
	ds_read_b128 v[136:139], v140 offset:64
	ds_read_b128 v[140:143], v140 offset:96
	s_waitcnt lgkmcnt(0)
	s_waitcnt lgkmcnt(0)
	v_mul_f32_e32 v34, v34, v130
	v_mul_f32_e32 v35, v35, v131
	v_mul_f32_e32 v36, v36, v132
	v_mul_f32_e32 v37, v37, v133
	v_mul_f32_e32 v40, v40, v136
	v_mul_f32_e32 v41, v41, v137
	v_mul_f32_e32 v44, v44, v140
	v_mul_f32_e32 v45, v45, v141
	v_mul_f32_e32 v46, v46, v142
	v_mul_f32_e32 v47, v47, v143
	v_mul_f32_e32 v42, v42, v138
	v_mul_f32_e32 v43, v43, v139
	v_mul_f32_e32 v38, v38, v134
	v_mul_f32_e32 v39, v39, v135
	v_mul_f32_e32 v32, v32, v128
	v_mul_f32_e32 v33, v33, v129
	v_mul_f32_e32 v28, v28, v140
	v_mul_f32_e32 v29, v29, v141
	v_mul_f32_e32 v24, v24, v136
	v_mul_f32_e32 v25, v25, v137
	v_mul_f32_e32 v20, v20, v132
	v_mul_f32_e32 v21, v21, v133
	v_mul_f32_e32 v30, v30, v142
	v_mul_f32_e32 v31, v31, v143
	v_mul_f32_e32 v26, v26, v138
	v_mul_f32_e32 v27, v27, v139
	v_mul_f32_e32 v22, v22, v134
	v_mul_f32_e32 v23, v23, v135
	v_mul_f32_e32 v18, v18, v130
	v_mul_f32_e32 v19, v19, v131
	v_mul_f32_e32 v16, v16, v128
	v_mul_f32_e32 v17, v17, v129
	v_mul_f32_e32 v12, v12, v140
	v_mul_f32_e32 v13, v13, v141
	v_mul_f32_e32 v8, v8, v136
	v_mul_f32_e32 v9, v9, v137
	v_mul_f32_e32 v4, v4, v132
	v_mul_f32_e32 v5, v5, v133
	v_mul_f32_e32 v14, v14, v142
	v_mul_f32_e32 v15, v15, v143
	v_mul_f32_e32 v10, v10, v138
	v_mul_f32_e32 v11, v11, v139
	v_mul_f32_e32 v6, v6, v134
	v_mul_f32_e32 v7, v7, v135
	v_mul_f32_e32 v2, v2, v130
	v_mul_f32_e32 v3, v3, v131
	v_mul_f32_e32 v0, v0, v128
	v_mul_f32_e32 v1, v1, v129
.LBB0_689:
	s_add_i32 s0, s9, 0
	v_add3_u32 v178, s0, v214, v215
	v_mov_b32_e32 v144, 0
	v_xor_b32_e32 v128, 0x80000000, v190
	v_add_u32_e32 v145, v178, v144
	ds_read_b128 v[160:163], v145 offset:6144
	ds_read_b128 v[166:169], v145 offset:6656
	v_add_u32_e32 v144, v213, v144
	ds_read_b128 v[170:173], v144 offset:24576
	v_mov_b32_e32 v164, 0
	v_mov_b32_e32 v129, v128
	v_mov_b32_e32 v130, v128
	v_mov_b32_e32 v131, v128
	v_mov_b32_e32 v132, v128
	v_mov_b32_e32 v133, v128
	v_mov_b32_e32 v134, v128
	v_mov_b32_e32 v135, v128
	v_mov_b32_e32 v136, v128
	v_mov_b32_e32 v137, v128
	v_mov_b32_e32 v138, v128
	v_mov_b32_e32 v139, v128
	v_mov_b32_e32 v140, v128
	v_mov_b32_e32 v141, v128
	v_mov_b32_e32 v142, v128
	v_mov_b32_e32 v143, v128
	v_exp_f32_e32 v116, v116
	v_add_u32_e32 v165, v178, v164
	ds_read_b128 v[174:177], v165 offset:8192
	s_waitcnt lgkmcnt(0)
	v_mfma_f32_32x32x16_bf16 v[144:159], v[160:163], v[170:173], v[128:143]
	ds_read_b128 v[226:229], v165 offset:8704
	v_add_u32_e32 v160, v213, v164
	v_exp_f32_e32 v164, v112
	v_exp_f32_e32 v165, v113
	v_exp_f32_e32 v117, v117
	v_exp_f32_e32 v124, v124
	v_exp_f32_e32 v123, v123
	v_mfma_f32_32x32x16_bf16 v[128:143], v[166:169], v[170:173], v[128:143]
	ds_read_b128 v[230:233], v160 offset:32768
	v_exp_f32_e32 v167, v114
	v_mov_b32_e32 v114, 0
	v_exp_f32_e32 v169, v115
	v_exp_f32_e32 v166, v96
	v_add_u32_e32 v115, v178, v114
	v_exp_f32_e32 v168, v97
	v_exp_f32_e32 v170, v98
	v_exp_f32_e32 v171, v99
	s_waitcnt lgkmcnt(0)
	v_mfma_f32_32x32x16_bf16 v[144:159], v[174:177], v[230:233], v[144:159]
	ds_read_b128 v[96:99], v115 offset:10240
	v_add_u32_e32 v114, v213, v114
	v_exp_f32_e32 v172, v101
	v_exp_f32_e32 v101, v118
	v_exp_f32_e32 v118, v119
	v_cvt_pk_bf16_f32 v160, v164, v165
	v_cvt_pk_bf16_f32 v161, v167, v169
	v_mfma_f32_32x32x16_bf16 v[128:143], v[226:229], v[230:233], v[128:143]
	ds_read_b128 v[174:177], v115 offset:10752
	ds_read_b128 v[226:229], v114 offset:40960
	v_cvt_pk_bf16_f32 v162, v116, v117
	v_cvt_pk_bf16_f32 v163, v101, v118
	v_exp_f32_e32 v119, v102
	v_exp_f32_e32 v173, v103
	v_exp_f32_e32 v102, v120
	s_waitcnt lgkmcnt(0)
	v_mfma_f32_32x32x16_bf16 v[128:143], v[174:177], v[226:229], v[128:143]
	v_exp_f32_e32 v103, v121
	v_exp_f32_e32 v121, v104
	v_exp_f32_e32 v174, v105
	v_exp_f32_e32 v104, v127
	v_exp_f32_e32 v105, v126
	v_exp_f32_e32 v120, v125
	v_exp_f32_e32 v122, v122
	v_mfma_f32_32x32x16_bf16 v[144:159], v[96:99], v[226:229], v[144:159]
	v_add_u32_e32 v96, s0, v220
	v_add_u32_e32 v221, v96, v215
	ds_read_b128 v[96:99], v221 offset:12288
	v_cvt_pk_bf16_f32 v176, v102, v103
	v_cvt_pk_bf16_f32 v179, v105, v104
	v_cvt_pk_bf16_f32 v178, v124, v120
	v_cvt_pk_bf16_f32 v177, v122, v123
	s_waitcnt lgkmcnt(0)
	v_mfma_f32_32x32x16_bf16 v[32:47], v[160:163], v[96:99], v[32:47]
	ds_read_b128 v[226:229], v221 offset:15360
	v_exp_f32_e32 v100, v100
	v_cvt_pk_bf16_f32 v112, v166, v168
	v_cvt_pk_bf16_f32 v113, v170, v171
	v_cvt_pk_bf16_f32 v115, v119, v173
	v_cvt_pk_bf16_f32 v114, v100, v172
	v_exp_f32_e32 v111, v111
	s_waitcnt lgkmcnt(0)
	v_mfma_f32_32x32x16_bf16 v[32:47], v[176:179], v[226:229], v[32:47]
	ds_read_b128 v[226:229], v221 offset:18432
	v_exp_f32_e32 v110, v110
	v_exp_f32_e32 v109, v109
	v_exp_f32_e32 v108, v108
	v_exp_f32_e32 v107, v107
	v_exp_f32_e32 v106, v106
	v_cvt_pk_bf16_f32 v96, v121, v174
	s_waitcnt lgkmcnt(0)
	v_mfma_f32_32x32x16_bf16 v[32:47], v[112:115], v[226:229], v[32:47]
	v_cvt_pk_bf16_f32 v99, v110, v111
	v_cvt_pk_bf16_f32 v98, v108, v109
	v_cvt_pk_bf16_f32 v97, v106, v107
	ds_read_b128 v[226:229], v221 offset:21504
	s_waitcnt lgkmcnt(0)
	v_mfma_f32_32x32x16_bf16 v[32:47], v[96:99], v[226:229], v[32:47]
	ds_read_b128 v[226:229], v221 offset:12800
	s_waitcnt lgkmcnt(0)
	v_mfma_f32_32x32x16_bf16 v[16:31], v[160:163], v[226:229], v[16:31]
	ds_read_b128 v[226:229], v221 offset:15872
	s_waitcnt lgkmcnt(0)
	v_mfma_f32_32x32x16_bf16 v[16:31], v[176:179], v[226:229], v[16:31]
	ds_read_b128 v[226:229], v221 offset:18944
	s_waitcnt lgkmcnt(0)
	v_mfma_f32_32x32x16_bf16 v[16:31], v[112:115], v[226:229], v[16:31]
	ds_read_b128 v[226:229], v221 offset:22016
	s_waitcnt lgkmcnt(0)
	v_mfma_f32_32x32x16_bf16 v[16:31], v[96:99], v[226:229], v[16:31]
	ds_read_b128 v[226:229], v221 offset:13312
	s_waitcnt lgkmcnt(0)
	v_mfma_f32_32x32x16_bf16 v[0:15], v[160:163], v[226:229], v[0:15]
	ds_read_b128 v[160:163], v221 offset:16384
	s_waitcnt lgkmcnt(0)
	v_mfma_f32_32x32x16_bf16 v[0:15], v[176:179], v[160:163], v[0:15]
	ds_read_b128 v[160:163], v221 offset:19456
	s_waitcnt lgkmcnt(0)
	v_mfma_f32_32x32x16_bf16 v[0:15], v[112:115], v[160:163], v[0:15]
	ds_read_b128 v[160:163], v221 offset:22528
	v_maximum3_f32 v112, v144, v128, v128
	v_maximum3_f32 v113, v129, v146, v130
	v_maximum3_f32 v112, v112, v145, v147
	v_maximum3_f32 v113, v113, v148, v132
	v_maximum3_f32 v112, v112, v131, v149
	v_maximum3_f32 v113, v113, v150, v134
	v_maximum3_f32 v112, v112, v133, v151
	v_maximum3_f32 v113, v113, v152, v136
	v_maximum3_f32 v112, v112, v135, v153
	v_maximum3_f32 v113, v113, v154, v138
	v_maximum3_f32 v112, v112, v137, v155
	s_waitcnt lgkmcnt(0)
	v_mfma_f32_32x32x16_bf16 v[0:15], v[96:99], v[160:163], v[0:15]
	v_maximum3_f32 v113, v113, v156, v140
	v_maximum3_f32 v112, v112, v139, v157
	v_maximum3_f32 v113, v113, v158, v142
	v_maximum3_f32 v112, v112, v141, v159
	v_maximum3_f32 v112, v112, v143, v113
	v_mov_b32_e32 v113, v112
	s_nop 1
	v_permlane32_swap_b32_e32 v112, v113
	v_maximum3_f32 v112, v112, v113, v113
	v_cmp_lt_f32_e32 vcc, s46, v112
	s_cbranch_vccz .LBB0_693
	v_max_f32_e32 v96, v112, v112
	v_max_f32_e32 v96, 0, v96
	v_exp_f32_e64 v97, -v96
	s_and_saveexec_b64 s[0:1], s[42:43]
	ds_write_b32 v219, v97
	s_or_b64 exec, exec, s[0:1]
	v_sub_f32_e32 v144, v144, v96
	v_sub_f32_e32 v145, v145, v96
	v_sub_f32_e32 v128, v128, v96
	v_sub_f32_e32 v129, v129, v96
	v_sub_f32_e32 v146, v146, v96
	v_sub_f32_e32 v147, v147, v96
	v_sub_f32_e32 v130, v130, v96
	v_sub_f32_e32 v131, v131, v96
	v_sub_f32_e32 v148, v148, v96
	v_sub_f32_e32 v149, v149, v96
	v_sub_f32_e32 v132, v132, v96
	v_sub_f32_e32 v133, v133, v96
	v_sub_f32_e32 v150, v150, v96
	v_sub_f32_e32 v151, v151, v96
	v_sub_f32_e32 v134, v134, v96
	v_sub_f32_e32 v135, v135, v96
	v_sub_f32_e32 v152, v152, v96
	v_sub_f32_e32 v153, v153, v96
	v_sub_f32_e32 v136, v136, v96
	v_sub_f32_e32 v137, v137, v96
	v_sub_f32_e32 v154, v154, v96
	v_sub_f32_e32 v155, v155, v96
	v_sub_f32_e32 v138, v138, v96
	v_sub_f32_e32 v139, v139, v96
	v_sub_f32_e32 v156, v156, v96
	v_sub_f32_e32 v157, v157, v96
	v_sub_f32_e32 v140, v140, v96
	v_sub_f32_e32 v141, v141, v96
	v_sub_f32_e32 v158, v158, v96
	v_sub_f32_e32 v159, v159, v96
	v_sub_f32_e32 v142, v142, v96
	v_sub_f32_e32 v143, v143, v96
	v_add_f32_e32 v208, v190, v96
	v_add_f32_e32 v209, v191, v97
	v_mul_f32_e32 v96, v190, v96
	v_mul_f32_e32 v97, v191, v97
	s_waitcnt lgkmcnt(0)
	v_add_u32_e32 v125, s5, v194
	v_mov_b32_e32 v209, v97
	ds_read_b128 v[96:99], v125
	ds_read_b128 v[112:115], v125 offset:32
	ds_read_b128 v[160:163], v125 offset:64
	ds_read_b128 v[176:179], v125 offset:96
	s_waitcnt lgkmcnt(0)
	s_waitcnt lgkmcnt(0)
	v_mul_f32_e32 v82, v82, v98
	v_mul_f32_e32 v83, v83, v99
	v_mul_f32_e32 v84, v84, v112
	v_mul_f32_e32 v85, v85, v113
	v_mul_f32_e32 v88, v88, v160
	v_mul_f32_e32 v89, v89, v161
	v_mul_f32_e32 v92, v92, v176
	v_mul_f32_e32 v93, v93, v177
	v_mul_f32_e32 v94, v94, v178
	v_mul_f32_e32 v95, v95, v179
	v_mul_f32_e32 v90, v90, v162
	v_mul_f32_e32 v91, v91, v163
	v_mul_f32_e32 v86, v86, v114
	v_mul_f32_e32 v87, v87, v115
	v_mul_f32_e32 v80, v80, v96
	v_mul_f32_e32 v81, v81, v97
	v_mul_f32_e32 v76, v76, v176
	v_mul_f32_e32 v77, v77, v177
	v_mul_f32_e32 v72, v72, v160
	v_mul_f32_e32 v73, v73, v161
	v_mul_f32_e32 v68, v68, v112
	v_mul_f32_e32 v69, v69, v113
	v_mul_f32_e32 v78, v78, v178
	v_mul_f32_e32 v79, v79, v179
	v_mul_f32_e32 v74, v74, v162
	v_mul_f32_e32 v75, v75, v163
	v_mul_f32_e32 v70, v70, v114
	v_mul_f32_e32 v71, v71, v115
	v_mul_f32_e32 v66, v66, v98
	v_mul_f32_e32 v67, v67, v99
	v_mul_f32_e32 v64, v64, v96
	v_mul_f32_e32 v65, v65, v97
	v_mul_f32_e32 v60, v60, v176
	v_mul_f32_e32 v61, v61, v177
	v_mul_f32_e32 v56, v56, v160
	v_mul_f32_e32 v57, v57, v161
	v_mul_f32_e32 v52, v52, v112
	v_mul_f32_e32 v53, v53, v113
	v_mul_f32_e32 v62, v62, v178
	v_mul_f32_e32 v63, v63, v179
	v_mul_f32_e32 v58, v58, v162
	v_mul_f32_e32 v59, v59, v163
	v_mul_f32_e32 v54, v54, v114
	v_mul_f32_e32 v55, v55, v115
	v_mul_f32_e32 v50, v50, v98
	v_mul_f32_e32 v51, v51, v99
	v_mul_f32_e32 v48, v48, v96
	v_mul_f32_e32 v49, v49, v97
	v_mov_b32_e32 v190, v208
	s_branch .LBB0_694

; #define ATT_SYNC() do { asm volatile("s_waitcnt vmcnt(0)" ::: "memory"); __syncthreads(); } while (0)
; template <int NS, int DQK, int DV, bool KSH  > ...
;     ...
;         for (int t = tlo; t < thi; ++t) {
;             if (t + 2 < thi) ATT_DMA(t + 2, bnn);
;             ATT_MAX(pA0, pA1, 0, t == tlo);
;             ATT_QKEXP(pB0, pB1, NS - 1, bc, pA0, pA1, 0);
;             ATT_PV(0, bc);
;             ATT_MAX(pB0, pB1, NS - 1, t == tlo);
;             ATT_QKEXP(pA0, pA1, 0, bn, pB0, pB1, NS - 1);
;             ATT_PV(NS - 1, bc);
;             ATT_SYNC();
;             const int tmp = bc; bc = bn; bn = bnn; bnn = tmp;
;         }
.LBB0_694:
	v_add_f32_e32 v96, v165, v164
	v_add_f32_e32 v97, v168, v166
	v_add_f32_e32 v96, v97, v96
	v_add_f32_e32 v97, v169, v167
	v_add_f32_e32 v98, v171, v170
	v_add_f32_e32 v96, 0, v96
	v_add_f32_e32 v97, v98, v97
	v_add_f32_e32 v96, v97, v96
	v_add_f32_e32 v97, v117, v116
	v_add_f32_e32 v98, v172, v100
	v_add_f32_e32 v97, v98, v97
	v_add_f32_e32 v96, v97, v96
	v_add_f32_e32 v97, v118, v101
	v_add_f32_e32 v98, v173, v119
	v_mov_b32_e32 v112, 0
	v_add_f32_e32 v97, v98, v97
	v_add_u32_e32 v162, s8, v218
	v_add_f32_e32 v96, v97, v96
	v_add_f32_e32 v97, v103, v102
	v_add_f32_e32 v98, v174, v121
	v_add_u32_e32 v113, v162, v112
	v_add_u32_e32 v112, v213, v112
	v_add_f32_e32 v97, v98, v97
	ds_read_b128 v[234:237], v112
	v_mov_b32_e32 v112, 0
	v_add_f32_e32 v96, v97, v96
	v_add_f32_e32 v97, v107, v106
	v_add_f32_e32 v98, v123, v122
	ds_read_b128 v[226:229], v113
	ds_read_b128 v[230:233], v113 offset:512
	v_add_f32_e32 v97, v97, v98
	v_add_u32_e32 v113, v162, v112
	v_add_u32_e32 v112, v213, v112
	v_add_f32_e32 v96, v97, v96
	v_add_f32_e32 v97, v109, v108
	v_add_f32_e32 v98, v120, v124
	ds_read_b128 v[176:179], v113 offset:2048
	ds_read_b128 v[168:171], v113 offset:2560
	ds_read_b128 v[172:175], v112 offset:8192
	v_exp_f32_e32 v113, v144
	v_exp_f32_e32 v115, v145
	v_exp_f32_e32 v117, v128
	v_exp_f32_e32 v119, v129
	v_exp_f32_e32 v112, v146
	v_exp_f32_e32 v114, v147
	v_exp_f32_e32 v116, v130
	v_exp_f32_e32 v118, v131
	v_add_f32_e32 v97, v97, v98
	v_add_f32_e32 v96, v97, v96
	v_add_f32_e32 v97, v111, v110
	v_add_f32_e32 v98, v104, v105
	v_add_f32_e32 v97, v97, v98
	v_add_f32_e32 v96, v97, v96
	v_add_f32_e32 v120, v114, v112
	v_add_f32_e32 v121, v115, v113
	v_add_f32_e32 v122, v118, v116
	v_add_f32_e32 v123, v119, v117
	v_mov_b32_e32 v144, 0
	v_add_f32_e32 v180, v180, v96
	v_xor_b32_e32 v96, 0x80000000, v181
	v_add_f32_e32 v120, v122, v120
	v_add_f32_e32 v121, v123, v121
	v_exp_f32_e32 v163, v148
	v_add_u32_e32 v128, v162, v144
	v_exp_f32_e32 v149, v149
	v_exp_f32_e32 v162, v132
	v_exp_f32_e32 v148, v133
	v_mov_b32_e32 v97, v96
	v_mov_b32_e32 v98, v96
	v_mov_b32_e32 v99, v96
	v_mov_b32_e32 v100, v96
	v_mov_b32_e32 v101, v96
	v_mov_b32_e32 v102, v96
	v_mov_b32_e32 v103, v96
	v_mov_b32_e32 v104, v96
	v_mov_b32_e32 v105, v96
	v_mov_b32_e32 v106, v96
	v_mov_b32_e32 v107, v96
	v_mov_b32_e32 v108, v96
	v_mov_b32_e32 v109, v96
	v_mov_b32_e32 v110, v96
	v_mov_b32_e32 v111, v96
	v_cvt_pk_bf16_f32 v164, v113, v115
	v_add_f32_e32 v113, 0, v121
	v_cvt_pk_bf16_f32 v160, v117, v119
	v_add_f32_e32 v223, v120, v113
	v_cvt_pk_bf16_f32 v165, v112, v114
	v_cvt_pk_bf16_f32 v161, v116, v118
	s_waitcnt lgkmcnt(0)
	v_mfma_f32_32x32x16_bf16 v[112:127], v[226:229], v[234:237], v[96:111]
	ds_read_b128 v[226:229], v128 offset:4096
	v_add_f32_e64 v132, v148, v162
	v_add_f32_e64 v133, v149, v163
	v_cvt_pk_bf16_f32 v162, v162, v148
	v_add_f32_e32 v133, v132, v133
	v_add_f32_e32 v132, v132, v132
	v_exp_f32_e32 v132, v150
	v_exp_f32_e32 v148, v151
	v_add_u32_e32 v144, v213, v144
	v_mfma_f32_32x32x16_bf16 v[96:111], v[230:233], v[234:237], v[96:111]
	v_exp_f32_e32 v134, v134
	v_exp_f32_e32 v135, v135
	ds_read_b128 v[128:131], v128 offset:4608
	ds_read_b128 v[144:147], v144 offset:16384
	v_cvt_pk_bf16_f32 v166, v163, v149
	v_add_f32_e32 v149, v148, v132
	v_cvt_pk_bf16_f32 v167, v132, v148
	v_exp_f32_e32 v222, v152
	v_exp_f32_e32 v132, v153
	v_exp_f32_e32 v148, v136
	v_exp_f32_e32 v150, v137
	v_mfma_f32_32x32x16_bf16 v[96:111], v[168:171], v[172:175], v[96:111]
	v_exp_f32_e32 v168, v139
	v_exp_f32_e32 v138, v138
	v_exp_f32_e32 v169, v155
	v_exp_f32_e32 v139, v154
	v_add_f32_e32 v151, v135, v134
	v_cvt_pk_bf16_f32 v163, v134, v135
	v_add_f32_e32 v134, v132, v222
	v_add_f32_e32 v135, v133, v223
	v_add_f32_e32 v136, v150, v148
	v_add_f32_e32 v137, v151, v149
	v_add_f32_e32 v154, v168, v138
	v_add_f32_e32 v155, v169, v139
	v_add_f32_e32 v134, v136, v134
	v_add_f32_e32 v135, v137, v135
	v_add_f32_e32 v155, v154, v155
	v_add_f32_e32 v154, v154, v154
	v_add_f32_e32 v152, v134, v134
	v_add_f32_e32 v153, v134, v135
	v_exp_f32_e32 v135, v141
	v_exp_f32_e32 v136, v140
	v_exp_f32_e32 v149, v157
	v_exp_f32_e32 v154, v156
	v_cvt_pk_bf16_f32 v134, v222, v132
	v_exp_f32_e32 v132, v142
	v_exp_f32_e32 v142, v143
	v_exp_f32_e32 v152, v158
	v_exp_f32_e32 v158, v159
	v_add_f32_e32 v143, v135, v136
	v_add_f32_e32 v133, v149, v154
	v_mov_b32_e32 v159, v155
	v_cvt_pk_bf16_f32 v151, v132, v142
	v_add_f32_e32 v132, v142, v132
	v_add_f32_e32 v133, v143, v133
	v_add_f32_e32 v140, v158, v152
	v_add_f32_e32 v141, v159, v153
	v_cvt_pk_bf16_f32 v148, v148, v150
	v_add_f32_e32 v132, v132, v140
	v_add_f32_e32 v133, v133, v141
	v_cvt_pk_bf16_f32 v150, v136, v135
	v_cvt_pk_bf16_f32 v136, v154, v149
	v_cvt_pk_bf16_f32 v149, v138, v168
	v_cvt_pk_bf16_f32 v135, v139, v169
	s_waitcnt lgkmcnt(0)
	v_mfma_f32_32x32x16_bf16 v[96:111], v[128:131], v[144:147], v[96:111]
	ds_read_b128 v[138:141], v221 offset:12288
	v_cvt_pk_bf16_f32 v137, v152, v158
	ds_read_b128 v[152:155], v221 offset:15360
	v_pk_add_f32 v[132:133], v[132:133], v[132:133] op_sel:[0,1] op_sel_hi:[1,0]
	s_add_i32 s7, s7, 1
	v_add_f32_e32 v132, v209, v132
	v_add_f32_e32 v133, v208, v133
	s_cmpk_eq_i32 s7, 0x84
	s_waitcnt lgkmcnt(0)
	v_mfma_f32_32x32x16_bf16 v[80:95], v[164:167], v[138:141], v[80:95]
	ds_read_b128 v[138:141], v221 offset:18432
	v_mfma_f32_32x32x16_bf16 v[80:95], v[134:137], v[152:155], v[80:95]
	ds_read_b128 v[152:155], v221 offset:21504
	s_waitcnt lgkmcnt(0)
	v_mfma_f32_32x32x16_bf16 v[80:95], v[160:163], v[138:141], v[80:95]
	ds_read_b128 v[138:141], v221 offset:12800
	v_mfma_f32_32x32x16_bf16 v[80:95], v[148:151], v[152:155], v[80:95]
	ds_read_b128 v[152:155], v221 offset:15872
	s_waitcnt lgkmcnt(0)
	v_mfma_f32_32x32x16_bf16 v[64:79], v[164:167], v[138:141], v[64:79]
	ds_read_b128 v[138:141], v221 offset:18944
	v_mfma_f32_32x32x16_bf16 v[64:79], v[134:137], v[152:155], v[64:79]
	ds_read_b128 v[152:155], v221 offset:22016
	s_waitcnt lgkmcnt(0)
	v_mfma_f32_32x32x16_bf16 v[64:79], v[160:163], v[138:141], v[64:79]
	ds_read_b128 v[138:141], v221 offset:13312
	v_mfma_f32_32x32x16_bf16 v[64:79], v[148:151], v[152:155], v[64:79]
	ds_read_b128 v[152:155], v221 offset:16384
	s_waitcnt lgkmcnt(0)
	v_mfma_f32_32x32x16_bf16 v[48:63], v[164:167], v[138:141], v[48:63]
	ds_read_b128 v[138:141], v221 offset:19456
	v_mfma_f32_32x32x16_bf16 v[48:63], v[134:137], v[152:155], v[48:63]
	ds_read_b128 v[134:137], v221 offset:22528
	s_waitcnt vmcnt(0)
	s_waitcnt vmcnt(0) lgkmcnt(0)
	s_barrier
	v_mfma_f32_32x32x16_bf16 v[48:63], v[160:163], v[138:141], v[48:63]
	v_mfma_f32_32x32x16_bf16 v[48:63], v[148:151], v[134:137], v[48:63]
	v_mfma_f32_32x32x16_bf16 v[112:127], v[176:179], v[172:175], v[112:127]
	v_mfma_f32_32x32x16_bf16 v[112:127], v[226:229], v[144:147], v[112:127]
	s_cbranch_scc1 .LBB0_699
	s_mov_b32 s0, s8
	s_mov_b32 s8, s6
	s_mov_b32 s6, s9
	v_mov_b32_e32 v191, v132
	s_cmpk_gt_u32 s7, 0x81
	s_mov_b32 s9, s0
	s_cbranch_scc0 .LBB0_680
	s_branch .LBB0_685

.LBB0_719:
	s_nop 6
	v_maximum3_f32 v32, v16, v0, v0
	v_maximum3_f32 v33, v1, v18, v2
	v_maximum3_f32 v32, v32, v17, v19
	v_maximum3_f32 v33, v33, v20, v4
	v_maximum3_f32 v32, v32, v3, v21
	v_maximum3_f32 v33, v33, v22, v6
	v_maximum3_f32 v32, v32, v5, v23
	v_maximum3_f32 v33, v33, v24, v8
	v_maximum3_f32 v32, v32, v7, v25
	v_maximum3_f32 v33, v33, v26, v10
	v_maximum3_f32 v32, v32, v9, v27
	v_maximum3_f32 v33, v33, v28, v12
	v_maximum3_f32 v32, v32, v11, v29
	v_maximum3_f32 v33, v33, v30, v14
	v_maximum3_f32 v32, v32, v13, v31
	v_maximum3_f32 v32, v32, v15, v33
	v_mov_b32_e32 v33, v32
	s_nop 1
	v_permlane32_swap_b32_e32 v32, v33
	v_maximum3_f32 v76, v32, v33, v33
	v_sub_f32_e32 v33, v2, v76
	v_mov_b32_e32 v2, v195
	v_sub_f32_e32 v16, v16, v76
	v_add_u32_e32 v2, v170, v2
	ds_read_b128 v[88:91], v2 offset:16384
	ds_read_b128 v[84:87], v2 offset:16896
	v_mov_b32_e32 v2, v195
	v_sub_f32_e32 v0, v0, v76
	v_sub_f32_e32 v17, v17, v76
	v_sub_f32_e32 v1, v1, v76
	v_sub_f32_e32 v18, v18, v76
	v_sub_f32_e32 v19, v19, v76
	v_sub_f32_e32 v34, v3, v76
	v_add_u32_e32 v2, v170, v2
	v_sub_f32_e32 v35, v4, v76
	v_sub_f32_e32 v36, v5, v76
	v_sub_f32_e32 v37, v6, v76
	v_sub_f32_e32 v38, v7, v76
	v_sub_f32_e32 v39, v8, v76
	v_sub_f32_e32 v40, v9, v76
	ds_read_b128 v[80:83], v2 offset:18432
	ds_read_b128 v[56:59], v2 offset:18944
	v_exp_f32_e32 v3, v16
	v_exp_f32_e32 v5, v17
	v_exp_f32_e32 v7, v0
	v_exp_f32_e32 v9, v1
	v_exp_f32_e32 v2, v18
	v_exp_f32_e32 v4, v19
	v_exp_f32_e32 v6, v33
	v_exp_f32_e32 v8, v34
	v_sub_f32_e32 v41, v10, v76
	v_sub_f32_e32 v42, v11, v76
	v_sub_f32_e32 v43, v12, v76
	v_sub_f32_e32 v44, v13, v76
	v_add_f32_e32 v10, v4, v2
	v_add_f32_e32 v11, v5, v3
	v_add_f32_e32 v12, v8, v6
	v_add_f32_e32 v13, v9, v7
	v_sub_f32_e32 v20, v20, v76
	v_sub_f32_e32 v21, v21, v76
	v_add_f32_e32 v10, v12, v10
	v_add_f32_e32 v11, v13, v11
	v_cvt_pk_bf16_f32 v32, v7, v9
	v_add_f32_e32 v1, 0, v11
	v_cvt_pk_bf16_f32 v33, v6, v8
	v_exp_f32_e32 v7, v20
	v_exp_f32_e32 v9, v21
	v_exp_f32_e32 v6, v35
	v_exp_f32_e32 v8, v36
	v_cvt_pk_bf16_f32 v0, v3, v5
	v_add_f32_e32 v5, v10, v1
	v_cvt_pk_bf16_f32 v1, v2, v4
	v_mov_b32_e32 v2, v195
	v_sub_f32_e32 v22, v22, v76
	v_add_u32_e32 v2, v170, v2
	v_sub_f32_e32 v23, v23, v76
	ds_read_b128 v[92:95], v2 offset:20480
	ds_read_b128 v[48:51], v2 offset:20992
	v_add_f32_e32 v2, v8, v6
	v_add_f32_e32 v3, v9, v7
	v_exp_f32_e32 v4, v23
	v_add_f32_e32 v10, v2, v2
	v_add_f32_e32 v11, v2, v3
	v_exp_f32_e32 v3, v22
	v_cvt_pk_bf16_f32 v34, v6, v8
	v_exp_f32_e32 v6, v37
	v_exp_f32_e32 v8, v38
	v_cvt_pk_bf16_f32 v2, v7, v9
	v_add_f32_e32 v7, v4, v3
	v_cvt_pk_bf16_f32 v3, v3, v4
	v_mov_b32_e32 v4, v195
	v_sub_f32_e32 v24, v24, v76
	v_sub_f32_e32 v25, v25, v76
	v_add_u32_e32 v4, v170, v4
	v_add_f32_e32 v9, v8, v6
	v_cvt_pk_bf16_f32 v35, v6, v8
	ds_read_b128 v[60:63], v4 offset:22528
	ds_read_b128 v[52:55], v4 offset:23040
	v_exp_f32_e32 v4, v24
	v_exp_f32_e32 v10, v25
	v_exp_f32_e32 v6, v39
	v_exp_f32_e32 v8, v40
	v_sub_f32_e32 v26, v26, v76
	v_sub_f32_e32 v27, v27, v76
	v_sub_f32_e32 v45, v14, v76
	v_sub_f32_e32 v46, v15, v76
	v_add_f32_e32 v12, v10, v4
	v_add_f32_e32 v13, v11, v5
	v_add_f32_e32 v14, v8, v6
	v_add_f32_e32 v15, v9, v7
	v_cvt_pk_bf16_f32 v36, v4, v10
	v_cvt_pk_bf16_f32 v40, v6, v8
	v_exp_f32_e32 v5, v26
	v_exp_f32_e32 v7, v27
	v_exp_f32_e32 v4, v41
	v_exp_f32_e32 v6, v42
	v_add_f32_e32 v12, v14, v12
	v_add_f32_e32 v13, v15, v13
	v_cvt_pk_bf16_f32 v37, v5, v7
	v_sub_f32_e32 v28, v28, v76
	v_add_f32_e32 v8, v6, v4
	v_add_f32_e32 v9, v7, v5
	v_cvt_pk_bf16_f32 v41, v4, v6
	ds_read_b128 v[4:7], v170 offset:8192
	v_sub_f32_e32 v29, v29, v76
	v_sub_f32_e32 v30, v30, v76
	v_sub_f32_e32 v31, v31, v76
	v_add_f32_e32 v68, v12, v12
	v_add_f32_e32 v69, v12, v13
	v_add_f32_e32 v70, v8, v8
	v_add_f32_e32 v71, v8, v9
	v_exp_f32_e32 v8, v28
	v_exp_f32_e32 v9, v29
	v_exp_f32_e32 v10, v43
	v_exp_f32_e32 v11, v44
	v_exp_f32_e32 v68, v30
	v_exp_f32_e32 v70, v31
	s_waitcnt lgkmcnt(0)
	v_mfma_f32_32x32x16_bf16 v[16:31], v[0:3], v[4:7], 0
	v_add_f32_e32 v73, v9, v8
	v_add_f32_e32 v75, v11, v10
	v_cvt_pk_bf16_f32 v38, v8, v9
	v_cvt_pk_bf16_f32 v42, v10, v11
	v_cvt_pk_bf16_f32 v39, v68, v70
	ds_read_b128 v[8:11], v170 offset:10240
	v_exp_f32_e32 v72, v45
	s_waitcnt lgkmcnt(0)
	v_mfma_f32_32x32x16_bf16 v[16:31], v[36:39], v[8:11], v[16:31]
	ds_read_b128 v[4:7], v170 offset:12288
	v_exp_f32_e32 v74, v46
	s_or_b32 s9, s22, 0xc0
	s_and_b64 vcc, exec, s[34:35]
	v_cvt_pk_bf16_f32 v43, v72, v74
	s_waitcnt lgkmcnt(0)
	v_mfma_f32_32x32x16_bf16 v[16:31], v[32:35], v[4:7], v[16:31]
	ds_read_b128 v[8:11], v170 offset:14336
	s_waitcnt lgkmcnt(0)
	v_mfma_f32_32x32x16_bf16 v[16:31], v[40:43], v[8:11], v[16:31]
	ds_read_b128 v[4:7], v170 offset:8704
	s_waitcnt lgkmcnt(0)
	v_mfma_f32_32x32x16_bf16 v[0:15], v[0:3], v[4:7], 0
	ds_read_b128 v[44:47], v170 offset:10752
	s_waitcnt lgkmcnt(0)
	v_mfma_f32_32x32x16_bf16 v[0:15], v[36:39], v[44:47], v[0:15]
	ds_read_b128 v[64:67], v170 offset:12800
	s_waitcnt lgkmcnt(0)
	v_mfma_f32_32x32x16_bf16 v[0:15], v[32:35], v[64:67], v[0:15]
	v_add_f32_e64 v32, v70, v68
	v_add_f32_e64 v33, v71, v69
	v_add_f32_e64 v34, v74, v72
	v_add_f32_e64 v35, v75, v73
	ds_read_b128 v[36:39], v170 offset:14848
	v_add_f32_e32 v32, v34, v32
	v_add_f32_e32 v33, v35, v33
	s_waitcnt vmcnt(0)
	s_waitcnt vmcnt(0) lgkmcnt(0)
	v_pk_add_f32 v[32:33], v[32:33], v[32:33] op_sel:[0,1] op_sel_hi:[1,0]
	v_mfma_f32_32x32x16_bf16 v[0:15], v[40:43], v[36:39], v[0:15]
	v_mov_b32_e32 v33, v76
	v_add_f32_e64 v164, v32, 0
	v_add_f32_e64 v165, v33, 0
	s_barrier
	v_xor_b32_e32 v32, 0x80000000, v165
	v_mov_b32_e32 v33, v32
	v_mov_b32_e32 v34, v32
	v_mov_b32_e32 v35, v32
	v_mov_b32_e32 v36, v32
	v_mov_b32_e32 v37, v32
	v_mov_b32_e32 v38, v32
	v_mov_b32_e32 v39, v32
	v_mov_b32_e32 v40, v32
	v_mov_b32_e32 v41, v32
	v_mov_b32_e32 v42, v32
	v_mov_b32_e32 v43, v32
	v_mov_b32_e32 v44, v32
	v_mov_b32_e32 v45, v32
	v_mov_b32_e32 v46, v32
	v_mov_b32_e32 v47, v32
	v_mov_b64_e32 v[110:111], v[46:47]
	v_mov_b64_e32 v[108:109], v[44:45]
	v_mfma_f32_32x32x16_bf16 v[64:79], v[88:91], v[152:155], v[32:47]
	v_mov_b64_e32 v[106:107], v[42:43]
	v_mov_b64_e32 v[104:105], v[40:41]
	v_mov_b64_e32 v[102:103], v[38:39]
	v_mov_b64_e32 v[100:101], v[36:37]
	v_mov_b64_e32 v[98:99], v[34:35]
	v_mov_b64_e32 v[96:97], v[32:33]
	v_mfma_f32_32x32x16_bf16 v[64:79], v[80:83], v[144:147], v[64:79]
	v_mfma_f32_32x32x16_bf16 v[64:79], v[92:95], v[148:151], v[64:79]
	v_mfma_f32_32x32x16_bf16 v[96:111], v[84:87], v[152:155], v[96:111]
	v_mfma_f32_32x32x16_bf16 v[96:111], v[56:59], v[144:147], v[96:111]
	v_mfma_f32_32x32x16_bf16 v[96:111], v[48:51], v[148:151], v[96:111]
	v_mfma_f32_32x32x16_bf16 v[64:79], v[60:63], v[156:159], v[64:79]
	v_mfma_f32_32x32x16_bf16 v[96:111], v[52:55], v[156:159], v[96:111]
	s_cbranch_vccnz .LBB0_721
	v_or_b32_e32 v33, s9, v115
	v_lshl_add_u32 v194, v33, 6, s72
	v_lshl_add_u64 v[34:35], v[194:195], 1, s[42:43]
	s_mov_b32 m0, s8
	s_nop 0
	global_load_lds_dwordx4 v[34:35], off

.LBB0_723:
	s_nop 8
	v_maximum3_f32 v33, v64, v96, v96
	v_maximum3_f32 v34, v97, v66, v98
	v_maximum3_f32 v33, v33, v65, v67
	v_maximum3_f32 v34, v34, v68, v100
	v_maximum3_f32 v33, v33, v99, v69
	v_maximum3_f32 v34, v34, v70, v102
	v_maximum3_f32 v33, v33, v101, v71
	v_maximum3_f32 v34, v34, v72, v104
	v_maximum3_f32 v33, v33, v103, v73
	v_maximum3_f32 v34, v34, v74, v106
	v_maximum3_f32 v33, v33, v105, v75
	v_maximum3_f32 v34, v34, v76, v108
	v_maximum3_f32 v33, v33, v107, v77
	v_maximum3_f32 v34, v34, v78, v110
	v_maximum3_f32 v33, v33, v109, v79
	v_maximum3_f32 v33, v33, v111, v34
	v_mov_b32_e32 v34, v33
	s_nop 1
	v_permlane32_swap_b32_e32 v33, v34
	v_and_b32_e32 v163, 63, v166
	v_maximum3_f32 v33, v33, v34, v34
	v_cmp_gt_u32_e64 s[38:39], 32, v163
	v_lshl_add_u32 v171, v167, 2, s73
	v_cmp_lt_f32_e32 vcc, s46, v33
	s_cbranch_vccz .LBB0_727
	v_max_f32_e32 v32, v33, v33
	v_max_f32_e32 v35, 0, v32
	v_exp_f32_e64 v34, -v35
	s_and_saveexec_b64 s[0:1], s[38:39]
	ds_write_b32 v171, v34 offset:49152
	s_or_b64 exec, exec, s[0:1]
	v_mov_b32_e32 v36, v35
	s_waitcnt lgkmcnt(0)
	v_add_u32_e32 v46, s73, v160
	v_add_f32_e32 v32, v164, v34
	v_add_f32_e32 v33, v165, v35
	v_sub_f32_e32 v64, v64, v36
	v_sub_f32_e32 v65, v65, v36
	v_sub_f32_e32 v96, v96, v36
	v_sub_f32_e32 v97, v97, v36
	v_sub_f32_e32 v66, v66, v36
	v_sub_f32_e32 v67, v67, v36
	v_sub_f32_e32 v98, v98, v36
	v_sub_f32_e32 v99, v99, v36
	v_sub_f32_e32 v68, v68, v36
	v_sub_f32_e32 v69, v69, v36
	v_sub_f32_e32 v100, v100, v36
	v_sub_f32_e32 v101, v101, v36
	v_sub_f32_e32 v70, v70, v36
	v_sub_f32_e32 v71, v71, v36
	v_sub_f32_e32 v102, v102, v36
	v_sub_f32_e32 v103, v103, v36
	v_sub_f32_e32 v72, v72, v36
	v_sub_f32_e32 v73, v73, v36
	v_sub_f32_e32 v104, v104, v36
	v_sub_f32_e32 v105, v105, v36
	v_sub_f32_e32 v74, v74, v36
	v_sub_f32_e32 v75, v75, v36
	v_sub_f32_e32 v106, v106, v36
	v_sub_f32_e32 v107, v107, v36
	v_sub_f32_e32 v76, v76, v36
	v_sub_f32_e32 v77, v77, v36
	v_sub_f32_e32 v108, v108, v36
	v_sub_f32_e32 v109, v109, v36
	v_sub_f32_e32 v78, v78, v36
	v_sub_f32_e32 v79, v79, v36
	v_sub_f32_e32 v110, v110, v36
	v_sub_f32_e32 v111, v111, v36
	v_mul_f32_e32 v164, v164, v34
	v_mul_f32_e32 v165, v165, v35
	ds_read_b128 v[34:37], v46 offset:49152
	ds_read_b128 v[38:41], v46 offset:49184
	ds_read_b128 v[42:45], v46 offset:49216
	ds_read_b128 v[46:49], v46 offset:49248
	s_waitcnt lgkmcnt(0)
	v_xor_b32_e32 v32, 0x80000000, v33
	s_waitcnt lgkmcnt(0)
	v_mul_f32_e32 v20, v20, v38
	v_mul_f32_e32 v21, v21, v39
	v_mul_f32_e32 v24, v24, v42
	v_mul_f32_e32 v25, v25, v43
	v_mul_f32_e32 v28, v28, v46
	v_mul_f32_e32 v29, v29, v47
	v_mul_f32_e32 v30, v30, v48
	v_mul_f32_e32 v31, v31, v49
	v_mul_f32_e32 v26, v26, v44
	v_mul_f32_e32 v27, v27, v45
	v_mul_f32_e32 v22, v22, v40
	v_mul_f32_e32 v23, v23, v41
	v_mul_f32_e32 v18, v18, v36
	v_mul_f32_e32 v19, v19, v37
	v_mul_f32_e32 v16, v16, v34
	v_mul_f32_e32 v17, v17, v35
	v_mul_f32_e32 v12, v12, v46
	v_mul_f32_e32 v13, v13, v47
	v_mul_f32_e32 v8, v8, v42
	v_mul_f32_e32 v9, v9, v43
	v_mul_f32_e32 v4, v4, v38
	v_mul_f32_e32 v5, v5, v39
	v_mul_f32_e32 v14, v14, v48
	v_mul_f32_e32 v15, v15, v49
	v_mul_f32_e32 v10, v10, v44
	v_mul_f32_e32 v11, v11, v45
	v_mul_f32_e32 v6, v6, v40
	v_mul_f32_e32 v7, v7, v41
	v_mul_f32_e32 v2, v2, v36
	v_mul_f32_e32 v3, v3, v37
	v_mul_f32_e32 v0, v0, v34
	v_mul_f32_e32 v1, v1, v35
	v_mov_b32_e32 v165, v33
; #define ATT_SYNC() do { asm volatile("s_waitcnt vmcnt(0)" ::: "memory"); __syncthreads(); } while (0)
; template <int NS, int DQK, int DV, bool KSH  > ...
;     ...
;     if constexpr (NS == 1) {
;         for (int t = tlo; t < thi; t += 2) {
;             if (t + 2 < thi) ATT_DMA(t + 2, bnn);
;             ATT_MAX(pA0, pA1, 0, t == tlo);
;             ATT_QKEXP(pB0, pB1, 0, bn, pA0, pA1, 0);
;             ATT_PV(0, bc);
;             ATT_SYNC();
;             if (t + 3 < thi) ATT_DMA(t + 3, bc);
.LBB0_727:
	v_mov_b32_e32 v48, v195
	v_mov_b32_e32 v33, v32
	v_add_u32_e32 v48, v170, v48
	ds_read_b128 v[80:83], v48 offset:32768
	ds_read_b128 v[116:119], v48 offset:33280
	v_mov_b32_e32 v48, v195
	v_mov_b32_e32 v34, v32
	v_mov_b32_e32 v35, v32
	v_mov_b32_e32 v36, v32
	v_mov_b32_e32 v37, v32
	v_mov_b32_e32 v38, v32
	v_mov_b32_e32 v39, v32
	v_mov_b32_e32 v40, v32
	v_mov_b32_e32 v41, v32
	v_mov_b32_e32 v42, v32
	v_mov_b32_e32 v43, v32
	v_mov_b32_e32 v44, v32
	v_mov_b32_e32 v45, v32
	v_mov_b32_e32 v46, v32
	v_mov_b32_e32 v47, v32
	v_add_u32_e32 v48, v170, v48
	ds_read_b128 v[120:123], v48 offset:34816
	ds_read_b128 v[124:127], v48 offset:35328
	s_waitcnt lgkmcnt(0)
	v_mfma_f32_32x32x16_bf16 v[48:63], v[80:83], v[152:155], v[32:47]
	v_mov_b64_e32 v[94:95], v[46:47]
	v_mov_b64_e32 v[92:93], v[44:45]
	v_mov_b64_e32 v[90:91], v[42:43]
	v_mov_b64_e32 v[88:89], v[40:41]
	v_mov_b64_e32 v[86:87], v[38:39]
	v_mov_b64_e32 v[84:85], v[36:37]
	v_mov_b64_e32 v[82:83], v[34:35]
	v_mov_b64_e32 v[80:81], v[32:33]
	v_exp_f32_e32 v37, v64
	v_exp_f32_e32 v41, v65
	v_exp_f32_e32 v43, v96
	v_exp_f32_e32 v45, v97
	v_exp_f32_e32 v36, v66
	v_exp_f32_e32 v40, v67
	v_exp_f32_e32 v42, v98
	v_exp_f32_e32 v44, v99
	v_cvt_pk_bf16_f32 v38, v37, v41
	v_add_f32_e32 v46, v40, v36
	v_add_f32_e32 v47, v41, v37
	v_cvt_pk_bf16_f32 v39, v36, v40
	v_add_f32_e32 v64, v44, v42
	v_add_f32_e32 v65, v45, v43
	v_exp_f32_e32 v37, v68
	v_add_f32_e32 v46, v64, v46
	v_add_f32_e32 v47, v65, v47
	v_exp_f32_e32 v69, v69
	v_add_f32_e32 v33, 0, v47
	v_exp_f32_e32 v36, v100
	v_exp_f32_e32 v68, v101
	v_cvt_pk_bf16_f32 v34, v43, v45
	v_add_f32_e32 v43, v46, v33
	v_mov_b32_e32 v33, v195
	v_cvt_pk_bf16_f32 v35, v42, v44
	v_add_u32_e32 v33, v170, v33
	ds_read_b128 v[44:47], v33 offset:36864
	v_mfma_f32_32x32x16_bf16 v[80:95], v[116:119], v[152:155], v[80:95]
	v_add_f32_e64 v40, v68, v36
	v_add_f32_e64 v41, v69, v37
	ds_read_b128 v[64:67], v33 offset:37376
	v_add_f32_e64 v116, v40, v40
	v_add_f32_e64 v117, v40, v41
	v_cvt_pk_bf16_f32 v40, v37, v69
	v_exp_f32_e32 v33, v70
	v_exp_f32_e32 v37, v71
	v_cvt_pk_bf16_f32 v36, v36, v68
	v_mfma_f32_32x32x16_bf16 v[48:63], v[120:123], v[144:147], v[48:63]
	v_exp_f32_e32 v42, v102
	v_add_f32_e32 v69, v37, v33
	v_cvt_pk_bf16_f32 v41, v33, v37
	v_mov_b32_e32 v33, v195
	v_exp_f32_e32 v68, v103
	v_exp_f32_e32 v116, v73
	v_add_u32_e32 v33, v170, v33
	ds_read_b128 v[96:99], v33 offset:38912
	v_mfma_f32_32x32x16_bf16 v[80:95], v[124:127], v[144:147], v[80:95]
	v_add_f32_e32 v71, v68, v42
	v_cvt_pk_bf16_f32 v37, v42, v68
	v_exp_f32_e32 v42, v72
	v_exp_f32_e32 v68, v104
	v_exp_f32_e32 v70, v105
	ds_read_b128 v[100:103], v33 offset:39424
	v_exp_f32_e32 v33, v76
	s_waitcnt lgkmcnt(0)
	v_mfma_f32_32x32x16_bf16 v[48:63], v[44:47], v[148:151], v[48:63]
	v_add_f32_e64 v44, v116, v42
	v_add_f32_e64 v45, v117, v43
	v_add_f32_e64 v46, v70, v68
	v_add_f32_e64 v47, v71, v69
	v_exp_f32_e32 v72, v111
	v_add_f32_e32 v44, v46, v44
	v_add_f32_e32 v45, v47, v45
	s_lshl_b32 s0, s58, 8
	v_add_f32_e32 v46, v44, v44
	v_add_f32_e32 v47, v44, v45
	v_exp_f32_e32 v45, v74
	v_mfma_f32_32x32x16_bf16 v[80:95], v[64:67], v[148:151], v[80:95]
	v_exp_f32_e32 v67, v75
	v_exp_f32_e32 v44, v106
	v_exp_f32_e32 v66, v107
	v_cvt_pk_bf16_f32 v64, v42, v116
	v_cvt_pk_bf16_f32 v42, v68, v70
	v_cvt_pk_bf16_f32 v65, v45, v67
	v_add_f32_e32 v68, v66, v44
	v_add_f32_e32 v69, v67, v45
	v_cvt_pk_bf16_f32 v43, v44, v66
	ds_read_b128 v[104:107], v170 offset:24576
	v_exp_f32_e32 v44, v77
	v_exp_f32_e32 v45, v108
	v_exp_f32_e32 v46, v109
	v_add_f32_e32 v69, v68, v69
	v_add_f32_e32 v68, v68, v68
	v_add_f32_e32 v71, v44, v33
	v_cvt_pk_bf16_f32 v66, v33, v44
	v_add_f32_e32 v73, v46, v45
	v_cvt_pk_bf16_f32 v44, v45, v46
	v_exp_f32_e32 v46, v78
	v_exp_f32_e32 v68, v79
	v_mfma_f32_32x32x16_bf16 v[48:63], v[96:99], v[156:159], v[48:63]
	ds_read_b128 v[74:77], v170 offset:26624
	ds_read_b128 v[96:99], v170 offset:28672
	v_cvt_pk_bf16_f32 v67, v46, v68
	v_exp_f32_e32 v70, v110
	s_or_b32 s10, s0, 0x6000
	s_or_b32 s11, s0, 0x60c0
	s_mov_b32 s12, 0
	s_waitcnt lgkmcnt(0)
	v_mfma_f32_32x32x16_bf16 v[16:31], v[38:41], v[104:107], v[16:31]
	v_cvt_pk_bf16_f32 v45, v70, v72
	s_add_i32 s13, s74, 0
	s_mov_b32 s14, 2
	s_movk_i32 s15, 0x4000
	s_mov_b32 s0, 0x8000
	s_mov_b32 s16, 0
	v_mfma_f32_32x32x16_bf16 v[16:31], v[64:67], v[74:77], v[16:31]
	ds_read_b128 v[74:77], v170 offset:30720
	v_mfma_f32_32x32x16_bf16 v[16:31], v[34:37], v[96:99], v[16:31]
	ds_read_b128 v[96:99], v170 offset:25088
	s_waitcnt lgkmcnt(0)
	v_mfma_f32_32x32x16_bf16 v[16:31], v[42:45], v[74:77], v[16:31]
	ds_read_b128 v[74:77], v170 offset:27136
	v_mfma_f32_32x32x16_bf16 v[0:15], v[38:41], v[96:99], v[0:15]
	s_waitcnt lgkmcnt(0)
	v_mfma_f32_32x32x16_bf16 v[0:15], v[64:67], v[74:77], v[0:15]
	ds_read_b128 v[64:67], v170 offset:31232
	v_mfma_f32_32x32x16_bf16 v[80:95], v[100:103], v[156:159], v[80:95]
	ds_read_b128 v[38:41], v170 offset:29184
	s_waitcnt vmcnt(0)
	s_waitcnt vmcnt(0) lgkmcnt(0)
	s_barrier
	v_mfma_f32_32x32x16_bf16 v[0:15], v[34:37], v[38:41], v[0:15]
	v_add_f32_e64 v34, v68, v46
	v_add_f32_e64 v35, v69, v47
	v_add_f32_e64 v36, v72, v70
	v_add_f32_e64 v37, v73, v71
	v_mov_b32_e32 v38, v32
	v_add_f32_e32 v34, v36, v34
	v_add_f32_e32 v35, v37, v35
	v_mov_b32_e32 v36, v32
	v_add_f32_e32 v33, v34, v35
	v_add_f32_e32 v172, v164, v33
	v_mfma_f32_32x32x16_bf16 v[0:15], v[42:45], v[64:67], v[0:15]
	v_add3_u32 v164, v114, v113, v112
	v_mov_b32_e32 v33, v32
	v_mov_b32_e32 v34, v32
	v_mov_b32_e32 v35, v32
	v_mov_b32_e32 v37, v32
	v_mov_b32_e32 v39, v32
	v_mov_b32_e32 v40, v32
	v_mov_b32_e32 v41, v32
	v_mov_b32_e32 v42, v32
	v_mov_b32_e32 v43, v32
	v_mov_b32_e32 v44, v32
	v_mov_b32_e32 v45, v32
	v_mov_b32_e32 v46, v32
	v_mov_b32_e32 v64, v32

.LBB0_733:
	v_maximum3_f32 v47, v48, v80, v80
	v_maximum3_f32 v65, v81, v50, v82
	v_maximum3_f32 v47, v47, v49, v51
	v_maximum3_f32 v65, v65, v52, v84
	v_maximum3_f32 v47, v47, v83, v53
	v_maximum3_f32 v65, v65, v54, v86
	v_maximum3_f32 v47, v47, v85, v55
	v_maximum3_f32 v65, v65, v56, v88
	v_maximum3_f32 v47, v47, v87, v57
	v_maximum3_f32 v65, v65, v58, v90
	v_maximum3_f32 v47, v47, v89, v59
	v_maximum3_f32 v65, v65, v60, v92
	v_maximum3_f32 v47, v47, v91, v61
	v_maximum3_f32 v65, v65, v62, v94
	v_maximum3_f32 v47, v47, v93, v63
	v_maximum3_f32 v47, v47, v95, v65
	v_mov_b32_e32 v65, v47
	s_nop 1
	v_permlane32_swap_b32_e32 v47, v65
	v_maximum3_f32 v47, v47, v65, v65
	v_cmp_lt_f32_e32 vcc, s46, v47
	s_cbranch_vccz .LBB0_737
	v_max_f32_e32 v32, v47, v47
	v_max_f32_e32 v32, 0, v32
	v_exp_f32_e64 v33, -v32
	s_and_saveexec_b64 s[6:7], s[38:39]
	ds_write_b32 v171, v33 offset:49152
	s_or_b64 exec, exec, s[6:7]
	s_waitcnt lgkmcnt(0)
	v_add_u32_e32 v46, s73, v160
	ds_read_b128 v[34:37], v46 offset:49216
	ds_read_b128 v[38:41], v46 offset:49248
	ds_read_b128 v[42:45], v46 offset:49152
	ds_read_b128 v[66:69], v46 offset:49184
	v_add_f32_e32 v165, v165, v32
	v_xor_b32_e32 v64, 0x80000000, v165
	s_waitcnt lgkmcnt(0)
	v_mov_b32_e32 v78, v64
	v_mov_b32_e32 v79, v64
	s_waitcnt lgkmcnt(0)
	v_mul_f32_e32 v4, v4, v66
	v_mul_f32_e32 v5, v5, v67
	v_mul_f32_e32 v20, v20, v66
	v_mul_f32_e32 v21, v21, v67
	v_mul_f32_e32 v6, v6, v68
	v_mul_f32_e32 v7, v7, v69
	v_mul_f32_e32 v22, v22, v68
	v_mul_f32_e32 v23, v23, v69
	v_mov_b32_e32 v65, v64
	v_mov_b32_e32 v66, v64
	v_mov_b32_e32 v67, v64
	v_mov_b32_e32 v68, v64
	v_mov_b32_e32 v69, v64
	v_mov_b32_e32 v70, v64
	v_mov_b32_e32 v71, v64
	v_mov_b32_e32 v72, v64
	v_mov_b32_e32 v73, v64
	v_mov_b32_e32 v74, v64
	v_mov_b32_e32 v75, v64
	v_mov_b32_e32 v76, v64
	v_mov_b32_e32 v77, v64
	v_mov_b64_e32 v[142:143], v[78:79]
	v_sub_f32_e32 v48, v48, v32
	v_sub_f32_e32 v49, v49, v32
	v_sub_f32_e32 v80, v80, v32
	v_sub_f32_e32 v81, v81, v32
	v_sub_f32_e32 v50, v50, v32
	v_sub_f32_e32 v51, v51, v32
	v_sub_f32_e32 v82, v82, v32
	v_sub_f32_e32 v83, v83, v32
	v_sub_f32_e32 v52, v52, v32
	v_sub_f32_e32 v53, v53, v32
	v_sub_f32_e32 v84, v84, v32
	v_sub_f32_e32 v85, v85, v32
	v_sub_f32_e32 v54, v54, v32
	v_sub_f32_e32 v55, v55, v32
	v_sub_f32_e32 v86, v86, v32
	v_sub_f32_e32 v87, v87, v32
	v_sub_f32_e32 v56, v56, v32
	v_sub_f32_e32 v57, v57, v32
	v_sub_f32_e32 v88, v88, v32
	v_sub_f32_e32 v89, v89, v32
	v_sub_f32_e32 v58, v58, v32
	v_sub_f32_e32 v59, v59, v32
	v_sub_f32_e32 v90, v90, v32
	v_sub_f32_e32 v91, v91, v32
	v_sub_f32_e32 v60, v60, v32
	v_sub_f32_e32 v61, v61, v32
	v_sub_f32_e32 v92, v92, v32
	v_sub_f32_e32 v93, v93, v32
	v_sub_f32_e32 v62, v62, v32
	v_sub_f32_e32 v63, v63, v32
	v_sub_f32_e32 v94, v94, v32
	v_sub_f32_e32 v95, v95, v32
	v_mul_f32_e32 v172, v172, v33
	v_mul_f32_e32 v12, v12, v38
	v_mul_f32_e32 v13, v13, v39
	v_mul_f32_e32 v8, v8, v34
	v_mul_f32_e32 v9, v9, v35
	v_mul_f32_e32 v0, v0, v42
	v_mul_f32_e32 v1, v1, v43
	v_mul_f32_e32 v28, v28, v38
	v_mul_f32_e32 v29, v29, v39
	v_mul_f32_e32 v24, v24, v34
	v_mul_f32_e32 v25, v25, v35
	v_mul_f32_e32 v14, v14, v40
	v_mul_f32_e32 v15, v15, v41
	v_mul_f32_e32 v10, v10, v36
	v_mul_f32_e32 v11, v11, v37
	v_mul_f32_e32 v2, v2, v44
	v_mul_f32_e32 v3, v3, v45
	v_mul_f32_e32 v30, v30, v40
	v_mul_f32_e32 v31, v31, v41
	v_mul_f32_e32 v26, v26, v36
	v_mul_f32_e32 v27, v27, v37
	v_mul_f32_e32 v18, v18, v44
	v_mul_f32_e32 v19, v19, v45
	v_mul_f32_e32 v16, v16, v42
	v_mul_f32_e32 v17, v17, v43
	v_mov_b32_e32 v46, v64
	v_mov_b32_e32 v45, v64
	v_mov_b32_e32 v44, v64
	v_mov_b32_e32 v43, v64
	v_mov_b32_e32 v42, v64
	v_mov_b32_e32 v41, v64
	v_mov_b32_e32 v40, v64
	v_mov_b32_e32 v39, v64
	v_mov_b32_e32 v38, v64
	v_mov_b32_e32 v37, v64
	v_mov_b32_e32 v36, v64
	v_mov_b32_e32 v35, v64
	v_mov_b32_e32 v34, v64
	v_mov_b32_e32 v33, v64
	v_mov_b32_e32 v32, v64
	v_mov_b64_e32 v[140:141], v[76:77]
	v_mov_b64_e32 v[138:139], v[74:75]
	v_mov_b64_e32 v[136:137], v[72:73]
	v_mov_b64_e32 v[134:135], v[70:71]
	v_mov_b64_e32 v[132:133], v[68:69]
	v_mov_b64_e32 v[130:131], v[66:67]
	v_mov_b64_e32 v[128:129], v[64:65]
	s_branch .LBB0_738

.LBB0_743:
	v_add_f32_e32 v48, v70, v65
	v_add_f32_e32 v49, v72, v71
	v_add_f32_e32 v48, v49, v48
	v_add_f32_e32 v49, v74, v73
	v_add_f32_e32 v50, v76, v75
	v_add_f32_e32 v48, 0, v48
	v_add_f32_e32 v49, v50, v49
	v_add_f32_e32 v48, v49, v48
	v_add_f32_e32 v49, v78, v77
	v_add_f32_e32 v50, v80, v79
	v_add_f32_e32 v49, v50, v49
	v_add_f32_e32 v48, v49, v48
	v_add_f32_e32 v49, v82, v81
	v_add_f32_e32 v50, v84, v83
	v_add_f32_e32 v49, v50, v49
	v_add_f32_e32 v48, v49, v48
	v_add_f32_e32 v49, v86, v85
	v_add_f32_e32 v50, v88, v87
	v_add_f32_e32 v49, v50, v49
	v_add_f32_e32 v48, v49, v48
	v_add_f32_e32 v49, v173, v89
	v_add_f32_e32 v50, v91, v90
	v_add_f32_e32 v49, v50, v49
	v_add_f32_e32 v48, v49, v48
	v_add_f32_e32 v49, v61, v60
	v_add_f32_e32 v50, v93, v92
	v_add_f32_e32 v49, v50, v49
	v_add_f32_e32 v50, v63, v62
	v_add_f32_e32 v51, v95, v94
	v_add_f32_e32 v50, v51, v50
	v_add_f32_e32 v48, v49, v48
	v_add_f32_e32 v48, v50, v48
	v_add_f32_e32 v172, v172, v48
	v_maximum3_f32 v48, v112, v96, v96
	v_maximum3_f32 v49, v97, v114, v98
	v_maximum3_f32 v48, v48, v113, v115
	v_maximum3_f32 v49, v49, v116, v100
	v_maximum3_f32 v48, v48, v99, v117
	v_maximum3_f32 v49, v49, v118, v102
	v_maximum3_f32 v48, v48, v101, v119
	v_maximum3_f32 v49, v49, v120, v104
	v_maximum3_f32 v48, v48, v103, v121
	v_maximum3_f32 v49, v49, v122, v106
	v_maximum3_f32 v48, v48, v105, v123
	v_maximum3_f32 v49, v49, v124, v108
	v_maximum3_f32 v48, v48, v107, v125
	v_maximum3_f32 v49, v49, v126, v110
	v_maximum3_f32 v48, v48, v109, v127
	v_maximum3_f32 v48, v48, v111, v49
	v_mov_b32_e32 v49, v48
	s_nop 1
	v_permlane32_swap_b32_e32 v48, v49
	v_maximum3_f32 v48, v48, v49, v49
	v_cmp_lt_f32_e32 vcc, s46, v48
	s_cbranch_vccz .LBB0_747
	v_max_f32_e32 v32, v48, v48
	v_max_f32_e32 v32, 0, v32
	v_exp_f32_e64 v33, -v32
	s_and_saveexec_b64 s[6:7], s[38:39]
	ds_write_b32 v171, v33 offset:49152
	s_or_b64 exec, exec, s[6:7]
	s_waitcnt lgkmcnt(0)
	v_add_u32_e32 v46, s73, v160
	ds_read_b128 v[34:37], v46 offset:49216
	ds_read_b128 v[38:41], v46 offset:49248
	ds_read_b128 v[42:45], v46 offset:49152
	ds_read_b128 v[48:51], v46 offset:49184
	v_add_f32_e32 v165, v165, v32
	v_xor_b32_e32 v64, 0x80000000, v165
	s_waitcnt lgkmcnt(0)
	v_mov_b32_e32 v78, v64
	v_mov_b32_e32 v79, v64
	v_mov_b32_e32 v65, v64
	v_mov_b32_e32 v66, v64
	v_mov_b32_e32 v67, v64
	v_mov_b32_e32 v68, v64
	v_mov_b32_e32 v69, v64
	v_mov_b32_e32 v70, v64
	v_mov_b32_e32 v71, v64
	v_mov_b32_e32 v72, v64
	v_mov_b32_e32 v73, v64
	v_mov_b32_e32 v74, v64
	v_mov_b32_e32 v75, v64
	v_mov_b32_e32 v76, v64
	v_mov_b32_e32 v77, v64
	v_mov_b64_e32 v[142:143], v[78:79]
	v_sub_f32_e32 v112, v112, v32
	v_sub_f32_e32 v113, v113, v32
	v_sub_f32_e32 v96, v96, v32
	v_sub_f32_e32 v97, v97, v32
	v_sub_f32_e32 v114, v114, v32
	v_sub_f32_e32 v115, v115, v32
	v_sub_f32_e32 v98, v98, v32
	v_sub_f32_e32 v99, v99, v32
	v_sub_f32_e32 v116, v116, v32
	v_sub_f32_e32 v117, v117, v32
	v_sub_f32_e32 v100, v100, v32
	v_sub_f32_e32 v101, v101, v32
	v_sub_f32_e32 v118, v118, v32
	v_sub_f32_e32 v119, v119, v32
	v_sub_f32_e32 v102, v102, v32
	v_sub_f32_e32 v103, v103, v32
	v_sub_f32_e32 v120, v120, v32
	v_sub_f32_e32 v121, v121, v32
	v_sub_f32_e32 v104, v104, v32
	v_sub_f32_e32 v105, v105, v32
	v_sub_f32_e32 v122, v122, v32
	v_sub_f32_e32 v123, v123, v32
	v_sub_f32_e32 v106, v106, v32
	v_sub_f32_e32 v107, v107, v32
	v_sub_f32_e32 v124, v124, v32
	v_sub_f32_e32 v125, v125, v32
	v_sub_f32_e32 v108, v108, v32
	v_sub_f32_e32 v109, v109, v32
	v_sub_f32_e32 v126, v126, v32
	v_sub_f32_e32 v127, v127, v32
	v_sub_f32_e32 v110, v110, v32
	v_sub_f32_e32 v111, v111, v32
	v_mul_f32_e32 v172, v172, v33
	s_waitcnt lgkmcnt(0)
	v_mul_f32_e32 v28, v28, v38
	v_mul_f32_e32 v29, v29, v39
	v_mul_f32_e32 v24, v24, v34
	v_mul_f32_e32 v25, v25, v35
	v_mul_f32_e32 v20, v20, v48
	v_mul_f32_e32 v21, v21, v49
	v_mul_f32_e32 v30, v30, v40
	v_mul_f32_e32 v31, v31, v41
	v_mul_f32_e32 v26, v26, v36
	v_mul_f32_e32 v27, v27, v37
	v_mul_f32_e32 v22, v22, v50
	v_mul_f32_e32 v23, v23, v51
	v_mul_f32_e32 v18, v18, v44
	v_mul_f32_e32 v19, v19, v45
	v_mul_f32_e32 v16, v16, v42
	v_mul_f32_e32 v17, v17, v43
	v_mul_f32_e32 v12, v12, v38
	v_mul_f32_e32 v13, v13, v39
	v_mul_f32_e32 v8, v8, v34
	v_mul_f32_e32 v9, v9, v35
	v_mul_f32_e32 v4, v4, v48
	v_mul_f32_e32 v5, v5, v49
	v_mul_f32_e32 v14, v14, v40
	v_mul_f32_e32 v15, v15, v41
	v_mul_f32_e32 v10, v10, v36
	v_mul_f32_e32 v11, v11, v37
	v_mul_f32_e32 v6, v6, v50
	v_mul_f32_e32 v7, v7, v51
	v_mul_f32_e32 v2, v2, v44
	v_mul_f32_e32 v3, v3, v45
	v_mul_f32_e32 v0, v0, v42
	v_mul_f32_e32 v1, v1, v43
	v_mov_b32_e32 v46, v64
	v_mov_b32_e32 v45, v64
	v_mov_b32_e32 v44, v64
	v_mov_b32_e32 v43, v64
	v_mov_b32_e32 v42, v64
	v_mov_b32_e32 v41, v64
	v_mov_b32_e32 v40, v64
	v_mov_b32_e32 v39, v64
	v_mov_b32_e32 v38, v64
	v_mov_b32_e32 v37, v64
	v_mov_b32_e32 v36, v64
	v_mov_b32_e32 v35, v64
	v_mov_b32_e32 v34, v64
	v_mov_b32_e32 v33, v64
	v_mov_b32_e32 v32, v64
	v_mov_b64_e32 v[140:141], v[76:77]
	v_mov_b64_e32 v[138:139], v[74:75]
	v_mov_b64_e32 v[136:137], v[72:73]
	v_mov_b64_e32 v[134:135], v[70:71]
	v_mov_b64_e32 v[132:133], v[68:69]
	v_mov_b64_e32 v[130:131], v[66:67]
	v_mov_b64_e32 v[128:129], v[64:65]
; #define ATT_SYNC() do { asm volatile("s_waitcnt vmcnt(0)" ::: "memory"); __syncthreads(); } while (0)
; template <int NS, int DQK, int DV, bool KSH  > ...
;     ...
;     if constexpr (NS == 1) {
;         for (int t = tlo; t < thi; t += 2) {
;             if (t + 2 < thi) ATT_DMA(t + 2, bnn);
;             ATT_MAX(pA0, pA1, 0, t == tlo);
;             ATT_QKEXP(pB0, pB1, 0, bn, pA0, pA1, 0);
;             ATT_PV(0, bc);
;             ATT_SYNC();
;             if (t + 3 < thi) ATT_DMA(t + 3, bc);
;             ATT_MAX(pB0, pB1, 0, false);
;             ATT_QKEXP(pA0, pA1, 0, bnn, pB0, pB1, 0);
;             ATT_PV(0, bn);
;             ATT_SYNC();
;             const int tmp = bc; bc = bnn; bnn = bn; bn = tmp;
;         }
.LBB0_747:
	v_mov_b32_e32 v48, 0
	v_add_u32_e32 v65, s15, v170
	v_exp_f32_e32 v75, v96
	v_add_u32_e32 v48, v65, v48
	ds_read_b128 v[66:69], v48
	ds_read_b128 v[70:73], v48 offset:512
	v_mov_b32_e32 v48, 0
	v_exp_f32_e32 v85, v97
	v_add_u32_e32 v48, v65, v48
	ds_read_b128 v[76:79], v48 offset:2048
	ds_read_b128 v[80:83], v48 offset:2560
	s_waitcnt lgkmcnt(0)
	v_mfma_f32_32x32x16_bf16 v[48:63], v[66:69], v[152:155], v[128:143]
	v_exp_f32_e32 v69, v112
	v_exp_f32_e32 v68, v114
	v_exp_f32_e32 v74, v98
	v_exp_f32_e32 v84, v99
	v_cvt_pk_bf16_f32 v66, v75, v85
	v_exp_f32_e32 v94, v105
	s_add_i32 s14, s14, 2
	v_mfma_f32_32x32x16_bf16 v[128:143], v[70:73], v[152:155], v[128:143]
	v_exp_f32_e32 v73, v113
	v_exp_f32_e32 v72, v115
	v_add_f32_e32 v88, v84, v74
	v_add_f32_e32 v89, v85, v75
	s_addk_i32 s12, 0x80
	v_cvt_pk_bf16_f32 v70, v69, v73
	v_add_f32_e32 v86, v72, v68
	v_add_f32_e32 v87, v73, v69
	v_cvt_pk_bf16_f32 v71, v68, v72
	v_mov_b32_e32 v68, 0
	v_add_f32_e32 v86, v88, v86
	v_add_f32_e32 v87, v89, v87
	v_exp_f32_e32 v69, v116
	v_add_f32_e32 v67, 0, v87
	v_add_u32_e32 v68, v65, v68
	v_add_f32_e32 v75, v86, v67
	v_cvt_pk_bf16_f32 v67, v74, v84
	ds_read_b128 v[84:87], v68 offset:4096
	v_mfma_f32_32x32x16_bf16 v[48:63], v[76:79], v[144:147], v[48:63]
	ds_read_b128 v[88:91], v68 offset:4608
	v_exp_f32_e32 v77, v117
	v_exp_f32_e32 v68, v100
	v_exp_f32_e32 v76, v101
	v_exp_f32_e32 v74, v102
	v_exp_f32_e32 v102, v110
	s_and_b64 vcc, exec, s[0:1]
	v_add_f32_e32 v72, v76, v68
	v_add_f32_e32 v73, v77, v69
	v_cvt_pk_bf16_f32 v68, v68, v76
	v_add_f32_e32 v92, v72, v72
	v_add_f32_e32 v93, v72, v73
	v_cvt_pk_bf16_f32 v72, v69, v77
	v_exp_f32_e32 v69, v118
	v_exp_f32_e32 v73, v119
	v_exp_f32_e32 v76, v103
	v_mfma_f32_32x32x16_bf16 v[128:143], v[80:83], v[144:147], v[128:143]
	v_exp_f32_e32 v92, v121
	v_add_f32_e32 v77, v73, v69
	v_add_f32_e32 v95, v76, v74
	v_cvt_pk_bf16_f32 v73, v69, v73
	v_cvt_pk_bf16_f32 v69, v74, v76
	v_mov_b32_e32 v74, 0
	v_exp_f32_e32 v76, v104
	v_add_u32_e32 v65, v65, v74
	v_exp_f32_e32 v74, v120
	ds_read_b128 v[80:83], v65 offset:6144
	s_waitcnt lgkmcnt(0)
	v_mfma_f32_32x32x16_bf16 v[48:63], v[84:87], v[148:151], v[48:63]
	ds_read_b128 v[112:115], v65 offset:6656
	v_add_f32_e64 v78, v92, v74
	v_add_f32_e64 v79, v93, v75
	v_add_f32_e64 v84, v94, v76
	v_add_f32_e64 v85, v95, v77
	v_cvt_pk_bf16_f32 v96, v74, v92
	v_add_f32_e32 v78, v84, v78
	v_add_f32_e32 v79, v85, v79
	v_cvt_pk_bf16_f32 v74, v76, v94
	v_exp_f32_e32 v77, v122
	v_mfma_f32_32x32x16_bf16 v[128:143], v[88:91], v[148:151], v[128:143]
	v_exp_f32_e32 v85, v123
	v_exp_f32_e32 v76, v106
	v_exp_f32_e32 v84, v107
	v_add_f32_e32 v79, v78, v79
	v_add_f32_e32 v78, v78, v78
	v_cvt_pk_bf16_f32 v97, v77, v85
	ds_read_b128 v[116:119], v47 offset:8192
	v_add_f32_e32 v86, v84, v76
	v_add_f32_e32 v87, v85, v77
	v_cvt_pk_bf16_f32 v75, v76, v84
	v_exp_f32_e32 v65, v124
	v_exp_f32_e32 v76, v125
	v_exp_f32_e32 v77, v108
	v_exp_f32_e32 v78, v109
	v_add_f32_e32 v100, v86, v86
	v_add_f32_e32 v101, v86, v87
	v_mfma_f32_32x32x16_bf16 v[48:63], v[80:83], v[156:159], v[48:63]
	v_mov_b64_e32 v[80:81], v[128:129]
	v_mov_b64_e32 v[82:83], v[130:131]
	v_mov_b64_e32 v[84:85], v[132:133]
	v_mov_b64_e32 v[86:87], v[134:135]
	v_mov_b64_e32 v[88:89], v[136:137]
	v_mov_b64_e32 v[90:91], v[138:139]
	v_mov_b64_e32 v[92:93], v[140:141]
	v_mov_b64_e32 v[94:95], v[142:143]
	v_add_f32_e32 v103, v76, v65
	v_add_f32_e32 v105, v78, v77
	v_cvt_pk_bf16_f32 v98, v65, v76
	v_cvt_pk_bf16_f32 v76, v77, v78
	v_exp_f32_e32 v78, v126
	v_exp_f32_e32 v100, v127
	v_exp_f32_e32 v104, v111
	ds_read_b128 v[106:109], v47 offset:10240
	s_waitcnt lgkmcnt(0)
	v_mfma_f32_32x32x16_bf16 v[80:95], v[112:115], v[156:159], v[80:95]
	ds_read_b128 v[110:113], v47 offset:12288
	v_cvt_pk_bf16_f32 v99, v78, v100
	v_cvt_pk_bf16_f32 v77, v102, v104
	v_mfma_f32_32x32x16_bf16 v[16:31], v[70:73], v[116:119], v[16:31]
	v_mfma_f32_32x32x16_bf16 v[16:31], v[96:99], v[106:109], v[16:31]
	ds_read_b128 v[106:109], v47 offset:14336
	s_waitcnt lgkmcnt(0)
	v_mfma_f32_32x32x16_bf16 v[16:31], v[66:69], v[110:113], v[16:31]
	ds_read_b128 v[110:113], v47 offset:8704
	v_mfma_f32_32x32x16_bf16 v[16:31], v[74:77], v[106:109], v[16:31]
	ds_read_b128 v[106:109], v47 offset:10752
	s_waitcnt lgkmcnt(0)
	v_mfma_f32_32x32x16_bf16 v[0:15], v[70:73], v[110:113], v[0:15]
	v_mfma_f32_32x32x16_bf16 v[0:15], v[96:99], v[106:109], v[0:15]
	ds_read_b128 v[96:99], v47 offset:14848
	ds_read_b128 v[70:73], v47 offset:12800
	s_waitcnt vmcnt(0)
	s_waitcnt vmcnt(0) lgkmcnt(0)
	s_barrier
	v_mfma_f32_32x32x16_bf16 v[0:15], v[66:69], v[70:73], v[0:15]
	v_add_f32_e64 v66, v100, v78
	v_add_f32_e64 v67, v101, v79
	v_add_f32_e64 v68, v104, v102
	v_add_f32_e64 v69, v105, v103
	v_add_f32_e64 v66, v68, v66
	v_add_f32_e64 v67, v69, v67
	v_add_f32_e32 v47, v66, v67
	v_add_f32_e32 v172, v172, v47
	v_mfma_f32_32x32x16_bf16 v[0:15], v[74:77], v[96:99], v[0:15]
	s_cbranch_vccnz .LBB0_749
	s_mov_b32 s0, s15
	s_mov_b32 s15, s17
	s_branch .LBB0_728

.LBB0_764:
	s_nop 6
	v_maximum3_f32 v32, v16, v0, v0
	v_maximum3_f32 v33, v1, v18, v2
	v_maximum3_f32 v32, v32, v17, v19
	v_maximum3_f32 v33, v33, v20, v4
	v_maximum3_f32 v32, v32, v3, v21
	v_maximum3_f32 v33, v33, v22, v6
	v_maximum3_f32 v32, v32, v5, v23
	v_maximum3_f32 v33, v33, v24, v8
	v_maximum3_f32 v32, v32, v7, v25
	v_maximum3_f32 v33, v33, v26, v10
	v_maximum3_f32 v32, v32, v9, v27
	v_maximum3_f32 v33, v33, v28, v12
	v_maximum3_f32 v32, v32, v11, v29
	v_maximum3_f32 v33, v33, v30, v14
	v_maximum3_f32 v32, v32, v13, v31
	v_maximum3_f32 v32, v32, v15, v33
	v_mov_b32_e32 v33, v32
	s_nop 1
	v_permlane32_swap_b32_e32 v32, v33
	v_maximum3_f32 v48, v32, v33, v33
	v_sub_f32_e32 v81, v8, v48
	v_mov_b32_e32 v8, v195
	v_sub_f32_e32 v59, v4, v48
	v_sub_f32_e32 v50, v0, v48
	v_add_u32_e32 v4, v222, v8
	v_sub_f32_e32 v52, v1, v48
	v_sub_f32_e32 v55, v2, v48
	v_sub_f32_e32 v57, v3, v48
	ds_read_b128 v[0:3], v4
	v_sub_f32_e32 v62, v5, v48
	v_sub_f32_e32 v63, v6, v48
	v_sub_f32_e32 v80, v7, v48
	ds_read_b128 v[4:7], v4 offset:512
	s_mov_b32 s6, 0x14800
	v_add3_u32 v8, v219, v8, s6
	v_sub_f32_e32 v82, v9, v48
	v_sub_f32_e32 v83, v10, v48
	v_sub_f32_e32 v90, v11, v48
	ds_read_b128 v[8:11], v8
	v_sub_f32_e32 v94, v12, v48
	v_mov_b32_e32 v12, v195
	v_sub_f32_e32 v58, v20, v48
	v_sub_f32_e32 v49, v16, v48
	v_add_u32_e32 v20, v222, v12
	v_sub_f32_e32 v51, v17, v48
	v_sub_f32_e32 v54, v18, v48
	v_sub_f32_e32 v56, v19, v48
	ds_read_b128 v[16:19], v20 offset:2048
	s_waitcnt lgkmcnt(0)
	v_mfma_f32_32x32x16_bf16 v[32:47], v[0:3], v[8:11], 0
	s_mov_b32 s6, 0x16800
	v_sub_f32_e32 v95, v13, v48
	v_sub_f32_e32 v96, v14, v48
	ds_read_b128 v[0:3], v20 offset:2560
	v_add3_u32 v14, v219, v12, s6
	v_exp_f32_e32 v13, v51
	v_exp_f32_e32 v51, v50
	v_mfma_f32_32x32x16_bf16 v[64:79], v[4:7], v[8:11], 0
	v_exp_f32_e32 v11, v49
	v_exp_f32_e32 v53, v52
	v_exp_f32_e32 v10, v54
	v_exp_f32_e32 v12, v56
	v_exp_f32_e32 v50, v55
	v_exp_f32_e32 v52, v57
	ds_read_b128 v[4:7], v14
	v_sub_f32_e32 v60, v21, v48
	v_sub_f32_e32 v97, v15, v48
	v_add_f32_e32 v14, v12, v10
	v_add_f32_e32 v15, v13, v11
	v_add_f32_e32 v20, v52, v50
	v_add_f32_e32 v21, v53, v51
	s_waitcnt lgkmcnt(0)
	v_mfma_f32_32x32x16_bf16 v[32:47], v[16:19], v[4:7], v[32:47]
	v_add_f32_e64 v14, v20, v14
	v_add_f32_e64 v15, v21, v15
	v_cvt_pk_bf16_f32 v8, v11, v13
	v_add_f32_e32 v9, 0, v15
	v_add_f32_e32 v17, v14, v9
	v_mov_b32_e32 v14, v195
	v_cvt_pk_bf16_f32 v9, v10, v12
	v_add_u32_e32 v15, v222, v14
	ds_read_b128 v[10:13], v15 offset:4096
	s_mov_b32 s6, 0x18800
	v_mfma_f32_32x32x16_bf16 v[64:79], v[0:3], v[4:7], v[64:79]
	v_add3_u32 v4, v219, v14, s6
	ds_read_b128 v[0:3], v15 offset:4608
	ds_read_b128 v[4:7], v4
	v_exp_f32_e32 v55, v58
	v_exp_f32_e32 v61, v60
	v_exp_f32_e32 v54, v59
	v_exp_f32_e32 v60, v62
	s_waitcnt lgkmcnt(0)
	v_mfma_f32_32x32x16_bf16 v[32:47], v[10:13], v[4:7], v[32:47]
	v_mov_b32_e32 v11, v195
	v_add_f32_e64 v14, v60, v54
	v_add_f32_e64 v15, v61, v55
	v_add_u32_e32 v16, v222, v11
	v_add_f32_e64 v18, v14, v14
	v_add_f32_e64 v19, v14, v15
	ds_read_b128 v[12:15], v16 offset:6144
	s_mov_b32 s6, 0x1a800
	v_mfma_f32_32x32x16_bf16 v[64:79], v[0:3], v[4:7], v[64:79]
	ds_read_b128 v[0:3], v16 offset:6656
	v_add3_u32 v4, v219, v11, s6
	v_sub_f32_e32 v22, v22, v48
	v_sub_f32_e32 v23, v23, v48
	ds_read_b128 v[4:7], v4
	v_sub_f32_e32 v24, v24, v48
	v_sub_f32_e32 v25, v25, v48
	v_exp_f32_e32 v20, v22
	v_exp_f32_e32 v21, v23
	v_exp_f32_e32 v49, v63
	v_exp_f32_e32 v98, v80
	v_sub_f32_e32 v26, v26, v48
	v_sub_f32_e32 v27, v27, v48
	v_exp_f32_e32 v16, v24
	v_exp_f32_e32 v18, v25
	v_exp_f32_e32 v62, v81
	v_exp_f32_e32 v84, v82
	v_exp_f32_e32 v87, v26
	v_exp_f32_e32 v91, v27
	v_exp_f32_e32 v86, v83
	v_exp_f32_e32 v90, v90
	v_cvt_pk_bf16_f32 v10, v55, v61
	v_add_f32_e32 v63, v21, v20
	v_add_f32_e32 v85, v98, v49
	v_cvt_pk_bf16_f32 v11, v20, v21
	s_waitcnt lgkmcnt(0)
	v_mfma_f32_32x32x16_bf16 v[32:47], v[12:15], v[4:7], v[32:47]
	ds_read_b128 v[12:15], v222 offset:8192
	v_add_f32_e64 v20, v18, v16
	v_add_f32_e64 v21, v19, v17
	v_add_f32_e64 v22, v84, v62
	v_add_f32_e64 v23, v85, v63
	v_sub_f32_e32 v28, v28, v48
	v_add_f32_e32 v20, v22, v20
	v_add_f32_e32 v21, v23, v21
	v_sub_f32_e32 v29, v29, v48
	v_sub_f32_e32 v30, v30, v48
	v_mfma_f32_32x32x16_bf16 v[64:79], v[0:3], v[4:7], v[64:79]
	v_add_f32_e64 v0, v90, v86
	v_add_f32_e64 v1, v91, v87
	v_sub_f32_e32 v31, v31, v48
	v_add_f32_e64 v88, v20, v20
	v_add_f32_e64 v89, v20, v21
	v_add_f32_e32 v92, v0, v0
	v_add_f32_e32 v93, v0, v1
	v_exp_f32_e32 v55, v28
	v_exp_f32_e32 v61, v29
	v_exp_f32_e32 v88, v30
	v_exp_f32_e32 v92, v31
	v_cvt_pk_bf16_f32 v56, v16, v18
	ds_read_b128 v[0:3], v222 offset:10240
	s_waitcnt lgkmcnt(0)
	v_mfma_f32_32x32x16_bf16 v[16:31], v[8:11], v[12:15], 0
	v_cvt_pk_bf16_f32 v57, v87, v91
	v_cvt_pk_bf16_f32 v58, v55, v61
	v_cvt_pk_bf16_f32 v59, v88, v92
	ds_read_b128 v[4:7], v222 offset:12288
	v_cvt_pk_bf16_f32 v80, v51, v53
	v_cvt_pk_bf16_f32 v81, v50, v52
	v_cvt_pk_bf16_f32 v82, v54, v60
	v_mfma_f32_32x32x16_bf16 v[16:31], v[56:59], v[0:3], v[16:31]
	v_cvt_pk_bf16_f32 v83, v49, v98
	v_exp_f32_e32 v15, v94
	v_exp_f32_e32 v49, v95
	v_exp_f32_e32 v12, v96
	v_exp_f32_e32 v14, v97
	ds_read_b128 v[0:3], v222 offset:14336
	v_cvt_pk_bf16_f32 v84, v62, v84
	s_waitcnt lgkmcnt(0)
	v_mfma_f32_32x32x16_bf16 v[16:31], v[80:83], v[4:7], v[16:31]
	v_cvt_pk_bf16_f32 v85, v86, v90
	v_cvt_pk_bf16_f32 v86, v15, v49
	v_cvt_pk_bf16_f32 v87, v12, v14
	ds_read_b128 v[4:7], v222 offset:8704
	v_add_f32_e32 v13, v61, v55
	v_add_f32_e32 v15, v49, v15
	v_add_f32_e32 v50, v92, v88
	v_add_f32_e32 v51, v93, v89
	v_mfma_f32_32x32x16_bf16 v[16:31], v[84:87], v[0:3], v[16:31]
	v_add_f32_e64 v0, v14, v12
	v_add_f32_e64 v1, v15, v13
	ds_read_b128 v[60:63], v222 offset:10752
	v_add_f32_e64 v0, v0, v50
	v_add_f32_e64 v1, v1, v51
	s_mov_b32 s6, 0x12800
	v_add_f32_e32 v1, v0, v1
	v_add_f32_e32 v0, v0, v0
	v_mov_b32_e32 v49, v1
	v_add_f32_e32 v210, 0, v48
	v_add_f32_e32 v211, 0, v49
	s_waitcnt lgkmcnt(0)
	v_mfma_f32_32x32x16_bf16 v[0:15], v[8:11], v[4:7], 0
	ds_read_b128 v[88:91], v222 offset:12800
	v_add_f32_e64 v48, -v210, neg(0)
	v_add_f32_e64 v49, -v211, neg(0)
	s_mov_b32 s22, 0x1a800
	v_mov_b32_e32 v49, v48
	v_mov_b32_e32 v50, v48
	v_mov_b32_e32 v51, v48
	v_mov_b32_e32 v52, v48
	v_mfma_f32_32x32x16_bf16 v[0:15], v[56:59], v[60:63], v[0:15]
	ds_read_b128 v[92:95], v222 offset:14848
	v_mov_b32_e32 v53, v48
	v_mov_b32_e32 v54, v48
	v_mov_b32_e32 v55, v48
	v_mov_b32_e32 v56, v48
	v_mov_b32_e32 v57, v48
	v_mov_b32_e32 v58, v48
	s_waitcnt lgkmcnt(0)
	v_mfma_f32_32x32x16_bf16 v[0:15], v[80:83], v[88:91], v[0:15]
	v_maximum3_f32 v80, v32, v64, v64
	v_maximum3_f32 v83, v65, v34, v66
	v_maximum3_f32 v80, v80, v33, v35
	v_maximum3_f32 v83, v83, v36, v68
	v_maximum3_f32 v80, v80, v67, v37
	v_maximum3_f32 v83, v83, v38, v70
	v_maximum3_f32 v80, v80, v69, v39
	v_maximum3_f32 v83, v83, v40, v72
	v_maximum3_f32 v80, v80, v71, v41
	v_maximum3_f32 v83, v83, v42, v74
	v_maximum3_f32 v80, v80, v73, v43
	v_maximum3_f32 v83, v83, v44, v76
	v_maximum3_f32 v80, v80, v75, v45
	v_maximum3_f32 v83, v83, v46, v78
	v_maximum3_f32 v80, v80, v77, v47
	v_mov_b32_e32 v81, v195
	v_maximum3_f32 v80, v80, v79, v83
	v_mov_b32_e32 v83, v80
	v_add_u32_e32 v82, v222, v81
	ds_read_b128 v[88:91], v82 offset:16384
	v_permlane32_swap_b32_e32 v80, v83
	v_maximum3_f32 v80, v80, v83, v83
	v_mfma_f32_32x32x16_bf16 v[0:15], v[84:87], v[92:95], v[0:15]
	v_sub_f32_e32 v83, v32, v80
	v_sub_f32_e32 v84, v33, v80
	v_sub_f32_e32 v85, v34, v80
	v_sub_f32_e32 v86, v35, v80
	ds_read_b128 v[32:35], v82 offset:16896
	v_sub_f32_e32 v87, v36, v80
	v_add_u32_e32 v36, v219, v81
	v_sub_f32_e32 v92, v37, v80
	v_sub_f32_e32 v93, v38, v80
	v_sub_f32_e32 v94, v39, v80
	ds_read_b128 v[36:39], v36 offset:51200
	v_sub_f32_e32 v119, v44, v80
	v_mov_b32_e32 v44, v195
	v_mov_b32_e32 v59, v48
	v_mov_b32_e32 v60, v48
	v_mov_b32_e32 v61, v48
	v_mov_b32_e32 v62, v48
	v_mov_b32_e32 v63, v48
	v_sub_f32_e32 v81, v45, v80
	v_sub_f32_e32 v95, v40, v80
	v_add_u32_e32 v45, v222, v44
	v_sub_f32_e32 v113, v41, v80
	v_sub_f32_e32 v115, v42, v80
	v_sub_f32_e32 v117, v43, v80
	s_waitcnt lgkmcnt(0)
	v_mfma_f32_32x32x16_bf16 v[96:111], v[88:91], v[36:39], v[48:63]
	ds_read_b128 v[40:43], v45 offset:18432
	v_mov_b64_e32 v[142:143], v[62:63]
	v_mov_b64_e32 v[140:141], v[60:61]
	v_mov_b64_e32 v[138:139], v[58:59]
	v_mov_b64_e32 v[136:137], v[56:57]
	v_mov_b64_e32 v[134:135], v[54:55]
	v_mov_b64_e32 v[132:133], v[52:53]
	v_mov_b64_e32 v[130:131], v[50:51]
	v_mov_b64_e32 v[128:129], v[48:49]
	v_sub_f32_e32 v64, v64, v80
	v_sub_f32_e32 v65, v65, v80
	v_sub_f32_e32 v66, v66, v80
	v_sub_f32_e32 v67, v67, v80
	v_mfma_f32_32x32x16_bf16 v[128:143], v[32:35], v[36:39], v[128:143]
	ds_read_b128 v[32:35], v45 offset:18944
	v_sub_f32_e32 v112, v72, v80
	v_sub_f32_e32 v114, v73, v80
	v_sub_f32_e32 v122, v46, v80
	v_sub_f32_e32 v89, v47, v80
	v_add_u32_e32 v36, v219, v44
	v_exp_f32_e32 v45, v83
	v_exp_f32_e32 v47, v84
	v_exp_f32_e32 v61, v64
	v_exp_f32_e32 v73, v65
	v_exp_f32_e32 v44, v85
	v_exp_f32_e32 v46, v86
	v_exp_f32_e32 v60, v66
	v_exp_f32_e32 v72, v67
	ds_read_b128 v[36:39], v36 offset:59392
	v_add_f32_e32 v52, v46, v44
	v_add_f32_e32 v53, v47, v45
	v_cvt_pk_bf16_f32 v51, v44, v46
	v_add_f32_e32 v54, v72, v60
	v_add_f32_e32 v55, v73, v61
	v_mov_b32_e32 v44, v195
	v_add_f32_e32 v52, v54, v52
	v_add_f32_e32 v53, v55, v53
	v_sub_f32_e32 v68, v68, v80
	v_sub_f32_e32 v69, v69, v80
	s_waitcnt lgkmcnt(0)
	v_mfma_f32_32x32x16_bf16 v[96:111], v[40:43], v[36:39], v[96:111]
	v_add_f32_e32 v40, 0, v53
	v_sub_f32_e32 v116, v74, v80
	v_add_u32_e32 v46, v222, v44
	v_sub_f32_e32 v118, v75, v80
	v_sub_f32_e32 v120, v76, v80
	v_sub_f32_e32 v121, v77, v80
	v_cvt_pk_bf16_f32 v50, v45, v47
	v_add_f32_e32 v45, v52, v40
	ds_read_b128 v[40:43], v46 offset:20480
	v_exp_f32_e32 v75, v87
	v_exp_f32_e32 v77, v92
	v_exp_f32_e32 v74, v68
	v_exp_f32_e32 v76, v69
	v_mfma_f32_32x32x16_bf16 v[128:143], v[32:35], v[36:39], v[128:143]
	ds_read_b128 v[32:35], v46 offset:20992
	v_add3_u32 v36, v219, v44, s45
	v_exp_f32_e32 v44, v93
	v_exp_f32_e32 v49, v94
	v_sub_f32_e32 v70, v70, v80
	v_sub_f32_e32 v71, v71, v80
	ds_read_b128 v[36:39], v36
	v_add_f32_e32 v46, v76, v74
	v_add_f32_e32 v47, v77, v75
	v_exp_f32_e32 v86, v70
	v_exp_f32_e32 v87, v71
	v_add_f32_e32 v47, v46, v47
	v_add_f32_e32 v46, v46, v46
	v_sub_f32_e32 v123, v78, v80
	v_sub_f32_e32 v124, v79, v80
	v_add_f32_e32 v79, v49, v44
	v_cvt_pk_bf16_f32 v53, v44, v49
	v_exp_f32_e32 v44, v95
	v_exp_f32_e32 v46, v113
	v_exp_f32_e32 v78, v112
	v_exp_f32_e32 v84, v114
	v_mov_b32_e32 v49, v195
	v_exp_f32_e32 v93, v115
	v_exp_f32_e32 v95, v117
	v_exp_f32_e32 v92, v116
	v_exp_f32_e32 v94, v118
	v_add_f32_e32 v85, v87, v86
	s_waitcnt lgkmcnt(0)
; #define ATT_SYNC() do { asm volatile("s_waitcnt vmcnt(0)" ::: "memory"); __syncthreads(); } while (0)
; template <int NS, int DQK, int DV, bool KSH  > ...
;     ...
;         for (int t = tlo; t < thi; ++t) {
;             if (t + 2 < thi) ATT_DMA(t + 2, bnn);
;             ATT_MAX(pA0, pA1, 0, t == tlo);
;             ATT_QKEXP(pB0, pB1, NS - 1, bc, pA0, pA1, 0);
;             ATT_PV(0, bc);
;             ATT_MAX(pB0, pB1, NS - 1, t == tlo);
;             ATT_QKEXP(pA0, pA1, 0, bn, pB0, pB1, NS - 1);
;             ATT_PV(NS - 1, bc);
;             ATT_SYNC();
;             const int tmp = bc; bc = bn; bn = bnn; bnn = tmp;
;         }
	v_mfma_f32_32x32x16_bf16 v[96:111], v[40:43], v[36:39], v[96:111]
	v_cvt_pk_bf16_f32 v52, v75, v77
	v_add_u32_e32 v40, v222, v49
	ds_read_b128 v[64:67], v40 offset:22528
	v_exp_f32_e32 v81, v81
	v_cvt_pk_bf16_f32 v88, v44, v46
	v_cvt_pk_bf16_f32 v58, v61, v73
	v_mfma_f32_32x32x16_bf16 v[128:143], v[32:35], v[36:39], v[128:143]
	v_add_f32_e64 v32, v46, v44
	v_add_f32_e64 v33, v47, v45
	v_add_f32_e64 v34, v84, v78
	v_add_f32_e64 v35, v85, v79
	ds_read_b128 v[68:71], v40 offset:23040
	v_add_f32_e32 v32, v34, v32
	v_add_f32_e32 v33, v35, v33
	v_exp_f32_e32 v85, v119
	v_add_f32_e32 v62, v32, v32
	v_add_f32_e32 v63, v32, v33
	v_add_f32_e32 v32, v94, v92
	v_add_f32_e32 v33, v95, v93
	v_exp_f32_e32 v62, v122
	v_add_f32_e32 v82, v32, v32
	v_add_f32_e32 v83, v32, v33
	ds_read_b128 v[32:35], v222 offset:8704
	v_exp_f32_e32 v82, v89
	s_waitcnt lgkmcnt(0)
	v_mfma_f32_32x32x16_bf16 v[32:47], v[50:53], v[32:35], 0
	ds_read_b128 v[54:57], v222 offset:10752
	v_cvt_pk_bf16_f32 v89, v93, v95
	v_cvt_pk_bf16_f32 v90, v85, v81
	v_cvt_pk_bf16_f32 v91, v62, v82
	v_cvt_pk_bf16_f32 v59, v60, v72
	v_cvt_pk_bf16_f32 v60, v74, v76
	v_cvt_pk_bf16_f32 v61, v86, v87
	s_waitcnt lgkmcnt(0)
	v_mfma_f32_32x32x16_bf16 v[32:47], v[88:91], v[54:57], v[32:47]
	ds_read_b128 v[72:75], v222 offset:12800
	v_cvt_pk_bf16_f32 v54, v78, v84
	v_exp_f32_e32 v87, v120
	v_exp_f32_e32 v112, v121
	v_exp_f32_e32 v84, v123
	v_exp_f32_e32 v86, v124
	v_cvt_pk_bf16_f32 v55, v92, v94
	s_waitcnt lgkmcnt(0)
	v_mfma_f32_32x32x16_bf16 v[32:47], v[58:61], v[72:75], v[32:47]
	ds_read_b128 v[76:79], v222 offset:14848
	v_cvt_pk_bf16_f32 v56, v87, v112
	v_cvt_pk_bf16_f32 v57, v84, v86
	v_add3_u32 v49, v219, v49, s6
	v_add_f32_e32 v85, v81, v85
	v_add_f32_e32 v87, v112, v87
	s_lshl_b32 s6, s58, 8
	s_waitcnt lgkmcnt(0)
	v_mfma_f32_32x32x16_bf16 v[32:47], v[54:57], v[76:79], v[32:47]
	ds_read_b128 v[72:75], v49
	s_mov_b32 s58, 0x12800
	s_mov_b32 s19, 0x18800
	s_mov_b32 s18, 0x16800
	s_mov_b32 s15, 0x14800
	s_or_b32 s8, s6, 0x6080
	v_cmp_gt_u32_e64 s[38:39], 32, v215
	s_waitcnt lgkmcnt(0)
	v_mfma_f32_32x32x16_bf16 v[96:111], v[64:67], v[72:75], v[96:111]
	ds_read_b128 v[64:67], v222 offset:8192
	v_lshl_add_u32 v209, v218, 2, s67
	s_mov_b32 s9, 0
	s_add_i32 s10, s68, 0
	s_mov_b32 s11, 0x8000
	s_movk_i32 s6, 0x4000
	s_mov_b32 s12, 64
	v_mfma_f32_32x32x16_bf16 v[128:143], v[68:71], v[72:75], v[128:143]
	ds_read_b128 v[92:95], v222 offset:10240
	s_mov_b32 s13, 0
	v_mov_b32_e32 v49, v48
	v_mov_b32_e32 v112, v48
	s_waitcnt lgkmcnt(0)
	v_mfma_f32_32x32x16_bf16 v[64:79], v[50:53], v[64:67], 0
	ds_read_b128 v[50:53], v222 offset:12288
	v_mfma_f32_32x32x16_bf16 v[64:79], v[88:91], v[92:95], v[64:79]
	ds_read_b128 v[88:91], v222 offset:14336
	s_waitcnt vmcnt(0)
	s_waitcnt vmcnt(0) lgkmcnt(0)
	s_barrier
	v_mfma_f32_32x32x16_bf16 v[64:79], v[58:61], v[50:53], v[64:79]
	v_add_f32_e64 v50, v82, v62
	v_add_f32_e64 v51, v83, v63
	v_add_f32_e64 v52, v86, v84
	v_add_f32_e64 v53, v87, v85
	v_mov_b32_e32 v58, v48
	v_add_f32_e32 v50, v52, v50
	v_add_f32_e32 v51, v53, v51
	v_mov_b32_e32 v52, v48
	v_add_f32_e32 v51, v50, v51
	v_add_f32_e32 v50, v50, v50
	v_mov_b32_e32 v81, v51
	v_mfma_f32_32x32x16_bf16 v[64:79], v[54:57], v[88:91], v[64:79]
	v_add_f32_e64 v212, v80, 0
	v_add_f32_e64 v213, v81, 0
	v_mov_b32_e32 v50, v48
	v_add_f32_e64 v80, -v212, neg(0)
	v_add_f32_e64 v81, -v213, neg(0)
	v_mov_b32_e32 v51, v48
	v_mov_b32_e32 v53, v48
	v_mov_b32_e32 v54, v48
	v_mov_b32_e32 v55, v48
	v_mov_b32_e32 v56, v48
	v_mov_b32_e32 v57, v48
	v_mov_b32_e32 v59, v48
	v_mov_b32_e32 v60, v48
	v_mov_b32_e32 v61, v48
	v_mov_b32_e32 v62, v48
	v_mov_b32_e32 v81, v80
	v_mov_b32_e32 v82, v80
	v_mov_b32_e32 v83, v80
	v_mov_b32_e32 v84, v80
	v_mov_b32_e32 v85, v80
	v_mov_b32_e32 v86, v80
	v_mov_b32_e32 v87, v80
	v_mov_b32_e32 v88, v80
	v_mov_b32_e32 v89, v80
	v_mov_b32_e32 v90, v80
	v_mov_b32_e32 v91, v80
	v_mov_b32_e32 v92, v80
	v_mov_b32_e32 v93, v80
	v_mov_b32_e32 v94, v80
	v_mov_b32_e32 v95, v80
	s_cmpk_gt_u32 s13, 0x80
	s_mov_b32 s14, s6
	s_cbranch_scc1 .LBB0_769

.LBB0_769:
	v_maximum3_f32 v63, v96, v128, v128
	v_maximum3_f32 v113, v129, v98, v130
	v_maximum3_f32 v63, v63, v97, v99
	v_maximum3_f32 v113, v113, v100, v132
	v_maximum3_f32 v63, v63, v131, v101
	v_maximum3_f32 v113, v113, v102, v134
	v_maximum3_f32 v63, v63, v133, v103
	v_maximum3_f32 v113, v113, v104, v136
	v_maximum3_f32 v63, v63, v135, v105
	v_maximum3_f32 v113, v113, v106, v138
	v_maximum3_f32 v63, v63, v137, v107
	v_maximum3_f32 v113, v113, v108, v140
	v_maximum3_f32 v63, v63, v139, v109
	v_maximum3_f32 v113, v113, v110, v142
	v_maximum3_f32 v63, v63, v141, v111
	v_maximum3_f32 v63, v63, v143, v113
	v_mov_b32_e32 v113, v63
	s_nop 1
	v_permlane32_swap_b32_e32 v63, v113
	v_maximum3_f32 v63, v63, v113, v113
	v_cmp_lt_f32_e32 vcc, s46, v63
	s_cbranch_vccz .LBB0_773
	v_max_f32_e32 v48, v63, v63
	v_max_f32_e32 v48, 0, v48
	v_exp_f32_e64 v49, -v48
	s_and_saveexec_b64 s[6:7], s[38:39]
	ds_write_b32 v209, v49 offset:49152
	s_or_b64 exec, exec, s[6:7]
	v_sub_f32_e32 v96, v96, v48
	v_sub_f32_e32 v97, v97, v48
	v_sub_f32_e32 v128, v128, v48
	v_sub_f32_e32 v129, v129, v48
	v_sub_f32_e32 v98, v98, v48
	v_sub_f32_e32 v99, v99, v48
	v_sub_f32_e32 v130, v130, v48
	v_sub_f32_e32 v131, v131, v48
	v_sub_f32_e32 v100, v100, v48
	v_sub_f32_e32 v101, v101, v48
	v_sub_f32_e32 v132, v132, v48
	v_sub_f32_e32 v133, v133, v48
	v_sub_f32_e32 v102, v102, v48
	v_sub_f32_e32 v103, v103, v48
	v_sub_f32_e32 v134, v134, v48
	v_sub_f32_e32 v135, v135, v48
	v_sub_f32_e32 v104, v104, v48
	v_sub_f32_e32 v105, v105, v48
	v_sub_f32_e32 v136, v136, v48
	v_sub_f32_e32 v137, v137, v48
	v_sub_f32_e32 v106, v106, v48
	v_sub_f32_e32 v107, v107, v48
	v_sub_f32_e32 v138, v138, v48
	v_sub_f32_e32 v139, v139, v48
	v_sub_f32_e32 v108, v108, v48
	v_sub_f32_e32 v109, v109, v48
	v_sub_f32_e32 v140, v140, v48
	v_sub_f32_e32 v141, v141, v48
	v_sub_f32_e32 v110, v110, v48
	v_sub_f32_e32 v111, v111, v48
	v_sub_f32_e32 v142, v142, v48
	v_sub_f32_e32 v143, v143, v48
	v_add_f32_e32 v144, v210, v48
	v_add_f32_e32 v145, v211, v49
	v_mul_f32_e32 v48, v210, v48
	v_mul_f32_e32 v49, v211, v49
	s_waitcnt lgkmcnt(0)
	v_add_u32_e32 v60, s67, v194
	v_mov_b32_e32 v145, v49
	ds_read_b128 v[48:51], v60 offset:49216
	ds_read_b128 v[52:55], v60 offset:49248
	ds_read_b128 v[56:59], v60 offset:49152
	ds_read_b128 v[60:63], v60 offset:49184
	v_pk_add_f32 v[112:113], v[144:145], 0 neg_lo:[1,1] neg_hi:[1,1]
	s_waitcnt lgkmcnt(0)
	v_mov_b64_e32 v[210:211], v[144:145]
	v_mov_b32_e32 v126, v112
	v_mov_b32_e32 v127, v112
	v_mov_b32_e32 v113, v112
	v_mov_b32_e32 v114, v112
	v_mov_b32_e32 v115, v112
	v_mov_b32_e32 v116, v112
	v_mov_b32_e32 v117, v112
	v_mov_b32_e32 v118, v112
	v_mov_b32_e32 v119, v112
	v_mov_b32_e32 v120, v112
	v_mov_b32_e32 v121, v112
	v_mov_b32_e32 v122, v112
	v_mov_b32_e32 v123, v112
	v_mov_b32_e32 v124, v112
	v_mov_b32_e32 v125, v112
	v_mov_b64_e32 v[158:159], v[126:127]
	s_waitcnt lgkmcnt(0)
	v_mul_f32_e32 v28, v28, v52
	v_mul_f32_e32 v29, v29, v53
	v_mul_f32_e32 v24, v24, v48
	v_mul_f32_e32 v25, v25, v49
	v_mul_f32_e32 v20, v20, v60
	v_mul_f32_e32 v21, v21, v61
	v_mul_f32_e32 v30, v30, v54
	v_mul_f32_e32 v31, v31, v55
	v_mul_f32_e32 v26, v26, v50
	v_mul_f32_e32 v27, v27, v51
	v_mul_f32_e32 v22, v22, v62
	v_mul_f32_e32 v23, v23, v63
	v_mul_f32_e32 v18, v18, v58
	v_mul_f32_e32 v19, v19, v59
	v_mul_f32_e32 v16, v16, v56
	v_mul_f32_e32 v17, v17, v57
	v_mul_f32_e32 v12, v12, v52
	v_mul_f32_e32 v13, v13, v53
	v_mul_f32_e32 v8, v8, v48
	v_mul_f32_e32 v9, v9, v49
	v_mul_f32_e32 v4, v4, v60
	v_mul_f32_e32 v5, v5, v61
	v_mul_f32_e32 v14, v14, v54
	v_mul_f32_e32 v15, v15, v55
	v_mul_f32_e32 v10, v10, v50
	v_mul_f32_e32 v11, v11, v51
	v_mul_f32_e32 v6, v6, v62
	v_mul_f32_e32 v7, v7, v63
	v_mul_f32_e32 v2, v2, v58
	v_mul_f32_e32 v3, v3, v59
	v_mul_f32_e32 v0, v0, v56
	v_mul_f32_e32 v1, v1, v57
	v_mov_b32_e32 v62, v112
	v_mov_b32_e32 v61, v112
	v_mov_b32_e32 v60, v112
	v_mov_b32_e32 v59, v112
	v_mov_b32_e32 v58, v112
	v_mov_b32_e32 v57, v112
	v_mov_b32_e32 v56, v112
	v_mov_b32_e32 v55, v112
	v_mov_b32_e32 v54, v112
	v_mov_b32_e32 v53, v112
	v_mov_b32_e32 v52, v112
	v_mov_b32_e32 v51, v112
	v_mov_b32_e32 v50, v112
	v_mov_b32_e32 v49, v112
	v_mov_b32_e32 v48, v112
	v_mov_b64_e32 v[156:157], v[124:125]
	v_mov_b64_e32 v[154:155], v[122:123]
	v_mov_b64_e32 v[152:153], v[120:121]
	v_mov_b64_e32 v[150:151], v[118:119]
	v_mov_b64_e32 v[148:149], v[116:117]
	v_mov_b64_e32 v[146:147], v[114:115]
	v_mov_b64_e32 v[144:145], v[112:113]
	s_branch .LBB0_774

.LBB0_774:
	v_add_u32_e32 v63, s14, v222
	v_mov_b32_e32 v113, 0
	v_mov_b32_e32 v126, 0
	v_add_u32_e32 v122, v63, v113
	ds_read_b128 v[114:117], v122
	ds_read_b128 v[122:125], v122 offset:512
	v_add3_u32 v113, v219, v113, s15
	ds_read_b128 v[118:121], v113
	v_mov_b64_e32 v[174:175], v[94:95]
	v_add_u32_e32 v113, v63, v126
	ds_read_b128 v[226:229], v113 offset:2048
	s_waitcnt lgkmcnt(0)
	v_mfma_f32_32x32x16_bf16 v[176:191], v[114:117], v[118:121], v[80:95]
	ds_read_b128 v[238:241], v113 offset:2560
	v_mov_b64_e32 v[172:173], v[92:93]
	v_mov_b64_e32 v[170:171], v[90:91]
	v_mov_b64_e32 v[168:169], v[88:89]
	v_mov_b64_e32 v[166:167], v[86:87]
	v_mov_b64_e32 v[164:165], v[84:85]
	v_mov_b64_e32 v[162:163], v[82:83]
	v_mov_b64_e32 v[160:161], v[80:81]
	v_add3_u32 v113, v219, v126, s18
	v_exp_f32_e32 v231, v98
	v_mfma_f32_32x32x16_bf16 v[160:175], v[122:125], v[118:121], v[160:175]
	ds_read_b128 v[116:119], v113
	v_mov_b32_e32 v98, 0
	v_exp_f32_e32 v234, v99
	v_exp_f32_e32 v122, v128
	v_add_u32_e32 v99, v63, v98
	v_add3_u32 v98, v219, v98, s19
	s_waitcnt lgkmcnt(0)
	v_mfma_f32_32x32x16_bf16 v[176:191], v[226:229], v[116:119], v[176:191]
	ds_read_b128 v[124:127], v99 offset:4096
	v_exp_f32_e32 v123, v129
	v_exp_f32_e32 v235, v130
	v_exp_f32_e32 v237, v131
	v_exp_f32_e32 v113, v100
	v_exp_f32_e32 v223, v101
	v_exp_f32_e32 v233, v102
	v_mfma_f32_32x32x16_bf16 v[160:175], v[238:241], v[116:119], v[160:175]
	ds_read_b128 v[116:119], v99 offset:4608
	ds_read_b128 v[128:131], v98
	v_mov_b32_e32 v99, 0
	v_exp_f32_e32 v238, v103
	v_add_u32_e32 v115, v63, v99
	v_add3_u32 v99, v219, v99, s22
	s_waitcnt lgkmcnt(0)
	v_mfma_f32_32x32x16_bf16 v[176:191], v[124:127], v[128:131], v[176:191]
	ds_read_b128 v[100:103], v115 offset:6144
	v_exp_f32_e32 v120, v96
	v_exp_f32_e32 v121, v97
	v_cvt_pk_bf16_f32 v97, v231, v234
	v_cvt_pk_bf16_f32 v98, v113, v223
	v_exp_f32_e32 v241, v104
	v_cvt_pk_bf16_f32 v96, v120, v121
	v_mfma_f32_32x32x16_bf16 v[160:175], v[116:119], v[128:131], v[160:175]
	ds_read_b128 v[116:119], v115 offset:6656
	ds_read_b128 v[124:127], v99
	v_cvt_pk_bf16_f32 v99, v233, v238
	v_exp_f32_e32 v242, v105
	v_exp_f32_e32 v249, v106
	v_exp_f32_e32 v250, v107
	v_exp_f32_e32 v246, v108
	s_waitcnt lgkmcnt(0)
	v_mfma_f32_32x32x16_bf16 v[176:191], v[100:103], v[124:127], v[176:191]
	v_exp_f32_e32 v248, v109
	v_exp_f32_e32 v243, v110
	v_exp_f32_e32 v244, v111
	v_cvt_pk_bf16_f32 v104, v241, v242
	v_cvt_pk_bf16_f32 v105, v249, v250
	v_cvt_pk_bf16_f32 v106, v246, v248
	v_cvt_pk_bf16_f32 v107, v243, v244
	v_mfma_f32_32x32x16_bf16 v[160:175], v[116:119], v[124:127], v[160:175]
	ds_read_b128 v[116:119], v63 offset:8192
	v_exp_f32_e32 v232, v132
	v_exp_f32_e32 v236, v133
	v_exp_f32_e32 v239, v134
	v_exp_f32_e32 v240, v135
	v_cvt_pk_bf16_f32 v114, v122, v123
	v_cvt_pk_bf16_f32 v115, v235, v237
	s_waitcnt lgkmcnt(0)
	v_mfma_f32_32x32x16_bf16 v[16:31], v[96:99], v[116:119], v[16:31]
	ds_read_b128 v[108:111], v63 offset:10240
	v_cvt_pk_bf16_f32 v116, v232, v236
	v_cvt_pk_bf16_f32 v117, v239, v240
	v_exp_f32_e32 v245, v136
	v_exp_f32_e32 v247, v137
	v_exp_f32_e32 v227, v138
	v_exp_f32_e32 v228, v139
	s_waitcnt lgkmcnt(0)
	v_mfma_f32_32x32x16_bf16 v[16:31], v[104:107], v[108:111], v[16:31]
	ds_read_b128 v[108:111], v63 offset:12288
	v_exp_f32_e32 v225, v140
	v_exp_f32_e32 v226, v141
	v_exp_f32_e32 v251, v142
	v_exp_f32_e32 v230, v143
	v_cvt_pk_bf16_f32 v128, v245, v247
	v_cvt_pk_bf16_f32 v129, v227, v228
	s_waitcnt lgkmcnt(0)
	v_mfma_f32_32x32x16_bf16 v[16:31], v[114:117], v[108:111], v[16:31]
	ds_read_b128 v[108:111], v63 offset:14336
	v_cvt_pk_bf16_f32 v130, v225, v226
	v_cvt_pk_bf16_f32 v131, v251, v230
	s_waitcnt lgkmcnt(0)
	s_nop 0
	v_mfma_f32_32x32x16_bf16 v[16:31], v[128:131], v[108:111], v[16:31]
	ds_read_b128 v[108:111], v63 offset:8704
	s_waitcnt lgkmcnt(0)
	v_mfma_f32_32x32x16_bf16 v[0:15], v[96:99], v[108:111], v[0:15]
	ds_read_b128 v[96:99], v63 offset:10752
	s_waitcnt lgkmcnt(0)
	v_mfma_f32_32x32x16_bf16 v[0:15], v[104:107], v[96:99], v[0:15]
	ds_read_b128 v[96:99], v63 offset:12800
	s_waitcnt lgkmcnt(0)
	v_mfma_f32_32x32x16_bf16 v[0:15], v[114:117], v[96:99], v[0:15]
	ds_read_b128 v[96:99], v63 offset:14848
	s_waitcnt lgkmcnt(0)
	v_mfma_f32_32x32x16_bf16 v[0:15], v[128:131], v[96:99], v[0:15]
	v_maximum3_f32 v96, v176, v160, v160
	v_maximum3_f32 v97, v161, v178, v162
	v_maximum3_f32 v96, v96, v177, v179
	v_maximum3_f32 v97, v97, v180, v164
	v_maximum3_f32 v96, v96, v163, v181
	v_maximum3_f32 v97, v97, v182, v166
	v_maximum3_f32 v96, v96, v165, v183
	v_maximum3_f32 v97, v97, v184, v168
	v_maximum3_f32 v96, v96, v167, v185
	v_maximum3_f32 v97, v97, v186, v170
	v_maximum3_f32 v96, v96, v169, v187
	v_maximum3_f32 v97, v97, v188, v172
	v_maximum3_f32 v96, v96, v171, v189
	v_maximum3_f32 v97, v97, v190, v174
	v_maximum3_f32 v96, v96, v173, v191
	v_maximum3_f32 v96, v96, v175, v97
	v_mov_b32_e32 v97, v96
	s_nop 1
	v_permlane32_swap_b32_e32 v96, v97
	v_maximum3_f32 v96, v96, v97, v97
	v_cmp_lt_f32_e32 vcc, s46, v96
	s_cbranch_vccz .LBB0_778
	v_max_f32_e32 v80, v96, v96
	v_max_f32_e32 v80, 0, v80
	v_exp_f32_e64 v81, -v80
	s_and_saveexec_b64 s[6:7], s[38:39]
	ds_write_b32 v209, v81 offset:49152
	s_or_b64 exec, exec, s[6:7]
	v_mul_f32_e32 v92, v212, v80
	v_mul_f32_e32 v93, v213, v81
	s_waitcnt lgkmcnt(0)
	v_sub_f32_e32 v176, v176, v80
	v_sub_f32_e32 v177, v177, v80
	v_add_u32_e32 v92, s67, v194
	v_sub_f32_e32 v160, v160, v80
	v_sub_f32_e32 v161, v161, v80
	v_sub_f32_e32 v178, v178, v80
	v_sub_f32_e32 v179, v179, v80
	v_sub_f32_e32 v162, v162, v80
	v_sub_f32_e32 v163, v163, v80
	v_sub_f32_e32 v180, v180, v80
	v_sub_f32_e32 v181, v181, v80
	v_sub_f32_e32 v164, v164, v80
	v_sub_f32_e32 v165, v165, v80
	v_sub_f32_e32 v182, v182, v80
	v_sub_f32_e32 v183, v183, v80
	v_sub_f32_e32 v166, v166, v80
	v_sub_f32_e32 v167, v167, v80
	v_sub_f32_e32 v184, v184, v80
	v_sub_f32_e32 v185, v185, v80
	v_sub_f32_e32 v168, v168, v80
	v_sub_f32_e32 v169, v169, v80
	v_sub_f32_e32 v186, v186, v80
	v_sub_f32_e32 v187, v187, v80
	v_sub_f32_e32 v170, v170, v80
	v_sub_f32_e32 v171, v171, v80
	v_sub_f32_e32 v188, v188, v80
	v_sub_f32_e32 v189, v189, v80
	v_sub_f32_e32 v172, v172, v80
	v_sub_f32_e32 v173, v173, v80
	v_sub_f32_e32 v190, v190, v80
	v_sub_f32_e32 v191, v191, v80
	v_sub_f32_e32 v174, v174, v80
	v_sub_f32_e32 v175, v175, v80
	v_add_f32_e32 v126, v212, v80
	v_add_f32_e32 v127, v213, v81
	ds_read_b128 v[80:83], v92 offset:49216
	ds_read_b128 v[84:87], v92 offset:49248
	ds_read_b128 v[88:91], v92 offset:49152
	ds_read_b128 v[96:99], v92 offset:49184
	v_mov_b32_e32 v127, v93
	s_waitcnt lgkmcnt(0)
	v_pk_add_f32 v[94:95], v[126:127], 0 neg_lo:[1,1] neg_hi:[1,1]
	s_waitcnt lgkmcnt(0)
	v_mul_f32_e32 v76, v76, v84
	v_mul_f32_e32 v77, v77, v85
	v_mul_f32_e32 v72, v72, v80
	v_mul_f32_e32 v73, v73, v81
	v_mul_f32_e32 v68, v68, v96
	v_mul_f32_e32 v69, v69, v97
	v_mul_f32_e32 v78, v78, v86
	v_mul_f32_e32 v79, v79, v87
	v_mul_f32_e32 v74, v74, v82
	v_mul_f32_e32 v75, v75, v83
	v_mul_f32_e32 v70, v70, v98
	v_mul_f32_e32 v71, v71, v99
	v_mul_f32_e32 v66, v66, v90
	v_mul_f32_e32 v67, v67, v91
	v_mul_f32_e32 v64, v64, v88
	v_mul_f32_e32 v65, v65, v89
	v_mul_f32_e32 v44, v44, v84
	v_mul_f32_e32 v45, v45, v85
	v_mul_f32_e32 v40, v40, v80
	v_mul_f32_e32 v41, v41, v81
	v_mul_f32_e32 v36, v36, v96
	v_mul_f32_e32 v37, v37, v97
	v_mul_f32_e32 v46, v46, v86
	v_mul_f32_e32 v47, v47, v87
	v_mul_f32_e32 v42, v42, v82
	v_mul_f32_e32 v43, v43, v83
	v_mul_f32_e32 v38, v38, v98
	v_mul_f32_e32 v39, v39, v99
	v_mul_f32_e32 v34, v34, v90
	v_mul_f32_e32 v35, v35, v91
	v_mul_f32_e32 v32, v32, v88
	v_mul_f32_e32 v33, v33, v89
	v_mov_b32_e32 v212, v126
	v_mov_b32_e32 v95, v94
	v_mov_b32_e32 v93, v94
	v_mov_b32_e32 v92, v94
	v_mov_b32_e32 v91, v94
	v_mov_b32_e32 v90, v94
	v_mov_b32_e32 v89, v94
	v_mov_b32_e32 v88, v94
	v_mov_b32_e32 v87, v94
	v_mov_b32_e32 v86, v94
	v_mov_b32_e32 v85, v94
	v_mov_b32_e32 v84, v94
	v_mov_b32_e32 v83, v94
	v_mov_b32_e32 v82, v94
	v_mov_b32_e32 v81, v94
	v_mov_b32_e32 v80, v94
	s_branch .LBB0_779

; #define ATT_SYNC() do { asm volatile("s_waitcnt vmcnt(0)" ::: "memory"); __syncthreads(); } while (0)
; template <int NS, int DQK, int DV, bool KSH  > ...
;     ...
;         for (int t = tlo; t < thi; ++t) {
;             if (t + 2 < thi) ATT_DMA(t + 2, bnn);
;             ATT_MAX(pA0, pA1, 0, t == tlo);
;             ATT_QKEXP(pB0, pB1, NS - 1, bc, pA0, pA1, 0);
;             ATT_PV(0, bc);
;             ATT_MAX(pB0, pB1, NS - 1, t == tlo);
;             ATT_QKEXP(pA0, pA1, 0, bn, pB0, pB1, NS - 1);
;             ATT_PV(NS - 1, bc);
;             ATT_SYNC();
;             const int tmp = bc; bc = bn; bn = bnn; bnn = tmp;
;         }
.LBB0_779:
	v_add_u32_e32 v213, s11, v222
	v_mov_b32_e32 v96, 0
	v_mov_b32_e32 v124, 0
	v_add_u32_e32 v97, v213, v96
	ds_read_b128 v[114:117], v97
	ds_read_b128 v[132:135], v97 offset:512
	v_add_u32_e32 v96, v219, v96
	ds_read_b128 v[128:131], v96 offset:51200
	v_exp_f32_e32 v125, v176
	v_add_u32_e32 v118, v213, v124
	ds_read_b128 v[136:139], v118 offset:2048
	s_waitcnt lgkmcnt(0)
	v_mfma_f32_32x32x16_bf16 v[96:111], v[114:117], v[128:131], v[144:159]
	ds_read_b128 v[116:119], v118 offset:2560
	v_add_u32_e32 v114, v219, v124
	v_exp_f32_e32 v124, v178
	v_add_f32_e32 v140, v121, v120
	v_add_f32_e32 v141, v123, v122
	v_exp_f32_e32 v229, v166
	v_exp_f32_e32 v224, v167
	v_mfma_f32_32x32x16_bf16 v[144:159], v[132:135], v[128:131], v[144:159]
	v_exp_f32_e32 v133, v177
	v_exp_f32_e32 v129, v160
	v_exp_f32_e32 v131, v161
	v_exp_f32_e32 v132, v179
	v_exp_f32_e32 v128, v162
	v_exp_f32_e32 v130, v163
	ds_read_b128 v[120:123], v114 offset:59392
	v_add_f32_e32 v134, v132, v124
	v_add_f32_e32 v135, v133, v125
	s_waitcnt lgkmcnt(0)
	v_mfma_f32_32x32x16_bf16 v[96:111], v[136:139], v[120:123], v[96:111]
	v_add_f32_e64 v142, v130, v128
	v_add_f32_e64 v143, v131, v129
	v_mov_b32_e32 v136, 0
	v_add_f32_e64 v134, v142, v134
	v_add_f32_e64 v135, v143, v135
	v_cvt_pk_bf16_f32 v114, v125, v133
	v_add_f32_e32 v115, 0, v135
	v_add_f32_e32 v143, v134, v115
	v_cvt_pk_bf16_f32 v115, v124, v132
	v_exp_f32_e32 v133, v180
	v_add_u32_e32 v124, v213, v136
	v_exp_f32_e32 v135, v181
	v_exp_f32_e32 v132, v164
	v_exp_f32_e32 v134, v165
	ds_read_b128 v[160:163], v124 offset:4096
	v_mfma_f32_32x32x16_bf16 v[144:159], v[116:119], v[120:123], v[144:159]
	ds_read_b128 v[122:125], v124 offset:4608
	v_add3_u32 v116, v219, v136, s45
	ds_read_b128 v[176:179], v116
	v_add_f32_e64 v116, v134, v132
	v_add_f32_e64 v117, v135, v133
	v_exp_f32_e32 v118, v182
	v_exp_f32_e32 v119, v183
	v_add_f32_e32 v166, v116, v116
	v_add_f32_e32 v167, v116, v117
	v_exp_f32_e32 v142, v184
	v_exp_f32_e32 v166, v185
	v_exp_f32_e32 v136, v168
	v_exp_f32_e32 v138, v169
	v_mov_b32_e32 v200, 0
	v_exp_f32_e32 v181, v186
	v_exp_f32_e32 v183, v187
	v_exp_f32_e32 v180, v170
	v_exp_f32_e32 v182, v171
	v_cvt_pk_bf16_f32 v116, v133, v135
	v_add_f32_e32 v137, v119, v118
	v_add_f32_e32 v139, v224, v229
	v_cvt_pk_bf16_f32 v117, v118, v119
	v_add_u32_e32 v133, v213, v200
	s_waitcnt lgkmcnt(0)
	v_mfma_f32_32x32x16_bf16 v[96:111], v[160:163], v[176:179], v[96:111]
	ds_read_b128 v[118:121], v133 offset:6144
	v_add_f32_e64 v160, v166, v142
	v_add_f32_e64 v161, v167, v143
	v_add_f32_e64 v162, v138, v136
	v_add_f32_e64 v163, v139, v137
	v_exp_f32_e32 v185, v188
	v_add_f32_e32 v160, v162, v160
	v_add_f32_e32 v161, v163, v161
	v_exp_f32_e32 v187, v189
	v_add_f32_e32 v164, v160, v160
	v_add_f32_e32 v165, v160, v161
	v_mfma_f32_32x32x16_bf16 v[144:159], v[122:125], v[176:179], v[144:159]
	ds_read_b128 v[122:125], v133 offset:6656
	ds_read_b128 v[168:171], v63 offset:8704
	v_cvt_pk_bf16_f32 v160, v142, v166
	v_add_f32_e64 v142, v182, v180
	v_add_f32_e64 v143, v183, v181
	v_exp_f32_e32 v164, v190
	v_add_f32_e32 v166, v142, v142
	v_add_f32_e32 v167, v142, v143
	v_exp_f32_e32 v166, v191
	s_waitcnt lgkmcnt(0)
	v_mfma_f32_32x32x16_bf16 v[32:47], v[114:117], v[168:171], v[32:47]
	ds_read_b128 v[176:179], v63 offset:10752
	v_cvt_pk_bf16_f32 v161, v181, v183
	v_cvt_pk_bf16_f32 v162, v185, v187
	v_cvt_pk_bf16_f32 v163, v164, v166
	v_cvt_pk_bf16_f32 v168, v129, v131
	v_cvt_pk_bf16_f32 v169, v128, v130
	v_cvt_pk_bf16_f32 v170, v132, v134
	s_waitcnt lgkmcnt(0)
	v_mfma_f32_32x32x16_bf16 v[32:47], v[160:163], v[176:179], v[32:47]
	ds_read_b128 v[128:131], v63 offset:12800
	v_cvt_pk_bf16_f32 v171, v229, v224
	v_exp_f32_e32 v181, v172
	v_exp_f32_e32 v183, v173
	v_exp_f32_e32 v184, v174
	v_exp_f32_e32 v186, v175
	v_cvt_pk_bf16_f32 v176, v136, v138
	s_waitcnt lgkmcnt(0)
	v_mfma_f32_32x32x16_bf16 v[32:47], v[168:171], v[128:131], v[32:47]
	ds_read_b128 v[132:135], v63 offset:14848
	v_cvt_pk_bf16_f32 v177, v180, v182
	v_cvt_pk_bf16_f32 v178, v181, v183
	v_cvt_pk_bf16_f32 v179, v184, v186
	v_add_f32_e32 v129, v234, v231
	v_add_f32_e32 v130, v237, v235
	v_add_f32_e32 v129, v130, v129
	v_add3_u32 v130, v219, v200, s58
	s_waitcnt lgkmcnt(0)
	v_mfma_f32_32x32x16_bf16 v[32:47], v[176:179], v[132:135], v[32:47]
	ds_read_b128 v[172:175], v130
	v_add_f32_e32 v128, v141, v140
	v_add_f32_e32 v128, 0, v128
	v_add_f32_e32 v128, v129, v128
	v_add_f32_e32 v113, v223, v113
	v_add_f32_e32 v129, v236, v232
	v_add_f32_e32 v113, v129, v113
	s_waitcnt lgkmcnt(0)
	v_mfma_f32_32x32x16_bf16 v[96:111], v[118:121], v[172:175], v[96:111]
	v_add_f32_e32 v118, v238, v233
	v_add_f32_e32 v119, v240, v239
	v_add_f32_e32 v113, v113, v128
	v_add_f32_e32 v118, v119, v118
	v_add_f32_e32 v113, v118, v113
	ds_read_b128 v[118:121], v63 offset:8192
	v_mov_b64_e32 v[128:129], v[144:145]
	v_mov_b64_e32 v[130:131], v[146:147]
	v_mov_b64_e32 v[132:133], v[148:149]
	v_mov_b64_e32 v[134:135], v[150:151]
	v_mov_b64_e32 v[136:137], v[152:153]
	v_mov_b64_e32 v[138:139], v[154:155]
	v_mov_b64_e32 v[140:141], v[156:157]
	v_mov_b64_e32 v[142:143], v[158:159]
	v_add_f32_e32 v144, v250, v249
	v_add_f32_e32 v145, v228, v227
	v_mfma_f32_32x32x16_bf16 v[128:143], v[122:125], v[172:175], v[128:143]
	v_add_f32_e32 v122, v242, v241
	v_add_f32_e32 v123, v247, v245
	v_add_f32_e32 v122, v123, v122
	v_add_f32_e32 v113, v122, v113
	ds_read_b128 v[122:125], v63 offset:10240
	v_add_f32_e32 v185, v187, v185
	v_add_f32_e32 v187, v183, v181
	s_waitcnt lgkmcnt(0)
	v_mfma_f32_32x32x16_bf16 v[64:79], v[114:117], v[118:121], v[64:79]
	v_add_f32_e32 v114, v145, v144
	v_add_f32_e32 v113, v114, v113
	v_add_f32_e32 v114, v248, v246
	v_add_f32_e32 v115, v226, v225
	v_add_f32_e32 v114, v115, v114
	v_add_f32_e32 v113, v114, v113
	ds_read_b128 v[114:117], v63 offset:12288
	v_mfma_f32_32x32x16_bf16 v[64:79], v[160:163], v[122:125], v[64:79]
	v_add_f32_e32 v118, v244, v243
	v_add_f32_e32 v119, v230, v251
	v_add_f32_e32 v118, v119, v118
	v_add_f32_e32 v113, v118, v113
	ds_read_b128 v[118:121], v63 offset:14336
	s_waitcnt vmcnt(0)
	s_add_i32 s13, s13, 1
	s_waitcnt lgkmcnt(0)
	v_mfma_f32_32x32x16_bf16 v[64:79], v[168:171], v[114:117], v[64:79]
	v_add_f32_e64 v114, v166, v164
	v_add_f32_e64 v115, v167, v165
	v_add_f32_e64 v116, v186, v184
	v_add_f32_e64 v117, v187, v185
	s_add_i32 s12, s12, 64
	v_add_f32_e32 v114, v116, v114
	v_add_f32_e32 v115, v117, v115
	v_add_f32_e32 v211, v211, v113
	v_pk_add_f32 v[114:115], v[114:115], v[114:115] op_sel:[0,1] op_sel_hi:[1,0]
	s_cmpk_eq_i32 s13, 0x83
	v_mfma_f32_32x32x16_bf16 v[64:79], v[176:179], v[118:121], v[64:79]
	v_add_f32_e64 v114, v127, v114
	v_add_f32_e64 v115, v126, v115
	s_waitcnt vmcnt(0)
	s_barrier
	s_cbranch_scc1 .LBB0_831
	s_mov_b32 s6, s11
	s_mov_b32 s11, s9
	s_mov_b32 s9, s14
	v_mov_b32_e32 v213, v114
	s_cmpk_gt_u32 s13, 0x80
	s_mov_b32 s14, s6
	s_cbranch_scc0 .LBB0_765
	s_branch .LBB0_769

; #define LAS __attribute__((address_space(3)))
; __device__ __forceinline__ int opaque_tid() { int t = threadIdx.x; asm volatile("" : "+v"(t)); return t; }
; __device__ __forceinline__ int pi16(int t) { return (t & ~12) | ((t & 8) >> 1) | ((t & 4) << 1); }
; template <int NS, int DQK, int DV, bool KSH  > ...
;     ...
;     const int tid = opaque_tid(), lane = tid & 63, r32 = lane & 31, hi = lane >> 5; const int wid = __builtin_amdgcn_readfirstlane(tid >> 6);
;     LAS float* wsf = (LAS float*)(lds + 3 * BUFB) + wid * 64;
;     int kg[NKL]; int vg[NVL];
; #pragma unroll
;     for (int i = 0; i < NKL; ++i) { const int cck = wid + i * NWAVES; const int c2 = cck < NKW ? cck : 0; const int c = c2 / CK, ck = c2 % CK; kg[i] = c * sstride + pi16(lane) * DQK + ck * 8; }
; #pragma unroll
;     for (int i = 0; i < NVL; ++i) { const int idx = tid + i * NTHREADS; const int id2 = idx < NVP ? idx : 0; const int c8 = id2 / DV, d = id2 % DV; vg[i] = d * R + c8 * 8; }
;     auto tokbase = [&](int t) -> int { return t < 128 ? bidx * SEQ + 64 * t : RL + bidx * CTXL + 64 * (t - 128); };
;     ...
;     constexpr bool QLDS = (NS > 1);
;     LAS unsigned char* qlds = lds + 3 * BUFB + 2048 + wid * 1024 + lane * 16;
;     bf16x8 qr[QLDS ? 1 : NS][QLDS ? 1 : KS];
; #pragma unroll
;     for (int c = 0; c < NS; ++c)
; #pragma unroll
;         for (int d0 = 0; d0 < KS; ++d0) {
;             const bf16x8 qv = *(const bf16x8*)(Qh0 + (size_t)c * sstride + (size_t)(qrow0 + wid * 32 + r32) * DQK + d0 * 16 + hi * 8);
;             if constexpr (QLDS) *(LAS bf16x8*)(qlds + (c * KS + d0) * 8192) = qv; else qr[c][d0] = qv;
;         }
.LBB0_783:
	s_bfe_u32 s58, s56, 0x20005
	s_ashr_i32 s42, s56, 7
	s_mul_i32 s5, s58, 0x318000
	s_add_u32 s0, s52, s5
	s_addc_u32 s1, s53, 0
	s_add_u32 s68, s50, s5
	s_addc_u32 s69, s51, 0
	s_lshl_b32 s5, s56, 8
	v_mov_b32_e32 v0, v192
	s_lshl_b32 s70, s42, 13
	s_and_b32 s5, s5, 0x1f00
	s_or_b32 s56, s70, s5
	v_readfirstlane_b32 s43, v0
	s_ashr_i32 s59, s43, 6
	s_cmp_lt_i32 s59, 12
	s_cselect_b64 s[6:7], -1, 0
	v_and_b32_e32 v208, 31, v0
	s_and_b64 s[8:9], s[6:7], exec
	s_cselect_b32 s5, s59, 0
	s_lshl_b32 s57, s59, 5
	v_or_b32_e32 v1, s56, v208
	v_bfe_u32 v191, v0, 5, 1
	v_add_u32_e32 v1, s57, v1
	v_mov_b64_e32 v[2:3], s[0:1]
	v_mad_i64_i32 v[2:3], s[0:1], v1, s61, v[2:3]
	v_lshlrev_b32_e32 v194, 4, v191
	v_lshl_add_u64 v[10:11], v[2:3], 0, v[194:195]
	v_add_co_u32_e32 v22, vcc, 0xc60000, v10
	global_load_dwordx4 v[2:5], v[10:11], off
	global_load_dwordx4 v[6:9], v[10:11], off offset:32
	v_addc_co_u32_e32 v23, vcc, 0, v11, vcc
	global_load_dwordx4 v[10:13], v[10:11], off offset:64
	s_nop 0
	global_load_dwordx4 v[14:17], v[22:23], off
	global_load_dwordx4 v[18:21], v[22:23], off offset:32
	s_nop 0
	global_load_dwordx4 v[22:25], v[22:23], off offset:64
	v_lshrrev_b32_e32 v26, 1, v0
	v_lshlrev_b32_e32 v27, 1, v0
	s_mul_hi_i32 s0, s5, 0x2aaaaaab
	v_and_b32_e32 v1, 51, v0
	v_and_b32_e32 v26, 4, v26
	v_and_b32_e32 v27, 8, v27
	s_lshl_b32 s66, s59, 10
	s_lshr_b32 s1, s0, 31
	v_and_b32_e32 v190, 63, v0
	v_or3_b32 v1, v26, v1, v27
	s_add_i32 s71, s66, 0
	s_add_i32 s0, s0, s1
	v_mul_u32_u24_e32 v1, 48, v1
	v_lshl_add_u32 v26, v190, 4, s71
	s_mul_i32 s1, s0, 6
	s_mul_i32 s0, s0, 0x630000
	v_add_u32_e32 v209, 0x12800, v26
	s_sub_i32 s1, s5, s1
	v_or_b32_e32 v26, s0, v1
	s_cmp_gt_i32 s59, 11
	v_lshl_add_u32 v210, s1, 3, v26
	s_mul_i32 s0, s42, 0x60000
	s_waitcnt vmcnt(5)
	ds_write_b128 v209, v[2:5]
	s_waitcnt vmcnt(4)
	ds_write_b128 v209, v[6:9] offset:8192
	s_waitcnt vmcnt(3)
	ds_write_b128 v209, v[10:13] offset:16384
	s_waitcnt vmcnt(2)
	ds_write_b128 v209, v[14:17] offset:24576
	s_waitcnt vmcnt(1)
	ds_write_b128 v209, v[18:21] offset:32768
	s_waitcnt vmcnt(0)
	ds_write_b128 v209, v[22:25] offset:40960
	s_cbranch_scc1 .LBB0_785
	v_add_u32_e32 v2, s0, v210
	v_ashrrev_i32_e32 v3, 31, v2
	v_lshl_add_u64 v[2:3], v[2:3], 1, s[68:69]
	s_mov_b32 m0, s71
	s_nop 0
	global_load_lds_dwordx4 v[2:3], off

; template <int NS, int DQK, int DV, bool KSH  > ...
;     ...
;         for (int t = tlo; t < thi; ++t) {
;             if (t + 2 < thi) ATT_DMA(t + 2, bnn);
;             ATT_MAX(pA0, pA1, 0, t == tlo);
;             ATT_QKEXP(pB0, pB1, NS - 1, bc, pA0, pA1, 0);
;             ATT_PV(0, bc);
;             ATT_MAX(pB0, pB1, NS - 1, t == tlo);
;             ATT_QKEXP(pA0, pA1, 0, bn, pB0, pB1, NS - 1);
;             ATT_PV(NS - 1, bc);
.LBB0_802:
	s_nop 2
	v_maximum3_f32 v33, v0, v16, v16
	v_maximum3_f32 v34, v17, v2, v18
	v_maximum3_f32 v33, v33, v1, v3
	v_maximum3_f32 v34, v34, v4, v20
	v_maximum3_f32 v33, v33, v19, v5
	v_maximum3_f32 v34, v34, v6, v22
	v_maximum3_f32 v33, v33, v21, v7
	v_maximum3_f32 v34, v34, v8, v24
	v_maximum3_f32 v33, v33, v23, v9
	v_maximum3_f32 v34, v34, v10, v26
	v_maximum3_f32 v33, v33, v25, v11
	v_maximum3_f32 v34, v34, v12, v28
	v_maximum3_f32 v33, v33, v27, v13
	v_maximum3_f32 v34, v34, v14, v30
	v_maximum3_f32 v33, v33, v29, v15
	v_maximum3_f32 v33, v33, v31, v34
	v_mov_b32_e32 v34, v33
	s_nop 1
	v_permlane32_swap_b32_e32 v33, v34
	v_maximum3_f32 v116, v33, v34, v34
	v_sub_f32_e32 v83, v8, v116
	v_mov_b32_e32 v8, v195
	v_sub_f32_e32 v45, v4, v116
	v_sub_f32_e32 v41, v24, v116
	v_add_u32_e32 v4, v212, v8
	v_sub_f32_e32 v42, v25, v116
	v_sub_f32_e32 v24, v0, v116
	v_sub_f32_e32 v25, v1, v116
	v_sub_f32_e32 v43, v2, v116
	v_sub_f32_e32 v44, v3, v116
	ds_read_b128 v[0:3], v4 offset:6144
	v_sub_f32_e32 v46, v5, v116
	v_sub_f32_e32 v47, v6, v116
	v_sub_f32_e32 v82, v7, v116
	ds_read_b128 v[4:7], v4 offset:6656
	v_add_u32_e32 v8, v209, v8
	v_sub_f32_e32 v33, v16, v116
	v_sub_f32_e32 v34, v17, v116
	v_sub_f32_e32 v35, v18, v116
	v_sub_f32_e32 v36, v19, v116
	ds_read_b128 v[16:19], v8 offset:24576
	v_mov_b32_e32 v8, v195
	s_mov_b32 s18, s4
	s_mov_b32 s19, s4
	v_sub_f32_e32 v92, v9, v116
	s_mov_b32 s5, s4
	v_add_u32_e32 v9, v212, v8
	s_mov_b32 s6, s4
	s_mov_b32 s7, s4
	s_mov_b32 s8, s4
	s_mov_b32 s9, s4
	s_mov_b32 s10, s4
	s_mov_b32 s11, s4
	s_mov_b32 s12, s4
	s_mov_b32 s13, s4
	s_mov_b32 s14, s4
	s_mov_b32 s15, s4
	s_mov_b32 s16, s4
	s_mov_b32 s17, s4
	v_mov_b64_e32 v[78:79], s[18:19]
	v_sub_f32_e32 v37, v20, v116
	v_sub_f32_e32 v38, v21, v116
	v_sub_f32_e32 v39, v22, v116
	v_sub_f32_e32 v40, v23, v116
	ds_read_b128 v[20:23], v9 offset:8192
	v_mov_b64_e32 v[76:77], s[16:17]
	v_mov_b64_e32 v[74:75], s[14:15]
	v_mov_b64_e32 v[72:73], s[12:13]
	v_mov_b64_e32 v[70:71], s[10:11]
	v_mov_b64_e32 v[68:69], s[8:9]
	v_mov_b64_e32 v[66:67], s[6:7]
	v_mov_b64_e32 v[64:65], s[4:5]
	v_sub_f32_e32 v93, v10, v116
	v_sub_f32_e32 v94, v11, v116
	s_waitcnt lgkmcnt(0)
	v_mfma_f32_32x32x16_bf16 v[48:63], v[0:3], v[16:19], v[64:79]
	v_sub_f32_e32 v95, v12, v116
	v_sub_f32_e32 v96, v13, v116
	v_sub_f32_e32 v97, v14, v116
	v_sub_f32_e32 v98, v15, v116
	ds_read_b128 v[0:3], v9 offset:8704
	v_exp_f32_e32 v11, v24
	v_exp_f32_e32 v13, v25
	v_mfma_f32_32x32x16_bf16 v[64:79], v[4:7], v[16:19], v[64:79]
	v_exp_f32_e32 v15, v33
	v_exp_f32_e32 v17, v34
	v_exp_f32_e32 v10, v43
	v_exp_f32_e32 v12, v44
	v_exp_f32_e32 v14, v35
	v_exp_f32_e32 v16, v36
	v_add_u32_e32 v8, v209, v8
	ds_read_b128 v[4:7], v8 offset:32768
	v_add_f32_e32 v18, v12, v10
	v_add_f32_e32 v19, v13, v11
	v_add_f32_e32 v24, v16, v14
	v_add_f32_e32 v25, v17, v15
	v_cvt_pk_bf16_f32 v80, v15, v17
	v_add_f32_e32 v18, v24, v18
	v_add_f32_e32 v19, v25, v19
	s_waitcnt lgkmcnt(0)
	v_mfma_f32_32x32x16_bf16 v[48:63], v[20:23], v[4:7], v[48:63]
	v_add_f32_e32 v9, 0, v19
	v_add_f32_e32 v17, v18, v9
	v_exp_f32_e32 v19, v45
	v_exp_f32_e32 v21, v46
	v_exp_f32_e32 v18, v37
	v_exp_f32_e32 v20, v38
	v_cvt_pk_bf16_f32 v9, v10, v12
	v_mov_b32_e32 v10, v195
	v_cvt_pk_bf16_f32 v8, v11, v13
	v_cvt_pk_bf16_f32 v81, v14, v16
	v_add_u32_e32 v11, v212, v10
	ds_read_b128 v[12:15], v11 offset:10240
	v_mfma_f32_32x32x16_bf16 v[64:79], v[0:3], v[4:7], v[64:79]
	v_add_u32_e32 v0, v209, v10
	ds_read_b128 v[84:87], v11 offset:10752
	ds_read_b128 v[88:91], v0 offset:40960
	v_add_f32_e64 v0, v20, v18
	v_add_f32_e64 v1, v21, v19
	v_exp_f32_e32 v2, v47
	v_add_f32_e32 v1, v0, v1
	v_add_f32_e32 v0, v0, v0
	v_exp_f32_e32 v3, v82
	v_cvt_pk_bf16_f32 v10, v19, v21
	v_exp_f32_e32 v19, v39
	v_exp_f32_e32 v21, v40
	v_exp_f32_e32 v16, v83
	v_exp_f32_e32 v0, v92
	v_exp_f32_e32 v4, v41
	v_exp_f32_e32 v6, v42
	v_add_f32_e32 v5, v3, v2
	v_add_f32_e32 v7, v21, v19
	v_cvt_pk_bf16_f32 v11, v2, v3
	v_add_f32_e32 v2, v0, v16
	v_add_f32_e32 v3, v1, v17
	v_add_f32_e32 v22, v6, v4
	v_add_f32_e32 v23, v7, v5
	v_cvt_pk_bf16_f32 v92, v16, v0
	v_lshlrev_b32_e32 v0, 9, v191
	v_add_f32_e32 v2, v22, v2
	v_add_f32_e32 v3, v23, v3
	v_add3_u32 v133, v32, v0, v183
	v_add_f32_e32 v104, v2, v2
	v_add_f32_e32 v105, v2, v3
	s_waitcnt lgkmcnt(0)
	v_mfma_f32_32x32x16_bf16 v[48:63], v[12:15], v[88:91], v[48:63]
	ds_read_b128 v[0:3], v133 offset:12288
	v_exp_f32_e32 v106, v98
	v_exp_f32_e32 v104, v97
	v_exp_f32_e32 v107, v96
	v_exp_f32_e32 v115, v95
	v_exp_f32_e32 v109, v94
	v_exp_f32_e32 v111, v93
	s_waitcnt lgkmcnt(0)
	v_mfma_f32_32x32x16_bf16 v[32:47], v[8:11], v[0:3], 0
	v_cvt_pk_bf16_f32 v95, v104, v106
	v_cvt_pk_bf16_f32 v94, v115, v107
	v_cvt_pk_bf16_f32 v93, v111, v109
	ds_read_b128 v[0:3], v133 offset:15360
	v_cvt_pk_bf16_f32 v82, v18, v20
	v_cvt_pk_bf16_f32 v83, v19, v21
	v_sub_f32_e32 v26, v26, v116
	s_waitcnt lgkmcnt(0)
	v_mfma_f32_32x32x16_bf16 v[32:47], v[92:95], v[0:3], v[32:47]
	ds_read_b128 v[0:3], v133 offset:18432
	v_sub_f32_e32 v27, v27, v116
	v_sub_f32_e32 v28, v28, v116
	v_sub_f32_e32 v29, v29, v116
	v_sub_f32_e32 v30, v30, v116
	v_sub_f32_e32 v31, v31, v116
	v_exp_f32_e32 v112, v31
	v_exp_f32_e32 v114, v30
	v_exp_f32_e32 v113, v29
	v_exp_f32_e32 v117, v28
	v_exp_f32_e32 v108, v27
	v_exp_f32_e32 v110, v26
	s_waitcnt lgkmcnt(0)
	v_mfma_f32_32x32x16_bf16 v[32:47], v[80:83], v[0:3], v[32:47]
	v_cvt_pk_bf16_f32 v96, v4, v6
	v_cvt_pk_bf16_f32 v99, v114, v112
	v_cvt_pk_bf16_f32 v98, v117, v113
	v_cvt_pk_bf16_f32 v97, v110, v108
	ds_read_b128 v[0:3], v133 offset:21504
	v_add_f32_e32 v113, v113, v117
	v_add_f32_e32 v115, v107, v115
	s_waitcnt lgkmcnt(0)
	v_mfma_f32_32x32x16_bf16 v[32:47], v[96:99], v[0:3], v[32:47]
	ds_read_b128 v[0:3], v133 offset:12800
	s_lshl_b32 s5, s43, 2
	s_add_i32 s5, s5, 0
	s_lshl_b32 s8, s42, 8
	s_add_i32 s5, s5, 0x12000
	s_addk_i32 s8, 0x6080
	v_cmp_gt_u32_e64 s[42:43], 32, v190
	s_waitcnt lgkmcnt(0)
	v_mfma_f32_32x32x16_bf16 v[16:31], v[8:11], v[0:3], 0
	ds_read_b128 v[0:3], v133 offset:15872
	v_lshl_add_u32 v213, v208, 2, s5
	v_mul_u32_u24_e32 v214, 0x600, v191
	s_mov_b32 s9, 0
	s_mov_b32 s10, 1
	s_mov_b32 s11, 0xc000
	s_movk_i32 s6, 0x6000
	s_waitcnt lgkmcnt(0)
	v_mfma_f32_32x32x16_bf16 v[16:31], v[92:95], v[0:3], v[16:31]
	ds_read_b128 v[0:3], v133 offset:18944
	s_mov_b32 s12, 64
	s_waitcnt lgkmcnt(0)
	v_mfma_f32_32x32x16_bf16 v[16:31], v[80:83], v[0:3], v[16:31]
	ds_read_b128 v[0:3], v133 offset:22016
	s_waitcnt lgkmcnt(0)
	v_mfma_f32_32x32x16_bf16 v[16:31], v[96:99], v[0:3], v[16:31]
	ds_read_b128 v[0:3], v133 offset:13312
	s_waitcnt lgkmcnt(0)
	v_mfma_f32_32x32x16_bf16 v[0:15], v[8:11], v[0:3], 0
	ds_read_b128 v[100:103], v133 offset:16384
	s_waitcnt lgkmcnt(0)
	v_mfma_f32_32x32x16_bf16 v[0:15], v[92:95], v[100:103], v[0:15]
	ds_read_b128 v[92:95], v133 offset:19456
	v_add_f32_e64 v100, v108, v110
	v_add_f32_e64 v101, v109, v111
	v_add_f32_e32 v101, v100, v101
	v_add_f32_e32 v100, v100, v100
	v_mov_b32_e32 v107, v101
	s_waitcnt lgkmcnt(0)
	v_mfma_f32_32x32x16_bf16 v[0:15], v[80:83], v[92:95], v[0:15]
	ds_read_b128 v[80:83], v133 offset:22528
	v_add_f32_e64 v92, v112, v114
	v_add_f32_e64 v93, v113, v115
	v_add_f32_e64 v94, v106, v104
	v_add_f32_e64 v95, v107, v105
	v_add_f32_e32 v92, v92, v94
	v_add_f32_e32 v93, v93, v95
	s_waitcnt lgkmcnt(0)
	v_mfma_f32_32x32x16_bf16 v[0:15], v[96:99], v[80:83], v[0:15]
	v_add_f32_e64 v80, v92, v93
	v_add_f32_e64 v81, v93, v92
	v_mov_b32_e32 v92, v195
	v_mov_b32_e32 v81, v116
	v_add_f32_e64 v184, v80, 0
	v_add_f32_e64 v185, v81, 0
	v_add_u32_e32 v93, v212, v92
	ds_read_b128 v[80:83], v93 offset:24576
	v_mfma_f32_32x32x16_bf16 v[64:79], v[84:87], v[88:91], v[64:79]
	v_xor_b32_e32 v96, 0x80000000, v185
	v_mov_b32_e32 v97, v96
	v_mov_b32_e32 v98, v96
	v_mov_b32_e32 v99, v96
	v_mov_b32_e32 v100, v96
	v_mov_b32_e32 v101, v96
	v_mov_b32_e32 v102, v96
	s_nop 4
	v_maximum3_f32 v84, v48, v64, v64
	v_maximum3_f32 v85, v65, v50, v66
	v_maximum3_f32 v84, v84, v49, v51
	v_maximum3_f32 v85, v85, v52, v68
	v_maximum3_f32 v84, v84, v67, v53
	v_maximum3_f32 v85, v85, v54, v70
	v_maximum3_f32 v84, v84, v69, v55
	v_maximum3_f32 v85, v85, v56, v72
	v_maximum3_f32 v84, v84, v71, v57
	v_maximum3_f32 v85, v85, v58, v74
	v_maximum3_f32 v84, v84, v73, v59
	v_maximum3_f32 v85, v85, v60, v76
	v_maximum3_f32 v84, v84, v75, v61
	v_maximum3_f32 v85, v85, v62, v78
	v_maximum3_f32 v84, v84, v77, v63
	v_maximum3_f32 v84, v84, v79, v85
	v_mov_b32_e32 v85, v84
	s_nop 1
	v_permlane32_swap_b32_e32 v84, v85
	v_maximum3_f32 v132, v84, v85, v85
	v_sub_f32_e32 v84, v48, v132
	v_sub_f32_e32 v85, v49, v132
	v_sub_f32_e32 v86, v50, v132
	v_sub_f32_e32 v87, v51, v132
	ds_read_b128 v[48:51], v93 offset:25088
	v_sub_f32_e32 v88, v52, v132
	v_add_u32_e32 v52, v209, v92
	v_sub_f32_e32 v89, v53, v132
	v_sub_f32_e32 v90, v54, v132
	v_sub_f32_e32 v91, v55, v132
	ds_read_b128 v[52:55], v52
	v_sub_f32_e32 v147, v60, v132
	v_mov_b32_e32 v103, v96
	v_mov_b32_e32 v104, v96
	v_mov_b32_e32 v105, v96
	v_mov_b32_e32 v106, v96
	v_mov_b32_e32 v107, v96
	v_mov_b32_e32 v108, v96
	v_mov_b32_e32 v109, v96
	v_mov_b32_e32 v110, v96
	v_mov_b32_e32 v111, v96
	v_mov_b32_e32 v60, v195
	v_sub_f32_e32 v94, v56, v132
	s_waitcnt lgkmcnt(0)
	v_mfma_f32_32x32x16_bf16 v[112:127], v[80:83], v[52:55], v[96:111]
	v_sub_f32_e32 v80, v61, v132
	v_add_u32_e32 v61, v212, v60
	v_sub_f32_e32 v95, v57, v132
	v_sub_f32_e32 v130, v58, v132
	v_sub_f32_e32 v131, v59, v132
	ds_read_b128 v[56:59], v61 offset:26624
	v_sub_f32_e32 v81, v62, v132
	v_mfma_f32_32x32x16_bf16 v[96:111], v[48:51], v[52:55], v[96:111]
	ds_read_b128 v[50:53], v61 offset:27136
	v_add_u32_e32 v48, v209, v60
	v_sub_f32_e32 v82, v63, v132
	ds_read_b128 v[60:63], v48 offset:8192
	v_sub_f32_e32 v64, v64, v132
	v_exp_f32_e32 v139, v64
	v_mov_b32_e32 v64, v195
	s_waitcnt lgkmcnt(0)
	v_mfma_f32_32x32x16_bf16 v[112:127], v[56:59], v[60:63], v[112:127]
	v_sub_f32_e32 v65, v65, v132
	v_add_u32_e32 v58, v212, v64
	ds_read_b128 v[54:57], v58 offset:28672
	v_exp_f32_e32 v141, v65
	v_exp_f32_e32 v135, v84
	v_exp_f32_e32 v137, v85
	v_mfma_f32_32x32x16_bf16 v[96:111], v[50:53], v[60:63], v[96:111]
	ds_read_b128 v[58:61], v58 offset:29184
	v_add_u32_e32 v50, v209, v64
	ds_read_b128 v[62:65], v50 offset:16384
	v_exp_f32_e32 v134, v86
	v_exp_f32_e32 v136, v87
	v_exp_f32_e32 v143, v88
	v_exp_f32_e32 v145, v89
	v_exp_f32_e32 v149, v90
	v_exp_f32_e32 v151, v91
	v_cvt_pk_bf16_f32 v48, v135, v137
	v_cvt_pk_bf16_f32 v49, v134, v136
	v_cvt_pk_bf16_f32 v50, v143, v145
	s_waitcnt lgkmcnt(0)
; #define ATT_SYNC() do { asm volatile("s_waitcnt vmcnt(0)" ::: "memory"); __syncthreads(); } while (0)
; template <int NS, int DQK, int DV, bool KSH  > ...
;     ...
;         for (int t = tlo; t < thi; ++t) {
;             if (t + 2 < thi) ATT_DMA(t + 2, bnn);
;             ATT_MAX(pA0, pA1, 0, t == tlo);
;             ATT_QKEXP(pB0, pB1, NS - 1, bc, pA0, pA1, 0);
;             ATT_PV(0, bc);
;             ATT_MAX(pB0, pB1, NS - 1, t == tlo);
;             ATT_QKEXP(pA0, pA1, 0, bn, pB0, pB1, NS - 1);
;             ATT_PV(NS - 1, bc);
;             ATT_SYNC();
;             const int tmp = bc; bc = bn; bn = bnn; bnn = tmp;
;         }
	v_mfma_f32_32x32x16_bf16 v[96:111], v[58:61], v[62:65], v[96:111]
	v_cvt_pk_bf16_f32 v51, v149, v151
	ds_read_b128 v[174:177], v133 offset:16384
	v_exp_f32_e32 v150, v94
	v_exp_f32_e32 v152, v95
	v_exp_f32_e32 v146, v81
	v_exp_f32_e32 v148, v82
	v_exp_f32_e32 v163, v131
	v_mfma_f32_32x32x16_bf16 v[112:127], v[54:57], v[62:65], v[112:127]
	ds_read_b128 v[52:55], v133 offset:12288
	v_exp_f32_e32 v157, v80
	v_exp_f32_e32 v147, v147
	v_exp_f32_e32 v165, v130
	v_cvt_pk_bf16_f32 v166, v150, v152
	v_cvt_pk_bf16_f32 v169, v146, v148
	v_cvt_pk_bf16_f32 v168, v147, v157
	s_waitcnt lgkmcnt(0)
	v_mfma_f32_32x32x16_bf16 v[80:95], v[48:51], v[52:55], 0
	v_cvt_pk_bf16_f32 v167, v165, v163
	ds_read_b128 v[52:55], v133 offset:15360
	v_sub_f32_e32 v66, v66, v132
	v_sub_f32_e32 v67, v67, v132
	v_sub_f32_e32 v68, v68, v132
	v_sub_f32_e32 v69, v69, v132
	v_sub_f32_e32 v70, v70, v132
	v_sub_f32_e32 v71, v71, v132
	v_exp_f32_e32 v138, v66
	v_exp_f32_e32 v140, v67
	v_exp_f32_e32 v142, v68
	v_exp_f32_e32 v144, v69
	v_exp_f32_e32 v153, v70
	v_exp_f32_e32 v155, v71
	s_waitcnt lgkmcnt(0)
	v_mfma_f32_32x32x16_bf16 v[80:95], v[166:169], v[52:55], v[80:95]
	v_cvt_pk_bf16_f32 v128, v139, v141
	v_cvt_pk_bf16_f32 v129, v138, v140
	v_cvt_pk_bf16_f32 v130, v142, v144
	v_cvt_pk_bf16_f32 v131, v153, v155
	ds_read_b128 v[52:55], v133 offset:18432
	v_sub_f32_e32 v72, v72, v132
	v_sub_f32_e32 v73, v73, v132
	v_sub_f32_e32 v74, v74, v132
	v_sub_f32_e32 v75, v75, v132
	v_sub_f32_e32 v76, v76, v132
	v_sub_f32_e32 v77, v77, v132
	v_sub_f32_e32 v78, v78, v132
	v_sub_f32_e32 v79, v79, v132
	v_exp_f32_e32 v154, v72
	v_exp_f32_e32 v156, v73
	v_exp_f32_e32 v158, v78
	v_exp_f32_e32 v160, v79
	v_exp_f32_e32 v162, v75
	v_exp_f32_e32 v159, v77
	v_exp_f32_e32 v161, v76
	v_exp_f32_e32 v164, v74
	s_waitcnt lgkmcnt(0)
	v_mfma_f32_32x32x16_bf16 v[80:95], v[128:131], v[52:55], v[80:95]
	v_cvt_pk_bf16_f32 v170, v154, v156
	v_cvt_pk_bf16_f32 v173, v158, v160
	v_cvt_pk_bf16_f32 v172, v161, v159
	v_cvt_pk_bf16_f32 v171, v164, v162
	ds_read_b128 v[52:55], v133 offset:21504
	v_add_f32_e32 v138, v140, v138
	v_add_f32_e32 v139, v141, v139
	v_add_f32_e32 v134, v136, v134
	v_add_f32_e32 v135, v137, v135
	s_waitcnt lgkmcnt(0)
	v_mfma_f32_32x32x16_bf16 v[80:95], v[170:173], v[52:55], v[80:95]
	ds_read_b128 v[52:55], v133 offset:12800
	v_add_f32_e64 v134, v138, v134
	v_add_f32_e64 v135, v139, v135
	v_add_f32_e32 v161, v159, v161
	v_add_f32_e32 v159, v157, v147
	v_add_f32_e32 v157, v155, v153
	v_add_f32_e32 v155, v151, v149
	s_waitcnt lgkmcnt(0)
	v_mfma_f32_32x32x16_bf16 v[64:79], v[48:51], v[52:55], 0
	ds_read_b128 v[52:55], v133 offset:15872
	s_waitcnt lgkmcnt(0)
	v_mfma_f32_32x32x16_bf16 v[64:79], v[166:169], v[52:55], v[64:79]
	ds_read_b128 v[52:55], v133 offset:18944
	s_waitcnt lgkmcnt(0)
	v_mfma_f32_32x32x16_bf16 v[64:79], v[128:131], v[52:55], v[64:79]
	ds_read_b128 v[52:55], v133 offset:22016
	s_waitcnt lgkmcnt(0)
	v_mfma_f32_32x32x16_bf16 v[64:79], v[170:173], v[52:55], v[64:79]
	ds_read_b128 v[52:55], v133 offset:13312
	s_waitcnt lgkmcnt(0)
	v_mfma_f32_32x32x16_bf16 v[48:63], v[48:51], v[52:55], 0
	v_mfma_f32_32x32x16_bf16 v[48:63], v[166:169], v[174:177], v[48:63]
	ds_read_b128 v[166:169], v133 offset:19456
	s_waitcnt lgkmcnt(0)
	v_mfma_f32_32x32x16_bf16 v[48:63], v[128:131], v[166:169], v[48:63]
	ds_read_b128 v[128:131], v133 offset:22528
	s_waitcnt vmcnt(0)
	s_waitcnt vmcnt(0) lgkmcnt(0)
	s_barrier
	v_mfma_f32_32x32x16_bf16 v[48:63], v[170:173], v[128:131], v[48:63]
	v_add_f32_e64 v128, v162, v164
	v_add_f32_e64 v129, v163, v165
	v_add_f32_e64 v130, v144, v142
	v_add_f32_e64 v131, v145, v143
	v_add_f32_e32 v129, v128, v129
	v_add_f32_e32 v128, v128, v128
	v_add_f32_e32 v131, v130, v131
	v_add_f32_e32 v130, v130, v130
	v_add_f32_e32 v128, 0, v135
	v_add_f32_e32 v151, v134, v128
	v_mov_b32_e32 v153, v131
	v_add_f32_e32 v134, v156, v154
	v_add_f32_e32 v135, v157, v155
	v_add_f32_e32 v130, v152, v150
	v_add_f32_e32 v131, v153, v151
	v_mov_b32_e32 v149, v129
	v_add_f32_e32 v130, v134, v130
	v_add_f32_e32 v131, v135, v131
	v_add_f32_e32 v134, v160, v158
	v_add_f32_e32 v135, v161, v159
	v_add_f32_e32 v131, v130, v131
	v_add_f32_e32 v130, v130, v130
	v_mov_b32_e32 v147, v131
	v_add_f32_e32 v128, v148, v146
	v_add_f32_e32 v129, v149, v147
	s_nop 0
	v_add_f32_e32 v128, v134, v128
	v_add_f32_e32 v129, v135, v129
	s_nop 0
	v_add_f32_e32 v129, v128, v129
	v_add_f32_e32 v128, v128, v128
	v_mov_b32_e32 v133, v129
	v_add_f32_e32 v186, 0, v132
	v_add_f32_e32 v187, 0, v133
	s_cmpk_gt_u32 s10, 0x81
	s_mov_b32 s13, s6
	s_cbranch_scc1 .LBB0_808

.LBB0_808:
	s_nop 2
	v_maximum3_f32 v128, v112, v96, v96
	v_maximum3_f32 v129, v97, v114, v98
	v_maximum3_f32 v128, v128, v113, v115
	v_maximum3_f32 v129, v129, v116, v100
	v_maximum3_f32 v128, v128, v99, v117
	v_maximum3_f32 v129, v129, v118, v102
	v_maximum3_f32 v128, v128, v101, v119
	v_maximum3_f32 v129, v129, v120, v104
	v_maximum3_f32 v128, v128, v103, v121
	v_maximum3_f32 v129, v129, v122, v106
	v_maximum3_f32 v128, v128, v105, v123
	v_maximum3_f32 v129, v129, v124, v108
	v_maximum3_f32 v128, v128, v107, v125
	v_maximum3_f32 v129, v129, v126, v110
	v_maximum3_f32 v128, v128, v109, v127
	v_maximum3_f32 v128, v128, v111, v129
	v_mov_b32_e32 v129, v128
	s_nop 1
	v_permlane32_swap_b32_e32 v128, v129
	v_maximum3_f32 v128, v128, v129, v129
	v_cmp_lt_f32_e32 vcc, s46, v128
	s_cbranch_vccz .LBB0_812
	v_max_f32_e32 v128, v128, v128
	v_max_f32_e32 v130, 0, v128
	v_exp_f32_e64 v128, -v130
	s_and_saveexec_b64 s[6:7], s[42:43]
	ds_write_b32 v213, v128
	s_or_b64 exec, exec, s[6:7]
	v_mov_b32_e32 v129, v130
	v_sub_f32_e32 v112, v112, v130
	v_sub_f32_e32 v113, v113, v130
	v_sub_f32_e32 v96, v96, v130
	v_sub_f32_e32 v97, v97, v130
	v_sub_f32_e32 v114, v114, v130
	v_sub_f32_e32 v115, v115, v130
	v_sub_f32_e32 v98, v98, v130
	v_sub_f32_e32 v99, v99, v130
	v_sub_f32_e32 v116, v116, v130
	v_sub_f32_e32 v117, v117, v130
	v_sub_f32_e32 v100, v100, v130
	v_sub_f32_e32 v101, v101, v130
	v_sub_f32_e32 v118, v118, v130
	v_sub_f32_e32 v119, v119, v130
	v_sub_f32_e32 v102, v102, v130
	v_sub_f32_e32 v103, v103, v130
	v_sub_f32_e32 v120, v120, v130
	v_sub_f32_e32 v121, v121, v130
	v_sub_f32_e32 v104, v104, v130
	v_sub_f32_e32 v105, v105, v130
	v_sub_f32_e32 v122, v122, v130
	v_sub_f32_e32 v123, v123, v130
	v_sub_f32_e32 v106, v106, v130
	v_sub_f32_e32 v107, v107, v130
	v_sub_f32_e32 v124, v124, v130
	v_sub_f32_e32 v125, v125, v130
	v_sub_f32_e32 v108, v108, v130
	v_sub_f32_e32 v109, v109, v130
	v_sub_f32_e32 v126, v126, v130
	v_sub_f32_e32 v127, v127, v130
	v_sub_f32_e32 v110, v110, v130
	v_sub_f32_e32 v111, v111, v130
	v_add_f32_e32 v130, v184, v128
	v_add_f32_e32 v131, v185, v129
	v_mul_f32_e32 v184, v184, v128
	v_mul_f32_e32 v185, v185, v129
	s_waitcnt lgkmcnt(0)
	v_add_u32_e32 v140, s5, v194
	v_mov_b32_e32 v185, v131
	ds_read_b128 v[128:131], v140
	ds_read_b128 v[132:135], v140 offset:32
	ds_read_b128 v[136:139], v140 offset:64
	ds_read_b128 v[140:143], v140 offset:96
	s_waitcnt lgkmcnt(0)
	s_waitcnt lgkmcnt(0)
	v_mul_f32_e32 v34, v34, v130
	v_mul_f32_e32 v35, v35, v131
	v_mul_f32_e32 v36, v36, v132
	v_mul_f32_e32 v37, v37, v133
	v_mul_f32_e32 v40, v40, v136
	v_mul_f32_e32 v41, v41, v137
	v_mul_f32_e32 v44, v44, v140
	v_mul_f32_e32 v45, v45, v141
	v_mul_f32_e32 v46, v46, v142
	v_mul_f32_e32 v47, v47, v143
	v_mul_f32_e32 v42, v42, v138
	v_mul_f32_e32 v43, v43, v139
	v_mul_f32_e32 v38, v38, v134
	v_mul_f32_e32 v39, v39, v135
	v_mul_f32_e32 v32, v32, v128
	v_mul_f32_e32 v33, v33, v129
	v_mul_f32_e32 v28, v28, v140
	v_mul_f32_e32 v29, v29, v141
	v_mul_f32_e32 v24, v24, v136
	v_mul_f32_e32 v25, v25, v137
	v_mul_f32_e32 v20, v20, v132
	v_mul_f32_e32 v21, v21, v133
	v_mul_f32_e32 v30, v30, v142
	v_mul_f32_e32 v31, v31, v143
	v_mul_f32_e32 v26, v26, v138
	v_mul_f32_e32 v27, v27, v139
	v_mul_f32_e32 v22, v22, v134
	v_mul_f32_e32 v23, v23, v135
	v_mul_f32_e32 v18, v18, v130
	v_mul_f32_e32 v19, v19, v131
	v_mul_f32_e32 v16, v16, v128
	v_mul_f32_e32 v17, v17, v129
	v_mul_f32_e32 v12, v12, v140
	v_mul_f32_e32 v13, v13, v141
	v_mul_f32_e32 v8, v8, v136
	v_mul_f32_e32 v9, v9, v137
	v_mul_f32_e32 v4, v4, v132
	v_mul_f32_e32 v5, v5, v133
	v_mul_f32_e32 v14, v14, v142
	v_mul_f32_e32 v15, v15, v143
	v_mul_f32_e32 v10, v10, v138
	v_mul_f32_e32 v11, v11, v139
	v_mul_f32_e32 v6, v6, v134
	v_mul_f32_e32 v7, v7, v135
	v_mul_f32_e32 v2, v2, v130
	v_mul_f32_e32 v3, v3, v131
	v_mul_f32_e32 v0, v0, v128
	v_mul_f32_e32 v1, v1, v129
.LBB0_812:
	s_add_i32 s6, s13, 0
	v_add3_u32 v178, s6, v181, v183
	v_mov_b32_e32 v144, 0
	v_xor_b32_e32 v128, 0x80000000, v186
	v_add_u32_e32 v145, v178, v144
	ds_read_b128 v[160:163], v145 offset:6144
	ds_read_b128 v[166:169], v145 offset:6656
	v_add_u32_e32 v144, v209, v144
	ds_read_b128 v[170:173], v144 offset:24576
	v_mov_b32_e32 v164, 0
	v_mov_b32_e32 v129, v128
	v_mov_b32_e32 v130, v128
	v_mov_b32_e32 v131, v128
	v_mov_b32_e32 v132, v128
	v_mov_b32_e32 v133, v128
	v_mov_b32_e32 v134, v128
	v_mov_b32_e32 v135, v128
	v_mov_b32_e32 v136, v128
	v_mov_b32_e32 v137, v128
	v_mov_b32_e32 v138, v128
	v_mov_b32_e32 v139, v128
	v_mov_b32_e32 v140, v128
	v_mov_b32_e32 v141, v128
	v_mov_b32_e32 v142, v128
	v_mov_b32_e32 v143, v128
	v_exp_f32_e32 v116, v116
	v_add_u32_e32 v165, v178, v164
	ds_read_b128 v[174:177], v165 offset:8192
	s_waitcnt lgkmcnt(0)
	v_mfma_f32_32x32x16_bf16 v[144:159], v[160:163], v[170:173], v[128:143]
	ds_read_b128 v[218:221], v165 offset:8704
	v_add_u32_e32 v160, v209, v164
	v_exp_f32_e32 v164, v112
	v_exp_f32_e32 v165, v113
	v_exp_f32_e32 v117, v117
	v_exp_f32_e32 v124, v124
	v_exp_f32_e32 v123, v123
	v_mfma_f32_32x32x16_bf16 v[128:143], v[166:169], v[170:173], v[128:143]
	ds_read_b128 v[226:229], v160 offset:32768
	v_exp_f32_e32 v167, v114
	v_mov_b32_e32 v114, 0
	v_exp_f32_e32 v169, v115
	v_exp_f32_e32 v166, v96
	v_add_u32_e32 v115, v178, v114
	v_exp_f32_e32 v168, v97
	v_exp_f32_e32 v170, v98
	v_exp_f32_e32 v171, v99
	s_waitcnt lgkmcnt(0)
	v_mfma_f32_32x32x16_bf16 v[144:159], v[174:177], v[226:229], v[144:159]
	ds_read_b128 v[96:99], v115 offset:10240
	v_add_u32_e32 v114, v209, v114
	v_exp_f32_e32 v172, v101
	v_exp_f32_e32 v101, v118
	v_exp_f32_e32 v118, v119
	v_cvt_pk_bf16_f32 v160, v164, v165
	v_cvt_pk_bf16_f32 v161, v167, v169
	v_mfma_f32_32x32x16_bf16 v[128:143], v[218:221], v[226:229], v[128:143]
	ds_read_b128 v[174:177], v115 offset:10752
	ds_read_b128 v[218:221], v114 offset:40960
	v_cvt_pk_bf16_f32 v162, v116, v117
	v_cvt_pk_bf16_f32 v163, v101, v118
	v_exp_f32_e32 v119, v102
	v_exp_f32_e32 v173, v103
	v_exp_f32_e32 v102, v120
	s_waitcnt lgkmcnt(0)
	v_mfma_f32_32x32x16_bf16 v[128:143], v[174:177], v[218:221], v[128:143]
	v_exp_f32_e32 v103, v121
	v_exp_f32_e32 v121, v104
	v_exp_f32_e32 v174, v105
	v_exp_f32_e32 v104, v127
	v_exp_f32_e32 v105, v126
	v_exp_f32_e32 v120, v125
	v_exp_f32_e32 v122, v122
	v_mfma_f32_32x32x16_bf16 v[144:159], v[96:99], v[218:221], v[144:159]
	v_add_u32_e32 v96, s6, v214
	v_add_u32_e32 v215, v96, v183
	ds_read_b128 v[96:99], v215 offset:12288
	v_cvt_pk_bf16_f32 v176, v102, v103
	v_cvt_pk_bf16_f32 v179, v105, v104
	v_cvt_pk_bf16_f32 v178, v124, v120
	v_cvt_pk_bf16_f32 v177, v122, v123
	s_waitcnt lgkmcnt(0)
	v_mfma_f32_32x32x16_bf16 v[32:47], v[160:163], v[96:99], v[32:47]
	ds_read_b128 v[218:221], v215 offset:15360
	v_exp_f32_e32 v100, v100
	v_cvt_pk_bf16_f32 v112, v166, v168
	v_cvt_pk_bf16_f32 v113, v170, v171
	v_cvt_pk_bf16_f32 v115, v119, v173
	v_cvt_pk_bf16_f32 v114, v100, v172
	v_exp_f32_e32 v111, v111
	s_waitcnt lgkmcnt(0)
	v_mfma_f32_32x32x16_bf16 v[32:47], v[176:179], v[218:221], v[32:47]
	ds_read_b128 v[218:221], v215 offset:18432
	v_exp_f32_e32 v110, v110
	v_exp_f32_e32 v109, v109
	v_exp_f32_e32 v108, v108
	v_exp_f32_e32 v107, v107
	v_exp_f32_e32 v106, v106
	v_cvt_pk_bf16_f32 v96, v121, v174
	s_waitcnt lgkmcnt(0)
	v_mfma_f32_32x32x16_bf16 v[32:47], v[112:115], v[218:221], v[32:47]
	v_cvt_pk_bf16_f32 v99, v110, v111
	v_cvt_pk_bf16_f32 v98, v108, v109
	v_cvt_pk_bf16_f32 v97, v106, v107
	ds_read_b128 v[218:221], v215 offset:21504
	s_waitcnt lgkmcnt(0)
	v_mfma_f32_32x32x16_bf16 v[32:47], v[96:99], v[218:221], v[32:47]
	ds_read_b128 v[218:221], v215 offset:12800
	s_waitcnt lgkmcnt(0)
	v_mfma_f32_32x32x16_bf16 v[16:31], v[160:163], v[218:221], v[16:31]
	ds_read_b128 v[218:221], v215 offset:15872
	s_waitcnt lgkmcnt(0)
	v_mfma_f32_32x32x16_bf16 v[16:31], v[176:179], v[218:221], v[16:31]
	ds_read_b128 v[218:221], v215 offset:18944
	s_waitcnt lgkmcnt(0)
	v_mfma_f32_32x32x16_bf16 v[16:31], v[112:115], v[218:221], v[16:31]
	ds_read_b128 v[218:221], v215 offset:22016
	s_waitcnt lgkmcnt(0)
	v_mfma_f32_32x32x16_bf16 v[16:31], v[96:99], v[218:221], v[16:31]
	ds_read_b128 v[218:221], v215 offset:13312
	s_waitcnt lgkmcnt(0)
	v_mfma_f32_32x32x16_bf16 v[0:15], v[160:163], v[218:221], v[0:15]
	ds_read_b128 v[160:163], v215 offset:16384
	s_waitcnt lgkmcnt(0)
	v_mfma_f32_32x32x16_bf16 v[0:15], v[176:179], v[160:163], v[0:15]
	ds_read_b128 v[160:163], v215 offset:19456
	s_waitcnt lgkmcnt(0)
	v_mfma_f32_32x32x16_bf16 v[0:15], v[112:115], v[160:163], v[0:15]
	ds_read_b128 v[160:163], v215 offset:22528
	v_maximum3_f32 v112, v144, v128, v128
	v_maximum3_f32 v113, v129, v146, v130
	v_maximum3_f32 v112, v112, v145, v147
	v_maximum3_f32 v113, v113, v148, v132
	v_maximum3_f32 v112, v112, v131, v149
	v_maximum3_f32 v113, v113, v150, v134
	v_maximum3_f32 v112, v112, v133, v151
	v_maximum3_f32 v113, v113, v152, v136
	v_maximum3_f32 v112, v112, v135, v153
	v_maximum3_f32 v113, v113, v154, v138
	v_maximum3_f32 v112, v112, v137, v155
	s_waitcnt lgkmcnt(0)
	v_mfma_f32_32x32x16_bf16 v[0:15], v[96:99], v[160:163], v[0:15]
	v_maximum3_f32 v113, v113, v156, v140
	v_maximum3_f32 v112, v112, v139, v157
	v_maximum3_f32 v113, v113, v158, v142
	v_maximum3_f32 v112, v112, v141, v159
	v_maximum3_f32 v112, v112, v143, v113
	v_mov_b32_e32 v113, v112
	s_nop 1
	v_permlane32_swap_b32_e32 v112, v113
	v_maximum3_f32 v112, v112, v113, v113
	v_cmp_lt_f32_e32 vcc, s46, v112
	s_cbranch_vccz .LBB0_816
	v_max_f32_e32 v96, v112, v112
	v_max_f32_e32 v96, 0, v96
	v_exp_f32_e64 v97, -v96
	s_and_saveexec_b64 s[6:7], s[42:43]
	ds_write_b32 v213, v97
	s_or_b64 exec, exec, s[6:7]
	v_sub_f32_e32 v144, v144, v96
	v_sub_f32_e32 v145, v145, v96
	v_sub_f32_e32 v128, v128, v96
	v_sub_f32_e32 v129, v129, v96
	v_sub_f32_e32 v146, v146, v96
	v_sub_f32_e32 v147, v147, v96
	v_sub_f32_e32 v130, v130, v96
	v_sub_f32_e32 v131, v131, v96
	v_sub_f32_e32 v148, v148, v96
	v_sub_f32_e32 v149, v149, v96
	v_sub_f32_e32 v132, v132, v96
	v_sub_f32_e32 v133, v133, v96
	v_sub_f32_e32 v150, v150, v96
	v_sub_f32_e32 v151, v151, v96
	v_sub_f32_e32 v134, v134, v96
	v_sub_f32_e32 v135, v135, v96
	v_sub_f32_e32 v152, v152, v96
	v_sub_f32_e32 v153, v153, v96
	v_sub_f32_e32 v136, v136, v96
	v_sub_f32_e32 v137, v137, v96
	v_sub_f32_e32 v154, v154, v96
	v_sub_f32_e32 v155, v155, v96
	v_sub_f32_e32 v138, v138, v96
	v_sub_f32_e32 v139, v139, v96
	v_sub_f32_e32 v156, v156, v96
	v_sub_f32_e32 v157, v157, v96
	v_sub_f32_e32 v140, v140, v96
	v_sub_f32_e32 v141, v141, v96
	v_sub_f32_e32 v158, v158, v96
	v_sub_f32_e32 v159, v159, v96
	v_sub_f32_e32 v142, v142, v96
	v_sub_f32_e32 v143, v143, v96
	v_add_f32_e32 v188, v186, v96
	v_add_f32_e32 v189, v187, v97
	v_mul_f32_e32 v96, v186, v96
	v_mul_f32_e32 v97, v187, v97
	s_waitcnt lgkmcnt(0)
	v_add_u32_e32 v125, s5, v194
	v_mov_b32_e32 v189, v97
	ds_read_b128 v[96:99], v125
	ds_read_b128 v[112:115], v125 offset:32
	ds_read_b128 v[160:163], v125 offset:64
	ds_read_b128 v[176:179], v125 offset:96
	s_waitcnt lgkmcnt(0)
	s_waitcnt lgkmcnt(0)
	v_mul_f32_e32 v82, v82, v98
	v_mul_f32_e32 v83, v83, v99
	v_mul_f32_e32 v84, v84, v112
	v_mul_f32_e32 v85, v85, v113
	v_mul_f32_e32 v88, v88, v160
	v_mul_f32_e32 v89, v89, v161
	v_mul_f32_e32 v92, v92, v176
	v_mul_f32_e32 v93, v93, v177
	v_mul_f32_e32 v94, v94, v178
	v_mul_f32_e32 v95, v95, v179
	v_mul_f32_e32 v90, v90, v162
	v_mul_f32_e32 v91, v91, v163
	v_mul_f32_e32 v86, v86, v114
	v_mul_f32_e32 v87, v87, v115
	v_mul_f32_e32 v80, v80, v96
	v_mul_f32_e32 v81, v81, v97
	v_mul_f32_e32 v76, v76, v176
	v_mul_f32_e32 v77, v77, v177
	v_mul_f32_e32 v72, v72, v160
	v_mul_f32_e32 v73, v73, v161
	v_mul_f32_e32 v68, v68, v112
	v_mul_f32_e32 v69, v69, v113
	v_mul_f32_e32 v78, v78, v178
	v_mul_f32_e32 v79, v79, v179
	v_mul_f32_e32 v74, v74, v162
	v_mul_f32_e32 v75, v75, v163
	v_mul_f32_e32 v70, v70, v114
	v_mul_f32_e32 v71, v71, v115
	v_mul_f32_e32 v66, v66, v98
	v_mul_f32_e32 v67, v67, v99
	v_mul_f32_e32 v64, v64, v96
	v_mul_f32_e32 v65, v65, v97
	v_mul_f32_e32 v60, v60, v176
	v_mul_f32_e32 v61, v61, v177
	v_mul_f32_e32 v56, v56, v160
	v_mul_f32_e32 v57, v57, v161
	v_mul_f32_e32 v52, v52, v112
	v_mul_f32_e32 v53, v53, v113
	v_mul_f32_e32 v62, v62, v178
	v_mul_f32_e32 v63, v63, v179
	v_mul_f32_e32 v58, v58, v162
	v_mul_f32_e32 v59, v59, v163
	v_mul_f32_e32 v54, v54, v114
	v_mul_f32_e32 v55, v55, v115
	v_mul_f32_e32 v50, v50, v98
	v_mul_f32_e32 v51, v51, v99
	v_mul_f32_e32 v48, v48, v96
	v_mul_f32_e32 v49, v49, v97
	v_mov_b32_e32 v186, v188
	s_branch .LBB0_817

; #define ATT_SYNC() do { asm volatile("s_waitcnt vmcnt(0)" ::: "memory"); __syncthreads(); } while (0)
; template <int NS, int DQK, int DV, bool KSH  > ...
;     ...
;         for (int t = tlo; t < thi; ++t) {
;             if (t + 2 < thi) ATT_DMA(t + 2, bnn);
;             ATT_MAX(pA0, pA1, 0, t == tlo);
;             ATT_QKEXP(pB0, pB1, NS - 1, bc, pA0, pA1, 0);
;             ATT_PV(0, bc);
;             ATT_MAX(pB0, pB1, NS - 1, t == tlo);
;             ATT_QKEXP(pA0, pA1, 0, bn, pB0, pB1, NS - 1);
;             ATT_PV(NS - 1, bc);
;             ATT_SYNC();
;             const int tmp = bc; bc = bn; bn = bnn; bnn = tmp;
;         }
.LBB0_817:
	v_add_f32_e32 v96, v165, v164
	v_add_f32_e32 v97, v168, v166
	v_add_f32_e32 v96, v97, v96
	v_add_f32_e32 v97, v169, v167
	v_add_f32_e32 v98, v171, v170
	v_add_f32_e32 v96, 0, v96
	v_add_f32_e32 v97, v98, v97
	v_add_f32_e32 v96, v97, v96
	v_add_f32_e32 v97, v117, v116
	v_add_f32_e32 v98, v172, v100
	v_add_f32_e32 v97, v98, v97
	v_add_f32_e32 v96, v97, v96
	v_add_f32_e32 v97, v118, v101
	v_add_f32_e32 v98, v173, v119
	v_mov_b32_e32 v112, 0
	v_add_f32_e32 v97, v98, v97
	v_add_u32_e32 v162, s11, v212
	v_add_f32_e32 v96, v97, v96
	v_add_f32_e32 v97, v103, v102
	v_add_f32_e32 v98, v174, v121
	v_add_u32_e32 v113, v162, v112
	v_add_u32_e32 v112, v209, v112
	v_add_f32_e32 v97, v98, v97
	ds_read_b128 v[230:233], v112
	v_mov_b32_e32 v112, 0
	v_add_f32_e32 v96, v97, v96
	v_add_f32_e32 v97, v107, v106
	v_add_f32_e32 v98, v123, v122
	ds_read_b128 v[218:221], v113
	ds_read_b128 v[226:229], v113 offset:512
	v_add_f32_e32 v97, v97, v98
	v_add_u32_e32 v113, v162, v112
	v_add_u32_e32 v112, v209, v112
	v_add_f32_e32 v96, v97, v96
	v_add_f32_e32 v97, v109, v108
	v_add_f32_e32 v98, v120, v124
	ds_read_b128 v[176:179], v113 offset:2048
	ds_read_b128 v[168:171], v113 offset:2560
	ds_read_b128 v[172:175], v112 offset:8192
	v_exp_f32_e32 v113, v144
	v_exp_f32_e32 v115, v145
	v_exp_f32_e32 v117, v128
	v_exp_f32_e32 v119, v129
	v_exp_f32_e32 v112, v146
	v_exp_f32_e32 v114, v147
	v_exp_f32_e32 v116, v130
	v_exp_f32_e32 v118, v131
	v_add_f32_e32 v97, v97, v98
	v_add_f32_e32 v96, v97, v96
	v_add_f32_e32 v97, v111, v110
	v_add_f32_e32 v98, v104, v105
	v_add_f32_e32 v97, v97, v98
	v_add_f32_e32 v96, v97, v96
	v_add_f32_e32 v120, v114, v112
	v_add_f32_e32 v121, v115, v113
	v_add_f32_e32 v122, v118, v116
	v_add_f32_e32 v123, v119, v117
	v_mov_b32_e32 v144, 0
	v_add_f32_e32 v184, v184, v96
	v_xor_b32_e32 v96, 0x80000000, v185
	v_add_f32_e32 v120, v122, v120
	v_add_f32_e32 v121, v123, v121
	v_exp_f32_e32 v163, v148
	v_add_u32_e32 v128, v162, v144
	v_exp_f32_e32 v149, v149
	v_exp_f32_e32 v162, v132
	v_exp_f32_e32 v148, v133
	v_mov_b32_e32 v97, v96
	v_mov_b32_e32 v98, v96
	v_mov_b32_e32 v99, v96
	v_mov_b32_e32 v100, v96
	v_mov_b32_e32 v101, v96
	v_mov_b32_e32 v102, v96
	v_mov_b32_e32 v103, v96
	v_mov_b32_e32 v104, v96
	v_mov_b32_e32 v105, v96
	v_mov_b32_e32 v106, v96
	v_mov_b32_e32 v107, v96
	v_mov_b32_e32 v108, v96
	v_mov_b32_e32 v109, v96
	v_mov_b32_e32 v110, v96
	v_mov_b32_e32 v111, v96
	v_cvt_pk_bf16_f32 v164, v113, v115
	v_add_f32_e32 v113, 0, v121
	v_cvt_pk_bf16_f32 v160, v117, v119
	v_add_f32_e32 v223, v120, v113
	v_cvt_pk_bf16_f32 v165, v112, v114
	v_cvt_pk_bf16_f32 v161, v116, v118
	s_waitcnt lgkmcnt(0)
	v_mfma_f32_32x32x16_bf16 v[112:127], v[218:221], v[230:233], v[96:111]
	ds_read_b128 v[218:221], v128 offset:4096
	v_add_f32_e64 v132, v148, v162
	v_add_f32_e64 v133, v149, v163
	v_cvt_pk_bf16_f32 v162, v162, v148
	v_add_f32_e32 v133, v132, v133
	v_add_f32_e32 v132, v132, v132
	v_exp_f32_e32 v132, v150
	v_exp_f32_e32 v148, v151
	v_add_u32_e32 v144, v209, v144
	v_mfma_f32_32x32x16_bf16 v[96:111], v[226:229], v[230:233], v[96:111]
	v_exp_f32_e32 v134, v134
	v_exp_f32_e32 v135, v135
	ds_read_b128 v[128:131], v128 offset:4608
	ds_read_b128 v[144:147], v144 offset:16384
	v_cvt_pk_bf16_f32 v166, v163, v149
	v_add_f32_e32 v149, v148, v132
	v_cvt_pk_bf16_f32 v167, v132, v148
	v_exp_f32_e32 v222, v152
	v_exp_f32_e32 v132, v153
	v_exp_f32_e32 v148, v136
	v_exp_f32_e32 v150, v137
	v_mfma_f32_32x32x16_bf16 v[96:111], v[168:171], v[172:175], v[96:111]
	v_exp_f32_e32 v168, v139
	v_exp_f32_e32 v138, v138
	v_exp_f32_e32 v169, v155
	v_exp_f32_e32 v139, v154
	v_add_f32_e32 v151, v135, v134
	v_cvt_pk_bf16_f32 v163, v134, v135
	v_add_f32_e32 v134, v132, v222
	v_add_f32_e32 v135, v133, v223
	v_add_f32_e32 v136, v150, v148
	v_add_f32_e32 v137, v151, v149
	v_add_f32_e32 v154, v168, v138
	v_add_f32_e32 v155, v169, v139
	v_add_f32_e32 v134, v136, v134
	v_add_f32_e32 v135, v137, v135
	v_add_f32_e32 v155, v154, v155
	v_add_f32_e32 v154, v154, v154
	v_add_f32_e32 v152, v134, v134
	v_add_f32_e32 v153, v134, v135
	v_exp_f32_e32 v135, v141
	v_exp_f32_e32 v136, v140
	v_exp_f32_e32 v149, v157
	v_exp_f32_e32 v154, v156
	v_cvt_pk_bf16_f32 v134, v222, v132
	v_exp_f32_e32 v132, v142
	v_exp_f32_e32 v142, v143
	v_exp_f32_e32 v152, v158
	v_exp_f32_e32 v158, v159
	v_add_f32_e32 v143, v135, v136
	v_add_f32_e32 v133, v149, v154
	v_mov_b32_e32 v159, v155
	v_cvt_pk_bf16_f32 v151, v132, v142
	v_add_f32_e32 v132, v142, v132
	v_add_f32_e32 v133, v143, v133
	v_add_f32_e32 v140, v158, v152
	v_add_f32_e32 v141, v159, v153
	v_cvt_pk_bf16_f32 v148, v148, v150
	v_add_f32_e32 v132, v132, v140
	v_add_f32_e32 v133, v133, v141
	v_cvt_pk_bf16_f32 v150, v136, v135
	v_cvt_pk_bf16_f32 v136, v154, v149
	v_cvt_pk_bf16_f32 v149, v138, v168
	v_cvt_pk_bf16_f32 v135, v139, v169
	s_waitcnt lgkmcnt(0)
	v_mfma_f32_32x32x16_bf16 v[96:111], v[128:131], v[144:147], v[96:111]
	ds_read_b128 v[138:141], v215 offset:12288
	v_cvt_pk_bf16_f32 v137, v152, v158
	ds_read_b128 v[152:155], v215 offset:15360
	v_pk_add_f32 v[132:133], v[132:133], v[132:133] op_sel:[0,1] op_sel_hi:[1,0]
	s_add_i32 s10, s10, 1
	s_add_i32 s12, s12, 64
	v_add_f32_e32 v132, v189, v132
	v_add_f32_e32 v133, v188, v133
	s_waitcnt lgkmcnt(0)
	v_mfma_f32_32x32x16_bf16 v[80:95], v[164:167], v[138:141], v[80:95]
	ds_read_b128 v[138:141], v215 offset:18432
	s_cmpk_eq_i32 s10, 0x84
	v_mfma_f32_32x32x16_bf16 v[80:95], v[134:137], v[152:155], v[80:95]
	ds_read_b128 v[152:155], v215 offset:21504
	s_waitcnt lgkmcnt(0)
	v_mfma_f32_32x32x16_bf16 v[80:95], v[160:163], v[138:141], v[80:95]
	ds_read_b128 v[138:141], v215 offset:12800
	v_mfma_f32_32x32x16_bf16 v[80:95], v[148:151], v[152:155], v[80:95]
	ds_read_b128 v[152:155], v215 offset:15872
	s_waitcnt lgkmcnt(0)
	v_mfma_f32_32x32x16_bf16 v[64:79], v[164:167], v[138:141], v[64:79]
	ds_read_b128 v[138:141], v215 offset:18944
	v_mfma_f32_32x32x16_bf16 v[64:79], v[134:137], v[152:155], v[64:79]
	ds_read_b128 v[152:155], v215 offset:22016
	s_waitcnt lgkmcnt(0)
	v_mfma_f32_32x32x16_bf16 v[64:79], v[160:163], v[138:141], v[64:79]
	ds_read_b128 v[138:141], v215 offset:13312
	v_mfma_f32_32x32x16_bf16 v[64:79], v[148:151], v[152:155], v[64:79]
	ds_read_b128 v[152:155], v215 offset:16384
	s_waitcnt lgkmcnt(0)
	v_mfma_f32_32x32x16_bf16 v[48:63], v[164:167], v[138:141], v[48:63]
	ds_read_b128 v[138:141], v215 offset:19456
	v_mfma_f32_32x32x16_bf16 v[48:63], v[134:137], v[152:155], v[48:63]
	ds_read_b128 v[134:137], v215 offset:22528
	s_waitcnt vmcnt(0)
	s_waitcnt vmcnt(0) lgkmcnt(0)
	s_barrier
	v_mfma_f32_32x32x16_bf16 v[48:63], v[160:163], v[138:141], v[48:63]
	v_mfma_f32_32x32x16_bf16 v[48:63], v[148:151], v[134:137], v[48:63]
	v_mfma_f32_32x32x16_bf16 v[112:127], v[176:179], v[172:175], v[112:127]
	v_mfma_f32_32x32x16_bf16 v[112:127], v[218:221], v[144:147], v[112:127]
	s_cbranch_scc1 .LBB0_822
	s_mov_b32 s6, s11
	s_mov_b32 s11, s9
	s_mov_b32 s9, s13
	v_mov_b32_e32 v187, v132
	s_cmpk_gt_u32 s10, 0x81
	s_mov_b32 s13, s6
	s_cbranch_scc0 .LBB0_803
	s_branch .LBB0_808

;     __device__ __forceinline__ void operator()(const f32x4 (&acc)[2][2][4][2], const Unit& u, int wr, int wc, int fr, int fq) const {
;         asm volatile("" : "+v"(fr), "+v"(fq));
;         const int s = u.pm < 128 ? (u.pm >> 5) : 4;
;         const int row0 = u.pm * BM + wr * 64 + fr; const int col0 = u.pn * BM + wc * 32 + 8 * fq;
;         const float* xo = (u.pm < 128) ? xoldL + (size_t)row0 * DM : xoldC + (size_t)(row0 - RL) * DM;
;         float* xn = xnew + (size_t)row0 * DM;
;         const bool partial = (u.kind >= 1);
;         float* pp = part + ((size_t)(u.kind - 1) * RC + (row0 - RL)) * DM;
;         f32x4 gv[2][2];
; #pragma unroll
;         for (int bj = 0; bj < 2; ++bj)
; #pragma unroll
;             for (int n = 0; n < 2; ++n) gv[bj][n] = *(const f32x4*)(gate + (size_t)s * 9216 + col0 + bj * HALF + 4 * n) * gscale;
;         if (partial) {
; #pragma unroll
;             for (int ai = 0; ai < 2; ++ai)
; #pragma unroll
;                 for (int m = 0; m < 4; ++m) {
;                     const size_t ro = (size_t)(ai * HALF + m * 16) * DM + col0;
; #pragma unroll
;                     for (int bj = 0; bj < 2; ++bj)
; #pragma unroll
;                         for (int n = 0; n < 2; ++n) *(f32x4*)(pp + ro + bj * HALF + 4 * n) = acc[ai][bj][m][n];
;                 }
;         } else {
; #pragma unroll
;             for (int ai = 0; ai < 2; ++ai) {
;                 f32x4 xv[4][2][2];
; #pragma unroll
;                 for (int m = 0; m < 4; ++m)
; #pragma unroll
;                     for (int bj = 0; bj < 2; ++bj)
; #pragma unroll
;                         for (int n = 0; n < 2; ++n) xv[m][bj][n] = *(const f32x4*)(xo + (size_t)(ai * HALF + m * 16) * DM + col0 + bj * HALF + 4 * n);
;                 __builtin_amdgcn_sched_barrier(0);
; #pragma unroll
;                 for (int m = 0; m < 4; ++m)
; #pragma unroll
;                     for (int bj = 0; bj < 2; ++bj)
; #pragma unroll
;                         for (int n = 0; n < 2; ++n) *(f32x4*)(xn + (size_t)(ai * HALF + m * 16) * DM + col0 + bj * HALF + 4 * n) = xv[m][bj][n] + gv[bj][n] * acc[ai][bj][m][n];
;                 __builtin_amdgcn_sched_barrier(0);
;             }
.LBB0_939:
	s_lshl_b64 s[36:37], s[38:39], 2
	v_lshlrev_b64 v[168:169], 2, v[156:157]
	s_add_u32 s36, s70, s36
	v_lshl_add_u64 v[160:161], v[158:159], 0, v[168:169]
	s_addc_u32 s37, s71, s37
	v_add_co_u32_e32 v190, vcc, s21, v160
	v_lshl_add_u64 v[140:141], s[36:37], 0, v[168:169]
	s_nop 0
	v_addc_co_u32_e32 v191, vcc, 0, v161, vcc
	s_mov_b64 s[36:37], 0x10200
	v_lshl_add_u64 v[166:167], s[82:83], 0, v[128:129]
	v_lshl_add_u64 v[186:187], v[160:161], 0, s[54:55]
	v_lshl_add_u64 v[212:213], v[160:161], 0, s[36:37]
	s_mov_b64 s[36:37], 0x20000
	v_add_co_u32_e32 v226, vcc, s24, v160
	global_load_dwordx4 v[128:131], v[140:141], off offset:528
	global_load_dwordx4 v[132:135], v[140:141], off offset:512
	global_load_dwordx4 v[136:139], v[140:141], off offset:16
	s_nop 0
	global_load_dwordx4 v[140:143], v[140:141], off
	v_lshl_add_u64 v[158:159], v[166:167], 0, v[168:169]
	global_load_dwordx4 v[166:169], v[160:161], off offset:16
	global_load_dwordx4 v[170:173], v[160:161], off
	global_load_dwordx4 v[174:177], v[160:161], off offset:528
	global_load_dwordx4 v[178:181], v[160:161], off offset:512
	global_load_dwordx4 v[182:185], v[190:191], off
	s_nop 0
	global_load_dwordx4 v[186:189], v[186:187], off offset:16
	s_nop 0
	global_load_dwordx4 v[208:211], v[190:191], off offset:512
	s_nop 0
	global_load_dwordx4 v[212:215], v[212:213], off offset:16
	v_lshl_add_u64 v[190:191], v[160:161], 0, s[36:37]
	v_addc_co_u32_e32 v227, vcc, 0, v161, vcc
	s_mov_b64 s[36:37], 0x20200
	global_load_dwordx4 v[216:219], v[226:227], off
	global_load_dwordx4 v[220:223], v[190:191], off offset:16
	v_lshl_add_u64 v[190:191], v[160:161], 0, s[36:37]
	s_mov_b64 s[36:37], 0x30000
	v_add_co_u32_e32 v242, vcc, s48, v160
	global_load_dwordx4 v[226:229], v[226:227], off offset:512
	s_nop 0
	global_load_dwordx4 v[230:233], v[190:191], off offset:16
	v_lshl_add_u64 v[190:191], v[160:161], 0, s[36:37]
	v_addc_co_u32_e32 v243, vcc, 0, v161, vcc
	s_mov_b64 s[36:37], 0x30200
	global_load_dwordx4 v[234:237], v[242:243], off
	global_load_dwordx4 v[238:241], v[190:191], off offset:16
	v_lshl_add_u64 v[190:191], v[160:161], 0, s[36:37]
	global_load_dwordx4 v[242:245], v[242:243], off offset:512
	s_nop 0
	global_load_dwordx4 v[246:249], v[190:191], off offset:16
	s_waitcnt vmcnt(0)
	v_fma_f32 v168, v122, v138, v168
	v_fma_f32 v169, v123, v139, v169
	v_fma_f32 v166, v120, v136, v166
	v_fma_f32 v167, v121, v137, v167
	v_fma_f32 v172, v126, v142, v172
	v_fma_f32 v173, v127, v143, v173
	v_fma_f32 v170, v124, v140, v170
	v_fma_f32 v171, v125, v141, v171
	global_store_dwordx4 v[158:159], v[166:169], off offset:16
	global_store_dwordx4 v[158:159], v[170:173], off
	s_nop 0
	v_fma_f32 v168, v110, v134, v180
	v_fma_f32 v169, v111, v135, v181
	v_fma_f32 v166, v108, v132, v178
	v_fma_f32 v167, v109, v133, v179
	global_store_dwordx4 v[158:159], v[166:169], off offset:512
	v_add_co_u32_e32 v170, vcc, s21, v158
	s_nop 0
	v_fma_f32 v168, v102, v130, v176
	v_fma_f32 v169, v103, v131, v177
	v_fma_f32 v166, v100, v128, v174
	v_fma_f32 v167, v101, v129, v175
	global_store_dwordx4 v[158:159], v[166:169], off offset:528
	v_addc_co_u32_e32 v171, vcc, 0, v159, vcc
	s_nop 0
	v_fma_f32 v168, v118, v142, v184
	v_fma_f32 v169, v119, v143, v185
	v_fma_f32 v166, v116, v140, v182
	v_fma_f32 v167, v117, v141, v183
	global_store_dwordx4 v[170:171], v[166:169], off
	s_nop 1
	v_fma_f32 v168, v114, v138, v188
	v_fma_f32 v169, v115, v139, v189
	v_fma_f32 v166, v112, v136, v186
	v_fma_f32 v167, v113, v137, v187
	global_store_dwordx4 v[170:171], v[166:169], off offset:16
	s_nop 1
	v_fma_f32 v168, v94, v134, v210
	v_fma_f32 v169, v95, v135, v211
	v_fma_f32 v166, v92, v132, v208
	v_fma_f32 v167, v93, v133, v209
	global_store_dwordx4 v[170:171], v[166:169], off offset:512
	s_nop 1
	v_fma_f32 v168, v86, v130, v214
	v_fma_f32 v169, v87, v131, v215
	v_fma_f32 v166, v84, v128, v212
	v_fma_f32 v167, v85, v129, v213
	global_store_dwordx4 v[170:171], v[166:169], off offset:528
	v_add_co_u32_e32 v170, vcc, s24, v158
	s_nop 0
	v_fma_f32 v168, v106, v142, v218
	v_fma_f32 v169, v107, v143, v219
	v_fma_f32 v166, v104, v140, v216
	v_fma_f32 v167, v105, v141, v217
	v_addc_co_u32_e32 v171, vcc, 0, v159, vcc
	global_store_dwordx4 v[170:171], v[166:169], off
	s_nop 1
	v_fma_f32 v168, v98, v138, v222
	v_fma_f32 v169, v99, v139, v223
	v_fma_f32 v166, v96, v136, v220
	v_fma_f32 v167, v97, v137, v221
	global_store_dwordx4 v[170:171], v[166:169], off offset:16
	s_nop 1
	v_fma_f32 v168, v78, v134, v228
	v_fma_f32 v169, v79, v135, v229
	v_fma_f32 v166, v76, v132, v226
	v_fma_f32 v167, v77, v133, v227
	global_store_dwordx4 v[170:171], v[166:169], off offset:512
	s_nop 1
	v_fma_f32 v168, v74, v130, v232
	v_fma_f32 v169, v75, v131, v233
	v_fma_f32 v166, v72, v128, v230
	v_fma_f32 v167, v73, v129, v231
	global_store_dwordx4 v[170:171], v[166:169], off offset:528
	v_add_co_u32_e32 v170, vcc, s48, v158
	s_nop 0
	v_fma_f32 v168, v90, v142, v236
	v_fma_f32 v169, v91, v143, v237
	v_fma_f32 v166, v88, v140, v234
	v_fma_f32 v167, v89, v141, v235
	v_addc_co_u32_e32 v171, vcc, 0, v159, vcc
	global_store_dwordx4 v[170:171], v[166:169], off
	s_nop 1
	v_fma_f32 v168, v82, v138, v240
	v_fma_f32 v169, v83, v139, v241
	v_fma_f32 v166, v80, v136, v238
	v_fma_f32 v167, v81, v137, v239
	global_store_dwordx4 v[170:171], v[166:169], off offset:16
	s_nop 1
	v_fma_f32 v168, v70, v134, v244
	v_fma_f32 v169, v71, v135, v245
	v_fma_f32 v166, v68, v132, v242
	v_fma_f32 v167, v69, v133, v243
	global_store_dwordx4 v[170:171], v[166:169], off offset:512
	s_nop 1
	v_fma_f32 v168, v66, v130, v248
	v_fma_f32 v169, v67, v131, v249
	v_fma_f32 v166, v64, v128, v246
	v_fma_f32 v167, v65, v129, v247
;     __device__ __forceinline__ void operator()(const f32x4 (&acc)[2][2][4][2], const Unit& u, int wr, int wc, int fr, int fq) const {
;     ...
;             for (int ai = 0; ai < 2; ++ai) {
;                 f32x4 xv[4][2][2];
; #pragma unroll
;                 for (int m = 0; m < 4; ++m)
; #pragma unroll
;                     for (int bj = 0; bj < 2; ++bj)
; #pragma unroll
;                         for (int n = 0; n < 2; ++n) xv[m][bj][n] = *(const f32x4*)(xo + (size_t)(ai * HALF + m * 16) * DM + col0 + bj * HALF + 4 * n);
;                 __builtin_amdgcn_sched_barrier(0);
; #pragma unroll
;                 for (int m = 0; m < 4; ++m)
; #pragma unroll
;                     for (int bj = 0; bj < 2; ++bj)
; #pragma unroll
;                         for (int n = 0; n < 2; ++n) *(f32x4*)(xn + (size_t)(ai * HALF + m * 16) * DM + col0 + bj * HALF + 4 * n) = xv[m][bj][n] + gv[bj][n] * acc[ai][bj][m][n];
;                 __builtin_amdgcn_sched_barrier(0);
;             }
	global_store_dwordx4 v[170:171], v[166:169], off offset:528
	v_add_co_u32_e32 v174, vcc, s49, v160
	s_mov_b64 s[36:37], 0x80000
	s_nop 0
	v_addc_co_u32_e32 v175, vcc, 0, v161, vcc
	v_lshl_add_u64 v[170:171], v[160:161], 0, s[36:37]
	s_mov_b64 s[36:37], 0x80200
	v_add_co_u32_e32 v190, vcc, s50, v160
	v_lshl_add_u64 v[178:179], v[160:161], 0, s[36:37]
	s_mov_b64 s[36:37], 0x90000
	v_addc_co_u32_e32 v191, vcc, 0, v161, vcc
	v_lshl_add_u64 v[186:187], v[160:161], 0, s[36:37]
	s_mov_b64 s[36:37], 0x90200
	v_add_co_u32_e32 v226, vcc, s51, v160
	v_lshl_add_u64 v[212:213], v[160:161], 0, s[36:37]
	s_mov_b64 s[36:37], 0xa0000
	v_addc_co_u32_e32 v227, vcc, 0, v161, vcc
	global_load_dwordx4 v[166:169], v[174:175], off
	s_nop 0
	global_load_dwordx4 v[170:173], v[170:171], off offset:16
	s_nop 0
	global_load_dwordx4 v[174:177], v[174:175], off offset:512
	s_nop 0
	global_load_dwordx4 v[178:181], v[178:179], off offset:16
	s_nop 0
	global_load_dwordx4 v[182:185], v[190:191], off
	s_nop 0
	global_load_dwordx4 v[186:189], v[186:187], off offset:16
	s_nop 0
	global_load_dwordx4 v[208:211], v[190:191], off offset:512
	s_nop 0
	global_load_dwordx4 v[212:215], v[212:213], off offset:16
	v_lshl_add_u64 v[190:191], v[160:161], 0, s[36:37]
	s_mov_b64 s[36:37], 0xa0200
	v_add_co_u32_e32 v242, vcc, s52, v160
	global_load_dwordx4 v[216:219], v[226:227], off
	global_load_dwordx4 v[220:223], v[190:191], off offset:16
	v_lshl_add_u64 v[190:191], v[160:161], 0, s[36:37]
	v_addc_co_u32_e32 v243, vcc, 0, v161, vcc
	s_mov_b64 s[36:37], 0xb0200
	global_load_dwordx4 v[226:229], v[226:227], off offset:512
	s_nop 0
	global_load_dwordx4 v[230:233], v[190:191], off offset:16
	v_lshl_add_u64 v[190:191], v[160:161], 0, s[26:27]
	global_load_dwordx4 v[234:237], v[242:243], off
	global_load_dwordx4 v[238:241], v[190:191], off offset:16
	v_lshl_add_u64 v[160:161], v[160:161], 0, s[36:37]
	global_load_dwordx4 v[242:245], v[242:243], off offset:512
	s_nop 0
	global_load_dwordx4 v[246:249], v[160:161], off offset:16
	v_add_co_u32_e32 v160, vcc, s49, v158
	s_waitcnt vmcnt(15)
	v_fma_f32 v168, v62, v142, v168
	v_fma_f32 v169, v63, v143, v169
	v_fma_f32 v166, v60, v140, v166
	v_fma_f32 v167, v61, v141, v167
	v_addc_co_u32_e32 v161, vcc, 0, v159, vcc
	global_store_dwordx4 v[160:161], v[166:169], off
	s_waitcnt vmcnt(15)
	s_nop 0
	v_fma_f32 v168, v58, v138, v172
	v_fma_f32 v169, v59, v139, v173
	v_fma_f32 v166, v56, v136, v170
	v_fma_f32 v167, v57, v137, v171
	global_store_dwordx4 v[160:161], v[166:169], off offset:16
	s_waitcnt vmcnt(15)
	s_nop 0
	v_fma_f32 v168, v46, v134, v176
	v_fma_f32 v169, v47, v135, v177
	v_fma_f32 v166, v44, v132, v174
	v_fma_f32 v167, v45, v133, v175
	global_store_dwordx4 v[160:161], v[166:169], off offset:512
	s_waitcnt vmcnt(15)
	s_nop 0
	v_fma_f32 v168, v38, v130, v180
	v_fma_f32 v169, v39, v131, v181
	v_fma_f32 v166, v36, v128, v178
	v_fma_f32 v167, v37, v129, v179
	global_store_dwordx4 v[160:161], v[166:169], off offset:528
	v_add_co_u32_e32 v160, vcc, s50, v158
	s_waitcnt vmcnt(15)
	v_fma_f32 v168, v54, v142, v184
	v_fma_f32 v169, v55, v143, v185
	v_fma_f32 v166, v52, v140, v182
	v_fma_f32 v167, v53, v141, v183
	v_addc_co_u32_e32 v161, vcc, 0, v159, vcc
	global_store_dwordx4 v[160:161], v[166:169], off
	s_waitcnt vmcnt(15)
	s_nop 0
	v_fma_f32 v168, v50, v138, v188
	v_fma_f32 v169, v51, v139, v189
	v_fma_f32 v166, v48, v136, v186
	v_fma_f32 v167, v49, v137, v187
	global_store_dwordx4 v[160:161], v[166:169], off offset:16
	s_waitcnt vmcnt(15)
	s_nop 0
	v_fma_f32 v168, v30, v134, v210
	v_fma_f32 v169, v31, v135, v211
	v_fma_f32 v166, v28, v132, v208
	v_fma_f32 v167, v29, v133, v209
	global_store_dwordx4 v[160:161], v[166:169], off offset:512
	s_waitcnt vmcnt(15)
	s_nop 0
	v_fma_f32 v168, v22, v130, v214
	v_fma_f32 v169, v23, v131, v215
	v_fma_f32 v166, v20, v128, v212
	v_fma_f32 v167, v21, v129, v213
	global_store_dwordx4 v[160:161], v[166:169], off offset:528
	v_add_co_u32_e32 v160, vcc, s51, v158
	s_waitcnt vmcnt(15)
	v_fma_f32 v168, v42, v142, v218
	v_fma_f32 v169, v43, v143, v219
	v_fma_f32 v166, v40, v140, v216
	v_fma_f32 v167, v41, v141, v217
	v_addc_co_u32_e32 v161, vcc, 0, v159, vcc
	global_store_dwordx4 v[160:161], v[166:169], off
	v_add_co_u32_e32 v158, vcc, s52, v158
	s_waitcnt vmcnt(15)
	v_fma_f32 v168, v34, v138, v222
	v_fma_f32 v169, v35, v139, v223
	v_fma_f32 v166, v32, v136, v220
	v_fma_f32 v167, v33, v137, v221
	global_store_dwordx4 v[160:161], v[166:169], off offset:16
	s_waitcnt vmcnt(13)
	v_fma_f32 v142, v26, v142, v236
	v_fma_f32 v143, v27, v143, v237
	v_fma_f32 v140, v24, v140, v234
	v_fma_f32 v141, v25, v141, v235
	v_fma_f32 v168, v14, v134, v228
	v_fma_f32 v169, v15, v135, v229
	v_fma_f32 v166, v12, v132, v226
	v_fma_f32 v167, v13, v133, v227
	global_store_dwordx4 v[160:161], v[166:169], off offset:512
	v_addc_co_u32_e32 v159, vcc, 0, v159, vcc
	s_nop 0
	v_fma_f32 v168, v10, v130, v232
	v_fma_f32 v169, v11, v131, v233
	v_fma_f32 v166, v8, v128, v230
	v_fma_f32 v167, v9, v129, v231
	s_waitcnt vmcnt(13)
	v_fma_f32 v138, v18, v138, v240
	v_fma_f32 v139, v19, v139, v241
	v_fma_f32 v136, v16, v136, v238
	v_fma_f32 v137, v17, v137, v239
	s_waitcnt vmcnt(12)
	v_fma_f32 v134, v6, v134, v244
	v_fma_f32 v135, v7, v135, v245
	v_fma_f32 v132, v4, v132, v242
	v_fma_f32 v133, v5, v133, v243
	s_waitcnt vmcnt(11)
	v_fma_f32 v130, v2, v130, v248
	v_fma_f32 v131, v3, v131, v249
	v_fma_f32 v128, v0, v128, v246
	v_fma_f32 v129, v1, v129, v247
	global_store_dwordx4 v[160:161], v[166:169], off offset:528
	global_store_dwordx4 v[158:159], v[140:143], off
	global_store_dwordx4 v[158:159], v[136:139], off offset:16
	global_store_dwordx4 v[158:159], v[132:135], off offset:512
	global_store_dwordx4 v[158:159], v[128:131], off offset:528
	s_cbranch_execnz .LBB0_938

; __device__ __forceinline__ unsigned cvt_pk_bf16(float lo, float hi) { const f32x2 v = {lo, hi}; const bf16x2_t b = __builtin_convertvector(v, bf16x2_t); return __builtin_bit_cast(unsigned, b); }
; __device__ __forceinline__ float wave_sum(float v) { return xadd32(sum32(v)); }
; __device__ __forceinline__ void norm_row(const f32x4 (&v)[4], const f32x4 (&gn)[4], const float* sh, bf16_t* hrow, int lane) {
;     const float* scl = sh + 1024;
;     f32x4 sv[4], cv[4];
; #pragma unroll
;     for (int j = 0; j < 4; ++j) { sv[j] = *(const f32x4*)(sh + 4 * lane + 256 * j); cv[j] = *(const f32x4*)(scl + 4 * lane + 256 * j); }
;     float ss = 0.f;
; #pragma unroll
;     for (int j = 0; j < 4; ++j) ss += (v[j][0] * v[j][0] + v[j][1] * v[j][1]) + (v[j][2] * v[j][2] + v[j][3] * v[j][3]);
;     const float rstd = __builtin_amdgcn_rsqf(wave_sum(ss) * (1.0f / DM) + EPS);
; #pragma unroll
;     for (int j = 0; j < 4; ++j) {
;         const f32x4 y = v[j] * rstd * gn[j] * (cv[j] + 1.0f) + sv[j];
;         u32x2 w; w.x = cvt_pk_bf16(y[0], y[1]); w.y = cvt_pk_bf16(y[2], y[3]);
;         *(u32x2*)(hrow + 4 * lane + 256 * j) = w;
;     }
; __device__ __forceinline__ void norm_phase(const float* xL, const float* xC, const float* gain, const float* modl  , int ishift, bf16_t* H, int nrows,
;                                            const float* part, int nsplit, const float* pgate  , float pscale, float* xCw) {
;     ...
;         for (; row < nplain; row += NGW) {
;             const int rn = row + NGW;
;             if (rn < nplain) { const float* xr = rn < RL ? xL + (size_t)rn * DM : xC + (size_t)(rn - RL) * DM;
; #pragma unroll
;                 for (int j = 0; j < 4; ++j) vn[j] = *(const f32x4*)(xr + 4 * lane + 256 * j); }
;             const int s = row < RL ? (row >> 13) : 4;
;             norm_row(v, gn, modl + (size_t)s * 9216 + ishift * 1024, H + (size_t)row * DM, lane);
; #pragma unroll
;             for (int j = 0; j < 4; ++j) v[j] = vn[j];
;         }
.LBB0_999:
	s_ashr_i32 s9, s9, 13
	s_mul_hi_i32 s11, s9, 0x9000
	s_mul_i32 s9, s9, 0x9000
	s_add_u32 s10, s5, s9
	s_addc_u32 s11, s8, s11
	global_load_dwordx4 v[74:77], v194, s[10:11]
	v_lshl_add_u64 v[48:49], s[10:11], 0, v[194:195]
	v_lshl_add_u64 v[52:53], v[48:49], 0, s[24:25]
	v_add_co_u32_e32 v48, vcc, s76, v48
	v_mul_f32_e32 v73, v45, v45
	s_nop 0
	v_addc_co_u32_e32 v49, vcc, 0, v49, vcc
	global_load_dwordx4 v[78:81], v[48:49], off
	global_load_dwordx4 v[82:85], v194, s[10:11] offset:1024
	global_load_dwordx4 v[86:89], v[52:53], off offset:1024
	global_load_dwordx4 v[56:59], v194, s[10:11] offset:2048
	global_load_dwordx4 v[60:63], v[52:53], off offset:2048
	s_nop 0
	global_load_dwordx4 v[48:51], v194, s[10:11] offset:3072
	s_nop 0
	global_load_dwordx4 v[52:55], v[52:53], off offset:3072
	v_mul_f32_e32 v90, v47, v47
	v_fmac_f32_e32 v73, v44, v44
	v_fmac_f32_e32 v90, v46, v46
	v_add_f32_e32 v73, v73, v90
	v_mul_f32_e32 v90, v41, v41
	v_mul_f32_e32 v91, v43, v43
	v_fmac_f32_e32 v90, v40, v40
	v_fmac_f32_e32 v91, v42, v42
	v_add_f32_e32 v90, v90, v91
	v_add_f32_e32 v73, v73, v90
	v_mul_f32_e32 v90, v37, v37
	v_mul_f32_e32 v91, v39, v39
	v_mul_f32_e32 v70, v70, v70
	v_fmac_f32_e32 v90, v36, v36
	v_fmac_f32_e32 v91, v38, v38
	v_fmac_f32_e32 v70, v68, v68
	v_mul_f32_e32 v68, v71, v71
	v_add_f32_e32 v90, v90, v91
	v_fmac_f32_e32 v68, v69, v69
	v_add_f32_e32 v73, v90, v73
	v_add_f32_e32 v68, v70, v68
	v_add_f32_e32 v68, v68, v73
	ds_swizzle_b32 v69, v68 offset:swizzle(SWAP,1)
	v_lshl_add_u64 v[70:71], s[96:97], 0, v[64:65]
	v_lshl_add_u64 v[64:65], v[64:65], 0, s[92:93]
	v_lshl_add_u64 v[66:67], v[66:67], 0, s[64:65]
	s_mov_b32 s9, s7
	s_waitcnt lgkmcnt(0)
	v_add_f32_e32 v68, v68, v69
	ds_swizzle_b32 v69, v68 offset:swizzle(SWAP,2)
	s_waitcnt lgkmcnt(0)
	v_add_f32_e32 v68, v68, v69
	ds_swizzle_b32 v69, v68 offset:swizzle(SWAP,4)
	s_waitcnt lgkmcnt(0)
	v_add_f32_e32 v68, v68, v69
	ds_swizzle_b32 v69, v68 offset:swizzle(SWAP,8)
	s_waitcnt lgkmcnt(0)
	v_add_f32_e32 v68, v68, v69
	ds_swizzle_b32 v69, v68 offset:swizzle(SWAP,16)
	s_waitcnt lgkmcnt(0)
	v_add_f32_e32 v68, v68, v69
	v_mov_b32_e32 v69, v68
	s_nop 1
	v_permlane32_swap_b32_e32 v68, v69
	v_add_f32_e32 v68, v68, v69
	v_fmamk_f32 v68, v68, 0x3a800000, v193
	v_rsq_f32_e32 v68, v68
	s_waitcnt vmcnt(6)
	v_add_f32_e32 v80, 1.0, v80
	v_add_f32_e32 v81, 1.0, v81
	v_mul_f32_e32 v46, v46, v68
	v_mul_f32_e32 v47, v47, v68
	v_mul_f32_e32 v44, v44, v68
	v_mul_f32_e32 v45, v45, v68
	v_mul_f32_e32 v46, v2, v46
	v_mul_f32_e32 v47, v3, v47
	v_mul_f32_e32 v44, v0, v44
	v_mul_f32_e32 v45, v1, v45
	v_add_f32_e32 v78, 1.0, v78
	v_add_f32_e32 v79, 1.0, v79
	v_fma_f32 v46, v80, v46, v76
	v_fma_f32 v47, v81, v47, v77
	v_fma_f32 v44, v78, v44, v74
	v_fma_f32 v45, v79, v45, v75
	v_mul_f32_e32 v42, v42, v68
	v_mul_f32_e32 v43, v43, v68
	v_cvt_pk_bf16_f32 v44, v44, v45
	v_cvt_pk_bf16_f32 v45, v46, v47
	v_add_co_u32_e32 v46, vcc, s47, v70
	v_mul_f32_e32 v40, v40, v68
	v_mul_f32_e32 v41, v41, v68
	s_nop 0
	v_addc_co_u32_e32 v47, vcc, 0, v71, vcc
	global_store_dwordx2 v[46:47], v[44:45], off
	v_mul_f32_e32 v40, v4, v40
	v_mul_f32_e32 v41, v5, v41
	v_mul_f32_e32 v42, v6, v42
	v_mul_f32_e32 v43, v7, v43
	s_waitcnt vmcnt(5)
	v_add_f32_e32 v44, 1.0, v88
	v_add_f32_e32 v45, 1.0, v89
	v_add_f32_e32 v70, 1.0, v86
	v_add_f32_e32 v71, 1.0, v87
	v_fma_f32 v42, v44, v42, v84
	v_fma_f32 v43, v45, v43, v85
	v_fma_f32 v40, v70, v40, v82
	v_fma_f32 v41, v71, v41, v83
	v_mul_f32_e32 v38, v38, v68
	v_mul_f32_e32 v39, v39, v68
	v_cvt_pk_bf16_f32 v40, v40, v41
	v_cvt_pk_bf16_f32 v41, v42, v43
	v_mul_f32_e32 v36, v36, v68
	v_mul_f32_e32 v37, v37, v68
	global_store_dwordx2 v[46:47], v[40:41], off offset:512
	v_mul_f32_e32 v36, v8, v36
	v_mul_f32_e32 v37, v9, v37
	v_mul_f32_e32 v38, v10, v38
	v_mul_f32_e32 v39, v11, v39
	s_waitcnt vmcnt(4)
	v_add_f32_e32 v40, 1.0, v62
	v_add_f32_e32 v41, 1.0, v63
	v_add_f32_e32 v42, 1.0, v60
	v_add_f32_e32 v43, 1.0, v61
	v_fma_f32 v38, v40, v38, v58
	v_fma_f32 v39, v41, v39, v59
	v_fma_f32 v36, v42, v36, v56
	v_fma_f32 v37, v43, v37, v57
	v_mul_f32_e32 v18, v18, v68
	v_mul_f32_e32 v19, v19, v68
	v_cvt_pk_bf16_f32 v36, v36, v37
	v_cvt_pk_bf16_f32 v37, v38, v39
	v_mul_f32_e32 v16, v16, v68
	v_mul_f32_e32 v17, v17, v68
	global_store_dwordx2 v[46:47], v[36:37], off offset:1024
	v_mul_f32_e32 v16, v12, v16
	v_mul_f32_e32 v17, v13, v17
	v_mul_f32_e32 v18, v14, v18
	v_mul_f32_e32 v19, v15, v19
	s_waitcnt vmcnt(3)
	v_add_f32_e32 v36, 1.0, v54
	v_add_f32_e32 v37, 1.0, v55
	v_add_f32_e32 v38, 1.0, v52
	v_add_f32_e32 v39, 1.0, v53
	v_fma_f32 v18, v36, v18, v50
	v_fma_f32 v19, v37, v19, v51
	v_fma_f32 v16, v38, v16, v48
	v_fma_f32 v17, v39, v17, v49
	s_andn2_b64 vcc, exec, s[0:1]
	v_cvt_pk_bf16_f32 v16, v16, v17
	v_cvt_pk_bf16_f32 v17, v18, v19
	global_store_dwordx2 v[46:47], v[16:17], off offset:1536
	v_mov_b64_e32 v[16:17], v[20:21]
	v_mov_b64_e32 v[18:19], v[22:23]
	v_mov_b32_e32 v44, v32
	v_mov_b32_e32 v45, v33
	v_mov_b32_e32 v46, v34
	v_mov_b32_e32 v47, v35
	v_mov_b32_e32 v40, v28
	v_mov_b32_e32 v41, v29
	v_mov_b32_e32 v42, v30
	v_mov_b32_e32 v43, v31
	v_mov_b32_e32 v36, v24
	v_mov_b32_e32 v37, v25
	v_mov_b32_e32 v38, v26
	v_mov_b32_e32 v39, v27
	v_mov_b32_e32 v68, v20
	v_mov_b32_e32 v70, v21
	v_mov_b32_e32 v69, v22
	v_mov_b32_e32 v71, v23
	s_cbranch_vccz .LBB0_1002

; __device__ __forceinline__ void norm_phase(const float* xL, const float* xC, const float* gain, const float* modl  , int ishift, bf16_t* H, int nrows,
;                                            const float* part, int nsplit, const float* pgate  , float pscale, float* xCw) {
;     ...
;     if (nsplit > 0) for (int row = RL + gw; row < nrows; row += NGW) {
;         f32x4 v[4];
;         const float* xr = xC + (size_t)(row - RL) * DM;
; #pragma unroll
;         for (int j = 0; j < 4; ++j) v[j] = *(const f32x4*)(xr + 4 * lane + 256 * j);
; #pragma unroll
;         for (int j = 0; j < 4; ++j) {
;             f32x4 pv[11];
; #pragma unroll
;             for (int ks = 0; ks < 11; ++ks) if (ks < nsplit) pv[ks] = *(const f32x4*)(part + ((size_t)ks * RC + (row - RL)) * DM + 4 * lane + 256 * j);
;             f32x4 sum = {0.f, 0.f, 0.f, 0.f};
; #pragma unroll
;             for (int ks = 0; ks < 11; ++ks) if (ks < nsplit) sum += pv[ks];
;             v[j] += sum * (*(const f32x4*)(pgate + 4 * lane + 256 * j) * pscale);
;             *(f32x4*)(xCw + (size_t)(row - RL) * DM + 4 * lane + 256 * j) = v[j];
.LBB0_1004:
	v_lshl_add_u64 v[40:41], s[96:97], 0, v[72:73]
	v_add_co_u32_e32 v32, vcc, 0x12000000, v40
	s_add_i32 s0, s0, s88
	s_nop 0
	v_addc_co_u32_e32 v33, vcc, 0, v41, vcc
	v_add_co_u32_e32 v34, vcc, 0x21b80000, v40
	global_load_dwordx4 v[16:19], v[32:33], off
	global_load_dwordx4 v[24:27], v[32:33], off offset:1024
	global_load_dwordx4 v[28:31], v[32:33], off offset:2048
	global_load_dwordx4 v[20:23], v[32:33], off offset:3072
	v_addc_co_u32_e32 v35, vcc, 0, v41, vcc
	v_add_co_u32_e32 v36, vcc, 0x21f80000, v40
	global_load_dwordx4 v[42:45], v[34:35], off
	s_nop 0
	v_addc_co_u32_e32 v37, vcc, 0, v41, vcc
	v_add_co_u32_e32 v38, vcc, 0x22380000, v40
	global_load_dwordx4 v[46:49], v[36:37], off
	s_nop 0
	v_addc_co_u32_e32 v39, vcc, 0, v41, vcc
	v_add_co_u32_e32 v40, vcc, 0x22780000, v40
	global_load_dwordx4 v[50:53], v[38:39], off
	s_nop 0
	v_addc_co_u32_e32 v41, vcc, 0, v41, vcc
	global_load_dwordx4 v[54:57], v[40:41], off
	v_lshl_add_u64 v[72:73], v[72:73], 0, s[64:65]
	s_cmp_lt_i32 s0, s5
	s_waitcnt vmcnt(3)
	v_add_f32_e32 v44, 0, v44
	v_add_f32_e32 v45, 0, v45
	v_add_f32_e32 v42, 0, v42
	v_add_f32_e32 v43, 0, v43
	s_waitcnt vmcnt(2)
	v_add_f32_e32 v44, v44, v48
	v_add_f32_e32 v45, v45, v49
	v_add_f32_e32 v42, v42, v46
	v_add_f32_e32 v43, v43, v47
	s_waitcnt vmcnt(1)
	v_add_f32_e32 v44, v44, v52
	v_add_f32_e32 v45, v45, v53
	v_add_f32_e32 v42, v42, v50
	v_add_f32_e32 v43, v43, v51
	s_waitcnt vmcnt(0)
	v_add_f32_e32 v46, v44, v56
	v_add_f32_e32 v47, v45, v57
	v_add_f32_e32 v48, v42, v54
	v_add_f32_e32 v49, v43, v55
	global_load_dwordx4 v[42:45], v[64:65], off
	s_waitcnt vmcnt(0)
	v_fma_f32 v18, v46, v44, v18
	v_fma_f32 v19, v47, v45, v19
	v_fma_f32 v16, v48, v42, v16
	v_fma_f32 v17, v49, v43, v17
	global_store_dwordx4 v[32:33], v[16:19], off
	global_load_dwordx4 v[42:45], v[34:35], off offset:1024
	global_load_dwordx4 v[46:49], v[36:37], off offset:1024
	global_load_dwordx4 v[50:53], v[38:39], off offset:1024
	global_load_dwordx4 v[54:57], v[40:41], off offset:1024
	v_mul_f32_e32 v74, v17, v17
	v_mul_f32_e32 v75, v19, v19
	v_fmac_f32_e32 v74, v16, v16
	v_fmac_f32_e32 v75, v18, v18
	v_add_f32_e32 v74, v74, v75
	s_waitcnt vmcnt(3)
	v_add_f32_e32 v44, 0, v44
	v_add_f32_e32 v45, 0, v45
	v_add_f32_e32 v42, 0, v42
	v_add_f32_e32 v43, 0, v43
	s_waitcnt vmcnt(2)
	v_add_f32_e32 v44, v44, v48
	v_add_f32_e32 v45, v45, v49
	v_add_f32_e32 v42, v42, v46
	v_add_f32_e32 v43, v43, v47
	s_waitcnt vmcnt(1)
	v_add_f32_e32 v44, v44, v52
	v_add_f32_e32 v45, v45, v53
	v_add_f32_e32 v42, v42, v50
	v_add_f32_e32 v43, v43, v51
	s_waitcnt vmcnt(0)
	v_add_f32_e32 v46, v44, v56
	v_add_f32_e32 v47, v45, v57
	v_add_f32_e32 v48, v42, v54
	v_add_f32_e32 v49, v43, v55
	global_load_dwordx4 v[42:45], v[64:65], off offset:1024
	s_waitcnt vmcnt(0)
	v_fma_f32 v26, v46, v44, v26
	v_fma_f32 v27, v47, v45, v27
	v_fma_f32 v24, v48, v42, v24
	v_fma_f32 v25, v49, v43, v25
	global_store_dwordx4 v[32:33], v[24:27], off offset:1024
	global_load_dwordx4 v[42:45], v[34:35], off offset:2048
	global_load_dwordx4 v[46:49], v[36:37], off offset:2048
	global_load_dwordx4 v[50:53], v[38:39], off offset:2048
	global_load_dwordx4 v[54:57], v[40:41], off offset:2048
	v_mul_f32_e32 v75, v25, v25
	v_mul_f32_e32 v76, v27, v27
	v_fmac_f32_e32 v75, v24, v24
	v_fmac_f32_e32 v76, v26, v26
	v_add_f32_e32 v75, v75, v76
	v_add_f32_e32 v74, v74, v75
	s_waitcnt vmcnt(3)
	v_add_f32_e32 v44, 0, v44
	v_add_f32_e32 v45, 0, v45
	v_add_f32_e32 v42, 0, v42
	v_add_f32_e32 v43, 0, v43
	s_waitcnt vmcnt(2)
	v_add_f32_e32 v44, v44, v48
	v_add_f32_e32 v45, v45, v49
	v_add_f32_e32 v42, v42, v46
	v_add_f32_e32 v43, v43, v47
	s_waitcnt vmcnt(1)
	v_add_f32_e32 v44, v44, v52
	v_add_f32_e32 v45, v45, v53
	v_add_f32_e32 v42, v42, v50
	v_add_f32_e32 v43, v43, v51
	s_waitcnt vmcnt(0)
	v_add_f32_e32 v46, v44, v56
	v_add_f32_e32 v47, v45, v57
	v_add_f32_e32 v48, v42, v54
	v_add_f32_e32 v49, v43, v55
	global_load_dwordx4 v[42:45], v[64:65], off offset:2048
	s_waitcnt vmcnt(0)
	v_fma_f32 v30, v46, v44, v30
	v_fma_f32 v31, v47, v45, v31
	v_fma_f32 v28, v48, v42, v28
	v_fma_f32 v29, v49, v43, v29
	global_store_dwordx4 v[32:33], v[28:31], off offset:2048
	global_load_dwordx4 v[42:45], v[34:35], off offset:3072
	s_nop 0
	global_load_dwordx4 v[34:37], v[36:37], off offset:3072
	s_nop 0
	global_load_dwordx4 v[46:49], v[38:39], off offset:3072
	s_nop 0
	global_load_dwordx4 v[38:41], v[40:41], off offset:3072
	v_mul_f32_e32 v75, v29, v29
	v_mul_f32_e32 v76, v31, v31
	v_fmac_f32_e32 v75, v28, v28
	v_fmac_f32_e32 v76, v30, v30
	v_add_f32_e32 v75, v75, v76
	v_add_f32_e32 v74, v74, v75
	s_waitcnt vmcnt(3)
; __device__ __forceinline__ unsigned cvt_pk_bf16(float lo, float hi) { const f32x2 v = {lo, hi}; const bf16x2_t b = __builtin_convertvector(v, bf16x2_t); return __builtin_bit_cast(unsigned, b); }
; __device__ __forceinline__ float wave_sum(float v) { return xadd32(sum32(v)); }
; __device__ __forceinline__ void norm_row(const f32x4 (&v)[4], const f32x4 (&gn)[4], const float* sh, bf16_t* hrow, int lane) {
;     const float* scl = sh + 1024;
;     f32x4 sv[4], cv[4];
; #pragma unroll
;     for (int j = 0; j < 4; ++j) { sv[j] = *(const f32x4*)(sh + 4 * lane + 256 * j); cv[j] = *(const f32x4*)(scl + 4 * lane + 256 * j); }
;     float ss = 0.f;
; #pragma unroll
;     for (int j = 0; j < 4; ++j) ss += (v[j][0] * v[j][0] + v[j][1] * v[j][1]) + (v[j][2] * v[j][2] + v[j][3] * v[j][3]);
;     const float rstd = __builtin_amdgcn_rsqf(wave_sum(ss) * (1.0f / DM) + EPS);
; #pragma unroll
;     for (int j = 0; j < 4; ++j) {
;         const f32x4 y = v[j] * rstd * gn[j] * (cv[j] + 1.0f) + sv[j];
;         u32x2 w; w.x = cvt_pk_bf16(y[0], y[1]); w.y = cvt_pk_bf16(y[2], y[3]);
;         *(u32x2*)(hrow + 4 * lane + 256 * j) = w;
;     }
; __device__ __forceinline__ void norm_phase(const float* xL, const float* xC, const float* gain, const float* modl  , int ishift, bf16_t* H, int nrows,
;                                            const float* part, int nsplit, const float* pgate  , float pscale, float* xCw) {
;     ...
; #pragma unroll
;         for (int j = 0; j < 4; ++j) {
;             f32x4 pv[11];
; #pragma unroll
;             for (int ks = 0; ks < 11; ++ks) if (ks < nsplit) pv[ks] = *(const f32x4*)(part + ((size_t)ks * RC + (row - RL)) * DM + 4 * lane + 256 * j);
;             f32x4 sum = {0.f, 0.f, 0.f, 0.f};
; #pragma unroll
;             for (int ks = 0; ks < 11; ++ks) if (ks < nsplit) sum += pv[ks];
;             v[j] += sum * (*(const f32x4*)(pgate + 4 * lane + 256 * j) * pscale);
;             *(f32x4*)(xCw + (size_t)(row - RL) * DM + 4 * lane + 256 * j) = v[j];
;         }
;         norm_row(v, gn, modl + (size_t)4 * 9216 + ishift * 1024, H + (size_t)row * DM, lane);
	v_add_f32_e32 v44, 0, v44
	v_add_f32_e32 v45, 0, v45
	v_add_f32_e32 v42, 0, v42
	v_add_f32_e32 v43, 0, v43
	s_waitcnt vmcnt(2)
	v_add_f32_e32 v36, v44, v36
	v_add_f32_e32 v37, v45, v37
	v_add_f32_e32 v34, v42, v34
	v_add_f32_e32 v35, v43, v35
	s_waitcnt vmcnt(1)
	v_add_f32_e32 v36, v36, v48
	v_add_f32_e32 v37, v37, v49
	v_add_f32_e32 v34, v34, v46
	v_add_f32_e32 v35, v35, v47
	s_waitcnt vmcnt(0)
	v_add_f32_e32 v40, v36, v40
	v_add_f32_e32 v41, v37, v41
	v_add_f32_e32 v38, v34, v38
	v_add_f32_e32 v39, v35, v39
	global_load_dwordx4 v[34:37], v[64:65], off offset:3072
	s_waitcnt vmcnt(0)
	v_fma_f32 v22, v40, v36, v22
	v_fma_f32 v23, v41, v37, v23
	v_fma_f32 v20, v38, v34, v20
	v_fma_f32 v21, v39, v35, v21
	global_store_dwordx4 v[32:33], v[20:23], off offset:3072
	global_load_dwordx4 v[56:59], v[66:67], off
	global_load_dwordx4 v[60:63], v[68:69], off
	global_load_dwordx4 v[48:51], v[66:67], off offset:1024
	global_load_dwordx4 v[52:55], v[68:69], off offset:1024
	global_load_dwordx4 v[40:43], v[66:67], off offset:2048
	global_load_dwordx4 v[44:47], v[68:69], off offset:2048
	global_load_dwordx4 v[32:35], v[66:67], off offset:3072
	global_load_dwordx4 v[36:39], v[68:69], off offset:3072
	v_mul_f32_e32 v75, v21, v21
	v_mul_f32_e32 v76, v23, v23
	v_fmac_f32_e32 v75, v20, v20
	v_fmac_f32_e32 v76, v22, v22
	v_add_f32_e32 v75, v75, v76
	v_add_f32_e32 v74, v74, v75
	ds_swizzle_b32 v75, v74 offset:swizzle(SWAP,1)
	v_lshl_add_u64 v[76:77], s[96:97], 0, v[70:71]
	v_lshl_add_u64 v[70:71], v[70:71], 0, s[92:93]
	s_waitcnt lgkmcnt(0)
	v_add_f32_e32 v74, v74, v75
	ds_swizzle_b32 v75, v74 offset:swizzle(SWAP,2)
	s_waitcnt lgkmcnt(0)
	v_add_f32_e32 v74, v74, v75
	ds_swizzle_b32 v75, v74 offset:swizzle(SWAP,4)
	s_waitcnt lgkmcnt(0)
	v_add_f32_e32 v74, v74, v75
	ds_swizzle_b32 v75, v74 offset:swizzle(SWAP,8)
	s_waitcnt lgkmcnt(0)
	v_add_f32_e32 v74, v74, v75
	ds_swizzle_b32 v75, v74 offset:swizzle(SWAP,16)
	s_waitcnt lgkmcnt(0)
	v_add_f32_e32 v74, v74, v75
	v_mov_b32_e32 v75, v74
	s_nop 1
	v_permlane32_swap_b32_e32 v74, v75
	v_add_f32_e32 v74, v74, v75
	v_fmamk_f32 v74, v74, 0x3a800000, v193
	v_rsq_f32_e32 v74, v74
	s_waitcnt vmcnt(6)
	v_add_f32_e32 v62, 1.0, v62
	v_add_f32_e32 v63, 1.0, v63
	v_mul_f32_e32 v18, v18, v74
	v_mul_f32_e32 v19, v19, v74
	v_mul_f32_e32 v16, v16, v74
	v_mul_f32_e32 v17, v17, v74
	v_mul_f32_e32 v18, v2, v18
	v_mul_f32_e32 v19, v3, v19
	v_mul_f32_e32 v16, v0, v16
	v_mul_f32_e32 v17, v1, v17
	v_add_f32_e32 v60, 1.0, v60
	v_add_f32_e32 v61, 1.0, v61
	v_fma_f32 v18, v62, v18, v58
	v_fma_f32 v19, v63, v19, v59
	v_fma_f32 v16, v60, v16, v56
	v_fma_f32 v17, v61, v17, v57
	v_mul_f32_e32 v24, v24, v74
	v_mul_f32_e32 v25, v25, v74
	v_cvt_pk_bf16_f32 v16, v16, v17
	v_cvt_pk_bf16_f32 v17, v18, v19
	v_add_co_u32_e32 v18, vcc, s47, v76
	v_mul_f32_e32 v24, v4, v24
	v_mul_f32_e32 v25, v5, v25
	s_nop 0
	v_addc_co_u32_e32 v19, vcc, 0, v77, vcc
	global_store_dwordx2 v[18:19], v[16:17], off
	v_mul_f32_e32 v16, v26, v74
	v_mul_f32_e32 v17, v27, v74
	s_waitcnt vmcnt(5)
	v_add_f32_e32 v26, 1.0, v54
	v_add_f32_e32 v27, 1.0, v55
	v_mul_f32_e32 v16, v6, v16
	v_mul_f32_e32 v17, v7, v17
	v_add_f32_e32 v52, 1.0, v52
	v_add_f32_e32 v53, 1.0, v53
	v_fma_f32 v16, v26, v16, v50
	v_fma_f32 v17, v27, v17, v51
	v_fma_f32 v24, v52, v24, v48
	v_fma_f32 v25, v53, v25, v49
	s_waitcnt vmcnt(3)
	v_add_f32_e32 v26, 1.0, v46
	v_add_f32_e32 v27, 1.0, v47
	v_cvt_pk_bf16_f32 v24, v24, v25
	v_cvt_pk_bf16_f32 v25, v16, v17
	global_store_dwordx2 v[18:19], v[24:25], off offset:512
	v_mul_f32_e32 v16, v30, v74
	v_mul_f32_e32 v17, v31, v74
	v_mul_f32_e32 v24, v28, v74
	v_mul_f32_e32 v25, v29, v74
	v_mul_f32_e32 v16, v10, v16
	v_mul_f32_e32 v17, v11, v17
	v_mul_f32_e32 v24, v8, v24
	v_mul_f32_e32 v25, v9, v25
	v_add_f32_e32 v28, 1.0, v44
	v_add_f32_e32 v29, 1.0, v45
	v_fma_f32 v16, v26, v16, v42
	v_fma_f32 v17, v27, v17, v43
	v_fma_f32 v24, v28, v24, v40
	v_fma_f32 v25, v29, v25, v41
	v_mul_f32_e32 v20, v20, v74
	v_mul_f32_e32 v21, v21, v74
	v_cvt_pk_bf16_f32 v24, v24, v25
	v_cvt_pk_bf16_f32 v25, v16, v17
	v_mul_f32_e32 v16, v22, v74
	v_mul_f32_e32 v17, v23, v74
	global_store_dwordx2 v[18:19], v[24:25], off offset:1024
	v_mul_f32_e32 v20, v12, v20
	v_mul_f32_e32 v21, v13, v21
	v_mul_f32_e32 v16, v14, v16
	v_mul_f32_e32 v17, v15, v17
	s_waitcnt vmcnt(3)
	v_add_f32_e32 v22, 1.0, v38
	v_add_f32_e32 v23, 1.0, v39
	v_add_f32_e32 v24, 1.0, v36
	v_add_f32_e32 v25, 1.0, v37
	v_fma_f32 v16, v22, v16, v34
	v_fma_f32 v17, v23, v17, v35
	v_fma_f32 v20, v24, v20, v32
	v_fma_f32 v21, v25, v21, v33
	s_nop 0
	v_cvt_pk_bf16_f32 v20, v20, v21
	v_cvt_pk_bf16_f32 v21, v16, v17
	global_store_dwordx2 v[18:19], v[20:21], off offset:1536
	s_cbranch_scc1 .LBB0_1004

; __device__ __forceinline__ unsigned cvt_pk_bf16(float lo, float hi) { const f32x2 v = {lo, hi}; const bf16x2_t b = __builtin_convertvector(v, bf16x2_t); return __builtin_bit_cast(unsigned, b); }
; __device__ __forceinline__ float fast_exp2(float x) { return __builtin_amdgcn_exp2f(x); }
; __device__ __forceinline__ float fast_rcp(float x) { return __builtin_amdgcn_rcpf(x); }
; __device__ __forceinline__ float silu_f(float x) { return x * fast_rcp(1.0f + fast_exp2(-x * LOG2E)); }
;     __device__ __forceinline__ void operator()(const f32x4 (&acc)[2][2][4][2], const Unit& u, int wr, int wc, int fr, int fq) const {
;         asm volatile("" : "+v"(fr), "+v"(fq));
;         const int row0 = u.pm * BM + wr * 64 + fr; const int col0 = u.pn * 128 + wc * 32 + 8 * fq;
; #pragma unroll
;         for (int ai = 0; ai < 2; ++ai)
; #pragma unroll
;             for (int m = 0; m < 4; ++m) {
;                 bf16_t* rowp = act + (size_t)(row0 + ai * HALF + m * 16) * FF + col0;
;                 const f32x4 g0 = acc[ai][0][m][0], g1 = acc[ai][0][m][1], u0 = acc[ai][1][m][0], u1 = acc[ai][1][m][1];
;                 u32x4 w;
;                 w.x = cvt_pk_bf16(silu_f(g0[0]) * u0[0], silu_f(g0[1]) * u0[1]); w.y = cvt_pk_bf16(silu_f(g0[2]) * u0[2], silu_f(g0[3]) * u0[3]);
;                 w.z = cvt_pk_bf16(silu_f(g1[0]) * u1[0], silu_f(g1[1]) * u1[1]); w.w = cvt_pk_bf16(silu_f(g1[2]) * u1[2], silu_f(g1[3]) * u1[3]);
;                 *(u32x4*)rowp = w;
;             }
.LBB0_1069:
	v_mul_f32_e32 v147, 0xbfb8aa3b, v124
	v_exp_f32_e32 v147, v147
	s_lshl_b32 s9, s18, 8
	v_mov_b32_e32 v138, v142
	v_mov_b32_e32 v139, v143
	v_add_f32_e32 v147, 1.0, v147
	v_rcp_f32_e32 v150, v147
	v_mul_f32_e32 v147, 0xbfb8aa3b, v125
	v_exp_f32_e32 v147, v147
	s_add_i32 s9, s9, s67
	s_andn2_b64 vcc, exec, s[34:35]
	v_add_f32_e32 v147, 1.0, v147
	v_rcp_f32_e32 v151, v147
	v_add_u32_e32 v146, s9, v138
	s_lshl_b32 s9, s16, 7
	s_or_b32 s9, s9, s68
	v_mul_f32_e32 v124, v124, v150
	v_mul_f32_e32 v125, v125, v151
	v_lshl_add_u32 v140, v139, 3, s9
	v_mul_f32_e32 v120, v120, v124
	v_mul_f32_e32 v121, v121, v125
	v_ashrrev_i32_e32 v141, 31, v140
	v_cvt_pk_bf16_f32 v120, v120, v121
	v_mul_f32_e32 v121, 0xbfb8aa3b, v126
	v_exp_f32_e32 v121, v121
	v_mov_b64_e32 v[138:139], s[90:91]
	v_mad_i64_i32 v[148:149], s[16:17], v146, s44, v[138:139]
	v_add_f32_e32 v121, 1.0, v121
	v_rcp_f32_e32 v124, v121
	v_mul_f32_e32 v121, 0xbfb8aa3b, v127
	v_exp_f32_e32 v121, v121
	v_lshlrev_b64 v[140:141], 1, v[140:141]
	v_lshl_add_u64 v[148:149], v[148:149], 0, v[140:141]
	v_add_f32_e32 v121, 1.0, v121
	v_rcp_f32_e32 v125, v121
	s_nop 0
	v_mul_f32_e32 v124, v126, v124
	v_mul_f32_e32 v125, v127, v125
	s_nop 0
	v_mul_f32_e32 v122, v122, v124
	v_mul_f32_e32 v123, v123, v125
	s_nop 0
	v_cvt_pk_bf16_f32 v121, v122, v123
	v_mul_f32_e32 v122, 0xbfb8aa3b, v116
	v_mul_f32_e32 v123, 0xbfb8aa3b, v117
	v_exp_f32_e32 v122, v122
	v_exp_f32_e32 v123, v123
	v_add_f32_e32 v122, 1.0, v122
	v_add_f32_e32 v123, 1.0, v123
	v_rcp_f32_e32 v122, v122
	v_rcp_f32_e32 v123, v123
	s_nop 0
	v_mul_f32_e32 v116, v116, v122
	v_mul_f32_e32 v117, v117, v123
	s_nop 0
	v_mul_f32_e32 v112, v112, v116
	v_mul_f32_e32 v113, v113, v117
	s_nop 0
	v_cvt_pk_bf16_f32 v122, v112, v113
	v_mul_f32_e32 v112, 0xbfb8aa3b, v118
	v_mul_f32_e32 v113, 0xbfb8aa3b, v119
	v_exp_f32_e32 v112, v112
	v_exp_f32_e32 v113, v113
	v_add_f32_e32 v112, 1.0, v112
	v_add_f32_e32 v113, 1.0, v113
	v_rcp_f32_e32 v112, v112
	v_rcp_f32_e32 v113, v113
	s_nop 0
	v_mul_f32_e32 v112, v118, v112
	v_mul_f32_e32 v113, v119, v113
	s_nop 0
	v_mul_f32_e32 v112, v114, v112
	v_mul_f32_e32 v113, v115, v113
	v_mul_f32_e32 v114, 0xbfb8aa3b, v108
	v_mul_f32_e32 v115, 0xbfb8aa3b, v109
	v_exp_f32_e32 v114, v114
	v_exp_f32_e32 v115, v115
	v_cvt_pk_bf16_f32 v123, v112, v113
	v_add_u32_e32 v112, 16, v146
	v_add_f32_e32 v114, 1.0, v114
	v_add_f32_e32 v115, 1.0, v115
	v_rcp_f32_e32 v114, v114
	v_rcp_f32_e32 v115, v115
	v_mad_i64_i32 v[112:113], s[16:17], v112, s44, v[138:139]
	v_lshl_add_u64 v[112:113], v[112:113], 0, v[140:141]
	v_mul_f32_e32 v108, v108, v114
	v_mul_f32_e32 v109, v109, v115
	global_store_dwordx4 v[148:149], v[120:123], off
	v_mul_f32_e32 v104, v104, v108
	v_mul_f32_e32 v105, v105, v109
	s_nop 0
	v_cvt_pk_bf16_f32 v104, v104, v105
	v_mul_f32_e32 v105, 0xbfb8aa3b, v110
	v_exp_f32_e32 v105, v105
	s_nop 0
	v_add_f32_e32 v105, 1.0, v105
	v_rcp_f32_e32 v108, v105
	v_mul_f32_e32 v105, 0xbfb8aa3b, v111
	v_exp_f32_e32 v105, v105
	s_nop 0
	v_add_f32_e32 v105, 1.0, v105
	v_rcp_f32_e32 v109, v105
	s_nop 0
	v_mul_f32_e32 v108, v110, v108
	v_mul_f32_e32 v109, v111, v109
	s_nop 0
	v_mul_f32_e32 v106, v106, v108
	v_mul_f32_e32 v107, v107, v109
	s_nop 0
	v_cvt_pk_bf16_f32 v105, v106, v107
	v_mul_f32_e32 v106, 0xbfb8aa3b, v100
	v_mul_f32_e32 v107, 0xbfb8aa3b, v101
	v_exp_f32_e32 v106, v106
	v_exp_f32_e32 v107, v107
	v_add_f32_e32 v106, 1.0, v106
	v_add_f32_e32 v107, 1.0, v107
	v_rcp_f32_e32 v106, v106
	v_rcp_f32_e32 v107, v107
	s_nop 0
	v_mul_f32_e32 v100, v100, v106
	v_mul_f32_e32 v101, v101, v107
	s_nop 0
	v_mul_f32_e32 v96, v96, v100
	v_mul_f32_e32 v97, v97, v101
	s_nop 0
	v_cvt_pk_bf16_f32 v106, v96, v97
	v_mul_f32_e32 v96, 0xbfb8aa3b, v102
	v_mul_f32_e32 v97, 0xbfb8aa3b, v103
	v_exp_f32_e32 v96, v96
	v_exp_f32_e32 v97, v97
	v_add_f32_e32 v96, 1.0, v96
	v_add_f32_e32 v97, 1.0, v97
	v_rcp_f32_e32 v96, v96
	v_rcp_f32_e32 v97, v97
	s_nop 0
	v_mul_f32_e32 v96, v102, v96
	v_mul_f32_e32 v97, v103, v97
	s_nop 0
	v_mul_f32_e32 v96, v98, v96
	v_mul_f32_e32 v97, v99, v97
	v_mul_f32_e32 v98, 0xbfb8aa3b, v92
	v_mul_f32_e32 v99, 0xbfb8aa3b, v93
	v_exp_f32_e32 v98, v98
	v_exp_f32_e32 v99, v99
	v_cvt_pk_bf16_f32 v107, v96, v97
	v_add_u32_e32 v96, 32, v146
	v_add_f32_e32 v98, 1.0, v98
	v_add_f32_e32 v99, 1.0, v99
	v_rcp_f32_e32 v98, v98
	v_rcp_f32_e32 v99, v99
	v_mad_i64_i32 v[96:97], s[16:17], v96, s44, v[138:139]
	v_lshl_add_u64 v[96:97], v[96:97], 0, v[140:141]
	v_mul_f32_e32 v92, v92, v98
	v_mul_f32_e32 v93, v93, v99
	global_store_dwordx4 v[112:113], v[104:107], off
	v_mul_f32_e32 v88, v88, v92
	v_mul_f32_e32 v89, v89, v93
	s_nop 0
	v_cvt_pk_bf16_f32 v88, v88, v89
	v_mul_f32_e32 v89, 0xbfb8aa3b, v94
	v_exp_f32_e32 v89, v89
	s_nop 0
	v_add_f32_e32 v89, 1.0, v89
	v_rcp_f32_e32 v92, v89
	v_mul_f32_e32 v89, 0xbfb8aa3b, v95
	v_exp_f32_e32 v89, v89
	s_nop 0
	v_add_f32_e32 v89, 1.0, v89
	v_rcp_f32_e32 v93, v89
	s_nop 0
	v_mul_f32_e32 v92, v94, v92
	v_mul_f32_e32 v93, v95, v93
	s_nop 0
	v_mul_f32_e32 v90, v90, v92
	v_mul_f32_e32 v91, v91, v93
	s_nop 0
	v_cvt_pk_bf16_f32 v89, v90, v91
	v_mul_f32_e32 v90, 0xbfb8aa3b, v84
	v_mul_f32_e32 v91, 0xbfb8aa3b, v85
	v_exp_f32_e32 v90, v90
	v_exp_f32_e32 v91, v91
	v_add_f32_e32 v90, 1.0, v90
	v_add_f32_e32 v91, 1.0, v91
	v_rcp_f32_e32 v90, v90
	v_rcp_f32_e32 v91, v91
	s_nop 0
	v_mul_f32_e32 v84, v84, v90
	v_mul_f32_e32 v85, v85, v91
	s_nop 0
	v_mul_f32_e32 v80, v80, v84
	v_mul_f32_e32 v81, v81, v85
	s_nop 0
	v_cvt_pk_bf16_f32 v90, v80, v81
	v_mul_f32_e32 v80, 0xbfb8aa3b, v86
	v_mul_f32_e32 v81, 0xbfb8aa3b, v87
	v_exp_f32_e32 v80, v80
	v_exp_f32_e32 v81, v81
	v_add_f32_e32 v80, 1.0, v80
	v_add_f32_e32 v81, 1.0, v81
	v_rcp_f32_e32 v80, v80
; __device__ __forceinline__ unsigned cvt_pk_bf16(float lo, float hi) { const f32x2 v = {lo, hi}; const bf16x2_t b = __builtin_convertvector(v, bf16x2_t); return __builtin_bit_cast(unsigned, b); }
; __device__ __forceinline__ float silu_f(float x) { return x * fast_rcp(1.0f + fast_exp2(-x * LOG2E)); }
;     __device__ __forceinline__ void operator()(const f32x4 (&acc)[2][2][4][2], const Unit& u, int wr, int wc, int fr, int fq) const {
;         asm volatile("" : "+v"(fr), "+v"(fq));
;         const int row0 = u.pm * BM + wr * 64 + fr; const int col0 = u.pn * 128 + wc * 32 + 8 * fq;
; #pragma unroll
;         for (int ai = 0; ai < 2; ++ai)
; #pragma unroll
;             for (int m = 0; m < 4; ++m) {
;                 bf16_t* rowp = act + (size_t)(row0 + ai * HALF + m * 16) * FF + col0;
;                 const f32x4 g0 = acc[ai][0][m][0], g1 = acc[ai][0][m][1], u0 = acc[ai][1][m][0], u1 = acc[ai][1][m][1];
;                 u32x4 w;
;                 w.x = cvt_pk_bf16(silu_f(g0[0]) * u0[0], silu_f(g0[1]) * u0[1]); w.y = cvt_pk_bf16(silu_f(g0[2]) * u0[2], silu_f(g0[3]) * u0[3]);
;                 w.z = cvt_pk_bf16(silu_f(g1[0]) * u1[0], silu_f(g1[1]) * u1[1]); w.w = cvt_pk_bf16(silu_f(g1[2]) * u1[2], silu_f(g1[3]) * u1[3]);
;                 *(u32x4*)rowp = w;
;             }
	v_rcp_f32_e32 v81, v81
	s_nop 0
	v_mul_f32_e32 v80, v86, v80
	v_mul_f32_e32 v81, v87, v81
	s_nop 0
	v_mul_f32_e32 v80, v82, v80
	v_mul_f32_e32 v81, v83, v81
	v_mul_f32_e32 v82, 0xbfb8aa3b, v76
	v_mul_f32_e32 v83, 0xbfb8aa3b, v77
	v_exp_f32_e32 v82, v82
	v_exp_f32_e32 v83, v83
	v_cvt_pk_bf16_f32 v91, v80, v81
	v_add_u32_e32 v80, 48, v146
	v_add_f32_e32 v82, 1.0, v82
	v_add_f32_e32 v83, 1.0, v83
	v_rcp_f32_e32 v82, v82
	v_rcp_f32_e32 v83, v83
	v_mad_i64_i32 v[80:81], s[16:17], v80, s44, v[138:139]
	v_lshl_add_u64 v[80:81], v[80:81], 0, v[140:141]
	v_mul_f32_e32 v76, v76, v82
	v_mul_f32_e32 v77, v77, v83
	global_store_dwordx4 v[96:97], v[88:91], off
	v_mul_f32_e32 v72, v72, v76
	v_mul_f32_e32 v73, v73, v77
	s_nop 0
	v_cvt_pk_bf16_f32 v72, v72, v73
	v_mul_f32_e32 v73, 0xbfb8aa3b, v78
	v_exp_f32_e32 v73, v73
	s_nop 0
	v_add_f32_e32 v73, 1.0, v73
	v_rcp_f32_e32 v76, v73
	v_mul_f32_e32 v73, 0xbfb8aa3b, v79
	v_exp_f32_e32 v73, v73
	s_nop 0
	v_add_f32_e32 v73, 1.0, v73
	v_rcp_f32_e32 v77, v73
	s_nop 0
	v_mul_f32_e32 v76, v78, v76
	v_mul_f32_e32 v77, v79, v77
	s_nop 0
	v_mul_f32_e32 v74, v74, v76
	v_mul_f32_e32 v75, v75, v77
	s_nop 0
	v_cvt_pk_bf16_f32 v73, v74, v75
	v_mul_f32_e32 v74, 0xbfb8aa3b, v68
	v_mul_f32_e32 v75, 0xbfb8aa3b, v69
	v_exp_f32_e32 v74, v74
	v_exp_f32_e32 v75, v75
	v_add_f32_e32 v74, 1.0, v74
	v_add_f32_e32 v75, 1.0, v75
	v_rcp_f32_e32 v74, v74
	v_rcp_f32_e32 v75, v75
	s_nop 0
	v_mul_f32_e32 v68, v68, v74
	v_mul_f32_e32 v69, v69, v75
	s_nop 0
	v_mul_f32_e32 v64, v64, v68
	v_mul_f32_e32 v65, v65, v69
	s_nop 0
	v_cvt_pk_bf16_f32 v74, v64, v65
	v_mul_f32_e32 v64, 0xbfb8aa3b, v70
	v_mul_f32_e32 v65, 0xbfb8aa3b, v71
	v_exp_f32_e32 v64, v64
	v_exp_f32_e32 v65, v65
	v_add_f32_e32 v64, 1.0, v64
	v_add_f32_e32 v65, 1.0, v65
	v_rcp_f32_e32 v64, v64
	v_rcp_f32_e32 v65, v65
	s_nop 0
	v_mul_f32_e32 v64, v70, v64
	v_mul_f32_e32 v65, v71, v65
	s_nop 0
	v_mul_f32_e32 v64, v66, v64
	v_mul_f32_e32 v65, v67, v65
	v_mul_f32_e32 v66, 0xbfb8aa3b, v60
	v_mul_f32_e32 v67, 0xbfb8aa3b, v61
	v_exp_f32_e32 v66, v66
	v_exp_f32_e32 v67, v67
	v_cvt_pk_bf16_f32 v75, v64, v65
	v_add_u32_e32 v64, 0x80, v146
	v_add_f32_e32 v66, 1.0, v66
	v_add_f32_e32 v67, 1.0, v67
	v_rcp_f32_e32 v66, v66
	v_rcp_f32_e32 v67, v67
	v_mad_i64_i32 v[64:65], s[16:17], v64, s44, v[138:139]
	v_lshl_add_u64 v[64:65], v[64:65], 0, v[140:141]
	v_mul_f32_e32 v60, v60, v66
	v_mul_f32_e32 v61, v61, v67
	global_store_dwordx4 v[80:81], v[72:75], off
	v_mul_f32_e32 v56, v56, v60
	v_mul_f32_e32 v57, v57, v61
	s_nop 0
	v_cvt_pk_bf16_f32 v56, v56, v57
	v_mul_f32_e32 v57, 0xbfb8aa3b, v62
	v_exp_f32_e32 v57, v57
	s_nop 0
	v_add_f32_e32 v57, 1.0, v57
	v_rcp_f32_e32 v60, v57
	v_mul_f32_e32 v57, 0xbfb8aa3b, v63
	v_exp_f32_e32 v57, v57
	s_nop 0
	v_add_f32_e32 v57, 1.0, v57
	v_rcp_f32_e32 v61, v57
	s_nop 0
	v_mul_f32_e32 v60, v62, v60
	v_mul_f32_e32 v61, v63, v61
	s_nop 0
	v_mul_f32_e32 v58, v58, v60
	v_mul_f32_e32 v59, v59, v61
	s_nop 0
	v_cvt_pk_bf16_f32 v57, v58, v59
	v_mul_f32_e32 v58, 0xbfb8aa3b, v52
	v_mul_f32_e32 v59, 0xbfb8aa3b, v53
	v_exp_f32_e32 v58, v58
	v_exp_f32_e32 v59, v59
	v_add_f32_e32 v58, 1.0, v58
	v_add_f32_e32 v59, 1.0, v59
	v_rcp_f32_e32 v58, v58
	v_rcp_f32_e32 v59, v59
	s_nop 0
	v_mul_f32_e32 v52, v52, v58
	v_mul_f32_e32 v53, v53, v59
	s_nop 0
	v_mul_f32_e32 v48, v48, v52
	v_mul_f32_e32 v49, v49, v53
	s_nop 0
	v_cvt_pk_bf16_f32 v58, v48, v49
	v_mul_f32_e32 v48, 0xbfb8aa3b, v54
	v_mul_f32_e32 v49, 0xbfb8aa3b, v55
	v_exp_f32_e32 v48, v48
	v_exp_f32_e32 v49, v49
	v_add_f32_e32 v48, 1.0, v48
	v_add_f32_e32 v49, 1.0, v49
	v_rcp_f32_e32 v48, v48
	v_rcp_f32_e32 v49, v49
	s_nop 0
	v_mul_f32_e32 v48, v54, v48
	v_mul_f32_e32 v49, v55, v49
	s_nop 0
	v_mul_f32_e32 v48, v50, v48
	v_mul_f32_e32 v49, v51, v49
	v_mul_f32_e32 v50, 0xbfb8aa3b, v44
	v_mul_f32_e32 v51, 0xbfb8aa3b, v45
	v_exp_f32_e32 v50, v50
	v_exp_f32_e32 v51, v51
	v_cvt_pk_bf16_f32 v59, v48, v49
	v_add_u32_e32 v48, 0x90, v146
	v_add_f32_e32 v50, 1.0, v50
	v_add_f32_e32 v51, 1.0, v51
	v_rcp_f32_e32 v50, v50
	v_rcp_f32_e32 v51, v51
	v_mad_i64_i32 v[48:49], s[16:17], v48, s44, v[138:139]
	v_lshl_add_u64 v[48:49], v[48:49], 0, v[140:141]
	v_mul_f32_e32 v44, v44, v50
	v_mul_f32_e32 v45, v45, v51
	global_store_dwordx4 v[64:65], v[56:59], off
	v_mul_f32_e32 v40, v40, v44
	v_mul_f32_e32 v41, v41, v45
	s_nop 0
	v_cvt_pk_bf16_f32 v40, v40, v41
	v_mul_f32_e32 v41, 0xbfb8aa3b, v46
	v_exp_f32_e32 v41, v41
	s_nop 0
	v_add_f32_e32 v41, 1.0, v41
	v_rcp_f32_e32 v44, v41
	v_mul_f32_e32 v41, 0xbfb8aa3b, v47
	v_exp_f32_e32 v41, v41
	s_nop 0
	v_add_f32_e32 v41, 1.0, v41
	v_rcp_f32_e32 v45, v41
	s_nop 0
	v_mul_f32_e32 v44, v46, v44
; __device__ __forceinline__ unsigned cvt_pk_bf16(float lo, float hi) { const f32x2 v = {lo, hi}; const bf16x2_t b = __builtin_convertvector(v, bf16x2_t); return __builtin_bit_cast(unsigned, b); }
; __device__ __forceinline__ float silu_f(float x) { return x * fast_rcp(1.0f + fast_exp2(-x * LOG2E)); }
;     __device__ __forceinline__ void operator()(const f32x4 (&acc)[2][2][4][2], const Unit& u, int wr, int wc, int fr, int fq) const {
;         asm volatile("" : "+v"(fr), "+v"(fq));
;         const int row0 = u.pm * BM + wr * 64 + fr; const int col0 = u.pn * 128 + wc * 32 + 8 * fq;
; #pragma unroll
;         for (int ai = 0; ai < 2; ++ai)
; #pragma unroll
;             for (int m = 0; m < 4; ++m) {
;                 bf16_t* rowp = act + (size_t)(row0 + ai * HALF + m * 16) * FF + col0;
;                 const f32x4 g0 = acc[ai][0][m][0], g1 = acc[ai][0][m][1], u0 = acc[ai][1][m][0], u1 = acc[ai][1][m][1];
;                 u32x4 w;
;                 w.x = cvt_pk_bf16(silu_f(g0[0]) * u0[0], silu_f(g0[1]) * u0[1]); w.y = cvt_pk_bf16(silu_f(g0[2]) * u0[2], silu_f(g0[3]) * u0[3]);
;                 w.z = cvt_pk_bf16(silu_f(g1[0]) * u1[0], silu_f(g1[1]) * u1[1]); w.w = cvt_pk_bf16(silu_f(g1[2]) * u1[2], silu_f(g1[3]) * u1[3]);
;                 *(u32x4*)rowp = w;
;             }
	v_mul_f32_e32 v45, v47, v45
	s_nop 0
	v_mul_f32_e32 v42, v42, v44
	v_mul_f32_e32 v43, v43, v45
	s_nop 0
	v_cvt_pk_bf16_f32 v41, v42, v43
	v_mul_f32_e32 v42, 0xbfb8aa3b, v36
	v_mul_f32_e32 v43, 0xbfb8aa3b, v37
	v_exp_f32_e32 v42, v42
	v_exp_f32_e32 v43, v43
	v_add_f32_e32 v42, 1.0, v42
	v_add_f32_e32 v43, 1.0, v43
	v_rcp_f32_e32 v42, v42
	v_rcp_f32_e32 v43, v43
	s_nop 0
	v_mul_f32_e32 v36, v36, v42
	v_mul_f32_e32 v37, v37, v43
	s_nop 0
	v_mul_f32_e32 v32, v32, v36
	v_mul_f32_e32 v33, v33, v37
	s_nop 0
	v_cvt_pk_bf16_f32 v42, v32, v33
	v_mul_f32_e32 v32, 0xbfb8aa3b, v38
	v_mul_f32_e32 v33, 0xbfb8aa3b, v39
	v_exp_f32_e32 v32, v32
	v_exp_f32_e32 v33, v33
	v_add_f32_e32 v32, 1.0, v32
	v_add_f32_e32 v33, 1.0, v33
	v_rcp_f32_e32 v32, v32
	v_rcp_f32_e32 v33, v33
	s_nop 0
	v_mul_f32_e32 v32, v38, v32
	v_mul_f32_e32 v33, v39, v33
	s_nop 0
	v_mul_f32_e32 v32, v34, v32
	v_mul_f32_e32 v33, v35, v33
	v_mul_f32_e32 v34, 0xbfb8aa3b, v28
	v_mul_f32_e32 v35, 0xbfb8aa3b, v29
	v_exp_f32_e32 v34, v34
	v_exp_f32_e32 v35, v35
	v_cvt_pk_bf16_f32 v43, v32, v33
	v_add_u32_e32 v32, 0xa0, v146
	v_add_f32_e32 v34, 1.0, v34
	v_add_f32_e32 v35, 1.0, v35
	v_rcp_f32_e32 v34, v34
	v_rcp_f32_e32 v35, v35
	v_mad_i64_i32 v[32:33], s[16:17], v32, s44, v[138:139]
	v_lshl_add_u64 v[32:33], v[32:33], 0, v[140:141]
	v_mul_f32_e32 v28, v28, v34
	v_mul_f32_e32 v29, v29, v35
	global_store_dwordx4 v[48:49], v[40:43], off
	v_mul_f32_e32 v24, v24, v28
	v_mul_f32_e32 v25, v25, v29
	s_nop 0
	v_cvt_pk_bf16_f32 v24, v24, v25
	v_mul_f32_e32 v25, 0xbfb8aa3b, v30
	v_exp_f32_e32 v25, v25
	s_nop 0
	v_add_f32_e32 v25, 1.0, v25
	v_rcp_f32_e32 v28, v25
	v_mul_f32_e32 v25, 0xbfb8aa3b, v31
	v_exp_f32_e32 v25, v25
	s_nop 0
	v_add_f32_e32 v25, 1.0, v25
	v_rcp_f32_e32 v29, v25
	s_nop 0
	v_mul_f32_e32 v28, v30, v28
	v_mul_f32_e32 v29, v31, v29
	s_nop 0
	v_mul_f32_e32 v26, v26, v28
	v_mul_f32_e32 v27, v27, v29
	s_nop 0
	v_cvt_pk_bf16_f32 v25, v26, v27
	v_mul_f32_e32 v26, 0xbfb8aa3b, v20
	v_mul_f32_e32 v27, 0xbfb8aa3b, v21
	v_exp_f32_e32 v26, v26
	v_exp_f32_e32 v27, v27
	v_add_f32_e32 v26, 1.0, v26
	v_add_f32_e32 v27, 1.0, v27
	v_rcp_f32_e32 v26, v26
	v_rcp_f32_e32 v27, v27
	s_nop 0
	v_mul_f32_e32 v20, v20, v26
	v_mul_f32_e32 v21, v21, v27
	s_nop 0
	v_mul_f32_e32 v16, v16, v20
	v_mul_f32_e32 v17, v17, v21
	s_nop 0
	v_cvt_pk_bf16_f32 v26, v16, v17
	v_mul_f32_e32 v16, 0xbfb8aa3b, v22
	v_mul_f32_e32 v17, 0xbfb8aa3b, v23
	v_exp_f32_e32 v16, v16
	v_exp_f32_e32 v17, v17
	v_add_f32_e32 v16, 1.0, v16
	v_add_f32_e32 v17, 1.0, v17
	v_rcp_f32_e32 v16, v16
	v_rcp_f32_e32 v17, v17
	s_nop 0
	v_mul_f32_e32 v16, v22, v16
	v_mul_f32_e32 v17, v23, v17
	s_nop 0
	v_mul_f32_e32 v16, v18, v16
	v_mul_f32_e32 v17, v19, v17
	v_mul_f32_e32 v18, 0xbfb8aa3b, v12
	v_mul_f32_e32 v19, 0xbfb8aa3b, v13
	v_exp_f32_e32 v18, v18
	v_exp_f32_e32 v19, v19
	v_cvt_pk_bf16_f32 v27, v16, v17
	v_add_u32_e32 v16, 0xb0, v146
	v_add_f32_e32 v18, 1.0, v18
	v_add_f32_e32 v19, 1.0, v19
	v_rcp_f32_e32 v18, v18
	v_rcp_f32_e32 v19, v19
	v_mad_i64_i32 v[16:17], s[16:17], v16, s44, v[138:139]
	v_lshl_add_u64 v[16:17], v[16:17], 0, v[140:141]
	v_mul_f32_e32 v12, v12, v18
	v_mul_f32_e32 v13, v13, v19
	s_mov_b64 s[16:17], -1
	v_mul_f32_e32 v8, v8, v12
	v_mul_f32_e32 v9, v9, v13
	global_store_dwordx4 v[32:33], v[24:27], off
	v_cvt_pk_bf16_f32 v8, v8, v9
	v_mul_f32_e32 v9, 0xbfb8aa3b, v14
	v_exp_f32_e32 v9, v9
	s_nop 0
	v_add_f32_e32 v9, 1.0, v9
	v_rcp_f32_e32 v12, v9
	v_mul_f32_e32 v9, 0xbfb8aa3b, v15
	v_exp_f32_e32 v9, v9
	s_nop 0
	v_add_f32_e32 v9, 1.0, v9
	v_rcp_f32_e32 v13, v9
	s_nop 0
	v_mul_f32_e32 v12, v14, v12
	v_mul_f32_e32 v13, v15, v13
	s_nop 0
	v_mul_f32_e32 v10, v10, v12
	v_mul_f32_e32 v11, v11, v13
	s_nop 0
	v_cvt_pk_bf16_f32 v9, v10, v11
	v_mul_f32_e32 v10, 0xbfb8aa3b, v4
	v_mul_f32_e32 v11, 0xbfb8aa3b, v5
	v_exp_f32_e32 v10, v10
	v_exp_f32_e32 v11, v11
	v_add_f32_e32 v10, 1.0, v10
	v_add_f32_e32 v11, 1.0, v11
	v_rcp_f32_e32 v10, v10
	v_rcp_f32_e32 v11, v11
	s_nop 0
	v_mul_f32_e32 v4, v4, v10
	v_mul_f32_e32 v5, v5, v11
	s_nop 0
	v_mul_f32_e32 v0, v0, v4
	v_mul_f32_e32 v1, v1, v5
	s_nop 0
	v_cvt_pk_bf16_f32 v10, v0, v1
	v_mul_f32_e32 v0, 0xbfb8aa3b, v6
	v_mul_f32_e32 v1, 0xbfb8aa3b, v7
	v_exp_f32_e32 v0, v0
	v_exp_f32_e32 v1, v1
	v_add_f32_e32 v0, 1.0, v0
	v_add_f32_e32 v1, 1.0, v1
	v_rcp_f32_e32 v0, v0
	v_rcp_f32_e32 v1, v1
	s_nop 0
	v_mul_f32_e32 v0, v6, v0
	v_mul_f32_e32 v1, v7, v1
	s_nop 0
	v_mul_f32_e32 v0, v2, v0
	v_mul_f32_e32 v1, v3, v1
	s_nop 0
	v_cvt_pk_bf16_f32 v11, v0, v1
	global_store_dwordx4 v[16:17], v[8:11], off
	s_cbranch_vccnz .LBB0_1062
	s_andn2_b64 vcc, exec, s[0:1]
	s_cbranch_vccnz .LBB0_1061
	s_barrier
	s_branch .LBB0_1061

;     __device__ __forceinline__ void operator()(const f32x4 (&acc)[2][2][4][2], const Unit& u, int wr, int wc, int fr, int fq) const {
;     ...
;         f32x4 gv[2][2];
; #pragma unroll
;         for (int bj = 0; bj < 2; ++bj)
; #pragma unroll
;             for (int n = 0; n < 2; ++n) gv[bj][n] = *(const f32x4*)(gate + (size_t)s * 9216 + col0 + bj * HALF + 4 * n) * gscale;
;         if (partial) {
; #pragma unroll
;             for (int ai = 0; ai < 2; ++ai)
; #pragma unroll
;                 for (int m = 0; m < 4; ++m) {
;                     const size_t ro = (size_t)(ai * HALF + m * 16) * DM + col0;
; #pragma unroll
;                     for (int bj = 0; bj < 2; ++bj)
; #pragma unroll
;                         for (int n = 0; n < 2; ++n) *(f32x4*)(pp + ro + bj * HALF + 4 * n) = acc[ai][bj][m][n];
;                 }
;         } else {
; #pragma unroll
;             for (int ai = 0; ai < 2; ++ai) {
;                 f32x4 xv[4][2][2];
; #pragma unroll
;                 for (int m = 0; m < 4; ++m)
; #pragma unroll
;                     for (int bj = 0; bj < 2; ++bj)
; #pragma unroll
;                         for (int n = 0; n < 2; ++n) xv[m][bj][n] = *(const f32x4*)(xo + (size_t)(ai * HALF + m * 16) * DM + col0 + bj * HALF + 4 * n);
;                 __builtin_amdgcn_sched_barrier(0);
; #pragma unroll
;                 for (int m = 0; m < 4; ++m)
; #pragma unroll
;                     for (int bj = 0; bj < 2; ++bj)
; #pragma unroll
;                         for (int n = 0; n < 2; ++n) *(f32x4*)(xn + (size_t)(ai * HALF + m * 16) * DM + col0 + bj * HALF + 4 * n) = xv[m][bj][n] + gv[bj][n] * acc[ai][bj][m][n];
;                 __builtin_amdgcn_sched_barrier(0);
;             }
.LBB0_1159:
	s_lshl_b64 s[16:17], s[16:17], 2
	s_add_u32 s16, s58, s16
	s_addc_u32 s17, s59, s17
	v_lshlrev_b64 v[172:173], 2, v[140:141]
	v_lshl_add_u64 v[152:153], s[16:17], 0, v[172:173]
	global_load_dwordx4 v[148:151], v[152:153], off offset:512
	global_load_dwordx4 v[144:147], v[152:153], off offset:528
	global_load_dwordx4 v[166:169], v[152:153], off
	s_nop 0
	global_load_dwordx4 v[152:155], v[152:153], off offset:16
	v_lshl_add_u64 v[160:161], v[158:159], 0, v[172:173]
	v_add_co_u32_e32 v190, vcc, s24, v160
	s_mov_b64 s[16:17], 0x10200
	s_nop 0
	v_addc_co_u32_e32 v191, vcc, 0, v161, vcc
	v_lshl_add_u64 v[170:171], s[82:83], 0, v[142:143]
	v_lshl_add_u64 v[186:187], v[160:161], 0, s[54:55]
	v_lshl_add_u64 v[212:213], v[160:161], 0, s[16:17]
	s_mov_b64 s[16:17], 0x20000
	v_add_co_u32_e32 v226, vcc, s48, v160
	v_lshl_add_u64 v[158:159], v[170:171], 0, v[172:173]
	s_nop 0
	v_addc_co_u32_e32 v227, vcc, 0, v161, vcc
	v_add_co_u32_e32 v242, vcc, s49, v160
	s_waitcnt vmcnt(0)
	v_mul_f32_e32 v148, 0.5, v148
	v_mul_f32_e32 v149, 0.5, v149
	v_mul_f32_e32 v142, 0.5, v146
	v_mul_f32_e32 v143, 0.5, v147
	v_mul_f32_e32 v146, 0.5, v150
	v_mul_f32_e32 v147, 0.5, v151
	v_mul_f32_e32 v150, 0.5, v154
	v_mul_f32_e32 v151, 0.5, v155
	v_mul_f32_e32 v154, 0.5, v168
	v_mul_f32_e32 v155, 0.5, v169
	v_mul_f32_e32 v156, 0.5, v166
	v_mul_f32_e32 v157, 0.5, v167
	global_load_dwordx4 v[166:169], v[160:161], off offset:16
	global_load_dwordx4 v[170:173], v[160:161], off
	global_load_dwordx4 v[174:177], v[160:161], off offset:528
	global_load_dwordx4 v[178:181], v[160:161], off offset:512
	global_load_dwordx4 v[182:185], v[190:191], off
	s_nop 0
	global_load_dwordx4 v[186:189], v[186:187], off offset:16
	s_nop 0
	global_load_dwordx4 v[208:211], v[190:191], off offset:512
	s_nop 0
	global_load_dwordx4 v[212:215], v[212:213], off offset:16
	v_lshl_add_u64 v[190:191], v[160:161], 0, s[16:17]
	s_mov_b64 s[16:17], 0x20200
	global_load_dwordx4 v[216:219], v[226:227], off
	global_load_dwordx4 v[220:223], v[190:191], off offset:16
	v_lshl_add_u64 v[190:191], v[160:161], 0, s[16:17]
	s_mov_b64 s[16:17], 0x30000
	global_load_dwordx4 v[226:229], v[226:227], off offset:512
	s_nop 0
	global_load_dwordx4 v[230:233], v[190:191], off offset:16
	v_lshl_add_u64 v[190:191], v[160:161], 0, s[16:17]
	v_addc_co_u32_e32 v243, vcc, 0, v161, vcc
	s_mov_b64 s[16:17], 0x30200
	global_load_dwordx4 v[234:237], v[242:243], off
	global_load_dwordx4 v[238:241], v[190:191], off offset:16
	v_lshl_add_u64 v[190:191], v[160:161], 0, s[16:17]
	global_load_dwordx4 v[242:245], v[242:243], off offset:512
	s_nop 0
	global_load_dwordx4 v[246:249], v[190:191], off offset:16
	v_mul_f32_e32 v144, 0.5, v144
	v_mul_f32_e32 v145, 0.5, v145
	v_mul_f32_e32 v152, 0.5, v152
	v_mul_f32_e32 v153, 0.5, v153
	s_waitcnt vmcnt(15)
	v_fma_f32 v168, v122, v150, v168
	v_fma_f32 v169, v123, v151, v169
	v_fma_f32 v166, v120, v152, v166
	v_fma_f32 v167, v121, v153, v167
	s_waitcnt vmcnt(14)
	v_fma_f32 v172, v126, v154, v172
	v_fma_f32 v173, v127, v155, v173
	v_fma_f32 v170, v124, v156, v170
	v_fma_f32 v171, v125, v157, v171
	global_store_dwordx4 v[158:159], v[166:169], off offset:16
	global_store_dwordx4 v[158:159], v[170:173], off
	s_waitcnt vmcnt(14)
	v_fma_f32 v168, v110, v146, v180
	v_fma_f32 v169, v111, v147, v181
	v_fma_f32 v166, v108, v148, v178
	v_fma_f32 v167, v109, v149, v179
	global_store_dwordx4 v[158:159], v[166:169], off offset:512
	v_add_co_u32_e32 v170, vcc, s24, v158
	s_nop 0
	v_fma_f32 v168, v102, v142, v176
	v_fma_f32 v169, v103, v143, v177
	v_fma_f32 v166, v100, v144, v174
	v_fma_f32 v167, v101, v145, v175
	global_store_dwordx4 v[158:159], v[166:169], off offset:528
	v_addc_co_u32_e32 v171, vcc, 0, v159, vcc
	s_waitcnt vmcnt(15)
	v_fma_f32 v168, v118, v154, v184
	v_fma_f32 v169, v119, v155, v185
	v_fma_f32 v166, v116, v156, v182
	v_fma_f32 v167, v117, v157, v183
	global_store_dwordx4 v[170:171], v[166:169], off
	s_waitcnt vmcnt(15)
	s_nop 0
	v_fma_f32 v168, v114, v150, v188
	v_fma_f32 v169, v115, v151, v189
	v_fma_f32 v166, v112, v152, v186
	v_fma_f32 v167, v113, v153, v187
	global_store_dwordx4 v[170:171], v[166:169], off offset:16
	s_waitcnt vmcnt(15)
	s_nop 0
	v_fma_f32 v168, v94, v146, v210
	v_fma_f32 v169, v95, v147, v211
	v_fma_f32 v166, v92, v148, v208
	v_fma_f32 v167, v93, v149, v209
	global_store_dwordx4 v[170:171], v[166:169], off offset:512
	s_waitcnt vmcnt(15)
	s_nop 0
	v_fma_f32 v168, v86, v142, v214
	v_fma_f32 v169, v87, v143, v215
	v_fma_f32 v166, v84, v144, v212
	v_fma_f32 v167, v85, v145, v213
	global_store_dwordx4 v[170:171], v[166:169], off offset:528
	v_add_co_u32_e32 v170, vcc, s48, v158
	s_waitcnt vmcnt(15)
	v_fma_f32 v168, v106, v154, v218
	v_fma_f32 v169, v107, v155, v219
	v_fma_f32 v166, v104, v156, v216
	v_fma_f32 v167, v105, v157, v217
	v_addc_co_u32_e32 v171, vcc, 0, v159, vcc
	global_store_dwordx4 v[170:171], v[166:169], off
	s_waitcnt vmcnt(15)
	s_nop 0
	v_fma_f32 v168, v98, v150, v222
	v_fma_f32 v169, v99, v151, v223
	v_fma_f32 v166, v96, v152, v220
	v_fma_f32 v167, v97, v153, v221
	global_store_dwordx4 v[170:171], v[166:169], off offset:16
	s_waitcnt vmcnt(15)
	s_nop 0
	v_fma_f32 v168, v78, v146, v228
	v_fma_f32 v169, v79, v147, v229
	v_fma_f32 v166, v76, v148, v226
	v_fma_f32 v167, v77, v149, v227
	global_store_dwordx4 v[170:171], v[166:169], off offset:512
	s_waitcnt vmcnt(15)
	s_nop 0
	v_fma_f32 v168, v74, v142, v232
	v_fma_f32 v169, v75, v143, v233
	v_fma_f32 v166, v72, v144, v230
	v_fma_f32 v167, v73, v145, v231
	global_store_dwordx4 v[170:171], v[166:169], off offset:528
	v_add_co_u32_e32 v170, vcc, s49, v158
	s_waitcnt vmcnt(15)
;     __device__ __forceinline__ void operator()(const f32x4 (&acc)[2][2][4][2], const Unit& u, int wr, int wc, int fr, int fq) const {
;     ...
;             for (int ai = 0; ai < 2; ++ai) {
;                 f32x4 xv[4][2][2];
; #pragma unroll
;                 for (int m = 0; m < 4; ++m)
; #pragma unroll
;                     for (int bj = 0; bj < 2; ++bj)
; #pragma unroll
;                         for (int n = 0; n < 2; ++n) xv[m][bj][n] = *(const f32x4*)(xo + (size_t)(ai * HALF + m * 16) * DM + col0 + bj * HALF + 4 * n);
;                 __builtin_amdgcn_sched_barrier(0);
; #pragma unroll
;                 for (int m = 0; m < 4; ++m)
; #pragma unroll
;                     for (int bj = 0; bj < 2; ++bj)
; #pragma unroll
;                         for (int n = 0; n < 2; ++n) *(f32x4*)(xn + (size_t)(ai * HALF + m * 16) * DM + col0 + bj * HALF + 4 * n) = xv[m][bj][n] + gv[bj][n] * acc[ai][bj][m][n];
;                 __builtin_amdgcn_sched_barrier(0);
	v_fma_f32 v168, v90, v154, v236
	v_fma_f32 v169, v91, v155, v237
	v_fma_f32 v166, v88, v156, v234
	v_fma_f32 v167, v89, v157, v235
	v_addc_co_u32_e32 v171, vcc, 0, v159, vcc
	global_store_dwordx4 v[170:171], v[166:169], off
	s_waitcnt vmcnt(15)
	s_nop 0
	v_fma_f32 v168, v82, v150, v240
	v_fma_f32 v169, v83, v151, v241
	v_fma_f32 v166, v80, v152, v238
	v_fma_f32 v167, v81, v153, v239
	global_store_dwordx4 v[170:171], v[166:169], off offset:16
	s_waitcnt vmcnt(15)
	s_nop 0
	v_fma_f32 v168, v70, v146, v244
	v_fma_f32 v169, v71, v147, v245
	v_fma_f32 v166, v68, v148, v242
	v_fma_f32 v167, v69, v149, v243
	global_store_dwordx4 v[170:171], v[166:169], off offset:512
	s_waitcnt vmcnt(15)
	s_nop 0
	v_fma_f32 v168, v66, v142, v248
	v_fma_f32 v169, v67, v143, v249
	v_fma_f32 v166, v64, v144, v246
	v_fma_f32 v167, v65, v145, v247
	global_store_dwordx4 v[170:171], v[166:169], off offset:528
	v_add_co_u32_e32 v174, vcc, s50, v160
	s_mov_b64 s[16:17], 0x80000
	s_nop 0
	v_addc_co_u32_e32 v175, vcc, 0, v161, vcc
	v_lshl_add_u64 v[170:171], v[160:161], 0, s[16:17]
	s_mov_b64 s[16:17], 0x80200
	v_add_co_u32_e32 v190, vcc, s51, v160
	v_lshl_add_u64 v[178:179], v[160:161], 0, s[16:17]
	s_mov_b64 s[16:17], 0x90000
	v_addc_co_u32_e32 v191, vcc, 0, v161, vcc
	v_lshl_add_u64 v[186:187], v[160:161], 0, s[16:17]
	s_mov_b64 s[16:17], 0x90200
	v_add_co_u32_e32 v226, vcc, s52, v160
	v_lshl_add_u64 v[212:213], v[160:161], 0, s[16:17]
	s_mov_b64 s[16:17], 0xa0000
	v_addc_co_u32_e32 v227, vcc, 0, v161, vcc
	global_load_dwordx4 v[166:169], v[174:175], off
	s_nop 0
	global_load_dwordx4 v[170:173], v[170:171], off offset:16
	s_nop 0
	global_load_dwordx4 v[174:177], v[174:175], off offset:512
	s_nop 0
	global_load_dwordx4 v[178:181], v[178:179], off offset:16
	s_nop 0
	global_load_dwordx4 v[182:185], v[190:191], off
	s_nop 0
	global_load_dwordx4 v[186:189], v[186:187], off offset:16
	s_nop 0
	global_load_dwordx4 v[208:211], v[190:191], off offset:512
	s_nop 0
	global_load_dwordx4 v[212:215], v[212:213], off offset:16
	v_lshl_add_u64 v[190:191], v[160:161], 0, s[16:17]
	s_mov_b64 s[16:17], 0xa0200
	v_add_co_u32_e32 v242, vcc, s53, v160
	global_load_dwordx4 v[216:219], v[226:227], off
	global_load_dwordx4 v[220:223], v[190:191], off offset:16
	v_lshl_add_u64 v[190:191], v[160:161], 0, s[16:17]
	v_addc_co_u32_e32 v243, vcc, 0, v161, vcc
	s_mov_b64 s[16:17], 0xb0200
	global_load_dwordx4 v[226:229], v[226:227], off offset:512
	s_nop 0
	global_load_dwordx4 v[230:233], v[190:191], off offset:16
	v_lshl_add_u64 v[190:191], v[160:161], 0, s[60:61]
	global_load_dwordx4 v[234:237], v[242:243], off
	global_load_dwordx4 v[238:241], v[190:191], off offset:16
	v_lshl_add_u64 v[160:161], v[160:161], 0, s[16:17]
	global_load_dwordx4 v[242:245], v[242:243], off offset:512
	s_nop 0
	global_load_dwordx4 v[246:249], v[160:161], off offset:16
	v_add_co_u32_e32 v160, vcc, s50, v158
	s_waitcnt vmcnt(15)
	v_fma_f32 v168, v62, v154, v168
	v_fma_f32 v169, v63, v155, v169
	v_fma_f32 v166, v60, v156, v166
	v_fma_f32 v167, v61, v157, v167
	v_addc_co_u32_e32 v161, vcc, 0, v159, vcc
	global_store_dwordx4 v[160:161], v[166:169], off
	s_waitcnt vmcnt(15)
	s_nop 0
	v_fma_f32 v168, v58, v150, v172
	v_fma_f32 v169, v59, v151, v173
	v_fma_f32 v166, v56, v152, v170
	v_fma_f32 v167, v57, v153, v171
	global_store_dwordx4 v[160:161], v[166:169], off offset:16
	s_waitcnt vmcnt(15)
	s_nop 0
	v_fma_f32 v168, v46, v146, v176
	v_fma_f32 v169, v47, v147, v177
	v_fma_f32 v166, v44, v148, v174
	v_fma_f32 v167, v45, v149, v175
	global_store_dwordx4 v[160:161], v[166:169], off offset:512
	s_waitcnt vmcnt(15)
	s_nop 0
	v_fma_f32 v168, v38, v142, v180
	v_fma_f32 v169, v39, v143, v181
	v_fma_f32 v166, v36, v144, v178
	v_fma_f32 v167, v37, v145, v179
	global_store_dwordx4 v[160:161], v[166:169], off offset:528
	v_add_co_u32_e32 v160, vcc, s51, v158
	s_waitcnt vmcnt(15)
	v_fma_f32 v168, v54, v154, v184
	v_fma_f32 v169, v55, v155, v185
	v_fma_f32 v166, v52, v156, v182
	v_fma_f32 v167, v53, v157, v183
	v_addc_co_u32_e32 v161, vcc, 0, v159, vcc
	global_store_dwordx4 v[160:161], v[166:169], off
	s_waitcnt vmcnt(15)
	s_nop 0
	v_fma_f32 v168, v50, v150, v188
	v_fma_f32 v169, v51, v151, v189
	v_fma_f32 v166, v48, v152, v186
	v_fma_f32 v167, v49, v153, v187
	global_store_dwordx4 v[160:161], v[166:169], off offset:16
	s_waitcnt vmcnt(15)
	s_nop 0
	v_fma_f32 v168, v30, v146, v210
	v_fma_f32 v169, v31, v147, v211
	v_fma_f32 v166, v28, v148, v208
	v_fma_f32 v167, v29, v149, v209
	global_store_dwordx4 v[160:161], v[166:169], off offset:512
	s_waitcnt vmcnt(15)
	s_nop 0
	v_fma_f32 v168, v22, v142, v214
	v_fma_f32 v169, v23, v143, v215
	v_fma_f32 v166, v20, v144, v212
	v_fma_f32 v167, v21, v145, v213
	global_store_dwordx4 v[160:161], v[166:169], off offset:528
	v_add_co_u32_e32 v160, vcc, s52, v158
	s_waitcnt vmcnt(15)
	v_fma_f32 v168, v42, v154, v218
	v_fma_f32 v169, v43, v155, v219
	v_fma_f32 v166, v40, v156, v216
	v_fma_f32 v167, v41, v157, v217
	v_addc_co_u32_e32 v161, vcc, 0, v159, vcc
	global_store_dwordx4 v[160:161], v[166:169], off
	s_waitcnt vmcnt(15)
	s_nop 0
	v_fma_f32 v168, v34, v150, v222
	v_fma_f32 v169, v35, v151, v223
	v_fma_f32 v166, v32, v152, v220
	v_fma_f32 v167, v33, v153, v221
	global_store_dwordx4 v[160:161], v[166:169], off offset:16
	s_waitcnt vmcnt(12)
	v_fma_f32 v152, v16, v152, v238
	v_fma_f32 v153, v17, v153, v239
	v_fma_f32 v168, v14, v146, v228
	v_fma_f32 v169, v15, v147, v229
	v_fma_f32 v166, v12, v148, v226
	v_fma_f32 v167, v13, v149, v227
	global_store_dwordx4 v[160:161], v[166:169], off offset:512
	s_waitcnt vmcnt(12)
	v_fma_f32 v148, v4, v148, v242
	v_fma_f32 v149, v5, v149, v243
	v_fma_f32 v168, v10, v142, v232
	v_fma_f32 v169, v11, v143, v233
	v_fma_f32 v166, v8, v144, v230
	v_fma_f32 v167, v9, v145, v231
	global_store_dwordx4 v[160:161], v[166:169], off offset:528
	s_waitcnt vmcnt(12)
	v_fma_f32 v144, v0, v144, v246
	v_fma_f32 v145, v1, v145, v247
	v_fma_f32 v166, v24, v156, v234
	v_fma_f32 v167, v25, v157, v235
	v_add_co_u32_e32 v156, vcc, s53, v158
	v_fma_f32 v168, v26, v154, v236
	v_fma_f32 v169, v27, v155, v237
	s_nop 0
	v_addc_co_u32_e32 v157, vcc, 0, v159, vcc
	v_fma_f32 v154, v18, v150, v240
	v_fma_f32 v155, v19, v151, v241
	v_fma_f32 v150, v6, v146, v244
	v_fma_f32 v151, v7, v147, v245
	v_fma_f32 v146, v2, v142, v248
	v_fma_f32 v147, v3, v143, v249
	global_store_dwordx4 v[156:157], v[166:169], off
	global_store_dwordx4 v[156:157], v[152:155], off offset:16
	global_store_dwordx4 v[156:157], v[148:151], off offset:512
	global_store_dwordx4 v[156:157], v[144:147], off offset:528
	s_cbranch_execnz .LBB0_1158

; __device__ __forceinline__ float wave_sum(float v) { return xadd32(sum32(v)); }
; __device__ __forceinline__ void final_phase(const float* x, const float* gain, float* out) {
;     ...
;     for (; row < RL; row += NGW) {
;         const int rn = row + NGW;
;         if (rn < RL) {
; #pragma unroll
;             for (int j = 0; j < 4; ++j) vn[j] = *(const f32x4*)(x + (size_t)rn * DM + 4 * lane + 256 * j); }
;         float ss = 0.f;
; #pragma unroll
;         for (int j = 0; j < 4; ++j) ss += (v[j][0] * v[j][0] + v[j][1] * v[j][1]) + (v[j][2] * v[j][2] + v[j][3] * v[j][3]);
;         const float rstd = __builtin_amdgcn_rsqf(wave_sum(ss) * (1.0f / DM) + EPS);
; #pragma unroll
;         for (int j = 0; j < 4; ++j) *(f32x4*)(out + (size_t)row * DM + 4 * lane + 256 * j) = v[j] * rstd * gn[j];
; #pragma unroll
;         for (int j = 0; j < 4; ++j) v[j] = vn[j];
;     }
.LBB0_1218:
	s_waitcnt vmcnt(3)
	v_mul_f32_e32 v51, v33, v33
	v_mul_f32_e32 v52, v35, v35
	v_fmac_f32_e32 v51, v32, v32
	v_fmac_f32_e32 v52, v34, v34
	v_add_f32_e32 v51, v51, v52
	s_waitcnt vmcnt(2)
	v_mul_f32_e32 v52, v25, v25
	v_mul_f32_e32 v53, v27, v27
	v_fmac_f32_e32 v52, v24, v24
	v_fmac_f32_e32 v53, v26, v26
	v_add_f32_e32 v52, v52, v53
	v_add_f32_e32 v51, v51, v52
	s_waitcnt vmcnt(1)
	v_mul_f32_e32 v52, v21, v21
	v_mul_f32_e32 v53, v23, v23
	v_fmac_f32_e32 v52, v20, v20
	v_fmac_f32_e32 v53, v22, v22
	v_add_f32_e32 v52, v52, v53
	v_add_f32_e32 v51, v52, v51
	s_waitcnt vmcnt(0)
	v_mul_f32_e32 v52, v17, v17
	v_mul_f32_e32 v53, v19, v19
	v_fmac_f32_e32 v52, v16, v16
	v_fmac_f32_e32 v53, v18, v18
	v_add_f32_e32 v52, v52, v53
	v_add_f32_e32 v51, v52, v51
	ds_swizzle_b32 v52, v51 offset:swizzle(SWAP,1)
	v_lshl_add_u64 v[54:55], s[2:3], 0, v[48:49]
	s_add_u32 s2, s2, s64
	s_addc_u32 s3, s3, s65
	s_add_u32 s4, s4, s64
	s_waitcnt lgkmcnt(0)
	v_add_f32_e32 v51, v51, v52
	ds_swizzle_b32 v52, v51 offset:swizzle(SWAP,2)
	s_addc_u32 s5, s5, s65
	s_andn2_b64 vcc, exec, s[6:7]
	s_waitcnt lgkmcnt(0)
	v_add_f32_e32 v51, v51, v52
	ds_swizzle_b32 v52, v51 offset:swizzle(SWAP,4)
	s_waitcnt lgkmcnt(0)
	v_add_f32_e32 v51, v51, v52
	ds_swizzle_b32 v52, v51 offset:swizzle(SWAP,8)
	s_waitcnt lgkmcnt(0)
	v_add_f32_e32 v51, v51, v52
	ds_swizzle_b32 v52, v51 offset:swizzle(SWAP,16)
	s_waitcnt lgkmcnt(0)
	v_add_f32_e32 v51, v51, v52
	v_mov_b32_e32 v52, v51
	s_nop 1
	v_permlane32_swap_b32_e32 v51, v52
	v_add_f32_e32 v51, v51, v52
	v_fmamk_f32 v51, v51, 0x3a800000, v50
	v_rsq_f32_e32 v52, v51
	s_nop 0
	v_mul_f32_e32 v32, v32, v52
	v_mul_f32_e32 v33, v33, v52
	v_mul_f32_e32 v34, v34, v52
	v_mul_f32_e32 v35, v35, v52
	v_mul_f32_e32 v56, v24, v52
	v_mul_f32_e32 v57, v25, v52
	v_mul_f32_e32 v58, v26, v52
	v_mul_f32_e32 v59, v27, v52
	v_mul_f32_e32 v26, v2, v34
	v_mul_f32_e32 v27, v3, v35
	v_mul_f32_e32 v24, v0, v32
	v_mul_f32_e32 v25, v1, v33
	v_mul_f32_e32 v20, v20, v52
	v_mul_f32_e32 v21, v21, v52
	v_mul_f32_e32 v22, v22, v52
	v_mul_f32_e32 v23, v23, v52
	v_mul_f32_e32 v16, v16, v52
	v_mul_f32_e32 v17, v17, v52
	v_mul_f32_e32 v18, v18, v52
	v_mul_f32_e32 v19, v19, v52
	global_store_dwordx4 v[54:55], v[24:27], off
	v_mul_f32_e32 v22, v10, v22
	v_mul_f32_e32 v23, v11, v23
	v_mul_f32_e32 v20, v8, v20
	v_mul_f32_e32 v21, v9, v21
	v_mul_f32_e32 v26, v6, v58
	v_mul_f32_e32 v27, v7, v59
	v_mul_f32_e32 v24, v4, v56
	v_mul_f32_e32 v25, v5, v57
	v_mul_f32_e32 v18, v14, v18
	v_mul_f32_e32 v19, v15, v19
	v_mul_f32_e32 v16, v12, v16
	v_mul_f32_e32 v17, v13, v17
	global_store_dwordx4 v[54:55], v[24:27], off offset:1024
	global_store_dwordx4 v[54:55], v[20:23], off offset:2048
	global_store_dwordx4 v[54:55], v[16:19], off offset:3072
	v_mov_b32_e32 v32, v28
	v_mov_b32_e32 v33, v29
	v_mov_b32_e32 v34, v30
	v_mov_b32_e32 v35, v31
	v_mov_b32_e32 v24, v36
	v_mov_b32_e32 v25, v37
	v_mov_b32_e32 v26, v38
	v_mov_b32_e32 v27, v39
	v_mov_b32_e32 v20, v40
	v_mov_b32_e32 v21, v41
	v_mov_b32_e32 v22, v42
	v_mov_b32_e32 v23, v43
	v_mov_b32_e32 v16, v44
	v_mov_b32_e32 v17, v45
	v_mov_b32_e32 v18, v46
	v_mov_b32_e32 v19, v47
	s_cbranch_vccz .LBB0_1221

; #define LAS __attribute__((address_space(3)))
; __global__ void __launch_bounds__(NTHREADS, 2) fwd_megakernel(Args a) {
;     extern __shared__ __attribute__((aligned(16))) unsigned char lds_raw[];
;     LAS unsigned char* lds = (LAS unsigned char*)lds_raw;
	.amdhsa_kernel _Z14fwd_megakernel4Args
		.amdhsa_group_segment_fixed_size 0
		.amdhsa_private_segment_fixed_size 0
		.amdhsa_kernarg_size 456
		.amdhsa_user_sgpr_count 2
		.amdhsa_user_sgpr_dispatch_ptr 0
		.amdhsa_user_sgpr_queue_ptr 0
		.amdhsa_user_sgpr_kernarg_segment_ptr 1
		.amdhsa_user_sgpr_dispatch_id 0
		.amdhsa_user_sgpr_kernarg_preload_length 0
		.amdhsa_user_sgpr_kernarg_preload_offset 0
		.amdhsa_user_sgpr_private_segment_size 0
		.amdhsa_uses_dynamic_stack 0
		.amdhsa_enable_private_segment 0
		.amdhsa_system_sgpr_workgroup_id_x 1
		.amdhsa_system_sgpr_workgroup_id_y 0
		.amdhsa_system_sgpr_workgroup_id_z 0
		.amdhsa_system_sgpr_workgroup_info 0
		.amdhsa_system_vgpr_workitem_id 2
		.amdhsa_next_free_vgpr 256
		.amdhsa_next_free_sgpr 100
		.amdhsa_accum_offset 256
		.amdhsa_reserve_vcc 1
		.amdhsa_float_round_mode_32 0
		.amdhsa_float_round_mode_16_64 0
		.amdhsa_float_denorm_mode_32 3
		.amdhsa_float_denorm_mode_16_64 3
		.amdhsa_dx10_clamp 1
		.amdhsa_ieee_mode 1
		.amdhsa_fp16_overflow 0
		.amdhsa_tg_split 0
		.amdhsa_exception_fp_ieee_invalid_op 0
		.amdhsa_exception_fp_denorm_src 0
		.amdhsa_exception_fp_ieee_div_zero 0
		.amdhsa_exception_fp_ieee_overflow 0
		.amdhsa_exception_fp_ieee_underflow 0
		.amdhsa_exception_fp_ieee_inexact 0
		.amdhsa_exception_int_div_zero 0
	.end_amdhsa_kernel

; #define LAS __attribute__((address_space(3)))
; __global__ void __launch_bounds__(NTHREADS, 2) fwd_megakernel(Args a) {
;     extern __shared__ __attribute__((aligned(16))) unsigned char lds_raw[];
;     LAS unsigned char* lds = (LAS unsigned char*)lds_raw;
amdhsa.kernels:
  - .agpr_count:     0
    .args:
      - .offset:         0
        .size:           200
        .value_kind:     by_value
      - .offset:         200
        .size:           4
        .value_kind:     hidden_block_count_x
      - .offset:         204
        .size:           4
        .value_kind:     hidden_block_count_y
      - .offset:         208
        .size:           4
        .value_kind:     hidden_block_count_z
      - .offset:         212
        .size:           2
        .value_kind:     hidden_group_size_x
      - .offset:         214
        .size:           2
        .value_kind:     hidden_group_size_y
      - .offset:         216
        .size:           2
        .value_kind:     hidden_group_size_z
      - .offset:         218
        .size:           2
        .value_kind:     hidden_remainder_x
      - .offset:         220
        .size:           2
        .value_kind:     hidden_remainder_y
      - .offset:         222
        .size:           2
        .value_kind:     hidden_remainder_z
      - .offset:         240
        .size:           8
        .value_kind:     hidden_global_offset_x
      - .offset:         248
        .size:           8
        .value_kind:     hidden_global_offset_y
      - .offset:         256
        .size:           8
        .value_kind:     hidden_global_offset_z
      - .offset:         264
        .size:           2
        .value_kind:     hidden_grid_dims
      - .offset:         288
        .size:           8
        .value_kind:     hidden_multigrid_sync_arg
      - .offset:         320
        .size:           4
        .value_kind:     hidden_dynamic_lds_size
    .group_segment_fixed_size: 0
    .kernarg_segment_align: 8
    .kernarg_segment_size: 456
    .language:       OpenCL C
    .language_version:
      - 2
      - 0
    .max_flat_workgroup_size: 512
    .name:           _Z14fwd_megakernel4Args
    .private_segment_fixed_size: 0
    .sgpr_count:     106
    .sgpr_spill_count: 239
    .symbol:         _Z14fwd_megakernel4Args.kd
    .uniform_work_group_size: 1
    .uses_dynamic_stack: false
    .vgpr_count:     256
    .vgpr_spill_count: 0
    .wavefront_size: 64
